# embedded LDS-DMA groups after MFMA 12 and 28 of each MFMA segment (was 14 and 30)
# baseline (speedup 1.0000x reference)
; #define PG8_STAGE(bufoff, gbase, voff) do { _Pragma("unroll") for (int _i = 0; _i < 2; ++_i) \
;         __builtin_amdgcn_global_load_lds((const unsigned*)((const char*)(gbase) + (voff)[_i]), (PG8_LAS unsigned*)(lds + (bufoff) + ldsw + _i * 8192), 16, 0, 0); } while (0)
; #define PG8_LDA(dst, b, h) do { _Pragma("unroll") for (int m = 0; m < 4; ++m) _Pragma("unroll") for (int k = 0; k < 2; ++k) dst[m][k] = *(const PG8_LAS bf16x8*)(lds + PG8_SA(b, h) + aoff + m * 2048 + k * 1024); } while (0)
; #define PG8_LDB(dst, b, h) do { _Pragma("unroll") for (int n = 0; n < 2; ++n) _Pragma("unroll") for (int k = 0; k < 2; ++k) dst[n][k] = *(const PG8_LAS bf16x8*)(lds + PG8_SB(b, h) + boff + n * 2048 + k * 1024); } while (0)
; #define PG8_WAIT_V(n) asm volatile("s_waitcnt vmcnt(" #n ")" ::: "memory")
; #define PG8_WAIT_L(n) asm volatile("s_waitcnt lgkmcnt(" #n ")" ::: "memory")
; #define PG8_BAR __builtin_amdgcn_s_barrier()
; #define PG8_SCHED __builtin_amdgcn_sched_barrier(0)
; template <class Epi, class Sched, bool ALIGN_EPI = false, bool SP2 = false>
; __device__ __forceinline__ void gemm_phase(PG8_LAS unsigned char* lds, const Gemm g, const Sched& S, const Epi& E) {
;     ...
;         const bool has_next = S.next(ui + 1, nxt);
;         const char* nA = has_next ? (const char*)g.A + (size_t)nxt.pm * tstep : cA; const char* nB = has_next ? (const char*)g.Bt + (size_t)nxt.pn * tstep : cB;
;         for (int t = 0; t < nt; t += 2) {
;             const bool last = (t == nt - 2);
;             const char* a1 = cA + (size_t)(t + 1) * kstep;
;             const char* a2 = last ? nA : cA + (size_t)(t + 2) * kstep; const char* b2 = last ? nB : cB + (size_t)(t + 2) * kstep;
;             const char* a3 = a2 + kstep; const char* b3 = b2 + kstep;
;             if (last && has_next) S.a_ready(nxt);
;             if constexpr (SP2) {
;             PG8_LDB(B0, 0, 0); PG8_LDB(B1, 0, 1); PG8_SCHED; PG8_LDA(At, 0, 0); PG8_STAGE(PG8_SA(1, 1), a1 + hstep, voffA);
;             PG8_WAIT_V(8); PG8_WAIT_L(0); PG8_BAR; PG8_MMA(0, 0, At, B0); PG8_MMA(0, 1, At, B1); PG8_BAR; PG8_SCHED;
;             PG8_LDA(At, 0, 1); PG8_STAGE(PG8_SB(0, 0), b2, voffB); PG8_STAGE(PG8_SB(0, 1), b2 + hstep, voffB); PG8_STAGE(PG8_SA(0, 0), a2, voffA);
;             PG8_WAIT_V(8); PG8_WAIT_L(0); PG8_BAR; PG8_MMA(1, 0, At, B0); PG8_MMA(1, 1, At, B1); PG8_BAR; PG8_SCHED;
.LBB0_190:
	s_ashr_i32 s27, s26, 31
	s_lshl_b64 s[14:15], s[26:27], 19
	s_add_u32 s28, s22, s14
	s_addc_u32 s29, s23, s15
	s_and_b64 s[14:15], s[0:1], exec
	s_cselect_b32 s27, s29, s49
	s_cselect_b32 s67, s28, s48
	s_ashr_i32 s25, s24, 31
	s_lshl_b64 s[14:15], s[24:25], 19
	s_add_u32 s40, s94, s14
	s_addc_u32 s41, s96, s15
	s_and_b64 s[14:15], s[0:1], exec
	s_cselect_b32 s25, s41, s51
	s_cselect_b32 s86, s40, s50
	s_add_u32 s48, s48, 0x40080
	s_addc_u32 s49, s49, 0
	s_add_u32 s87, s50, 0x100
	s_addc_u32 s88, s51, 0
	s_mov_b32 s89, -2
	ds_read_b128 v[144:147], v155
	ds_read_b128 v[148:151], v155 offset:1024
	ds_read_b128 v[160:163], v155 offset:2048
	ds_read_b128 v[168:171], v155 offset:3072
	ds_read_b128 v[172:175], v156
	ds_read_b128 v[176:179], v156 offset:1024
	ds_read_b128 v[182:185], v156 offset:2048
	ds_read_b128 v[186:189], v156 offset:3072
	s_add_u32 s3, s48, 0xfffc0080
	s_addc_u32 s14, s49, -1
	s_cmp_eq_u32 s89, 12
	s_cselect_b32 s55, s27, s14
	s_cselect_b32 s54, s67, s3
	s_cselect_b32 s51, s25, s88
	s_cselect_b32 s50, s86, s87
	v_lshl_add_u64 v[164:165], s[48:49], 0, v[136:137]
	s_add_i32 m0, s45, 0xc000
	ds_read_b128 v[190:193], v157
	ds_read_b128 v[194:197], v157 offset:1024
	ds_read_b128 v[198:201], v157 offset:2048
	ds_read_b128 v[208:211], v157 offset:3072
	ds_read_b128 v[212:215], v157 offset:4096
	ds_read_b128 v[216:219], v157 offset:5120
	ds_read_b128 v[220:223], v157 offset:6144
	ds_read_b128 v[224:227], v157 offset:7168
	global_load_lds_dwordx4 v[164:165], off
	v_lshl_add_u64 v[164:165], s[48:49], 0, v[138:139]
	s_add_i32 m0, s45, 0xe000
	s_nop 0
	global_load_lds_dwordx4 v[164:165], off
	s_waitcnt vmcnt(8)
	s_waitcnt lgkmcnt(0)
	s_barrier
	s_setprio 1
	s_waitcnt lgkmcnt(0)
	v_mfma_f32_16x16x32_bf16 v[124:127], v[144:147], v[190:193], 0
	v_mfma_f32_16x16x32_bf16 v[120:123], v[160:163], v[190:193], 0
	v_mfma_f32_16x16x32_bf16 v[108:111], v[144:147], v[198:201], 0
	v_mfma_f32_16x16x32_bf16 v[104:107], v[160:163], v[198:201], 0
	v_mfma_f32_16x16x32_bf16 v[92:95], v[144:147], v[212:215], 0
	v_mfma_f32_16x16x32_bf16 v[88:91], v[160:163], v[212:215], 0
	v_mfma_f32_16x16x32_bf16 v[76:79], v[144:147], v[220:223], 0
	v_mfma_f32_16x16x32_bf16 v[72:75], v[160:163], v[220:223], 0
	v_mfma_f32_16x16x32_bf16 v[124:127], v[148:151], v[194:197], v[124:127]
	v_mfma_f32_16x16x32_bf16 v[120:123], v[168:171], v[194:197], v[120:123]
	v_mfma_f32_16x16x32_bf16 v[108:111], v[148:151], v[208:211], v[108:111]
	v_mfma_f32_16x16x32_bf16 v[104:107], v[168:171], v[208:211], v[104:107]
	v_mfma_f32_16x16x32_bf16 v[92:95], v[148:151], v[216:219], v[92:95]
	v_mfma_f32_16x16x32_bf16 v[88:91], v[168:171], v[216:219], v[88:91]
	v_mfma_f32_16x16x32_bf16 v[76:79], v[148:151], v[224:227], v[76:79]
	v_mfma_f32_16x16x32_bf16 v[72:75], v[168:171], v[224:227], v[72:75]
	s_setprio 0
	s_setprio 1
	v_mfma_f32_16x16x32_bf16 v[116:119], v[172:175], v[190:193], 0
	v_mfma_f32_16x16x32_bf16 v[112:115], v[182:185], v[190:193], 0
	v_mfma_f32_16x16x32_bf16 v[100:103], v[172:175], v[198:201], 0
	v_mfma_f32_16x16x32_bf16 v[96:99], v[182:185], v[198:201], 0
	v_mfma_f32_16x16x32_bf16 v[84:87], v[172:175], v[212:215], 0
	v_mfma_f32_16x16x32_bf16 v[80:83], v[182:185], v[212:215], 0
	v_mfma_f32_16x16x32_bf16 v[68:71], v[172:175], v[220:223], 0
	v_mfma_f32_16x16x32_bf16 v[64:67], v[182:185], v[220:223], 0
	v_mfma_f32_16x16x32_bf16 v[116:119], v[176:179], v[194:197], v[116:119]
	v_mfma_f32_16x16x32_bf16 v[112:115], v[186:189], v[194:197], v[112:115]
	v_mfma_f32_16x16x32_bf16 v[100:103], v[176:179], v[208:211], v[100:103]
	v_mfma_f32_16x16x32_bf16 v[96:99], v[186:189], v[208:211], v[96:99]
	v_mfma_f32_16x16x32_bf16 v[84:87], v[176:179], v[216:219], v[84:87]
	v_mfma_f32_16x16x32_bf16 v[80:83], v[186:189], v[216:219], v[80:83]
	v_mfma_f32_16x16x32_bf16 v[68:71], v[176:179], v[224:227], v[68:71]
	v_mfma_f32_16x16x32_bf16 v[64:67], v[186:189], v[224:227], v[64:67]
	s_setprio 0
	s_barrier
	s_add_i32 s3, s63, s43
	v_lshl_add_u64 v[164:165], s[50:51], 0, v[132:133]
	s_mov_b32 m0, s3
	ds_read_b128 v[190:193], v157 offset:16384
	ds_read_b128 v[194:197], v157 offset:17408
	ds_read_b128 v[198:201], v157 offset:18432
	ds_read_b128 v[208:211], v157 offset:19456
	ds_read_b128 v[212:215], v157 offset:20480
	ds_read_b128 v[216:219], v157 offset:21504
	ds_read_b128 v[220:223], v157 offset:22528
	ds_read_b128 v[224:227], v157 offset:23552
	global_load_lds_dwordx4 v[164:165], off
	s_add_i32 m0, s3, 0x2000
	s_add_u32 s14, s50, 0x40000
	v_lshl_add_u64 v[202:203], s[50:51], 0, v[128:129]
	s_addc_u32 s15, s51, 0
	s_add_i32 s3, s64, s43
	global_load_lds_dwordx4 v[202:203], off
	v_lshl_add_u64 v[228:229], s[14:15], 0, v[132:133]
	s_mov_b32 m0, s3
	global_load_lds_dwordx4 v[228:229], off
	v_lshl_add_u64 v[228:229], s[14:15], 0, v[128:129]
	s_add_i32 m0, s3, 0x2000
	s_nop 0
	global_load_lds_dwordx4 v[228:229], off
	s_waitcnt vmcnt(6)
	s_waitcnt lgkmcnt(0)
	s_barrier
; #define PG8_STAGE(bufoff, gbase, voff) do { _Pragma("unroll") for (int _i = 0; _i < 2; ++_i) \
;         __builtin_amdgcn_global_load_lds((const unsigned*)((const char*)(gbase) + (voff)[_i]), (PG8_LAS unsigned*)(lds + (bufoff) + ldsw + _i * 8192), 16, 0, 0); } while (0)
; #define PG8_LDA(dst, b, h) do { _Pragma("unroll") for (int m = 0; m < 4; ++m) _Pragma("unroll") for (int k = 0; k < 2; ++k) dst[m][k] = *(const PG8_LAS bf16x8*)(lds + PG8_SA(b, h) + aoff + m * 2048 + k * 1024); } while (0)
; #define PG8_LDB(dst, b, h) do { _Pragma("unroll") for (int n = 0; n < 2; ++n) _Pragma("unroll") for (int k = 0; k < 2; ++k) dst[n][k] = *(const PG8_LAS bf16x8*)(lds + PG8_SB(b, h) + boff + n * 2048 + k * 1024); } while (0)
; #define PG8_MMA(ai, bj, At, Bt) do { __builtin_amdgcn_s_setprio(1); _Pragma("unroll") for (int m = 0; m < 4; ++m) _Pragma("unroll") for (int n = 0; n < 2; ++n) _Pragma("unroll") for (int k = 0; k < 2; ++k) \
;         acc[ai][bj][m][n] = __builtin_amdgcn_mfma_f32_16x16x32_bf16(Bt[n][k], At[m][k], acc[ai][bj][m][n], 0, 0, 0); __builtin_amdgcn_s_setprio(0); } while (0)
; #define PG8_WAIT_V(n) asm volatile("s_waitcnt vmcnt(" #n ")" ::: "memory")
; #define PG8_WAIT_L(n) asm volatile("s_waitcnt lgkmcnt(" #n ")" ::: "memory")
; #define PG8_BAR __builtin_amdgcn_s_barrier()
; #define PG8_SCHED __builtin_amdgcn_sched_barrier(0)
; template <class Epi, class Sched, bool ALIGN_EPI = false, bool SP2 = false>
; __device__ __forceinline__ void gemm_phase(PG8_LAS unsigned char* lds, const Gemm g, const Sched& S, const Epi& E) {
;     ...
;             PG8_WAIT_V(8); PG8_WAIT_L(0); PG8_BAR; PG8_MMA(1, 0, At, B0); PG8_MMA(1, 1, At, B1); PG8_BAR; PG8_SCHED;
;             PG8_LDB(B0, 1, 0); PG8_LDB(B1, 1, 1); PG8_SCHED; PG8_LDA(At, 1, 0); PG8_STAGE(PG8_SA(0, 1), a2 + hstep, voffA);
;             PG8_WAIT_V(8); PG8_WAIT_L(0); PG8_BAR; PG8_MMA(0, 0, At, B0); PG8_MMA(0, 1, At, B1); PG8_BAR; PG8_SCHED;
	s_setprio 1
	s_waitcnt lgkmcnt(0)
	v_mfma_f32_16x16x32_bf16 v[60:63], v[144:147], v[190:193], 0
	v_mfma_f32_16x16x32_bf16 v[56:59], v[160:163], v[190:193], 0
	v_mfma_f32_16x16x32_bf16 v[44:47], v[144:147], v[198:201], 0
	v_mfma_f32_16x16x32_bf16 v[40:43], v[160:163], v[198:201], 0
	v_mfma_f32_16x16x32_bf16 v[28:31], v[144:147], v[212:215], 0
	v_mfma_f32_16x16x32_bf16 v[24:27], v[160:163], v[212:215], 0
	v_mfma_f32_16x16x32_bf16 v[12:15], v[144:147], v[220:223], 0
	v_mfma_f32_16x16x32_bf16 v[8:11], v[160:163], v[220:223], 0
	v_mfma_f32_16x16x32_bf16 v[60:63], v[148:151], v[194:197], v[60:63]
	v_mfma_f32_16x16x32_bf16 v[56:59], v[168:171], v[194:197], v[56:59]
	v_mfma_f32_16x16x32_bf16 v[44:47], v[148:151], v[208:211], v[44:47]
	v_mfma_f32_16x16x32_bf16 v[40:43], v[168:171], v[208:211], v[40:43]
	v_lshl_add_u64 v[228:229], s[54:55], 0, v[134:135]
	s_mov_b32 m0, s45
	s_nop 0
	global_load_lds_dwordx4 v[228:229], off
	v_mfma_f32_16x16x32_bf16 v[28:31], v[148:151], v[216:219], v[28:31]
	v_mfma_f32_16x16x32_bf16 v[24:27], v[168:171], v[216:219], v[24:27]
	v_mfma_f32_16x16x32_bf16 v[12:15], v[148:151], v[224:227], v[12:15]
	v_mfma_f32_16x16x32_bf16 v[8:11], v[168:171], v[224:227], v[8:11]
	s_setprio 0
	s_setprio 1
	v_mfma_f32_16x16x32_bf16 v[52:55], v[172:175], v[190:193], 0
	v_mfma_f32_16x16x32_bf16 v[48:51], v[182:185], v[190:193], 0
	v_mfma_f32_16x16x32_bf16 v[36:39], v[172:175], v[198:201], 0
	v_mfma_f32_16x16x32_bf16 v[32:35], v[182:185], v[198:201], 0
	v_mfma_f32_16x16x32_bf16 v[20:23], v[172:175], v[212:215], 0
	v_mfma_f32_16x16x32_bf16 v[16:19], v[182:185], v[212:215], 0
	v_mfma_f32_16x16x32_bf16 v[4:7], v[172:175], v[220:223], 0
	v_mfma_f32_16x16x32_bf16 v[0:3], v[182:185], v[220:223], 0
	v_mfma_f32_16x16x32_bf16 v[52:55], v[176:179], v[194:197], v[52:55]
	v_mfma_f32_16x16x32_bf16 v[48:51], v[186:189], v[194:197], v[48:51]
	v_mfma_f32_16x16x32_bf16 v[36:39], v[176:179], v[208:211], v[36:39]
	v_mfma_f32_16x16x32_bf16 v[32:35], v[186:189], v[208:211], v[32:35]
	v_lshl_add_u64 v[230:231], s[54:55], 0, v[130:131]
	s_mov_b32 m0, s57
	s_nop 0
	global_load_lds_dwordx4 v[230:231], off
	v_mfma_f32_16x16x32_bf16 v[20:23], v[176:179], v[216:219], v[20:23]
	v_mfma_f32_16x16x32_bf16 v[16:19], v[186:189], v[216:219], v[16:19]
	v_mfma_f32_16x16x32_bf16 v[4:7], v[176:179], v[224:227], v[4:7]
	v_mfma_f32_16x16x32_bf16 v[0:3], v[186:189], v[224:227], v[0:3]
	s_setprio 0
	s_barrier
	s_add_i32 s3, 0, 0x18000
	v_add_u32_e32 v159, s3, v153
	s_add_i32 s33, 0, 0x1c000
	ds_read_b128 v[144:147], v159
	ds_read_b128 v[148:151], v159 offset:1024
	ds_read_b128 v[160:163], v159 offset:2048
	ds_read_b128 v[168:171], v159 offset:3072
	v_add_u32_e32 v159, s33, v153
	ds_read_b128 v[172:175], v159
	ds_read_b128 v[176:179], v159 offset:1024
	ds_read_b128 v[182:185], v159 offset:2048
	ds_read_b128 v[186:189], v159 offset:3072
	s_add_u32 s14, s54, 0x40000
	s_addc_u32 s15, s55, 0
	s_mov_b32 m0, s58
	v_lshl_add_u64 v[232:233], s[14:15], 0, v[134:135]
	ds_read_b128 v[190:193], v157 offset:32768
	ds_read_b128 v[194:197], v157 offset:33792
	ds_read_b128 v[198:201], v157 offset:34816
	ds_read_b128 v[208:211], v157 offset:35840
	ds_read_b128 v[212:215], v157 offset:36864
	ds_read_b128 v[216:219], v157 offset:37888
	ds_read_b128 v[220:223], v157 offset:38912
	ds_read_b128 v[224:227], v157 offset:39936
	global_load_lds_dwordx4 v[232:233], off
	v_lshl_add_u64 v[232:233], s[14:15], 0, v[130:131]
	s_mov_b32 m0, s59
	s_nop 0
	global_load_lds_dwordx4 v[232:233], off
	s_waitcnt vmcnt(8)
	s_waitcnt lgkmcnt(0)
	s_barrier
	s_setprio 1
	s_waitcnt lgkmcnt(0)
	v_mfma_f32_16x16x32_bf16 v[124:127], v[144:147], v[190:193], v[124:127]
	v_mfma_f32_16x16x32_bf16 v[120:123], v[160:163], v[190:193], v[120:123]
	v_mfma_f32_16x16x32_bf16 v[108:111], v[144:147], v[198:201], v[108:111]
	v_mfma_f32_16x16x32_bf16 v[104:107], v[160:163], v[198:201], v[104:107]
	v_mfma_f32_16x16x32_bf16 v[92:95], v[144:147], v[212:215], v[92:95]
	v_mfma_f32_16x16x32_bf16 v[88:91], v[160:163], v[212:215], v[88:91]
	v_mfma_f32_16x16x32_bf16 v[76:79], v[144:147], v[220:223], v[76:79]
	v_mfma_f32_16x16x32_bf16 v[72:75], v[160:163], v[220:223], v[72:75]
	v_mfma_f32_16x16x32_bf16 v[124:127], v[148:151], v[194:197], v[124:127]
	v_mfma_f32_16x16x32_bf16 v[120:123], v[168:171], v[194:197], v[120:123]
	v_mfma_f32_16x16x32_bf16 v[108:111], v[148:151], v[208:211], v[108:111]
	v_mfma_f32_16x16x32_bf16 v[104:107], v[168:171], v[208:211], v[104:107]
	v_mfma_f32_16x16x32_bf16 v[92:95], v[148:151], v[216:219], v[92:95]
	v_mfma_f32_16x16x32_bf16 v[88:91], v[168:171], v[216:219], v[88:91]
	v_mfma_f32_16x16x32_bf16 v[76:79], v[148:151], v[224:227], v[76:79]
	v_mfma_f32_16x16x32_bf16 v[72:75], v[168:171], v[224:227], v[72:75]
	s_setprio 0
	s_setprio 1
	v_mfma_f32_16x16x32_bf16 v[116:119], v[172:175], v[190:193], v[116:119]
	v_mfma_f32_16x16x32_bf16 v[112:115], v[182:185], v[190:193], v[112:115]
	v_mfma_f32_16x16x32_bf16 v[100:103], v[172:175], v[198:201], v[100:103]
	v_mfma_f32_16x16x32_bf16 v[96:99], v[182:185], v[198:201], v[96:99]
	v_mfma_f32_16x16x32_bf16 v[84:87], v[172:175], v[212:215], v[84:87]
	v_mfma_f32_16x16x32_bf16 v[80:83], v[182:185], v[212:215], v[80:83]
	v_mfma_f32_16x16x32_bf16 v[68:71], v[172:175], v[220:223], v[68:71]
	v_mfma_f32_16x16x32_bf16 v[64:67], v[182:185], v[220:223], v[64:67]
	v_mfma_f32_16x16x32_bf16 v[116:119], v[176:179], v[194:197], v[116:119]
	v_mfma_f32_16x16x32_bf16 v[112:115], v[186:189], v[194:197], v[112:115]
	v_mfma_f32_16x16x32_bf16 v[100:103], v[176:179], v[208:211], v[100:103]
	v_mfma_f32_16x16x32_bf16 v[96:99], v[186:189], v[208:211], v[96:99]
	v_mfma_f32_16x16x32_bf16 v[84:87], v[176:179], v[216:219], v[84:87]
	v_mfma_f32_16x16x32_bf16 v[80:83], v[186:189], v[216:219], v[80:83]
	v_mfma_f32_16x16x32_bf16 v[68:71], v[176:179], v[224:227], v[68:71]
	v_mfma_f32_16x16x32_bf16 v[64:67], v[186:189], v[224:227], v[64:67]
	s_setprio 0
	s_barrier
; #define PG8_STAGE(bufoff, gbase, voff) do { _Pragma("unroll") for (int _i = 0; _i < 2; ++_i) \
;         __builtin_amdgcn_global_load_lds((const unsigned*)((const char*)(gbase) + (voff)[_i]), (PG8_LAS unsigned*)(lds + (bufoff) + ldsw + _i * 8192), 16, 0, 0); } while (0)
; #define PG8_LDA(dst, b, h) do { _Pragma("unroll") for (int m = 0; m < 4; ++m) _Pragma("unroll") for (int k = 0; k < 2; ++k) dst[m][k] = *(const PG8_LAS bf16x8*)(lds + PG8_SA(b, h) + aoff + m * 2048 + k * 1024); } while (0)
; #define PG8_LDB(dst, b, h) do { _Pragma("unroll") for (int n = 0; n < 2; ++n) _Pragma("unroll") for (int k = 0; k < 2; ++k) dst[n][k] = *(const PG8_LAS bf16x8*)(lds + PG8_SB(b, h) + boff + n * 2048 + k * 1024); } while (0)
; #define PG8_MMA(ai, bj, At, Bt) do { __builtin_amdgcn_s_setprio(1); _Pragma("unroll") for (int m = 0; m < 4; ++m) _Pragma("unroll") for (int n = 0; n < 2; ++n) _Pragma("unroll") for (int k = 0; k < 2; ++k) \
;         acc[ai][bj][m][n] = __builtin_amdgcn_mfma_f32_16x16x32_bf16(Bt[n][k], At[m][k], acc[ai][bj][m][n], 0, 0, 0); __builtin_amdgcn_s_setprio(0); } while (0)
; #define PG8_WAIT_V(n) asm volatile("s_waitcnt vmcnt(" #n ")" ::: "memory")
; template <class Epi, class Sched, bool ALIGN_EPI = false, bool SP2 = false>
; __device__ __forceinline__ void gemm_phase(PG8_LAS unsigned char* lds, const Gemm g, const Sched& S, const Epi& E) {
;     ...
;             PG8_LDB(B0, 0, 0); PG8_LDB(B1, 0, 1); PG8_SCHED; PG8_LDA(At, 0, 0); PG8_STAGE(PG8_SA(1, 1), a1 + hstep, voffA);
;             PG8_WAIT_V(8); PG8_WAIT_L(0); PG8_BAR; PG8_MMA(0, 0, At, B0); PG8_MMA(0, 1, At, B1); PG8_BAR; PG8_SCHED;
;             PG8_LDA(At, 0, 1); PG8_STAGE(PG8_SB(0, 0), b2, voffB); PG8_STAGE(PG8_SB(0, 1), b2 + hstep, voffB); PG8_STAGE(PG8_SA(0, 0), a2, voffA);
;             PG8_WAIT_V(8); PG8_WAIT_L(0); PG8_BAR; PG8_MMA(1, 0, At, B0); PG8_MMA(1, 1, At, B1); PG8_BAR; PG8_SCHED;
;             PG8_LDB(B0, 1, 0); PG8_LDB(B1, 1, 1); PG8_SCHED; PG8_LDA(At, 1, 0); PG8_STAGE(PG8_SA(0, 1), a2 + hstep, voffA);
;             PG8_WAIT_V(8); PG8_WAIT_L(0); PG8_BAR; PG8_MMA(0, 0, At, B0); PG8_MMA(0, 1, At, B1); PG8_BAR; PG8_SCHED;
;             PG8_LDA(At, 1, 1); PG8_STAGE(PG8_SB(1, 0), b3, voffB); PG8_STAGE(PG8_SB(1, 1), b3 + hstep, voffB); PG8_STAGE(PG8_SA(1, 0), a3, voffA);
;             PG8_WAIT_V(8); PG8_WAIT_L(0); PG8_BAR; PG8_MMA(1, 0, At, B0); PG8_MMA(1, 1, At, B1); PG8_BAR; PG8_SCHED;
	s_add_i32 s3, s3, s43
	v_lshl_add_u64 v[164:165], v[164:165], 0, s[10:11]
	s_mov_b32 m0, s3
	ds_read_b128 v[190:193], v157 offset:49152
	ds_read_b128 v[194:197], v157 offset:50176
	ds_read_b128 v[198:201], v157 offset:51200
	ds_read_b128 v[208:211], v157 offset:52224
	ds_read_b128 v[212:215], v157 offset:53248
	ds_read_b128 v[216:219], v157 offset:54272
	ds_read_b128 v[220:223], v157 offset:55296
	ds_read_b128 v[224:227], v157 offset:56320
	global_load_lds_dwordx4 v[164:165], off
	s_add_i32 m0, s3, 0x2000
	s_add_u32 s14, s50, 0x40080
	v_lshl_add_u64 v[164:165], v[202:203], 0, s[10:11]
	s_addc_u32 s15, s51, 0
	s_add_i32 s3, s33, s43
	global_load_lds_dwordx4 v[164:165], off
	v_lshl_add_u64 v[164:165], s[14:15], 0, v[132:133]
	s_mov_b32 m0, s3
	s_nop 0
	global_load_lds_dwordx4 v[164:165], off
	v_lshl_add_u64 v[164:165], s[14:15], 0, v[128:129]
	s_add_i32 m0, s3, 0x2000
	s_nop 0
	global_load_lds_dwordx4 v[164:165], off
	s_waitcnt vmcnt(6)
	s_waitcnt lgkmcnt(0)
	s_barrier
	s_setprio 1
	s_waitcnt lgkmcnt(0)
	v_mfma_f32_16x16x32_bf16 v[60:63], v[144:147], v[190:193], v[60:63]
	v_mfma_f32_16x16x32_bf16 v[56:59], v[160:163], v[190:193], v[56:59]
	v_mfma_f32_16x16x32_bf16 v[44:47], v[144:147], v[198:201], v[44:47]
	v_mfma_f32_16x16x32_bf16 v[40:43], v[160:163], v[198:201], v[40:43]
	v_mfma_f32_16x16x32_bf16 v[28:31], v[144:147], v[212:215], v[28:31]
	v_mfma_f32_16x16x32_bf16 v[24:27], v[160:163], v[212:215], v[24:27]
	v_mfma_f32_16x16x32_bf16 v[12:15], v[144:147], v[220:223], v[12:15]
	v_mfma_f32_16x16x32_bf16 v[8:11], v[160:163], v[220:223], v[8:11]
	v_mfma_f32_16x16x32_bf16 v[60:63], v[148:151], v[194:197], v[60:63]
	v_mfma_f32_16x16x32_bf16 v[56:59], v[168:171], v[194:197], v[56:59]
	v_mfma_f32_16x16x32_bf16 v[44:47], v[148:151], v[208:211], v[44:47]
	v_mfma_f32_16x16x32_bf16 v[40:43], v[168:171], v[208:211], v[40:43]
	v_lshl_add_u64 v[164:165], v[228:229], 0, s[10:11]
	s_mov_b32 m0, s61
	s_nop 0
	global_load_lds_dwordx4 v[164:165], off
	v_mfma_f32_16x16x32_bf16 v[28:31], v[148:151], v[216:219], v[28:31]
	v_mfma_f32_16x16x32_bf16 v[24:27], v[168:171], v[216:219], v[24:27]
	v_mfma_f32_16x16x32_bf16 v[12:15], v[148:151], v[224:227], v[12:15]
	v_mfma_f32_16x16x32_bf16 v[8:11], v[168:171], v[224:227], v[8:11]
	s_setprio 0
	s_setprio 1
	v_mfma_f32_16x16x32_bf16 v[52:55], v[172:175], v[190:193], v[52:55]
	v_mfma_f32_16x16x32_bf16 v[48:51], v[182:185], v[190:193], v[48:51]
	v_mfma_f32_16x16x32_bf16 v[36:39], v[172:175], v[198:201], v[36:39]
	v_mfma_f32_16x16x32_bf16 v[32:35], v[182:185], v[198:201], v[32:35]
	v_mfma_f32_16x16x32_bf16 v[20:23], v[172:175], v[212:215], v[20:23]
	v_mfma_f32_16x16x32_bf16 v[16:19], v[182:185], v[212:215], v[16:19]
	v_mfma_f32_16x16x32_bf16 v[4:7], v[172:175], v[220:223], v[4:7]
	v_mfma_f32_16x16x32_bf16 v[0:3], v[182:185], v[220:223], v[0:3]
	v_mfma_f32_16x16x32_bf16 v[52:55], v[176:179], v[194:197], v[52:55]
	v_mfma_f32_16x16x32_bf16 v[48:51], v[186:189], v[194:197], v[48:51]
	v_mfma_f32_16x16x32_bf16 v[36:39], v[176:179], v[208:211], v[36:39]
	v_mfma_f32_16x16x32_bf16 v[32:35], v[186:189], v[208:211], v[32:35]
	v_lshl_add_u64 v[164:165], v[230:231], 0, s[10:11]
	s_mov_b32 m0, s62
	s_nop 0
	global_load_lds_dwordx4 v[164:165], off
	v_mfma_f32_16x16x32_bf16 v[20:23], v[176:179], v[216:219], v[20:23]
	v_mfma_f32_16x16x32_bf16 v[16:19], v[186:189], v[216:219], v[16:19]
	v_mfma_f32_16x16x32_bf16 v[4:7], v[176:179], v[224:227], v[4:7]
	v_mfma_f32_16x16x32_bf16 v[0:3], v[186:189], v[224:227], v[0:3]
	s_setprio 0
	s_barrier
	s_add_i32 s89, s89, 2
	s_add_u32 s48, s48, 0x100
	s_addc_u32 s49, s49, 0
	s_add_u32 s87, s87, 0x100
	s_addc_u32 s88, s88, 0
.LBB0_191:
	ds_read_b128 v[144:147], v155
	ds_read_b128 v[148:151], v155 offset:1024
	ds_read_b128 v[160:163], v155 offset:2048
	ds_read_b128 v[168:171], v155 offset:3072
	ds_read_b128 v[172:175], v156
	ds_read_b128 v[176:179], v156 offset:1024
	ds_read_b128 v[182:185], v156 offset:2048
	ds_read_b128 v[186:189], v156 offset:3072
	s_add_u32 s3, s48, 0xfffc0080
	s_addc_u32 s14, s49, -1
	s_cmp_eq_u32 s89, 12
	s_cselect_b32 s55, s27, s14
	s_cselect_b32 s54, s67, s3
	s_cselect_b32 s51, s25, s88
	s_cselect_b32 s50, s86, s87
	v_lshl_add_u64 v[164:165], s[48:49], 0, v[136:137]
	s_add_i32 m0, s45, 0xc000
	ds_read_b128 v[190:193], v157
	ds_read_b128 v[194:197], v157 offset:1024
	ds_read_b128 v[198:201], v157 offset:2048
	ds_read_b128 v[208:211], v157 offset:3072
	ds_read_b128 v[212:215], v157 offset:4096
	ds_read_b128 v[216:219], v157 offset:5120
	ds_read_b128 v[220:223], v157 offset:6144
	ds_read_b128 v[224:227], v157 offset:7168
	global_load_lds_dwordx4 v[164:165], off
	v_lshl_add_u64 v[164:165], s[48:49], 0, v[138:139]
	s_add_i32 m0, s45, 0xe000
	s_nop 0
	global_load_lds_dwordx4 v[164:165], off
	s_waitcnt vmcnt(8)
	s_waitcnt lgkmcnt(0)
	s_barrier
; #define PG8_STAGE(bufoff, gbase, voff) do { _Pragma("unroll") for (int _i = 0; _i < 2; ++_i) \
;         __builtin_amdgcn_global_load_lds((const unsigned*)((const char*)(gbase) + (voff)[_i]), (PG8_LAS unsigned*)(lds + (bufoff) + ldsw + _i * 8192), 16, 0, 0); } while (0)
; #define PG8_LDA(dst, b, h) do { _Pragma("unroll") for (int m = 0; m < 4; ++m) _Pragma("unroll") for (int k = 0; k < 2; ++k) dst[m][k] = *(const PG8_LAS bf16x8*)(lds + PG8_SA(b, h) + aoff + m * 2048 + k * 1024); } while (0)
; #define PG8_LDB(dst, b, h) do { _Pragma("unroll") for (int n = 0; n < 2; ++n) _Pragma("unroll") for (int k = 0; k < 2; ++k) dst[n][k] = *(const PG8_LAS bf16x8*)(lds + PG8_SB(b, h) + boff + n * 2048 + k * 1024); } while (0)
; #define PG8_MMA(ai, bj, At, Bt) do { __builtin_amdgcn_s_setprio(1); _Pragma("unroll") for (int m = 0; m < 4; ++m) _Pragma("unroll") for (int n = 0; n < 2; ++n) _Pragma("unroll") for (int k = 0; k < 2; ++k) \
;         acc[ai][bj][m][n] = __builtin_amdgcn_mfma_f32_16x16x32_bf16(Bt[n][k], At[m][k], acc[ai][bj][m][n], 0, 0, 0); __builtin_amdgcn_s_setprio(0); } while (0)
; #define PG8_WAIT_V(n) asm volatile("s_waitcnt vmcnt(" #n ")" ::: "memory")
; #define PG8_WAIT_L(n) asm volatile("s_waitcnt lgkmcnt(" #n ")" ::: "memory")
; #define PG8_BAR __builtin_amdgcn_s_barrier()
; #define PG8_SCHED __builtin_amdgcn_sched_barrier(0)
; template <class Epi, class Sched, bool ALIGN_EPI = false, bool SP2 = false>
; __device__ __forceinline__ void gemm_phase(PG8_LAS unsigned char* lds, const Gemm g, const Sched& S, const Epi& E) {
;     ...
;             PG8_LDB(B0, 0, 0); PG8_LDB(B1, 0, 1); PG8_SCHED; PG8_LDA(At, 0, 0); PG8_STAGE(PG8_SA(1, 1), a1 + hstep, voffA);
;             PG8_WAIT_V(8); PG8_WAIT_L(0); PG8_BAR; PG8_MMA(0, 0, At, B0); PG8_MMA(0, 1, At, B1); PG8_BAR; PG8_SCHED;
;             PG8_LDA(At, 0, 1); PG8_STAGE(PG8_SB(0, 0), b2, voffB); PG8_STAGE(PG8_SB(0, 1), b2 + hstep, voffB); PG8_STAGE(PG8_SA(0, 0), a2, voffA);
;             PG8_WAIT_V(8); PG8_WAIT_L(0); PG8_BAR; PG8_MMA(1, 0, At, B0); PG8_MMA(1, 1, At, B1); PG8_BAR; PG8_SCHED;
	s_setprio 1
	s_waitcnt lgkmcnt(0)
	v_mfma_f32_16x16x32_bf16 v[124:127], v[144:147], v[190:193], v[124:127]
	v_mfma_f32_16x16x32_bf16 v[120:123], v[160:163], v[190:193], v[120:123]
	v_mfma_f32_16x16x32_bf16 v[108:111], v[144:147], v[198:201], v[108:111]
	v_mfma_f32_16x16x32_bf16 v[104:107], v[160:163], v[198:201], v[104:107]
	v_mfma_f32_16x16x32_bf16 v[92:95], v[144:147], v[212:215], v[92:95]
	v_mfma_f32_16x16x32_bf16 v[88:91], v[160:163], v[212:215], v[88:91]
	v_mfma_f32_16x16x32_bf16 v[76:79], v[144:147], v[220:223], v[76:79]
	v_mfma_f32_16x16x32_bf16 v[72:75], v[160:163], v[220:223], v[72:75]
	v_mfma_f32_16x16x32_bf16 v[124:127], v[148:151], v[194:197], v[124:127]
	v_mfma_f32_16x16x32_bf16 v[120:123], v[168:171], v[194:197], v[120:123]
	v_mfma_f32_16x16x32_bf16 v[108:111], v[148:151], v[208:211], v[108:111]
	v_mfma_f32_16x16x32_bf16 v[104:107], v[168:171], v[208:211], v[104:107]
	v_mfma_f32_16x16x32_bf16 v[92:95], v[148:151], v[216:219], v[92:95]
	v_mfma_f32_16x16x32_bf16 v[88:91], v[168:171], v[216:219], v[88:91]
	v_mfma_f32_16x16x32_bf16 v[76:79], v[148:151], v[224:227], v[76:79]
	v_mfma_f32_16x16x32_bf16 v[72:75], v[168:171], v[224:227], v[72:75]
	s_setprio 0
	s_setprio 1
	v_mfma_f32_16x16x32_bf16 v[116:119], v[172:175], v[190:193], v[116:119]
	v_mfma_f32_16x16x32_bf16 v[112:115], v[182:185], v[190:193], v[112:115]
	v_mfma_f32_16x16x32_bf16 v[100:103], v[172:175], v[198:201], v[100:103]
	v_mfma_f32_16x16x32_bf16 v[96:99], v[182:185], v[198:201], v[96:99]
	v_mfma_f32_16x16x32_bf16 v[84:87], v[172:175], v[212:215], v[84:87]
	v_mfma_f32_16x16x32_bf16 v[80:83], v[182:185], v[212:215], v[80:83]
	v_mfma_f32_16x16x32_bf16 v[68:71], v[172:175], v[220:223], v[68:71]
	v_mfma_f32_16x16x32_bf16 v[64:67], v[182:185], v[220:223], v[64:67]
	v_mfma_f32_16x16x32_bf16 v[116:119], v[176:179], v[194:197], v[116:119]
	v_mfma_f32_16x16x32_bf16 v[112:115], v[186:189], v[194:197], v[112:115]
	v_mfma_f32_16x16x32_bf16 v[100:103], v[176:179], v[208:211], v[100:103]
	v_mfma_f32_16x16x32_bf16 v[96:99], v[186:189], v[208:211], v[96:99]
	v_mfma_f32_16x16x32_bf16 v[84:87], v[176:179], v[216:219], v[84:87]
	v_mfma_f32_16x16x32_bf16 v[80:83], v[186:189], v[216:219], v[80:83]
	v_mfma_f32_16x16x32_bf16 v[68:71], v[176:179], v[224:227], v[68:71]
	v_mfma_f32_16x16x32_bf16 v[64:67], v[186:189], v[224:227], v[64:67]
	s_setprio 0
	s_barrier
	s_add_i32 s3, s63, s43
	v_lshl_add_u64 v[164:165], s[50:51], 0, v[132:133]
	s_mov_b32 m0, s3
	ds_read_b128 v[190:193], v157 offset:16384
	ds_read_b128 v[194:197], v157 offset:17408
	ds_read_b128 v[198:201], v157 offset:18432
	ds_read_b128 v[208:211], v157 offset:19456
	ds_read_b128 v[212:215], v157 offset:20480
	ds_read_b128 v[216:219], v157 offset:21504
	ds_read_b128 v[220:223], v157 offset:22528
	ds_read_b128 v[224:227], v157 offset:23552
	global_load_lds_dwordx4 v[164:165], off
	s_add_i32 m0, s3, 0x2000
	s_add_u32 s14, s50, 0x40000
	v_lshl_add_u64 v[202:203], s[50:51], 0, v[128:129]
	s_addc_u32 s15, s51, 0
	s_add_i32 s3, s64, s43
	global_load_lds_dwordx4 v[202:203], off
	v_lshl_add_u64 v[228:229], s[14:15], 0, v[132:133]
	s_mov_b32 m0, s3
	global_load_lds_dwordx4 v[228:229], off
	v_lshl_add_u64 v[228:229], s[14:15], 0, v[128:129]
	s_add_i32 m0, s3, 0x2000
	s_nop 0
	global_load_lds_dwordx4 v[228:229], off
	s_waitcnt vmcnt(6)
	s_waitcnt lgkmcnt(0)
	s_barrier
	s_setprio 1
	s_waitcnt lgkmcnt(0)
	v_mfma_f32_16x16x32_bf16 v[60:63], v[144:147], v[190:193], v[60:63]
	v_mfma_f32_16x16x32_bf16 v[56:59], v[160:163], v[190:193], v[56:59]
	v_mfma_f32_16x16x32_bf16 v[44:47], v[144:147], v[198:201], v[44:47]
	v_mfma_f32_16x16x32_bf16 v[40:43], v[160:163], v[198:201], v[40:43]
	v_mfma_f32_16x16x32_bf16 v[28:31], v[144:147], v[212:215], v[28:31]
	v_mfma_f32_16x16x32_bf16 v[24:27], v[160:163], v[212:215], v[24:27]
	v_mfma_f32_16x16x32_bf16 v[12:15], v[144:147], v[220:223], v[12:15]
	v_mfma_f32_16x16x32_bf16 v[8:11], v[160:163], v[220:223], v[8:11]
	v_mfma_f32_16x16x32_bf16 v[60:63], v[148:151], v[194:197], v[60:63]
	v_mfma_f32_16x16x32_bf16 v[56:59], v[168:171], v[194:197], v[56:59]
	v_mfma_f32_16x16x32_bf16 v[44:47], v[148:151], v[208:211], v[44:47]
	v_mfma_f32_16x16x32_bf16 v[40:43], v[168:171], v[208:211], v[40:43]
	v_lshl_add_u64 v[228:229], s[54:55], 0, v[134:135]
	s_mov_b32 m0, s45
	s_nop 0
	global_load_lds_dwordx4 v[228:229], off
	v_mfma_f32_16x16x32_bf16 v[28:31], v[148:151], v[216:219], v[28:31]
	v_mfma_f32_16x16x32_bf16 v[24:27], v[168:171], v[216:219], v[24:27]
	v_mfma_f32_16x16x32_bf16 v[12:15], v[148:151], v[224:227], v[12:15]
	v_mfma_f32_16x16x32_bf16 v[8:11], v[168:171], v[224:227], v[8:11]
	s_setprio 0
	s_setprio 1
	v_mfma_f32_16x16x32_bf16 v[52:55], v[172:175], v[190:193], v[52:55]
	v_mfma_f32_16x16x32_bf16 v[48:51], v[182:185], v[190:193], v[48:51]
	v_mfma_f32_16x16x32_bf16 v[36:39], v[172:175], v[198:201], v[36:39]
	v_mfma_f32_16x16x32_bf16 v[32:35], v[182:185], v[198:201], v[32:35]
	v_mfma_f32_16x16x32_bf16 v[20:23], v[172:175], v[212:215], v[20:23]
	v_mfma_f32_16x16x32_bf16 v[16:19], v[182:185], v[212:215], v[16:19]
	v_mfma_f32_16x16x32_bf16 v[4:7], v[172:175], v[220:223], v[4:7]
	v_mfma_f32_16x16x32_bf16 v[0:3], v[182:185], v[220:223], v[0:3]
	v_mfma_f32_16x16x32_bf16 v[52:55], v[176:179], v[194:197], v[52:55]
	v_mfma_f32_16x16x32_bf16 v[48:51], v[186:189], v[194:197], v[48:51]
	v_mfma_f32_16x16x32_bf16 v[36:39], v[176:179], v[208:211], v[36:39]
	v_mfma_f32_16x16x32_bf16 v[32:35], v[186:189], v[208:211], v[32:35]
	v_lshl_add_u64 v[230:231], s[54:55], 0, v[130:131]
	s_mov_b32 m0, s57
	s_nop 0
	global_load_lds_dwordx4 v[230:231], off
	v_mfma_f32_16x16x32_bf16 v[20:23], v[176:179], v[216:219], v[20:23]
	v_mfma_f32_16x16x32_bf16 v[16:19], v[186:189], v[216:219], v[16:19]
	v_mfma_f32_16x16x32_bf16 v[4:7], v[176:179], v[224:227], v[4:7]
	v_mfma_f32_16x16x32_bf16 v[0:3], v[186:189], v[224:227], v[0:3]
	s_setprio 0
	s_barrier
; #define PG8_STAGE(bufoff, gbase, voff) do { _Pragma("unroll") for (int _i = 0; _i < 2; ++_i) \
;         __builtin_amdgcn_global_load_lds((const unsigned*)((const char*)(gbase) + (voff)[_i]), (PG8_LAS unsigned*)(lds + (bufoff) + ldsw + _i * 8192), 16, 0, 0); } while (0)
; #define PG8_LDA(dst, b, h) do { _Pragma("unroll") for (int m = 0; m < 4; ++m) _Pragma("unroll") for (int k = 0; k < 2; ++k) dst[m][k] = *(const PG8_LAS bf16x8*)(lds + PG8_SA(b, h) + aoff + m * 2048 + k * 1024); } while (0)
; #define PG8_LDB(dst, b, h) do { _Pragma("unroll") for (int n = 0; n < 2; ++n) _Pragma("unroll") for (int k = 0; k < 2; ++k) dst[n][k] = *(const PG8_LAS bf16x8*)(lds + PG8_SB(b, h) + boff + n * 2048 + k * 1024); } while (0)
; #define PG8_MMA(ai, bj, At, Bt) do { __builtin_amdgcn_s_setprio(1); _Pragma("unroll") for (int m = 0; m < 4; ++m) _Pragma("unroll") for (int n = 0; n < 2; ++n) _Pragma("unroll") for (int k = 0; k < 2; ++k) \
;         acc[ai][bj][m][n] = __builtin_amdgcn_mfma_f32_16x16x32_bf16(Bt[n][k], At[m][k], acc[ai][bj][m][n], 0, 0, 0); __builtin_amdgcn_s_setprio(0); } while (0)
; #define PG8_WAIT_V(n) asm volatile("s_waitcnt vmcnt(" #n ")" ::: "memory")
; #define PG8_WAIT_L(n) asm volatile("s_waitcnt lgkmcnt(" #n ")" ::: "memory")
; #define PG8_BAR __builtin_amdgcn_s_barrier()
; #define PG8_SCHED __builtin_amdgcn_sched_barrier(0)
; template <class Epi, class Sched, bool ALIGN_EPI = false, bool SP2 = false>
; __device__ __forceinline__ void gemm_phase(PG8_LAS unsigned char* lds, const Gemm g, const Sched& S, const Epi& E) {
;     ...
;             PG8_LDB(B0, 1, 0); PG8_LDB(B1, 1, 1); PG8_SCHED; PG8_LDA(At, 1, 0); PG8_STAGE(PG8_SA(0, 1), a2 + hstep, voffA);
;             PG8_WAIT_V(8); PG8_WAIT_L(0); PG8_BAR; PG8_MMA(0, 0, At, B0); PG8_MMA(0, 1, At, B1); PG8_BAR; PG8_SCHED;
	s_add_i32 s3, 0, 0x18000
	v_add_u32_e32 v159, s3, v153
	s_add_i32 s33, 0, 0x1c000
	ds_read_b128 v[144:147], v159
	ds_read_b128 v[148:151], v159 offset:1024
	ds_read_b128 v[160:163], v159 offset:2048
	ds_read_b128 v[168:171], v159 offset:3072
	v_add_u32_e32 v159, s33, v153
	ds_read_b128 v[172:175], v159
	ds_read_b128 v[176:179], v159 offset:1024
	ds_read_b128 v[182:185], v159 offset:2048
	ds_read_b128 v[186:189], v159 offset:3072
	s_add_u32 s14, s54, 0x40000
	s_addc_u32 s15, s55, 0
	s_mov_b32 m0, s58
	v_lshl_add_u64 v[232:233], s[14:15], 0, v[134:135]
	ds_read_b128 v[190:193], v157 offset:32768
	ds_read_b128 v[194:197], v157 offset:33792
	ds_read_b128 v[198:201], v157 offset:34816
	ds_read_b128 v[208:211], v157 offset:35840
	ds_read_b128 v[212:215], v157 offset:36864
	ds_read_b128 v[216:219], v157 offset:37888
	ds_read_b128 v[220:223], v157 offset:38912
	ds_read_b128 v[224:227], v157 offset:39936
	global_load_lds_dwordx4 v[232:233], off
	v_lshl_add_u64 v[232:233], s[14:15], 0, v[130:131]
	s_mov_b32 m0, s59
	s_nop 0
	global_load_lds_dwordx4 v[232:233], off
	s_waitcnt vmcnt(8)
	s_waitcnt lgkmcnt(0)
	s_barrier
	s_setprio 1
	s_waitcnt lgkmcnt(0)
	v_mfma_f32_16x16x32_bf16 v[124:127], v[144:147], v[190:193], v[124:127]
	v_mfma_f32_16x16x32_bf16 v[120:123], v[160:163], v[190:193], v[120:123]
	v_mfma_f32_16x16x32_bf16 v[108:111], v[144:147], v[198:201], v[108:111]
	v_mfma_f32_16x16x32_bf16 v[104:107], v[160:163], v[198:201], v[104:107]
	v_mfma_f32_16x16x32_bf16 v[92:95], v[144:147], v[212:215], v[92:95]
	v_mfma_f32_16x16x32_bf16 v[88:91], v[160:163], v[212:215], v[88:91]
	v_mfma_f32_16x16x32_bf16 v[76:79], v[144:147], v[220:223], v[76:79]
	v_mfma_f32_16x16x32_bf16 v[72:75], v[160:163], v[220:223], v[72:75]
	v_mfma_f32_16x16x32_bf16 v[124:127], v[148:151], v[194:197], v[124:127]
	v_mfma_f32_16x16x32_bf16 v[120:123], v[168:171], v[194:197], v[120:123]
	v_mfma_f32_16x16x32_bf16 v[108:111], v[148:151], v[208:211], v[108:111]
	v_mfma_f32_16x16x32_bf16 v[104:107], v[168:171], v[208:211], v[104:107]
	v_mfma_f32_16x16x32_bf16 v[92:95], v[148:151], v[216:219], v[92:95]
	v_mfma_f32_16x16x32_bf16 v[88:91], v[168:171], v[216:219], v[88:91]
	v_mfma_f32_16x16x32_bf16 v[76:79], v[148:151], v[224:227], v[76:79]
	v_mfma_f32_16x16x32_bf16 v[72:75], v[168:171], v[224:227], v[72:75]
	s_setprio 0
	s_setprio 1
	v_mfma_f32_16x16x32_bf16 v[116:119], v[172:175], v[190:193], v[116:119]
	v_mfma_f32_16x16x32_bf16 v[112:115], v[182:185], v[190:193], v[112:115]
	v_mfma_f32_16x16x32_bf16 v[100:103], v[172:175], v[198:201], v[100:103]
	v_mfma_f32_16x16x32_bf16 v[96:99], v[182:185], v[198:201], v[96:99]
	v_mfma_f32_16x16x32_bf16 v[84:87], v[172:175], v[212:215], v[84:87]
	v_mfma_f32_16x16x32_bf16 v[80:83], v[182:185], v[212:215], v[80:83]
	v_mfma_f32_16x16x32_bf16 v[68:71], v[172:175], v[220:223], v[68:71]
	v_mfma_f32_16x16x32_bf16 v[64:67], v[182:185], v[220:223], v[64:67]
	v_mfma_f32_16x16x32_bf16 v[116:119], v[176:179], v[194:197], v[116:119]
	v_mfma_f32_16x16x32_bf16 v[112:115], v[186:189], v[194:197], v[112:115]
	v_mfma_f32_16x16x32_bf16 v[100:103], v[176:179], v[208:211], v[100:103]
	v_mfma_f32_16x16x32_bf16 v[96:99], v[186:189], v[208:211], v[96:99]
	v_mfma_f32_16x16x32_bf16 v[84:87], v[176:179], v[216:219], v[84:87]
	v_mfma_f32_16x16x32_bf16 v[80:83], v[186:189], v[216:219], v[80:83]
	v_mfma_f32_16x16x32_bf16 v[68:71], v[176:179], v[224:227], v[68:71]
	v_mfma_f32_16x16x32_bf16 v[64:67], v[186:189], v[224:227], v[64:67]
	s_setprio 0
	s_barrier
; #define PG8_STAGE(bufoff, gbase, voff) do { _Pragma("unroll") for (int _i = 0; _i < 2; ++_i) \
;         __builtin_amdgcn_global_load_lds((const unsigned*)((const char*)(gbase) + (voff)[_i]), (PG8_LAS unsigned*)(lds + (bufoff) + ldsw + _i * 8192), 16, 0, 0); } while (0)
; #define PG8_LDA(dst, b, h) do { _Pragma("unroll") for (int m = 0; m < 4; ++m) _Pragma("unroll") for (int k = 0; k < 2; ++k) dst[m][k] = *(const PG8_LAS bf16x8*)(lds + PG8_SA(b, h) + aoff + m * 2048 + k * 1024); } while (0)
; #define PG8_MMA(ai, bj, At, Bt) do { __builtin_amdgcn_s_setprio(1); _Pragma("unroll") for (int m = 0; m < 4; ++m) _Pragma("unroll") for (int n = 0; n < 2; ++n) _Pragma("unroll") for (int k = 0; k < 2; ++k) \
;         acc[ai][bj][m][n] = __builtin_amdgcn_mfma_f32_16x16x32_bf16(Bt[n][k], At[m][k], acc[ai][bj][m][n], 0, 0, 0); __builtin_amdgcn_s_setprio(0); } while (0)
; #define PG8_WAIT_V(n) asm volatile("s_waitcnt vmcnt(" #n ")" ::: "memory")
; #define PG8_WAIT_L(n) asm volatile("s_waitcnt lgkmcnt(" #n ")" ::: "memory")
; #define PG8_BAR __builtin_amdgcn_s_barrier()
; #define PG8_SCHED __builtin_amdgcn_sched_barrier(0)
; __device__ __forceinline__ float row_rs(const float* ssp, int row) { const unsigned long long v = ((const unsigned long long*)ssp)[row];
;     return __builtin_amdgcn_rsqf((float)v * (1.0f / 4294967296.0f) * (1.0f / 1024.0f) + RMS_EPS); }
; template <class Epi, class Sched, bool ALIGN_EPI = false, bool SP2 = false>
; __device__ __forceinline__ void gemm_phase(PG8_LAS unsigned char* lds, const Gemm g, const Sched& S, const Epi& E) {
;     ...
;             PG8_LDA(At, 1, 1); PG8_STAGE(PG8_SB(1, 0), b3, voffB); PG8_STAGE(PG8_SB(1, 1), b3 + hstep, voffB); PG8_STAGE(PG8_SA(1, 0), a3, voffA);
;             PG8_WAIT_V(8); PG8_WAIT_L(0); PG8_BAR; PG8_MMA(1, 0, At, B0); PG8_MMA(1, 1, At, B1); PG8_BAR; PG8_SCHED;
	s_add_i32 s3, s3, s43
	v_lshl_add_u64 v[164:165], v[164:165], 0, s[10:11]
	s_mov_b32 m0, s3
	ds_read_b128 v[190:193], v157 offset:49152
	ds_read_b128 v[194:197], v157 offset:50176
	ds_read_b128 v[198:201], v157 offset:51200
	ds_read_b128 v[208:211], v157 offset:52224
	ds_read_b128 v[212:215], v157 offset:53248
	ds_read_b128 v[216:219], v157 offset:54272
	ds_read_b128 v[220:223], v157 offset:55296
	ds_read_b128 v[224:227], v157 offset:56320
	global_load_lds_dwordx4 v[164:165], off
	s_add_i32 m0, s3, 0x2000
	s_add_u32 s14, s50, 0x40080
	v_lshl_add_u64 v[164:165], v[202:203], 0, s[10:11]
	s_addc_u32 s15, s51, 0
	s_add_i32 s3, s33, s43
	global_load_lds_dwordx4 v[164:165], off
	v_lshl_add_u64 v[164:165], s[14:15], 0, v[132:133]
	s_mov_b32 m0, s3
	s_nop 0
	global_load_lds_dwordx4 v[164:165], off
	v_lshl_add_u64 v[164:165], s[14:15], 0, v[128:129]
	s_add_i32 m0, s3, 0x2000
	s_nop 0
	global_load_lds_dwordx4 v[164:165], off
	s_waitcnt vmcnt(6)
	s_waitcnt lgkmcnt(0)
	s_barrier
	s_setprio 1
	s_waitcnt lgkmcnt(0)
	v_mfma_f32_16x16x32_bf16 v[60:63], v[144:147], v[190:193], v[60:63]
	v_mfma_f32_16x16x32_bf16 v[56:59], v[160:163], v[190:193], v[56:59]
	v_mfma_f32_16x16x32_bf16 v[44:47], v[144:147], v[198:201], v[44:47]
	v_mfma_f32_16x16x32_bf16 v[40:43], v[160:163], v[198:201], v[40:43]
	v_mfma_f32_16x16x32_bf16 v[28:31], v[144:147], v[212:215], v[28:31]
	v_mfma_f32_16x16x32_bf16 v[24:27], v[160:163], v[212:215], v[24:27]
	v_mfma_f32_16x16x32_bf16 v[12:15], v[144:147], v[220:223], v[12:15]
	v_mfma_f32_16x16x32_bf16 v[8:11], v[160:163], v[220:223], v[8:11]
	v_mfma_f32_16x16x32_bf16 v[60:63], v[148:151], v[194:197], v[60:63]
	v_mfma_f32_16x16x32_bf16 v[56:59], v[168:171], v[194:197], v[56:59]
	v_mfma_f32_16x16x32_bf16 v[44:47], v[148:151], v[208:211], v[44:47]
	v_mfma_f32_16x16x32_bf16 v[40:43], v[168:171], v[208:211], v[40:43]
	v_lshl_add_u64 v[164:165], v[228:229], 0, s[10:11]
	s_mov_b32 m0, s61
	s_nop 0
	global_load_lds_dwordx4 v[164:165], off
	v_mfma_f32_16x16x32_bf16 v[28:31], v[148:151], v[216:219], v[28:31]
	v_mfma_f32_16x16x32_bf16 v[24:27], v[168:171], v[216:219], v[24:27]
	v_mfma_f32_16x16x32_bf16 v[12:15], v[148:151], v[224:227], v[12:15]
	v_mfma_f32_16x16x32_bf16 v[8:11], v[168:171], v[224:227], v[8:11]
	s_setprio 0
	s_setprio 1
	v_mfma_f32_16x16x32_bf16 v[52:55], v[172:175], v[190:193], v[52:55]
	v_mfma_f32_16x16x32_bf16 v[48:51], v[182:185], v[190:193], v[48:51]
	v_mfma_f32_16x16x32_bf16 v[36:39], v[172:175], v[198:201], v[36:39]
	v_mfma_f32_16x16x32_bf16 v[32:35], v[182:185], v[198:201], v[32:35]
	v_mfma_f32_16x16x32_bf16 v[20:23], v[172:175], v[212:215], v[20:23]
	v_mfma_f32_16x16x32_bf16 v[16:19], v[182:185], v[212:215], v[16:19]
	v_mfma_f32_16x16x32_bf16 v[4:7], v[172:175], v[220:223], v[4:7]
	v_mfma_f32_16x16x32_bf16 v[0:3], v[182:185], v[220:223], v[0:3]
	v_mfma_f32_16x16x32_bf16 v[52:55], v[176:179], v[194:197], v[52:55]
	v_mfma_f32_16x16x32_bf16 v[48:51], v[186:189], v[194:197], v[48:51]
	v_mfma_f32_16x16x32_bf16 v[36:39], v[176:179], v[208:211], v[36:39]
	v_mfma_f32_16x16x32_bf16 v[32:35], v[186:189], v[208:211], v[32:35]
	v_lshl_add_u64 v[164:165], v[230:231], 0, s[10:11]
	s_mov_b32 m0, s62
	s_nop 0
	global_load_lds_dwordx4 v[164:165], off
	v_mfma_f32_16x16x32_bf16 v[20:23], v[176:179], v[216:219], v[20:23]
	v_mfma_f32_16x16x32_bf16 v[16:19], v[186:189], v[216:219], v[16:19]
	v_mfma_f32_16x16x32_bf16 v[4:7], v[176:179], v[224:227], v[4:7]
	v_mfma_f32_16x16x32_bf16 v[0:3], v[186:189], v[224:227], v[0:3]
	s_setprio 0
	s_barrier
	s_add_i32 s89, s89, 2
	s_add_u32 s48, s48, 0x100
	s_addc_u32 s49, s49, 0
	s_add_u32 s87, s87, 0x100
	s_addc_u32 s88, s88, 0
	s_cmp_gt_u32 s89, 13
	s_cbranch_scc0 .LBB0_191
	v_lshl_add_u32 v144, s44, 8, v152
	v_ashrrev_i32_e32 v145, 31, v144
	v_lshl_add_u64 v[150:151], v[144:145], 3, s[6:7]
	global_load_dwordx2 v[182:183], v[150:151], off
	global_load_dwordx2 v[184:185], v[150:151], off offset:128
	global_load_dwordx2 v[186:187], v[150:151], off offset:256
	global_load_dwordx2 v[188:189], v[150:151], off offset:384
	global_load_dwordx2 v[190:191], v[150:151], off offset:1024
	global_load_dwordx2 v[192:193], v[150:151], off offset:1152
	global_load_dwordx2 v[194:195], v[150:151], off offset:1280
	global_load_dwordx2 v[196:197], v[150:151], off offset:1408
	s_and_b64 vcc, exec, s[16:17]
	s_cbranch_vccz .LBB0_194
	s_barrier

; #define PG8_STAGE(bufoff, gbase, voff) do { _Pragma("unroll") for (int _i = 0; _i < 2; ++_i) \
;         __builtin_amdgcn_global_load_lds((const unsigned*)((const char*)(gbase) + (voff)[_i]), (PG8_LAS unsigned*)(lds + (bufoff) + ldsw + _i * 8192), 16, 0, 0); } while (0)
; #define PG8_LDA(dst, b, h) do { _Pragma("unroll") for (int m = 0; m < 4; ++m) _Pragma("unroll") for (int k = 0; k < 2; ++k) dst[m][k] = *(const PG8_LAS bf16x8*)(lds + PG8_SA(b, h) + aoff + m * 2048 + k * 1024); } while (0)
; #define PG8_LDB(dst, b, h) do { _Pragma("unroll") for (int n = 0; n < 2; ++n) _Pragma("unroll") for (int k = 0; k < 2; ++k) dst[n][k] = *(const PG8_LAS bf16x8*)(lds + PG8_SB(b, h) + boff + n * 2048 + k * 1024); } while (0)
; #define PG8_WAIT_V(n) asm volatile("s_waitcnt vmcnt(" #n ")" ::: "memory")
; #define PG8_WAIT_L(n) asm volatile("s_waitcnt lgkmcnt(" #n ")" ::: "memory")
; #define PG8_BAR __builtin_amdgcn_s_barrier()
; #define PG8_SCHED __builtin_amdgcn_sched_barrier(0)
; template <class Epi, class Sched, bool ALIGN_EPI = false, bool SP2 = false>
; __device__ __forceinline__ void gemm_phase(PG8_LAS unsigned char* lds, const Gemm g, const Sched& S, const Epi& E) {
;     ...
;         const bool has_next = S.next(ui + 1, nxt);
;         const char* nA = has_next ? (const char*)g.A + (size_t)nxt.pm * tstep : cA; const char* nB = has_next ? (const char*)g.Bt + (size_t)nxt.pn * tstep : cB;
;         for (int t = 0; t < nt; t += 2) {
;             const bool last = (t == nt - 2);
;             const char* a1 = cA + (size_t)(t + 1) * kstep;
;             const char* a2 = last ? nA : cA + (size_t)(t + 2) * kstep; const char* b2 = last ? nB : cB + (size_t)(t + 2) * kstep;
;             const char* a3 = a2 + kstep; const char* b3 = b2 + kstep;
;             if (last && has_next) S.a_ready(nxt);
;             if constexpr (SP2) {
;             PG8_LDB(B0, 0, 0); PG8_LDB(B1, 0, 1); PG8_SCHED; PG8_LDA(At, 0, 0); PG8_STAGE(PG8_SA(1, 1), a1 + hstep, voffA);
;             PG8_WAIT_V(8); PG8_WAIT_L(0); PG8_BAR; PG8_MMA(0, 0, At, B0); PG8_MMA(0, 1, At, B1); PG8_BAR; PG8_SCHED;
;             PG8_LDA(At, 0, 1); PG8_STAGE(PG8_SB(0, 0), b2, voffB); PG8_STAGE(PG8_SB(0, 1), b2 + hstep, voffB); PG8_STAGE(PG8_SA(0, 0), a2, voffA);
;             PG8_WAIT_V(8); PG8_WAIT_L(0); PG8_BAR; PG8_MMA(1, 0, At, B0); PG8_MMA(1, 1, At, B1); PG8_BAR; PG8_SCHED;
.LBB0_268:
	s_add_u32 s91, s50, 0x100
	s_addc_u32 s92, s51, 0
	s_mov_b32 s93, -2
	s_waitcnt lgkmcnt(0)
	ds_read_b128 v[128:131], v165
	ds_read_b128 v[132:135], v165 offset:1024
	ds_read_b128 v[152:155], v165 offset:2048
	ds_read_b128 v[156:159], v165 offset:3072
	ds_read_b128 v[172:175], v168
	ds_read_b128 v[176:179], v168 offset:1024
	ds_read_b128 v[182:185], v168 offset:2048
	ds_read_b128 v[186:189], v168 offset:3072
	s_add_u32 s50, s10, 0x100
	s_addc_u32 s51, s11, 0
	s_cmp_eq_u32 s93, 40
	s_cselect_b32 s57, s1, s51
	s_cselect_b32 s56, s0, s50
	s_cselect_b32 s55, s49, s92
	s_cselect_b32 s54, s48, s91
	v_lshl_add_u64 v[160:161], s[10:11], 0, v[144:145]
	s_add_i32 m0, s58, 0xc000
	ds_read_b128 v[190:193], v169
	ds_read_b128 v[194:197], v169 offset:1024
	ds_read_b128 v[198:201], v169 offset:2048
	ds_read_b128 v[208:211], v169 offset:3072
	ds_read_b128 v[212:215], v169 offset:4096
	ds_read_b128 v[216:219], v169 offset:5120
	ds_read_b128 v[220:223], v169 offset:6144
	ds_read_b128 v[224:227], v169 offset:7168
	global_load_lds_dwordx4 v[160:161], off
	v_lshl_add_u64 v[160:161], s[10:11], 0, v[146:147]
	s_add_i32 m0, s58, 0xe000
	s_nop 0
	global_load_lds_dwordx4 v[160:161], off
	s_waitcnt vmcnt(8)
	s_waitcnt lgkmcnt(0)
	s_barrier
	s_setprio 1
	s_waitcnt lgkmcnt(0)
	v_mfma_f32_16x16x32_bf16 v[124:127], v[128:131], v[190:193], 0
	v_mfma_f32_16x16x32_bf16 v[120:123], v[152:155], v[190:193], 0
	v_mfma_f32_16x16x32_bf16 v[108:111], v[128:131], v[198:201], 0
	v_mfma_f32_16x16x32_bf16 v[104:107], v[152:155], v[198:201], 0
	v_mfma_f32_16x16x32_bf16 v[92:95], v[128:131], v[212:215], 0
	v_mfma_f32_16x16x32_bf16 v[88:91], v[152:155], v[212:215], 0
	v_mfma_f32_16x16x32_bf16 v[76:79], v[128:131], v[220:223], 0
	v_mfma_f32_16x16x32_bf16 v[72:75], v[152:155], v[220:223], 0
	v_mfma_f32_16x16x32_bf16 v[124:127], v[132:135], v[194:197], v[124:127]
	v_mfma_f32_16x16x32_bf16 v[120:123], v[156:159], v[194:197], v[120:123]
	v_mfma_f32_16x16x32_bf16 v[108:111], v[132:135], v[208:211], v[108:111]
	v_mfma_f32_16x16x32_bf16 v[104:107], v[156:159], v[208:211], v[104:107]
	v_mfma_f32_16x16x32_bf16 v[92:95], v[132:135], v[216:219], v[92:95]
	v_mfma_f32_16x16x32_bf16 v[88:91], v[156:159], v[216:219], v[88:91]
	v_mfma_f32_16x16x32_bf16 v[76:79], v[132:135], v[224:227], v[76:79]
	v_mfma_f32_16x16x32_bf16 v[72:75], v[156:159], v[224:227], v[72:75]
	s_setprio 0
	s_setprio 1
	v_mfma_f32_16x16x32_bf16 v[116:119], v[172:175], v[190:193], 0
	v_mfma_f32_16x16x32_bf16 v[112:115], v[182:185], v[190:193], 0
	v_mfma_f32_16x16x32_bf16 v[100:103], v[172:175], v[198:201], 0
	v_mfma_f32_16x16x32_bf16 v[96:99], v[182:185], v[198:201], 0
	v_mfma_f32_16x16x32_bf16 v[84:87], v[172:175], v[212:215], 0
	v_mfma_f32_16x16x32_bf16 v[80:83], v[182:185], v[212:215], 0
	v_mfma_f32_16x16x32_bf16 v[68:71], v[172:175], v[220:223], 0
	v_mfma_f32_16x16x32_bf16 v[64:67], v[182:185], v[220:223], 0
	v_mfma_f32_16x16x32_bf16 v[116:119], v[176:179], v[194:197], v[116:119]
	v_mfma_f32_16x16x32_bf16 v[112:115], v[186:189], v[194:197], v[112:115]
	v_mfma_f32_16x16x32_bf16 v[100:103], v[176:179], v[208:211], v[100:103]
	v_mfma_f32_16x16x32_bf16 v[96:99], v[186:189], v[208:211], v[96:99]
	v_mfma_f32_16x16x32_bf16 v[84:87], v[176:179], v[216:219], v[84:87]
	v_mfma_f32_16x16x32_bf16 v[80:83], v[186:189], v[216:219], v[80:83]
	v_mfma_f32_16x16x32_bf16 v[68:71], v[176:179], v[224:227], v[68:71]
	v_mfma_f32_16x16x32_bf16 v[64:67], v[186:189], v[224:227], v[64:67]
	s_setprio 0
	s_barrier
	s_add_i32 s3, s65, s43
	v_lshl_add_u64 v[160:161], s[54:55], 0, v[138:139]
	s_mov_b32 m0, s3
	ds_read_b128 v[190:193], v169 offset:16384
	ds_read_b128 v[194:197], v169 offset:17408
	ds_read_b128 v[198:201], v169 offset:18432
	ds_read_b128 v[208:211], v169 offset:19456
	ds_read_b128 v[212:215], v169 offset:20480
	ds_read_b128 v[216:219], v169 offset:21504
	ds_read_b128 v[220:223], v169 offset:22528
	ds_read_b128 v[224:227], v169 offset:23552
	global_load_lds_dwordx4 v[160:161], off
	s_add_i32 m0, s3, 0x2000
	s_add_u32 s10, s54, 0xb0000
	v_lshl_add_u64 v[202:203], s[54:55], 0, v[142:143]
	s_addc_u32 s11, s55, 0
	s_add_i32 s3, s66, s43
	global_load_lds_dwordx4 v[202:203], off
	v_lshl_add_u64 v[228:229], s[10:11], 0, v[138:139]
	s_mov_b32 m0, s3
	global_load_lds_dwordx4 v[228:229], off
	v_lshl_add_u64 v[228:229], s[10:11], 0, v[142:143]
	s_add_i32 m0, s3, 0x2000
	s_nop 0
	global_load_lds_dwordx4 v[228:229], off
	s_waitcnt vmcnt(6)
	s_waitcnt lgkmcnt(0)
	s_barrier
; #define PG8_STAGE(bufoff, gbase, voff) do { _Pragma("unroll") for (int _i = 0; _i < 2; ++_i) \
;         __builtin_amdgcn_global_load_lds((const unsigned*)((const char*)(gbase) + (voff)[_i]), (PG8_LAS unsigned*)(lds + (bufoff) + ldsw + _i * 8192), 16, 0, 0); } while (0)
; #define PG8_LDA(dst, b, h) do { _Pragma("unroll") for (int m = 0; m < 4; ++m) _Pragma("unroll") for (int k = 0; k < 2; ++k) dst[m][k] = *(const PG8_LAS bf16x8*)(lds + PG8_SA(b, h) + aoff + m * 2048 + k * 1024); } while (0)
; #define PG8_LDB(dst, b, h) do { _Pragma("unroll") for (int n = 0; n < 2; ++n) _Pragma("unroll") for (int k = 0; k < 2; ++k) dst[n][k] = *(const PG8_LAS bf16x8*)(lds + PG8_SB(b, h) + boff + n * 2048 + k * 1024); } while (0)
; #define PG8_MMA(ai, bj, At, Bt) do { __builtin_amdgcn_s_setprio(1); _Pragma("unroll") for (int m = 0; m < 4; ++m) _Pragma("unroll") for (int n = 0; n < 2; ++n) _Pragma("unroll") for (int k = 0; k < 2; ++k) \
;         acc[ai][bj][m][n] = __builtin_amdgcn_mfma_f32_16x16x32_bf16(Bt[n][k], At[m][k], acc[ai][bj][m][n], 0, 0, 0); __builtin_amdgcn_s_setprio(0); } while (0)
; #define PG8_WAIT_V(n) asm volatile("s_waitcnt vmcnt(" #n ")" ::: "memory")
; #define PG8_WAIT_L(n) asm volatile("s_waitcnt lgkmcnt(" #n ")" ::: "memory")
; #define PG8_BAR __builtin_amdgcn_s_barrier()
; #define PG8_SCHED __builtin_amdgcn_sched_barrier(0)
; template <class Epi, class Sched, bool ALIGN_EPI = false, bool SP2 = false>
; __device__ __forceinline__ void gemm_phase(PG8_LAS unsigned char* lds, const Gemm g, const Sched& S, const Epi& E) {
;     ...
;             PG8_WAIT_V(8); PG8_WAIT_L(0); PG8_BAR; PG8_MMA(1, 0, At, B0); PG8_MMA(1, 1, At, B1); PG8_BAR; PG8_SCHED;
;             PG8_LDB(B0, 1, 0); PG8_LDB(B1, 1, 1); PG8_SCHED; PG8_LDA(At, 1, 0); PG8_STAGE(PG8_SA(0, 1), a2 + hstep, voffA);
;             PG8_WAIT_V(8); PG8_WAIT_L(0); PG8_BAR; PG8_MMA(0, 0, At, B0); PG8_MMA(0, 1, At, B1); PG8_BAR; PG8_SCHED;
	s_setprio 1
	s_waitcnt lgkmcnt(0)
	v_mfma_f32_16x16x32_bf16 v[60:63], v[128:131], v[190:193], 0
	v_mfma_f32_16x16x32_bf16 v[56:59], v[152:155], v[190:193], 0
	v_mfma_f32_16x16x32_bf16 v[44:47], v[128:131], v[198:201], 0
	v_mfma_f32_16x16x32_bf16 v[40:43], v[152:155], v[198:201], 0
	v_mfma_f32_16x16x32_bf16 v[28:31], v[128:131], v[212:215], 0
	v_mfma_f32_16x16x32_bf16 v[24:27], v[152:155], v[212:215], 0
	v_mfma_f32_16x16x32_bf16 v[12:15], v[128:131], v[220:223], 0
	v_mfma_f32_16x16x32_bf16 v[8:11], v[152:155], v[220:223], 0
	v_mfma_f32_16x16x32_bf16 v[60:63], v[132:135], v[194:197], v[60:63]
	v_mfma_f32_16x16x32_bf16 v[56:59], v[156:159], v[194:197], v[56:59]
	v_mfma_f32_16x16x32_bf16 v[44:47], v[132:135], v[208:211], v[44:47]
	v_mfma_f32_16x16x32_bf16 v[40:43], v[156:159], v[208:211], v[40:43]
	v_lshl_add_u64 v[228:229], s[56:57], 0, v[136:137]
	s_mov_b32 m0, s58
	s_nop 0
	global_load_lds_dwordx4 v[228:229], off
	v_mfma_f32_16x16x32_bf16 v[28:31], v[132:135], v[216:219], v[28:31]
	v_mfma_f32_16x16x32_bf16 v[24:27], v[156:159], v[216:219], v[24:27]
	v_mfma_f32_16x16x32_bf16 v[12:15], v[132:135], v[224:227], v[12:15]
	v_mfma_f32_16x16x32_bf16 v[8:11], v[156:159], v[224:227], v[8:11]
	s_setprio 0
	s_setprio 1
	v_mfma_f32_16x16x32_bf16 v[52:55], v[172:175], v[190:193], 0
	v_mfma_f32_16x16x32_bf16 v[48:51], v[182:185], v[190:193], 0
	v_mfma_f32_16x16x32_bf16 v[36:39], v[172:175], v[198:201], 0
	v_mfma_f32_16x16x32_bf16 v[32:35], v[182:185], v[198:201], 0
	v_mfma_f32_16x16x32_bf16 v[20:23], v[172:175], v[212:215], 0
	v_mfma_f32_16x16x32_bf16 v[16:19], v[182:185], v[212:215], 0
	v_mfma_f32_16x16x32_bf16 v[4:7], v[172:175], v[220:223], 0
	v_mfma_f32_16x16x32_bf16 v[0:3], v[182:185], v[220:223], 0
	v_mfma_f32_16x16x32_bf16 v[52:55], v[176:179], v[194:197], v[52:55]
	v_mfma_f32_16x16x32_bf16 v[48:51], v[186:189], v[194:197], v[48:51]
	v_mfma_f32_16x16x32_bf16 v[36:39], v[176:179], v[208:211], v[36:39]
	v_mfma_f32_16x16x32_bf16 v[32:35], v[186:189], v[208:211], v[32:35]
	v_lshl_add_u64 v[230:231], s[56:57], 0, v[140:141]
	s_mov_b32 m0, s59
	s_nop 0
	global_load_lds_dwordx4 v[230:231], off
	v_mfma_f32_16x16x32_bf16 v[20:23], v[176:179], v[216:219], v[20:23]
	v_mfma_f32_16x16x32_bf16 v[16:19], v[186:189], v[216:219], v[16:19]
	v_mfma_f32_16x16x32_bf16 v[4:7], v[176:179], v[224:227], v[4:7]
	v_mfma_f32_16x16x32_bf16 v[0:3], v[186:189], v[224:227], v[0:3]
	s_setprio 0
	s_barrier
	s_add_i32 s3, 0, 0x18000
	s_add_i32 s14, 0, 0x1c000
	v_add_u32_e32 v156, s3, v163
	v_add_u32_e32 v171, s14, v163
	ds_read_b128 v[128:131], v156
	ds_read_b128 v[132:135], v156 offset:1024
	ds_read_b128 v[152:155], v156 offset:2048
	ds_read_b128 v[156:159], v156 offset:3072
	ds_read_b128 v[172:175], v171
	ds_read_b128 v[176:179], v171 offset:1024
	ds_read_b128 v[182:185], v171 offset:2048
	ds_read_b128 v[186:189], v171 offset:3072
	s_add_u32 s10, s56, 0xb0000
	s_addc_u32 s11, s57, 0
	s_mov_b32 m0, s60
	v_lshl_add_u64 v[232:233], s[10:11], 0, v[136:137]
	ds_read_b128 v[190:193], v169 offset:32768
	ds_read_b128 v[194:197], v169 offset:33792
	ds_read_b128 v[198:201], v169 offset:34816
	ds_read_b128 v[208:211], v169 offset:35840
	ds_read_b128 v[212:215], v169 offset:36864
	ds_read_b128 v[216:219], v169 offset:37888
	ds_read_b128 v[220:223], v169 offset:38912
	ds_read_b128 v[224:227], v169 offset:39936
	global_load_lds_dwordx4 v[232:233], off
	v_lshl_add_u64 v[232:233], s[10:11], 0, v[140:141]
	s_mov_b32 m0, s61
	s_nop 0
	global_load_lds_dwordx4 v[232:233], off
	s_waitcnt vmcnt(8)
	s_waitcnt lgkmcnt(0)
	s_barrier
	s_setprio 1
	s_waitcnt lgkmcnt(0)
	v_mfma_f32_16x16x32_bf16 v[124:127], v[128:131], v[190:193], v[124:127]
	v_mfma_f32_16x16x32_bf16 v[120:123], v[152:155], v[190:193], v[120:123]
	v_mfma_f32_16x16x32_bf16 v[108:111], v[128:131], v[198:201], v[108:111]
	v_mfma_f32_16x16x32_bf16 v[104:107], v[152:155], v[198:201], v[104:107]
	v_mfma_f32_16x16x32_bf16 v[92:95], v[128:131], v[212:215], v[92:95]
	v_mfma_f32_16x16x32_bf16 v[88:91], v[152:155], v[212:215], v[88:91]
	v_mfma_f32_16x16x32_bf16 v[76:79], v[128:131], v[220:223], v[76:79]
	v_mfma_f32_16x16x32_bf16 v[72:75], v[152:155], v[220:223], v[72:75]
	v_mfma_f32_16x16x32_bf16 v[124:127], v[132:135], v[194:197], v[124:127]
	v_mfma_f32_16x16x32_bf16 v[120:123], v[156:159], v[194:197], v[120:123]
	v_mfma_f32_16x16x32_bf16 v[108:111], v[132:135], v[208:211], v[108:111]
	v_mfma_f32_16x16x32_bf16 v[104:107], v[156:159], v[208:211], v[104:107]
	v_mfma_f32_16x16x32_bf16 v[92:95], v[132:135], v[216:219], v[92:95]
	v_mfma_f32_16x16x32_bf16 v[88:91], v[156:159], v[216:219], v[88:91]
	v_mfma_f32_16x16x32_bf16 v[76:79], v[132:135], v[224:227], v[76:79]
	v_mfma_f32_16x16x32_bf16 v[72:75], v[156:159], v[224:227], v[72:75]
	s_setprio 0
	s_setprio 1
	v_mfma_f32_16x16x32_bf16 v[116:119], v[172:175], v[190:193], v[116:119]
	v_mfma_f32_16x16x32_bf16 v[112:115], v[182:185], v[190:193], v[112:115]
	v_mfma_f32_16x16x32_bf16 v[100:103], v[172:175], v[198:201], v[100:103]
	v_mfma_f32_16x16x32_bf16 v[96:99], v[182:185], v[198:201], v[96:99]
	v_mfma_f32_16x16x32_bf16 v[84:87], v[172:175], v[212:215], v[84:87]
	v_mfma_f32_16x16x32_bf16 v[80:83], v[182:185], v[212:215], v[80:83]
	v_mfma_f32_16x16x32_bf16 v[68:71], v[172:175], v[220:223], v[68:71]
	v_mfma_f32_16x16x32_bf16 v[64:67], v[182:185], v[220:223], v[64:67]
	v_mfma_f32_16x16x32_bf16 v[116:119], v[176:179], v[194:197], v[116:119]
	v_mfma_f32_16x16x32_bf16 v[112:115], v[186:189], v[194:197], v[112:115]
	v_mfma_f32_16x16x32_bf16 v[100:103], v[176:179], v[208:211], v[100:103]
	v_mfma_f32_16x16x32_bf16 v[96:99], v[186:189], v[208:211], v[96:99]
	v_mfma_f32_16x16x32_bf16 v[84:87], v[176:179], v[216:219], v[84:87]
	v_mfma_f32_16x16x32_bf16 v[80:83], v[186:189], v[216:219], v[80:83]
	v_mfma_f32_16x16x32_bf16 v[68:71], v[176:179], v[224:227], v[68:71]
	v_mfma_f32_16x16x32_bf16 v[64:67], v[186:189], v[224:227], v[64:67]
	s_setprio 0
	s_barrier
; #define PG8_STAGE(bufoff, gbase, voff) do { _Pragma("unroll") for (int _i = 0; _i < 2; ++_i) \
;         __builtin_amdgcn_global_load_lds((const unsigned*)((const char*)(gbase) + (voff)[_i]), (PG8_LAS unsigned*)(lds + (bufoff) + ldsw + _i * 8192), 16, 0, 0); } while (0)
; #define PG8_LDA(dst, b, h) do { _Pragma("unroll") for (int m = 0; m < 4; ++m) _Pragma("unroll") for (int k = 0; k < 2; ++k) dst[m][k] = *(const PG8_LAS bf16x8*)(lds + PG8_SA(b, h) + aoff + m * 2048 + k * 1024); } while (0)
; #define PG8_LDB(dst, b, h) do { _Pragma("unroll") for (int n = 0; n < 2; ++n) _Pragma("unroll") for (int k = 0; k < 2; ++k) dst[n][k] = *(const PG8_LAS bf16x8*)(lds + PG8_SB(b, h) + boff + n * 2048 + k * 1024); } while (0)
; #define PG8_MMA(ai, bj, At, Bt) do { __builtin_amdgcn_s_setprio(1); _Pragma("unroll") for (int m = 0; m < 4; ++m) _Pragma("unroll") for (int n = 0; n < 2; ++n) _Pragma("unroll") for (int k = 0; k < 2; ++k) \
;         acc[ai][bj][m][n] = __builtin_amdgcn_mfma_f32_16x16x32_bf16(Bt[n][k], At[m][k], acc[ai][bj][m][n], 0, 0, 0); __builtin_amdgcn_s_setprio(0); } while (0)
; #define PG8_WAIT_V(n) asm volatile("s_waitcnt vmcnt(" #n ")" ::: "memory")
; template <class Epi, class Sched, bool ALIGN_EPI = false, bool SP2 = false>
; __device__ __forceinline__ void gemm_phase(PG8_LAS unsigned char* lds, const Gemm g, const Sched& S, const Epi& E) {
;     ...
;             PG8_LDB(B0, 0, 0); PG8_LDB(B1, 0, 1); PG8_SCHED; PG8_LDA(At, 0, 0); PG8_STAGE(PG8_SA(1, 1), a1 + hstep, voffA);
;             PG8_WAIT_V(8); PG8_WAIT_L(0); PG8_BAR; PG8_MMA(0, 0, At, B0); PG8_MMA(0, 1, At, B1); PG8_BAR; PG8_SCHED;
;             PG8_LDA(At, 0, 1); PG8_STAGE(PG8_SB(0, 0), b2, voffB); PG8_STAGE(PG8_SB(0, 1), b2 + hstep, voffB); PG8_STAGE(PG8_SA(0, 0), a2, voffA);
;             PG8_WAIT_V(8); PG8_WAIT_L(0); PG8_BAR; PG8_MMA(1, 0, At, B0); PG8_MMA(1, 1, At, B1); PG8_BAR; PG8_SCHED;
;             PG8_LDB(B0, 1, 0); PG8_LDB(B1, 1, 1); PG8_SCHED; PG8_LDA(At, 1, 0); PG8_STAGE(PG8_SA(0, 1), a2 + hstep, voffA);
;             PG8_WAIT_V(8); PG8_WAIT_L(0); PG8_BAR; PG8_MMA(0, 0, At, B0); PG8_MMA(0, 1, At, B1); PG8_BAR; PG8_SCHED;
;             PG8_LDA(At, 1, 1); PG8_STAGE(PG8_SB(1, 0), b3, voffB); PG8_STAGE(PG8_SB(1, 1), b3 + hstep, voffB); PG8_STAGE(PG8_SA(1, 0), a3, voffA);
;             PG8_WAIT_V(8); PG8_WAIT_L(0); PG8_BAR; PG8_MMA(1, 0, At, B0); PG8_MMA(1, 1, At, B1); PG8_BAR; PG8_SCHED;
	s_add_i32 s3, s3, s43
	v_lshl_add_u64 v[160:161], v[160:161], 0, s[40:41]
	s_mov_b32 m0, s3
	ds_read_b128 v[190:193], v169 offset:49152
	ds_read_b128 v[194:197], v169 offset:50176
	ds_read_b128 v[198:201], v169 offset:51200
	ds_read_b128 v[208:211], v169 offset:52224
	ds_read_b128 v[212:215], v169 offset:53248
	ds_read_b128 v[216:219], v169 offset:54272
	ds_read_b128 v[220:223], v169 offset:55296
	ds_read_b128 v[224:227], v169 offset:56320
	global_load_lds_dwordx4 v[160:161], off
	s_add_i32 m0, s3, 0x2000
	s_add_u32 s10, s54, 0xb0080
	v_lshl_add_u64 v[160:161], v[202:203], 0, s[40:41]
	s_addc_u32 s11, s55, 0
	s_add_i32 s3, s14, s43
	global_load_lds_dwordx4 v[160:161], off
	v_lshl_add_u64 v[160:161], s[10:11], 0, v[138:139]
	s_mov_b32 m0, s3
	s_nop 0
	global_load_lds_dwordx4 v[160:161], off
	v_lshl_add_u64 v[160:161], s[10:11], 0, v[142:143]
	s_add_i32 m0, s3, 0x2000
	s_nop 0
	global_load_lds_dwordx4 v[160:161], off
	s_waitcnt vmcnt(6)
	s_waitcnt lgkmcnt(0)
	s_barrier
	s_setprio 1
	s_waitcnt lgkmcnt(0)
	v_mfma_f32_16x16x32_bf16 v[60:63], v[128:131], v[190:193], v[60:63]
	v_mfma_f32_16x16x32_bf16 v[56:59], v[152:155], v[190:193], v[56:59]
	v_mfma_f32_16x16x32_bf16 v[44:47], v[128:131], v[198:201], v[44:47]
	v_mfma_f32_16x16x32_bf16 v[40:43], v[152:155], v[198:201], v[40:43]
	v_mfma_f32_16x16x32_bf16 v[28:31], v[128:131], v[212:215], v[28:31]
	v_mfma_f32_16x16x32_bf16 v[24:27], v[152:155], v[212:215], v[24:27]
	v_mfma_f32_16x16x32_bf16 v[12:15], v[128:131], v[220:223], v[12:15]
	v_mfma_f32_16x16x32_bf16 v[8:11], v[152:155], v[220:223], v[8:11]
	v_mfma_f32_16x16x32_bf16 v[60:63], v[132:135], v[194:197], v[60:63]
	v_mfma_f32_16x16x32_bf16 v[56:59], v[156:159], v[194:197], v[56:59]
	v_mfma_f32_16x16x32_bf16 v[44:47], v[132:135], v[208:211], v[44:47]
	v_mfma_f32_16x16x32_bf16 v[40:43], v[156:159], v[208:211], v[40:43]
	v_lshl_add_u64 v[160:161], v[228:229], 0, s[40:41]
	s_mov_b32 m0, s63
	s_nop 0
	global_load_lds_dwordx4 v[160:161], off
	v_mfma_f32_16x16x32_bf16 v[28:31], v[132:135], v[216:219], v[28:31]
	v_mfma_f32_16x16x32_bf16 v[24:27], v[156:159], v[216:219], v[24:27]
	v_mfma_f32_16x16x32_bf16 v[12:15], v[132:135], v[224:227], v[12:15]
	v_mfma_f32_16x16x32_bf16 v[8:11], v[156:159], v[224:227], v[8:11]
	s_setprio 0
	s_setprio 1
	v_mfma_f32_16x16x32_bf16 v[52:55], v[172:175], v[190:193], v[52:55]
	v_mfma_f32_16x16x32_bf16 v[48:51], v[182:185], v[190:193], v[48:51]
	v_mfma_f32_16x16x32_bf16 v[36:39], v[172:175], v[198:201], v[36:39]
	v_mfma_f32_16x16x32_bf16 v[32:35], v[182:185], v[198:201], v[32:35]
	v_mfma_f32_16x16x32_bf16 v[20:23], v[172:175], v[212:215], v[20:23]
	v_mfma_f32_16x16x32_bf16 v[16:19], v[182:185], v[212:215], v[16:19]
	v_mfma_f32_16x16x32_bf16 v[4:7], v[172:175], v[220:223], v[4:7]
	v_mfma_f32_16x16x32_bf16 v[0:3], v[182:185], v[220:223], v[0:3]
	v_mfma_f32_16x16x32_bf16 v[52:55], v[176:179], v[194:197], v[52:55]
	v_mfma_f32_16x16x32_bf16 v[48:51], v[186:189], v[194:197], v[48:51]
	v_mfma_f32_16x16x32_bf16 v[36:39], v[176:179], v[208:211], v[36:39]
	v_mfma_f32_16x16x32_bf16 v[32:35], v[186:189], v[208:211], v[32:35]
	v_lshl_add_u64 v[160:161], v[230:231], 0, s[40:41]
	s_mov_b32 m0, s64
	s_nop 0
	global_load_lds_dwordx4 v[160:161], off
	v_mfma_f32_16x16x32_bf16 v[20:23], v[176:179], v[216:219], v[20:23]
	v_mfma_f32_16x16x32_bf16 v[16:19], v[186:189], v[216:219], v[16:19]
	v_mfma_f32_16x16x32_bf16 v[4:7], v[176:179], v[224:227], v[4:7]
	v_mfma_f32_16x16x32_bf16 v[0:3], v[186:189], v[224:227], v[0:3]
	s_setprio 0
	s_barrier
	s_add_i32 s93, s93, 2
	s_add_u32 s91, s91, 0x100
	s_addc_u32 s92, s92, 0
	s_mov_b64 s[10:11], s[50:51]
.LBB0_269:
	ds_read_b128 v[128:131], v165
	ds_read_b128 v[132:135], v165 offset:1024
	ds_read_b128 v[152:155], v165 offset:2048
	ds_read_b128 v[156:159], v165 offset:3072
	ds_read_b128 v[172:175], v168
	ds_read_b128 v[176:179], v168 offset:1024
	ds_read_b128 v[182:185], v168 offset:2048
	ds_read_b128 v[186:189], v168 offset:3072
	s_add_u32 s50, s10, 0x100
	s_addc_u32 s51, s11, 0
	s_cmp_eq_u32 s93, 40
	s_cselect_b32 s57, s1, s51
	s_cselect_b32 s56, s0, s50
	s_cselect_b32 s55, s49, s92
	s_cselect_b32 s54, s48, s91
	v_lshl_add_u64 v[160:161], s[10:11], 0, v[144:145]
	s_add_i32 m0, s58, 0xc000
	ds_read_b128 v[190:193], v169
	ds_read_b128 v[194:197], v169 offset:1024
	ds_read_b128 v[198:201], v169 offset:2048
	ds_read_b128 v[208:211], v169 offset:3072
	ds_read_b128 v[212:215], v169 offset:4096
	ds_read_b128 v[216:219], v169 offset:5120
	ds_read_b128 v[220:223], v169 offset:6144
	ds_read_b128 v[224:227], v169 offset:7168
	global_load_lds_dwordx4 v[160:161], off
	v_lshl_add_u64 v[160:161], s[10:11], 0, v[146:147]
	s_add_i32 m0, s58, 0xe000
	s_nop 0
	global_load_lds_dwordx4 v[160:161], off
	s_waitcnt vmcnt(8)
	s_waitcnt lgkmcnt(0)
	s_barrier
; #define PG8_STAGE(bufoff, gbase, voff) do { _Pragma("unroll") for (int _i = 0; _i < 2; ++_i) \
;         __builtin_amdgcn_global_load_lds((const unsigned*)((const char*)(gbase) + (voff)[_i]), (PG8_LAS unsigned*)(lds + (bufoff) + ldsw + _i * 8192), 16, 0, 0); } while (0)
; #define PG8_LDA(dst, b, h) do { _Pragma("unroll") for (int m = 0; m < 4; ++m) _Pragma("unroll") for (int k = 0; k < 2; ++k) dst[m][k] = *(const PG8_LAS bf16x8*)(lds + PG8_SA(b, h) + aoff + m * 2048 + k * 1024); } while (0)
; #define PG8_LDB(dst, b, h) do { _Pragma("unroll") for (int n = 0; n < 2; ++n) _Pragma("unroll") for (int k = 0; k < 2; ++k) dst[n][k] = *(const PG8_LAS bf16x8*)(lds + PG8_SB(b, h) + boff + n * 2048 + k * 1024); } while (0)
; #define PG8_MMA(ai, bj, At, Bt) do { __builtin_amdgcn_s_setprio(1); _Pragma("unroll") for (int m = 0; m < 4; ++m) _Pragma("unroll") for (int n = 0; n < 2; ++n) _Pragma("unroll") for (int k = 0; k < 2; ++k) \
;         acc[ai][bj][m][n] = __builtin_amdgcn_mfma_f32_16x16x32_bf16(Bt[n][k], At[m][k], acc[ai][bj][m][n], 0, 0, 0); __builtin_amdgcn_s_setprio(0); } while (0)
; #define PG8_WAIT_V(n) asm volatile("s_waitcnt vmcnt(" #n ")" ::: "memory")
; #define PG8_WAIT_L(n) asm volatile("s_waitcnt lgkmcnt(" #n ")" ::: "memory")
; #define PG8_BAR __builtin_amdgcn_s_barrier()
; #define PG8_SCHED __builtin_amdgcn_sched_barrier(0)
; template <class Epi, class Sched, bool ALIGN_EPI = false, bool SP2 = false>
; __device__ __forceinline__ void gemm_phase(PG8_LAS unsigned char* lds, const Gemm g, const Sched& S, const Epi& E) {
;     ...
;             PG8_LDB(B0, 0, 0); PG8_LDB(B1, 0, 1); PG8_SCHED; PG8_LDA(At, 0, 0); PG8_STAGE(PG8_SA(1, 1), a1 + hstep, voffA);
;             PG8_WAIT_V(8); PG8_WAIT_L(0); PG8_BAR; PG8_MMA(0, 0, At, B0); PG8_MMA(0, 1, At, B1); PG8_BAR; PG8_SCHED;
;             PG8_LDA(At, 0, 1); PG8_STAGE(PG8_SB(0, 0), b2, voffB); PG8_STAGE(PG8_SB(0, 1), b2 + hstep, voffB); PG8_STAGE(PG8_SA(0, 0), a2, voffA);
;             PG8_WAIT_V(8); PG8_WAIT_L(0); PG8_BAR; PG8_MMA(1, 0, At, B0); PG8_MMA(1, 1, At, B1); PG8_BAR; PG8_SCHED;
	s_setprio 1
	s_waitcnt lgkmcnt(0)
	v_mfma_f32_16x16x32_bf16 v[124:127], v[128:131], v[190:193], v[124:127]
	v_mfma_f32_16x16x32_bf16 v[120:123], v[152:155], v[190:193], v[120:123]
	v_mfma_f32_16x16x32_bf16 v[108:111], v[128:131], v[198:201], v[108:111]
	v_mfma_f32_16x16x32_bf16 v[104:107], v[152:155], v[198:201], v[104:107]
	v_mfma_f32_16x16x32_bf16 v[92:95], v[128:131], v[212:215], v[92:95]
	v_mfma_f32_16x16x32_bf16 v[88:91], v[152:155], v[212:215], v[88:91]
	v_mfma_f32_16x16x32_bf16 v[76:79], v[128:131], v[220:223], v[76:79]
	v_mfma_f32_16x16x32_bf16 v[72:75], v[152:155], v[220:223], v[72:75]
	v_mfma_f32_16x16x32_bf16 v[124:127], v[132:135], v[194:197], v[124:127]
	v_mfma_f32_16x16x32_bf16 v[120:123], v[156:159], v[194:197], v[120:123]
	v_mfma_f32_16x16x32_bf16 v[108:111], v[132:135], v[208:211], v[108:111]
	v_mfma_f32_16x16x32_bf16 v[104:107], v[156:159], v[208:211], v[104:107]
	v_mfma_f32_16x16x32_bf16 v[92:95], v[132:135], v[216:219], v[92:95]
	v_mfma_f32_16x16x32_bf16 v[88:91], v[156:159], v[216:219], v[88:91]
	v_mfma_f32_16x16x32_bf16 v[76:79], v[132:135], v[224:227], v[76:79]
	v_mfma_f32_16x16x32_bf16 v[72:75], v[156:159], v[224:227], v[72:75]
	s_setprio 0
	s_setprio 1
	v_mfma_f32_16x16x32_bf16 v[116:119], v[172:175], v[190:193], v[116:119]
	v_mfma_f32_16x16x32_bf16 v[112:115], v[182:185], v[190:193], v[112:115]
	v_mfma_f32_16x16x32_bf16 v[100:103], v[172:175], v[198:201], v[100:103]
	v_mfma_f32_16x16x32_bf16 v[96:99], v[182:185], v[198:201], v[96:99]
	v_mfma_f32_16x16x32_bf16 v[84:87], v[172:175], v[212:215], v[84:87]
	v_mfma_f32_16x16x32_bf16 v[80:83], v[182:185], v[212:215], v[80:83]
	v_mfma_f32_16x16x32_bf16 v[68:71], v[172:175], v[220:223], v[68:71]
	v_mfma_f32_16x16x32_bf16 v[64:67], v[182:185], v[220:223], v[64:67]
	v_mfma_f32_16x16x32_bf16 v[116:119], v[176:179], v[194:197], v[116:119]
	v_mfma_f32_16x16x32_bf16 v[112:115], v[186:189], v[194:197], v[112:115]
	v_mfma_f32_16x16x32_bf16 v[100:103], v[176:179], v[208:211], v[100:103]
	v_mfma_f32_16x16x32_bf16 v[96:99], v[186:189], v[208:211], v[96:99]
	v_mfma_f32_16x16x32_bf16 v[84:87], v[176:179], v[216:219], v[84:87]
	v_mfma_f32_16x16x32_bf16 v[80:83], v[186:189], v[216:219], v[80:83]
	v_mfma_f32_16x16x32_bf16 v[68:71], v[176:179], v[224:227], v[68:71]
	v_mfma_f32_16x16x32_bf16 v[64:67], v[186:189], v[224:227], v[64:67]
	s_setprio 0
	s_barrier
	s_add_i32 s3, s65, s43
	v_lshl_add_u64 v[160:161], s[54:55], 0, v[138:139]
	s_mov_b32 m0, s3
	ds_read_b128 v[190:193], v169 offset:16384
	ds_read_b128 v[194:197], v169 offset:17408
	ds_read_b128 v[198:201], v169 offset:18432
	ds_read_b128 v[208:211], v169 offset:19456
	ds_read_b128 v[212:215], v169 offset:20480
	ds_read_b128 v[216:219], v169 offset:21504
	ds_read_b128 v[220:223], v169 offset:22528
	ds_read_b128 v[224:227], v169 offset:23552
	global_load_lds_dwordx4 v[160:161], off
	s_add_i32 m0, s3, 0x2000
	s_add_u32 s10, s54, 0xb0000
	v_lshl_add_u64 v[202:203], s[54:55], 0, v[142:143]
	s_addc_u32 s11, s55, 0
	s_add_i32 s3, s66, s43
	global_load_lds_dwordx4 v[202:203], off
	v_lshl_add_u64 v[228:229], s[10:11], 0, v[138:139]
	s_mov_b32 m0, s3
	global_load_lds_dwordx4 v[228:229], off
	v_lshl_add_u64 v[228:229], s[10:11], 0, v[142:143]
	s_add_i32 m0, s3, 0x2000
	s_nop 0
	global_load_lds_dwordx4 v[228:229], off
	s_waitcnt vmcnt(6)
	s_waitcnt lgkmcnt(0)
	s_barrier
	s_setprio 1
	s_waitcnt lgkmcnt(0)
	v_mfma_f32_16x16x32_bf16 v[60:63], v[128:131], v[190:193], v[60:63]
	v_mfma_f32_16x16x32_bf16 v[56:59], v[152:155], v[190:193], v[56:59]
	v_mfma_f32_16x16x32_bf16 v[44:47], v[128:131], v[198:201], v[44:47]
	v_mfma_f32_16x16x32_bf16 v[40:43], v[152:155], v[198:201], v[40:43]
	v_mfma_f32_16x16x32_bf16 v[28:31], v[128:131], v[212:215], v[28:31]
	v_mfma_f32_16x16x32_bf16 v[24:27], v[152:155], v[212:215], v[24:27]
	v_mfma_f32_16x16x32_bf16 v[12:15], v[128:131], v[220:223], v[12:15]
	v_mfma_f32_16x16x32_bf16 v[8:11], v[152:155], v[220:223], v[8:11]
	v_mfma_f32_16x16x32_bf16 v[60:63], v[132:135], v[194:197], v[60:63]
	v_mfma_f32_16x16x32_bf16 v[56:59], v[156:159], v[194:197], v[56:59]
	v_mfma_f32_16x16x32_bf16 v[44:47], v[132:135], v[208:211], v[44:47]
	v_mfma_f32_16x16x32_bf16 v[40:43], v[156:159], v[208:211], v[40:43]
	v_lshl_add_u64 v[228:229], s[56:57], 0, v[136:137]
	s_mov_b32 m0, s58
	s_nop 0
	global_load_lds_dwordx4 v[228:229], off
	v_mfma_f32_16x16x32_bf16 v[28:31], v[132:135], v[216:219], v[28:31]
	v_mfma_f32_16x16x32_bf16 v[24:27], v[156:159], v[216:219], v[24:27]
	v_mfma_f32_16x16x32_bf16 v[12:15], v[132:135], v[224:227], v[12:15]
	v_mfma_f32_16x16x32_bf16 v[8:11], v[156:159], v[224:227], v[8:11]
	s_setprio 0
	s_setprio 1
	v_mfma_f32_16x16x32_bf16 v[52:55], v[172:175], v[190:193], v[52:55]
	v_mfma_f32_16x16x32_bf16 v[48:51], v[182:185], v[190:193], v[48:51]
	v_mfma_f32_16x16x32_bf16 v[36:39], v[172:175], v[198:201], v[36:39]
	v_mfma_f32_16x16x32_bf16 v[32:35], v[182:185], v[198:201], v[32:35]
	v_mfma_f32_16x16x32_bf16 v[20:23], v[172:175], v[212:215], v[20:23]
	v_mfma_f32_16x16x32_bf16 v[16:19], v[182:185], v[212:215], v[16:19]
	v_mfma_f32_16x16x32_bf16 v[4:7], v[172:175], v[220:223], v[4:7]
	v_mfma_f32_16x16x32_bf16 v[0:3], v[182:185], v[220:223], v[0:3]
	v_mfma_f32_16x16x32_bf16 v[52:55], v[176:179], v[194:197], v[52:55]
	v_mfma_f32_16x16x32_bf16 v[48:51], v[186:189], v[194:197], v[48:51]
	v_mfma_f32_16x16x32_bf16 v[36:39], v[176:179], v[208:211], v[36:39]
	v_mfma_f32_16x16x32_bf16 v[32:35], v[186:189], v[208:211], v[32:35]
	v_lshl_add_u64 v[230:231], s[56:57], 0, v[140:141]
	s_mov_b32 m0, s59
	s_nop 0
	global_load_lds_dwordx4 v[230:231], off
	v_mfma_f32_16x16x32_bf16 v[20:23], v[176:179], v[216:219], v[20:23]
	v_mfma_f32_16x16x32_bf16 v[16:19], v[186:189], v[216:219], v[16:19]
	v_mfma_f32_16x16x32_bf16 v[4:7], v[176:179], v[224:227], v[4:7]
	v_mfma_f32_16x16x32_bf16 v[0:3], v[186:189], v[224:227], v[0:3]
	s_setprio 0
	s_barrier
; #define PG8_STAGE(bufoff, gbase, voff) do { _Pragma("unroll") for (int _i = 0; _i < 2; ++_i) \
;         __builtin_amdgcn_global_load_lds((const unsigned*)((const char*)(gbase) + (voff)[_i]), (PG8_LAS unsigned*)(lds + (bufoff) + ldsw + _i * 8192), 16, 0, 0); } while (0)
; #define PG8_LDA(dst, b, h) do { _Pragma("unroll") for (int m = 0; m < 4; ++m) _Pragma("unroll") for (int k = 0; k < 2; ++k) dst[m][k] = *(const PG8_LAS bf16x8*)(lds + PG8_SA(b, h) + aoff + m * 2048 + k * 1024); } while (0)
; #define PG8_LDB(dst, b, h) do { _Pragma("unroll") for (int n = 0; n < 2; ++n) _Pragma("unroll") for (int k = 0; k < 2; ++k) dst[n][k] = *(const PG8_LAS bf16x8*)(lds + PG8_SB(b, h) + boff + n * 2048 + k * 1024); } while (0)
; #define PG8_MMA(ai, bj, At, Bt) do { __builtin_amdgcn_s_setprio(1); _Pragma("unroll") for (int m = 0; m < 4; ++m) _Pragma("unroll") for (int n = 0; n < 2; ++n) _Pragma("unroll") for (int k = 0; k < 2; ++k) \
;         acc[ai][bj][m][n] = __builtin_amdgcn_mfma_f32_16x16x32_bf16(Bt[n][k], At[m][k], acc[ai][bj][m][n], 0, 0, 0); __builtin_amdgcn_s_setprio(0); } while (0)
; #define PG8_WAIT_V(n) asm volatile("s_waitcnt vmcnt(" #n ")" ::: "memory")
; #define PG8_WAIT_L(n) asm volatile("s_waitcnt lgkmcnt(" #n ")" ::: "memory")
; #define PG8_BAR __builtin_amdgcn_s_barrier()
; #define PG8_SCHED __builtin_amdgcn_sched_barrier(0)
; template <class Epi, class Sched, bool ALIGN_EPI = false, bool SP2 = false>
; __device__ __forceinline__ void gemm_phase(PG8_LAS unsigned char* lds, const Gemm g, const Sched& S, const Epi& E) {
;     ...
;             PG8_LDB(B0, 1, 0); PG8_LDB(B1, 1, 1); PG8_SCHED; PG8_LDA(At, 1, 0); PG8_STAGE(PG8_SA(0, 1), a2 + hstep, voffA);
;             PG8_WAIT_V(8); PG8_WAIT_L(0); PG8_BAR; PG8_MMA(0, 0, At, B0); PG8_MMA(0, 1, At, B1); PG8_BAR; PG8_SCHED;
	s_add_i32 s3, 0, 0x18000
	s_add_i32 s14, 0, 0x1c000
	v_add_u32_e32 v156, s3, v163
	v_add_u32_e32 v171, s14, v163
	ds_read_b128 v[128:131], v156
	ds_read_b128 v[132:135], v156 offset:1024
	ds_read_b128 v[152:155], v156 offset:2048
	ds_read_b128 v[156:159], v156 offset:3072
	ds_read_b128 v[172:175], v171
	ds_read_b128 v[176:179], v171 offset:1024
	ds_read_b128 v[182:185], v171 offset:2048
	ds_read_b128 v[186:189], v171 offset:3072
	s_add_u32 s10, s56, 0xb0000
	s_addc_u32 s11, s57, 0
	s_mov_b32 m0, s60
	v_lshl_add_u64 v[232:233], s[10:11], 0, v[136:137]
	ds_read_b128 v[190:193], v169 offset:32768
	ds_read_b128 v[194:197], v169 offset:33792
	ds_read_b128 v[198:201], v169 offset:34816
	ds_read_b128 v[208:211], v169 offset:35840
	ds_read_b128 v[212:215], v169 offset:36864
	ds_read_b128 v[216:219], v169 offset:37888
	ds_read_b128 v[220:223], v169 offset:38912
	ds_read_b128 v[224:227], v169 offset:39936
	global_load_lds_dwordx4 v[232:233], off
	v_lshl_add_u64 v[232:233], s[10:11], 0, v[140:141]
	s_mov_b32 m0, s61
	s_nop 0
	global_load_lds_dwordx4 v[232:233], off
	s_waitcnt vmcnt(8)
	s_waitcnt lgkmcnt(0)
	s_barrier
	s_setprio 1
	s_waitcnt lgkmcnt(0)
	v_mfma_f32_16x16x32_bf16 v[124:127], v[128:131], v[190:193], v[124:127]
	v_mfma_f32_16x16x32_bf16 v[120:123], v[152:155], v[190:193], v[120:123]
	v_mfma_f32_16x16x32_bf16 v[108:111], v[128:131], v[198:201], v[108:111]
	v_mfma_f32_16x16x32_bf16 v[104:107], v[152:155], v[198:201], v[104:107]
	v_mfma_f32_16x16x32_bf16 v[92:95], v[128:131], v[212:215], v[92:95]
	v_mfma_f32_16x16x32_bf16 v[88:91], v[152:155], v[212:215], v[88:91]
	v_mfma_f32_16x16x32_bf16 v[76:79], v[128:131], v[220:223], v[76:79]
	v_mfma_f32_16x16x32_bf16 v[72:75], v[152:155], v[220:223], v[72:75]
	v_mfma_f32_16x16x32_bf16 v[124:127], v[132:135], v[194:197], v[124:127]
	v_mfma_f32_16x16x32_bf16 v[120:123], v[156:159], v[194:197], v[120:123]
	v_mfma_f32_16x16x32_bf16 v[108:111], v[132:135], v[208:211], v[108:111]
	v_mfma_f32_16x16x32_bf16 v[104:107], v[156:159], v[208:211], v[104:107]
	v_mfma_f32_16x16x32_bf16 v[92:95], v[132:135], v[216:219], v[92:95]
	v_mfma_f32_16x16x32_bf16 v[88:91], v[156:159], v[216:219], v[88:91]
	v_mfma_f32_16x16x32_bf16 v[76:79], v[132:135], v[224:227], v[76:79]
	v_mfma_f32_16x16x32_bf16 v[72:75], v[156:159], v[224:227], v[72:75]
	s_setprio 0
	s_setprio 1
	v_mfma_f32_16x16x32_bf16 v[116:119], v[172:175], v[190:193], v[116:119]
	v_mfma_f32_16x16x32_bf16 v[112:115], v[182:185], v[190:193], v[112:115]
	v_mfma_f32_16x16x32_bf16 v[100:103], v[172:175], v[198:201], v[100:103]
	v_mfma_f32_16x16x32_bf16 v[96:99], v[182:185], v[198:201], v[96:99]
	v_mfma_f32_16x16x32_bf16 v[84:87], v[172:175], v[212:215], v[84:87]
	v_mfma_f32_16x16x32_bf16 v[80:83], v[182:185], v[212:215], v[80:83]
	v_mfma_f32_16x16x32_bf16 v[68:71], v[172:175], v[220:223], v[68:71]
	v_mfma_f32_16x16x32_bf16 v[64:67], v[182:185], v[220:223], v[64:67]
	v_mfma_f32_16x16x32_bf16 v[116:119], v[176:179], v[194:197], v[116:119]
	v_mfma_f32_16x16x32_bf16 v[112:115], v[186:189], v[194:197], v[112:115]
	v_mfma_f32_16x16x32_bf16 v[100:103], v[176:179], v[208:211], v[100:103]
	v_mfma_f32_16x16x32_bf16 v[96:99], v[186:189], v[208:211], v[96:99]
	v_mfma_f32_16x16x32_bf16 v[84:87], v[176:179], v[216:219], v[84:87]
	v_mfma_f32_16x16x32_bf16 v[80:83], v[186:189], v[216:219], v[80:83]
	v_mfma_f32_16x16x32_bf16 v[68:71], v[176:179], v[224:227], v[68:71]
	v_mfma_f32_16x16x32_bf16 v[64:67], v[186:189], v[224:227], v[64:67]
	s_setprio 0
	s_barrier
; #define PG8_STAGE(bufoff, gbase, voff) do { _Pragma("unroll") for (int _i = 0; _i < 2; ++_i) \
;         __builtin_amdgcn_global_load_lds((const unsigned*)((const char*)(gbase) + (voff)[_i]), (PG8_LAS unsigned*)(lds + (bufoff) + ldsw + _i * 8192), 16, 0, 0); } while (0)
; #define PG8_LDA(dst, b, h) do { _Pragma("unroll") for (int m = 0; m < 4; ++m) _Pragma("unroll") for (int k = 0; k < 2; ++k) dst[m][k] = *(const PG8_LAS bf16x8*)(lds + PG8_SA(b, h) + aoff + m * 2048 + k * 1024); } while (0)
; #define PG8_MMA(ai, bj, At, Bt) do { __builtin_amdgcn_s_setprio(1); _Pragma("unroll") for (int m = 0; m < 4; ++m) _Pragma("unroll") for (int n = 0; n < 2; ++n) _Pragma("unroll") for (int k = 0; k < 2; ++k) \
;         acc[ai][bj][m][n] = __builtin_amdgcn_mfma_f32_16x16x32_bf16(Bt[n][k], At[m][k], acc[ai][bj][m][n], 0, 0, 0); __builtin_amdgcn_s_setprio(0); } while (0)
; #define PG8_WAIT_V(n) asm volatile("s_waitcnt vmcnt(" #n ")" ::: "memory")
; #define PG8_WAIT_L(n) asm volatile("s_waitcnt lgkmcnt(" #n ")" ::: "memory")
; #define PG8_BAR __builtin_amdgcn_s_barrier()
; #define PG8_SCHED __builtin_amdgcn_sched_barrier(0)
; template <class Epi, class Sched, bool ALIGN_EPI = false, bool SP2 = false>
; __device__ __forceinline__ void gemm_phase(PG8_LAS unsigned char* lds, const Gemm g, const Sched& S, const Epi& E) {
;     ...
;             PG8_LDA(At, 1, 1); PG8_STAGE(PG8_SB(1, 0), b3, voffB); PG8_STAGE(PG8_SB(1, 1), b3 + hstep, voffB); PG8_STAGE(PG8_SA(1, 0), a3, voffA);
;             PG8_WAIT_V(8); PG8_WAIT_L(0); PG8_BAR; PG8_MMA(1, 0, At, B0); PG8_MMA(1, 1, At, B1); PG8_BAR; PG8_SCHED;
;     ...
;         if constexpr (ALIGN_EPI) { if (wr == 0) PG8_BAR; }
	s_add_i32 s3, s3, s43
	v_lshl_add_u64 v[160:161], v[160:161], 0, s[40:41]
	s_mov_b32 m0, s3
	ds_read_b128 v[190:193], v169 offset:49152
	ds_read_b128 v[194:197], v169 offset:50176
	ds_read_b128 v[198:201], v169 offset:51200
	ds_read_b128 v[208:211], v169 offset:52224
	ds_read_b128 v[212:215], v169 offset:53248
	ds_read_b128 v[216:219], v169 offset:54272
	ds_read_b128 v[220:223], v169 offset:55296
	ds_read_b128 v[224:227], v169 offset:56320
	global_load_lds_dwordx4 v[160:161], off
	s_add_i32 m0, s3, 0x2000
	s_add_u32 s10, s54, 0xb0080
	v_lshl_add_u64 v[160:161], v[202:203], 0, s[40:41]
	s_addc_u32 s11, s55, 0
	s_add_i32 s3, s14, s43
	global_load_lds_dwordx4 v[160:161], off
	v_lshl_add_u64 v[160:161], s[10:11], 0, v[138:139]
	s_mov_b32 m0, s3
	s_nop 0
	global_load_lds_dwordx4 v[160:161], off
	v_lshl_add_u64 v[160:161], s[10:11], 0, v[142:143]
	s_add_i32 m0, s3, 0x2000
	s_nop 0
	global_load_lds_dwordx4 v[160:161], off
	s_waitcnt vmcnt(6)
	s_waitcnt lgkmcnt(0)
	s_barrier
	s_setprio 1
	s_waitcnt lgkmcnt(0)
	v_mfma_f32_16x16x32_bf16 v[60:63], v[128:131], v[190:193], v[60:63]
	v_mfma_f32_16x16x32_bf16 v[56:59], v[152:155], v[190:193], v[56:59]
	v_mfma_f32_16x16x32_bf16 v[44:47], v[128:131], v[198:201], v[44:47]
	v_mfma_f32_16x16x32_bf16 v[40:43], v[152:155], v[198:201], v[40:43]
	v_mfma_f32_16x16x32_bf16 v[28:31], v[128:131], v[212:215], v[28:31]
	v_mfma_f32_16x16x32_bf16 v[24:27], v[152:155], v[212:215], v[24:27]
	v_mfma_f32_16x16x32_bf16 v[12:15], v[128:131], v[220:223], v[12:15]
	v_mfma_f32_16x16x32_bf16 v[8:11], v[152:155], v[220:223], v[8:11]
	v_mfma_f32_16x16x32_bf16 v[60:63], v[132:135], v[194:197], v[60:63]
	v_mfma_f32_16x16x32_bf16 v[56:59], v[156:159], v[194:197], v[56:59]
	v_mfma_f32_16x16x32_bf16 v[44:47], v[132:135], v[208:211], v[44:47]
	v_mfma_f32_16x16x32_bf16 v[40:43], v[156:159], v[208:211], v[40:43]
	v_lshl_add_u64 v[160:161], v[228:229], 0, s[40:41]
	s_mov_b32 m0, s63
	s_nop 0
	global_load_lds_dwordx4 v[160:161], off
	v_mfma_f32_16x16x32_bf16 v[28:31], v[132:135], v[216:219], v[28:31]
	v_mfma_f32_16x16x32_bf16 v[24:27], v[156:159], v[216:219], v[24:27]
	v_mfma_f32_16x16x32_bf16 v[12:15], v[132:135], v[224:227], v[12:15]
	v_mfma_f32_16x16x32_bf16 v[8:11], v[156:159], v[224:227], v[8:11]
	s_setprio 0
	s_setprio 1
	v_mfma_f32_16x16x32_bf16 v[52:55], v[172:175], v[190:193], v[52:55]
	v_mfma_f32_16x16x32_bf16 v[48:51], v[182:185], v[190:193], v[48:51]
	v_mfma_f32_16x16x32_bf16 v[36:39], v[172:175], v[198:201], v[36:39]
	v_mfma_f32_16x16x32_bf16 v[32:35], v[182:185], v[198:201], v[32:35]
	v_mfma_f32_16x16x32_bf16 v[20:23], v[172:175], v[212:215], v[20:23]
	v_mfma_f32_16x16x32_bf16 v[16:19], v[182:185], v[212:215], v[16:19]
	v_mfma_f32_16x16x32_bf16 v[4:7], v[172:175], v[220:223], v[4:7]
	v_mfma_f32_16x16x32_bf16 v[0:3], v[182:185], v[220:223], v[0:3]
	v_mfma_f32_16x16x32_bf16 v[52:55], v[176:179], v[194:197], v[52:55]
	v_mfma_f32_16x16x32_bf16 v[48:51], v[186:189], v[194:197], v[48:51]
	v_mfma_f32_16x16x32_bf16 v[36:39], v[176:179], v[208:211], v[36:39]
	v_mfma_f32_16x16x32_bf16 v[32:35], v[186:189], v[208:211], v[32:35]
	v_lshl_add_u64 v[160:161], v[230:231], 0, s[40:41]
	s_mov_b32 m0, s64
	s_nop 0
	global_load_lds_dwordx4 v[160:161], off
	v_mfma_f32_16x16x32_bf16 v[20:23], v[176:179], v[216:219], v[20:23]
	v_mfma_f32_16x16x32_bf16 v[16:19], v[186:189], v[216:219], v[16:19]
	v_mfma_f32_16x16x32_bf16 v[4:7], v[176:179], v[224:227], v[4:7]
	v_mfma_f32_16x16x32_bf16 v[0:3], v[186:189], v[224:227], v[0:3]
	s_setprio 0
	s_barrier
	s_add_i32 s93, s93, 2
	s_add_u32 s91, s91, 0x100
	s_addc_u32 s92, s92, 0
	s_cmp_gt_u32 s93, 41
	s_mov_b64 s[10:11], s[50:51]
	s_cbranch_scc0 .LBB0_269
	s_and_b64 vcc, exec, s[44:45]
	s_cbranch_vccz .LBB0_272
	s_barrier

; #define PG8_STAGE(bufoff, gbase, voff) do { _Pragma("unroll") for (int _i = 0; _i < 2; ++_i) \
;         __builtin_amdgcn_global_load_lds((const unsigned*)((const char*)(gbase) + (voff)[_i]), (PG8_LAS unsigned*)(lds + (bufoff) + ldsw + _i * 8192), 16, 0, 0); } while (0)
; #define PG8_LDA(dst, b, h) do { _Pragma("unroll") for (int m = 0; m < 4; ++m) _Pragma("unroll") for (int k = 0; k < 2; ++k) dst[m][k] = *(const PG8_LAS bf16x8*)(lds + PG8_SA(b, h) + aoff + m * 2048 + k * 1024); } while (0)
; #define PG8_LDB(dst, b, h) do { _Pragma("unroll") for (int n = 0; n < 2; ++n) _Pragma("unroll") for (int k = 0; k < 2; ++k) dst[n][k] = *(const PG8_LAS bf16x8*)(lds + PG8_SB(b, h) + boff + n * 2048 + k * 1024); } while (0)
; #define PG8_WAIT_V(n) asm volatile("s_waitcnt vmcnt(" #n ")" ::: "memory")
; #define PG8_WAIT_L(n) asm volatile("s_waitcnt lgkmcnt(" #n ")" ::: "memory")
; #define PG8_BAR __builtin_amdgcn_s_barrier()
; #define PG8_SCHED __builtin_amdgcn_sched_barrier(0)
; template <class Epi, class Sched, bool ALIGN_EPI = false, bool SP2 = false>
; __device__ __forceinline__ void gemm_phase(PG8_LAS unsigned char* lds, const Gemm g, const Sched& S, const Epi& E) {
;     ...
;         const bool has_next = S.next(ui + 1, nxt);
;         const char* nA = has_next ? (const char*)g.A + (size_t)nxt.pm * tstep : cA; const char* nB = has_next ? (const char*)g.Bt + (size_t)nxt.pn * tstep : cB;
;         for (int t = 0; t < nt; t += 2) {
;             const bool last = (t == nt - 2);
;             const char* a1 = cA + (size_t)(t + 1) * kstep;
;             const char* a2 = last ? nA : cA + (size_t)(t + 2) * kstep; const char* b2 = last ? nB : cB + (size_t)(t + 2) * kstep;
;             const char* a3 = a2 + kstep; const char* b3 = b2 + kstep;
;             if (last && has_next) S.a_ready(nxt);
;             if constexpr (SP2) {
;             PG8_LDB(B0, 0, 0); PG8_LDB(B1, 0, 1); PG8_SCHED; PG8_LDA(At, 0, 0); PG8_STAGE(PG8_SA(1, 1), a1 + hstep, voffA);
;             PG8_WAIT_V(8); PG8_WAIT_L(0); PG8_BAR; PG8_MMA(0, 0, At, B0); PG8_MMA(0, 1, At, B1); PG8_BAR; PG8_SCHED;
;             PG8_LDA(At, 0, 1); PG8_STAGE(PG8_SB(0, 0), b2, voffB); PG8_STAGE(PG8_SB(0, 1), b2 + hstep, voffB); PG8_STAGE(PG8_SA(0, 0), a2, voffA);
;             PG8_WAIT_V(8); PG8_WAIT_L(0); PG8_BAR; PG8_MMA(1, 0, At, B0); PG8_MMA(1, 1, At, B1); PG8_BAR; PG8_SCHED;
.LBB0_416:
	s_ashr_i32 s45, s44, 31
	s_lshl_b64 s[14:15], s[44:45], 19
	s_add_u32 s48, s22, s14
	s_addc_u32 s49, s23, s15
	s_and_b64 s[14:15], s[6:7], exec
	s_cselect_b32 s45, s49, s55
	s_cselect_b32 s89, s48, s54
	s_ashr_i32 s41, s40, 31
	s_lshl_b64 s[14:15], s[40:41], 19
	s_add_u32 s50, s84, s14
	s_addc_u32 s51, s85, s15
	s_and_b64 s[14:15], s[6:7], exec
	s_cselect_b32 s41, s51, s57
	s_cselect_b32 s90, s50, s56
	s_add_u32 s54, s54, 0x40080
	s_addc_u32 s55, s55, 0
	s_add_u32 s91, s56, 0x100
	s_addc_u32 s92, s57, 0
	s_mov_b32 s93, -2
	ds_read_b128 v[154:157], v169
	ds_read_b128 v[158:161], v169 offset:1024
	ds_read_b128 v[162:165], v169 offset:2048
	ds_read_b128 v[174:177], v169 offset:3072
	ds_read_b128 v[182:185], v170
	ds_read_b128 v[186:189], v170 offset:1024
	ds_read_b128 v[190:193], v170 offset:2048
	ds_read_b128 v[194:197], v170 offset:3072
	s_add_u32 s3, s54, 0xfffc0080
	s_addc_u32 s14, s55, -1
	s_cmp_eq_u32 s93, 12
	s_cselect_b32 s59, s45, s14
	s_cselect_b32 s58, s89, s3
	s_cselect_b32 s57, s41, s92
	s_cselect_b32 s56, s90, s91
	v_lshl_add_u64 v[178:179], s[54:55], 0, v[146:147]
	s_add_i32 m0, s60, 0xc000
	ds_read_b128 v[198:201], v171
	ds_read_b128 v[208:211], v171 offset:1024
	ds_read_b128 v[212:215], v171 offset:2048
	ds_read_b128 v[216:219], v171 offset:3072
	ds_read_b128 v[220:223], v171 offset:4096
	ds_read_b128 v[224:227], v171 offset:5120
	ds_read_b128 v[228:231], v171 offset:6144
	ds_read_b128 v[232:235], v171 offset:7168
	global_load_lds_dwordx4 v[178:179], off
	v_lshl_add_u64 v[178:179], s[54:55], 0, v[148:149]
	s_add_i32 m0, s60, 0xe000
	s_nop 0
	global_load_lds_dwordx4 v[178:179], off
	s_waitcnt vmcnt(8)
	s_waitcnt lgkmcnt(0)
	s_barrier
	s_setprio 1
	s_waitcnt lgkmcnt(0)
	v_mfma_f32_16x16x32_bf16 v[124:127], v[154:157], v[198:201], 0
	v_mfma_f32_16x16x32_bf16 v[120:123], v[162:165], v[198:201], 0
	v_mfma_f32_16x16x32_bf16 v[116:119], v[154:157], v[212:215], 0
	v_mfma_f32_16x16x32_bf16 v[112:115], v[162:165], v[212:215], 0
	v_mfma_f32_16x16x32_bf16 v[108:111], v[154:157], v[220:223], 0
	v_mfma_f32_16x16x32_bf16 v[104:107], v[162:165], v[220:223], 0
	v_mfma_f32_16x16x32_bf16 v[100:103], v[154:157], v[228:231], 0
	v_mfma_f32_16x16x32_bf16 v[96:99], v[162:165], v[228:231], 0
	v_mfma_f32_16x16x32_bf16 v[124:127], v[158:161], v[208:211], v[124:127]
	v_mfma_f32_16x16x32_bf16 v[120:123], v[174:177], v[208:211], v[120:123]
	v_mfma_f32_16x16x32_bf16 v[116:119], v[158:161], v[216:219], v[116:119]
	v_mfma_f32_16x16x32_bf16 v[112:115], v[174:177], v[216:219], v[112:115]
	v_mfma_f32_16x16x32_bf16 v[108:111], v[158:161], v[224:227], v[108:111]
	v_mfma_f32_16x16x32_bf16 v[104:107], v[174:177], v[224:227], v[104:107]
	v_mfma_f32_16x16x32_bf16 v[100:103], v[158:161], v[232:235], v[100:103]
	v_mfma_f32_16x16x32_bf16 v[96:99], v[174:177], v[232:235], v[96:99]
	s_setprio 0
	s_setprio 1
	v_mfma_f32_16x16x32_bf16 v[68:71], v[182:185], v[198:201], 0
	v_mfma_f32_16x16x32_bf16 v[64:67], v[190:193], v[198:201], 0
	v_mfma_f32_16x16x32_bf16 v[52:55], v[182:185], v[212:215], 0
	v_mfma_f32_16x16x32_bf16 v[48:51], v[190:193], v[212:215], 0
	v_mfma_f32_16x16x32_bf16 v[44:47], v[182:185], v[220:223], 0
	v_mfma_f32_16x16x32_bf16 v[40:43], v[190:193], v[220:223], 0
	v_mfma_f32_16x16x32_bf16 v[36:39], v[182:185], v[228:231], 0
	v_mfma_f32_16x16x32_bf16 v[32:35], v[190:193], v[228:231], 0
	v_mfma_f32_16x16x32_bf16 v[68:71], v[186:189], v[208:211], v[68:71]
	v_mfma_f32_16x16x32_bf16 v[64:67], v[194:197], v[208:211], v[64:67]
	v_mfma_f32_16x16x32_bf16 v[52:55], v[186:189], v[216:219], v[52:55]
	v_mfma_f32_16x16x32_bf16 v[48:51], v[194:197], v[216:219], v[48:51]
	v_mfma_f32_16x16x32_bf16 v[44:47], v[186:189], v[224:227], v[44:47]
	v_mfma_f32_16x16x32_bf16 v[40:43], v[194:197], v[224:227], v[40:43]
	v_mfma_f32_16x16x32_bf16 v[36:39], v[186:189], v[232:235], v[36:39]
	v_mfma_f32_16x16x32_bf16 v[32:35], v[194:197], v[232:235], v[32:35]
	s_setprio 0
	s_barrier
	s_add_i32 s3, s86, s34
	v_lshl_add_u64 v[178:179], s[56:57], 0, v[132:133]
	s_mov_b32 m0, s3
	ds_read_b128 v[198:201], v171 offset:16384
	ds_read_b128 v[208:211], v171 offset:17408
	ds_read_b128 v[212:215], v171 offset:18432
	ds_read_b128 v[216:219], v171 offset:19456
	ds_read_b128 v[220:223], v171 offset:20480
	ds_read_b128 v[224:227], v171 offset:21504
	ds_read_b128 v[228:231], v171 offset:22528
	ds_read_b128 v[232:235], v171 offset:23552
	global_load_lds_dwordx4 v[178:179], off
	s_add_i32 m0, s3, 0x2000
	s_add_u32 s14, s56, 0x40000
	v_lshl_add_u64 v[202:203], s[56:57], 0, v[128:129]
	s_addc_u32 s15, s57, 0
	s_add_i32 s3, s87, s34
	global_load_lds_dwordx4 v[202:203], off
	v_lshl_add_u64 v[236:237], s[14:15], 0, v[132:133]
	s_mov_b32 m0, s3
	global_load_lds_dwordx4 v[236:237], off
	v_lshl_add_u64 v[236:237], s[14:15], 0, v[128:129]
	s_add_i32 m0, s3, 0x2000
	s_nop 0
	global_load_lds_dwordx4 v[236:237], off
	s_waitcnt vmcnt(6)
	s_waitcnt lgkmcnt(0)
	s_barrier
; #define PG8_STAGE(bufoff, gbase, voff) do { _Pragma("unroll") for (int _i = 0; _i < 2; ++_i) \
;         __builtin_amdgcn_global_load_lds((const unsigned*)((const char*)(gbase) + (voff)[_i]), (PG8_LAS unsigned*)(lds + (bufoff) + ldsw + _i * 8192), 16, 0, 0); } while (0)
; #define PG8_LDA(dst, b, h) do { _Pragma("unroll") for (int m = 0; m < 4; ++m) _Pragma("unroll") for (int k = 0; k < 2; ++k) dst[m][k] = *(const PG8_LAS bf16x8*)(lds + PG8_SA(b, h) + aoff + m * 2048 + k * 1024); } while (0)
; #define PG8_LDB(dst, b, h) do { _Pragma("unroll") for (int n = 0; n < 2; ++n) _Pragma("unroll") for (int k = 0; k < 2; ++k) dst[n][k] = *(const PG8_LAS bf16x8*)(lds + PG8_SB(b, h) + boff + n * 2048 + k * 1024); } while (0)
; #define PG8_MMA(ai, bj, At, Bt) do { __builtin_amdgcn_s_setprio(1); _Pragma("unroll") for (int m = 0; m < 4; ++m) _Pragma("unroll") for (int n = 0; n < 2; ++n) _Pragma("unroll") for (int k = 0; k < 2; ++k) \
;         acc[ai][bj][m][n] = __builtin_amdgcn_mfma_f32_16x16x32_bf16(Bt[n][k], At[m][k], acc[ai][bj][m][n], 0, 0, 0); __builtin_amdgcn_s_setprio(0); } while (0)
; #define PG8_WAIT_V(n) asm volatile("s_waitcnt vmcnt(" #n ")" ::: "memory")
; #define PG8_WAIT_L(n) asm volatile("s_waitcnt lgkmcnt(" #n ")" ::: "memory")
; #define PG8_BAR __builtin_amdgcn_s_barrier()
; #define PG8_SCHED __builtin_amdgcn_sched_barrier(0)
; template <class Epi, class Sched, bool ALIGN_EPI = false, bool SP2 = false>
; __device__ __forceinline__ void gemm_phase(PG8_LAS unsigned char* lds, const Gemm g, const Sched& S, const Epi& E) {
;     ...
;             PG8_WAIT_V(8); PG8_WAIT_L(0); PG8_BAR; PG8_MMA(1, 0, At, B0); PG8_MMA(1, 1, At, B1); PG8_BAR; PG8_SCHED;
;             PG8_LDB(B0, 1, 0); PG8_LDB(B1, 1, 1); PG8_SCHED; PG8_LDA(At, 1, 0); PG8_STAGE(PG8_SA(0, 1), a2 + hstep, voffA);
;             PG8_WAIT_V(8); PG8_WAIT_L(0); PG8_BAR; PG8_MMA(0, 0, At, B0); PG8_MMA(0, 1, At, B1); PG8_BAR; PG8_SCHED;
	s_setprio 1
	s_waitcnt lgkmcnt(0)
	v_mfma_f32_16x16x32_bf16 v[92:95], v[154:157], v[198:201], 0
	v_mfma_f32_16x16x32_bf16 v[88:91], v[162:165], v[198:201], 0
	v_mfma_f32_16x16x32_bf16 v[84:87], v[154:157], v[212:215], 0
	v_mfma_f32_16x16x32_bf16 v[80:83], v[162:165], v[212:215], 0
	v_mfma_f32_16x16x32_bf16 v[76:79], v[154:157], v[220:223], 0
	v_mfma_f32_16x16x32_bf16 v[72:75], v[162:165], v[220:223], 0
	v_mfma_f32_16x16x32_bf16 v[60:63], v[154:157], v[228:231], 0
	v_mfma_f32_16x16x32_bf16 v[56:59], v[162:165], v[228:231], 0
	v_mfma_f32_16x16x32_bf16 v[92:95], v[158:161], v[208:211], v[92:95]
	v_mfma_f32_16x16x32_bf16 v[88:91], v[174:177], v[208:211], v[88:91]
	v_mfma_f32_16x16x32_bf16 v[84:87], v[158:161], v[216:219], v[84:87]
	v_mfma_f32_16x16x32_bf16 v[80:83], v[174:177], v[216:219], v[80:83]
	v_lshl_add_u64 v[236:237], s[58:59], 0, v[134:135]
	s_mov_b32 m0, s60
	s_nop 0
	global_load_lds_dwordx4 v[236:237], off
	v_mfma_f32_16x16x32_bf16 v[76:79], v[158:161], v[224:227], v[76:79]
	v_mfma_f32_16x16x32_bf16 v[72:75], v[174:177], v[224:227], v[72:75]
	v_mfma_f32_16x16x32_bf16 v[60:63], v[158:161], v[232:235], v[60:63]
	v_mfma_f32_16x16x32_bf16 v[56:59], v[174:177], v[232:235], v[56:59]
	s_setprio 0
	s_setprio 1
	v_mfma_f32_16x16x32_bf16 v[28:31], v[182:185], v[198:201], 0
	v_mfma_f32_16x16x32_bf16 v[24:27], v[190:193], v[198:201], 0
	v_mfma_f32_16x16x32_bf16 v[20:23], v[182:185], v[212:215], 0
	v_mfma_f32_16x16x32_bf16 v[16:19], v[190:193], v[212:215], 0
	v_mfma_f32_16x16x32_bf16 v[12:15], v[182:185], v[220:223], 0
	v_mfma_f32_16x16x32_bf16 v[8:11], v[190:193], v[220:223], 0
	v_mfma_f32_16x16x32_bf16 v[4:7], v[182:185], v[228:231], 0
	v_mfma_f32_16x16x32_bf16 v[0:3], v[190:193], v[228:231], 0
	v_mfma_f32_16x16x32_bf16 v[28:31], v[186:189], v[208:211], v[28:31]
	v_mfma_f32_16x16x32_bf16 v[24:27], v[194:197], v[208:211], v[24:27]
	v_mfma_f32_16x16x32_bf16 v[20:23], v[186:189], v[216:219], v[20:23]
	v_mfma_f32_16x16x32_bf16 v[16:19], v[194:197], v[216:219], v[16:19]
	v_lshl_add_u64 v[238:239], s[58:59], 0, v[130:131]
	s_mov_b32 m0, s61
	s_nop 0
	global_load_lds_dwordx4 v[238:239], off
	v_mfma_f32_16x16x32_bf16 v[12:15], v[186:189], v[224:227], v[12:15]
	v_mfma_f32_16x16x32_bf16 v[8:11], v[194:197], v[224:227], v[8:11]
	v_mfma_f32_16x16x32_bf16 v[4:7], v[186:189], v[232:235], v[4:7]
	v_mfma_f32_16x16x32_bf16 v[0:3], v[194:197], v[232:235], v[0:3]
	s_setprio 0
	s_barrier
	s_add_i32 s3, 0, 0x18000
	v_add_u32_e32 v136, s3, v143
	s_add_i32 s33, 0, 0x1c000
	ds_read_b128 v[154:157], v136
	ds_read_b128 v[158:161], v136 offset:1024
	ds_read_b128 v[162:165], v136 offset:2048
	ds_read_b128 v[174:177], v136 offset:3072
	v_add_u32_e32 v136, s33, v143
	ds_read_b128 v[182:185], v136
	ds_read_b128 v[186:189], v136 offset:1024
	ds_read_b128 v[190:193], v136 offset:2048
	ds_read_b128 v[194:197], v136 offset:3072
	s_add_u32 s14, s58, 0x40000
	s_addc_u32 s15, s59, 0
	s_mov_b32 m0, s62
	v_lshl_add_u64 v[240:241], s[14:15], 0, v[134:135]
	ds_read_b128 v[198:201], v171 offset:32768
	ds_read_b128 v[208:211], v171 offset:33792
	ds_read_b128 v[212:215], v171 offset:34816
	ds_read_b128 v[216:219], v171 offset:35840
	ds_read_b128 v[220:223], v171 offset:36864
	ds_read_b128 v[224:227], v171 offset:37888
	ds_read_b128 v[228:231], v171 offset:38912
	ds_read_b128 v[232:235], v171 offset:39936
	global_load_lds_dwordx4 v[240:241], off
	v_lshl_add_u64 v[240:241], s[14:15], 0, v[130:131]
	s_mov_b32 m0, s63
	s_nop 0
	global_load_lds_dwordx4 v[240:241], off
	s_waitcnt vmcnt(8)
	s_waitcnt lgkmcnt(0)
	s_barrier
	s_setprio 1
	s_waitcnt lgkmcnt(0)
	v_mfma_f32_16x16x32_bf16 v[124:127], v[154:157], v[198:201], v[124:127]
	v_mfma_f32_16x16x32_bf16 v[120:123], v[162:165], v[198:201], v[120:123]
	v_mfma_f32_16x16x32_bf16 v[116:119], v[154:157], v[212:215], v[116:119]
	v_mfma_f32_16x16x32_bf16 v[112:115], v[162:165], v[212:215], v[112:115]
	v_mfma_f32_16x16x32_bf16 v[108:111], v[154:157], v[220:223], v[108:111]
	v_mfma_f32_16x16x32_bf16 v[104:107], v[162:165], v[220:223], v[104:107]
	v_mfma_f32_16x16x32_bf16 v[100:103], v[154:157], v[228:231], v[100:103]
	v_mfma_f32_16x16x32_bf16 v[96:99], v[162:165], v[228:231], v[96:99]
	v_mfma_f32_16x16x32_bf16 v[124:127], v[158:161], v[208:211], v[124:127]
	v_mfma_f32_16x16x32_bf16 v[120:123], v[174:177], v[208:211], v[120:123]
	v_mfma_f32_16x16x32_bf16 v[116:119], v[158:161], v[216:219], v[116:119]
	v_mfma_f32_16x16x32_bf16 v[112:115], v[174:177], v[216:219], v[112:115]
	v_mfma_f32_16x16x32_bf16 v[108:111], v[158:161], v[224:227], v[108:111]
	v_mfma_f32_16x16x32_bf16 v[104:107], v[174:177], v[224:227], v[104:107]
	v_mfma_f32_16x16x32_bf16 v[100:103], v[158:161], v[232:235], v[100:103]
	v_mfma_f32_16x16x32_bf16 v[96:99], v[174:177], v[232:235], v[96:99]
	s_setprio 0
	s_setprio 1
	v_mfma_f32_16x16x32_bf16 v[68:71], v[182:185], v[198:201], v[68:71]
	v_mfma_f32_16x16x32_bf16 v[64:67], v[190:193], v[198:201], v[64:67]
	v_mfma_f32_16x16x32_bf16 v[52:55], v[182:185], v[212:215], v[52:55]
	v_mfma_f32_16x16x32_bf16 v[48:51], v[190:193], v[212:215], v[48:51]
	v_mfma_f32_16x16x32_bf16 v[44:47], v[182:185], v[220:223], v[44:47]
	v_mfma_f32_16x16x32_bf16 v[40:43], v[190:193], v[220:223], v[40:43]
	v_mfma_f32_16x16x32_bf16 v[36:39], v[182:185], v[228:231], v[36:39]
	v_mfma_f32_16x16x32_bf16 v[32:35], v[190:193], v[228:231], v[32:35]
	v_mfma_f32_16x16x32_bf16 v[68:71], v[186:189], v[208:211], v[68:71]
	v_mfma_f32_16x16x32_bf16 v[64:67], v[194:197], v[208:211], v[64:67]
	v_mfma_f32_16x16x32_bf16 v[52:55], v[186:189], v[216:219], v[52:55]
	v_mfma_f32_16x16x32_bf16 v[48:51], v[194:197], v[216:219], v[48:51]
	v_mfma_f32_16x16x32_bf16 v[44:47], v[186:189], v[224:227], v[44:47]
	v_mfma_f32_16x16x32_bf16 v[40:43], v[194:197], v[224:227], v[40:43]
	v_mfma_f32_16x16x32_bf16 v[36:39], v[186:189], v[232:235], v[36:39]
	v_mfma_f32_16x16x32_bf16 v[32:35], v[194:197], v[232:235], v[32:35]
	s_setprio 0
	s_barrier
; #define PG8_STAGE(bufoff, gbase, voff) do { _Pragma("unroll") for (int _i = 0; _i < 2; ++_i) \
;         __builtin_amdgcn_global_load_lds((const unsigned*)((const char*)(gbase) + (voff)[_i]), (PG8_LAS unsigned*)(lds + (bufoff) + ldsw + _i * 8192), 16, 0, 0); } while (0)
; #define PG8_LDA(dst, b, h) do { _Pragma("unroll") for (int m = 0; m < 4; ++m) _Pragma("unroll") for (int k = 0; k < 2; ++k) dst[m][k] = *(const PG8_LAS bf16x8*)(lds + PG8_SA(b, h) + aoff + m * 2048 + k * 1024); } while (0)
; #define PG8_LDB(dst, b, h) do { _Pragma("unroll") for (int n = 0; n < 2; ++n) _Pragma("unroll") for (int k = 0; k < 2; ++k) dst[n][k] = *(const PG8_LAS bf16x8*)(lds + PG8_SB(b, h) + boff + n * 2048 + k * 1024); } while (0)
; #define PG8_MMA(ai, bj, At, Bt) do { __builtin_amdgcn_s_setprio(1); _Pragma("unroll") for (int m = 0; m < 4; ++m) _Pragma("unroll") for (int n = 0; n < 2; ++n) _Pragma("unroll") for (int k = 0; k < 2; ++k) \
;         acc[ai][bj][m][n] = __builtin_amdgcn_mfma_f32_16x16x32_bf16(Bt[n][k], At[m][k], acc[ai][bj][m][n], 0, 0, 0); __builtin_amdgcn_s_setprio(0); } while (0)
; #define PG8_WAIT_V(n) asm volatile("s_waitcnt vmcnt(" #n ")" ::: "memory")
; template <class Epi, class Sched, bool ALIGN_EPI = false, bool SP2 = false>
; __device__ __forceinline__ void gemm_phase(PG8_LAS unsigned char* lds, const Gemm g, const Sched& S, const Epi& E) {
;     ...
;             PG8_LDB(B0, 0, 0); PG8_LDB(B1, 0, 1); PG8_SCHED; PG8_LDA(At, 0, 0); PG8_STAGE(PG8_SA(1, 1), a1 + hstep, voffA);
;             PG8_WAIT_V(8); PG8_WAIT_L(0); PG8_BAR; PG8_MMA(0, 0, At, B0); PG8_MMA(0, 1, At, B1); PG8_BAR; PG8_SCHED;
;             PG8_LDA(At, 0, 1); PG8_STAGE(PG8_SB(0, 0), b2, voffB); PG8_STAGE(PG8_SB(0, 1), b2 + hstep, voffB); PG8_STAGE(PG8_SA(0, 0), a2, voffA);
;             PG8_WAIT_V(8); PG8_WAIT_L(0); PG8_BAR; PG8_MMA(1, 0, At, B0); PG8_MMA(1, 1, At, B1); PG8_BAR; PG8_SCHED;
;             PG8_LDB(B0, 1, 0); PG8_LDB(B1, 1, 1); PG8_SCHED; PG8_LDA(At, 1, 0); PG8_STAGE(PG8_SA(0, 1), a2 + hstep, voffA);
;             PG8_WAIT_V(8); PG8_WAIT_L(0); PG8_BAR; PG8_MMA(0, 0, At, B0); PG8_MMA(0, 1, At, B1); PG8_BAR; PG8_SCHED;
;             PG8_LDA(At, 1, 1); PG8_STAGE(PG8_SB(1, 0), b3, voffB); PG8_STAGE(PG8_SB(1, 1), b3 + hstep, voffB); PG8_STAGE(PG8_SA(1, 0), a3, voffA);
;             PG8_WAIT_V(8); PG8_WAIT_L(0); PG8_BAR; PG8_MMA(1, 0, At, B0); PG8_MMA(1, 1, At, B1); PG8_BAR; PG8_SCHED;
	s_add_i32 s3, s3, s34
	v_lshl_add_u64 v[178:179], v[178:179], 0, s[8:9]
	s_mov_b32 m0, s3
	ds_read_b128 v[198:201], v171 offset:49152
	ds_read_b128 v[208:211], v171 offset:50176
	ds_read_b128 v[212:215], v171 offset:51200
	ds_read_b128 v[216:219], v171 offset:52224
	ds_read_b128 v[220:223], v171 offset:53248
	ds_read_b128 v[224:227], v171 offset:54272
	ds_read_b128 v[228:231], v171 offset:55296
	ds_read_b128 v[232:235], v171 offset:56320
	global_load_lds_dwordx4 v[178:179], off
	s_add_i32 m0, s3, 0x2000
	s_add_u32 s14, s56, 0x40080
	v_lshl_add_u64 v[178:179], v[202:203], 0, s[8:9]
	s_addc_u32 s15, s57, 0
	s_add_i32 s3, s33, s34
	global_load_lds_dwordx4 v[178:179], off
	v_lshl_add_u64 v[178:179], s[14:15], 0, v[132:133]
	s_mov_b32 m0, s3
	s_nop 0
	global_load_lds_dwordx4 v[178:179], off
	v_lshl_add_u64 v[178:179], s[14:15], 0, v[128:129]
	s_add_i32 m0, s3, 0x2000
	s_nop 0
	global_load_lds_dwordx4 v[178:179], off
	s_waitcnt vmcnt(6)
	s_waitcnt lgkmcnt(0)
	s_barrier
	s_setprio 1
	s_waitcnt lgkmcnt(0)
	v_mfma_f32_16x16x32_bf16 v[92:95], v[154:157], v[198:201], v[92:95]
	v_mfma_f32_16x16x32_bf16 v[88:91], v[162:165], v[198:201], v[88:91]
	v_mfma_f32_16x16x32_bf16 v[84:87], v[154:157], v[212:215], v[84:87]
	v_mfma_f32_16x16x32_bf16 v[80:83], v[162:165], v[212:215], v[80:83]
	v_mfma_f32_16x16x32_bf16 v[76:79], v[154:157], v[220:223], v[76:79]
	v_mfma_f32_16x16x32_bf16 v[72:75], v[162:165], v[220:223], v[72:75]
	v_mfma_f32_16x16x32_bf16 v[60:63], v[154:157], v[228:231], v[60:63]
	v_mfma_f32_16x16x32_bf16 v[56:59], v[162:165], v[228:231], v[56:59]
	v_mfma_f32_16x16x32_bf16 v[92:95], v[158:161], v[208:211], v[92:95]
	v_mfma_f32_16x16x32_bf16 v[88:91], v[174:177], v[208:211], v[88:91]
	v_mfma_f32_16x16x32_bf16 v[84:87], v[158:161], v[216:219], v[84:87]
	v_mfma_f32_16x16x32_bf16 v[80:83], v[174:177], v[216:219], v[80:83]
	v_lshl_add_u64 v[178:179], v[236:237], 0, s[8:9]
	s_mov_b32 m0, s66
	s_nop 0
	global_load_lds_dwordx4 v[178:179], off
	v_mfma_f32_16x16x32_bf16 v[76:79], v[158:161], v[224:227], v[76:79]
	v_mfma_f32_16x16x32_bf16 v[72:75], v[174:177], v[224:227], v[72:75]
	v_mfma_f32_16x16x32_bf16 v[60:63], v[158:161], v[232:235], v[60:63]
	v_mfma_f32_16x16x32_bf16 v[56:59], v[174:177], v[232:235], v[56:59]
	s_setprio 0
	s_setprio 1
	v_mfma_f32_16x16x32_bf16 v[28:31], v[182:185], v[198:201], v[28:31]
	v_mfma_f32_16x16x32_bf16 v[24:27], v[190:193], v[198:201], v[24:27]
	v_mfma_f32_16x16x32_bf16 v[20:23], v[182:185], v[212:215], v[20:23]
	v_mfma_f32_16x16x32_bf16 v[16:19], v[190:193], v[212:215], v[16:19]
	v_mfma_f32_16x16x32_bf16 v[12:15], v[182:185], v[220:223], v[12:15]
	v_mfma_f32_16x16x32_bf16 v[8:11], v[190:193], v[220:223], v[8:11]
	v_mfma_f32_16x16x32_bf16 v[4:7], v[182:185], v[228:231], v[4:7]
	v_mfma_f32_16x16x32_bf16 v[0:3], v[190:193], v[228:231], v[0:3]
	v_mfma_f32_16x16x32_bf16 v[28:31], v[186:189], v[208:211], v[28:31]
	v_mfma_f32_16x16x32_bf16 v[24:27], v[194:197], v[208:211], v[24:27]
	v_mfma_f32_16x16x32_bf16 v[20:23], v[186:189], v[216:219], v[20:23]
	v_mfma_f32_16x16x32_bf16 v[16:19], v[194:197], v[216:219], v[16:19]
	v_lshl_add_u64 v[178:179], v[238:239], 0, s[8:9]
	s_mov_b32 m0, s67
	s_nop 0
	global_load_lds_dwordx4 v[178:179], off
	v_mfma_f32_16x16x32_bf16 v[12:15], v[186:189], v[224:227], v[12:15]
	v_mfma_f32_16x16x32_bf16 v[8:11], v[194:197], v[224:227], v[8:11]
	v_mfma_f32_16x16x32_bf16 v[4:7], v[186:189], v[232:235], v[4:7]
	v_mfma_f32_16x16x32_bf16 v[0:3], v[194:197], v[232:235], v[0:3]
	s_setprio 0
	s_barrier
	s_add_i32 s93, s93, 2
	s_add_u32 s54, s54, 0x100
	s_addc_u32 s55, s55, 0
	s_add_u32 s91, s91, 0x100
	s_addc_u32 s92, s92, 0
.LBB0_417:
	ds_read_b128 v[154:157], v169
	ds_read_b128 v[158:161], v169 offset:1024
	ds_read_b128 v[162:165], v169 offset:2048
	ds_read_b128 v[174:177], v169 offset:3072
	ds_read_b128 v[182:185], v170
	ds_read_b128 v[186:189], v170 offset:1024
	ds_read_b128 v[190:193], v170 offset:2048
	ds_read_b128 v[194:197], v170 offset:3072
	s_add_u32 s3, s54, 0xfffc0080
	s_addc_u32 s14, s55, -1
	s_cmp_eq_u32 s93, 12
	s_cselect_b32 s59, s45, s14
	s_cselect_b32 s58, s89, s3
	s_cselect_b32 s57, s41, s92
	s_cselect_b32 s56, s90, s91
	v_lshl_add_u64 v[178:179], s[54:55], 0, v[146:147]
	s_add_i32 m0, s60, 0xc000
	ds_read_b128 v[198:201], v171
	ds_read_b128 v[208:211], v171 offset:1024
	ds_read_b128 v[212:215], v171 offset:2048
	ds_read_b128 v[216:219], v171 offset:3072
	ds_read_b128 v[220:223], v171 offset:4096
	ds_read_b128 v[224:227], v171 offset:5120
	ds_read_b128 v[228:231], v171 offset:6144
	ds_read_b128 v[232:235], v171 offset:7168
	global_load_lds_dwordx4 v[178:179], off
	v_lshl_add_u64 v[178:179], s[54:55], 0, v[148:149]
	s_add_i32 m0, s60, 0xe000
	s_nop 0
	global_load_lds_dwordx4 v[178:179], off
	s_waitcnt vmcnt(8)
	s_waitcnt lgkmcnt(0)
	s_barrier
; #define PG8_STAGE(bufoff, gbase, voff) do { _Pragma("unroll") for (int _i = 0; _i < 2; ++_i) \
;         __builtin_amdgcn_global_load_lds((const unsigned*)((const char*)(gbase) + (voff)[_i]), (PG8_LAS unsigned*)(lds + (bufoff) + ldsw + _i * 8192), 16, 0, 0); } while (0)
; #define PG8_LDA(dst, b, h) do { _Pragma("unroll") for (int m = 0; m < 4; ++m) _Pragma("unroll") for (int k = 0; k < 2; ++k) dst[m][k] = *(const PG8_LAS bf16x8*)(lds + PG8_SA(b, h) + aoff + m * 2048 + k * 1024); } while (0)
; #define PG8_LDB(dst, b, h) do { _Pragma("unroll") for (int n = 0; n < 2; ++n) _Pragma("unroll") for (int k = 0; k < 2; ++k) dst[n][k] = *(const PG8_LAS bf16x8*)(lds + PG8_SB(b, h) + boff + n * 2048 + k * 1024); } while (0)
; #define PG8_MMA(ai, bj, At, Bt) do { __builtin_amdgcn_s_setprio(1); _Pragma("unroll") for (int m = 0; m < 4; ++m) _Pragma("unroll") for (int n = 0; n < 2; ++n) _Pragma("unroll") for (int k = 0; k < 2; ++k) \
;         acc[ai][bj][m][n] = __builtin_amdgcn_mfma_f32_16x16x32_bf16(Bt[n][k], At[m][k], acc[ai][bj][m][n], 0, 0, 0); __builtin_amdgcn_s_setprio(0); } while (0)
; #define PG8_WAIT_V(n) asm volatile("s_waitcnt vmcnt(" #n ")" ::: "memory")
; #define PG8_WAIT_L(n) asm volatile("s_waitcnt lgkmcnt(" #n ")" ::: "memory")
; #define PG8_BAR __builtin_amdgcn_s_barrier()
; #define PG8_SCHED __builtin_amdgcn_sched_barrier(0)
; template <class Epi, class Sched, bool ALIGN_EPI = false, bool SP2 = false>
; __device__ __forceinline__ void gemm_phase(PG8_LAS unsigned char* lds, const Gemm g, const Sched& S, const Epi& E) {
;     ...
;             PG8_LDB(B0, 0, 0); PG8_LDB(B1, 0, 1); PG8_SCHED; PG8_LDA(At, 0, 0); PG8_STAGE(PG8_SA(1, 1), a1 + hstep, voffA);
;             PG8_WAIT_V(8); PG8_WAIT_L(0); PG8_BAR; PG8_MMA(0, 0, At, B0); PG8_MMA(0, 1, At, B1); PG8_BAR; PG8_SCHED;
;             PG8_LDA(At, 0, 1); PG8_STAGE(PG8_SB(0, 0), b2, voffB); PG8_STAGE(PG8_SB(0, 1), b2 + hstep, voffB); PG8_STAGE(PG8_SA(0, 0), a2, voffA);
;             PG8_WAIT_V(8); PG8_WAIT_L(0); PG8_BAR; PG8_MMA(1, 0, At, B0); PG8_MMA(1, 1, At, B1); PG8_BAR; PG8_SCHED;
	s_setprio 1
	s_waitcnt lgkmcnt(0)
	v_mfma_f32_16x16x32_bf16 v[124:127], v[154:157], v[198:201], v[124:127]
	v_mfma_f32_16x16x32_bf16 v[120:123], v[162:165], v[198:201], v[120:123]
	v_mfma_f32_16x16x32_bf16 v[116:119], v[154:157], v[212:215], v[116:119]
	v_mfma_f32_16x16x32_bf16 v[112:115], v[162:165], v[212:215], v[112:115]
	v_mfma_f32_16x16x32_bf16 v[108:111], v[154:157], v[220:223], v[108:111]
	v_mfma_f32_16x16x32_bf16 v[104:107], v[162:165], v[220:223], v[104:107]
	v_mfma_f32_16x16x32_bf16 v[100:103], v[154:157], v[228:231], v[100:103]
	v_mfma_f32_16x16x32_bf16 v[96:99], v[162:165], v[228:231], v[96:99]
	v_mfma_f32_16x16x32_bf16 v[124:127], v[158:161], v[208:211], v[124:127]
	v_mfma_f32_16x16x32_bf16 v[120:123], v[174:177], v[208:211], v[120:123]
	v_mfma_f32_16x16x32_bf16 v[116:119], v[158:161], v[216:219], v[116:119]
	v_mfma_f32_16x16x32_bf16 v[112:115], v[174:177], v[216:219], v[112:115]
	v_mfma_f32_16x16x32_bf16 v[108:111], v[158:161], v[224:227], v[108:111]
	v_mfma_f32_16x16x32_bf16 v[104:107], v[174:177], v[224:227], v[104:107]
	v_mfma_f32_16x16x32_bf16 v[100:103], v[158:161], v[232:235], v[100:103]
	v_mfma_f32_16x16x32_bf16 v[96:99], v[174:177], v[232:235], v[96:99]
	s_setprio 0
	s_setprio 1
	v_mfma_f32_16x16x32_bf16 v[68:71], v[182:185], v[198:201], v[68:71]
	v_mfma_f32_16x16x32_bf16 v[64:67], v[190:193], v[198:201], v[64:67]
	v_mfma_f32_16x16x32_bf16 v[52:55], v[182:185], v[212:215], v[52:55]
	v_mfma_f32_16x16x32_bf16 v[48:51], v[190:193], v[212:215], v[48:51]
	v_mfma_f32_16x16x32_bf16 v[44:47], v[182:185], v[220:223], v[44:47]
	v_mfma_f32_16x16x32_bf16 v[40:43], v[190:193], v[220:223], v[40:43]
	v_mfma_f32_16x16x32_bf16 v[36:39], v[182:185], v[228:231], v[36:39]
	v_mfma_f32_16x16x32_bf16 v[32:35], v[190:193], v[228:231], v[32:35]
	v_mfma_f32_16x16x32_bf16 v[68:71], v[186:189], v[208:211], v[68:71]
	v_mfma_f32_16x16x32_bf16 v[64:67], v[194:197], v[208:211], v[64:67]
	v_mfma_f32_16x16x32_bf16 v[52:55], v[186:189], v[216:219], v[52:55]
	v_mfma_f32_16x16x32_bf16 v[48:51], v[194:197], v[216:219], v[48:51]
	v_mfma_f32_16x16x32_bf16 v[44:47], v[186:189], v[224:227], v[44:47]
	v_mfma_f32_16x16x32_bf16 v[40:43], v[194:197], v[224:227], v[40:43]
	v_mfma_f32_16x16x32_bf16 v[36:39], v[186:189], v[232:235], v[36:39]
	v_mfma_f32_16x16x32_bf16 v[32:35], v[194:197], v[232:235], v[32:35]
	s_setprio 0
	s_barrier
	s_add_i32 s3, s86, s34
	v_lshl_add_u64 v[178:179], s[56:57], 0, v[132:133]
	s_mov_b32 m0, s3
	ds_read_b128 v[198:201], v171 offset:16384
	ds_read_b128 v[208:211], v171 offset:17408
	ds_read_b128 v[212:215], v171 offset:18432
	ds_read_b128 v[216:219], v171 offset:19456
	ds_read_b128 v[220:223], v171 offset:20480
	ds_read_b128 v[224:227], v171 offset:21504
	ds_read_b128 v[228:231], v171 offset:22528
	ds_read_b128 v[232:235], v171 offset:23552
	global_load_lds_dwordx4 v[178:179], off
	s_add_i32 m0, s3, 0x2000
	s_add_u32 s14, s56, 0x40000
	v_lshl_add_u64 v[202:203], s[56:57], 0, v[128:129]
	s_addc_u32 s15, s57, 0
	s_add_i32 s3, s87, s34
	global_load_lds_dwordx4 v[202:203], off
	v_lshl_add_u64 v[236:237], s[14:15], 0, v[132:133]
	s_mov_b32 m0, s3
	global_load_lds_dwordx4 v[236:237], off
	v_lshl_add_u64 v[236:237], s[14:15], 0, v[128:129]
	s_add_i32 m0, s3, 0x2000
	s_nop 0
	global_load_lds_dwordx4 v[236:237], off
	s_waitcnt vmcnt(6)
	s_waitcnt lgkmcnt(0)
	s_barrier
	s_setprio 1
	s_waitcnt lgkmcnt(0)
	v_mfma_f32_16x16x32_bf16 v[92:95], v[154:157], v[198:201], v[92:95]
	v_mfma_f32_16x16x32_bf16 v[88:91], v[162:165], v[198:201], v[88:91]
	v_mfma_f32_16x16x32_bf16 v[84:87], v[154:157], v[212:215], v[84:87]
	v_mfma_f32_16x16x32_bf16 v[80:83], v[162:165], v[212:215], v[80:83]
	v_mfma_f32_16x16x32_bf16 v[76:79], v[154:157], v[220:223], v[76:79]
	v_mfma_f32_16x16x32_bf16 v[72:75], v[162:165], v[220:223], v[72:75]
	v_mfma_f32_16x16x32_bf16 v[60:63], v[154:157], v[228:231], v[60:63]
	v_mfma_f32_16x16x32_bf16 v[56:59], v[162:165], v[228:231], v[56:59]
	v_mfma_f32_16x16x32_bf16 v[92:95], v[158:161], v[208:211], v[92:95]
	v_mfma_f32_16x16x32_bf16 v[88:91], v[174:177], v[208:211], v[88:91]
	v_mfma_f32_16x16x32_bf16 v[84:87], v[158:161], v[216:219], v[84:87]
	v_mfma_f32_16x16x32_bf16 v[80:83], v[174:177], v[216:219], v[80:83]
	v_lshl_add_u64 v[236:237], s[58:59], 0, v[134:135]
	s_mov_b32 m0, s60
	s_nop 0
	global_load_lds_dwordx4 v[236:237], off
	v_mfma_f32_16x16x32_bf16 v[76:79], v[158:161], v[224:227], v[76:79]
	v_mfma_f32_16x16x32_bf16 v[72:75], v[174:177], v[224:227], v[72:75]
	v_mfma_f32_16x16x32_bf16 v[60:63], v[158:161], v[232:235], v[60:63]
	v_mfma_f32_16x16x32_bf16 v[56:59], v[174:177], v[232:235], v[56:59]
	s_setprio 0
	s_setprio 1
	v_mfma_f32_16x16x32_bf16 v[28:31], v[182:185], v[198:201], v[28:31]
	v_mfma_f32_16x16x32_bf16 v[24:27], v[190:193], v[198:201], v[24:27]
	v_mfma_f32_16x16x32_bf16 v[20:23], v[182:185], v[212:215], v[20:23]
	v_mfma_f32_16x16x32_bf16 v[16:19], v[190:193], v[212:215], v[16:19]
	v_mfma_f32_16x16x32_bf16 v[12:15], v[182:185], v[220:223], v[12:15]
	v_mfma_f32_16x16x32_bf16 v[8:11], v[190:193], v[220:223], v[8:11]
	v_mfma_f32_16x16x32_bf16 v[4:7], v[182:185], v[228:231], v[4:7]
	v_mfma_f32_16x16x32_bf16 v[0:3], v[190:193], v[228:231], v[0:3]
	v_mfma_f32_16x16x32_bf16 v[28:31], v[186:189], v[208:211], v[28:31]
	v_mfma_f32_16x16x32_bf16 v[24:27], v[194:197], v[208:211], v[24:27]
	v_mfma_f32_16x16x32_bf16 v[20:23], v[186:189], v[216:219], v[20:23]
	v_mfma_f32_16x16x32_bf16 v[16:19], v[194:197], v[216:219], v[16:19]
	v_lshl_add_u64 v[238:239], s[58:59], 0, v[130:131]
	s_mov_b32 m0, s61
	s_nop 0
	global_load_lds_dwordx4 v[238:239], off
	v_mfma_f32_16x16x32_bf16 v[12:15], v[186:189], v[224:227], v[12:15]
	v_mfma_f32_16x16x32_bf16 v[8:11], v[194:197], v[224:227], v[8:11]
	v_mfma_f32_16x16x32_bf16 v[4:7], v[186:189], v[232:235], v[4:7]
	v_mfma_f32_16x16x32_bf16 v[0:3], v[194:197], v[232:235], v[0:3]
	s_setprio 0
	s_barrier
; #define PG8_STAGE(bufoff, gbase, voff) do { _Pragma("unroll") for (int _i = 0; _i < 2; ++_i) \
;         __builtin_amdgcn_global_load_lds((const unsigned*)((const char*)(gbase) + (voff)[_i]), (PG8_LAS unsigned*)(lds + (bufoff) + ldsw + _i * 8192), 16, 0, 0); } while (0)
; #define PG8_LDA(dst, b, h) do { _Pragma("unroll") for (int m = 0; m < 4; ++m) _Pragma("unroll") for (int k = 0; k < 2; ++k) dst[m][k] = *(const PG8_LAS bf16x8*)(lds + PG8_SA(b, h) + aoff + m * 2048 + k * 1024); } while (0)
; #define PG8_LDB(dst, b, h) do { _Pragma("unroll") for (int n = 0; n < 2; ++n) _Pragma("unroll") for (int k = 0; k < 2; ++k) dst[n][k] = *(const PG8_LAS bf16x8*)(lds + PG8_SB(b, h) + boff + n * 2048 + k * 1024); } while (0)
; #define PG8_MMA(ai, bj, At, Bt) do { __builtin_amdgcn_s_setprio(1); _Pragma("unroll") for (int m = 0; m < 4; ++m) _Pragma("unroll") for (int n = 0; n < 2; ++n) _Pragma("unroll") for (int k = 0; k < 2; ++k) \
;         acc[ai][bj][m][n] = __builtin_amdgcn_mfma_f32_16x16x32_bf16(Bt[n][k], At[m][k], acc[ai][bj][m][n], 0, 0, 0); __builtin_amdgcn_s_setprio(0); } while (0)
; #define PG8_WAIT_V(n) asm volatile("s_waitcnt vmcnt(" #n ")" ::: "memory")
; #define PG8_WAIT_L(n) asm volatile("s_waitcnt lgkmcnt(" #n ")" ::: "memory")
; #define PG8_BAR __builtin_amdgcn_s_barrier()
; #define PG8_SCHED __builtin_amdgcn_sched_barrier(0)
; template <class Epi, class Sched, bool ALIGN_EPI = false, bool SP2 = false>
; __device__ __forceinline__ void gemm_phase(PG8_LAS unsigned char* lds, const Gemm g, const Sched& S, const Epi& E) {
;     ...
;             PG8_LDB(B0, 1, 0); PG8_LDB(B1, 1, 1); PG8_SCHED; PG8_LDA(At, 1, 0); PG8_STAGE(PG8_SA(0, 1), a2 + hstep, voffA);
;             PG8_WAIT_V(8); PG8_WAIT_L(0); PG8_BAR; PG8_MMA(0, 0, At, B0); PG8_MMA(0, 1, At, B1); PG8_BAR; PG8_SCHED;
	s_add_i32 s3, 0, 0x18000
	v_add_u32_e32 v136, s3, v143
	s_add_i32 s33, 0, 0x1c000
	ds_read_b128 v[154:157], v136
	ds_read_b128 v[158:161], v136 offset:1024
	ds_read_b128 v[162:165], v136 offset:2048
	ds_read_b128 v[174:177], v136 offset:3072
	v_add_u32_e32 v136, s33, v143
	ds_read_b128 v[182:185], v136
	ds_read_b128 v[186:189], v136 offset:1024
	ds_read_b128 v[190:193], v136 offset:2048
	ds_read_b128 v[194:197], v136 offset:3072
	s_add_u32 s14, s58, 0x40000
	s_addc_u32 s15, s59, 0
	s_mov_b32 m0, s62
	v_lshl_add_u64 v[240:241], s[14:15], 0, v[134:135]
	ds_read_b128 v[198:201], v171 offset:32768
	ds_read_b128 v[208:211], v171 offset:33792
	ds_read_b128 v[212:215], v171 offset:34816
	ds_read_b128 v[216:219], v171 offset:35840
	ds_read_b128 v[220:223], v171 offset:36864
	ds_read_b128 v[224:227], v171 offset:37888
	ds_read_b128 v[228:231], v171 offset:38912
	ds_read_b128 v[232:235], v171 offset:39936
	global_load_lds_dwordx4 v[240:241], off
	v_lshl_add_u64 v[240:241], s[14:15], 0, v[130:131]
	s_mov_b32 m0, s63
	s_nop 0
	global_load_lds_dwordx4 v[240:241], off
	s_waitcnt vmcnt(8)
	s_waitcnt lgkmcnt(0)
	s_barrier
	s_setprio 1
	s_waitcnt lgkmcnt(0)
	v_mfma_f32_16x16x32_bf16 v[124:127], v[154:157], v[198:201], v[124:127]
	v_mfma_f32_16x16x32_bf16 v[120:123], v[162:165], v[198:201], v[120:123]
	v_mfma_f32_16x16x32_bf16 v[116:119], v[154:157], v[212:215], v[116:119]
	v_mfma_f32_16x16x32_bf16 v[112:115], v[162:165], v[212:215], v[112:115]
	v_mfma_f32_16x16x32_bf16 v[108:111], v[154:157], v[220:223], v[108:111]
	v_mfma_f32_16x16x32_bf16 v[104:107], v[162:165], v[220:223], v[104:107]
	v_mfma_f32_16x16x32_bf16 v[100:103], v[154:157], v[228:231], v[100:103]
	v_mfma_f32_16x16x32_bf16 v[96:99], v[162:165], v[228:231], v[96:99]
	v_mfma_f32_16x16x32_bf16 v[124:127], v[158:161], v[208:211], v[124:127]
	v_mfma_f32_16x16x32_bf16 v[120:123], v[174:177], v[208:211], v[120:123]
	v_mfma_f32_16x16x32_bf16 v[116:119], v[158:161], v[216:219], v[116:119]
	v_mfma_f32_16x16x32_bf16 v[112:115], v[174:177], v[216:219], v[112:115]
	v_mfma_f32_16x16x32_bf16 v[108:111], v[158:161], v[224:227], v[108:111]
	v_mfma_f32_16x16x32_bf16 v[104:107], v[174:177], v[224:227], v[104:107]
	v_mfma_f32_16x16x32_bf16 v[100:103], v[158:161], v[232:235], v[100:103]
	v_mfma_f32_16x16x32_bf16 v[96:99], v[174:177], v[232:235], v[96:99]
	s_setprio 0
	s_setprio 1
	v_mfma_f32_16x16x32_bf16 v[68:71], v[182:185], v[198:201], v[68:71]
	v_mfma_f32_16x16x32_bf16 v[64:67], v[190:193], v[198:201], v[64:67]
	v_mfma_f32_16x16x32_bf16 v[52:55], v[182:185], v[212:215], v[52:55]
	v_mfma_f32_16x16x32_bf16 v[48:51], v[190:193], v[212:215], v[48:51]
	v_mfma_f32_16x16x32_bf16 v[44:47], v[182:185], v[220:223], v[44:47]
	v_mfma_f32_16x16x32_bf16 v[40:43], v[190:193], v[220:223], v[40:43]
	v_mfma_f32_16x16x32_bf16 v[36:39], v[182:185], v[228:231], v[36:39]
	v_mfma_f32_16x16x32_bf16 v[32:35], v[190:193], v[228:231], v[32:35]
	v_mfma_f32_16x16x32_bf16 v[68:71], v[186:189], v[208:211], v[68:71]
	v_mfma_f32_16x16x32_bf16 v[64:67], v[194:197], v[208:211], v[64:67]
	v_mfma_f32_16x16x32_bf16 v[52:55], v[186:189], v[216:219], v[52:55]
	v_mfma_f32_16x16x32_bf16 v[48:51], v[194:197], v[216:219], v[48:51]
	v_mfma_f32_16x16x32_bf16 v[44:47], v[186:189], v[224:227], v[44:47]
	v_mfma_f32_16x16x32_bf16 v[40:43], v[194:197], v[224:227], v[40:43]
	v_mfma_f32_16x16x32_bf16 v[36:39], v[186:189], v[232:235], v[36:39]
	v_mfma_f32_16x16x32_bf16 v[32:35], v[194:197], v[232:235], v[32:35]
	s_setprio 0
	s_barrier
; #define PG8_STAGE(bufoff, gbase, voff) do { _Pragma("unroll") for (int _i = 0; _i < 2; ++_i) \
;         __builtin_amdgcn_global_load_lds((const unsigned*)((const char*)(gbase) + (voff)[_i]), (PG8_LAS unsigned*)(lds + (bufoff) + ldsw + _i * 8192), 16, 0, 0); } while (0)
; #define PG8_LDA(dst, b, h) do { _Pragma("unroll") for (int m = 0; m < 4; ++m) _Pragma("unroll") for (int k = 0; k < 2; ++k) dst[m][k] = *(const PG8_LAS bf16x8*)(lds + PG8_SA(b, h) + aoff + m * 2048 + k * 1024); } while (0)
; #define PG8_MMA(ai, bj, At, Bt) do { __builtin_amdgcn_s_setprio(1); _Pragma("unroll") for (int m = 0; m < 4; ++m) _Pragma("unroll") for (int n = 0; n < 2; ++n) _Pragma("unroll") for (int k = 0; k < 2; ++k) \
;         acc[ai][bj][m][n] = __builtin_amdgcn_mfma_f32_16x16x32_bf16(Bt[n][k], At[m][k], acc[ai][bj][m][n], 0, 0, 0); __builtin_amdgcn_s_setprio(0); } while (0)
; #define PG8_WAIT_V(n) asm volatile("s_waitcnt vmcnt(" #n ")" ::: "memory")
; #define PG8_WAIT_L(n) asm volatile("s_waitcnt lgkmcnt(" #n ")" ::: "memory")
; #define PG8_BAR __builtin_amdgcn_s_barrier()
; #define PG8_SCHED __builtin_amdgcn_sched_barrier(0)
; template <class Epi, class Sched, bool ALIGN_EPI = false, bool SP2 = false>
; __device__ __forceinline__ void gemm_phase(PG8_LAS unsigned char* lds, const Gemm g, const Sched& S, const Epi& E) {
;     ...
;             PG8_LDA(At, 1, 1); PG8_STAGE(PG8_SB(1, 0), b3, voffB); PG8_STAGE(PG8_SB(1, 1), b3 + hstep, voffB); PG8_STAGE(PG8_SA(1, 0), a3, voffA);
;             PG8_WAIT_V(8); PG8_WAIT_L(0); PG8_BAR; PG8_MMA(1, 0, At, B0); PG8_MMA(1, 1, At, B1); PG8_BAR; PG8_SCHED;
;     ...
;         if constexpr (ALIGN_EPI) { if (wr == 0) PG8_BAR; }
	s_add_i32 s3, s3, s34
	v_lshl_add_u64 v[178:179], v[178:179], 0, s[8:9]
	s_mov_b32 m0, s3
	ds_read_b128 v[198:201], v171 offset:49152
	ds_read_b128 v[208:211], v171 offset:50176
	ds_read_b128 v[212:215], v171 offset:51200
	ds_read_b128 v[216:219], v171 offset:52224
	ds_read_b128 v[220:223], v171 offset:53248
	ds_read_b128 v[224:227], v171 offset:54272
	ds_read_b128 v[228:231], v171 offset:55296
	ds_read_b128 v[232:235], v171 offset:56320
	global_load_lds_dwordx4 v[178:179], off
	s_add_i32 m0, s3, 0x2000
	s_add_u32 s14, s56, 0x40080
	v_lshl_add_u64 v[178:179], v[202:203], 0, s[8:9]
	s_addc_u32 s15, s57, 0
	s_add_i32 s3, s33, s34
	global_load_lds_dwordx4 v[178:179], off
	v_lshl_add_u64 v[178:179], s[14:15], 0, v[132:133]
	s_mov_b32 m0, s3
	s_nop 0
	global_load_lds_dwordx4 v[178:179], off
	v_lshl_add_u64 v[178:179], s[14:15], 0, v[128:129]
	s_add_i32 m0, s3, 0x2000
	s_nop 0
	global_load_lds_dwordx4 v[178:179], off
	s_waitcnt vmcnt(6)
	s_waitcnt lgkmcnt(0)
	s_barrier
	s_setprio 1
	s_waitcnt lgkmcnt(0)
	v_mfma_f32_16x16x32_bf16 v[92:95], v[154:157], v[198:201], v[92:95]
	v_mfma_f32_16x16x32_bf16 v[88:91], v[162:165], v[198:201], v[88:91]
	v_mfma_f32_16x16x32_bf16 v[84:87], v[154:157], v[212:215], v[84:87]
	v_mfma_f32_16x16x32_bf16 v[80:83], v[162:165], v[212:215], v[80:83]
	v_mfma_f32_16x16x32_bf16 v[76:79], v[154:157], v[220:223], v[76:79]
	v_mfma_f32_16x16x32_bf16 v[72:75], v[162:165], v[220:223], v[72:75]
	v_mfma_f32_16x16x32_bf16 v[60:63], v[154:157], v[228:231], v[60:63]
	v_mfma_f32_16x16x32_bf16 v[56:59], v[162:165], v[228:231], v[56:59]
	v_mfma_f32_16x16x32_bf16 v[92:95], v[158:161], v[208:211], v[92:95]
	v_mfma_f32_16x16x32_bf16 v[88:91], v[174:177], v[208:211], v[88:91]
	v_mfma_f32_16x16x32_bf16 v[84:87], v[158:161], v[216:219], v[84:87]
	v_mfma_f32_16x16x32_bf16 v[80:83], v[174:177], v[216:219], v[80:83]
	v_lshl_add_u64 v[178:179], v[236:237], 0, s[8:9]
	s_mov_b32 m0, s66
	s_nop 0
	global_load_lds_dwordx4 v[178:179], off
	v_mfma_f32_16x16x32_bf16 v[76:79], v[158:161], v[224:227], v[76:79]
	v_mfma_f32_16x16x32_bf16 v[72:75], v[174:177], v[224:227], v[72:75]
	v_mfma_f32_16x16x32_bf16 v[60:63], v[158:161], v[232:235], v[60:63]
	v_mfma_f32_16x16x32_bf16 v[56:59], v[174:177], v[232:235], v[56:59]
	s_setprio 0
	s_setprio 1
	v_mfma_f32_16x16x32_bf16 v[28:31], v[182:185], v[198:201], v[28:31]
	v_mfma_f32_16x16x32_bf16 v[24:27], v[190:193], v[198:201], v[24:27]
	v_mfma_f32_16x16x32_bf16 v[20:23], v[182:185], v[212:215], v[20:23]
	v_mfma_f32_16x16x32_bf16 v[16:19], v[190:193], v[212:215], v[16:19]
	v_mfma_f32_16x16x32_bf16 v[12:15], v[182:185], v[220:223], v[12:15]
	v_mfma_f32_16x16x32_bf16 v[8:11], v[190:193], v[220:223], v[8:11]
	v_mfma_f32_16x16x32_bf16 v[4:7], v[182:185], v[228:231], v[4:7]
	v_mfma_f32_16x16x32_bf16 v[0:3], v[190:193], v[228:231], v[0:3]
	v_mfma_f32_16x16x32_bf16 v[28:31], v[186:189], v[208:211], v[28:31]
	v_mfma_f32_16x16x32_bf16 v[24:27], v[194:197], v[208:211], v[24:27]
	v_mfma_f32_16x16x32_bf16 v[20:23], v[186:189], v[216:219], v[20:23]
	v_mfma_f32_16x16x32_bf16 v[16:19], v[194:197], v[216:219], v[16:19]
	v_lshl_add_u64 v[178:179], v[238:239], 0, s[8:9]
	s_mov_b32 m0, s67
	s_nop 0
	global_load_lds_dwordx4 v[178:179], off
	v_mfma_f32_16x16x32_bf16 v[12:15], v[186:189], v[224:227], v[12:15]
	v_mfma_f32_16x16x32_bf16 v[8:11], v[194:197], v[224:227], v[8:11]
	v_mfma_f32_16x16x32_bf16 v[4:7], v[186:189], v[232:235], v[4:7]
	v_mfma_f32_16x16x32_bf16 v[0:3], v[194:197], v[232:235], v[0:3]
	s_setprio 0
	s_barrier
	s_add_i32 s93, s93, 2
	s_add_u32 s54, s54, 0x100
	s_addc_u32 s55, s55, 0
	s_add_u32 s91, s91, 0x100
	s_addc_u32 s92, s92, 0
	s_cmp_gt_u32 s93, 13
	s_cbranch_scc0 .LBB0_417
	s_and_b64 vcc, exec, s[10:11]
	s_cbranch_vccz .LBB0_420
	s_barrier

; #define PG8_STAGE(bufoff, gbase, voff) do { _Pragma("unroll") for (int _i = 0; _i < 2; ++_i) \
;         __builtin_amdgcn_global_load_lds((const unsigned*)((const char*)(gbase) + (voff)[_i]), (PG8_LAS unsigned*)(lds + (bufoff) + ldsw + _i * 8192), 16, 0, 0); } while (0)
; #define PG8_LDA(dst, b, h) do { _Pragma("unroll") for (int m = 0; m < 4; ++m) _Pragma("unroll") for (int k = 0; k < 2; ++k) dst[m][k] = *(const PG8_LAS bf16x8*)(lds + PG8_SA(b, h) + aoff + m * 2048 + k * 1024); } while (0)
; #define PG8_LDB(dst, b, h) do { _Pragma("unroll") for (int n = 0; n < 2; ++n) _Pragma("unroll") for (int k = 0; k < 2; ++k) dst[n][k] = *(const PG8_LAS bf16x8*)(lds + PG8_SB(b, h) + boff + n * 2048 + k * 1024); } while (0)
; #define PG8_WAIT_V(n) asm volatile("s_waitcnt vmcnt(" #n ")" ::: "memory")
; #define PG8_WAIT_L(n) asm volatile("s_waitcnt lgkmcnt(" #n ")" ::: "memory")
; #define PG8_BAR __builtin_amdgcn_s_barrier()
; #define PG8_SCHED __builtin_amdgcn_sched_barrier(0)
; template <class Epi, class Sched, bool ALIGN_EPI = false, bool SP2 = false>
; __device__ __forceinline__ void gemm_phase(PG8_LAS unsigned char* lds, const Gemm g, const Sched& S, const Epi& E) {
;     ...
;         const bool has_next = S.next(ui + 1, nxt);
;         const char* nA = has_next ? (const char*)g.A + (size_t)nxt.pm * tstep : cA; const char* nB = has_next ? (const char*)g.Bt + (size_t)nxt.pn * tstep : cB;
;         for (int t = 0; t < nt; t += 2) {
;             const bool last = (t == nt - 2);
;             const char* a1 = cA + (size_t)(t + 1) * kstep;
;             const char* a2 = last ? nA : cA + (size_t)(t + 2) * kstep; const char* b2 = last ? nB : cB + (size_t)(t + 2) * kstep;
;             const char* a3 = a2 + kstep; const char* b3 = b2 + kstep;
;             if (last && has_next) S.a_ready(nxt);
;             if constexpr (SP2) {
;             PG8_LDB(B0, 0, 0); PG8_LDB(B1, 0, 1); PG8_SCHED; PG8_LDA(At, 0, 0); PG8_STAGE(PG8_SA(1, 1), a1 + hstep, voffA);
;             PG8_WAIT_V(8); PG8_WAIT_L(0); PG8_BAR; PG8_MMA(0, 0, At, B0); PG8_MMA(0, 1, At, B1); PG8_BAR; PG8_SCHED;
;             PG8_LDA(At, 0, 1); PG8_STAGE(PG8_SB(0, 0), b2, voffB); PG8_STAGE(PG8_SB(0, 1), b2 + hstep, voffB); PG8_STAGE(PG8_SA(0, 0), a2, voffA);
;             PG8_WAIT_V(8); PG8_WAIT_L(0); PG8_BAR; PG8_MMA(1, 0, At, B0); PG8_MMA(1, 1, At, B1); PG8_BAR; PG8_SCHED;
.LBB0_458:
	s_ashr_i32 s49, s48, 31
	s_lshl_b64 s[14:15], s[48:49], 19
	s_add_u32 s50, s34, s14
	s_addc_u32 s51, s43, s15
	s_and_b64 s[14:15], s[40:41], exec
	s_cselect_b32 s49, s51, s59
	s_cselect_b32 s55, s50, s58
	s_ashr_i32 s45, s44, 31
	s_lshl_b64 s[14:15], s[44:45], 19
	v_readlane_b32 s3, v250, 13
	s_add_u32 s52, s3, s14
	v_readlane_b32 s3, v250, 14
	s_addc_u32 s53, s3, s15
	s_and_b64 s[14:15], s[40:41], exec
	s_cselect_b32 s45, s53, s61
	s_cselect_b32 s57, s52, s60
	s_add_u32 s58, s58, 0x40080
	s_addc_u32 s59, s59, 0
	s_add_u32 s96, s60, 0x100
	s_addc_u32 s97, s61, 0
	s_mov_b32 vcc_lo, -2
	ds_read_b128 v[170:173], v165
	ds_read_b128 v[174:177], v165 offset:1024
	ds_read_b128 v[182:185], v165 offset:2048
	ds_read_b128 v[186:189], v165 offset:3072
	ds_read_b128 v[190:193], v168
	ds_read_b128 v[194:197], v168 offset:1024
	ds_read_b128 v[198:201], v168 offset:2048
	ds_read_b128 v[208:211], v168 offset:3072
	s_add_u32 s3, s58, 0xfffc0080
	s_addc_u32 s14, s59, -1
	s_cmp_eq_u32 vcc_lo, 12
	s_cselect_b32 s63, s49, s14
	s_cselect_b32 s62, s55, s3
	s_cselect_b32 s61, s45, s97
	s_cselect_b32 s60, s57, s96
	v_lshl_add_u64 v[178:179], s[58:59], 0, v[160:161]
	s_add_i32 m0, s85, 0xc000
	ds_read_b128 v[212:215], v164
	ds_read_b128 v[216:219], v164 offset:1024
	ds_read_b128 v[220:223], v164 offset:2048
	ds_read_b128 v[224:227], v164 offset:3072
	ds_read_b128 v[228:231], v164 offset:4096
	ds_read_b128 v[232:235], v164 offset:5120
	ds_read_b128 v[236:239], v164 offset:6144
	ds_read_b128 v[240:243], v164 offset:7168
	global_load_lds_dwordx4 v[178:179], off
	v_lshl_add_u64 v[178:179], s[58:59], 0, v[162:163]
	s_add_i32 m0, s85, 0xe000
	s_nop 0
	global_load_lds_dwordx4 v[178:179], off
	s_waitcnt vmcnt(8)
	s_waitcnt lgkmcnt(0)
	s_barrier
	s_setprio 1
	s_waitcnt lgkmcnt(0)
	v_mfma_f32_16x16x32_bf16 v[124:127], v[170:173], v[212:215], 0
	v_mfma_f32_16x16x32_bf16 v[120:123], v[182:185], v[212:215], 0
	v_mfma_f32_16x16x32_bf16 v[116:119], v[170:173], v[220:223], 0
	v_mfma_f32_16x16x32_bf16 v[112:115], v[182:185], v[220:223], 0
	v_mfma_f32_16x16x32_bf16 v[108:111], v[170:173], v[228:231], 0
	v_mfma_f32_16x16x32_bf16 v[104:107], v[182:185], v[228:231], 0
	v_mfma_f32_16x16x32_bf16 v[100:103], v[170:173], v[236:239], 0
	v_mfma_f32_16x16x32_bf16 v[96:99], v[182:185], v[236:239], 0
	v_mfma_f32_16x16x32_bf16 v[124:127], v[174:177], v[216:219], v[124:127]
	v_mfma_f32_16x16x32_bf16 v[120:123], v[186:189], v[216:219], v[120:123]
	v_mfma_f32_16x16x32_bf16 v[116:119], v[174:177], v[224:227], v[116:119]
	v_mfma_f32_16x16x32_bf16 v[112:115], v[186:189], v[224:227], v[112:115]
	v_mfma_f32_16x16x32_bf16 v[108:111], v[174:177], v[232:235], v[108:111]
	v_mfma_f32_16x16x32_bf16 v[104:107], v[186:189], v[232:235], v[104:107]
	v_mfma_f32_16x16x32_bf16 v[100:103], v[174:177], v[240:243], v[100:103]
	v_mfma_f32_16x16x32_bf16 v[96:99], v[186:189], v[240:243], v[96:99]
	s_setprio 0
	s_setprio 1
	v_mfma_f32_16x16x32_bf16 v[60:63], v[190:193], v[212:215], 0
	v_mfma_f32_16x16x32_bf16 v[56:59], v[198:201], v[212:215], 0
	v_mfma_f32_16x16x32_bf16 v[52:55], v[190:193], v[220:223], 0
	v_mfma_f32_16x16x32_bf16 v[48:51], v[198:201], v[220:223], 0
	v_mfma_f32_16x16x32_bf16 v[44:47], v[190:193], v[228:231], 0
	v_mfma_f32_16x16x32_bf16 v[40:43], v[198:201], v[228:231], 0
	v_mfma_f32_16x16x32_bf16 v[36:39], v[190:193], v[236:239], 0
	v_mfma_f32_16x16x32_bf16 v[32:35], v[198:201], v[236:239], 0
	v_mfma_f32_16x16x32_bf16 v[60:63], v[194:197], v[216:219], v[60:63]
	v_mfma_f32_16x16x32_bf16 v[56:59], v[208:211], v[216:219], v[56:59]
	v_mfma_f32_16x16x32_bf16 v[52:55], v[194:197], v[224:227], v[52:55]
	v_mfma_f32_16x16x32_bf16 v[48:51], v[208:211], v[224:227], v[48:51]
	v_mfma_f32_16x16x32_bf16 v[44:47], v[194:197], v[232:235], v[44:47]
	v_mfma_f32_16x16x32_bf16 v[40:43], v[208:211], v[232:235], v[40:43]
	v_mfma_f32_16x16x32_bf16 v[36:39], v[194:197], v[240:243], v[36:39]
	v_mfma_f32_16x16x32_bf16 v[32:35], v[208:211], v[240:243], v[32:35]
	s_setprio 0
	s_barrier
	s_add_i32 s3, s94, s84
	v_lshl_add_u64 v[178:179], s[60:61], 0, v[130:131]
	s_mov_b32 m0, s3
	ds_read_b128 v[212:215], v164 offset:16384
	ds_read_b128 v[216:219], v164 offset:17408
	ds_read_b128 v[220:223], v164 offset:18432
	ds_read_b128 v[224:227], v164 offset:19456
	ds_read_b128 v[228:231], v164 offset:20480
	ds_read_b128 v[232:235], v164 offset:21504
	ds_read_b128 v[236:239], v164 offset:22528
	ds_read_b128 v[240:243], v164 offset:23552
	global_load_lds_dwordx4 v[178:179], off
	s_add_i32 m0, s3, 0x2000
	s_add_u32 s14, s60, 0x40000
	v_lshl_add_u64 v[202:203], s[60:61], 0, v[134:135]
	s_addc_u32 s15, s61, 0
	s_add_i32 s3, s95, s84
	global_load_lds_dwordx4 v[202:203], off
	v_lshl_add_u64 v[244:245], s[14:15], 0, v[130:131]
	s_mov_b32 m0, s3
	global_load_lds_dwordx4 v[244:245], off
	v_lshl_add_u64 v[244:245], s[14:15], 0, v[134:135]
	s_add_i32 m0, s3, 0x2000
	s_nop 0
	global_load_lds_dwordx4 v[244:245], off
	s_waitcnt vmcnt(6)
	s_waitcnt lgkmcnt(0)
	s_barrier
; #define PG8_STAGE(bufoff, gbase, voff) do { _Pragma("unroll") for (int _i = 0; _i < 2; ++_i) \
;         __builtin_amdgcn_global_load_lds((const unsigned*)((const char*)(gbase) + (voff)[_i]), (PG8_LAS unsigned*)(lds + (bufoff) + ldsw + _i * 8192), 16, 0, 0); } while (0)
; #define PG8_LDA(dst, b, h) do { _Pragma("unroll") for (int m = 0; m < 4; ++m) _Pragma("unroll") for (int k = 0; k < 2; ++k) dst[m][k] = *(const PG8_LAS bf16x8*)(lds + PG8_SA(b, h) + aoff + m * 2048 + k * 1024); } while (0)
; #define PG8_LDB(dst, b, h) do { _Pragma("unroll") for (int n = 0; n < 2; ++n) _Pragma("unroll") for (int k = 0; k < 2; ++k) dst[n][k] = *(const PG8_LAS bf16x8*)(lds + PG8_SB(b, h) + boff + n * 2048 + k * 1024); } while (0)
; #define PG8_MMA(ai, bj, At, Bt) do { __builtin_amdgcn_s_setprio(1); _Pragma("unroll") for (int m = 0; m < 4; ++m) _Pragma("unroll") for (int n = 0; n < 2; ++n) _Pragma("unroll") for (int k = 0; k < 2; ++k) \
;         acc[ai][bj][m][n] = __builtin_amdgcn_mfma_f32_16x16x32_bf16(Bt[n][k], At[m][k], acc[ai][bj][m][n], 0, 0, 0); __builtin_amdgcn_s_setprio(0); } while (0)
; #define PG8_WAIT_V(n) asm volatile("s_waitcnt vmcnt(" #n ")" ::: "memory")
; #define PG8_WAIT_L(n) asm volatile("s_waitcnt lgkmcnt(" #n ")" ::: "memory")
; #define PG8_BAR __builtin_amdgcn_s_barrier()
; #define PG8_SCHED __builtin_amdgcn_sched_barrier(0)
; template <class Epi, class Sched, bool ALIGN_EPI = false, bool SP2 = false>
; __device__ __forceinline__ void gemm_phase(PG8_LAS unsigned char* lds, const Gemm g, const Sched& S, const Epi& E) {
;     ...
;             PG8_WAIT_V(8); PG8_WAIT_L(0); PG8_BAR; PG8_MMA(1, 0, At, B0); PG8_MMA(1, 1, At, B1); PG8_BAR; PG8_SCHED;
;             PG8_LDB(B0, 1, 0); PG8_LDB(B1, 1, 1); PG8_SCHED; PG8_LDA(At, 1, 0); PG8_STAGE(PG8_SA(0, 1), a2 + hstep, voffA);
;             PG8_WAIT_V(8); PG8_WAIT_L(0); PG8_BAR; PG8_MMA(0, 0, At, B0); PG8_MMA(0, 1, At, B1); PG8_BAR; PG8_SCHED;
	s_setprio 1
	s_waitcnt lgkmcnt(0)
	v_mfma_f32_16x16x32_bf16 v[92:95], v[170:173], v[212:215], 0
	v_mfma_f32_16x16x32_bf16 v[88:91], v[182:185], v[212:215], 0
	v_mfma_f32_16x16x32_bf16 v[84:87], v[170:173], v[220:223], 0
	v_mfma_f32_16x16x32_bf16 v[80:83], v[182:185], v[220:223], 0
	v_mfma_f32_16x16x32_bf16 v[76:79], v[170:173], v[228:231], 0
	v_mfma_f32_16x16x32_bf16 v[72:75], v[182:185], v[228:231], 0
	v_mfma_f32_16x16x32_bf16 v[68:71], v[170:173], v[236:239], 0
	v_mfma_f32_16x16x32_bf16 v[64:67], v[182:185], v[236:239], 0
	v_mfma_f32_16x16x32_bf16 v[92:95], v[174:177], v[216:219], v[92:95]
	v_mfma_f32_16x16x32_bf16 v[88:91], v[186:189], v[216:219], v[88:91]
	v_mfma_f32_16x16x32_bf16 v[84:87], v[174:177], v[224:227], v[84:87]
	v_mfma_f32_16x16x32_bf16 v[80:83], v[186:189], v[224:227], v[80:83]
	v_lshl_add_u64 v[244:245], s[62:63], 0, v[128:129]
	s_mov_b32 m0, s85
	s_nop 0
	global_load_lds_dwordx4 v[244:245], off
	v_mfma_f32_16x16x32_bf16 v[76:79], v[174:177], v[232:235], v[76:79]
	v_mfma_f32_16x16x32_bf16 v[72:75], v[186:189], v[232:235], v[72:75]
	v_mfma_f32_16x16x32_bf16 v[68:71], v[174:177], v[240:243], v[68:71]
	v_mfma_f32_16x16x32_bf16 v[64:67], v[186:189], v[240:243], v[64:67]
	s_setprio 0
	s_setprio 1
	v_mfma_f32_16x16x32_bf16 v[28:31], v[190:193], v[212:215], 0
	v_mfma_f32_16x16x32_bf16 v[24:27], v[198:201], v[212:215], 0
	v_mfma_f32_16x16x32_bf16 v[20:23], v[190:193], v[220:223], 0
	v_mfma_f32_16x16x32_bf16 v[16:19], v[198:201], v[220:223], 0
	v_mfma_f32_16x16x32_bf16 v[12:15], v[190:193], v[228:231], 0
	v_mfma_f32_16x16x32_bf16 v[8:11], v[198:201], v[228:231], 0
	v_mfma_f32_16x16x32_bf16 v[4:7], v[190:193], v[236:239], 0
	v_mfma_f32_16x16x32_bf16 v[0:3], v[198:201], v[236:239], 0
	v_mfma_f32_16x16x32_bf16 v[28:31], v[194:197], v[216:219], v[28:31]
	v_mfma_f32_16x16x32_bf16 v[24:27], v[208:211], v[216:219], v[24:27]
	v_mfma_f32_16x16x32_bf16 v[20:23], v[194:197], v[224:227], v[20:23]
	v_mfma_f32_16x16x32_bf16 v[16:19], v[208:211], v[224:227], v[16:19]
	v_lshl_add_u64 v[246:247], s[62:63], 0, v[132:133]
	s_mov_b32 m0, s86
	s_nop 0
	global_load_lds_dwordx4 v[246:247], off
	v_mfma_f32_16x16x32_bf16 v[12:15], v[194:197], v[232:235], v[12:15]
	v_mfma_f32_16x16x32_bf16 v[8:11], v[208:211], v[232:235], v[8:11]
	v_mfma_f32_16x16x32_bf16 v[4:7], v[194:197], v[240:243], v[4:7]
	v_mfma_f32_16x16x32_bf16 v[0:3], v[208:211], v[240:243], v[0:3]
	s_setprio 0
	s_barrier
	s_add_i32 s3, 0, 0x18000
	v_add_u32_e32 v136, s3, v141
	s_add_i32 s33, 0, 0x1c000
	ds_read_b128 v[170:173], v136
	ds_read_b128 v[174:177], v136 offset:1024
	ds_read_b128 v[182:185], v136 offset:2048
	ds_read_b128 v[186:189], v136 offset:3072
	v_add_u32_e32 v136, s33, v141
	ds_read_b128 v[190:193], v136
	ds_read_b128 v[194:197], v136 offset:1024
	ds_read_b128 v[198:201], v136 offset:2048
	ds_read_b128 v[208:211], v136 offset:3072
	s_add_u32 s14, s62, 0x40000
	s_addc_u32 s15, s63, 0
	s_mov_b32 m0, s87
	v_lshl_add_u64 v[248:249], s[14:15], 0, v[128:129]
	ds_read_b128 v[212:215], v164 offset:32768
	ds_read_b128 v[216:219], v164 offset:33792
	ds_read_b128 v[220:223], v164 offset:34816
	ds_read_b128 v[224:227], v164 offset:35840
	ds_read_b128 v[228:231], v164 offset:36864
	ds_read_b128 v[232:235], v164 offset:37888
	ds_read_b128 v[236:239], v164 offset:38912
	ds_read_b128 v[240:243], v164 offset:39936
	global_load_lds_dwordx4 v[248:249], off
	v_lshl_add_u64 v[248:249], s[14:15], 0, v[132:133]
	s_mov_b32 m0, s88
	s_nop 0
	global_load_lds_dwordx4 v[248:249], off
	s_waitcnt vmcnt(8)
	s_waitcnt lgkmcnt(0)
	s_barrier
	s_setprio 1
	s_waitcnt lgkmcnt(0)
	v_mfma_f32_16x16x32_bf16 v[124:127], v[170:173], v[212:215], v[124:127]
	v_mfma_f32_16x16x32_bf16 v[120:123], v[182:185], v[212:215], v[120:123]
	v_mfma_f32_16x16x32_bf16 v[116:119], v[170:173], v[220:223], v[116:119]
	v_mfma_f32_16x16x32_bf16 v[112:115], v[182:185], v[220:223], v[112:115]
	v_mfma_f32_16x16x32_bf16 v[108:111], v[170:173], v[228:231], v[108:111]
	v_mfma_f32_16x16x32_bf16 v[104:107], v[182:185], v[228:231], v[104:107]
	v_mfma_f32_16x16x32_bf16 v[100:103], v[170:173], v[236:239], v[100:103]
	v_mfma_f32_16x16x32_bf16 v[96:99], v[182:185], v[236:239], v[96:99]
	v_mfma_f32_16x16x32_bf16 v[124:127], v[174:177], v[216:219], v[124:127]
	v_mfma_f32_16x16x32_bf16 v[120:123], v[186:189], v[216:219], v[120:123]
	v_mfma_f32_16x16x32_bf16 v[116:119], v[174:177], v[224:227], v[116:119]
	v_mfma_f32_16x16x32_bf16 v[112:115], v[186:189], v[224:227], v[112:115]
	v_mfma_f32_16x16x32_bf16 v[108:111], v[174:177], v[232:235], v[108:111]
	v_mfma_f32_16x16x32_bf16 v[104:107], v[186:189], v[232:235], v[104:107]
	v_mfma_f32_16x16x32_bf16 v[100:103], v[174:177], v[240:243], v[100:103]
	v_mfma_f32_16x16x32_bf16 v[96:99], v[186:189], v[240:243], v[96:99]
	s_setprio 0
	s_setprio 1
	v_mfma_f32_16x16x32_bf16 v[60:63], v[190:193], v[212:215], v[60:63]
	v_mfma_f32_16x16x32_bf16 v[56:59], v[198:201], v[212:215], v[56:59]
	v_mfma_f32_16x16x32_bf16 v[52:55], v[190:193], v[220:223], v[52:55]
	v_mfma_f32_16x16x32_bf16 v[48:51], v[198:201], v[220:223], v[48:51]
	v_mfma_f32_16x16x32_bf16 v[44:47], v[190:193], v[228:231], v[44:47]
	v_mfma_f32_16x16x32_bf16 v[40:43], v[198:201], v[228:231], v[40:43]
	v_mfma_f32_16x16x32_bf16 v[36:39], v[190:193], v[236:239], v[36:39]
	v_mfma_f32_16x16x32_bf16 v[32:35], v[198:201], v[236:239], v[32:35]
	v_mfma_f32_16x16x32_bf16 v[60:63], v[194:197], v[216:219], v[60:63]
	v_mfma_f32_16x16x32_bf16 v[56:59], v[208:211], v[216:219], v[56:59]
	v_mfma_f32_16x16x32_bf16 v[52:55], v[194:197], v[224:227], v[52:55]
	v_mfma_f32_16x16x32_bf16 v[48:51], v[208:211], v[224:227], v[48:51]
	v_mfma_f32_16x16x32_bf16 v[44:47], v[194:197], v[232:235], v[44:47]
	v_mfma_f32_16x16x32_bf16 v[40:43], v[208:211], v[232:235], v[40:43]
	v_mfma_f32_16x16x32_bf16 v[36:39], v[194:197], v[240:243], v[36:39]
	v_mfma_f32_16x16x32_bf16 v[32:35], v[208:211], v[240:243], v[32:35]
	s_setprio 0
	s_barrier
; #define PG8_STAGE(bufoff, gbase, voff) do { _Pragma("unroll") for (int _i = 0; _i < 2; ++_i) \
;         __builtin_amdgcn_global_load_lds((const unsigned*)((const char*)(gbase) + (voff)[_i]), (PG8_LAS unsigned*)(lds + (bufoff) + ldsw + _i * 8192), 16, 0, 0); } while (0)
; #define PG8_LDA(dst, b, h) do { _Pragma("unroll") for (int m = 0; m < 4; ++m) _Pragma("unroll") for (int k = 0; k < 2; ++k) dst[m][k] = *(const PG8_LAS bf16x8*)(lds + PG8_SA(b, h) + aoff + m * 2048 + k * 1024); } while (0)
; #define PG8_LDB(dst, b, h) do { _Pragma("unroll") for (int n = 0; n < 2; ++n) _Pragma("unroll") for (int k = 0; k < 2; ++k) dst[n][k] = *(const PG8_LAS bf16x8*)(lds + PG8_SB(b, h) + boff + n * 2048 + k * 1024); } while (0)
; #define PG8_MMA(ai, bj, At, Bt) do { __builtin_amdgcn_s_setprio(1); _Pragma("unroll") for (int m = 0; m < 4; ++m) _Pragma("unroll") for (int n = 0; n < 2; ++n) _Pragma("unroll") for (int k = 0; k < 2; ++k) \
;         acc[ai][bj][m][n] = __builtin_amdgcn_mfma_f32_16x16x32_bf16(Bt[n][k], At[m][k], acc[ai][bj][m][n], 0, 0, 0); __builtin_amdgcn_s_setprio(0); } while (0)
; #define PG8_WAIT_V(n) asm volatile("s_waitcnt vmcnt(" #n ")" ::: "memory")
; template <class Epi, class Sched, bool ALIGN_EPI = false, bool SP2 = false>
; __device__ __forceinline__ void gemm_phase(PG8_LAS unsigned char* lds, const Gemm g, const Sched& S, const Epi& E) {
;     ...
;             PG8_LDB(B0, 0, 0); PG8_LDB(B1, 0, 1); PG8_SCHED; PG8_LDA(At, 0, 0); PG8_STAGE(PG8_SA(1, 1), a1 + hstep, voffA);
;             PG8_WAIT_V(8); PG8_WAIT_L(0); PG8_BAR; PG8_MMA(0, 0, At, B0); PG8_MMA(0, 1, At, B1); PG8_BAR; PG8_SCHED;
;             PG8_LDA(At, 0, 1); PG8_STAGE(PG8_SB(0, 0), b2, voffB); PG8_STAGE(PG8_SB(0, 1), b2 + hstep, voffB); PG8_STAGE(PG8_SA(0, 0), a2, voffA);
;             PG8_WAIT_V(8); PG8_WAIT_L(0); PG8_BAR; PG8_MMA(1, 0, At, B0); PG8_MMA(1, 1, At, B1); PG8_BAR; PG8_SCHED;
;             PG8_LDB(B0, 1, 0); PG8_LDB(B1, 1, 1); PG8_SCHED; PG8_LDA(At, 1, 0); PG8_STAGE(PG8_SA(0, 1), a2 + hstep, voffA);
;             PG8_WAIT_V(8); PG8_WAIT_L(0); PG8_BAR; PG8_MMA(0, 0, At, B0); PG8_MMA(0, 1, At, B1); PG8_BAR; PG8_SCHED;
;             PG8_LDA(At, 1, 1); PG8_STAGE(PG8_SB(1, 0), b3, voffB); PG8_STAGE(PG8_SB(1, 1), b3 + hstep, voffB); PG8_STAGE(PG8_SA(1, 0), a3, voffA);
;             PG8_WAIT_V(8); PG8_WAIT_L(0); PG8_BAR; PG8_MMA(1, 0, At, B0); PG8_MMA(1, 1, At, B1); PG8_BAR; PG8_SCHED;
	s_add_i32 s3, s3, s84
	v_lshl_add_u64 v[178:179], v[178:179], 0, s[8:9]
	s_mov_b32 m0, s3
	ds_read_b128 v[212:215], v164 offset:49152
	ds_read_b128 v[216:219], v164 offset:50176
	ds_read_b128 v[220:223], v164 offset:51200
	ds_read_b128 v[224:227], v164 offset:52224
	ds_read_b128 v[228:231], v164 offset:53248
	ds_read_b128 v[232:235], v164 offset:54272
	ds_read_b128 v[236:239], v164 offset:55296
	ds_read_b128 v[240:243], v164 offset:56320
	global_load_lds_dwordx4 v[178:179], off
	s_add_i32 m0, s3, 0x2000
	s_add_u32 s14, s60, 0x40080
	v_lshl_add_u64 v[178:179], v[202:203], 0, s[8:9]
	s_addc_u32 s15, s61, 0
	s_add_i32 s3, s33, s84
	global_load_lds_dwordx4 v[178:179], off
	v_lshl_add_u64 v[178:179], s[14:15], 0, v[130:131]
	s_mov_b32 m0, s3
	s_nop 0
	global_load_lds_dwordx4 v[178:179], off
	v_lshl_add_u64 v[178:179], s[14:15], 0, v[134:135]
	s_add_i32 m0, s3, 0x2000
	s_nop 0
	global_load_lds_dwordx4 v[178:179], off
	s_waitcnt vmcnt(6)
	s_waitcnt lgkmcnt(0)
	s_barrier
	s_setprio 1
	s_waitcnt lgkmcnt(0)
	v_mfma_f32_16x16x32_bf16 v[92:95], v[170:173], v[212:215], v[92:95]
	v_mfma_f32_16x16x32_bf16 v[88:91], v[182:185], v[212:215], v[88:91]
	v_mfma_f32_16x16x32_bf16 v[84:87], v[170:173], v[220:223], v[84:87]
	v_mfma_f32_16x16x32_bf16 v[80:83], v[182:185], v[220:223], v[80:83]
	v_mfma_f32_16x16x32_bf16 v[76:79], v[170:173], v[228:231], v[76:79]
	v_mfma_f32_16x16x32_bf16 v[72:75], v[182:185], v[228:231], v[72:75]
	v_mfma_f32_16x16x32_bf16 v[68:71], v[170:173], v[236:239], v[68:71]
	v_mfma_f32_16x16x32_bf16 v[64:67], v[182:185], v[236:239], v[64:67]
	v_mfma_f32_16x16x32_bf16 v[92:95], v[174:177], v[216:219], v[92:95]
	v_mfma_f32_16x16x32_bf16 v[88:91], v[186:189], v[216:219], v[88:91]
	v_mfma_f32_16x16x32_bf16 v[84:87], v[174:177], v[224:227], v[84:87]
	v_mfma_f32_16x16x32_bf16 v[80:83], v[186:189], v[224:227], v[80:83]
	v_lshl_add_u64 v[178:179], v[244:245], 0, s[8:9]
	s_mov_b32 m0, s90
	s_nop 0
	global_load_lds_dwordx4 v[178:179], off
	v_mfma_f32_16x16x32_bf16 v[76:79], v[174:177], v[232:235], v[76:79]
	v_mfma_f32_16x16x32_bf16 v[72:75], v[186:189], v[232:235], v[72:75]
	v_mfma_f32_16x16x32_bf16 v[68:71], v[174:177], v[240:243], v[68:71]
	v_mfma_f32_16x16x32_bf16 v[64:67], v[186:189], v[240:243], v[64:67]
	s_setprio 0
	s_setprio 1
	v_mfma_f32_16x16x32_bf16 v[28:31], v[190:193], v[212:215], v[28:31]
	v_mfma_f32_16x16x32_bf16 v[24:27], v[198:201], v[212:215], v[24:27]
	v_mfma_f32_16x16x32_bf16 v[20:23], v[190:193], v[220:223], v[20:23]
	v_mfma_f32_16x16x32_bf16 v[16:19], v[198:201], v[220:223], v[16:19]
	v_mfma_f32_16x16x32_bf16 v[12:15], v[190:193], v[228:231], v[12:15]
	v_mfma_f32_16x16x32_bf16 v[8:11], v[198:201], v[228:231], v[8:11]
	v_mfma_f32_16x16x32_bf16 v[4:7], v[190:193], v[236:239], v[4:7]
	v_mfma_f32_16x16x32_bf16 v[0:3], v[198:201], v[236:239], v[0:3]
	v_mfma_f32_16x16x32_bf16 v[28:31], v[194:197], v[216:219], v[28:31]
	v_mfma_f32_16x16x32_bf16 v[24:27], v[208:211], v[216:219], v[24:27]
	v_mfma_f32_16x16x32_bf16 v[20:23], v[194:197], v[224:227], v[20:23]
	v_mfma_f32_16x16x32_bf16 v[16:19], v[208:211], v[224:227], v[16:19]
	v_lshl_add_u64 v[178:179], v[246:247], 0, s[8:9]
	s_mov_b32 m0, s91
	s_nop 0
	global_load_lds_dwordx4 v[178:179], off
	v_mfma_f32_16x16x32_bf16 v[12:15], v[194:197], v[232:235], v[12:15]
	v_mfma_f32_16x16x32_bf16 v[8:11], v[208:211], v[232:235], v[8:11]
	v_mfma_f32_16x16x32_bf16 v[4:7], v[194:197], v[240:243], v[4:7]
	v_mfma_f32_16x16x32_bf16 v[0:3], v[208:211], v[240:243], v[0:3]
	s_setprio 0
	s_barrier
	s_add_i32 vcc_lo, vcc_lo, 2
	s_add_u32 s58, s58, 0x100
	s_addc_u32 s59, s59, 0
	s_add_u32 s96, s96, 0x100
	s_addc_u32 s97, s97, 0
.LBB0_459:
	ds_read_b128 v[170:173], v165
	ds_read_b128 v[174:177], v165 offset:1024
	ds_read_b128 v[182:185], v165 offset:2048
	ds_read_b128 v[186:189], v165 offset:3072
	ds_read_b128 v[190:193], v168
	ds_read_b128 v[194:197], v168 offset:1024
	ds_read_b128 v[198:201], v168 offset:2048
	ds_read_b128 v[208:211], v168 offset:3072
	s_add_u32 s3, s58, 0xfffc0080
	s_addc_u32 s14, s59, -1
	s_cmp_eq_u32 vcc_lo, 12
	s_cselect_b32 s63, s49, s14
	s_cselect_b32 s62, s55, s3
	s_cselect_b32 s61, s45, s97
	s_cselect_b32 s60, s57, s96
	v_lshl_add_u64 v[178:179], s[58:59], 0, v[160:161]
	s_add_i32 m0, s85, 0xc000
	ds_read_b128 v[212:215], v164
	ds_read_b128 v[216:219], v164 offset:1024
	ds_read_b128 v[220:223], v164 offset:2048
	ds_read_b128 v[224:227], v164 offset:3072
	ds_read_b128 v[228:231], v164 offset:4096
	ds_read_b128 v[232:235], v164 offset:5120
	ds_read_b128 v[236:239], v164 offset:6144
	ds_read_b128 v[240:243], v164 offset:7168
	global_load_lds_dwordx4 v[178:179], off
	v_lshl_add_u64 v[178:179], s[58:59], 0, v[162:163]
	s_add_i32 m0, s85, 0xe000
	s_nop 0
	global_load_lds_dwordx4 v[178:179], off
	s_waitcnt vmcnt(8)
	s_waitcnt lgkmcnt(0)
	s_barrier
; #define PG8_STAGE(bufoff, gbase, voff) do { _Pragma("unroll") for (int _i = 0; _i < 2; ++_i) \
;         __builtin_amdgcn_global_load_lds((const unsigned*)((const char*)(gbase) + (voff)[_i]), (PG8_LAS unsigned*)(lds + (bufoff) + ldsw + _i * 8192), 16, 0, 0); } while (0)
; #define PG8_LDA(dst, b, h) do { _Pragma("unroll") for (int m = 0; m < 4; ++m) _Pragma("unroll") for (int k = 0; k < 2; ++k) dst[m][k] = *(const PG8_LAS bf16x8*)(lds + PG8_SA(b, h) + aoff + m * 2048 + k * 1024); } while (0)
; #define PG8_MMA(ai, bj, At, Bt) do { __builtin_amdgcn_s_setprio(1); _Pragma("unroll") for (int m = 0; m < 4; ++m) _Pragma("unroll") for (int n = 0; n < 2; ++n) _Pragma("unroll") for (int k = 0; k < 2; ++k) \
;         acc[ai][bj][m][n] = __builtin_amdgcn_mfma_f32_16x16x32_bf16(Bt[n][k], At[m][k], acc[ai][bj][m][n], 0, 0, 0); __builtin_amdgcn_s_setprio(0); } while (0)
; #define PG8_WAIT_V(n) asm volatile("s_waitcnt vmcnt(" #n ")" ::: "memory")
; #define PG8_WAIT_L(n) asm volatile("s_waitcnt lgkmcnt(" #n ")" ::: "memory")
; #define PG8_BAR __builtin_amdgcn_s_barrier()
; #define PG8_SCHED __builtin_amdgcn_sched_barrier(0)
; template <class Epi, class Sched, bool ALIGN_EPI = false, bool SP2 = false>
; __device__ __forceinline__ void gemm_phase(PG8_LAS unsigned char* lds, const Gemm g, const Sched& S, const Epi& E) {
;     ...
;             PG8_WAIT_V(8); PG8_WAIT_L(0); PG8_BAR; PG8_MMA(0, 0, At, B0); PG8_MMA(0, 1, At, B1); PG8_BAR; PG8_SCHED;
;             PG8_LDA(At, 0, 1); PG8_STAGE(PG8_SB(0, 0), b2, voffB); PG8_STAGE(PG8_SB(0, 1), b2 + hstep, voffB); PG8_STAGE(PG8_SA(0, 0), a2, voffA);
;             PG8_WAIT_V(8); PG8_WAIT_L(0); PG8_BAR; PG8_MMA(1, 0, At, B0); PG8_MMA(1, 1, At, B1); PG8_BAR; PG8_SCHED;
	s_setprio 1
	s_waitcnt lgkmcnt(0)
	v_mfma_f32_16x16x32_bf16 v[124:127], v[170:173], v[212:215], v[124:127]
	v_mfma_f32_16x16x32_bf16 v[120:123], v[182:185], v[212:215], v[120:123]
	v_mfma_f32_16x16x32_bf16 v[116:119], v[170:173], v[220:223], v[116:119]
	v_mfma_f32_16x16x32_bf16 v[112:115], v[182:185], v[220:223], v[112:115]
	v_mfma_f32_16x16x32_bf16 v[108:111], v[170:173], v[228:231], v[108:111]
	v_mfma_f32_16x16x32_bf16 v[104:107], v[182:185], v[228:231], v[104:107]
	v_mfma_f32_16x16x32_bf16 v[100:103], v[170:173], v[236:239], v[100:103]
	v_mfma_f32_16x16x32_bf16 v[96:99], v[182:185], v[236:239], v[96:99]
	v_mfma_f32_16x16x32_bf16 v[124:127], v[174:177], v[216:219], v[124:127]
	v_mfma_f32_16x16x32_bf16 v[120:123], v[186:189], v[216:219], v[120:123]
	v_mfma_f32_16x16x32_bf16 v[116:119], v[174:177], v[224:227], v[116:119]
	v_mfma_f32_16x16x32_bf16 v[112:115], v[186:189], v[224:227], v[112:115]
	v_mfma_f32_16x16x32_bf16 v[108:111], v[174:177], v[232:235], v[108:111]
	v_mfma_f32_16x16x32_bf16 v[104:107], v[186:189], v[232:235], v[104:107]
	v_mfma_f32_16x16x32_bf16 v[100:103], v[174:177], v[240:243], v[100:103]
	v_mfma_f32_16x16x32_bf16 v[96:99], v[186:189], v[240:243], v[96:99]
	s_setprio 0
	s_setprio 1
	v_mfma_f32_16x16x32_bf16 v[60:63], v[190:193], v[212:215], v[60:63]
	v_mfma_f32_16x16x32_bf16 v[56:59], v[198:201], v[212:215], v[56:59]
	v_mfma_f32_16x16x32_bf16 v[52:55], v[190:193], v[220:223], v[52:55]
	v_mfma_f32_16x16x32_bf16 v[48:51], v[198:201], v[220:223], v[48:51]
	v_mfma_f32_16x16x32_bf16 v[44:47], v[190:193], v[228:231], v[44:47]
	v_mfma_f32_16x16x32_bf16 v[40:43], v[198:201], v[228:231], v[40:43]
	v_mfma_f32_16x16x32_bf16 v[36:39], v[190:193], v[236:239], v[36:39]
	v_mfma_f32_16x16x32_bf16 v[32:35], v[198:201], v[236:239], v[32:35]
	v_mfma_f32_16x16x32_bf16 v[60:63], v[194:197], v[216:219], v[60:63]
	v_mfma_f32_16x16x32_bf16 v[56:59], v[208:211], v[216:219], v[56:59]
	v_mfma_f32_16x16x32_bf16 v[52:55], v[194:197], v[224:227], v[52:55]
	v_mfma_f32_16x16x32_bf16 v[48:51], v[208:211], v[224:227], v[48:51]
	v_mfma_f32_16x16x32_bf16 v[44:47], v[194:197], v[232:235], v[44:47]
	v_mfma_f32_16x16x32_bf16 v[40:43], v[208:211], v[232:235], v[40:43]
	v_mfma_f32_16x16x32_bf16 v[36:39], v[194:197], v[240:243], v[36:39]
	v_mfma_f32_16x16x32_bf16 v[32:35], v[208:211], v[240:243], v[32:35]
	s_setprio 0
	s_barrier
	s_add_i32 s3, s94, s84
	v_lshl_add_u64 v[178:179], s[60:61], 0, v[130:131]
	s_mov_b32 m0, s3
	ds_read_b128 v[212:215], v164 offset:16384
	ds_read_b128 v[216:219], v164 offset:17408
	ds_read_b128 v[220:223], v164 offset:18432
	ds_read_b128 v[224:227], v164 offset:19456
	ds_read_b128 v[228:231], v164 offset:20480
	ds_read_b128 v[232:235], v164 offset:21504
	ds_read_b128 v[236:239], v164 offset:22528
	ds_read_b128 v[240:243], v164 offset:23552
	global_load_lds_dwordx4 v[178:179], off
	s_add_i32 m0, s3, 0x2000
	s_add_u32 s14, s60, 0x40000
	v_lshl_add_u64 v[202:203], s[60:61], 0, v[134:135]
	s_addc_u32 s15, s61, 0
	s_add_i32 s3, s95, s84
	global_load_lds_dwordx4 v[202:203], off
	v_lshl_add_u64 v[244:245], s[14:15], 0, v[130:131]
	s_mov_b32 m0, s3
	global_load_lds_dwordx4 v[244:245], off
	v_lshl_add_u64 v[244:245], s[14:15], 0, v[134:135]
	s_add_i32 m0, s3, 0x2000
	s_nop 0
	global_load_lds_dwordx4 v[244:245], off
	s_waitcnt vmcnt(6)
	s_waitcnt lgkmcnt(0)
	s_barrier
	s_setprio 1
	s_waitcnt lgkmcnt(0)
	v_mfma_f32_16x16x32_bf16 v[92:95], v[170:173], v[212:215], v[92:95]
	v_mfma_f32_16x16x32_bf16 v[88:91], v[182:185], v[212:215], v[88:91]
	v_mfma_f32_16x16x32_bf16 v[84:87], v[170:173], v[220:223], v[84:87]
	v_mfma_f32_16x16x32_bf16 v[80:83], v[182:185], v[220:223], v[80:83]
	v_mfma_f32_16x16x32_bf16 v[76:79], v[170:173], v[228:231], v[76:79]
	v_mfma_f32_16x16x32_bf16 v[72:75], v[182:185], v[228:231], v[72:75]
	v_mfma_f32_16x16x32_bf16 v[68:71], v[170:173], v[236:239], v[68:71]
	v_mfma_f32_16x16x32_bf16 v[64:67], v[182:185], v[236:239], v[64:67]
	v_mfma_f32_16x16x32_bf16 v[92:95], v[174:177], v[216:219], v[92:95]
	v_mfma_f32_16x16x32_bf16 v[88:91], v[186:189], v[216:219], v[88:91]
	v_mfma_f32_16x16x32_bf16 v[84:87], v[174:177], v[224:227], v[84:87]
	v_mfma_f32_16x16x32_bf16 v[80:83], v[186:189], v[224:227], v[80:83]
	v_lshl_add_u64 v[244:245], s[62:63], 0, v[128:129]
	s_mov_b32 m0, s85
	s_nop 0
	global_load_lds_dwordx4 v[244:245], off
	v_mfma_f32_16x16x32_bf16 v[76:79], v[174:177], v[232:235], v[76:79]
	v_mfma_f32_16x16x32_bf16 v[72:75], v[186:189], v[232:235], v[72:75]
	v_mfma_f32_16x16x32_bf16 v[68:71], v[174:177], v[240:243], v[68:71]
	v_mfma_f32_16x16x32_bf16 v[64:67], v[186:189], v[240:243], v[64:67]
	s_setprio 0
	s_setprio 1
	v_mfma_f32_16x16x32_bf16 v[28:31], v[190:193], v[212:215], v[28:31]
	v_mfma_f32_16x16x32_bf16 v[24:27], v[198:201], v[212:215], v[24:27]
	v_mfma_f32_16x16x32_bf16 v[20:23], v[190:193], v[220:223], v[20:23]
	v_mfma_f32_16x16x32_bf16 v[16:19], v[198:201], v[220:223], v[16:19]
	v_mfma_f32_16x16x32_bf16 v[12:15], v[190:193], v[228:231], v[12:15]
	v_mfma_f32_16x16x32_bf16 v[8:11], v[198:201], v[228:231], v[8:11]
	v_mfma_f32_16x16x32_bf16 v[4:7], v[190:193], v[236:239], v[4:7]
	v_mfma_f32_16x16x32_bf16 v[0:3], v[198:201], v[236:239], v[0:3]
	v_mfma_f32_16x16x32_bf16 v[28:31], v[194:197], v[216:219], v[28:31]
	v_mfma_f32_16x16x32_bf16 v[24:27], v[208:211], v[216:219], v[24:27]
	v_mfma_f32_16x16x32_bf16 v[20:23], v[194:197], v[224:227], v[20:23]
	v_mfma_f32_16x16x32_bf16 v[16:19], v[208:211], v[224:227], v[16:19]
	v_lshl_add_u64 v[246:247], s[62:63], 0, v[132:133]
	s_mov_b32 m0, s86
	s_nop 0
	global_load_lds_dwordx4 v[246:247], off
	v_mfma_f32_16x16x32_bf16 v[12:15], v[194:197], v[232:235], v[12:15]
	v_mfma_f32_16x16x32_bf16 v[8:11], v[208:211], v[232:235], v[8:11]
	v_mfma_f32_16x16x32_bf16 v[4:7], v[194:197], v[240:243], v[4:7]
	v_mfma_f32_16x16x32_bf16 v[0:3], v[208:211], v[240:243], v[0:3]
	s_setprio 0
	s_barrier
; #define PG8_STAGE(bufoff, gbase, voff) do { _Pragma("unroll") for (int _i = 0; _i < 2; ++_i) \
;         __builtin_amdgcn_global_load_lds((const unsigned*)((const char*)(gbase) + (voff)[_i]), (PG8_LAS unsigned*)(lds + (bufoff) + ldsw + _i * 8192), 16, 0, 0); } while (0)
; #define PG8_LDA(dst, b, h) do { _Pragma("unroll") for (int m = 0; m < 4; ++m) _Pragma("unroll") for (int k = 0; k < 2; ++k) dst[m][k] = *(const PG8_LAS bf16x8*)(lds + PG8_SA(b, h) + aoff + m * 2048 + k * 1024); } while (0)
; #define PG8_LDB(dst, b, h) do { _Pragma("unroll") for (int n = 0; n < 2; ++n) _Pragma("unroll") for (int k = 0; k < 2; ++k) dst[n][k] = *(const PG8_LAS bf16x8*)(lds + PG8_SB(b, h) + boff + n * 2048 + k * 1024); } while (0)
; #define PG8_MMA(ai, bj, At, Bt) do { __builtin_amdgcn_s_setprio(1); _Pragma("unroll") for (int m = 0; m < 4; ++m) _Pragma("unroll") for (int n = 0; n < 2; ++n) _Pragma("unroll") for (int k = 0; k < 2; ++k) \
;         acc[ai][bj][m][n] = __builtin_amdgcn_mfma_f32_16x16x32_bf16(Bt[n][k], At[m][k], acc[ai][bj][m][n], 0, 0, 0); __builtin_amdgcn_s_setprio(0); } while (0)
; #define PG8_WAIT_V(n) asm volatile("s_waitcnt vmcnt(" #n ")" ::: "memory")
; #define PG8_WAIT_L(n) asm volatile("s_waitcnt lgkmcnt(" #n ")" ::: "memory")
; #define PG8_BAR __builtin_amdgcn_s_barrier()
; #define PG8_SCHED __builtin_amdgcn_sched_barrier(0)
; template <class Epi, class Sched, bool ALIGN_EPI = false, bool SP2 = false>
; __device__ __forceinline__ void gemm_phase(PG8_LAS unsigned char* lds, const Gemm g, const Sched& S, const Epi& E) {
;     ...
;             PG8_LDB(B0, 1, 0); PG8_LDB(B1, 1, 1); PG8_SCHED; PG8_LDA(At, 1, 0); PG8_STAGE(PG8_SA(0, 1), a2 + hstep, voffA);
;             PG8_WAIT_V(8); PG8_WAIT_L(0); PG8_BAR; PG8_MMA(0, 0, At, B0); PG8_MMA(0, 1, At, B1); PG8_BAR; PG8_SCHED;
	s_add_i32 s3, 0, 0x18000
	v_add_u32_e32 v136, s3, v141
	s_add_i32 s33, 0, 0x1c000
	ds_read_b128 v[170:173], v136
	ds_read_b128 v[174:177], v136 offset:1024
	ds_read_b128 v[182:185], v136 offset:2048
	ds_read_b128 v[186:189], v136 offset:3072
	v_add_u32_e32 v136, s33, v141
	ds_read_b128 v[190:193], v136
	ds_read_b128 v[194:197], v136 offset:1024
	ds_read_b128 v[198:201], v136 offset:2048
	ds_read_b128 v[208:211], v136 offset:3072
	s_add_u32 s14, s62, 0x40000
	s_addc_u32 s15, s63, 0
	s_mov_b32 m0, s87
	v_lshl_add_u64 v[248:249], s[14:15], 0, v[128:129]
	ds_read_b128 v[212:215], v164 offset:32768
	ds_read_b128 v[216:219], v164 offset:33792
	ds_read_b128 v[220:223], v164 offset:34816
	ds_read_b128 v[224:227], v164 offset:35840
	ds_read_b128 v[228:231], v164 offset:36864
	ds_read_b128 v[232:235], v164 offset:37888
	ds_read_b128 v[236:239], v164 offset:38912
	ds_read_b128 v[240:243], v164 offset:39936
	global_load_lds_dwordx4 v[248:249], off
	v_lshl_add_u64 v[248:249], s[14:15], 0, v[132:133]
	s_mov_b32 m0, s88
	s_nop 0
	global_load_lds_dwordx4 v[248:249], off
	s_waitcnt vmcnt(8)
	s_waitcnt lgkmcnt(0)
	s_barrier
	s_setprio 1
	s_waitcnt lgkmcnt(0)
	v_mfma_f32_16x16x32_bf16 v[124:127], v[170:173], v[212:215], v[124:127]
	v_mfma_f32_16x16x32_bf16 v[120:123], v[182:185], v[212:215], v[120:123]
	v_mfma_f32_16x16x32_bf16 v[116:119], v[170:173], v[220:223], v[116:119]
	v_mfma_f32_16x16x32_bf16 v[112:115], v[182:185], v[220:223], v[112:115]
	v_mfma_f32_16x16x32_bf16 v[108:111], v[170:173], v[228:231], v[108:111]
	v_mfma_f32_16x16x32_bf16 v[104:107], v[182:185], v[228:231], v[104:107]
	v_mfma_f32_16x16x32_bf16 v[100:103], v[170:173], v[236:239], v[100:103]
	v_mfma_f32_16x16x32_bf16 v[96:99], v[182:185], v[236:239], v[96:99]
	v_mfma_f32_16x16x32_bf16 v[124:127], v[174:177], v[216:219], v[124:127]
	v_mfma_f32_16x16x32_bf16 v[120:123], v[186:189], v[216:219], v[120:123]
	v_mfma_f32_16x16x32_bf16 v[116:119], v[174:177], v[224:227], v[116:119]
	v_mfma_f32_16x16x32_bf16 v[112:115], v[186:189], v[224:227], v[112:115]
	v_mfma_f32_16x16x32_bf16 v[108:111], v[174:177], v[232:235], v[108:111]
	v_mfma_f32_16x16x32_bf16 v[104:107], v[186:189], v[232:235], v[104:107]
	v_mfma_f32_16x16x32_bf16 v[100:103], v[174:177], v[240:243], v[100:103]
	v_mfma_f32_16x16x32_bf16 v[96:99], v[186:189], v[240:243], v[96:99]
	s_setprio 0
	s_setprio 1
	v_mfma_f32_16x16x32_bf16 v[60:63], v[190:193], v[212:215], v[60:63]
	v_mfma_f32_16x16x32_bf16 v[56:59], v[198:201], v[212:215], v[56:59]
	v_mfma_f32_16x16x32_bf16 v[52:55], v[190:193], v[220:223], v[52:55]
	v_mfma_f32_16x16x32_bf16 v[48:51], v[198:201], v[220:223], v[48:51]
	v_mfma_f32_16x16x32_bf16 v[44:47], v[190:193], v[228:231], v[44:47]
	v_mfma_f32_16x16x32_bf16 v[40:43], v[198:201], v[228:231], v[40:43]
	v_mfma_f32_16x16x32_bf16 v[36:39], v[190:193], v[236:239], v[36:39]
	v_mfma_f32_16x16x32_bf16 v[32:35], v[198:201], v[236:239], v[32:35]
	v_mfma_f32_16x16x32_bf16 v[60:63], v[194:197], v[216:219], v[60:63]
	v_mfma_f32_16x16x32_bf16 v[56:59], v[208:211], v[216:219], v[56:59]
	v_mfma_f32_16x16x32_bf16 v[52:55], v[194:197], v[224:227], v[52:55]
	v_mfma_f32_16x16x32_bf16 v[48:51], v[208:211], v[224:227], v[48:51]
	v_mfma_f32_16x16x32_bf16 v[44:47], v[194:197], v[232:235], v[44:47]
	v_mfma_f32_16x16x32_bf16 v[40:43], v[208:211], v[232:235], v[40:43]
	v_mfma_f32_16x16x32_bf16 v[36:39], v[194:197], v[240:243], v[36:39]
	v_mfma_f32_16x16x32_bf16 v[32:35], v[208:211], v[240:243], v[32:35]
	s_setprio 0
	s_barrier
; #define PG8_STAGE(bufoff, gbase, voff) do { _Pragma("unroll") for (int _i = 0; _i < 2; ++_i) \
;         __builtin_amdgcn_global_load_lds((const unsigned*)((const char*)(gbase) + (voff)[_i]), (PG8_LAS unsigned*)(lds + (bufoff) + ldsw + _i * 8192), 16, 0, 0); } while (0)
; #define PG8_LDA(dst, b, h) do { _Pragma("unroll") for (int m = 0; m < 4; ++m) _Pragma("unroll") for (int k = 0; k < 2; ++k) dst[m][k] = *(const PG8_LAS bf16x8*)(lds + PG8_SA(b, h) + aoff + m * 2048 + k * 1024); } while (0)
; #define PG8_MMA(ai, bj, At, Bt) do { __builtin_amdgcn_s_setprio(1); _Pragma("unroll") for (int m = 0; m < 4; ++m) _Pragma("unroll") for (int n = 0; n < 2; ++n) _Pragma("unroll") for (int k = 0; k < 2; ++k) \
;         acc[ai][bj][m][n] = __builtin_amdgcn_mfma_f32_16x16x32_bf16(Bt[n][k], At[m][k], acc[ai][bj][m][n], 0, 0, 0); __builtin_amdgcn_s_setprio(0); } while (0)
; #define PG8_WAIT_V(n) asm volatile("s_waitcnt vmcnt(" #n ")" ::: "memory")
; #define PG8_WAIT_L(n) asm volatile("s_waitcnt lgkmcnt(" #n ")" ::: "memory")
; #define PG8_BAR __builtin_amdgcn_s_barrier()
; #define PG8_SCHED __builtin_amdgcn_sched_barrier(0)
; template <class Epi, class Sched, bool ALIGN_EPI = false, bool SP2 = false>
; __device__ __forceinline__ void gemm_phase(PG8_LAS unsigned char* lds, const Gemm g, const Sched& S, const Epi& E) {
;     ...
;         for (int t = 0; t < nt; t += 2) {
;     ...
;             PG8_LDA(At, 1, 1); PG8_STAGE(PG8_SB(1, 0), b3, voffB); PG8_STAGE(PG8_SB(1, 1), b3 + hstep, voffB); PG8_STAGE(PG8_SA(1, 0), a3, voffA);
;             PG8_WAIT_V(8); PG8_WAIT_L(0); PG8_BAR; PG8_MMA(1, 0, At, B0); PG8_MMA(1, 1, At, B1); PG8_BAR; PG8_SCHED;
	s_add_i32 s3, s3, s84
	v_lshl_add_u64 v[178:179], v[178:179], 0, s[8:9]
	s_mov_b32 m0, s3
	ds_read_b128 v[212:215], v164 offset:49152
	ds_read_b128 v[216:219], v164 offset:50176
	ds_read_b128 v[220:223], v164 offset:51200
	ds_read_b128 v[224:227], v164 offset:52224
	ds_read_b128 v[228:231], v164 offset:53248
	ds_read_b128 v[232:235], v164 offset:54272
	ds_read_b128 v[236:239], v164 offset:55296
	ds_read_b128 v[240:243], v164 offset:56320
	global_load_lds_dwordx4 v[178:179], off
	s_add_i32 m0, s3, 0x2000
	s_add_u32 s14, s60, 0x40080
	v_lshl_add_u64 v[178:179], v[202:203], 0, s[8:9]
	s_addc_u32 s15, s61, 0
	s_add_i32 s3, s33, s84
	global_load_lds_dwordx4 v[178:179], off
	v_lshl_add_u64 v[178:179], s[14:15], 0, v[130:131]
	s_mov_b32 m0, s3
	s_nop 0
	global_load_lds_dwordx4 v[178:179], off
	v_lshl_add_u64 v[178:179], s[14:15], 0, v[134:135]
	s_add_i32 m0, s3, 0x2000
	s_nop 0
	global_load_lds_dwordx4 v[178:179], off
	s_waitcnt vmcnt(6)
	s_waitcnt lgkmcnt(0)
	s_barrier
	s_setprio 1
	s_waitcnt lgkmcnt(0)
	v_mfma_f32_16x16x32_bf16 v[92:95], v[170:173], v[212:215], v[92:95]
	v_mfma_f32_16x16x32_bf16 v[88:91], v[182:185], v[212:215], v[88:91]
	v_mfma_f32_16x16x32_bf16 v[84:87], v[170:173], v[220:223], v[84:87]
	v_mfma_f32_16x16x32_bf16 v[80:83], v[182:185], v[220:223], v[80:83]
	v_mfma_f32_16x16x32_bf16 v[76:79], v[170:173], v[228:231], v[76:79]
	v_mfma_f32_16x16x32_bf16 v[72:75], v[182:185], v[228:231], v[72:75]
	v_mfma_f32_16x16x32_bf16 v[68:71], v[170:173], v[236:239], v[68:71]
	v_mfma_f32_16x16x32_bf16 v[64:67], v[182:185], v[236:239], v[64:67]
	v_mfma_f32_16x16x32_bf16 v[92:95], v[174:177], v[216:219], v[92:95]
	v_mfma_f32_16x16x32_bf16 v[88:91], v[186:189], v[216:219], v[88:91]
	v_mfma_f32_16x16x32_bf16 v[84:87], v[174:177], v[224:227], v[84:87]
	v_mfma_f32_16x16x32_bf16 v[80:83], v[186:189], v[224:227], v[80:83]
	v_lshl_add_u64 v[178:179], v[244:245], 0, s[8:9]
	s_mov_b32 m0, s90
	s_nop 0
	global_load_lds_dwordx4 v[178:179], off
	v_mfma_f32_16x16x32_bf16 v[76:79], v[174:177], v[232:235], v[76:79]
	v_mfma_f32_16x16x32_bf16 v[72:75], v[186:189], v[232:235], v[72:75]
	v_mfma_f32_16x16x32_bf16 v[68:71], v[174:177], v[240:243], v[68:71]
	v_mfma_f32_16x16x32_bf16 v[64:67], v[186:189], v[240:243], v[64:67]
	s_setprio 0
	s_setprio 1
	v_mfma_f32_16x16x32_bf16 v[28:31], v[190:193], v[212:215], v[28:31]
	v_mfma_f32_16x16x32_bf16 v[24:27], v[198:201], v[212:215], v[24:27]
	v_mfma_f32_16x16x32_bf16 v[20:23], v[190:193], v[220:223], v[20:23]
	v_mfma_f32_16x16x32_bf16 v[16:19], v[198:201], v[220:223], v[16:19]
	v_mfma_f32_16x16x32_bf16 v[12:15], v[190:193], v[228:231], v[12:15]
	v_mfma_f32_16x16x32_bf16 v[8:11], v[198:201], v[228:231], v[8:11]
	v_mfma_f32_16x16x32_bf16 v[4:7], v[190:193], v[236:239], v[4:7]
	v_mfma_f32_16x16x32_bf16 v[0:3], v[198:201], v[236:239], v[0:3]
	v_mfma_f32_16x16x32_bf16 v[28:31], v[194:197], v[216:219], v[28:31]
	v_mfma_f32_16x16x32_bf16 v[24:27], v[208:211], v[216:219], v[24:27]
	v_mfma_f32_16x16x32_bf16 v[20:23], v[194:197], v[224:227], v[20:23]
	v_mfma_f32_16x16x32_bf16 v[16:19], v[208:211], v[224:227], v[16:19]
	v_lshl_add_u64 v[178:179], v[246:247], 0, s[8:9]
	s_mov_b32 m0, s91
	s_nop 0
	global_load_lds_dwordx4 v[178:179], off
	v_mfma_f32_16x16x32_bf16 v[12:15], v[194:197], v[232:235], v[12:15]
	v_mfma_f32_16x16x32_bf16 v[8:11], v[208:211], v[232:235], v[8:11]
	v_mfma_f32_16x16x32_bf16 v[4:7], v[194:197], v[240:243], v[4:7]
	v_mfma_f32_16x16x32_bf16 v[0:3], v[208:211], v[240:243], v[0:3]
	s_setprio 0
	s_barrier
	s_add_i32 vcc_lo, vcc_lo, 2
	s_add_u32 s58, s58, 0x100
	s_addc_u32 s59, s59, 0
	s_add_u32 s96, s96, 0x100
	s_addc_u32 s97, s97, 0
	s_cmp_gt_u32 vcc_lo, 13
	s_cbranch_scc0 .LBB0_459
	s_and_b64 vcc, exec, s[10:11]
	s_cbranch_vccz .LBB0_462
	s_barrier

; #define PG8_STAGE(bufoff, gbase, voff) do { _Pragma("unroll") for (int _i = 0; _i < 2; ++_i) \
;         __builtin_amdgcn_global_load_lds((const unsigned*)((const char*)(gbase) + (voff)[_i]), (PG8_LAS unsigned*)(lds + (bufoff) + ldsw + _i * 8192), 16, 0, 0); } while (0)
; #define PG8_LDA(dst, b, h) do { _Pragma("unroll") for (int m = 0; m < 4; ++m) _Pragma("unroll") for (int k = 0; k < 2; ++k) dst[m][k] = *(const PG8_LAS bf16x8*)(lds + PG8_SA(b, h) + aoff + m * 2048 + k * 1024); } while (0)
; #define PG8_LDB(dst, b, h) do { _Pragma("unroll") for (int n = 0; n < 2; ++n) _Pragma("unroll") for (int k = 0; k < 2; ++k) dst[n][k] = *(const PG8_LAS bf16x8*)(lds + PG8_SB(b, h) + boff + n * 2048 + k * 1024); } while (0)
; #define PG8_MMA(ai, bj, At, Bt) do { __builtin_amdgcn_s_setprio(1); _Pragma("unroll") for (int m = 0; m < 4; ++m) _Pragma("unroll") for (int n = 0; n < 2; ++n) _Pragma("unroll") for (int k = 0; k < 2; ++k) \
;         acc[ai][bj][m][n] = __builtin_amdgcn_mfma_f32_16x16x32_bf16(Bt[n][k], At[m][k], acc[ai][bj][m][n], 0, 0, 0); __builtin_amdgcn_s_setprio(0); } while (0)
; #define PG8_BAR __builtin_amdgcn_s_barrier()
; template <class Epi, class Sched, bool ALIGN_EPI = false, bool SP2 = false>
; __device__ __forceinline__ void gemm_phase(PG8_LAS unsigned char* lds, const Gemm g, const Sched& S, const Epi& E) {
;     ...
;         const bool has_next = S.next(ui + 1, nxt);
;         const char* nA = has_next ? (const char*)g.A + (size_t)nxt.pm * tstep : cA; const char* nB = has_next ? (const char*)g.Bt + (size_t)nxt.pn * tstep : cB;
;         for (int t = 0; t < nt; t += 2) {
;             const bool last = (t == nt - 2);
;             const char* a1 = cA + (size_t)(t + 1) * kstep;
;             const char* a2 = last ? nA : cA + (size_t)(t + 2) * kstep; const char* b2 = last ? nB : cB + (size_t)(t + 2) * kstep;
;             const char* a3 = a2 + kstep; const char* b3 = b2 + kstep;
;             if (last && has_next) S.a_ready(nxt);
;             if constexpr (SP2) {
;             PG8_LDB(B0, 0, 0); PG8_LDB(B1, 0, 1); PG8_SCHED; PG8_LDA(At, 0, 0); PG8_STAGE(PG8_SA(1, 1), a1 + hstep, voffA);
;             PG8_WAIT_V(8); PG8_WAIT_L(0); PG8_BAR; PG8_MMA(0, 0, At, B0); PG8_MMA(0, 1, At, B1); PG8_BAR; PG8_SCHED;
;             PG8_LDA(At, 0, 1); PG8_STAGE(PG8_SB(0, 0), b2, voffB); PG8_STAGE(PG8_SB(0, 1), b2 + hstep, voffB); PG8_STAGE(PG8_SA(0, 0), a2, voffA);
.LBB0_495:
	ds_read_b128 v[170:173], v165
	ds_read_b128 v[174:177], v165 offset:1024
	ds_read_b128 v[182:185], v165 offset:2048
	ds_read_b128 v[186:189], v165 offset:3072
	ds_read_b128 v[190:193], v168
	ds_read_b128 v[194:197], v168 offset:1024
	ds_read_b128 v[198:201], v168 offset:2048
	ds_read_b128 v[208:211], v168 offset:3072
	s_add_u32 s3, s60, 0xfffc0080
	s_addc_u32 s14, s61, -1
	s_cmp_eq_u32 s97, 12
	s_cselect_b32 s65, s49, s14
	s_cselect_b32 s64, s57, s3
	s_cselect_b32 s63, s45, s96
	s_cselect_b32 s62, s94, s95
	v_lshl_add_u64 v[178:179], s[60:61], 0, v[160:161]
	s_add_i32 m0, s59, 0xc000
	ds_read_b128 v[212:215], v164
	ds_read_b128 v[216:219], v164 offset:1024
	ds_read_b128 v[220:223], v164 offset:2048
	ds_read_b128 v[224:227], v164 offset:3072
	ds_read_b128 v[228:231], v164 offset:4096
	ds_read_b128 v[232:235], v164 offset:5120
	ds_read_b128 v[236:239], v164 offset:6144
	ds_read_b128 v[240:243], v164 offset:7168
	global_load_lds_dwordx4 v[178:179], off
	v_lshl_add_u64 v[178:179], s[60:61], 0, v[162:163]
	s_add_i32 m0, s59, 0xe000
	s_nop 0
	global_load_lds_dwordx4 v[178:179], off
	s_waitcnt vmcnt(8)
	s_waitcnt lgkmcnt(0)
	s_barrier
	s_setprio 1
	s_waitcnt lgkmcnt(0)
	v_mfma_f32_16x16x32_bf16 v[124:127], v[170:173], v[212:215], v[124:127]
	v_mfma_f32_16x16x32_bf16 v[120:123], v[182:185], v[212:215], v[120:123]
	v_mfma_f32_16x16x32_bf16 v[116:119], v[170:173], v[220:223], v[116:119]
	v_mfma_f32_16x16x32_bf16 v[112:115], v[182:185], v[220:223], v[112:115]
	v_mfma_f32_16x16x32_bf16 v[108:111], v[170:173], v[228:231], v[108:111]
	v_mfma_f32_16x16x32_bf16 v[104:107], v[182:185], v[228:231], v[104:107]
	v_mfma_f32_16x16x32_bf16 v[100:103], v[170:173], v[236:239], v[100:103]
	v_mfma_f32_16x16x32_bf16 v[96:99], v[182:185], v[236:239], v[96:99]
	v_mfma_f32_16x16x32_bf16 v[124:127], v[174:177], v[216:219], v[124:127]
	v_mfma_f32_16x16x32_bf16 v[120:123], v[186:189], v[216:219], v[120:123]
	v_mfma_f32_16x16x32_bf16 v[116:119], v[174:177], v[224:227], v[116:119]
	v_mfma_f32_16x16x32_bf16 v[112:115], v[186:189], v[224:227], v[112:115]
	v_mfma_f32_16x16x32_bf16 v[108:111], v[174:177], v[232:235], v[108:111]
	v_mfma_f32_16x16x32_bf16 v[104:107], v[186:189], v[232:235], v[104:107]
	v_mfma_f32_16x16x32_bf16 v[100:103], v[174:177], v[240:243], v[100:103]
	v_mfma_f32_16x16x32_bf16 v[96:99], v[186:189], v[240:243], v[96:99]
	s_setprio 0
	s_setprio 1
	v_mfma_f32_16x16x32_bf16 v[60:63], v[190:193], v[212:215], v[60:63]
	v_mfma_f32_16x16x32_bf16 v[56:59], v[198:201], v[212:215], v[56:59]
	v_mfma_f32_16x16x32_bf16 v[52:55], v[190:193], v[220:223], v[52:55]
	v_mfma_f32_16x16x32_bf16 v[48:51], v[198:201], v[220:223], v[48:51]
	v_mfma_f32_16x16x32_bf16 v[44:47], v[190:193], v[228:231], v[44:47]
	v_mfma_f32_16x16x32_bf16 v[40:43], v[198:201], v[228:231], v[40:43]
	v_mfma_f32_16x16x32_bf16 v[36:39], v[190:193], v[236:239], v[36:39]
	v_mfma_f32_16x16x32_bf16 v[32:35], v[198:201], v[236:239], v[32:35]
	v_mfma_f32_16x16x32_bf16 v[60:63], v[194:197], v[216:219], v[60:63]
	v_mfma_f32_16x16x32_bf16 v[56:59], v[208:211], v[216:219], v[56:59]
	v_mfma_f32_16x16x32_bf16 v[52:55], v[194:197], v[224:227], v[52:55]
	v_mfma_f32_16x16x32_bf16 v[48:51], v[208:211], v[224:227], v[48:51]
	v_mfma_f32_16x16x32_bf16 v[44:47], v[194:197], v[232:235], v[44:47]
	v_mfma_f32_16x16x32_bf16 v[40:43], v[208:211], v[232:235], v[40:43]
	v_mfma_f32_16x16x32_bf16 v[36:39], v[194:197], v[240:243], v[36:39]
	v_mfma_f32_16x16x32_bf16 v[32:35], v[208:211], v[240:243], v[32:35]
	s_setprio 0
	s_barrier
	s_add_i32 s3, s92, s75
	v_lshl_add_u64 v[178:179], s[62:63], 0, v[130:131]
	s_mov_b32 m0, s3
	ds_read_b128 v[212:215], v164 offset:16384
	ds_read_b128 v[216:219], v164 offset:17408
	ds_read_b128 v[220:223], v164 offset:18432
	ds_read_b128 v[224:227], v164 offset:19456
	ds_read_b128 v[228:231], v164 offset:20480
	ds_read_b128 v[232:235], v164 offset:21504
	ds_read_b128 v[236:239], v164 offset:22528
	ds_read_b128 v[240:243], v164 offset:23552
	global_load_lds_dwordx4 v[178:179], off
	s_add_i32 m0, s3, 0x2000
	s_add_u32 s14, s62, 0x40000
	v_lshl_add_u64 v[202:203], s[62:63], 0, v[134:135]
	s_addc_u32 s15, s63, 0
	s_add_i32 s3, s93, s75
	global_load_lds_dwordx4 v[202:203], off
	v_lshl_add_u64 v[244:245], s[14:15], 0, v[130:131]
	s_mov_b32 m0, s3
	global_load_lds_dwordx4 v[244:245], off
	v_lshl_add_u64 v[244:245], s[14:15], 0, v[134:135]
	s_add_i32 m0, s3, 0x2000
	s_nop 0
	global_load_lds_dwordx4 v[244:245], off
	s_waitcnt vmcnt(6)
	s_waitcnt lgkmcnt(0)
	s_barrier
; #define PG8_STAGE(bufoff, gbase, voff) do { _Pragma("unroll") for (int _i = 0; _i < 2; ++_i) \
;         __builtin_amdgcn_global_load_lds((const unsigned*)((const char*)(gbase) + (voff)[_i]), (PG8_LAS unsigned*)(lds + (bufoff) + ldsw + _i * 8192), 16, 0, 0); } while (0)
; #define PG8_LDA(dst, b, h) do { _Pragma("unroll") for (int m = 0; m < 4; ++m) _Pragma("unroll") for (int k = 0; k < 2; ++k) dst[m][k] = *(const PG8_LAS bf16x8*)(lds + PG8_SA(b, h) + aoff + m * 2048 + k * 1024); } while (0)
; #define PG8_LDB(dst, b, h) do { _Pragma("unroll") for (int n = 0; n < 2; ++n) _Pragma("unroll") for (int k = 0; k < 2; ++k) dst[n][k] = *(const PG8_LAS bf16x8*)(lds + PG8_SB(b, h) + boff + n * 2048 + k * 1024); } while (0)
; #define PG8_MMA(ai, bj, At, Bt) do { __builtin_amdgcn_s_setprio(1); _Pragma("unroll") for (int m = 0; m < 4; ++m) _Pragma("unroll") for (int n = 0; n < 2; ++n) _Pragma("unroll") for (int k = 0; k < 2; ++k) \
;         acc[ai][bj][m][n] = __builtin_amdgcn_mfma_f32_16x16x32_bf16(Bt[n][k], At[m][k], acc[ai][bj][m][n], 0, 0, 0); __builtin_amdgcn_s_setprio(0); } while (0)
; #define PG8_WAIT_V(n) asm volatile("s_waitcnt vmcnt(" #n ")" ::: "memory")
; #define PG8_WAIT_L(n) asm volatile("s_waitcnt lgkmcnt(" #n ")" ::: "memory")
; #define PG8_BAR __builtin_amdgcn_s_barrier()
; #define PG8_SCHED __builtin_amdgcn_sched_barrier(0)
; template <class Epi, class Sched, bool ALIGN_EPI = false, bool SP2 = false>
; __device__ __forceinline__ void gemm_phase(PG8_LAS unsigned char* lds, const Gemm g, const Sched& S, const Epi& E) {
;     ...
;             PG8_LDA(At, 0, 1); PG8_STAGE(PG8_SB(0, 0), b2, voffB); PG8_STAGE(PG8_SB(0, 1), b2 + hstep, voffB); PG8_STAGE(PG8_SA(0, 0), a2, voffA);
;             PG8_WAIT_V(8); PG8_WAIT_L(0); PG8_BAR; PG8_MMA(1, 0, At, B0); PG8_MMA(1, 1, At, B1); PG8_BAR; PG8_SCHED;
;             PG8_LDB(B0, 1, 0); PG8_LDB(B1, 1, 1); PG8_SCHED; PG8_LDA(At, 1, 0); PG8_STAGE(PG8_SA(0, 1), a2 + hstep, voffA);
;             PG8_WAIT_V(8); PG8_WAIT_L(0); PG8_BAR; PG8_MMA(0, 0, At, B0); PG8_MMA(0, 1, At, B1); PG8_BAR; PG8_SCHED;
	s_setprio 1
	s_waitcnt lgkmcnt(0)
	v_mfma_f32_16x16x32_bf16 v[92:95], v[170:173], v[212:215], v[92:95]
	v_mfma_f32_16x16x32_bf16 v[88:91], v[182:185], v[212:215], v[88:91]
	v_mfma_f32_16x16x32_bf16 v[84:87], v[170:173], v[220:223], v[84:87]
	v_mfma_f32_16x16x32_bf16 v[80:83], v[182:185], v[220:223], v[80:83]
	v_mfma_f32_16x16x32_bf16 v[76:79], v[170:173], v[228:231], v[76:79]
	v_mfma_f32_16x16x32_bf16 v[72:75], v[182:185], v[228:231], v[72:75]
	v_mfma_f32_16x16x32_bf16 v[68:71], v[170:173], v[236:239], v[68:71]
	v_mfma_f32_16x16x32_bf16 v[64:67], v[182:185], v[236:239], v[64:67]
	v_mfma_f32_16x16x32_bf16 v[92:95], v[174:177], v[216:219], v[92:95]
	v_mfma_f32_16x16x32_bf16 v[88:91], v[186:189], v[216:219], v[88:91]
	v_mfma_f32_16x16x32_bf16 v[84:87], v[174:177], v[224:227], v[84:87]
	v_mfma_f32_16x16x32_bf16 v[80:83], v[186:189], v[224:227], v[80:83]
	v_lshl_add_u64 v[244:245], s[64:65], 0, v[128:129]
	s_mov_b32 m0, s59
	s_nop 0
	global_load_lds_dwordx4 v[244:245], off
	v_mfma_f32_16x16x32_bf16 v[76:79], v[174:177], v[232:235], v[76:79]
	v_mfma_f32_16x16x32_bf16 v[72:75], v[186:189], v[232:235], v[72:75]
	v_mfma_f32_16x16x32_bf16 v[68:71], v[174:177], v[240:243], v[68:71]
	v_mfma_f32_16x16x32_bf16 v[64:67], v[186:189], v[240:243], v[64:67]
	s_setprio 0
	s_setprio 1
	v_mfma_f32_16x16x32_bf16 v[28:31], v[190:193], v[212:215], v[28:31]
	v_mfma_f32_16x16x32_bf16 v[24:27], v[198:201], v[212:215], v[24:27]
	v_mfma_f32_16x16x32_bf16 v[20:23], v[190:193], v[220:223], v[20:23]
	v_mfma_f32_16x16x32_bf16 v[16:19], v[198:201], v[220:223], v[16:19]
	v_mfma_f32_16x16x32_bf16 v[12:15], v[190:193], v[228:231], v[12:15]
	v_mfma_f32_16x16x32_bf16 v[8:11], v[198:201], v[228:231], v[8:11]
	v_mfma_f32_16x16x32_bf16 v[4:7], v[190:193], v[236:239], v[4:7]
	v_mfma_f32_16x16x32_bf16 v[0:3], v[198:201], v[236:239], v[0:3]
	v_mfma_f32_16x16x32_bf16 v[28:31], v[194:197], v[216:219], v[28:31]
	v_mfma_f32_16x16x32_bf16 v[24:27], v[208:211], v[216:219], v[24:27]
	v_mfma_f32_16x16x32_bf16 v[20:23], v[194:197], v[224:227], v[20:23]
	v_mfma_f32_16x16x32_bf16 v[16:19], v[208:211], v[224:227], v[16:19]
	v_lshl_add_u64 v[246:247], s[64:65], 0, v[132:133]
	s_mov_b32 m0, s84
	s_nop 0
	global_load_lds_dwordx4 v[246:247], off
	v_mfma_f32_16x16x32_bf16 v[12:15], v[194:197], v[232:235], v[12:15]
	v_mfma_f32_16x16x32_bf16 v[8:11], v[208:211], v[232:235], v[8:11]
	v_mfma_f32_16x16x32_bf16 v[4:7], v[194:197], v[240:243], v[4:7]
	v_mfma_f32_16x16x32_bf16 v[0:3], v[208:211], v[240:243], v[0:3]
	s_setprio 0
	s_barrier
	s_add_i32 s3, 0, 0x18000
	v_add_u32_e32 v136, s3, v141
	s_add_i32 s33, 0, 0x1c000
	ds_read_b128 v[170:173], v136
	ds_read_b128 v[174:177], v136 offset:1024
	ds_read_b128 v[182:185], v136 offset:2048
	ds_read_b128 v[186:189], v136 offset:3072
	v_add_u32_e32 v136, s33, v141
	ds_read_b128 v[190:193], v136
	ds_read_b128 v[194:197], v136 offset:1024
	ds_read_b128 v[198:201], v136 offset:2048
	ds_read_b128 v[208:211], v136 offset:3072
	s_add_u32 s14, s64, 0x40000
	s_addc_u32 s15, s65, 0
	s_mov_b32 m0, s85
	v_lshl_add_u64 v[248:249], s[14:15], 0, v[128:129]
	ds_read_b128 v[212:215], v164 offset:32768
	ds_read_b128 v[216:219], v164 offset:33792
	ds_read_b128 v[220:223], v164 offset:34816
	ds_read_b128 v[224:227], v164 offset:35840
	ds_read_b128 v[228:231], v164 offset:36864
	ds_read_b128 v[232:235], v164 offset:37888
	ds_read_b128 v[236:239], v164 offset:38912
	ds_read_b128 v[240:243], v164 offset:39936
	global_load_lds_dwordx4 v[248:249], off
	v_lshl_add_u64 v[248:249], s[14:15], 0, v[132:133]
	s_mov_b32 m0, s86
	s_nop 0
	global_load_lds_dwordx4 v[248:249], off
	s_waitcnt vmcnt(8)
	s_waitcnt lgkmcnt(0)
	s_barrier
	s_setprio 1
	s_waitcnt lgkmcnt(0)
	v_mfma_f32_16x16x32_bf16 v[124:127], v[170:173], v[212:215], v[124:127]
	v_mfma_f32_16x16x32_bf16 v[120:123], v[182:185], v[212:215], v[120:123]
	v_mfma_f32_16x16x32_bf16 v[116:119], v[170:173], v[220:223], v[116:119]
	v_mfma_f32_16x16x32_bf16 v[112:115], v[182:185], v[220:223], v[112:115]
	v_mfma_f32_16x16x32_bf16 v[108:111], v[170:173], v[228:231], v[108:111]
	v_mfma_f32_16x16x32_bf16 v[104:107], v[182:185], v[228:231], v[104:107]
	v_mfma_f32_16x16x32_bf16 v[100:103], v[170:173], v[236:239], v[100:103]
	v_mfma_f32_16x16x32_bf16 v[96:99], v[182:185], v[236:239], v[96:99]
	v_mfma_f32_16x16x32_bf16 v[124:127], v[174:177], v[216:219], v[124:127]
	v_mfma_f32_16x16x32_bf16 v[120:123], v[186:189], v[216:219], v[120:123]
	v_mfma_f32_16x16x32_bf16 v[116:119], v[174:177], v[224:227], v[116:119]
	v_mfma_f32_16x16x32_bf16 v[112:115], v[186:189], v[224:227], v[112:115]
	v_mfma_f32_16x16x32_bf16 v[108:111], v[174:177], v[232:235], v[108:111]
	v_mfma_f32_16x16x32_bf16 v[104:107], v[186:189], v[232:235], v[104:107]
	v_mfma_f32_16x16x32_bf16 v[100:103], v[174:177], v[240:243], v[100:103]
	v_mfma_f32_16x16x32_bf16 v[96:99], v[186:189], v[240:243], v[96:99]
	s_setprio 0
	s_setprio 1
	v_mfma_f32_16x16x32_bf16 v[60:63], v[190:193], v[212:215], v[60:63]
	v_mfma_f32_16x16x32_bf16 v[56:59], v[198:201], v[212:215], v[56:59]
	v_mfma_f32_16x16x32_bf16 v[52:55], v[190:193], v[220:223], v[52:55]
	v_mfma_f32_16x16x32_bf16 v[48:51], v[198:201], v[220:223], v[48:51]
	v_mfma_f32_16x16x32_bf16 v[44:47], v[190:193], v[228:231], v[44:47]
	v_mfma_f32_16x16x32_bf16 v[40:43], v[198:201], v[228:231], v[40:43]
	v_mfma_f32_16x16x32_bf16 v[36:39], v[190:193], v[236:239], v[36:39]
	v_mfma_f32_16x16x32_bf16 v[32:35], v[198:201], v[236:239], v[32:35]
	v_mfma_f32_16x16x32_bf16 v[60:63], v[194:197], v[216:219], v[60:63]
	v_mfma_f32_16x16x32_bf16 v[56:59], v[208:211], v[216:219], v[56:59]
	v_mfma_f32_16x16x32_bf16 v[52:55], v[194:197], v[224:227], v[52:55]
	v_mfma_f32_16x16x32_bf16 v[48:51], v[208:211], v[224:227], v[48:51]
	v_mfma_f32_16x16x32_bf16 v[44:47], v[194:197], v[232:235], v[44:47]
	v_mfma_f32_16x16x32_bf16 v[40:43], v[208:211], v[232:235], v[40:43]
	v_mfma_f32_16x16x32_bf16 v[36:39], v[194:197], v[240:243], v[36:39]
	v_mfma_f32_16x16x32_bf16 v[32:35], v[208:211], v[240:243], v[32:35]
	s_setprio 0
	s_barrier
; #define PG8_STAGE(bufoff, gbase, voff) do { _Pragma("unroll") for (int _i = 0; _i < 2; ++_i) \
;         __builtin_amdgcn_global_load_lds((const unsigned*)((const char*)(gbase) + (voff)[_i]), (PG8_LAS unsigned*)(lds + (bufoff) + ldsw + _i * 8192), 16, 0, 0); } while (0)
; #define PG8_LDA(dst, b, h) do { _Pragma("unroll") for (int m = 0; m < 4; ++m) _Pragma("unroll") for (int k = 0; k < 2; ++k) dst[m][k] = *(const PG8_LAS bf16x8*)(lds + PG8_SA(b, h) + aoff + m * 2048 + k * 1024); } while (0)
; #define PG8_MMA(ai, bj, At, Bt) do { __builtin_amdgcn_s_setprio(1); _Pragma("unroll") for (int m = 0; m < 4; ++m) _Pragma("unroll") for (int n = 0; n < 2; ++n) _Pragma("unroll") for (int k = 0; k < 2; ++k) \
;         acc[ai][bj][m][n] = __builtin_amdgcn_mfma_f32_16x16x32_bf16(Bt[n][k], At[m][k], acc[ai][bj][m][n], 0, 0, 0); __builtin_amdgcn_s_setprio(0); } while (0)
; #define PG8_WAIT_V(n) asm volatile("s_waitcnt vmcnt(" #n ")" ::: "memory")
; #define PG8_WAIT_L(n) asm volatile("s_waitcnt lgkmcnt(" #n ")" ::: "memory")
; #define PG8_BAR __builtin_amdgcn_s_barrier()
; #define PG8_SCHED __builtin_amdgcn_sched_barrier(0)
; template <class Epi, class Sched, bool ALIGN_EPI = false, bool SP2 = false>
; __device__ __forceinline__ void gemm_phase(PG8_LAS unsigned char* lds, const Gemm g, const Sched& S, const Epi& E) {
;     ...
;         for (int t = 0; t < nt; t += 2) {
;     ...
;             PG8_LDA(At, 1, 1); PG8_STAGE(PG8_SB(1, 0), b3, voffB); PG8_STAGE(PG8_SB(1, 1), b3 + hstep, voffB); PG8_STAGE(PG8_SA(1, 0), a3, voffA);
;             PG8_WAIT_V(8); PG8_WAIT_L(0); PG8_BAR; PG8_MMA(1, 0, At, B0); PG8_MMA(1, 1, At, B1); PG8_BAR; PG8_SCHED;
	s_add_i32 s3, s3, s75
	v_lshl_add_u64 v[178:179], v[178:179], 0, s[10:11]
	s_mov_b32 m0, s3
	ds_read_b128 v[212:215], v164 offset:49152
	ds_read_b128 v[216:219], v164 offset:50176
	ds_read_b128 v[220:223], v164 offset:51200
	ds_read_b128 v[224:227], v164 offset:52224
	ds_read_b128 v[228:231], v164 offset:53248
	ds_read_b128 v[232:235], v164 offset:54272
	ds_read_b128 v[236:239], v164 offset:55296
	ds_read_b128 v[240:243], v164 offset:56320
	global_load_lds_dwordx4 v[178:179], off
	s_add_i32 m0, s3, 0x2000
	s_add_u32 s14, s62, 0x40080
	v_lshl_add_u64 v[178:179], v[202:203], 0, s[10:11]
	s_addc_u32 s15, s63, 0
	s_add_i32 s3, s33, s75
	global_load_lds_dwordx4 v[178:179], off
	v_lshl_add_u64 v[178:179], s[14:15], 0, v[130:131]
	s_mov_b32 m0, s3
	s_nop 0
	global_load_lds_dwordx4 v[178:179], off
	v_lshl_add_u64 v[178:179], s[14:15], 0, v[134:135]
	s_add_i32 m0, s3, 0x2000
	s_nop 0
	global_load_lds_dwordx4 v[178:179], off
	s_waitcnt vmcnt(6)
	s_waitcnt lgkmcnt(0)
	s_barrier
	s_setprio 1
	s_waitcnt lgkmcnt(0)
	v_mfma_f32_16x16x32_bf16 v[92:95], v[170:173], v[212:215], v[92:95]
	v_mfma_f32_16x16x32_bf16 v[88:91], v[182:185], v[212:215], v[88:91]
	v_mfma_f32_16x16x32_bf16 v[84:87], v[170:173], v[220:223], v[84:87]
	v_mfma_f32_16x16x32_bf16 v[80:83], v[182:185], v[220:223], v[80:83]
	v_mfma_f32_16x16x32_bf16 v[76:79], v[170:173], v[228:231], v[76:79]
	v_mfma_f32_16x16x32_bf16 v[72:75], v[182:185], v[228:231], v[72:75]
	v_mfma_f32_16x16x32_bf16 v[68:71], v[170:173], v[236:239], v[68:71]
	v_mfma_f32_16x16x32_bf16 v[64:67], v[182:185], v[236:239], v[64:67]
	v_mfma_f32_16x16x32_bf16 v[92:95], v[174:177], v[216:219], v[92:95]
	v_mfma_f32_16x16x32_bf16 v[88:91], v[186:189], v[216:219], v[88:91]
	v_mfma_f32_16x16x32_bf16 v[84:87], v[174:177], v[224:227], v[84:87]
	v_mfma_f32_16x16x32_bf16 v[80:83], v[186:189], v[224:227], v[80:83]
	v_lshl_add_u64 v[178:179], v[244:245], 0, s[10:11]
	s_mov_b32 m0, s88
	s_nop 0
	global_load_lds_dwordx4 v[178:179], off
	v_mfma_f32_16x16x32_bf16 v[76:79], v[174:177], v[232:235], v[76:79]
	v_mfma_f32_16x16x32_bf16 v[72:75], v[186:189], v[232:235], v[72:75]
	v_mfma_f32_16x16x32_bf16 v[68:71], v[174:177], v[240:243], v[68:71]
	v_mfma_f32_16x16x32_bf16 v[64:67], v[186:189], v[240:243], v[64:67]
	s_setprio 0
	s_setprio 1
	v_mfma_f32_16x16x32_bf16 v[28:31], v[190:193], v[212:215], v[28:31]
	v_mfma_f32_16x16x32_bf16 v[24:27], v[198:201], v[212:215], v[24:27]
	v_mfma_f32_16x16x32_bf16 v[20:23], v[190:193], v[220:223], v[20:23]
	v_mfma_f32_16x16x32_bf16 v[16:19], v[198:201], v[220:223], v[16:19]
	v_mfma_f32_16x16x32_bf16 v[12:15], v[190:193], v[228:231], v[12:15]
	v_mfma_f32_16x16x32_bf16 v[8:11], v[198:201], v[228:231], v[8:11]
	v_mfma_f32_16x16x32_bf16 v[4:7], v[190:193], v[236:239], v[4:7]
	v_mfma_f32_16x16x32_bf16 v[0:3], v[198:201], v[236:239], v[0:3]
	v_mfma_f32_16x16x32_bf16 v[28:31], v[194:197], v[216:219], v[28:31]
	v_mfma_f32_16x16x32_bf16 v[24:27], v[208:211], v[216:219], v[24:27]
	v_mfma_f32_16x16x32_bf16 v[20:23], v[194:197], v[224:227], v[20:23]
	v_mfma_f32_16x16x32_bf16 v[16:19], v[208:211], v[224:227], v[16:19]
	v_lshl_add_u64 v[178:179], v[246:247], 0, s[10:11]
	s_mov_b32 m0, s89
	s_nop 0
	global_load_lds_dwordx4 v[178:179], off
	v_mfma_f32_16x16x32_bf16 v[12:15], v[194:197], v[232:235], v[12:15]
	v_mfma_f32_16x16x32_bf16 v[8:11], v[208:211], v[232:235], v[8:11]
	v_mfma_f32_16x16x32_bf16 v[4:7], v[194:197], v[240:243], v[4:7]
	v_mfma_f32_16x16x32_bf16 v[0:3], v[208:211], v[240:243], v[0:3]
	s_setprio 0
	s_barrier
	s_add_i32 s97, s97, 2
	s_add_u32 s60, s60, 0x100
	s_addc_u32 s61, s61, 0
	s_add_u32 s95, s95, 0x100
	s_addc_u32 s96, s96, 0
	s_cmp_lt_u32 s97, 14
	s_cbranch_scc1 .LBB0_495
	s_andn2_b64 vcc, exec, s[40:41]
	s_cbranch_vccnz .LBB0_498
	s_barrier

; #define PG8_STAGE(bufoff, gbase, voff) do { _Pragma("unroll") for (int _i = 0; _i < 2; ++_i) \
;         __builtin_amdgcn_global_load_lds((const unsigned*)((const char*)(gbase) + (voff)[_i]), (PG8_LAS unsigned*)(lds + (bufoff) + ldsw + _i * 8192), 16, 0, 0); } while (0)
; #define PG8_LDA(dst, b, h) do { _Pragma("unroll") for (int m = 0; m < 4; ++m) _Pragma("unroll") for (int k = 0; k < 2; ++k) dst[m][k] = *(const PG8_LAS bf16x8*)(lds + PG8_SA(b, h) + aoff + m * 2048 + k * 1024); } while (0)
; #define PG8_LDB(dst, b, h) do { _Pragma("unroll") for (int n = 0; n < 2; ++n) _Pragma("unroll") for (int k = 0; k < 2; ++k) dst[n][k] = *(const PG8_LAS bf16x8*)(lds + PG8_SB(b, h) + boff + n * 2048 + k * 1024); } while (0)
; #define PG8_WAIT_V(n) asm volatile("s_waitcnt vmcnt(" #n ")" ::: "memory")
; template <class Epi, class Sched, bool ALIGN_EPI = false, bool SP2 = false>
; __device__ __forceinline__ void gemm_phase(PG8_LAS unsigned char* lds, const Gemm g, const Sched& S, const Epi& E) {
;     ...
;         const bool has_next = S.next(ui + 1, nxt);
;         const char* nA = has_next ? (const char*)g.A + (size_t)nxt.pm * tstep : cA; const char* nB = has_next ? (const char*)g.Bt + (size_t)nxt.pn * tstep : cB;
;         for (int t = 0; t < nt; t += 2) {
;             const bool last = (t == nt - 2);
;             const char* a1 = cA + (size_t)(t + 1) * kstep;
;             const char* a2 = last ? nA : cA + (size_t)(t + 2) * kstep; const char* b2 = last ? nB : cB + (size_t)(t + 2) * kstep;
;             const char* a3 = a2 + kstep; const char* b3 = b2 + kstep;
;             if (last && has_next) S.a_ready(nxt);
;             if constexpr (SP2) {
;             PG8_LDB(B0, 0, 0); PG8_LDB(B1, 0, 1); PG8_SCHED; PG8_LDA(At, 0, 0); PG8_STAGE(PG8_SA(1, 1), a1 + hstep, voffA);
;             PG8_WAIT_V(8); PG8_WAIT_L(0); PG8_BAR; PG8_MMA(0, 0, At, B0); PG8_MMA(0, 1, At, B1); PG8_BAR; PG8_SCHED;
;             PG8_LDA(At, 0, 1); PG8_STAGE(PG8_SB(0, 0), b2, voffB); PG8_STAGE(PG8_SB(0, 1), b2 + hstep, voffB); PG8_STAGE(PG8_SA(0, 0), a2, voffA);
;     ...
; #pragma unroll
;         for (int a = 0; a < 2; ++a)
; #pragma unroll
;             for (int b = 0; b < 2; ++b)
; #pragma unroll
;                 for (int m = 0; m < 4; ++m)
; #pragma unroll
;                     for (int n = 0; n < 2; ++n) acc[a][b][m][n] = (f32x4){0.f, 0.f, 0.f, 0.f};
;         cur = nxt; cA = nA; cB = nB; ++ui;
.LBB0_649:
	s_ashr_i32 s51, s50, 31
	s_lshl_b64 s[14:15], s[50:51], 19
	s_add_u32 s52, s40, s14
	s_addc_u32 s53, s41, s15
	s_and_b64 s[14:15], s[8:9], exec
	s_cselect_b32 s51, s53, s61
	s_cselect_b32 s57, s52, s60
	s_ashr_i32 s49, s48, 31
	s_lshl_b64 s[14:15], s[48:49], 19
	s_add_u32 s54, s82, s14
	s_addc_u32 s55, s83, s15
	s_and_b64 s[14:15], s[8:9], exec
	s_cselect_b32 s49, s55, s63
	s_cselect_b32 s89, s54, s62
	s_add_u32 s60, s60, 0x40080
	s_addc_u32 s61, s61, 0
	s_add_u32 s90, s62, 0x100
	s_addc_u32 s91, s63, 0
	s_mov_b32 s92, -2
	s_waitcnt lgkmcnt(0)
	s_waitcnt vmcnt(0)
	ds_read_b128 v[148:151], v155
	ds_read_b128 v[160:163], v155 offset:1024
	ds_read_b128 v[164:167], v155 offset:2048
	ds_read_b128 v[168:171], v155 offset:3072
	ds_read_b128 v[172:175], v156
	ds_read_b128 v[176:179], v156 offset:1024
	ds_read_b128 v[182:185], v156 offset:2048
	ds_read_b128 v[186:189], v156 offset:3072
	s_add_u32 s3, s60, 0xfffc0080
	s_addc_u32 s14, s61, -1
	s_cmp_eq_u32 s92, 12
	s_cselect_b32 s65, s51, s14
	s_cselect_b32 s64, s57, s3
	s_cselect_b32 s63, s49, s91
	s_cselect_b32 s62, s89, s90
	v_lshl_add_u64 v[202:203], s[60:61], 0, v[140:141]
	s_add_i32 m0, s43, 0xc000
	ds_read_b128 v[190:193], v157
	ds_read_b128 v[194:197], v157 offset:1024
	ds_read_b128 v[198:201], v157 offset:2048
	ds_read_b128 v[208:211], v157 offset:3072
	ds_read_b128 v[212:215], v157 offset:4096
	ds_read_b128 v[216:219], v157 offset:5120
	ds_read_b128 v[220:223], v157 offset:6144
	ds_read_b128 v[224:227], v157 offset:7168
	global_load_lds_dwordx4 v[202:203], off
	v_lshl_add_u64 v[202:203], s[60:61], 0, v[142:143]
	s_add_i32 m0, s43, 0xe000
	s_nop 0
	global_load_lds_dwordx4 v[202:203], off
	s_waitcnt vmcnt(8)
	s_waitcnt lgkmcnt(0)
	s_barrier
	s_setprio 1
	s_waitcnt lgkmcnt(0)
	v_mfma_f32_16x16x32_bf16 v[124:127], v[148:151], v[190:193], 0
	v_mfma_f32_16x16x32_bf16 v[120:123], v[164:167], v[190:193], 0
	v_mfma_f32_16x16x32_bf16 v[108:111], v[148:151], v[198:201], 0
	v_mfma_f32_16x16x32_bf16 v[104:107], v[164:167], v[198:201], 0
	v_mfma_f32_16x16x32_bf16 v[92:95], v[148:151], v[212:215], 0
	v_mfma_f32_16x16x32_bf16 v[88:91], v[164:167], v[212:215], 0
	v_mfma_f32_16x16x32_bf16 v[76:79], v[148:151], v[220:223], 0
	v_mfma_f32_16x16x32_bf16 v[72:75], v[164:167], v[220:223], 0
	v_mfma_f32_16x16x32_bf16 v[124:127], v[160:163], v[194:197], v[124:127]
	v_mfma_f32_16x16x32_bf16 v[120:123], v[168:171], v[194:197], v[120:123]
	v_mfma_f32_16x16x32_bf16 v[108:111], v[160:163], v[208:211], v[108:111]
	v_mfma_f32_16x16x32_bf16 v[104:107], v[168:171], v[208:211], v[104:107]
	v_mfma_f32_16x16x32_bf16 v[92:95], v[160:163], v[216:219], v[92:95]
	v_mfma_f32_16x16x32_bf16 v[88:91], v[168:171], v[216:219], v[88:91]
	v_mfma_f32_16x16x32_bf16 v[76:79], v[160:163], v[224:227], v[76:79]
	v_mfma_f32_16x16x32_bf16 v[72:75], v[168:171], v[224:227], v[72:75]
	s_setprio 0
	s_setprio 1
	v_mfma_f32_16x16x32_bf16 v[116:119], v[172:175], v[190:193], 0
	v_mfma_f32_16x16x32_bf16 v[112:115], v[182:185], v[190:193], 0
	v_mfma_f32_16x16x32_bf16 v[100:103], v[172:175], v[198:201], 0
	v_mfma_f32_16x16x32_bf16 v[96:99], v[182:185], v[198:201], 0
	v_mfma_f32_16x16x32_bf16 v[84:87], v[172:175], v[212:215], 0
	v_mfma_f32_16x16x32_bf16 v[80:83], v[182:185], v[212:215], 0
	v_mfma_f32_16x16x32_bf16 v[68:71], v[172:175], v[220:223], 0
	v_mfma_f32_16x16x32_bf16 v[64:67], v[182:185], v[220:223], 0
	v_mfma_f32_16x16x32_bf16 v[116:119], v[176:179], v[194:197], v[116:119]
	v_mfma_f32_16x16x32_bf16 v[112:115], v[186:189], v[194:197], v[112:115]
	v_mfma_f32_16x16x32_bf16 v[100:103], v[176:179], v[208:211], v[100:103]
	v_mfma_f32_16x16x32_bf16 v[96:99], v[186:189], v[208:211], v[96:99]
	v_mfma_f32_16x16x32_bf16 v[84:87], v[176:179], v[216:219], v[84:87]
	v_mfma_f32_16x16x32_bf16 v[80:83], v[186:189], v[216:219], v[80:83]
	v_mfma_f32_16x16x32_bf16 v[68:71], v[176:179], v[224:227], v[68:71]
	v_mfma_f32_16x16x32_bf16 v[64:67], v[186:189], v[224:227], v[64:67]
	s_setprio 0
	s_barrier
	s_add_i32 s3, s85, s34
	v_lshl_add_u64 v[202:203], s[62:63], 0, v[134:135]
	s_mov_b32 m0, s3
	ds_read_b128 v[190:193], v157 offset:16384
	ds_read_b128 v[194:197], v157 offset:17408
	ds_read_b128 v[198:201], v157 offset:18432
	ds_read_b128 v[208:211], v157 offset:19456
	ds_read_b128 v[212:215], v157 offset:20480
	ds_read_b128 v[216:219], v157 offset:21504
	ds_read_b128 v[220:223], v157 offset:22528
	ds_read_b128 v[224:227], v157 offset:23552
	global_load_lds_dwordx4 v[202:203], off
	s_add_i32 m0, s3, 0x2000
	s_add_u32 s14, s62, 0x40000
	v_lshl_add_u64 v[228:229], s[62:63], 0, v[138:139]
	s_addc_u32 s15, s63, 0
	s_add_i32 s3, s86, s34
	global_load_lds_dwordx4 v[228:229], off
	v_lshl_add_u64 v[230:231], s[14:15], 0, v[134:135]
	s_mov_b32 m0, s3
	global_load_lds_dwordx4 v[230:231], off
	v_lshl_add_u64 v[230:231], s[14:15], 0, v[138:139]
	s_add_i32 m0, s3, 0x2000
	s_nop 0
	global_load_lds_dwordx4 v[230:231], off
	s_waitcnt vmcnt(6)
	s_waitcnt lgkmcnt(0)
	s_barrier
; #define PG8_STAGE(bufoff, gbase, voff) do { _Pragma("unroll") for (int _i = 0; _i < 2; ++_i) \
;         __builtin_amdgcn_global_load_lds((const unsigned*)((const char*)(gbase) + (voff)[_i]), (PG8_LAS unsigned*)(lds + (bufoff) + ldsw + _i * 8192), 16, 0, 0); } while (0)
; #define PG8_LDA(dst, b, h) do { _Pragma("unroll") for (int m = 0; m < 4; ++m) _Pragma("unroll") for (int k = 0; k < 2; ++k) dst[m][k] = *(const PG8_LAS bf16x8*)(lds + PG8_SA(b, h) + aoff + m * 2048 + k * 1024); } while (0)
; #define PG8_LDB(dst, b, h) do { _Pragma("unroll") for (int n = 0; n < 2; ++n) _Pragma("unroll") for (int k = 0; k < 2; ++k) dst[n][k] = *(const PG8_LAS bf16x8*)(lds + PG8_SB(b, h) + boff + n * 2048 + k * 1024); } while (0)
; #define PG8_MMA(ai, bj, At, Bt) do { __builtin_amdgcn_s_setprio(1); _Pragma("unroll") for (int m = 0; m < 4; ++m) _Pragma("unroll") for (int n = 0; n < 2; ++n) _Pragma("unroll") for (int k = 0; k < 2; ++k) \
;         acc[ai][bj][m][n] = __builtin_amdgcn_mfma_f32_16x16x32_bf16(Bt[n][k], At[m][k], acc[ai][bj][m][n], 0, 0, 0); __builtin_amdgcn_s_setprio(0); } while (0)
; #define PG8_WAIT_V(n) asm volatile("s_waitcnt vmcnt(" #n ")" ::: "memory")
; #define PG8_WAIT_L(n) asm volatile("s_waitcnt lgkmcnt(" #n ")" ::: "memory")
; #define PG8_BAR __builtin_amdgcn_s_barrier()
; #define PG8_SCHED __builtin_amdgcn_sched_barrier(0)
; template <class Epi, class Sched, bool ALIGN_EPI = false, bool SP2 = false>
; __device__ __forceinline__ void gemm_phase(PG8_LAS unsigned char* lds, const Gemm g, const Sched& S, const Epi& E) {
;     ...
;             PG8_LDA(At, 0, 1); PG8_STAGE(PG8_SB(0, 0), b2, voffB); PG8_STAGE(PG8_SB(0, 1), b2 + hstep, voffB); PG8_STAGE(PG8_SA(0, 0), a2, voffA);
;             PG8_WAIT_V(8); PG8_WAIT_L(0); PG8_BAR; PG8_MMA(1, 0, At, B0); PG8_MMA(1, 1, At, B1); PG8_BAR; PG8_SCHED;
;             PG8_LDB(B0, 1, 0); PG8_LDB(B1, 1, 1); PG8_SCHED; PG8_LDA(At, 1, 0); PG8_STAGE(PG8_SA(0, 1), a2 + hstep, voffA);
;             PG8_WAIT_V(8); PG8_WAIT_L(0); PG8_BAR; PG8_MMA(0, 0, At, B0); PG8_MMA(0, 1, At, B1); PG8_BAR; PG8_SCHED;
	s_setprio 1
	s_waitcnt lgkmcnt(0)
	v_mfma_f32_16x16x32_bf16 v[60:63], v[148:151], v[190:193], 0
	v_mfma_f32_16x16x32_bf16 v[56:59], v[164:167], v[190:193], 0
	v_mfma_f32_16x16x32_bf16 v[44:47], v[148:151], v[198:201], 0
	v_mfma_f32_16x16x32_bf16 v[40:43], v[164:167], v[198:201], 0
	v_mfma_f32_16x16x32_bf16 v[28:31], v[148:151], v[212:215], 0
	v_mfma_f32_16x16x32_bf16 v[24:27], v[164:167], v[212:215], 0
	v_mfma_f32_16x16x32_bf16 v[12:15], v[148:151], v[220:223], 0
	v_mfma_f32_16x16x32_bf16 v[8:11], v[164:167], v[220:223], 0
	v_mfma_f32_16x16x32_bf16 v[60:63], v[160:163], v[194:197], v[60:63]
	v_mfma_f32_16x16x32_bf16 v[56:59], v[168:171], v[194:197], v[56:59]
	v_mfma_f32_16x16x32_bf16 v[44:47], v[160:163], v[208:211], v[44:47]
	v_mfma_f32_16x16x32_bf16 v[40:43], v[168:171], v[208:211], v[40:43]
	v_lshl_add_u64 v[230:231], s[64:65], 0, v[132:133]
	s_mov_b32 m0, s43
	s_nop 0
	global_load_lds_dwordx4 v[230:231], off
	v_mfma_f32_16x16x32_bf16 v[28:31], v[160:163], v[216:219], v[28:31]
	v_mfma_f32_16x16x32_bf16 v[24:27], v[168:171], v[216:219], v[24:27]
	v_mfma_f32_16x16x32_bf16 v[12:15], v[160:163], v[224:227], v[12:15]
	v_mfma_f32_16x16x32_bf16 v[8:11], v[168:171], v[224:227], v[8:11]
	s_setprio 0
	s_setprio 1
	v_mfma_f32_16x16x32_bf16 v[52:55], v[172:175], v[190:193], 0
	v_mfma_f32_16x16x32_bf16 v[48:51], v[182:185], v[190:193], 0
	v_mfma_f32_16x16x32_bf16 v[36:39], v[172:175], v[198:201], 0
	v_mfma_f32_16x16x32_bf16 v[32:35], v[182:185], v[198:201], 0
	v_mfma_f32_16x16x32_bf16 v[20:23], v[172:175], v[212:215], 0
	v_mfma_f32_16x16x32_bf16 v[16:19], v[182:185], v[212:215], 0
	v_mfma_f32_16x16x32_bf16 v[4:7], v[172:175], v[220:223], 0
	v_mfma_f32_16x16x32_bf16 v[0:3], v[182:185], v[220:223], 0
	v_mfma_f32_16x16x32_bf16 v[52:55], v[176:179], v[194:197], v[52:55]
	v_mfma_f32_16x16x32_bf16 v[48:51], v[186:189], v[194:197], v[48:51]
	v_mfma_f32_16x16x32_bf16 v[36:39], v[176:179], v[208:211], v[36:39]
	v_mfma_f32_16x16x32_bf16 v[32:35], v[186:189], v[208:211], v[32:35]
	v_lshl_add_u64 v[232:233], s[64:65], 0, v[136:137]
	s_mov_b32 m0, s59
	s_nop 0
	global_load_lds_dwordx4 v[232:233], off
	v_mfma_f32_16x16x32_bf16 v[20:23], v[176:179], v[216:219], v[20:23]
	v_mfma_f32_16x16x32_bf16 v[16:19], v[186:189], v[216:219], v[16:19]
	v_mfma_f32_16x16x32_bf16 v[4:7], v[176:179], v[224:227], v[4:7]
	v_mfma_f32_16x16x32_bf16 v[0:3], v[186:189], v[224:227], v[0:3]
	s_setprio 0
	s_barrier
	s_add_i32 s3, 0, 0x18000
	v_add_u32_e32 v159, s3, v131
	s_add_i32 s33, 0, 0x1c000
	ds_read_b128 v[148:151], v159
	ds_read_b128 v[160:163], v159 offset:1024
	ds_read_b128 v[164:167], v159 offset:2048
	ds_read_b128 v[168:171], v159 offset:3072
	v_add_u32_e32 v159, s33, v131
	ds_read_b128 v[172:175], v159
	ds_read_b128 v[176:179], v159 offset:1024
	ds_read_b128 v[182:185], v159 offset:2048
	ds_read_b128 v[186:189], v159 offset:3072
	s_add_u32 s14, s64, 0x40000
	s_addc_u32 s15, s65, 0
	s_mov_b32 m0, s66
	v_lshl_add_u64 v[234:235], s[14:15], 0, v[132:133]
	ds_read_b128 v[190:193], v157 offset:32768
	ds_read_b128 v[194:197], v157 offset:33792
	ds_read_b128 v[198:201], v157 offset:34816
	ds_read_b128 v[208:211], v157 offset:35840
	ds_read_b128 v[212:215], v157 offset:36864
	ds_read_b128 v[216:219], v157 offset:37888
	ds_read_b128 v[220:223], v157 offset:38912
	ds_read_b128 v[224:227], v157 offset:39936
	global_load_lds_dwordx4 v[234:235], off
	v_lshl_add_u64 v[234:235], s[14:15], 0, v[136:137]
	s_mov_b32 m0, s67
	s_nop 0
	global_load_lds_dwordx4 v[234:235], off
	s_waitcnt vmcnt(8)
	s_waitcnt lgkmcnt(0)
	s_barrier
	s_setprio 1
	s_waitcnt lgkmcnt(0)
	v_mfma_f32_16x16x32_bf16 v[124:127], v[148:151], v[190:193], v[124:127]
	v_mfma_f32_16x16x32_bf16 v[120:123], v[164:167], v[190:193], v[120:123]
	v_mfma_f32_16x16x32_bf16 v[108:111], v[148:151], v[198:201], v[108:111]
	v_mfma_f32_16x16x32_bf16 v[104:107], v[164:167], v[198:201], v[104:107]
	v_mfma_f32_16x16x32_bf16 v[92:95], v[148:151], v[212:215], v[92:95]
	v_mfma_f32_16x16x32_bf16 v[88:91], v[164:167], v[212:215], v[88:91]
	v_mfma_f32_16x16x32_bf16 v[76:79], v[148:151], v[220:223], v[76:79]
	v_mfma_f32_16x16x32_bf16 v[72:75], v[164:167], v[220:223], v[72:75]
	v_mfma_f32_16x16x32_bf16 v[124:127], v[160:163], v[194:197], v[124:127]
	v_mfma_f32_16x16x32_bf16 v[120:123], v[168:171], v[194:197], v[120:123]
	v_mfma_f32_16x16x32_bf16 v[108:111], v[160:163], v[208:211], v[108:111]
	v_mfma_f32_16x16x32_bf16 v[104:107], v[168:171], v[208:211], v[104:107]
	v_mfma_f32_16x16x32_bf16 v[92:95], v[160:163], v[216:219], v[92:95]
	v_mfma_f32_16x16x32_bf16 v[88:91], v[168:171], v[216:219], v[88:91]
	v_mfma_f32_16x16x32_bf16 v[76:79], v[160:163], v[224:227], v[76:79]
	v_mfma_f32_16x16x32_bf16 v[72:75], v[168:171], v[224:227], v[72:75]
	s_setprio 0
	s_setprio 1
	v_mfma_f32_16x16x32_bf16 v[116:119], v[172:175], v[190:193], v[116:119]
	v_mfma_f32_16x16x32_bf16 v[112:115], v[182:185], v[190:193], v[112:115]
	v_mfma_f32_16x16x32_bf16 v[100:103], v[172:175], v[198:201], v[100:103]
	v_mfma_f32_16x16x32_bf16 v[96:99], v[182:185], v[198:201], v[96:99]
	v_mfma_f32_16x16x32_bf16 v[84:87], v[172:175], v[212:215], v[84:87]
	v_mfma_f32_16x16x32_bf16 v[80:83], v[182:185], v[212:215], v[80:83]
	v_mfma_f32_16x16x32_bf16 v[68:71], v[172:175], v[220:223], v[68:71]
	v_mfma_f32_16x16x32_bf16 v[64:67], v[182:185], v[220:223], v[64:67]
	v_mfma_f32_16x16x32_bf16 v[116:119], v[176:179], v[194:197], v[116:119]
	v_mfma_f32_16x16x32_bf16 v[112:115], v[186:189], v[194:197], v[112:115]
	v_mfma_f32_16x16x32_bf16 v[100:103], v[176:179], v[208:211], v[100:103]
	v_mfma_f32_16x16x32_bf16 v[96:99], v[186:189], v[208:211], v[96:99]
	v_mfma_f32_16x16x32_bf16 v[84:87], v[176:179], v[216:219], v[84:87]
	v_mfma_f32_16x16x32_bf16 v[80:83], v[186:189], v[216:219], v[80:83]
	v_mfma_f32_16x16x32_bf16 v[68:71], v[176:179], v[224:227], v[68:71]
	v_mfma_f32_16x16x32_bf16 v[64:67], v[186:189], v[224:227], v[64:67]
	s_setprio 0
	s_barrier
; #define PG8_STAGE(bufoff, gbase, voff) do { _Pragma("unroll") for (int _i = 0; _i < 2; ++_i) \
;         __builtin_amdgcn_global_load_lds((const unsigned*)((const char*)(gbase) + (voff)[_i]), (PG8_LAS unsigned*)(lds + (bufoff) + ldsw + _i * 8192), 16, 0, 0); } while (0)
; #define PG8_LDA(dst, b, h) do { _Pragma("unroll") for (int m = 0; m < 4; ++m) _Pragma("unroll") for (int k = 0; k < 2; ++k) dst[m][k] = *(const PG8_LAS bf16x8*)(lds + PG8_SA(b, h) + aoff + m * 2048 + k * 1024); } while (0)
; #define PG8_LDB(dst, b, h) do { _Pragma("unroll") for (int n = 0; n < 2; ++n) _Pragma("unroll") for (int k = 0; k < 2; ++k) dst[n][k] = *(const PG8_LAS bf16x8*)(lds + PG8_SB(b, h) + boff + n * 2048 + k * 1024); } while (0)
; #define PG8_MMA(ai, bj, At, Bt) do { __builtin_amdgcn_s_setprio(1); _Pragma("unroll") for (int m = 0; m < 4; ++m) _Pragma("unroll") for (int n = 0; n < 2; ++n) _Pragma("unroll") for (int k = 0; k < 2; ++k) \
;         acc[ai][bj][m][n] = __builtin_amdgcn_mfma_f32_16x16x32_bf16(Bt[n][k], At[m][k], acc[ai][bj][m][n], 0, 0, 0); __builtin_amdgcn_s_setprio(0); } while (0)
; #define PG8_WAIT_V(n) asm volatile("s_waitcnt vmcnt(" #n ")" ::: "memory")
; #define PG8_WAIT_L(n) asm volatile("s_waitcnt lgkmcnt(" #n ")" ::: "memory")
; #define PG8_BAR __builtin_amdgcn_s_barrier()
; #define PG8_SCHED __builtin_amdgcn_sched_barrier(0)
; template <class Epi, class Sched, bool ALIGN_EPI = false, bool SP2 = false>
; __device__ __forceinline__ void gemm_phase(PG8_LAS unsigned char* lds, const Gemm g, const Sched& S, const Epi& E) {
;     ...
;         for (int t = 0; t < nt; t += 2) {
;             const bool last = (t == nt - 2);
;             const char* a1 = cA + (size_t)(t + 1) * kstep;
;             const char* a2 = last ? nA : cA + (size_t)(t + 2) * kstep; const char* b2 = last ? nB : cB + (size_t)(t + 2) * kstep;
;             const char* a3 = a2 + kstep; const char* b3 = b2 + kstep;
;             if (last && has_next) S.a_ready(nxt);
;             if constexpr (SP2) {
;             PG8_LDB(B0, 0, 0); PG8_LDB(B1, 0, 1); PG8_SCHED; PG8_LDA(At, 0, 0); PG8_STAGE(PG8_SA(1, 1), a1 + hstep, voffA);
;     ...
;             PG8_LDA(At, 1, 1); PG8_STAGE(PG8_SB(1, 0), b3, voffB); PG8_STAGE(PG8_SB(1, 1), b3 + hstep, voffB); PG8_STAGE(PG8_SA(1, 0), a3, voffA);
;             PG8_WAIT_V(8); PG8_WAIT_L(0); PG8_BAR; PG8_MMA(1, 0, At, B0); PG8_MMA(1, 1, At, B1); PG8_BAR; PG8_SCHED;
	s_add_i32 s3, s3, s34
	v_lshl_add_u64 v[202:203], v[202:203], 0, s[38:39]
	s_mov_b32 m0, s3
	ds_read_b128 v[190:193], v157 offset:49152
	ds_read_b128 v[194:197], v157 offset:50176
	ds_read_b128 v[198:201], v157 offset:51200
	ds_read_b128 v[208:211], v157 offset:52224
	ds_read_b128 v[212:215], v157 offset:53248
	ds_read_b128 v[216:219], v157 offset:54272
	ds_read_b128 v[220:223], v157 offset:55296
	ds_read_b128 v[224:227], v157 offset:56320
	global_load_lds_dwordx4 v[202:203], off
	s_add_i32 m0, s3, 0x2000
	s_add_u32 s14, s62, 0x40080
	v_lshl_add_u64 v[202:203], v[228:229], 0, s[38:39]
	s_addc_u32 s15, s63, 0
	s_add_i32 s3, s33, s34
	global_load_lds_dwordx4 v[202:203], off
	v_lshl_add_u64 v[202:203], s[14:15], 0, v[134:135]
	s_mov_b32 m0, s3
	s_nop 0
	global_load_lds_dwordx4 v[202:203], off
	v_lshl_add_u64 v[202:203], s[14:15], 0, v[138:139]
	s_add_i32 m0, s3, 0x2000
	s_nop 0
	global_load_lds_dwordx4 v[202:203], off
	s_waitcnt vmcnt(6)
	s_waitcnt lgkmcnt(0)
	s_barrier
	s_setprio 1
	s_waitcnt lgkmcnt(0)
	v_mfma_f32_16x16x32_bf16 v[60:63], v[148:151], v[190:193], v[60:63]
	v_mfma_f32_16x16x32_bf16 v[56:59], v[164:167], v[190:193], v[56:59]
	v_mfma_f32_16x16x32_bf16 v[44:47], v[148:151], v[198:201], v[44:47]
	v_mfma_f32_16x16x32_bf16 v[40:43], v[164:167], v[198:201], v[40:43]
	v_mfma_f32_16x16x32_bf16 v[28:31], v[148:151], v[212:215], v[28:31]
	v_mfma_f32_16x16x32_bf16 v[24:27], v[164:167], v[212:215], v[24:27]
	v_mfma_f32_16x16x32_bf16 v[12:15], v[148:151], v[220:223], v[12:15]
	v_mfma_f32_16x16x32_bf16 v[8:11], v[164:167], v[220:223], v[8:11]
	v_mfma_f32_16x16x32_bf16 v[60:63], v[160:163], v[194:197], v[60:63]
	v_mfma_f32_16x16x32_bf16 v[56:59], v[168:171], v[194:197], v[56:59]
	v_mfma_f32_16x16x32_bf16 v[44:47], v[160:163], v[208:211], v[44:47]
	v_mfma_f32_16x16x32_bf16 v[40:43], v[168:171], v[208:211], v[40:43]
	v_lshl_add_u64 v[202:203], v[230:231], 0, s[38:39]
	s_mov_b32 m0, s75
	s_nop 0
	global_load_lds_dwordx4 v[202:203], off
	v_mfma_f32_16x16x32_bf16 v[28:31], v[160:163], v[216:219], v[28:31]
	v_mfma_f32_16x16x32_bf16 v[24:27], v[168:171], v[216:219], v[24:27]
	v_mfma_f32_16x16x32_bf16 v[12:15], v[160:163], v[224:227], v[12:15]
	v_mfma_f32_16x16x32_bf16 v[8:11], v[168:171], v[224:227], v[8:11]
	s_setprio 0
	s_setprio 1
	v_mfma_f32_16x16x32_bf16 v[52:55], v[172:175], v[190:193], v[52:55]
	v_mfma_f32_16x16x32_bf16 v[48:51], v[182:185], v[190:193], v[48:51]
	v_mfma_f32_16x16x32_bf16 v[36:39], v[172:175], v[198:201], v[36:39]
	v_mfma_f32_16x16x32_bf16 v[32:35], v[182:185], v[198:201], v[32:35]
	v_mfma_f32_16x16x32_bf16 v[20:23], v[172:175], v[212:215], v[20:23]
	v_mfma_f32_16x16x32_bf16 v[16:19], v[182:185], v[212:215], v[16:19]
	v_mfma_f32_16x16x32_bf16 v[4:7], v[172:175], v[220:223], v[4:7]
	v_mfma_f32_16x16x32_bf16 v[0:3], v[182:185], v[220:223], v[0:3]
	v_mfma_f32_16x16x32_bf16 v[52:55], v[176:179], v[194:197], v[52:55]
	v_mfma_f32_16x16x32_bf16 v[48:51], v[186:189], v[194:197], v[48:51]
	v_mfma_f32_16x16x32_bf16 v[36:39], v[176:179], v[208:211], v[36:39]
	v_mfma_f32_16x16x32_bf16 v[32:35], v[186:189], v[208:211], v[32:35]
	v_lshl_add_u64 v[202:203], v[232:233], 0, s[38:39]
	s_mov_b32 m0, s84
	s_nop 0
	global_load_lds_dwordx4 v[202:203], off
	v_mfma_f32_16x16x32_bf16 v[20:23], v[176:179], v[216:219], v[20:23]
	v_mfma_f32_16x16x32_bf16 v[16:19], v[186:189], v[216:219], v[16:19]
	v_mfma_f32_16x16x32_bf16 v[4:7], v[176:179], v[224:227], v[4:7]
	v_mfma_f32_16x16x32_bf16 v[0:3], v[186:189], v[224:227], v[0:3]
	s_setprio 0
	s_barrier
	s_add_i32 s92, s92, 2
	s_add_u32 s60, s60, 0x100
	s_addc_u32 s61, s61, 0
	s_add_u32 s90, s90, 0x100
	s_addc_u32 s91, s91, 0
.LBB0_650:
	ds_read_b128 v[148:151], v155
	ds_read_b128 v[160:163], v155 offset:1024
	ds_read_b128 v[164:167], v155 offset:2048
	ds_read_b128 v[168:171], v155 offset:3072
	ds_read_b128 v[172:175], v156
	ds_read_b128 v[176:179], v156 offset:1024
	ds_read_b128 v[182:185], v156 offset:2048
	ds_read_b128 v[186:189], v156 offset:3072
	s_add_u32 s3, s60, 0xfffc0080
	s_addc_u32 s14, s61, -1
	s_cmp_eq_u32 s92, 12
	s_cselect_b32 s65, s51, s14
	s_cselect_b32 s64, s57, s3
	s_cselect_b32 s63, s49, s91
	s_cselect_b32 s62, s89, s90
	v_lshl_add_u64 v[202:203], s[60:61], 0, v[140:141]
	s_add_i32 m0, s43, 0xc000
	ds_read_b128 v[190:193], v157
	ds_read_b128 v[194:197], v157 offset:1024
	ds_read_b128 v[198:201], v157 offset:2048
	ds_read_b128 v[208:211], v157 offset:3072
	ds_read_b128 v[212:215], v157 offset:4096
	ds_read_b128 v[216:219], v157 offset:5120
	ds_read_b128 v[220:223], v157 offset:6144
	ds_read_b128 v[224:227], v157 offset:7168
	global_load_lds_dwordx4 v[202:203], off
	v_lshl_add_u64 v[202:203], s[60:61], 0, v[142:143]
	s_add_i32 m0, s43, 0xe000
	s_nop 0
	global_load_lds_dwordx4 v[202:203], off
	s_waitcnt vmcnt(8)
	s_waitcnt lgkmcnt(0)
	s_barrier
; #define PG8_STAGE(bufoff, gbase, voff) do { _Pragma("unroll") for (int _i = 0; _i < 2; ++_i) \
;         __builtin_amdgcn_global_load_lds((const unsigned*)((const char*)(gbase) + (voff)[_i]), (PG8_LAS unsigned*)(lds + (bufoff) + ldsw + _i * 8192), 16, 0, 0); } while (0)
; #define PG8_LDA(dst, b, h) do { _Pragma("unroll") for (int m = 0; m < 4; ++m) _Pragma("unroll") for (int k = 0; k < 2; ++k) dst[m][k] = *(const PG8_LAS bf16x8*)(lds + PG8_SA(b, h) + aoff + m * 2048 + k * 1024); } while (0)
; #define PG8_LDB(dst, b, h) do { _Pragma("unroll") for (int n = 0; n < 2; ++n) _Pragma("unroll") for (int k = 0; k < 2; ++k) dst[n][k] = *(const PG8_LAS bf16x8*)(lds + PG8_SB(b, h) + boff + n * 2048 + k * 1024); } while (0)
; #define PG8_MMA(ai, bj, At, Bt) do { __builtin_amdgcn_s_setprio(1); _Pragma("unroll") for (int m = 0; m < 4; ++m) _Pragma("unroll") for (int n = 0; n < 2; ++n) _Pragma("unroll") for (int k = 0; k < 2; ++k) \
;         acc[ai][bj][m][n] = __builtin_amdgcn_mfma_f32_16x16x32_bf16(Bt[n][k], At[m][k], acc[ai][bj][m][n], 0, 0, 0); __builtin_amdgcn_s_setprio(0); } while (0)
; #define PG8_WAIT_V(n) asm volatile("s_waitcnt vmcnt(" #n ")" ::: "memory")
; #define PG8_WAIT_L(n) asm volatile("s_waitcnt lgkmcnt(" #n ")" ::: "memory")
; #define PG8_BAR __builtin_amdgcn_s_barrier()
; #define PG8_SCHED __builtin_amdgcn_sched_barrier(0)
; template <class Epi, class Sched, bool ALIGN_EPI = false, bool SP2 = false>
; __device__ __forceinline__ void gemm_phase(PG8_LAS unsigned char* lds, const Gemm g, const Sched& S, const Epi& E) {
;     ...
;             PG8_LDB(B0, 0, 0); PG8_LDB(B1, 0, 1); PG8_SCHED; PG8_LDA(At, 0, 0); PG8_STAGE(PG8_SA(1, 1), a1 + hstep, voffA);
;             PG8_WAIT_V(8); PG8_WAIT_L(0); PG8_BAR; PG8_MMA(0, 0, At, B0); PG8_MMA(0, 1, At, B1); PG8_BAR; PG8_SCHED;
;             PG8_LDA(At, 0, 1); PG8_STAGE(PG8_SB(0, 0), b2, voffB); PG8_STAGE(PG8_SB(0, 1), b2 + hstep, voffB); PG8_STAGE(PG8_SA(0, 0), a2, voffA);
;             PG8_WAIT_V(8); PG8_WAIT_L(0); PG8_BAR; PG8_MMA(1, 0, At, B0); PG8_MMA(1, 1, At, B1); PG8_BAR; PG8_SCHED;
	s_setprio 1
	s_waitcnt lgkmcnt(0)
	v_mfma_f32_16x16x32_bf16 v[124:127], v[148:151], v[190:193], v[124:127]
	v_mfma_f32_16x16x32_bf16 v[120:123], v[164:167], v[190:193], v[120:123]
	v_mfma_f32_16x16x32_bf16 v[108:111], v[148:151], v[198:201], v[108:111]
	v_mfma_f32_16x16x32_bf16 v[104:107], v[164:167], v[198:201], v[104:107]
	v_mfma_f32_16x16x32_bf16 v[92:95], v[148:151], v[212:215], v[92:95]
	v_mfma_f32_16x16x32_bf16 v[88:91], v[164:167], v[212:215], v[88:91]
	v_mfma_f32_16x16x32_bf16 v[76:79], v[148:151], v[220:223], v[76:79]
	v_mfma_f32_16x16x32_bf16 v[72:75], v[164:167], v[220:223], v[72:75]
	v_mfma_f32_16x16x32_bf16 v[124:127], v[160:163], v[194:197], v[124:127]
	v_mfma_f32_16x16x32_bf16 v[120:123], v[168:171], v[194:197], v[120:123]
	v_mfma_f32_16x16x32_bf16 v[108:111], v[160:163], v[208:211], v[108:111]
	v_mfma_f32_16x16x32_bf16 v[104:107], v[168:171], v[208:211], v[104:107]
	v_mfma_f32_16x16x32_bf16 v[92:95], v[160:163], v[216:219], v[92:95]
	v_mfma_f32_16x16x32_bf16 v[88:91], v[168:171], v[216:219], v[88:91]
	v_mfma_f32_16x16x32_bf16 v[76:79], v[160:163], v[224:227], v[76:79]
	v_mfma_f32_16x16x32_bf16 v[72:75], v[168:171], v[224:227], v[72:75]
	s_setprio 0
	s_setprio 1
	v_mfma_f32_16x16x32_bf16 v[116:119], v[172:175], v[190:193], v[116:119]
	v_mfma_f32_16x16x32_bf16 v[112:115], v[182:185], v[190:193], v[112:115]
	v_mfma_f32_16x16x32_bf16 v[100:103], v[172:175], v[198:201], v[100:103]
	v_mfma_f32_16x16x32_bf16 v[96:99], v[182:185], v[198:201], v[96:99]
	v_mfma_f32_16x16x32_bf16 v[84:87], v[172:175], v[212:215], v[84:87]
	v_mfma_f32_16x16x32_bf16 v[80:83], v[182:185], v[212:215], v[80:83]
	v_mfma_f32_16x16x32_bf16 v[68:71], v[172:175], v[220:223], v[68:71]
	v_mfma_f32_16x16x32_bf16 v[64:67], v[182:185], v[220:223], v[64:67]
	v_mfma_f32_16x16x32_bf16 v[116:119], v[176:179], v[194:197], v[116:119]
	v_mfma_f32_16x16x32_bf16 v[112:115], v[186:189], v[194:197], v[112:115]
	v_mfma_f32_16x16x32_bf16 v[100:103], v[176:179], v[208:211], v[100:103]
	v_mfma_f32_16x16x32_bf16 v[96:99], v[186:189], v[208:211], v[96:99]
	v_mfma_f32_16x16x32_bf16 v[84:87], v[176:179], v[216:219], v[84:87]
	v_mfma_f32_16x16x32_bf16 v[80:83], v[186:189], v[216:219], v[80:83]
	v_mfma_f32_16x16x32_bf16 v[68:71], v[176:179], v[224:227], v[68:71]
	v_mfma_f32_16x16x32_bf16 v[64:67], v[186:189], v[224:227], v[64:67]
	s_setprio 0
	s_barrier
	s_add_i32 s3, s85, s34
	v_lshl_add_u64 v[202:203], s[62:63], 0, v[134:135]
	s_mov_b32 m0, s3
	ds_read_b128 v[190:193], v157 offset:16384
	ds_read_b128 v[194:197], v157 offset:17408
	ds_read_b128 v[198:201], v157 offset:18432
	ds_read_b128 v[208:211], v157 offset:19456
	ds_read_b128 v[212:215], v157 offset:20480
	ds_read_b128 v[216:219], v157 offset:21504
	ds_read_b128 v[220:223], v157 offset:22528
	ds_read_b128 v[224:227], v157 offset:23552
	global_load_lds_dwordx4 v[202:203], off
	s_add_i32 m0, s3, 0x2000
	s_add_u32 s14, s62, 0x40000
	v_lshl_add_u64 v[228:229], s[62:63], 0, v[138:139]
	s_addc_u32 s15, s63, 0
	s_add_i32 s3, s86, s34
	global_load_lds_dwordx4 v[228:229], off
	v_lshl_add_u64 v[230:231], s[14:15], 0, v[134:135]
	s_mov_b32 m0, s3
	global_load_lds_dwordx4 v[230:231], off
	v_lshl_add_u64 v[230:231], s[14:15], 0, v[138:139]
	s_add_i32 m0, s3, 0x2000
	s_nop 0
	global_load_lds_dwordx4 v[230:231], off
	s_waitcnt vmcnt(6)
	s_waitcnt lgkmcnt(0)
	s_barrier
	s_setprio 1
	s_waitcnt lgkmcnt(0)
	v_mfma_f32_16x16x32_bf16 v[60:63], v[148:151], v[190:193], v[60:63]
	v_mfma_f32_16x16x32_bf16 v[56:59], v[164:167], v[190:193], v[56:59]
	v_mfma_f32_16x16x32_bf16 v[44:47], v[148:151], v[198:201], v[44:47]
	v_mfma_f32_16x16x32_bf16 v[40:43], v[164:167], v[198:201], v[40:43]
	v_mfma_f32_16x16x32_bf16 v[28:31], v[148:151], v[212:215], v[28:31]
	v_mfma_f32_16x16x32_bf16 v[24:27], v[164:167], v[212:215], v[24:27]
	v_mfma_f32_16x16x32_bf16 v[12:15], v[148:151], v[220:223], v[12:15]
	v_mfma_f32_16x16x32_bf16 v[8:11], v[164:167], v[220:223], v[8:11]
	v_mfma_f32_16x16x32_bf16 v[60:63], v[160:163], v[194:197], v[60:63]
	v_mfma_f32_16x16x32_bf16 v[56:59], v[168:171], v[194:197], v[56:59]
	v_mfma_f32_16x16x32_bf16 v[44:47], v[160:163], v[208:211], v[44:47]
	v_mfma_f32_16x16x32_bf16 v[40:43], v[168:171], v[208:211], v[40:43]
	v_lshl_add_u64 v[230:231], s[64:65], 0, v[132:133]
	s_mov_b32 m0, s43
	s_nop 0
	global_load_lds_dwordx4 v[230:231], off
	v_mfma_f32_16x16x32_bf16 v[28:31], v[160:163], v[216:219], v[28:31]
	v_mfma_f32_16x16x32_bf16 v[24:27], v[168:171], v[216:219], v[24:27]
	v_mfma_f32_16x16x32_bf16 v[12:15], v[160:163], v[224:227], v[12:15]
	v_mfma_f32_16x16x32_bf16 v[8:11], v[168:171], v[224:227], v[8:11]
	s_setprio 0
	s_setprio 1
	v_mfma_f32_16x16x32_bf16 v[52:55], v[172:175], v[190:193], v[52:55]
	v_mfma_f32_16x16x32_bf16 v[48:51], v[182:185], v[190:193], v[48:51]
	v_mfma_f32_16x16x32_bf16 v[36:39], v[172:175], v[198:201], v[36:39]
	v_mfma_f32_16x16x32_bf16 v[32:35], v[182:185], v[198:201], v[32:35]
	v_mfma_f32_16x16x32_bf16 v[20:23], v[172:175], v[212:215], v[20:23]
	v_mfma_f32_16x16x32_bf16 v[16:19], v[182:185], v[212:215], v[16:19]
	v_mfma_f32_16x16x32_bf16 v[4:7], v[172:175], v[220:223], v[4:7]
	v_mfma_f32_16x16x32_bf16 v[0:3], v[182:185], v[220:223], v[0:3]
	v_mfma_f32_16x16x32_bf16 v[52:55], v[176:179], v[194:197], v[52:55]
	v_mfma_f32_16x16x32_bf16 v[48:51], v[186:189], v[194:197], v[48:51]
	v_mfma_f32_16x16x32_bf16 v[36:39], v[176:179], v[208:211], v[36:39]
	v_mfma_f32_16x16x32_bf16 v[32:35], v[186:189], v[208:211], v[32:35]
	v_lshl_add_u64 v[232:233], s[64:65], 0, v[136:137]
	s_mov_b32 m0, s59
	s_nop 0
	global_load_lds_dwordx4 v[232:233], off
	v_mfma_f32_16x16x32_bf16 v[20:23], v[176:179], v[216:219], v[20:23]
	v_mfma_f32_16x16x32_bf16 v[16:19], v[186:189], v[216:219], v[16:19]
	v_mfma_f32_16x16x32_bf16 v[4:7], v[176:179], v[224:227], v[4:7]
	v_mfma_f32_16x16x32_bf16 v[0:3], v[186:189], v[224:227], v[0:3]
	s_setprio 0
	s_barrier
; #define PG8_STAGE(bufoff, gbase, voff) do { _Pragma("unroll") for (int _i = 0; _i < 2; ++_i) \
;         __builtin_amdgcn_global_load_lds((const unsigned*)((const char*)(gbase) + (voff)[_i]), (PG8_LAS unsigned*)(lds + (bufoff) + ldsw + _i * 8192), 16, 0, 0); } while (0)
; #define PG8_LDA(dst, b, h) do { _Pragma("unroll") for (int m = 0; m < 4; ++m) _Pragma("unroll") for (int k = 0; k < 2; ++k) dst[m][k] = *(const PG8_LAS bf16x8*)(lds + PG8_SA(b, h) + aoff + m * 2048 + k * 1024); } while (0)
; #define PG8_LDB(dst, b, h) do { _Pragma("unroll") for (int n = 0; n < 2; ++n) _Pragma("unroll") for (int k = 0; k < 2; ++k) dst[n][k] = *(const PG8_LAS bf16x8*)(lds + PG8_SB(b, h) + boff + n * 2048 + k * 1024); } while (0)
; #define PG8_MMA(ai, bj, At, Bt) do { __builtin_amdgcn_s_setprio(1); _Pragma("unroll") for (int m = 0; m < 4; ++m) _Pragma("unroll") for (int n = 0; n < 2; ++n) _Pragma("unroll") for (int k = 0; k < 2; ++k) \
;         acc[ai][bj][m][n] = __builtin_amdgcn_mfma_f32_16x16x32_bf16(Bt[n][k], At[m][k], acc[ai][bj][m][n], 0, 0, 0); __builtin_amdgcn_s_setprio(0); } while (0)
; #define PG8_WAIT_V(n) asm volatile("s_waitcnt vmcnt(" #n ")" ::: "memory")
; #define PG8_WAIT_L(n) asm volatile("s_waitcnt lgkmcnt(" #n ")" ::: "memory")
; #define PG8_BAR __builtin_amdgcn_s_barrier()
; #define PG8_SCHED __builtin_amdgcn_sched_barrier(0)
; template <class Epi, class Sched, bool ALIGN_EPI = false, bool SP2 = false>
; __device__ __forceinline__ void gemm_phase(PG8_LAS unsigned char* lds, const Gemm g, const Sched& S, const Epi& E) {
;     ...
;             PG8_LDB(B0, 1, 0); PG8_LDB(B1, 1, 1); PG8_SCHED; PG8_LDA(At, 1, 0); PG8_STAGE(PG8_SA(0, 1), a2 + hstep, voffA);
;             PG8_WAIT_V(8); PG8_WAIT_L(0); PG8_BAR; PG8_MMA(0, 0, At, B0); PG8_MMA(0, 1, At, B1); PG8_BAR; PG8_SCHED;
	s_add_i32 s3, 0, 0x18000
	v_add_u32_e32 v159, s3, v131
	s_add_i32 s33, 0, 0x1c000
	ds_read_b128 v[148:151], v159
	ds_read_b128 v[160:163], v159 offset:1024
	ds_read_b128 v[164:167], v159 offset:2048
	ds_read_b128 v[168:171], v159 offset:3072
	v_add_u32_e32 v159, s33, v131
	ds_read_b128 v[172:175], v159
	ds_read_b128 v[176:179], v159 offset:1024
	ds_read_b128 v[182:185], v159 offset:2048
	ds_read_b128 v[186:189], v159 offset:3072
	s_add_u32 s14, s64, 0x40000
	s_addc_u32 s15, s65, 0
	s_mov_b32 m0, s66
	v_lshl_add_u64 v[234:235], s[14:15], 0, v[132:133]
	ds_read_b128 v[190:193], v157 offset:32768
	ds_read_b128 v[194:197], v157 offset:33792
	ds_read_b128 v[198:201], v157 offset:34816
	ds_read_b128 v[208:211], v157 offset:35840
	ds_read_b128 v[212:215], v157 offset:36864
	ds_read_b128 v[216:219], v157 offset:37888
	ds_read_b128 v[220:223], v157 offset:38912
	ds_read_b128 v[224:227], v157 offset:39936
	global_load_lds_dwordx4 v[234:235], off
	v_lshl_add_u64 v[234:235], s[14:15], 0, v[136:137]
	s_mov_b32 m0, s67
	s_nop 0
	global_load_lds_dwordx4 v[234:235], off
	s_waitcnt vmcnt(8)
	s_waitcnt lgkmcnt(0)
	s_barrier
	s_setprio 1
	s_waitcnt lgkmcnt(0)
	v_mfma_f32_16x16x32_bf16 v[124:127], v[148:151], v[190:193], v[124:127]
	v_mfma_f32_16x16x32_bf16 v[120:123], v[164:167], v[190:193], v[120:123]
	v_mfma_f32_16x16x32_bf16 v[108:111], v[148:151], v[198:201], v[108:111]
	v_mfma_f32_16x16x32_bf16 v[104:107], v[164:167], v[198:201], v[104:107]
	v_mfma_f32_16x16x32_bf16 v[92:95], v[148:151], v[212:215], v[92:95]
	v_mfma_f32_16x16x32_bf16 v[88:91], v[164:167], v[212:215], v[88:91]
	v_mfma_f32_16x16x32_bf16 v[76:79], v[148:151], v[220:223], v[76:79]
	v_mfma_f32_16x16x32_bf16 v[72:75], v[164:167], v[220:223], v[72:75]
	v_mfma_f32_16x16x32_bf16 v[124:127], v[160:163], v[194:197], v[124:127]
	v_mfma_f32_16x16x32_bf16 v[120:123], v[168:171], v[194:197], v[120:123]
	v_mfma_f32_16x16x32_bf16 v[108:111], v[160:163], v[208:211], v[108:111]
	v_mfma_f32_16x16x32_bf16 v[104:107], v[168:171], v[208:211], v[104:107]
	v_mfma_f32_16x16x32_bf16 v[92:95], v[160:163], v[216:219], v[92:95]
	v_mfma_f32_16x16x32_bf16 v[88:91], v[168:171], v[216:219], v[88:91]
	v_mfma_f32_16x16x32_bf16 v[76:79], v[160:163], v[224:227], v[76:79]
	v_mfma_f32_16x16x32_bf16 v[72:75], v[168:171], v[224:227], v[72:75]
	s_setprio 0
	s_setprio 1
	v_mfma_f32_16x16x32_bf16 v[116:119], v[172:175], v[190:193], v[116:119]
	v_mfma_f32_16x16x32_bf16 v[112:115], v[182:185], v[190:193], v[112:115]
	v_mfma_f32_16x16x32_bf16 v[100:103], v[172:175], v[198:201], v[100:103]
	v_mfma_f32_16x16x32_bf16 v[96:99], v[182:185], v[198:201], v[96:99]
	v_mfma_f32_16x16x32_bf16 v[84:87], v[172:175], v[212:215], v[84:87]
	v_mfma_f32_16x16x32_bf16 v[80:83], v[182:185], v[212:215], v[80:83]
	v_mfma_f32_16x16x32_bf16 v[68:71], v[172:175], v[220:223], v[68:71]
	v_mfma_f32_16x16x32_bf16 v[64:67], v[182:185], v[220:223], v[64:67]
	v_mfma_f32_16x16x32_bf16 v[116:119], v[176:179], v[194:197], v[116:119]
	v_mfma_f32_16x16x32_bf16 v[112:115], v[186:189], v[194:197], v[112:115]
	v_mfma_f32_16x16x32_bf16 v[100:103], v[176:179], v[208:211], v[100:103]
	v_mfma_f32_16x16x32_bf16 v[96:99], v[186:189], v[208:211], v[96:99]
	v_mfma_f32_16x16x32_bf16 v[84:87], v[176:179], v[216:219], v[84:87]
	v_mfma_f32_16x16x32_bf16 v[80:83], v[186:189], v[216:219], v[80:83]
	v_mfma_f32_16x16x32_bf16 v[68:71], v[176:179], v[224:227], v[68:71]
	v_mfma_f32_16x16x32_bf16 v[64:67], v[186:189], v[224:227], v[64:67]
	s_setprio 0
	s_barrier
; #define PG8_STAGE(bufoff, gbase, voff) do { _Pragma("unroll") for (int _i = 0; _i < 2; ++_i) \
;         __builtin_amdgcn_global_load_lds((const unsigned*)((const char*)(gbase) + (voff)[_i]), (PG8_LAS unsigned*)(lds + (bufoff) + ldsw + _i * 8192), 16, 0, 0); } while (0)
; #define PG8_LDA(dst, b, h) do { _Pragma("unroll") for (int m = 0; m < 4; ++m) _Pragma("unroll") for (int k = 0; k < 2; ++k) dst[m][k] = *(const PG8_LAS bf16x8*)(lds + PG8_SA(b, h) + aoff + m * 2048 + k * 1024); } while (0)
; #define PG8_MMA(ai, bj, At, Bt) do { __builtin_amdgcn_s_setprio(1); _Pragma("unroll") for (int m = 0; m < 4; ++m) _Pragma("unroll") for (int n = 0; n < 2; ++n) _Pragma("unroll") for (int k = 0; k < 2; ++k) \
;         acc[ai][bj][m][n] = __builtin_amdgcn_mfma_f32_16x16x32_bf16(Bt[n][k], At[m][k], acc[ai][bj][m][n], 0, 0, 0); __builtin_amdgcn_s_setprio(0); } while (0)
; #define PG8_WAIT_V(n) asm volatile("s_waitcnt vmcnt(" #n ")" ::: "memory")
; #define PG8_WAIT_L(n) asm volatile("s_waitcnt lgkmcnt(" #n ")" ::: "memory")
; #define PG8_BAR __builtin_amdgcn_s_barrier()
; #define PG8_SCHED __builtin_amdgcn_sched_barrier(0)
; template <class Epi, class Sched, bool ALIGN_EPI = false, bool SP2 = false>
; __device__ __forceinline__ void gemm_phase(PG8_LAS unsigned char* lds, const Gemm g, const Sched& S, const Epi& E) {
;     ...
;         for (int t = 0; t < nt; t += 2) {
;     ...
;             PG8_LDA(At, 1, 1); PG8_STAGE(PG8_SB(1, 0), b3, voffB); PG8_STAGE(PG8_SB(1, 1), b3 + hstep, voffB); PG8_STAGE(PG8_SA(1, 0), a3, voffA);
;             PG8_WAIT_V(8); PG8_WAIT_L(0); PG8_BAR; PG8_MMA(1, 0, At, B0); PG8_MMA(1, 1, At, B1); PG8_BAR; PG8_SCHED;
	s_add_i32 s3, s3, s34
	v_lshl_add_u64 v[202:203], v[202:203], 0, s[38:39]
	s_mov_b32 m0, s3
	ds_read_b128 v[190:193], v157 offset:49152
	ds_read_b128 v[194:197], v157 offset:50176
	ds_read_b128 v[198:201], v157 offset:51200
	ds_read_b128 v[208:211], v157 offset:52224
	ds_read_b128 v[212:215], v157 offset:53248
	ds_read_b128 v[216:219], v157 offset:54272
	ds_read_b128 v[220:223], v157 offset:55296
	ds_read_b128 v[224:227], v157 offset:56320
	global_load_lds_dwordx4 v[202:203], off
	s_add_i32 m0, s3, 0x2000
	s_add_u32 s14, s62, 0x40080
	v_lshl_add_u64 v[202:203], v[228:229], 0, s[38:39]
	s_addc_u32 s15, s63, 0
	s_add_i32 s3, s33, s34
	global_load_lds_dwordx4 v[202:203], off
	v_lshl_add_u64 v[202:203], s[14:15], 0, v[134:135]
	s_mov_b32 m0, s3
	s_nop 0
	global_load_lds_dwordx4 v[202:203], off
	v_lshl_add_u64 v[202:203], s[14:15], 0, v[138:139]
	s_add_i32 m0, s3, 0x2000
	s_nop 0
	global_load_lds_dwordx4 v[202:203], off
	s_waitcnt vmcnt(6)
	s_waitcnt lgkmcnt(0)
	s_barrier
	s_setprio 1
	s_waitcnt lgkmcnt(0)
	v_mfma_f32_16x16x32_bf16 v[60:63], v[148:151], v[190:193], v[60:63]
	v_mfma_f32_16x16x32_bf16 v[56:59], v[164:167], v[190:193], v[56:59]
	v_mfma_f32_16x16x32_bf16 v[44:47], v[148:151], v[198:201], v[44:47]
	v_mfma_f32_16x16x32_bf16 v[40:43], v[164:167], v[198:201], v[40:43]
	v_mfma_f32_16x16x32_bf16 v[28:31], v[148:151], v[212:215], v[28:31]
	v_mfma_f32_16x16x32_bf16 v[24:27], v[164:167], v[212:215], v[24:27]
	v_mfma_f32_16x16x32_bf16 v[12:15], v[148:151], v[220:223], v[12:15]
	v_mfma_f32_16x16x32_bf16 v[8:11], v[164:167], v[220:223], v[8:11]
	v_mfma_f32_16x16x32_bf16 v[60:63], v[160:163], v[194:197], v[60:63]
	v_mfma_f32_16x16x32_bf16 v[56:59], v[168:171], v[194:197], v[56:59]
	v_mfma_f32_16x16x32_bf16 v[44:47], v[160:163], v[208:211], v[44:47]
	v_mfma_f32_16x16x32_bf16 v[40:43], v[168:171], v[208:211], v[40:43]
	v_lshl_add_u64 v[202:203], v[230:231], 0, s[38:39]
	s_mov_b32 m0, s75
	s_nop 0
	global_load_lds_dwordx4 v[202:203], off
	v_mfma_f32_16x16x32_bf16 v[28:31], v[160:163], v[216:219], v[28:31]
	v_mfma_f32_16x16x32_bf16 v[24:27], v[168:171], v[216:219], v[24:27]
	v_mfma_f32_16x16x32_bf16 v[12:15], v[160:163], v[224:227], v[12:15]
	v_mfma_f32_16x16x32_bf16 v[8:11], v[168:171], v[224:227], v[8:11]
	s_setprio 0
	s_setprio 1
	v_mfma_f32_16x16x32_bf16 v[52:55], v[172:175], v[190:193], v[52:55]
	v_mfma_f32_16x16x32_bf16 v[48:51], v[182:185], v[190:193], v[48:51]
	v_mfma_f32_16x16x32_bf16 v[36:39], v[172:175], v[198:201], v[36:39]
	v_mfma_f32_16x16x32_bf16 v[32:35], v[182:185], v[198:201], v[32:35]
	v_mfma_f32_16x16x32_bf16 v[20:23], v[172:175], v[212:215], v[20:23]
	v_mfma_f32_16x16x32_bf16 v[16:19], v[182:185], v[212:215], v[16:19]
	v_mfma_f32_16x16x32_bf16 v[4:7], v[172:175], v[220:223], v[4:7]
	v_mfma_f32_16x16x32_bf16 v[0:3], v[182:185], v[220:223], v[0:3]
	v_mfma_f32_16x16x32_bf16 v[52:55], v[176:179], v[194:197], v[52:55]
	v_mfma_f32_16x16x32_bf16 v[48:51], v[186:189], v[194:197], v[48:51]
	v_mfma_f32_16x16x32_bf16 v[36:39], v[176:179], v[208:211], v[36:39]
	v_mfma_f32_16x16x32_bf16 v[32:35], v[186:189], v[208:211], v[32:35]
	v_lshl_add_u64 v[202:203], v[232:233], 0, s[38:39]
	s_mov_b32 m0, s84
	s_nop 0
	global_load_lds_dwordx4 v[202:203], off
	v_mfma_f32_16x16x32_bf16 v[20:23], v[176:179], v[216:219], v[20:23]
	v_mfma_f32_16x16x32_bf16 v[16:19], v[186:189], v[216:219], v[16:19]
	v_mfma_f32_16x16x32_bf16 v[4:7], v[176:179], v[224:227], v[4:7]
	v_mfma_f32_16x16x32_bf16 v[0:3], v[186:189], v[224:227], v[0:3]
	s_setprio 0
	s_barrier
	s_add_i32 s92, s92, 2
	s_add_u32 s60, s60, 0x100
	s_addc_u32 s61, s61, 0
	s_add_u32 s90, s90, 0x100
	s_addc_u32 s91, s91, 0
	s_cmp_gt_u32 s92, 13
	s_cbranch_scc0 .LBB0_650
	s_and_b64 vcc, exec, s[44:45]
	s_cbranch_vccz .LBB0_653
	s_barrier

; #define PG8_STAGE(bufoff, gbase, voff) do { _Pragma("unroll") for (int _i = 0; _i < 2; ++_i) \
;         __builtin_amdgcn_global_load_lds((const unsigned*)((const char*)(gbase) + (voff)[_i]), (PG8_LAS unsigned*)(lds + (bufoff) + ldsw + _i * 8192), 16, 0, 0); } while (0)
; #define PG8_LDA(dst, b, h) do { _Pragma("unroll") for (int m = 0; m < 4; ++m) _Pragma("unroll") for (int k = 0; k < 2; ++k) dst[m][k] = *(const PG8_LAS bf16x8*)(lds + PG8_SA(b, h) + aoff + m * 2048 + k * 1024); } while (0)
; #define PG8_LDB(dst, b, h) do { _Pragma("unroll") for (int n = 0; n < 2; ++n) _Pragma("unroll") for (int k = 0; k < 2; ++k) dst[n][k] = *(const PG8_LAS bf16x8*)(lds + PG8_SB(b, h) + boff + n * 2048 + k * 1024); } while (0)
; #define PG8_WAIT_V(n) asm volatile("s_waitcnt vmcnt(" #n ")" ::: "memory")
; template <class Epi, class Sched, bool ALIGN_EPI = false, bool SP2 = false>
; __device__ __forceinline__ void gemm_phase(PG8_LAS unsigned char* lds, const Gemm g, const Sched& S, const Epi& E) {
;     ...
;         const bool has_next = S.next(ui + 1, nxt);
;         const char* nA = has_next ? (const char*)g.A + (size_t)nxt.pm * tstep : cA; const char* nB = has_next ? (const char*)g.Bt + (size_t)nxt.pn * tstep : cB;
;         for (int t = 0; t < nt; t += 2) {
;             const bool last = (t == nt - 2);
;             const char* a1 = cA + (size_t)(t + 1) * kstep;
;             const char* a2 = last ? nA : cA + (size_t)(t + 2) * kstep; const char* b2 = last ? nB : cB + (size_t)(t + 2) * kstep;
;             const char* a3 = a2 + kstep; const char* b3 = b2 + kstep;
;             if (last && has_next) S.a_ready(nxt);
;             if constexpr (SP2) {
;             PG8_LDB(B0, 0, 0); PG8_LDB(B1, 0, 1); PG8_SCHED; PG8_LDA(At, 0, 0); PG8_STAGE(PG8_SA(1, 1), a1 + hstep, voffA);
;             PG8_WAIT_V(8); PG8_WAIT_L(0); PG8_BAR; PG8_MMA(0, 0, At, B0); PG8_MMA(0, 1, At, B1); PG8_BAR; PG8_SCHED;
;             PG8_LDA(At, 0, 1); PG8_STAGE(PG8_SB(0, 0), b2, voffB); PG8_STAGE(PG8_SB(0, 1), b2 + hstep, voffB); PG8_STAGE(PG8_SA(0, 0), a2, voffA);
;     ...
; #pragma unroll
;         for (int a = 0; a < 2; ++a)
; #pragma unroll
;             for (int b = 0; b < 2; ++b)
; #pragma unroll
;                 for (int m = 0; m < 4; ++m)
; #pragma unroll
;                     for (int n = 0; n < 2; ++n) acc[a][b][m][n] = (f32x4){0.f, 0.f, 0.f, 0.f};
;         cur = nxt; cA = nA; cB = nB; ++ui;
.LBB0_737:
	s_ashr_i32 s51, s50, 31
	s_lshl_b64 s[14:15], s[50:51], 19
	s_add_u32 s52, s22, s14
	s_addc_u32 s53, s23, s15
	s_and_b64 s[14:15], s[8:9], exec
	s_cselect_b32 s51, s53, s57
	s_cselect_b32 s82, s52, s56
	s_ashr_i32 s49, s48, 31
	s_lshl_b64 s[14:15], s[48:49], 19
	v_readlane_b32 s3, v250, 15
	s_add_u32 s54, s3, s14
	v_readlane_b32 s3, v250, 16
	s_addc_u32 s55, s3, s15
	s_and_b64 s[14:15], s[8:9], exec
	s_cselect_b32 s49, s55, s59
	s_cselect_b32 s83, s54, s58
	s_add_u32 s56, s56, 0x40080
	s_addc_u32 s57, s57, 0
	s_add_u32 s84, s58, 0x100
	s_addc_u32 s85, s59, 0
	s_mov_b32 s86, -2
	s_waitcnt vmcnt(0)
	ds_read_b128 v[148:151], v155
	ds_read_b128 v[160:163], v155 offset:1024
	ds_read_b128 v[164:167], v155 offset:2048
	ds_read_b128 v[168:171], v155 offset:3072
	ds_read_b128 v[172:175], v156
	ds_read_b128 v[176:179], v156 offset:1024
	ds_read_b128 v[182:185], v156 offset:2048
	ds_read_b128 v[186:189], v156 offset:3072
	s_add_u32 s3, s56, 0xfffc0080
	s_addc_u32 s14, s57, -1
	s_cmp_eq_u32 s86, 12
	s_cselect_b32 s61, s51, s14
	s_cselect_b32 s60, s82, s3
	s_cselect_b32 s59, s49, s85
	s_cselect_b32 s58, s83, s84
	v_lshl_add_u64 v[202:203], s[56:57], 0, v[140:141]
	s_add_i32 m0, s43, 0xc000
	ds_read_b128 v[190:193], v157
	ds_read_b128 v[194:197], v157 offset:1024
	ds_read_b128 v[198:201], v157 offset:2048
	ds_read_b128 v[208:211], v157 offset:3072
	ds_read_b128 v[212:215], v157 offset:4096
	ds_read_b128 v[216:219], v157 offset:5120
	ds_read_b128 v[220:223], v157 offset:6144
	ds_read_b128 v[224:227], v157 offset:7168
	global_load_lds_dwordx4 v[202:203], off
	v_lshl_add_u64 v[202:203], s[56:57], 0, v[142:143]
	s_add_i32 m0, s43, 0xe000
	s_nop 0
	global_load_lds_dwordx4 v[202:203], off
	s_waitcnt vmcnt(8)
	s_waitcnt lgkmcnt(0)
	s_barrier
	s_setprio 1
	s_waitcnt lgkmcnt(0)
	v_mfma_f32_16x16x32_bf16 v[124:127], v[148:151], v[190:193], 0
	v_mfma_f32_16x16x32_bf16 v[120:123], v[164:167], v[190:193], 0
	v_mfma_f32_16x16x32_bf16 v[108:111], v[148:151], v[198:201], 0
	v_mfma_f32_16x16x32_bf16 v[104:107], v[164:167], v[198:201], 0
	v_mfma_f32_16x16x32_bf16 v[92:95], v[148:151], v[212:215], 0
	v_mfma_f32_16x16x32_bf16 v[88:91], v[164:167], v[212:215], 0
	v_mfma_f32_16x16x32_bf16 v[76:79], v[148:151], v[220:223], 0
	v_mfma_f32_16x16x32_bf16 v[72:75], v[164:167], v[220:223], 0
	v_mfma_f32_16x16x32_bf16 v[124:127], v[160:163], v[194:197], v[124:127]
	v_mfma_f32_16x16x32_bf16 v[120:123], v[168:171], v[194:197], v[120:123]
	v_mfma_f32_16x16x32_bf16 v[108:111], v[160:163], v[208:211], v[108:111]
	v_mfma_f32_16x16x32_bf16 v[104:107], v[168:171], v[208:211], v[104:107]
	v_mfma_f32_16x16x32_bf16 v[92:95], v[160:163], v[216:219], v[92:95]
	v_mfma_f32_16x16x32_bf16 v[88:91], v[168:171], v[216:219], v[88:91]
	v_mfma_f32_16x16x32_bf16 v[76:79], v[160:163], v[224:227], v[76:79]
	v_mfma_f32_16x16x32_bf16 v[72:75], v[168:171], v[224:227], v[72:75]
	s_setprio 0
	s_setprio 1
	v_mfma_f32_16x16x32_bf16 v[116:119], v[172:175], v[190:193], 0
	v_mfma_f32_16x16x32_bf16 v[112:115], v[182:185], v[190:193], 0
	v_mfma_f32_16x16x32_bf16 v[100:103], v[172:175], v[198:201], 0
	v_mfma_f32_16x16x32_bf16 v[96:99], v[182:185], v[198:201], 0
	v_mfma_f32_16x16x32_bf16 v[84:87], v[172:175], v[212:215], 0
	v_mfma_f32_16x16x32_bf16 v[80:83], v[182:185], v[212:215], 0
	v_mfma_f32_16x16x32_bf16 v[68:71], v[172:175], v[220:223], 0
	v_mfma_f32_16x16x32_bf16 v[64:67], v[182:185], v[220:223], 0
	v_mfma_f32_16x16x32_bf16 v[116:119], v[176:179], v[194:197], v[116:119]
	v_mfma_f32_16x16x32_bf16 v[112:115], v[186:189], v[194:197], v[112:115]
	v_mfma_f32_16x16x32_bf16 v[100:103], v[176:179], v[208:211], v[100:103]
	v_mfma_f32_16x16x32_bf16 v[96:99], v[186:189], v[208:211], v[96:99]
	v_mfma_f32_16x16x32_bf16 v[84:87], v[176:179], v[216:219], v[84:87]
	v_mfma_f32_16x16x32_bf16 v[80:83], v[186:189], v[216:219], v[80:83]
	v_mfma_f32_16x16x32_bf16 v[68:71], v[176:179], v[224:227], v[68:71]
	v_mfma_f32_16x16x32_bf16 v[64:67], v[186:189], v[224:227], v[64:67]
	s_setprio 0
	s_barrier
	s_add_i32 s3, s74, s34
	v_lshl_add_u64 v[202:203], s[58:59], 0, v[136:137]
	s_mov_b32 m0, s3
	ds_read_b128 v[190:193], v157 offset:16384
	ds_read_b128 v[194:197], v157 offset:17408
	ds_read_b128 v[198:201], v157 offset:18432
	ds_read_b128 v[208:211], v157 offset:19456
	ds_read_b128 v[212:215], v157 offset:20480
	ds_read_b128 v[216:219], v157 offset:21504
	ds_read_b128 v[220:223], v157 offset:22528
	ds_read_b128 v[224:227], v157 offset:23552
	global_load_lds_dwordx4 v[202:203], off
	s_add_i32 m0, s3, 0x2000
	s_add_u32 s14, s58, 0x40000
	v_lshl_add_u64 v[228:229], s[58:59], 0, v[132:133]
	s_addc_u32 s15, s59, 0
	s_add_i32 s3, s75, s34
	global_load_lds_dwordx4 v[228:229], off
	v_lshl_add_u64 v[230:231], s[14:15], 0, v[136:137]
	s_mov_b32 m0, s3
	global_load_lds_dwordx4 v[230:231], off
	v_lshl_add_u64 v[230:231], s[14:15], 0, v[132:133]
	s_add_i32 m0, s3, 0x2000
	s_nop 0
	global_load_lds_dwordx4 v[230:231], off
	s_waitcnt vmcnt(6)
	s_waitcnt lgkmcnt(0)
	s_barrier
; #define PG8_STAGE(bufoff, gbase, voff) do { _Pragma("unroll") for (int _i = 0; _i < 2; ++_i) \
;         __builtin_amdgcn_global_load_lds((const unsigned*)((const char*)(gbase) + (voff)[_i]), (PG8_LAS unsigned*)(lds + (bufoff) + ldsw + _i * 8192), 16, 0, 0); } while (0)
; #define PG8_LDA(dst, b, h) do { _Pragma("unroll") for (int m = 0; m < 4; ++m) _Pragma("unroll") for (int k = 0; k < 2; ++k) dst[m][k] = *(const PG8_LAS bf16x8*)(lds + PG8_SA(b, h) + aoff + m * 2048 + k * 1024); } while (0)
; #define PG8_LDB(dst, b, h) do { _Pragma("unroll") for (int n = 0; n < 2; ++n) _Pragma("unroll") for (int k = 0; k < 2; ++k) dst[n][k] = *(const PG8_LAS bf16x8*)(lds + PG8_SB(b, h) + boff + n * 2048 + k * 1024); } while (0)
; #define PG8_MMA(ai, bj, At, Bt) do { __builtin_amdgcn_s_setprio(1); _Pragma("unroll") for (int m = 0; m < 4; ++m) _Pragma("unroll") for (int n = 0; n < 2; ++n) _Pragma("unroll") for (int k = 0; k < 2; ++k) \
;         acc[ai][bj][m][n] = __builtin_amdgcn_mfma_f32_16x16x32_bf16(Bt[n][k], At[m][k], acc[ai][bj][m][n], 0, 0, 0); __builtin_amdgcn_s_setprio(0); } while (0)
; #define PG8_WAIT_V(n) asm volatile("s_waitcnt vmcnt(" #n ")" ::: "memory")
; #define PG8_WAIT_L(n) asm volatile("s_waitcnt lgkmcnt(" #n ")" ::: "memory")
; #define PG8_BAR __builtin_amdgcn_s_barrier()
; #define PG8_SCHED __builtin_amdgcn_sched_barrier(0)
; template <class Epi, class Sched, bool ALIGN_EPI = false, bool SP2 = false>
; __device__ __forceinline__ void gemm_phase(PG8_LAS unsigned char* lds, const Gemm g, const Sched& S, const Epi& E) {
;     ...
;             PG8_LDA(At, 0, 1); PG8_STAGE(PG8_SB(0, 0), b2, voffB); PG8_STAGE(PG8_SB(0, 1), b2 + hstep, voffB); PG8_STAGE(PG8_SA(0, 0), a2, voffA);
;             PG8_WAIT_V(8); PG8_WAIT_L(0); PG8_BAR; PG8_MMA(1, 0, At, B0); PG8_MMA(1, 1, At, B1); PG8_BAR; PG8_SCHED;
;             PG8_LDB(B0, 1, 0); PG8_LDB(B1, 1, 1); PG8_SCHED; PG8_LDA(At, 1, 0); PG8_STAGE(PG8_SA(0, 1), a2 + hstep, voffA);
;             PG8_WAIT_V(8); PG8_WAIT_L(0); PG8_BAR; PG8_MMA(0, 0, At, B0); PG8_MMA(0, 1, At, B1); PG8_BAR; PG8_SCHED;
	s_setprio 1
	s_waitcnt lgkmcnt(0)
	v_mfma_f32_16x16x32_bf16 v[60:63], v[148:151], v[190:193], 0
	v_mfma_f32_16x16x32_bf16 v[56:59], v[164:167], v[190:193], 0
	v_mfma_f32_16x16x32_bf16 v[44:47], v[148:151], v[198:201], 0
	v_mfma_f32_16x16x32_bf16 v[40:43], v[164:167], v[198:201], 0
	v_mfma_f32_16x16x32_bf16 v[28:31], v[148:151], v[212:215], 0
	v_mfma_f32_16x16x32_bf16 v[24:27], v[164:167], v[212:215], 0
	v_mfma_f32_16x16x32_bf16 v[12:15], v[148:151], v[220:223], 0
	v_mfma_f32_16x16x32_bf16 v[8:11], v[164:167], v[220:223], 0
	v_mfma_f32_16x16x32_bf16 v[60:63], v[160:163], v[194:197], v[60:63]
	v_mfma_f32_16x16x32_bf16 v[56:59], v[168:171], v[194:197], v[56:59]
	v_mfma_f32_16x16x32_bf16 v[44:47], v[160:163], v[208:211], v[44:47]
	v_mfma_f32_16x16x32_bf16 v[40:43], v[168:171], v[208:211], v[40:43]
	v_lshl_add_u64 v[230:231], s[60:61], 0, v[138:139]
	s_mov_b32 m0, s43
	s_nop 0
	global_load_lds_dwordx4 v[230:231], off
	v_mfma_f32_16x16x32_bf16 v[28:31], v[160:163], v[216:219], v[28:31]
	v_mfma_f32_16x16x32_bf16 v[24:27], v[168:171], v[216:219], v[24:27]
	v_mfma_f32_16x16x32_bf16 v[12:15], v[160:163], v[224:227], v[12:15]
	v_mfma_f32_16x16x32_bf16 v[8:11], v[168:171], v[224:227], v[8:11]
	s_setprio 0
	s_setprio 1
	v_mfma_f32_16x16x32_bf16 v[52:55], v[172:175], v[190:193], 0
	v_mfma_f32_16x16x32_bf16 v[48:51], v[182:185], v[190:193], 0
	v_mfma_f32_16x16x32_bf16 v[36:39], v[172:175], v[198:201], 0
	v_mfma_f32_16x16x32_bf16 v[32:35], v[182:185], v[198:201], 0
	v_mfma_f32_16x16x32_bf16 v[20:23], v[172:175], v[212:215], 0
	v_mfma_f32_16x16x32_bf16 v[16:19], v[182:185], v[212:215], 0
	v_mfma_f32_16x16x32_bf16 v[4:7], v[172:175], v[220:223], 0
	v_mfma_f32_16x16x32_bf16 v[0:3], v[182:185], v[220:223], 0
	v_mfma_f32_16x16x32_bf16 v[52:55], v[176:179], v[194:197], v[52:55]
	v_mfma_f32_16x16x32_bf16 v[48:51], v[186:189], v[194:197], v[48:51]
	v_mfma_f32_16x16x32_bf16 v[36:39], v[176:179], v[208:211], v[36:39]
	v_mfma_f32_16x16x32_bf16 v[32:35], v[186:189], v[208:211], v[32:35]
	v_lshl_add_u64 v[232:233], s[60:61], 0, v[134:135]
	s_mov_b32 m0, s62
	s_nop 0
	global_load_lds_dwordx4 v[232:233], off
	v_mfma_f32_16x16x32_bf16 v[20:23], v[176:179], v[216:219], v[20:23]
	v_mfma_f32_16x16x32_bf16 v[16:19], v[186:189], v[216:219], v[16:19]
	v_mfma_f32_16x16x32_bf16 v[4:7], v[176:179], v[224:227], v[4:7]
	v_mfma_f32_16x16x32_bf16 v[0:3], v[186:189], v[224:227], v[0:3]
	s_setprio 0
	s_barrier
	s_add_i32 s3, 0, 0x18000
	v_add_u32_e32 v159, s3, v131
	s_add_i32 s33, 0, 0x1c000
	ds_read_b128 v[148:151], v159
	ds_read_b128 v[160:163], v159 offset:1024
	ds_read_b128 v[164:167], v159 offset:2048
	ds_read_b128 v[168:171], v159 offset:3072
	v_add_u32_e32 v159, s33, v131
	ds_read_b128 v[172:175], v159
	ds_read_b128 v[176:179], v159 offset:1024
	ds_read_b128 v[182:185], v159 offset:2048
	ds_read_b128 v[186:189], v159 offset:3072
	s_add_u32 s14, s60, 0x40000
	s_addc_u32 s15, s61, 0
	s_mov_b32 m0, s63
	v_lshl_add_u64 v[234:235], s[14:15], 0, v[138:139]
	ds_read_b128 v[190:193], v157 offset:32768
	ds_read_b128 v[194:197], v157 offset:33792
	ds_read_b128 v[198:201], v157 offset:34816
	ds_read_b128 v[208:211], v157 offset:35840
	ds_read_b128 v[212:215], v157 offset:36864
	ds_read_b128 v[216:219], v157 offset:37888
	ds_read_b128 v[220:223], v157 offset:38912
	ds_read_b128 v[224:227], v157 offset:39936
	global_load_lds_dwordx4 v[234:235], off
	v_lshl_add_u64 v[234:235], s[14:15], 0, v[134:135]
	s_mov_b32 m0, s64
	s_nop 0
	global_load_lds_dwordx4 v[234:235], off
	s_waitcnt vmcnt(8)
	s_waitcnt lgkmcnt(0)
	s_barrier
	s_setprio 1
	s_waitcnt lgkmcnt(0)
	v_mfma_f32_16x16x32_bf16 v[124:127], v[148:151], v[190:193], v[124:127]
	v_mfma_f32_16x16x32_bf16 v[120:123], v[164:167], v[190:193], v[120:123]
	v_mfma_f32_16x16x32_bf16 v[108:111], v[148:151], v[198:201], v[108:111]
	v_mfma_f32_16x16x32_bf16 v[104:107], v[164:167], v[198:201], v[104:107]
	v_mfma_f32_16x16x32_bf16 v[92:95], v[148:151], v[212:215], v[92:95]
	v_mfma_f32_16x16x32_bf16 v[88:91], v[164:167], v[212:215], v[88:91]
	v_mfma_f32_16x16x32_bf16 v[76:79], v[148:151], v[220:223], v[76:79]
	v_mfma_f32_16x16x32_bf16 v[72:75], v[164:167], v[220:223], v[72:75]
	v_mfma_f32_16x16x32_bf16 v[124:127], v[160:163], v[194:197], v[124:127]
	v_mfma_f32_16x16x32_bf16 v[120:123], v[168:171], v[194:197], v[120:123]
	v_mfma_f32_16x16x32_bf16 v[108:111], v[160:163], v[208:211], v[108:111]
	v_mfma_f32_16x16x32_bf16 v[104:107], v[168:171], v[208:211], v[104:107]
	v_mfma_f32_16x16x32_bf16 v[92:95], v[160:163], v[216:219], v[92:95]
	v_mfma_f32_16x16x32_bf16 v[88:91], v[168:171], v[216:219], v[88:91]
	v_mfma_f32_16x16x32_bf16 v[76:79], v[160:163], v[224:227], v[76:79]
	v_mfma_f32_16x16x32_bf16 v[72:75], v[168:171], v[224:227], v[72:75]
	s_setprio 0
	s_setprio 1
	v_mfma_f32_16x16x32_bf16 v[116:119], v[172:175], v[190:193], v[116:119]
	v_mfma_f32_16x16x32_bf16 v[112:115], v[182:185], v[190:193], v[112:115]
	v_mfma_f32_16x16x32_bf16 v[100:103], v[172:175], v[198:201], v[100:103]
	v_mfma_f32_16x16x32_bf16 v[96:99], v[182:185], v[198:201], v[96:99]
	v_mfma_f32_16x16x32_bf16 v[84:87], v[172:175], v[212:215], v[84:87]
	v_mfma_f32_16x16x32_bf16 v[80:83], v[182:185], v[212:215], v[80:83]
	v_mfma_f32_16x16x32_bf16 v[68:71], v[172:175], v[220:223], v[68:71]
	v_mfma_f32_16x16x32_bf16 v[64:67], v[182:185], v[220:223], v[64:67]
	v_mfma_f32_16x16x32_bf16 v[116:119], v[176:179], v[194:197], v[116:119]
	v_mfma_f32_16x16x32_bf16 v[112:115], v[186:189], v[194:197], v[112:115]
	v_mfma_f32_16x16x32_bf16 v[100:103], v[176:179], v[208:211], v[100:103]
	v_mfma_f32_16x16x32_bf16 v[96:99], v[186:189], v[208:211], v[96:99]
	v_mfma_f32_16x16x32_bf16 v[84:87], v[176:179], v[216:219], v[84:87]
	v_mfma_f32_16x16x32_bf16 v[80:83], v[186:189], v[216:219], v[80:83]
	v_mfma_f32_16x16x32_bf16 v[68:71], v[176:179], v[224:227], v[68:71]
	v_mfma_f32_16x16x32_bf16 v[64:67], v[186:189], v[224:227], v[64:67]
	s_setprio 0
	s_barrier
; #define PG8_STAGE(bufoff, gbase, voff) do { _Pragma("unroll") for (int _i = 0; _i < 2; ++_i) \
;         __builtin_amdgcn_global_load_lds((const unsigned*)((const char*)(gbase) + (voff)[_i]), (PG8_LAS unsigned*)(lds + (bufoff) + ldsw + _i * 8192), 16, 0, 0); } while (0)
; #define PG8_LDA(dst, b, h) do { _Pragma("unroll") for (int m = 0; m < 4; ++m) _Pragma("unroll") for (int k = 0; k < 2; ++k) dst[m][k] = *(const PG8_LAS bf16x8*)(lds + PG8_SA(b, h) + aoff + m * 2048 + k * 1024); } while (0)
; #define PG8_LDB(dst, b, h) do { _Pragma("unroll") for (int n = 0; n < 2; ++n) _Pragma("unroll") for (int k = 0; k < 2; ++k) dst[n][k] = *(const PG8_LAS bf16x8*)(lds + PG8_SB(b, h) + boff + n * 2048 + k * 1024); } while (0)
; #define PG8_MMA(ai, bj, At, Bt) do { __builtin_amdgcn_s_setprio(1); _Pragma("unroll") for (int m = 0; m < 4; ++m) _Pragma("unroll") for (int n = 0; n < 2; ++n) _Pragma("unroll") for (int k = 0; k < 2; ++k) \
;         acc[ai][bj][m][n] = __builtin_amdgcn_mfma_f32_16x16x32_bf16(Bt[n][k], At[m][k], acc[ai][bj][m][n], 0, 0, 0); __builtin_amdgcn_s_setprio(0); } while (0)
; #define PG8_WAIT_V(n) asm volatile("s_waitcnt vmcnt(" #n ")" ::: "memory")
; #define PG8_WAIT_L(n) asm volatile("s_waitcnt lgkmcnt(" #n ")" ::: "memory")
; #define PG8_BAR __builtin_amdgcn_s_barrier()
; #define PG8_SCHED __builtin_amdgcn_sched_barrier(0)
; template <class Epi, class Sched, bool ALIGN_EPI = false, bool SP2 = false>
; __device__ __forceinline__ void gemm_phase(PG8_LAS unsigned char* lds, const Gemm g, const Sched& S, const Epi& E) {
;     ...
;         for (int t = 0; t < nt; t += 2) {
;             const bool last = (t == nt - 2);
;             const char* a1 = cA + (size_t)(t + 1) * kstep;
;             const char* a2 = last ? nA : cA + (size_t)(t + 2) * kstep; const char* b2 = last ? nB : cB + (size_t)(t + 2) * kstep;
;             const char* a3 = a2 + kstep; const char* b3 = b2 + kstep;
;             if (last && has_next) S.a_ready(nxt);
;             if constexpr (SP2) {
;             PG8_LDB(B0, 0, 0); PG8_LDB(B1, 0, 1); PG8_SCHED; PG8_LDA(At, 0, 0); PG8_STAGE(PG8_SA(1, 1), a1 + hstep, voffA);
;     ...
;             PG8_LDA(At, 1, 1); PG8_STAGE(PG8_SB(1, 0), b3, voffB); PG8_STAGE(PG8_SB(1, 1), b3 + hstep, voffB); PG8_STAGE(PG8_SA(1, 0), a3, voffA);
;             PG8_WAIT_V(8); PG8_WAIT_L(0); PG8_BAR; PG8_MMA(1, 0, At, B0); PG8_MMA(1, 1, At, B1); PG8_BAR; PG8_SCHED;
	s_add_i32 s3, s3, s34
	v_lshl_add_u64 v[202:203], v[202:203], 0, s[38:39]
	s_mov_b32 m0, s3
	ds_read_b128 v[190:193], v157 offset:49152
	ds_read_b128 v[194:197], v157 offset:50176
	ds_read_b128 v[198:201], v157 offset:51200
	ds_read_b128 v[208:211], v157 offset:52224
	ds_read_b128 v[212:215], v157 offset:53248
	ds_read_b128 v[216:219], v157 offset:54272
	ds_read_b128 v[220:223], v157 offset:55296
	ds_read_b128 v[224:227], v157 offset:56320
	global_load_lds_dwordx4 v[202:203], off
	s_add_i32 m0, s3, 0x2000
	s_add_u32 s14, s58, 0x40080
	v_lshl_add_u64 v[202:203], v[228:229], 0, s[38:39]
	s_addc_u32 s15, s59, 0
	s_add_i32 s3, s33, s34
	global_load_lds_dwordx4 v[202:203], off
	v_lshl_add_u64 v[202:203], s[14:15], 0, v[136:137]
	s_mov_b32 m0, s3
	s_nop 0
	global_load_lds_dwordx4 v[202:203], off
	v_lshl_add_u64 v[202:203], s[14:15], 0, v[132:133]
	s_add_i32 m0, s3, 0x2000
	s_nop 0
	global_load_lds_dwordx4 v[202:203], off
	s_waitcnt vmcnt(6)
	s_waitcnt lgkmcnt(0)
	s_barrier
	s_setprio 1
	s_waitcnt lgkmcnt(0)
	v_mfma_f32_16x16x32_bf16 v[60:63], v[148:151], v[190:193], v[60:63]
	v_mfma_f32_16x16x32_bf16 v[56:59], v[164:167], v[190:193], v[56:59]
	v_mfma_f32_16x16x32_bf16 v[44:47], v[148:151], v[198:201], v[44:47]
	v_mfma_f32_16x16x32_bf16 v[40:43], v[164:167], v[198:201], v[40:43]
	v_mfma_f32_16x16x32_bf16 v[28:31], v[148:151], v[212:215], v[28:31]
	v_mfma_f32_16x16x32_bf16 v[24:27], v[164:167], v[212:215], v[24:27]
	v_mfma_f32_16x16x32_bf16 v[12:15], v[148:151], v[220:223], v[12:15]
	v_mfma_f32_16x16x32_bf16 v[8:11], v[164:167], v[220:223], v[8:11]
	v_mfma_f32_16x16x32_bf16 v[60:63], v[160:163], v[194:197], v[60:63]
	v_mfma_f32_16x16x32_bf16 v[56:59], v[168:171], v[194:197], v[56:59]
	v_mfma_f32_16x16x32_bf16 v[44:47], v[160:163], v[208:211], v[44:47]
	v_mfma_f32_16x16x32_bf16 v[40:43], v[168:171], v[208:211], v[40:43]
	v_lshl_add_u64 v[202:203], v[230:231], 0, s[38:39]
	s_mov_b32 m0, s66
	s_nop 0
	global_load_lds_dwordx4 v[202:203], off
	v_mfma_f32_16x16x32_bf16 v[28:31], v[160:163], v[216:219], v[28:31]
	v_mfma_f32_16x16x32_bf16 v[24:27], v[168:171], v[216:219], v[24:27]
	v_mfma_f32_16x16x32_bf16 v[12:15], v[160:163], v[224:227], v[12:15]
	v_mfma_f32_16x16x32_bf16 v[8:11], v[168:171], v[224:227], v[8:11]
	s_setprio 0
	s_setprio 1
	v_mfma_f32_16x16x32_bf16 v[52:55], v[172:175], v[190:193], v[52:55]
	v_mfma_f32_16x16x32_bf16 v[48:51], v[182:185], v[190:193], v[48:51]
	v_mfma_f32_16x16x32_bf16 v[36:39], v[172:175], v[198:201], v[36:39]
	v_mfma_f32_16x16x32_bf16 v[32:35], v[182:185], v[198:201], v[32:35]
	v_mfma_f32_16x16x32_bf16 v[20:23], v[172:175], v[212:215], v[20:23]
	v_mfma_f32_16x16x32_bf16 v[16:19], v[182:185], v[212:215], v[16:19]
	v_mfma_f32_16x16x32_bf16 v[4:7], v[172:175], v[220:223], v[4:7]
	v_mfma_f32_16x16x32_bf16 v[0:3], v[182:185], v[220:223], v[0:3]
	v_mfma_f32_16x16x32_bf16 v[52:55], v[176:179], v[194:197], v[52:55]
	v_mfma_f32_16x16x32_bf16 v[48:51], v[186:189], v[194:197], v[48:51]
	v_mfma_f32_16x16x32_bf16 v[36:39], v[176:179], v[208:211], v[36:39]
	v_mfma_f32_16x16x32_bf16 v[32:35], v[186:189], v[208:211], v[32:35]
	v_lshl_add_u64 v[202:203], v[232:233], 0, s[38:39]
	s_mov_b32 m0, s67
	s_nop 0
	global_load_lds_dwordx4 v[202:203], off
	v_mfma_f32_16x16x32_bf16 v[20:23], v[176:179], v[216:219], v[20:23]
	v_mfma_f32_16x16x32_bf16 v[16:19], v[186:189], v[216:219], v[16:19]
	v_mfma_f32_16x16x32_bf16 v[4:7], v[176:179], v[224:227], v[4:7]
	v_mfma_f32_16x16x32_bf16 v[0:3], v[186:189], v[224:227], v[0:3]
	s_setprio 0
	s_barrier
	s_add_i32 s86, s86, 2
	s_add_u32 s56, s56, 0x100
	s_addc_u32 s57, s57, 0
	s_add_u32 s84, s84, 0x100
	s_addc_u32 s85, s85, 0
.LBB0_738:
	ds_read_b128 v[148:151], v155
	ds_read_b128 v[160:163], v155 offset:1024
	ds_read_b128 v[164:167], v155 offset:2048
	ds_read_b128 v[168:171], v155 offset:3072
	ds_read_b128 v[172:175], v156
	ds_read_b128 v[176:179], v156 offset:1024
	ds_read_b128 v[182:185], v156 offset:2048
	ds_read_b128 v[186:189], v156 offset:3072
	s_add_u32 s3, s56, 0xfffc0080
	s_addc_u32 s14, s57, -1
	s_cmp_eq_u32 s86, 12
	s_cselect_b32 s61, s51, s14
	s_cselect_b32 s60, s82, s3
	s_cselect_b32 s59, s49, s85
	s_cselect_b32 s58, s83, s84
	v_lshl_add_u64 v[202:203], s[56:57], 0, v[140:141]
	s_add_i32 m0, s43, 0xc000
	ds_read_b128 v[190:193], v157
	ds_read_b128 v[194:197], v157 offset:1024
	ds_read_b128 v[198:201], v157 offset:2048
	ds_read_b128 v[208:211], v157 offset:3072
	ds_read_b128 v[212:215], v157 offset:4096
	ds_read_b128 v[216:219], v157 offset:5120
	ds_read_b128 v[220:223], v157 offset:6144
	ds_read_b128 v[224:227], v157 offset:7168
	global_load_lds_dwordx4 v[202:203], off
	v_lshl_add_u64 v[202:203], s[56:57], 0, v[142:143]
	s_add_i32 m0, s43, 0xe000
	s_nop 0
	global_load_lds_dwordx4 v[202:203], off
	s_waitcnt vmcnt(8)
	s_waitcnt lgkmcnt(0)
	s_barrier
; #define PG8_STAGE(bufoff, gbase, voff) do { _Pragma("unroll") for (int _i = 0; _i < 2; ++_i) \
;         __builtin_amdgcn_global_load_lds((const unsigned*)((const char*)(gbase) + (voff)[_i]), (PG8_LAS unsigned*)(lds + (bufoff) + ldsw + _i * 8192), 16, 0, 0); } while (0)
; #define PG8_LDA(dst, b, h) do { _Pragma("unroll") for (int m = 0; m < 4; ++m) _Pragma("unroll") for (int k = 0; k < 2; ++k) dst[m][k] = *(const PG8_LAS bf16x8*)(lds + PG8_SA(b, h) + aoff + m * 2048 + k * 1024); } while (0)
; #define PG8_LDB(dst, b, h) do { _Pragma("unroll") for (int n = 0; n < 2; ++n) _Pragma("unroll") for (int k = 0; k < 2; ++k) dst[n][k] = *(const PG8_LAS bf16x8*)(lds + PG8_SB(b, h) + boff + n * 2048 + k * 1024); } while (0)
; #define PG8_MMA(ai, bj, At, Bt) do { __builtin_amdgcn_s_setprio(1); _Pragma("unroll") for (int m = 0; m < 4; ++m) _Pragma("unroll") for (int n = 0; n < 2; ++n) _Pragma("unroll") for (int k = 0; k < 2; ++k) \
;         acc[ai][bj][m][n] = __builtin_amdgcn_mfma_f32_16x16x32_bf16(Bt[n][k], At[m][k], acc[ai][bj][m][n], 0, 0, 0); __builtin_amdgcn_s_setprio(0); } while (0)
; #define PG8_WAIT_V(n) asm volatile("s_waitcnt vmcnt(" #n ")" ::: "memory")
; #define PG8_WAIT_L(n) asm volatile("s_waitcnt lgkmcnt(" #n ")" ::: "memory")
; #define PG8_BAR __builtin_amdgcn_s_barrier()
; #define PG8_SCHED __builtin_amdgcn_sched_barrier(0)
; template <class Epi, class Sched, bool ALIGN_EPI = false, bool SP2 = false>
; __device__ __forceinline__ void gemm_phase(PG8_LAS unsigned char* lds, const Gemm g, const Sched& S, const Epi& E) {
;     ...
;             PG8_LDB(B0, 0, 0); PG8_LDB(B1, 0, 1); PG8_SCHED; PG8_LDA(At, 0, 0); PG8_STAGE(PG8_SA(1, 1), a1 + hstep, voffA);
;             PG8_WAIT_V(8); PG8_WAIT_L(0); PG8_BAR; PG8_MMA(0, 0, At, B0); PG8_MMA(0, 1, At, B1); PG8_BAR; PG8_SCHED;
;             PG8_LDA(At, 0, 1); PG8_STAGE(PG8_SB(0, 0), b2, voffB); PG8_STAGE(PG8_SB(0, 1), b2 + hstep, voffB); PG8_STAGE(PG8_SA(0, 0), a2, voffA);
;             PG8_WAIT_V(8); PG8_WAIT_L(0); PG8_BAR; PG8_MMA(1, 0, At, B0); PG8_MMA(1, 1, At, B1); PG8_BAR; PG8_SCHED;
	s_setprio 1
	s_waitcnt lgkmcnt(0)
	v_mfma_f32_16x16x32_bf16 v[124:127], v[148:151], v[190:193], v[124:127]
	v_mfma_f32_16x16x32_bf16 v[120:123], v[164:167], v[190:193], v[120:123]
	v_mfma_f32_16x16x32_bf16 v[108:111], v[148:151], v[198:201], v[108:111]
	v_mfma_f32_16x16x32_bf16 v[104:107], v[164:167], v[198:201], v[104:107]
	v_mfma_f32_16x16x32_bf16 v[92:95], v[148:151], v[212:215], v[92:95]
	v_mfma_f32_16x16x32_bf16 v[88:91], v[164:167], v[212:215], v[88:91]
	v_mfma_f32_16x16x32_bf16 v[76:79], v[148:151], v[220:223], v[76:79]
	v_mfma_f32_16x16x32_bf16 v[72:75], v[164:167], v[220:223], v[72:75]
	v_mfma_f32_16x16x32_bf16 v[124:127], v[160:163], v[194:197], v[124:127]
	v_mfma_f32_16x16x32_bf16 v[120:123], v[168:171], v[194:197], v[120:123]
	v_mfma_f32_16x16x32_bf16 v[108:111], v[160:163], v[208:211], v[108:111]
	v_mfma_f32_16x16x32_bf16 v[104:107], v[168:171], v[208:211], v[104:107]
	v_mfma_f32_16x16x32_bf16 v[92:95], v[160:163], v[216:219], v[92:95]
	v_mfma_f32_16x16x32_bf16 v[88:91], v[168:171], v[216:219], v[88:91]
	v_mfma_f32_16x16x32_bf16 v[76:79], v[160:163], v[224:227], v[76:79]
	v_mfma_f32_16x16x32_bf16 v[72:75], v[168:171], v[224:227], v[72:75]
	s_setprio 0
	s_setprio 1
	v_mfma_f32_16x16x32_bf16 v[116:119], v[172:175], v[190:193], v[116:119]
	v_mfma_f32_16x16x32_bf16 v[112:115], v[182:185], v[190:193], v[112:115]
	v_mfma_f32_16x16x32_bf16 v[100:103], v[172:175], v[198:201], v[100:103]
	v_mfma_f32_16x16x32_bf16 v[96:99], v[182:185], v[198:201], v[96:99]
	v_mfma_f32_16x16x32_bf16 v[84:87], v[172:175], v[212:215], v[84:87]
	v_mfma_f32_16x16x32_bf16 v[80:83], v[182:185], v[212:215], v[80:83]
	v_mfma_f32_16x16x32_bf16 v[68:71], v[172:175], v[220:223], v[68:71]
	v_mfma_f32_16x16x32_bf16 v[64:67], v[182:185], v[220:223], v[64:67]
	v_mfma_f32_16x16x32_bf16 v[116:119], v[176:179], v[194:197], v[116:119]
	v_mfma_f32_16x16x32_bf16 v[112:115], v[186:189], v[194:197], v[112:115]
	v_mfma_f32_16x16x32_bf16 v[100:103], v[176:179], v[208:211], v[100:103]
	v_mfma_f32_16x16x32_bf16 v[96:99], v[186:189], v[208:211], v[96:99]
	v_mfma_f32_16x16x32_bf16 v[84:87], v[176:179], v[216:219], v[84:87]
	v_mfma_f32_16x16x32_bf16 v[80:83], v[186:189], v[216:219], v[80:83]
	v_mfma_f32_16x16x32_bf16 v[68:71], v[176:179], v[224:227], v[68:71]
	v_mfma_f32_16x16x32_bf16 v[64:67], v[186:189], v[224:227], v[64:67]
	s_setprio 0
	s_barrier
	s_add_i32 s3, s74, s34
	v_lshl_add_u64 v[202:203], s[58:59], 0, v[136:137]
	s_mov_b32 m0, s3
	ds_read_b128 v[190:193], v157 offset:16384
	ds_read_b128 v[194:197], v157 offset:17408
	ds_read_b128 v[198:201], v157 offset:18432
	ds_read_b128 v[208:211], v157 offset:19456
	ds_read_b128 v[212:215], v157 offset:20480
	ds_read_b128 v[216:219], v157 offset:21504
	ds_read_b128 v[220:223], v157 offset:22528
	ds_read_b128 v[224:227], v157 offset:23552
	global_load_lds_dwordx4 v[202:203], off
	s_add_i32 m0, s3, 0x2000
	s_add_u32 s14, s58, 0x40000
	v_lshl_add_u64 v[228:229], s[58:59], 0, v[132:133]
	s_addc_u32 s15, s59, 0
	s_add_i32 s3, s75, s34
	global_load_lds_dwordx4 v[228:229], off
	v_lshl_add_u64 v[230:231], s[14:15], 0, v[136:137]
	s_mov_b32 m0, s3
	global_load_lds_dwordx4 v[230:231], off
	v_lshl_add_u64 v[230:231], s[14:15], 0, v[132:133]
	s_add_i32 m0, s3, 0x2000
	s_nop 0
	global_load_lds_dwordx4 v[230:231], off
	s_waitcnt vmcnt(6)
	s_waitcnt lgkmcnt(0)
	s_barrier
	s_setprio 1
	s_waitcnt lgkmcnt(0)
	v_mfma_f32_16x16x32_bf16 v[60:63], v[148:151], v[190:193], v[60:63]
	v_mfma_f32_16x16x32_bf16 v[56:59], v[164:167], v[190:193], v[56:59]
	v_mfma_f32_16x16x32_bf16 v[44:47], v[148:151], v[198:201], v[44:47]
	v_mfma_f32_16x16x32_bf16 v[40:43], v[164:167], v[198:201], v[40:43]
	v_mfma_f32_16x16x32_bf16 v[28:31], v[148:151], v[212:215], v[28:31]
	v_mfma_f32_16x16x32_bf16 v[24:27], v[164:167], v[212:215], v[24:27]
	v_mfma_f32_16x16x32_bf16 v[12:15], v[148:151], v[220:223], v[12:15]
	v_mfma_f32_16x16x32_bf16 v[8:11], v[164:167], v[220:223], v[8:11]
	v_mfma_f32_16x16x32_bf16 v[60:63], v[160:163], v[194:197], v[60:63]
	v_mfma_f32_16x16x32_bf16 v[56:59], v[168:171], v[194:197], v[56:59]
	v_mfma_f32_16x16x32_bf16 v[44:47], v[160:163], v[208:211], v[44:47]
	v_mfma_f32_16x16x32_bf16 v[40:43], v[168:171], v[208:211], v[40:43]
	v_lshl_add_u64 v[230:231], s[60:61], 0, v[138:139]
	s_mov_b32 m0, s43
	s_nop 0
	global_load_lds_dwordx4 v[230:231], off
	v_mfma_f32_16x16x32_bf16 v[28:31], v[160:163], v[216:219], v[28:31]
	v_mfma_f32_16x16x32_bf16 v[24:27], v[168:171], v[216:219], v[24:27]
	v_mfma_f32_16x16x32_bf16 v[12:15], v[160:163], v[224:227], v[12:15]
	v_mfma_f32_16x16x32_bf16 v[8:11], v[168:171], v[224:227], v[8:11]
	s_setprio 0
	s_setprio 1
	v_mfma_f32_16x16x32_bf16 v[52:55], v[172:175], v[190:193], v[52:55]
	v_mfma_f32_16x16x32_bf16 v[48:51], v[182:185], v[190:193], v[48:51]
	v_mfma_f32_16x16x32_bf16 v[36:39], v[172:175], v[198:201], v[36:39]
	v_mfma_f32_16x16x32_bf16 v[32:35], v[182:185], v[198:201], v[32:35]
	v_mfma_f32_16x16x32_bf16 v[20:23], v[172:175], v[212:215], v[20:23]
	v_mfma_f32_16x16x32_bf16 v[16:19], v[182:185], v[212:215], v[16:19]
	v_mfma_f32_16x16x32_bf16 v[4:7], v[172:175], v[220:223], v[4:7]
	v_mfma_f32_16x16x32_bf16 v[0:3], v[182:185], v[220:223], v[0:3]
	v_mfma_f32_16x16x32_bf16 v[52:55], v[176:179], v[194:197], v[52:55]
	v_mfma_f32_16x16x32_bf16 v[48:51], v[186:189], v[194:197], v[48:51]
	v_mfma_f32_16x16x32_bf16 v[36:39], v[176:179], v[208:211], v[36:39]
	v_mfma_f32_16x16x32_bf16 v[32:35], v[186:189], v[208:211], v[32:35]
	v_lshl_add_u64 v[232:233], s[60:61], 0, v[134:135]
	s_mov_b32 m0, s62
	s_nop 0
	global_load_lds_dwordx4 v[232:233], off
	v_mfma_f32_16x16x32_bf16 v[20:23], v[176:179], v[216:219], v[20:23]
	v_mfma_f32_16x16x32_bf16 v[16:19], v[186:189], v[216:219], v[16:19]
	v_mfma_f32_16x16x32_bf16 v[4:7], v[176:179], v[224:227], v[4:7]
	v_mfma_f32_16x16x32_bf16 v[0:3], v[186:189], v[224:227], v[0:3]
	s_setprio 0
	s_barrier
; #define PG8_STAGE(bufoff, gbase, voff) do { _Pragma("unroll") for (int _i = 0; _i < 2; ++_i) \
;         __builtin_amdgcn_global_load_lds((const unsigned*)((const char*)(gbase) + (voff)[_i]), (PG8_LAS unsigned*)(lds + (bufoff) + ldsw + _i * 8192), 16, 0, 0); } while (0)
; #define PG8_LDA(dst, b, h) do { _Pragma("unroll") for (int m = 0; m < 4; ++m) _Pragma("unroll") for (int k = 0; k < 2; ++k) dst[m][k] = *(const PG8_LAS bf16x8*)(lds + PG8_SA(b, h) + aoff + m * 2048 + k * 1024); } while (0)
; #define PG8_LDB(dst, b, h) do { _Pragma("unroll") for (int n = 0; n < 2; ++n) _Pragma("unroll") for (int k = 0; k < 2; ++k) dst[n][k] = *(const PG8_LAS bf16x8*)(lds + PG8_SB(b, h) + boff + n * 2048 + k * 1024); } while (0)
; #define PG8_MMA(ai, bj, At, Bt) do { __builtin_amdgcn_s_setprio(1); _Pragma("unroll") for (int m = 0; m < 4; ++m) _Pragma("unroll") for (int n = 0; n < 2; ++n) _Pragma("unroll") for (int k = 0; k < 2; ++k) \
;         acc[ai][bj][m][n] = __builtin_amdgcn_mfma_f32_16x16x32_bf16(Bt[n][k], At[m][k], acc[ai][bj][m][n], 0, 0, 0); __builtin_amdgcn_s_setprio(0); } while (0)
; #define PG8_WAIT_V(n) asm volatile("s_waitcnt vmcnt(" #n ")" ::: "memory")
; #define PG8_WAIT_L(n) asm volatile("s_waitcnt lgkmcnt(" #n ")" ::: "memory")
; #define PG8_BAR __builtin_amdgcn_s_barrier()
; #define PG8_SCHED __builtin_amdgcn_sched_barrier(0)
; template <class Epi, class Sched, bool ALIGN_EPI = false, bool SP2 = false>
; __device__ __forceinline__ void gemm_phase(PG8_LAS unsigned char* lds, const Gemm g, const Sched& S, const Epi& E) {
;     ...
;             PG8_LDB(B0, 1, 0); PG8_LDB(B1, 1, 1); PG8_SCHED; PG8_LDA(At, 1, 0); PG8_STAGE(PG8_SA(0, 1), a2 + hstep, voffA);
;             PG8_WAIT_V(8); PG8_WAIT_L(0); PG8_BAR; PG8_MMA(0, 0, At, B0); PG8_MMA(0, 1, At, B1); PG8_BAR; PG8_SCHED;
	s_add_i32 s3, 0, 0x18000
	v_add_u32_e32 v159, s3, v131
	s_add_i32 s33, 0, 0x1c000
	ds_read_b128 v[148:151], v159
	ds_read_b128 v[160:163], v159 offset:1024
	ds_read_b128 v[164:167], v159 offset:2048
	ds_read_b128 v[168:171], v159 offset:3072
	v_add_u32_e32 v159, s33, v131
	ds_read_b128 v[172:175], v159
	ds_read_b128 v[176:179], v159 offset:1024
	ds_read_b128 v[182:185], v159 offset:2048
	ds_read_b128 v[186:189], v159 offset:3072
	s_add_u32 s14, s60, 0x40000
	s_addc_u32 s15, s61, 0
	s_mov_b32 m0, s63
	v_lshl_add_u64 v[234:235], s[14:15], 0, v[138:139]
	ds_read_b128 v[190:193], v157 offset:32768
	ds_read_b128 v[194:197], v157 offset:33792
	ds_read_b128 v[198:201], v157 offset:34816
	ds_read_b128 v[208:211], v157 offset:35840
	ds_read_b128 v[212:215], v157 offset:36864
	ds_read_b128 v[216:219], v157 offset:37888
	ds_read_b128 v[220:223], v157 offset:38912
	ds_read_b128 v[224:227], v157 offset:39936
	global_load_lds_dwordx4 v[234:235], off
	v_lshl_add_u64 v[234:235], s[14:15], 0, v[134:135]
	s_mov_b32 m0, s64
	s_nop 0
	global_load_lds_dwordx4 v[234:235], off
	s_waitcnt vmcnt(8)
	s_waitcnt lgkmcnt(0)
	s_barrier
	s_setprio 1
	s_waitcnt lgkmcnt(0)
	v_mfma_f32_16x16x32_bf16 v[124:127], v[148:151], v[190:193], v[124:127]
	v_mfma_f32_16x16x32_bf16 v[120:123], v[164:167], v[190:193], v[120:123]
	v_mfma_f32_16x16x32_bf16 v[108:111], v[148:151], v[198:201], v[108:111]
	v_mfma_f32_16x16x32_bf16 v[104:107], v[164:167], v[198:201], v[104:107]
	v_mfma_f32_16x16x32_bf16 v[92:95], v[148:151], v[212:215], v[92:95]
	v_mfma_f32_16x16x32_bf16 v[88:91], v[164:167], v[212:215], v[88:91]
	v_mfma_f32_16x16x32_bf16 v[76:79], v[148:151], v[220:223], v[76:79]
	v_mfma_f32_16x16x32_bf16 v[72:75], v[164:167], v[220:223], v[72:75]
	v_mfma_f32_16x16x32_bf16 v[124:127], v[160:163], v[194:197], v[124:127]
	v_mfma_f32_16x16x32_bf16 v[120:123], v[168:171], v[194:197], v[120:123]
	v_mfma_f32_16x16x32_bf16 v[108:111], v[160:163], v[208:211], v[108:111]
	v_mfma_f32_16x16x32_bf16 v[104:107], v[168:171], v[208:211], v[104:107]
	v_mfma_f32_16x16x32_bf16 v[92:95], v[160:163], v[216:219], v[92:95]
	v_mfma_f32_16x16x32_bf16 v[88:91], v[168:171], v[216:219], v[88:91]
	v_mfma_f32_16x16x32_bf16 v[76:79], v[160:163], v[224:227], v[76:79]
	v_mfma_f32_16x16x32_bf16 v[72:75], v[168:171], v[224:227], v[72:75]
	s_setprio 0
	s_setprio 1
	v_mfma_f32_16x16x32_bf16 v[116:119], v[172:175], v[190:193], v[116:119]
	v_mfma_f32_16x16x32_bf16 v[112:115], v[182:185], v[190:193], v[112:115]
	v_mfma_f32_16x16x32_bf16 v[100:103], v[172:175], v[198:201], v[100:103]
	v_mfma_f32_16x16x32_bf16 v[96:99], v[182:185], v[198:201], v[96:99]
	v_mfma_f32_16x16x32_bf16 v[84:87], v[172:175], v[212:215], v[84:87]
	v_mfma_f32_16x16x32_bf16 v[80:83], v[182:185], v[212:215], v[80:83]
	v_mfma_f32_16x16x32_bf16 v[68:71], v[172:175], v[220:223], v[68:71]
	v_mfma_f32_16x16x32_bf16 v[64:67], v[182:185], v[220:223], v[64:67]
	v_mfma_f32_16x16x32_bf16 v[116:119], v[176:179], v[194:197], v[116:119]
	v_mfma_f32_16x16x32_bf16 v[112:115], v[186:189], v[194:197], v[112:115]
	v_mfma_f32_16x16x32_bf16 v[100:103], v[176:179], v[208:211], v[100:103]
	v_mfma_f32_16x16x32_bf16 v[96:99], v[186:189], v[208:211], v[96:99]
	v_mfma_f32_16x16x32_bf16 v[84:87], v[176:179], v[216:219], v[84:87]
	v_mfma_f32_16x16x32_bf16 v[80:83], v[186:189], v[216:219], v[80:83]
	v_mfma_f32_16x16x32_bf16 v[68:71], v[176:179], v[224:227], v[68:71]
	v_mfma_f32_16x16x32_bf16 v[64:67], v[186:189], v[224:227], v[64:67]
	s_setprio 0
	s_barrier
; #define PG8_STAGE(bufoff, gbase, voff) do { _Pragma("unroll") for (int _i = 0; _i < 2; ++_i) \
;         __builtin_amdgcn_global_load_lds((const unsigned*)((const char*)(gbase) + (voff)[_i]), (PG8_LAS unsigned*)(lds + (bufoff) + ldsw + _i * 8192), 16, 0, 0); } while (0)
; #define PG8_LDA(dst, b, h) do { _Pragma("unroll") for (int m = 0; m < 4; ++m) _Pragma("unroll") for (int k = 0; k < 2; ++k) dst[m][k] = *(const PG8_LAS bf16x8*)(lds + PG8_SA(b, h) + aoff + m * 2048 + k * 1024); } while (0)
; #define PG8_MMA(ai, bj, At, Bt) do { __builtin_amdgcn_s_setprio(1); _Pragma("unroll") for (int m = 0; m < 4; ++m) _Pragma("unroll") for (int n = 0; n < 2; ++n) _Pragma("unroll") for (int k = 0; k < 2; ++k) \
;         acc[ai][bj][m][n] = __builtin_amdgcn_mfma_f32_16x16x32_bf16(Bt[n][k], At[m][k], acc[ai][bj][m][n], 0, 0, 0); __builtin_amdgcn_s_setprio(0); } while (0)
; #define PG8_WAIT_V(n) asm volatile("s_waitcnt vmcnt(" #n ")" ::: "memory")
; #define PG8_WAIT_L(n) asm volatile("s_waitcnt lgkmcnt(" #n ")" ::: "memory")
; #define PG8_BAR __builtin_amdgcn_s_barrier()
; #define PG8_SCHED __builtin_amdgcn_sched_barrier(0)
; template <class Epi, class Sched, bool ALIGN_EPI = false, bool SP2 = false>
; __device__ __forceinline__ void gemm_phase(PG8_LAS unsigned char* lds, const Gemm g, const Sched& S, const Epi& E) {
;     ...
;         for (int t = 0; t < nt; t += 2) {
;     ...
;             PG8_LDA(At, 1, 1); PG8_STAGE(PG8_SB(1, 0), b3, voffB); PG8_STAGE(PG8_SB(1, 1), b3 + hstep, voffB); PG8_STAGE(PG8_SA(1, 0), a3, voffA);
;             PG8_WAIT_V(8); PG8_WAIT_L(0); PG8_BAR; PG8_MMA(1, 0, At, B0); PG8_MMA(1, 1, At, B1); PG8_BAR; PG8_SCHED;
	s_add_i32 s3, s3, s34
	v_lshl_add_u64 v[202:203], v[202:203], 0, s[38:39]
	s_mov_b32 m0, s3
	ds_read_b128 v[190:193], v157 offset:49152
	ds_read_b128 v[194:197], v157 offset:50176
	ds_read_b128 v[198:201], v157 offset:51200
	ds_read_b128 v[208:211], v157 offset:52224
	ds_read_b128 v[212:215], v157 offset:53248
	ds_read_b128 v[216:219], v157 offset:54272
	ds_read_b128 v[220:223], v157 offset:55296
	ds_read_b128 v[224:227], v157 offset:56320
	global_load_lds_dwordx4 v[202:203], off
	s_add_i32 m0, s3, 0x2000
	s_add_u32 s14, s58, 0x40080
	v_lshl_add_u64 v[202:203], v[228:229], 0, s[38:39]
	s_addc_u32 s15, s59, 0
	s_add_i32 s3, s33, s34
	global_load_lds_dwordx4 v[202:203], off
	v_lshl_add_u64 v[202:203], s[14:15], 0, v[136:137]
	s_mov_b32 m0, s3
	s_nop 0
	global_load_lds_dwordx4 v[202:203], off
	v_lshl_add_u64 v[202:203], s[14:15], 0, v[132:133]
	s_add_i32 m0, s3, 0x2000
	s_nop 0
	global_load_lds_dwordx4 v[202:203], off
	s_waitcnt vmcnt(6)
	s_waitcnt lgkmcnt(0)
	s_barrier
	s_setprio 1
	s_waitcnt lgkmcnt(0)
	v_mfma_f32_16x16x32_bf16 v[60:63], v[148:151], v[190:193], v[60:63]
	v_mfma_f32_16x16x32_bf16 v[56:59], v[164:167], v[190:193], v[56:59]
	v_mfma_f32_16x16x32_bf16 v[44:47], v[148:151], v[198:201], v[44:47]
	v_mfma_f32_16x16x32_bf16 v[40:43], v[164:167], v[198:201], v[40:43]
	v_mfma_f32_16x16x32_bf16 v[28:31], v[148:151], v[212:215], v[28:31]
	v_mfma_f32_16x16x32_bf16 v[24:27], v[164:167], v[212:215], v[24:27]
	v_mfma_f32_16x16x32_bf16 v[12:15], v[148:151], v[220:223], v[12:15]
	v_mfma_f32_16x16x32_bf16 v[8:11], v[164:167], v[220:223], v[8:11]
	v_mfma_f32_16x16x32_bf16 v[60:63], v[160:163], v[194:197], v[60:63]
	v_mfma_f32_16x16x32_bf16 v[56:59], v[168:171], v[194:197], v[56:59]
	v_mfma_f32_16x16x32_bf16 v[44:47], v[160:163], v[208:211], v[44:47]
	v_mfma_f32_16x16x32_bf16 v[40:43], v[168:171], v[208:211], v[40:43]
	v_lshl_add_u64 v[202:203], v[230:231], 0, s[38:39]
	s_mov_b32 m0, s66
	s_nop 0
	global_load_lds_dwordx4 v[202:203], off
	v_mfma_f32_16x16x32_bf16 v[28:31], v[160:163], v[216:219], v[28:31]
	v_mfma_f32_16x16x32_bf16 v[24:27], v[168:171], v[216:219], v[24:27]
	v_mfma_f32_16x16x32_bf16 v[12:15], v[160:163], v[224:227], v[12:15]
	v_mfma_f32_16x16x32_bf16 v[8:11], v[168:171], v[224:227], v[8:11]
	s_setprio 0
	s_setprio 1
	v_mfma_f32_16x16x32_bf16 v[52:55], v[172:175], v[190:193], v[52:55]
	v_mfma_f32_16x16x32_bf16 v[48:51], v[182:185], v[190:193], v[48:51]
	v_mfma_f32_16x16x32_bf16 v[36:39], v[172:175], v[198:201], v[36:39]
	v_mfma_f32_16x16x32_bf16 v[32:35], v[182:185], v[198:201], v[32:35]
	v_mfma_f32_16x16x32_bf16 v[20:23], v[172:175], v[212:215], v[20:23]
	v_mfma_f32_16x16x32_bf16 v[16:19], v[182:185], v[212:215], v[16:19]
	v_mfma_f32_16x16x32_bf16 v[4:7], v[172:175], v[220:223], v[4:7]
	v_mfma_f32_16x16x32_bf16 v[0:3], v[182:185], v[220:223], v[0:3]
	v_mfma_f32_16x16x32_bf16 v[52:55], v[176:179], v[194:197], v[52:55]
	v_mfma_f32_16x16x32_bf16 v[48:51], v[186:189], v[194:197], v[48:51]
	v_mfma_f32_16x16x32_bf16 v[36:39], v[176:179], v[208:211], v[36:39]
	v_mfma_f32_16x16x32_bf16 v[32:35], v[186:189], v[208:211], v[32:35]
	v_lshl_add_u64 v[202:203], v[232:233], 0, s[38:39]
	s_mov_b32 m0, s67
	s_nop 0
	global_load_lds_dwordx4 v[202:203], off
	v_mfma_f32_16x16x32_bf16 v[20:23], v[176:179], v[216:219], v[20:23]
	v_mfma_f32_16x16x32_bf16 v[16:19], v[186:189], v[216:219], v[16:19]
	v_mfma_f32_16x16x32_bf16 v[4:7], v[176:179], v[224:227], v[4:7]
	v_mfma_f32_16x16x32_bf16 v[0:3], v[186:189], v[224:227], v[0:3]
	s_setprio 0
	s_barrier
	s_add_i32 s86, s86, 2
	s_add_u32 s56, s56, 0x100
	s_addc_u32 s57, s57, 0
	s_add_u32 s84, s84, 0x100
	s_addc_u32 s85, s85, 0
	s_cmp_gt_u32 s86, 13
	s_cbranch_scc0 .LBB0_738
	s_and_b64 vcc, exec, s[44:45]
	s_cbranch_vccz .LBB0_741
	s_barrier

; #define PG8_STAGE(bufoff, gbase, voff) do { _Pragma("unroll") for (int _i = 0; _i < 2; ++_i) \
;         __builtin_amdgcn_global_load_lds((const unsigned*)((const char*)(gbase) + (voff)[_i]), (PG8_LAS unsigned*)(lds + (bufoff) + ldsw + _i * 8192), 16, 0, 0); } while (0)
; #define PG8_LDA(dst, b, h) do { _Pragma("unroll") for (int m = 0; m < 4; ++m) _Pragma("unroll") for (int k = 0; k < 2; ++k) dst[m][k] = *(const PG8_LAS bf16x8*)(lds + PG8_SA(b, h) + aoff + m * 2048 + k * 1024); } while (0)
; #define PG8_LDB(dst, b, h) do { _Pragma("unroll") for (int n = 0; n < 2; ++n) _Pragma("unroll") for (int k = 0; k < 2; ++k) dst[n][k] = *(const PG8_LAS bf16x8*)(lds + PG8_SB(b, h) + boff + n * 2048 + k * 1024); } while (0)
; #define PG8_WAIT_V(n) asm volatile("s_waitcnt vmcnt(" #n ")" ::: "memory")
; template <class Epi, class Sched, bool ALIGN_EPI = false, bool SP2 = false>
; __device__ __forceinline__ void gemm_phase(PG8_LAS unsigned char* lds, const Gemm g, const Sched& S, const Epi& E) {
;     ...
;         const bool has_next = S.next(ui + 1, nxt);
;         const char* nA = has_next ? (const char*)g.A + (size_t)nxt.pm * tstep : cA; const char* nB = has_next ? (const char*)g.Bt + (size_t)nxt.pn * tstep : cB;
;         for (int t = 0; t < nt; t += 2) {
;             const bool last = (t == nt - 2);
;             const char* a1 = cA + (size_t)(t + 1) * kstep;
;             const char* a2 = last ? nA : cA + (size_t)(t + 2) * kstep; const char* b2 = last ? nB : cB + (size_t)(t + 2) * kstep;
;             const char* a3 = a2 + kstep; const char* b3 = b2 + kstep;
;             if (last && has_next) S.a_ready(nxt);
;             if constexpr (SP2) {
;             PG8_LDB(B0, 0, 0); PG8_LDB(B1, 0, 1); PG8_SCHED; PG8_LDA(At, 0, 0); PG8_STAGE(PG8_SA(1, 1), a1 + hstep, voffA);
;             PG8_WAIT_V(8); PG8_WAIT_L(0); PG8_BAR; PG8_MMA(0, 0, At, B0); PG8_MMA(0, 1, At, B1); PG8_BAR; PG8_SCHED;
;             PG8_LDA(At, 0, 1); PG8_STAGE(PG8_SB(0, 0), b2, voffB); PG8_STAGE(PG8_SB(0, 1), b2 + hstep, voffB); PG8_STAGE(PG8_SA(0, 0), a2, voffA);
;     ...
; #pragma unroll
;         for (int a = 0; a < 2; ++a)
; #pragma unroll
;             for (int b = 0; b < 2; ++b)
; #pragma unroll
;                 for (int m = 0; m < 4; ++m)
; #pragma unroll
;                     for (int n = 0; n < 2; ++n) acc[a][b][m][n] = (f32x4){0.f, 0.f, 0.f, 0.f};
;         cur = nxt; cA = nA; cB = nB; ++ui;
.LBB0_872:
	s_ashr_i32 s49, s48, 31
	s_lshl_b64 s[50:51], s[48:49], 18
	s_add_u32 s50, s92, s50
	s_addc_u32 s51, s93, s51
	s_and_b64 s[52:53], s[10:11], exec
	s_cselect_b32 s49, s51, s59
	s_cselect_b32 s55, s50, s58
	s_ashr_i32 s45, s44, 31
	s_lshl_b64 s[52:53], s[44:45], 18
	s_add_u32 s52, s76, s52
	s_addc_u32 s53, s77, s53
	s_and_b64 s[62:63], s[10:11], exec
	s_cselect_b32 s45, s53, s61
	s_cselect_b32 s84, s52, s60
	s_add_u32 s58, s58, 0x20080
	s_addc_u32 s59, s59, 0
	s_add_u32 s85, s60, 0x100
	s_addc_u32 s86, s61, 0
	s_mov_b32 s87, -2
	s_waitcnt lgkmcnt(0)
	ds_read_b128 v[144:147], v151
	ds_read_b128 v[156:159], v151 offset:1024
	ds_read_b128 v[160:163], v151 offset:2048
	ds_read_b128 v[164:167], v151 offset:3072
	ds_read_b128 v[168:171], v152
	ds_read_b128 v[172:175], v152 offset:1024
	ds_read_b128 v[176:179], v152 offset:2048
	ds_read_b128 v[182:185], v152 offset:3072
	s_add_u32 s3, s58, 0xfffe0080
	s_addc_u32 s33, s59, -1
	s_cmp_eq_u32 s87, 4
	s_cselect_b32 s63, s49, s33
	s_cselect_b32 s62, s55, s3
	s_cselect_b32 s61, s45, s86
	s_cselect_b32 s60, s84, s85
	v_lshl_add_u64 v[202:203], s[58:59], 0, v[136:137]
	s_add_i32 m0, s15, 0xc000
	ds_read_b128 v[186:189], v153
	ds_read_b128 v[190:193], v153 offset:1024
	ds_read_b128 v[194:197], v153 offset:2048
	ds_read_b128 v[198:201], v153 offset:3072
	ds_read_b128 v[208:211], v153 offset:4096
	ds_read_b128 v[212:215], v153 offset:5120
	ds_read_b128 v[216:219], v153 offset:6144
	ds_read_b128 v[220:223], v153 offset:7168
	global_load_lds_dwordx4 v[202:203], off
	v_lshl_add_u64 v[202:203], s[58:59], 0, v[138:139]
	s_add_i32 m0, s15, 0xe000
	s_nop 0
	global_load_lds_dwordx4 v[202:203], off
	s_waitcnt vmcnt(8)
	s_waitcnt lgkmcnt(0)
	s_barrier
	s_setprio 1
	s_waitcnt lgkmcnt(0)
	v_mfma_f32_16x16x32_bf16 v[124:127], v[144:147], v[186:189], 0
	v_mfma_f32_16x16x32_bf16 v[120:123], v[160:163], v[186:189], 0
	v_mfma_f32_16x16x32_bf16 v[108:111], v[144:147], v[194:197], 0
	v_mfma_f32_16x16x32_bf16 v[104:107], v[160:163], v[194:197], 0
	v_mfma_f32_16x16x32_bf16 v[92:95], v[144:147], v[208:211], 0
	v_mfma_f32_16x16x32_bf16 v[88:91], v[160:163], v[208:211], 0
	v_mfma_f32_16x16x32_bf16 v[76:79], v[144:147], v[216:219], 0
	v_mfma_f32_16x16x32_bf16 v[72:75], v[160:163], v[216:219], 0
	v_mfma_f32_16x16x32_bf16 v[124:127], v[156:159], v[190:193], v[124:127]
	v_mfma_f32_16x16x32_bf16 v[120:123], v[164:167], v[190:193], v[120:123]
	v_mfma_f32_16x16x32_bf16 v[108:111], v[156:159], v[198:201], v[108:111]
	v_mfma_f32_16x16x32_bf16 v[104:107], v[164:167], v[198:201], v[104:107]
	v_mfma_f32_16x16x32_bf16 v[92:95], v[156:159], v[212:215], v[92:95]
	v_mfma_f32_16x16x32_bf16 v[88:91], v[164:167], v[212:215], v[88:91]
	v_mfma_f32_16x16x32_bf16 v[76:79], v[156:159], v[220:223], v[76:79]
	v_mfma_f32_16x16x32_bf16 v[72:75], v[164:167], v[220:223], v[72:75]
	s_setprio 0
	s_setprio 1
	v_mfma_f32_16x16x32_bf16 v[116:119], v[168:171], v[186:189], 0
	v_mfma_f32_16x16x32_bf16 v[112:115], v[176:179], v[186:189], 0
	v_mfma_f32_16x16x32_bf16 v[100:103], v[168:171], v[194:197], 0
	v_mfma_f32_16x16x32_bf16 v[96:99], v[176:179], v[194:197], 0
	v_mfma_f32_16x16x32_bf16 v[84:87], v[168:171], v[208:211], 0
	v_mfma_f32_16x16x32_bf16 v[80:83], v[176:179], v[208:211], 0
	v_mfma_f32_16x16x32_bf16 v[68:71], v[168:171], v[216:219], 0
	v_mfma_f32_16x16x32_bf16 v[64:67], v[176:179], v[216:219], 0
	v_mfma_f32_16x16x32_bf16 v[116:119], v[172:175], v[190:193], v[116:119]
	v_mfma_f32_16x16x32_bf16 v[112:115], v[182:185], v[190:193], v[112:115]
	v_mfma_f32_16x16x32_bf16 v[100:103], v[172:175], v[198:201], v[100:103]
	v_mfma_f32_16x16x32_bf16 v[96:99], v[182:185], v[198:201], v[96:99]
	v_mfma_f32_16x16x32_bf16 v[84:87], v[172:175], v[212:215], v[84:87]
	v_mfma_f32_16x16x32_bf16 v[80:83], v[182:185], v[212:215], v[80:83]
	v_mfma_f32_16x16x32_bf16 v[68:71], v[172:175], v[220:223], v[68:71]
	v_mfma_f32_16x16x32_bf16 v[64:67], v[182:185], v[220:223], v[64:67]
	s_setprio 0
	s_barrier
	s_add_i32 s3, s74, s14
	v_lshl_add_u64 v[202:203], s[60:61], 0, v[130:131]
	s_mov_b32 m0, s3
	ds_read_b128 v[186:189], v153 offset:16384
	ds_read_b128 v[190:193], v153 offset:17408
	ds_read_b128 v[194:197], v153 offset:18432
	ds_read_b128 v[198:201], v153 offset:19456
	ds_read_b128 v[208:211], v153 offset:20480
	ds_read_b128 v[212:215], v153 offset:21504
	ds_read_b128 v[216:219], v153 offset:22528
	ds_read_b128 v[220:223], v153 offset:23552
	global_load_lds_dwordx4 v[202:203], off
	s_add_i32 m0, s3, 0x2000
	s_add_u32 s78, s60, 0x20000
	v_lshl_add_u64 v[224:225], s[60:61], 0, v[134:135]
	s_addc_u32 s79, s61, 0
	s_add_i32 s3, s75, s14
	global_load_lds_dwordx4 v[224:225], off
	v_lshl_add_u64 v[226:227], s[78:79], 0, v[130:131]
	s_mov_b32 m0, s3
	global_load_lds_dwordx4 v[226:227], off
	v_lshl_add_u64 v[226:227], s[78:79], 0, v[134:135]
	s_add_i32 m0, s3, 0x2000
	s_nop 0
	global_load_lds_dwordx4 v[226:227], off
	s_waitcnt vmcnt(6)
	s_waitcnt lgkmcnt(0)
	s_barrier
; #define PG8_STAGE(bufoff, gbase, voff) do { _Pragma("unroll") for (int _i = 0; _i < 2; ++_i) \
;         __builtin_amdgcn_global_load_lds((const unsigned*)((const char*)(gbase) + (voff)[_i]), (PG8_LAS unsigned*)(lds + (bufoff) + ldsw + _i * 8192), 16, 0, 0); } while (0)
; #define PG8_LDA(dst, b, h) do { _Pragma("unroll") for (int m = 0; m < 4; ++m) _Pragma("unroll") for (int k = 0; k < 2; ++k) dst[m][k] = *(const PG8_LAS bf16x8*)(lds + PG8_SA(b, h) + aoff + m * 2048 + k * 1024); } while (0)
; #define PG8_LDB(dst, b, h) do { _Pragma("unroll") for (int n = 0; n < 2; ++n) _Pragma("unroll") for (int k = 0; k < 2; ++k) dst[n][k] = *(const PG8_LAS bf16x8*)(lds + PG8_SB(b, h) + boff + n * 2048 + k * 1024); } while (0)
; #define PG8_MMA(ai, bj, At, Bt) do { __builtin_amdgcn_s_setprio(1); _Pragma("unroll") for (int m = 0; m < 4; ++m) _Pragma("unroll") for (int n = 0; n < 2; ++n) _Pragma("unroll") for (int k = 0; k < 2; ++k) \
;         acc[ai][bj][m][n] = __builtin_amdgcn_mfma_f32_16x16x32_bf16(Bt[n][k], At[m][k], acc[ai][bj][m][n], 0, 0, 0); __builtin_amdgcn_s_setprio(0); } while (0)
; #define PG8_WAIT_V(n) asm volatile("s_waitcnt vmcnt(" #n ")" ::: "memory")
; #define PG8_WAIT_L(n) asm volatile("s_waitcnt lgkmcnt(" #n ")" ::: "memory")
; #define PG8_BAR __builtin_amdgcn_s_barrier()
; #define PG8_SCHED __builtin_amdgcn_sched_barrier(0)
; template <class Epi, class Sched, bool ALIGN_EPI = false, bool SP2 = false>
; __device__ __forceinline__ void gemm_phase(PG8_LAS unsigned char* lds, const Gemm g, const Sched& S, const Epi& E) {
;     ...
;             PG8_LDA(At, 0, 1); PG8_STAGE(PG8_SB(0, 0), b2, voffB); PG8_STAGE(PG8_SB(0, 1), b2 + hstep, voffB); PG8_STAGE(PG8_SA(0, 0), a2, voffA);
;             PG8_WAIT_V(8); PG8_WAIT_L(0); PG8_BAR; PG8_MMA(1, 0, At, B0); PG8_MMA(1, 1, At, B1); PG8_BAR; PG8_SCHED;
;             PG8_LDB(B0, 1, 0); PG8_LDB(B1, 1, 1); PG8_SCHED; PG8_LDA(At, 1, 0); PG8_STAGE(PG8_SA(0, 1), a2 + hstep, voffA);
;             PG8_WAIT_V(8); PG8_WAIT_L(0); PG8_BAR; PG8_MMA(0, 0, At, B0); PG8_MMA(0, 1, At, B1); PG8_BAR; PG8_SCHED;
	s_setprio 1
	s_waitcnt lgkmcnt(0)
	v_mfma_f32_16x16x32_bf16 v[60:63], v[144:147], v[186:189], 0
	v_mfma_f32_16x16x32_bf16 v[56:59], v[160:163], v[186:189], 0
	v_mfma_f32_16x16x32_bf16 v[44:47], v[144:147], v[194:197], 0
	v_mfma_f32_16x16x32_bf16 v[40:43], v[160:163], v[194:197], 0
	v_mfma_f32_16x16x32_bf16 v[28:31], v[144:147], v[208:211], 0
	v_mfma_f32_16x16x32_bf16 v[24:27], v[160:163], v[208:211], 0
	v_mfma_f32_16x16x32_bf16 v[12:15], v[144:147], v[216:219], 0
	v_mfma_f32_16x16x32_bf16 v[8:11], v[160:163], v[216:219], 0
	v_mfma_f32_16x16x32_bf16 v[60:63], v[156:159], v[190:193], v[60:63]
	v_mfma_f32_16x16x32_bf16 v[56:59], v[164:167], v[190:193], v[56:59]
	v_mfma_f32_16x16x32_bf16 v[44:47], v[156:159], v[198:201], v[44:47]
	v_mfma_f32_16x16x32_bf16 v[40:43], v[164:167], v[198:201], v[40:43]
	v_lshl_add_u64 v[226:227], s[62:63], 0, v[128:129]
	s_mov_b32 m0, s15
	s_nop 0
	global_load_lds_dwordx4 v[226:227], off
	v_mfma_f32_16x16x32_bf16 v[28:31], v[156:159], v[212:215], v[28:31]
	v_mfma_f32_16x16x32_bf16 v[24:27], v[164:167], v[212:215], v[24:27]
	v_mfma_f32_16x16x32_bf16 v[12:15], v[156:159], v[220:223], v[12:15]
	v_mfma_f32_16x16x32_bf16 v[8:11], v[164:167], v[220:223], v[8:11]
	s_setprio 0
	s_setprio 1
	v_mfma_f32_16x16x32_bf16 v[52:55], v[168:171], v[186:189], 0
	v_mfma_f32_16x16x32_bf16 v[48:51], v[176:179], v[186:189], 0
	v_mfma_f32_16x16x32_bf16 v[36:39], v[168:171], v[194:197], 0
	v_mfma_f32_16x16x32_bf16 v[32:35], v[176:179], v[194:197], 0
	v_mfma_f32_16x16x32_bf16 v[20:23], v[168:171], v[208:211], 0
	v_mfma_f32_16x16x32_bf16 v[16:19], v[176:179], v[208:211], 0
	v_mfma_f32_16x16x32_bf16 v[4:7], v[168:171], v[216:219], 0
	v_mfma_f32_16x16x32_bf16 v[0:3], v[176:179], v[216:219], 0
	v_mfma_f32_16x16x32_bf16 v[52:55], v[172:175], v[190:193], v[52:55]
	v_mfma_f32_16x16x32_bf16 v[48:51], v[182:185], v[190:193], v[48:51]
	v_mfma_f32_16x16x32_bf16 v[36:39], v[172:175], v[198:201], v[36:39]
	v_mfma_f32_16x16x32_bf16 v[32:35], v[182:185], v[198:201], v[32:35]
	v_lshl_add_u64 v[228:229], s[62:63], 0, v[132:133]
	s_mov_b32 m0, s34
	s_nop 0
	global_load_lds_dwordx4 v[228:229], off
	v_mfma_f32_16x16x32_bf16 v[20:23], v[172:175], v[212:215], v[20:23]
	v_mfma_f32_16x16x32_bf16 v[16:19], v[182:185], v[212:215], v[16:19]
	v_mfma_f32_16x16x32_bf16 v[4:7], v[172:175], v[220:223], v[4:7]
	v_mfma_f32_16x16x32_bf16 v[0:3], v[182:185], v[220:223], v[0:3]
	s_setprio 0
	s_barrier
	s_add_i32 s3, 0, 0x18000
	v_add_u32_e32 v155, s3, v149
	s_add_i32 s33, 0, 0x1c000
	ds_read_b128 v[144:147], v155
	ds_read_b128 v[156:159], v155 offset:1024
	ds_read_b128 v[160:163], v155 offset:2048
	ds_read_b128 v[164:167], v155 offset:3072
	v_add_u32_e32 v155, s33, v149
	ds_read_b128 v[168:171], v155
	ds_read_b128 v[172:175], v155 offset:1024
	ds_read_b128 v[176:179], v155 offset:2048
	ds_read_b128 v[182:185], v155 offset:3072
	s_add_u32 s62, s62, 0x20000
	s_addc_u32 s63, s63, 0
	s_mov_b32 m0, s57
	v_lshl_add_u64 v[230:231], s[62:63], 0, v[128:129]
	ds_read_b128 v[186:189], v153 offset:32768
	ds_read_b128 v[190:193], v153 offset:33792
	ds_read_b128 v[194:197], v153 offset:34816
	ds_read_b128 v[198:201], v153 offset:35840
	ds_read_b128 v[208:211], v153 offset:36864
	ds_read_b128 v[212:215], v153 offset:37888
	ds_read_b128 v[216:219], v153 offset:38912
	ds_read_b128 v[220:223], v153 offset:39936
	global_load_lds_dwordx4 v[230:231], off
	v_lshl_add_u64 v[230:231], s[62:63], 0, v[132:133]
	s_mov_b32 m0, s64
	s_nop 0
	global_load_lds_dwordx4 v[230:231], off
	s_waitcnt vmcnt(8)
	s_waitcnt lgkmcnt(0)
	s_barrier
	s_setprio 1
	s_waitcnt lgkmcnt(0)
	v_mfma_f32_16x16x32_bf16 v[124:127], v[144:147], v[186:189], v[124:127]
	v_mfma_f32_16x16x32_bf16 v[120:123], v[160:163], v[186:189], v[120:123]
	v_mfma_f32_16x16x32_bf16 v[108:111], v[144:147], v[194:197], v[108:111]
	v_mfma_f32_16x16x32_bf16 v[104:107], v[160:163], v[194:197], v[104:107]
	v_mfma_f32_16x16x32_bf16 v[92:95], v[144:147], v[208:211], v[92:95]
	v_mfma_f32_16x16x32_bf16 v[88:91], v[160:163], v[208:211], v[88:91]
	v_mfma_f32_16x16x32_bf16 v[76:79], v[144:147], v[216:219], v[76:79]
	v_mfma_f32_16x16x32_bf16 v[72:75], v[160:163], v[216:219], v[72:75]
	v_mfma_f32_16x16x32_bf16 v[124:127], v[156:159], v[190:193], v[124:127]
	v_mfma_f32_16x16x32_bf16 v[120:123], v[164:167], v[190:193], v[120:123]
	v_mfma_f32_16x16x32_bf16 v[108:111], v[156:159], v[198:201], v[108:111]
	v_mfma_f32_16x16x32_bf16 v[104:107], v[164:167], v[198:201], v[104:107]
	v_mfma_f32_16x16x32_bf16 v[92:95], v[156:159], v[212:215], v[92:95]
	v_mfma_f32_16x16x32_bf16 v[88:91], v[164:167], v[212:215], v[88:91]
	v_mfma_f32_16x16x32_bf16 v[76:79], v[156:159], v[220:223], v[76:79]
	v_mfma_f32_16x16x32_bf16 v[72:75], v[164:167], v[220:223], v[72:75]
	s_setprio 0
	s_setprio 1
	v_mfma_f32_16x16x32_bf16 v[116:119], v[168:171], v[186:189], v[116:119]
	v_mfma_f32_16x16x32_bf16 v[112:115], v[176:179], v[186:189], v[112:115]
	v_mfma_f32_16x16x32_bf16 v[100:103], v[168:171], v[194:197], v[100:103]
	v_mfma_f32_16x16x32_bf16 v[96:99], v[176:179], v[194:197], v[96:99]
	v_mfma_f32_16x16x32_bf16 v[84:87], v[168:171], v[208:211], v[84:87]
	v_mfma_f32_16x16x32_bf16 v[80:83], v[176:179], v[208:211], v[80:83]
	v_mfma_f32_16x16x32_bf16 v[68:71], v[168:171], v[216:219], v[68:71]
	v_mfma_f32_16x16x32_bf16 v[64:67], v[176:179], v[216:219], v[64:67]
	v_mfma_f32_16x16x32_bf16 v[116:119], v[172:175], v[190:193], v[116:119]
	v_mfma_f32_16x16x32_bf16 v[112:115], v[182:185], v[190:193], v[112:115]
	v_mfma_f32_16x16x32_bf16 v[100:103], v[172:175], v[198:201], v[100:103]
	v_mfma_f32_16x16x32_bf16 v[96:99], v[182:185], v[198:201], v[96:99]
	v_mfma_f32_16x16x32_bf16 v[84:87], v[172:175], v[212:215], v[84:87]
	v_mfma_f32_16x16x32_bf16 v[80:83], v[182:185], v[212:215], v[80:83]
	v_mfma_f32_16x16x32_bf16 v[68:71], v[172:175], v[220:223], v[68:71]
	v_mfma_f32_16x16x32_bf16 v[64:67], v[182:185], v[220:223], v[64:67]
	s_setprio 0
	s_barrier
; #define PG8_STAGE(bufoff, gbase, voff) do { _Pragma("unroll") for (int _i = 0; _i < 2; ++_i) \
;         __builtin_amdgcn_global_load_lds((const unsigned*)((const char*)(gbase) + (voff)[_i]), (PG8_LAS unsigned*)(lds + (bufoff) + ldsw + _i * 8192), 16, 0, 0); } while (0)
; #define PG8_LDA(dst, b, h) do { _Pragma("unroll") for (int m = 0; m < 4; ++m) _Pragma("unroll") for (int k = 0; k < 2; ++k) dst[m][k] = *(const PG8_LAS bf16x8*)(lds + PG8_SA(b, h) + aoff + m * 2048 + k * 1024); } while (0)
; #define PG8_LDB(dst, b, h) do { _Pragma("unroll") for (int n = 0; n < 2; ++n) _Pragma("unroll") for (int k = 0; k < 2; ++k) dst[n][k] = *(const PG8_LAS bf16x8*)(lds + PG8_SB(b, h) + boff + n * 2048 + k * 1024); } while (0)
; #define PG8_MMA(ai, bj, At, Bt) do { __builtin_amdgcn_s_setprio(1); _Pragma("unroll") for (int m = 0; m < 4; ++m) _Pragma("unroll") for (int n = 0; n < 2; ++n) _Pragma("unroll") for (int k = 0; k < 2; ++k) \
;         acc[ai][bj][m][n] = __builtin_amdgcn_mfma_f32_16x16x32_bf16(Bt[n][k], At[m][k], acc[ai][bj][m][n], 0, 0, 0); __builtin_amdgcn_s_setprio(0); } while (0)
; #define PG8_WAIT_V(n) asm volatile("s_waitcnt vmcnt(" #n ")" ::: "memory")
; #define PG8_WAIT_L(n) asm volatile("s_waitcnt lgkmcnt(" #n ")" ::: "memory")
; #define PG8_BAR __builtin_amdgcn_s_barrier()
; #define PG8_SCHED __builtin_amdgcn_sched_barrier(0)
; template <class Epi, class Sched, bool ALIGN_EPI = false, bool SP2 = false>
; __device__ __forceinline__ void gemm_phase(PG8_LAS unsigned char* lds, const Gemm g, const Sched& S, const Epi& E) {
;     ...
;         for (int t = 0; t < nt; t += 2) {
;             const bool last = (t == nt - 2);
;             const char* a1 = cA + (size_t)(t + 1) * kstep;
;             const char* a2 = last ? nA : cA + (size_t)(t + 2) * kstep; const char* b2 = last ? nB : cB + (size_t)(t + 2) * kstep;
;             const char* a3 = a2 + kstep; const char* b3 = b2 + kstep;
;             if (last && has_next) S.a_ready(nxt);
;             if constexpr (SP2) {
;             PG8_LDB(B0, 0, 0); PG8_LDB(B1, 0, 1); PG8_SCHED; PG8_LDA(At, 0, 0); PG8_STAGE(PG8_SA(1, 1), a1 + hstep, voffA);
;     ...
;             PG8_LDA(At, 1, 1); PG8_STAGE(PG8_SB(1, 0), b3, voffB); PG8_STAGE(PG8_SB(1, 1), b3 + hstep, voffB); PG8_STAGE(PG8_SA(1, 0), a3, voffA);
;             PG8_WAIT_V(8); PG8_WAIT_L(0); PG8_BAR; PG8_MMA(1, 0, At, B0); PG8_MMA(1, 1, At, B1); PG8_BAR; PG8_SCHED;
	s_add_i32 s3, s3, s14
	v_lshl_add_u64 v[202:203], v[202:203], 0, s[38:39]
	s_mov_b32 m0, s3
	ds_read_b128 v[186:189], v153 offset:49152
	ds_read_b128 v[190:193], v153 offset:50176
	ds_read_b128 v[194:197], v153 offset:51200
	ds_read_b128 v[198:201], v153 offset:52224
	ds_read_b128 v[208:211], v153 offset:53248
	ds_read_b128 v[212:215], v153 offset:54272
	ds_read_b128 v[216:219], v153 offset:55296
	ds_read_b128 v[220:223], v153 offset:56320
	global_load_lds_dwordx4 v[202:203], off
	s_add_i32 m0, s3, 0x2000
	s_add_u32 s60, s60, 0x20080
	v_lshl_add_u64 v[202:203], v[224:225], 0, s[38:39]
	s_addc_u32 s61, s61, 0
	s_add_i32 s3, s33, s14
	global_load_lds_dwordx4 v[202:203], off
	v_lshl_add_u64 v[202:203], s[60:61], 0, v[130:131]
	s_mov_b32 m0, s3
	s_nop 0
	global_load_lds_dwordx4 v[202:203], off
	v_lshl_add_u64 v[202:203], s[60:61], 0, v[134:135]
	s_add_i32 m0, s3, 0x2000
	s_nop 0
	global_load_lds_dwordx4 v[202:203], off
	s_waitcnt vmcnt(6)
	s_waitcnt lgkmcnt(0)
	s_barrier
	s_setprio 1
	s_waitcnt lgkmcnt(0)
	v_mfma_f32_16x16x32_bf16 v[60:63], v[144:147], v[186:189], v[60:63]
	v_mfma_f32_16x16x32_bf16 v[56:59], v[160:163], v[186:189], v[56:59]
	v_mfma_f32_16x16x32_bf16 v[44:47], v[144:147], v[194:197], v[44:47]
	v_mfma_f32_16x16x32_bf16 v[40:43], v[160:163], v[194:197], v[40:43]
	v_mfma_f32_16x16x32_bf16 v[28:31], v[144:147], v[208:211], v[28:31]
	v_mfma_f32_16x16x32_bf16 v[24:27], v[160:163], v[208:211], v[24:27]
	v_mfma_f32_16x16x32_bf16 v[12:15], v[144:147], v[216:219], v[12:15]
	v_mfma_f32_16x16x32_bf16 v[8:11], v[160:163], v[216:219], v[8:11]
	v_mfma_f32_16x16x32_bf16 v[60:63], v[156:159], v[190:193], v[60:63]
	v_mfma_f32_16x16x32_bf16 v[56:59], v[164:167], v[190:193], v[56:59]
	v_mfma_f32_16x16x32_bf16 v[44:47], v[156:159], v[198:201], v[44:47]
	v_mfma_f32_16x16x32_bf16 v[40:43], v[164:167], v[198:201], v[40:43]
	v_lshl_add_u64 v[202:203], v[226:227], 0, s[38:39]
	s_mov_b32 m0, s66
	s_nop 0
	global_load_lds_dwordx4 v[202:203], off
	v_mfma_f32_16x16x32_bf16 v[28:31], v[156:159], v[212:215], v[28:31]
	v_mfma_f32_16x16x32_bf16 v[24:27], v[164:167], v[212:215], v[24:27]
	v_mfma_f32_16x16x32_bf16 v[12:15], v[156:159], v[220:223], v[12:15]
	v_mfma_f32_16x16x32_bf16 v[8:11], v[164:167], v[220:223], v[8:11]
	s_setprio 0
	s_setprio 1
	v_mfma_f32_16x16x32_bf16 v[52:55], v[168:171], v[186:189], v[52:55]
	v_mfma_f32_16x16x32_bf16 v[48:51], v[176:179], v[186:189], v[48:51]
	v_mfma_f32_16x16x32_bf16 v[36:39], v[168:171], v[194:197], v[36:39]
	v_mfma_f32_16x16x32_bf16 v[32:35], v[176:179], v[194:197], v[32:35]
	v_mfma_f32_16x16x32_bf16 v[20:23], v[168:171], v[208:211], v[20:23]
	v_mfma_f32_16x16x32_bf16 v[16:19], v[176:179], v[208:211], v[16:19]
	v_mfma_f32_16x16x32_bf16 v[4:7], v[168:171], v[216:219], v[4:7]
	v_mfma_f32_16x16x32_bf16 v[0:3], v[176:179], v[216:219], v[0:3]
	v_mfma_f32_16x16x32_bf16 v[52:55], v[172:175], v[190:193], v[52:55]
	v_mfma_f32_16x16x32_bf16 v[48:51], v[182:185], v[190:193], v[48:51]
	v_mfma_f32_16x16x32_bf16 v[36:39], v[172:175], v[198:201], v[36:39]
	v_mfma_f32_16x16x32_bf16 v[32:35], v[182:185], v[198:201], v[32:35]
	v_lshl_add_u64 v[202:203], v[228:229], 0, s[38:39]
	s_mov_b32 m0, s67
	s_nop 0
	global_load_lds_dwordx4 v[202:203], off
	v_mfma_f32_16x16x32_bf16 v[20:23], v[172:175], v[212:215], v[20:23]
	v_mfma_f32_16x16x32_bf16 v[16:19], v[182:185], v[212:215], v[16:19]
	v_mfma_f32_16x16x32_bf16 v[4:7], v[172:175], v[220:223], v[4:7]
	v_mfma_f32_16x16x32_bf16 v[0:3], v[182:185], v[220:223], v[0:3]
	s_setprio 0
	s_barrier
	s_add_i32 s87, s87, 2
	s_add_u32 s58, s58, 0x100
	s_addc_u32 s59, s59, 0
	s_add_u32 s85, s85, 0x100
	s_addc_u32 s86, s86, 0
.LBB0_873:
	ds_read_b128 v[144:147], v151
	ds_read_b128 v[156:159], v151 offset:1024
	ds_read_b128 v[160:163], v151 offset:2048
	ds_read_b128 v[164:167], v151 offset:3072
	ds_read_b128 v[168:171], v152
	ds_read_b128 v[172:175], v152 offset:1024
	ds_read_b128 v[176:179], v152 offset:2048
	ds_read_b128 v[182:185], v152 offset:3072
	s_add_u32 s3, s58, 0xfffe0080
	s_addc_u32 s33, s59, -1
	s_cmp_eq_u32 s87, 4
	s_cselect_b32 s63, s49, s33
	s_cselect_b32 s62, s55, s3
	s_cselect_b32 s61, s45, s86
	s_cselect_b32 s60, s84, s85
	v_lshl_add_u64 v[202:203], s[58:59], 0, v[136:137]
	s_add_i32 m0, s15, 0xc000
	ds_read_b128 v[186:189], v153
	ds_read_b128 v[190:193], v153 offset:1024
	ds_read_b128 v[194:197], v153 offset:2048
	ds_read_b128 v[198:201], v153 offset:3072
	ds_read_b128 v[208:211], v153 offset:4096
	ds_read_b128 v[212:215], v153 offset:5120
	ds_read_b128 v[216:219], v153 offset:6144
	ds_read_b128 v[220:223], v153 offset:7168
	global_load_lds_dwordx4 v[202:203], off
	v_lshl_add_u64 v[202:203], s[58:59], 0, v[138:139]
	s_add_i32 m0, s15, 0xe000
	s_nop 0
	global_load_lds_dwordx4 v[202:203], off
	s_waitcnt vmcnt(8)
	s_waitcnt lgkmcnt(0)
	s_barrier
; #define PG8_STAGE(bufoff, gbase, voff) do { _Pragma("unroll") for (int _i = 0; _i < 2; ++_i) \
;         __builtin_amdgcn_global_load_lds((const unsigned*)((const char*)(gbase) + (voff)[_i]), (PG8_LAS unsigned*)(lds + (bufoff) + ldsw + _i * 8192), 16, 0, 0); } while (0)
; #define PG8_LDA(dst, b, h) do { _Pragma("unroll") for (int m = 0; m < 4; ++m) _Pragma("unroll") for (int k = 0; k < 2; ++k) dst[m][k] = *(const PG8_LAS bf16x8*)(lds + PG8_SA(b, h) + aoff + m * 2048 + k * 1024); } while (0)
; #define PG8_LDB(dst, b, h) do { _Pragma("unroll") for (int n = 0; n < 2; ++n) _Pragma("unroll") for (int k = 0; k < 2; ++k) dst[n][k] = *(const PG8_LAS bf16x8*)(lds + PG8_SB(b, h) + boff + n * 2048 + k * 1024); } while (0)
; #define PG8_MMA(ai, bj, At, Bt) do { __builtin_amdgcn_s_setprio(1); _Pragma("unroll") for (int m = 0; m < 4; ++m) _Pragma("unroll") for (int n = 0; n < 2; ++n) _Pragma("unroll") for (int k = 0; k < 2; ++k) \
;         acc[ai][bj][m][n] = __builtin_amdgcn_mfma_f32_16x16x32_bf16(Bt[n][k], At[m][k], acc[ai][bj][m][n], 0, 0, 0); __builtin_amdgcn_s_setprio(0); } while (0)
; #define PG8_WAIT_V(n) asm volatile("s_waitcnt vmcnt(" #n ")" ::: "memory")
; #define PG8_WAIT_L(n) asm volatile("s_waitcnt lgkmcnt(" #n ")" ::: "memory")
; #define PG8_BAR __builtin_amdgcn_s_barrier()
; #define PG8_SCHED __builtin_amdgcn_sched_barrier(0)
; template <class Epi, class Sched, bool ALIGN_EPI = false, bool SP2 = false>
; __device__ __forceinline__ void gemm_phase(PG8_LAS unsigned char* lds, const Gemm g, const Sched& S, const Epi& E) {
;     ...
;             PG8_WAIT_V(8); PG8_WAIT_L(0); PG8_BAR; PG8_MMA(0, 0, At, B0); PG8_MMA(0, 1, At, B1); PG8_BAR; PG8_SCHED;
;             PG8_LDA(At, 0, 1); PG8_STAGE(PG8_SB(0, 0), b2, voffB); PG8_STAGE(PG8_SB(0, 1), b2 + hstep, voffB); PG8_STAGE(PG8_SA(0, 0), a2, voffA);
;             PG8_WAIT_V(8); PG8_WAIT_L(0); PG8_BAR; PG8_MMA(1, 0, At, B0); PG8_MMA(1, 1, At, B1); PG8_BAR; PG8_SCHED;
;             PG8_LDB(B0, 1, 0); PG8_LDB(B1, 1, 1); PG8_SCHED; PG8_LDA(At, 1, 0); PG8_STAGE(PG8_SA(0, 1), a2 + hstep, voffA);
	s_setprio 1
	s_waitcnt lgkmcnt(0)
	v_mfma_f32_16x16x32_bf16 v[124:127], v[144:147], v[186:189], v[124:127]
	v_mfma_f32_16x16x32_bf16 v[120:123], v[160:163], v[186:189], v[120:123]
	v_mfma_f32_16x16x32_bf16 v[108:111], v[144:147], v[194:197], v[108:111]
	v_mfma_f32_16x16x32_bf16 v[104:107], v[160:163], v[194:197], v[104:107]
	v_mfma_f32_16x16x32_bf16 v[92:95], v[144:147], v[208:211], v[92:95]
	v_mfma_f32_16x16x32_bf16 v[88:91], v[160:163], v[208:211], v[88:91]
	v_mfma_f32_16x16x32_bf16 v[76:79], v[144:147], v[216:219], v[76:79]
	v_mfma_f32_16x16x32_bf16 v[72:75], v[160:163], v[216:219], v[72:75]
	v_mfma_f32_16x16x32_bf16 v[124:127], v[156:159], v[190:193], v[124:127]
	v_mfma_f32_16x16x32_bf16 v[120:123], v[164:167], v[190:193], v[120:123]
	v_mfma_f32_16x16x32_bf16 v[108:111], v[156:159], v[198:201], v[108:111]
	v_mfma_f32_16x16x32_bf16 v[104:107], v[164:167], v[198:201], v[104:107]
	v_mfma_f32_16x16x32_bf16 v[92:95], v[156:159], v[212:215], v[92:95]
	v_mfma_f32_16x16x32_bf16 v[88:91], v[164:167], v[212:215], v[88:91]
	v_mfma_f32_16x16x32_bf16 v[76:79], v[156:159], v[220:223], v[76:79]
	v_mfma_f32_16x16x32_bf16 v[72:75], v[164:167], v[220:223], v[72:75]
	s_setprio 0
	s_setprio 1
	v_mfma_f32_16x16x32_bf16 v[116:119], v[168:171], v[186:189], v[116:119]
	v_mfma_f32_16x16x32_bf16 v[112:115], v[176:179], v[186:189], v[112:115]
	v_mfma_f32_16x16x32_bf16 v[100:103], v[168:171], v[194:197], v[100:103]
	v_mfma_f32_16x16x32_bf16 v[96:99], v[176:179], v[194:197], v[96:99]
	v_mfma_f32_16x16x32_bf16 v[84:87], v[168:171], v[208:211], v[84:87]
	v_mfma_f32_16x16x32_bf16 v[80:83], v[176:179], v[208:211], v[80:83]
	v_mfma_f32_16x16x32_bf16 v[68:71], v[168:171], v[216:219], v[68:71]
	v_mfma_f32_16x16x32_bf16 v[64:67], v[176:179], v[216:219], v[64:67]
	v_mfma_f32_16x16x32_bf16 v[116:119], v[172:175], v[190:193], v[116:119]
	v_mfma_f32_16x16x32_bf16 v[112:115], v[182:185], v[190:193], v[112:115]
	v_mfma_f32_16x16x32_bf16 v[100:103], v[172:175], v[198:201], v[100:103]
	v_mfma_f32_16x16x32_bf16 v[96:99], v[182:185], v[198:201], v[96:99]
	v_mfma_f32_16x16x32_bf16 v[84:87], v[172:175], v[212:215], v[84:87]
	v_mfma_f32_16x16x32_bf16 v[80:83], v[182:185], v[212:215], v[80:83]
	v_mfma_f32_16x16x32_bf16 v[68:71], v[172:175], v[220:223], v[68:71]
	v_mfma_f32_16x16x32_bf16 v[64:67], v[182:185], v[220:223], v[64:67]
	s_setprio 0
	s_barrier
	s_add_i32 s3, s74, s14
	v_lshl_add_u64 v[202:203], s[60:61], 0, v[130:131]
	s_mov_b32 m0, s3
	ds_read_b128 v[186:189], v153 offset:16384
	ds_read_b128 v[190:193], v153 offset:17408
	ds_read_b128 v[194:197], v153 offset:18432
	ds_read_b128 v[198:201], v153 offset:19456
	ds_read_b128 v[208:211], v153 offset:20480
	ds_read_b128 v[212:215], v153 offset:21504
	ds_read_b128 v[216:219], v153 offset:22528
	ds_read_b128 v[220:223], v153 offset:23552
	global_load_lds_dwordx4 v[202:203], off
	s_add_i32 m0, s3, 0x2000
	s_add_u32 s78, s60, 0x20000
	v_lshl_add_u64 v[224:225], s[60:61], 0, v[134:135]
	s_addc_u32 s79, s61, 0
	s_add_i32 s3, s75, s14
	global_load_lds_dwordx4 v[224:225], off
	v_lshl_add_u64 v[226:227], s[78:79], 0, v[130:131]
	s_mov_b32 m0, s3
	global_load_lds_dwordx4 v[226:227], off
	v_lshl_add_u64 v[226:227], s[78:79], 0, v[134:135]
	s_add_i32 m0, s3, 0x2000
	s_nop 0
	global_load_lds_dwordx4 v[226:227], off
	s_waitcnt vmcnt(6)
	s_waitcnt lgkmcnt(0)
	s_barrier
	s_setprio 1
	s_waitcnt lgkmcnt(0)
	v_mfma_f32_16x16x32_bf16 v[60:63], v[144:147], v[186:189], v[60:63]
	v_mfma_f32_16x16x32_bf16 v[56:59], v[160:163], v[186:189], v[56:59]
	v_mfma_f32_16x16x32_bf16 v[44:47], v[144:147], v[194:197], v[44:47]
	v_mfma_f32_16x16x32_bf16 v[40:43], v[160:163], v[194:197], v[40:43]
	v_mfma_f32_16x16x32_bf16 v[28:31], v[144:147], v[208:211], v[28:31]
	v_mfma_f32_16x16x32_bf16 v[24:27], v[160:163], v[208:211], v[24:27]
	v_mfma_f32_16x16x32_bf16 v[12:15], v[144:147], v[216:219], v[12:15]
	v_mfma_f32_16x16x32_bf16 v[8:11], v[160:163], v[216:219], v[8:11]
	v_mfma_f32_16x16x32_bf16 v[60:63], v[156:159], v[190:193], v[60:63]
	v_mfma_f32_16x16x32_bf16 v[56:59], v[164:167], v[190:193], v[56:59]
	v_mfma_f32_16x16x32_bf16 v[44:47], v[156:159], v[198:201], v[44:47]
	v_mfma_f32_16x16x32_bf16 v[40:43], v[164:167], v[198:201], v[40:43]
	v_lshl_add_u64 v[226:227], s[62:63], 0, v[128:129]
	s_mov_b32 m0, s15
	s_nop 0
	global_load_lds_dwordx4 v[226:227], off
	v_mfma_f32_16x16x32_bf16 v[28:31], v[156:159], v[212:215], v[28:31]
	v_mfma_f32_16x16x32_bf16 v[24:27], v[164:167], v[212:215], v[24:27]
	v_mfma_f32_16x16x32_bf16 v[12:15], v[156:159], v[220:223], v[12:15]
	v_mfma_f32_16x16x32_bf16 v[8:11], v[164:167], v[220:223], v[8:11]
	s_setprio 0
	s_setprio 1
	v_mfma_f32_16x16x32_bf16 v[52:55], v[168:171], v[186:189], v[52:55]
	v_mfma_f32_16x16x32_bf16 v[48:51], v[176:179], v[186:189], v[48:51]
	v_mfma_f32_16x16x32_bf16 v[36:39], v[168:171], v[194:197], v[36:39]
	v_mfma_f32_16x16x32_bf16 v[32:35], v[176:179], v[194:197], v[32:35]
	v_mfma_f32_16x16x32_bf16 v[20:23], v[168:171], v[208:211], v[20:23]
	v_mfma_f32_16x16x32_bf16 v[16:19], v[176:179], v[208:211], v[16:19]
	v_mfma_f32_16x16x32_bf16 v[4:7], v[168:171], v[216:219], v[4:7]
	v_mfma_f32_16x16x32_bf16 v[0:3], v[176:179], v[216:219], v[0:3]
	v_mfma_f32_16x16x32_bf16 v[52:55], v[172:175], v[190:193], v[52:55]
	v_mfma_f32_16x16x32_bf16 v[48:51], v[182:185], v[190:193], v[48:51]
	v_mfma_f32_16x16x32_bf16 v[36:39], v[172:175], v[198:201], v[36:39]
	v_mfma_f32_16x16x32_bf16 v[32:35], v[182:185], v[198:201], v[32:35]
	v_lshl_add_u64 v[228:229], s[62:63], 0, v[132:133]
	s_mov_b32 m0, s34
	s_nop 0
	global_load_lds_dwordx4 v[228:229], off
	v_mfma_f32_16x16x32_bf16 v[20:23], v[172:175], v[212:215], v[20:23]
	v_mfma_f32_16x16x32_bf16 v[16:19], v[182:185], v[212:215], v[16:19]
	v_mfma_f32_16x16x32_bf16 v[4:7], v[172:175], v[220:223], v[4:7]
	v_mfma_f32_16x16x32_bf16 v[0:3], v[182:185], v[220:223], v[0:3]
	s_setprio 0
	s_barrier
; #define PG8_STAGE(bufoff, gbase, voff) do { _Pragma("unroll") for (int _i = 0; _i < 2; ++_i) \
;         __builtin_amdgcn_global_load_lds((const unsigned*)((const char*)(gbase) + (voff)[_i]), (PG8_LAS unsigned*)(lds + (bufoff) + ldsw + _i * 8192), 16, 0, 0); } while (0)
; #define PG8_LDA(dst, b, h) do { _Pragma("unroll") for (int m = 0; m < 4; ++m) _Pragma("unroll") for (int k = 0; k < 2; ++k) dst[m][k] = *(const PG8_LAS bf16x8*)(lds + PG8_SA(b, h) + aoff + m * 2048 + k * 1024); } while (0)
; #define PG8_LDB(dst, b, h) do { _Pragma("unroll") for (int n = 0; n < 2; ++n) _Pragma("unroll") for (int k = 0; k < 2; ++k) dst[n][k] = *(const PG8_LAS bf16x8*)(lds + PG8_SB(b, h) + boff + n * 2048 + k * 1024); } while (0)
; #define PG8_MMA(ai, bj, At, Bt) do { __builtin_amdgcn_s_setprio(1); _Pragma("unroll") for (int m = 0; m < 4; ++m) _Pragma("unroll") for (int n = 0; n < 2; ++n) _Pragma("unroll") for (int k = 0; k < 2; ++k) \
;         acc[ai][bj][m][n] = __builtin_amdgcn_mfma_f32_16x16x32_bf16(Bt[n][k], At[m][k], acc[ai][bj][m][n], 0, 0, 0); __builtin_amdgcn_s_setprio(0); } while (0)
; #define PG8_WAIT_V(n) asm volatile("s_waitcnt vmcnt(" #n ")" ::: "memory")
; #define PG8_WAIT_L(n) asm volatile("s_waitcnt lgkmcnt(" #n ")" ::: "memory")
; #define PG8_BAR __builtin_amdgcn_s_barrier()
; #define PG8_SCHED __builtin_amdgcn_sched_barrier(0)
; template <class Epi, class Sched, bool ALIGN_EPI = false, bool SP2 = false>
; __device__ __forceinline__ void gemm_phase(PG8_LAS unsigned char* lds, const Gemm g, const Sched& S, const Epi& E) {
;     ...
;             PG8_LDB(B0, 1, 0); PG8_LDB(B1, 1, 1); PG8_SCHED; PG8_LDA(At, 1, 0); PG8_STAGE(PG8_SA(0, 1), a2 + hstep, voffA);
;             PG8_WAIT_V(8); PG8_WAIT_L(0); PG8_BAR; PG8_MMA(0, 0, At, B0); PG8_MMA(0, 1, At, B1); PG8_BAR; PG8_SCHED;
	s_add_i32 s3, 0, 0x18000
	v_add_u32_e32 v155, s3, v149
	s_add_i32 s33, 0, 0x1c000
	ds_read_b128 v[144:147], v155
	ds_read_b128 v[156:159], v155 offset:1024
	ds_read_b128 v[160:163], v155 offset:2048
	ds_read_b128 v[164:167], v155 offset:3072
	v_add_u32_e32 v155, s33, v149
	ds_read_b128 v[168:171], v155
	ds_read_b128 v[172:175], v155 offset:1024
	ds_read_b128 v[176:179], v155 offset:2048
	ds_read_b128 v[182:185], v155 offset:3072
	s_add_u32 s62, s62, 0x20000
	s_addc_u32 s63, s63, 0
	s_mov_b32 m0, s57
	v_lshl_add_u64 v[230:231], s[62:63], 0, v[128:129]
	ds_read_b128 v[186:189], v153 offset:32768
	ds_read_b128 v[190:193], v153 offset:33792
	ds_read_b128 v[194:197], v153 offset:34816
	ds_read_b128 v[198:201], v153 offset:35840
	ds_read_b128 v[208:211], v153 offset:36864
	ds_read_b128 v[212:215], v153 offset:37888
	ds_read_b128 v[216:219], v153 offset:38912
	ds_read_b128 v[220:223], v153 offset:39936
	global_load_lds_dwordx4 v[230:231], off
	v_lshl_add_u64 v[230:231], s[62:63], 0, v[132:133]
	s_mov_b32 m0, s64
	s_nop 0
	global_load_lds_dwordx4 v[230:231], off
	s_waitcnt vmcnt(8)
	s_waitcnt lgkmcnt(0)
	s_barrier
	s_setprio 1
	s_waitcnt lgkmcnt(0)
	v_mfma_f32_16x16x32_bf16 v[124:127], v[144:147], v[186:189], v[124:127]
	v_mfma_f32_16x16x32_bf16 v[120:123], v[160:163], v[186:189], v[120:123]
	v_mfma_f32_16x16x32_bf16 v[108:111], v[144:147], v[194:197], v[108:111]
	v_mfma_f32_16x16x32_bf16 v[104:107], v[160:163], v[194:197], v[104:107]
	v_mfma_f32_16x16x32_bf16 v[92:95], v[144:147], v[208:211], v[92:95]
	v_mfma_f32_16x16x32_bf16 v[88:91], v[160:163], v[208:211], v[88:91]
	v_mfma_f32_16x16x32_bf16 v[76:79], v[144:147], v[216:219], v[76:79]
	v_mfma_f32_16x16x32_bf16 v[72:75], v[160:163], v[216:219], v[72:75]
	v_mfma_f32_16x16x32_bf16 v[124:127], v[156:159], v[190:193], v[124:127]
	v_mfma_f32_16x16x32_bf16 v[120:123], v[164:167], v[190:193], v[120:123]
	v_mfma_f32_16x16x32_bf16 v[108:111], v[156:159], v[198:201], v[108:111]
	v_mfma_f32_16x16x32_bf16 v[104:107], v[164:167], v[198:201], v[104:107]
	v_mfma_f32_16x16x32_bf16 v[92:95], v[156:159], v[212:215], v[92:95]
	v_mfma_f32_16x16x32_bf16 v[88:91], v[164:167], v[212:215], v[88:91]
	v_mfma_f32_16x16x32_bf16 v[76:79], v[156:159], v[220:223], v[76:79]
	v_mfma_f32_16x16x32_bf16 v[72:75], v[164:167], v[220:223], v[72:75]
	s_setprio 0
	s_setprio 1
	v_mfma_f32_16x16x32_bf16 v[116:119], v[168:171], v[186:189], v[116:119]
	v_mfma_f32_16x16x32_bf16 v[112:115], v[176:179], v[186:189], v[112:115]
	v_mfma_f32_16x16x32_bf16 v[100:103], v[168:171], v[194:197], v[100:103]
	v_mfma_f32_16x16x32_bf16 v[96:99], v[176:179], v[194:197], v[96:99]
	v_mfma_f32_16x16x32_bf16 v[84:87], v[168:171], v[208:211], v[84:87]
	v_mfma_f32_16x16x32_bf16 v[80:83], v[176:179], v[208:211], v[80:83]
	v_mfma_f32_16x16x32_bf16 v[68:71], v[168:171], v[216:219], v[68:71]
	v_mfma_f32_16x16x32_bf16 v[64:67], v[176:179], v[216:219], v[64:67]
	v_mfma_f32_16x16x32_bf16 v[116:119], v[172:175], v[190:193], v[116:119]
	v_mfma_f32_16x16x32_bf16 v[112:115], v[182:185], v[190:193], v[112:115]
	v_mfma_f32_16x16x32_bf16 v[100:103], v[172:175], v[198:201], v[100:103]
	v_mfma_f32_16x16x32_bf16 v[96:99], v[182:185], v[198:201], v[96:99]
	v_mfma_f32_16x16x32_bf16 v[84:87], v[172:175], v[212:215], v[84:87]
	v_mfma_f32_16x16x32_bf16 v[80:83], v[182:185], v[212:215], v[80:83]
	v_mfma_f32_16x16x32_bf16 v[68:71], v[172:175], v[220:223], v[68:71]
	v_mfma_f32_16x16x32_bf16 v[64:67], v[182:185], v[220:223], v[64:67]
	s_setprio 0
	s_barrier
; #define PG8_STAGE(bufoff, gbase, voff) do { _Pragma("unroll") for (int _i = 0; _i < 2; ++_i) \
;         __builtin_amdgcn_global_load_lds((const unsigned*)((const char*)(gbase) + (voff)[_i]), (PG8_LAS unsigned*)(lds + (bufoff) + ldsw + _i * 8192), 16, 0, 0); } while (0)
; #define PG8_LDA(dst, b, h) do { _Pragma("unroll") for (int m = 0; m < 4; ++m) _Pragma("unroll") for (int k = 0; k < 2; ++k) dst[m][k] = *(const PG8_LAS bf16x8*)(lds + PG8_SA(b, h) + aoff + m * 2048 + k * 1024); } while (0)
; #define PG8_MMA(ai, bj, At, Bt) do { __builtin_amdgcn_s_setprio(1); _Pragma("unroll") for (int m = 0; m < 4; ++m) _Pragma("unroll") for (int n = 0; n < 2; ++n) _Pragma("unroll") for (int k = 0; k < 2; ++k) \
;         acc[ai][bj][m][n] = __builtin_amdgcn_mfma_f32_16x16x32_bf16(Bt[n][k], At[m][k], acc[ai][bj][m][n], 0, 0, 0); __builtin_amdgcn_s_setprio(0); } while (0)
; #define PG8_WAIT_V(n) asm volatile("s_waitcnt vmcnt(" #n ")" ::: "memory")
; #define PG8_WAIT_L(n) asm volatile("s_waitcnt lgkmcnt(" #n ")" ::: "memory")
; #define PG8_BAR __builtin_amdgcn_s_barrier()
; #define PG8_SCHED __builtin_amdgcn_sched_barrier(0)
; template <class Epi, class Sched, bool ALIGN_EPI = false, bool SP2 = false>
; __device__ __forceinline__ void gemm_phase(PG8_LAS unsigned char* lds, const Gemm g, const Sched& S, const Epi& E) {
;     ...
;             PG8_LDA(At, 1, 1); PG8_STAGE(PG8_SB(1, 0), b3, voffB); PG8_STAGE(PG8_SB(1, 1), b3 + hstep, voffB); PG8_STAGE(PG8_SA(1, 0), a3, voffA);
;             PG8_WAIT_V(8); PG8_WAIT_L(0); PG8_BAR; PG8_MMA(1, 0, At, B0); PG8_MMA(1, 1, At, B1); PG8_BAR; PG8_SCHED;
;     ...
;         if constexpr (ALIGN_EPI) { if (wr == 0) PG8_BAR; }
	s_add_i32 s3, s3, s14
	v_lshl_add_u64 v[202:203], v[202:203], 0, s[38:39]
	s_mov_b32 m0, s3
	ds_read_b128 v[186:189], v153 offset:49152
	ds_read_b128 v[190:193], v153 offset:50176
	ds_read_b128 v[194:197], v153 offset:51200
	ds_read_b128 v[198:201], v153 offset:52224
	ds_read_b128 v[208:211], v153 offset:53248
	ds_read_b128 v[212:215], v153 offset:54272
	ds_read_b128 v[216:219], v153 offset:55296
	ds_read_b128 v[220:223], v153 offset:56320
	global_load_lds_dwordx4 v[202:203], off
	s_add_i32 m0, s3, 0x2000
	s_add_u32 s60, s60, 0x20080
	v_lshl_add_u64 v[202:203], v[224:225], 0, s[38:39]
	s_addc_u32 s61, s61, 0
	s_add_i32 s3, s33, s14
	global_load_lds_dwordx4 v[202:203], off
	v_lshl_add_u64 v[202:203], s[60:61], 0, v[130:131]
	s_mov_b32 m0, s3
	s_nop 0
	global_load_lds_dwordx4 v[202:203], off
	v_lshl_add_u64 v[202:203], s[60:61], 0, v[134:135]
	s_add_i32 m0, s3, 0x2000
	s_nop 0
	global_load_lds_dwordx4 v[202:203], off
	s_waitcnt vmcnt(6)
	s_waitcnt lgkmcnt(0)
	s_barrier
	s_setprio 1
	s_waitcnt lgkmcnt(0)
	v_mfma_f32_16x16x32_bf16 v[60:63], v[144:147], v[186:189], v[60:63]
	v_mfma_f32_16x16x32_bf16 v[56:59], v[160:163], v[186:189], v[56:59]
	v_mfma_f32_16x16x32_bf16 v[44:47], v[144:147], v[194:197], v[44:47]
	v_mfma_f32_16x16x32_bf16 v[40:43], v[160:163], v[194:197], v[40:43]
	v_mfma_f32_16x16x32_bf16 v[28:31], v[144:147], v[208:211], v[28:31]
	v_mfma_f32_16x16x32_bf16 v[24:27], v[160:163], v[208:211], v[24:27]
	v_mfma_f32_16x16x32_bf16 v[12:15], v[144:147], v[216:219], v[12:15]
	v_mfma_f32_16x16x32_bf16 v[8:11], v[160:163], v[216:219], v[8:11]
	v_mfma_f32_16x16x32_bf16 v[60:63], v[156:159], v[190:193], v[60:63]
	v_mfma_f32_16x16x32_bf16 v[56:59], v[164:167], v[190:193], v[56:59]
	v_mfma_f32_16x16x32_bf16 v[44:47], v[156:159], v[198:201], v[44:47]
	v_mfma_f32_16x16x32_bf16 v[40:43], v[164:167], v[198:201], v[40:43]
	v_lshl_add_u64 v[202:203], v[226:227], 0, s[38:39]
	s_mov_b32 m0, s66
	s_nop 0
	global_load_lds_dwordx4 v[202:203], off
	v_mfma_f32_16x16x32_bf16 v[28:31], v[156:159], v[212:215], v[28:31]
	v_mfma_f32_16x16x32_bf16 v[24:27], v[164:167], v[212:215], v[24:27]
	v_mfma_f32_16x16x32_bf16 v[12:15], v[156:159], v[220:223], v[12:15]
	v_mfma_f32_16x16x32_bf16 v[8:11], v[164:167], v[220:223], v[8:11]
	s_setprio 0
	s_setprio 1
	v_mfma_f32_16x16x32_bf16 v[52:55], v[168:171], v[186:189], v[52:55]
	v_mfma_f32_16x16x32_bf16 v[48:51], v[176:179], v[186:189], v[48:51]
	v_mfma_f32_16x16x32_bf16 v[36:39], v[168:171], v[194:197], v[36:39]
	v_mfma_f32_16x16x32_bf16 v[32:35], v[176:179], v[194:197], v[32:35]
	v_mfma_f32_16x16x32_bf16 v[20:23], v[168:171], v[208:211], v[20:23]
	v_mfma_f32_16x16x32_bf16 v[16:19], v[176:179], v[208:211], v[16:19]
	v_mfma_f32_16x16x32_bf16 v[4:7], v[168:171], v[216:219], v[4:7]
	v_mfma_f32_16x16x32_bf16 v[0:3], v[176:179], v[216:219], v[0:3]
	v_mfma_f32_16x16x32_bf16 v[52:55], v[172:175], v[190:193], v[52:55]
	v_mfma_f32_16x16x32_bf16 v[48:51], v[182:185], v[190:193], v[48:51]
	v_mfma_f32_16x16x32_bf16 v[36:39], v[172:175], v[198:201], v[36:39]
	v_mfma_f32_16x16x32_bf16 v[32:35], v[182:185], v[198:201], v[32:35]
	v_lshl_add_u64 v[202:203], v[228:229], 0, s[38:39]
	s_mov_b32 m0, s67
	s_nop 0
	global_load_lds_dwordx4 v[202:203], off
	v_mfma_f32_16x16x32_bf16 v[20:23], v[172:175], v[212:215], v[20:23]
	v_mfma_f32_16x16x32_bf16 v[16:19], v[182:185], v[212:215], v[16:19]
	v_mfma_f32_16x16x32_bf16 v[4:7], v[172:175], v[220:223], v[4:7]
	v_mfma_f32_16x16x32_bf16 v[0:3], v[182:185], v[220:223], v[0:3]
	s_setprio 0
	s_barrier
	s_add_i32 s87, s87, 2
	s_add_u32 s58, s58, 0x100
	s_addc_u32 s59, s59, 0
	s_add_u32 s85, s85, 0x100
	s_addc_u32 s86, s86, 0
	s_cmp_gt_u32 s87, 5
	s_cbranch_scc0 .LBB0_873
	s_and_b64 vcc, exec, s[42:43]
	s_cbranch_vccz .LBB0_876
	s_barrier

; #define PG8_STAGE(bufoff, gbase, voff) do { _Pragma("unroll") for (int _i = 0; _i < 2; ++_i) \
;         __builtin_amdgcn_global_load_lds((const unsigned*)((const char*)(gbase) + (voff)[_i]), (PG8_LAS unsigned*)(lds + (bufoff) + ldsw + _i * 8192), 16, 0, 0); } while (0)
; #define PG8_LDA(dst, b, h) do { _Pragma("unroll") for (int m = 0; m < 4; ++m) _Pragma("unroll") for (int k = 0; k < 2; ++k) dst[m][k] = *(const PG8_LAS bf16x8*)(lds + PG8_SA(b, h) + aoff + m * 2048 + k * 1024); } while (0)
; #define PG8_LDB(dst, b, h) do { _Pragma("unroll") for (int n = 0; n < 2; ++n) _Pragma("unroll") for (int k = 0; k < 2; ++k) dst[n][k] = *(const PG8_LAS bf16x8*)(lds + PG8_SB(b, h) + boff + n * 2048 + k * 1024); } while (0)
; #define PG8_MMA(ai, bj, At, Bt) do { __builtin_amdgcn_s_setprio(1); _Pragma("unroll") for (int m = 0; m < 4; ++m) _Pragma("unroll") for (int n = 0; n < 2; ++n) _Pragma("unroll") for (int k = 0; k < 2; ++k) \
;         acc[ai][bj][m][n] = __builtin_amdgcn_mfma_f32_16x16x32_bf16(Bt[n][k], At[m][k], acc[ai][bj][m][n], 0, 0, 0); __builtin_amdgcn_s_setprio(0); } while (0)
; #define PG8_BAR __builtin_amdgcn_s_barrier()
; template <class Epi, class Sched, bool ALIGN_EPI = false, bool SP2 = false>
; __device__ __forceinline__ void gemm_phase(PG8_LAS unsigned char* lds, const Gemm g, const Sched& S, const Epi& E) {
;     ...
;         const bool has_next = S.next(ui + 1, nxt);
;         const char* nA = has_next ? (const char*)g.A + (size_t)nxt.pm * tstep : cA; const char* nB = has_next ? (const char*)g.Bt + (size_t)nxt.pn * tstep : cB;
;         for (int t = 0; t < nt; t += 2) {
;             const bool last = (t == nt - 2);
;             const char* a1 = cA + (size_t)(t + 1) * kstep;
;             const char* a2 = last ? nA : cA + (size_t)(t + 2) * kstep; const char* b2 = last ? nB : cB + (size_t)(t + 2) * kstep;
;             const char* a3 = a2 + kstep; const char* b3 = b2 + kstep;
;             if (last && has_next) S.a_ready(nxt);
;             if constexpr (SP2) {
;             PG8_LDB(B0, 0, 0); PG8_LDB(B1, 0, 1); PG8_SCHED; PG8_LDA(At, 0, 0); PG8_STAGE(PG8_SA(1, 1), a1 + hstep, voffA);
;             PG8_WAIT_V(8); PG8_WAIT_L(0); PG8_BAR; PG8_MMA(0, 0, At, B0); PG8_MMA(0, 1, At, B1); PG8_BAR; PG8_SCHED;
;             PG8_LDA(At, 0, 1); PG8_STAGE(PG8_SB(0, 0), b2, voffB); PG8_STAGE(PG8_SB(0, 1), b2 + hstep, voffB); PG8_STAGE(PG8_SA(0, 0), a2, voffA);
.LBB0_956:
	s_ashr_i32 s45, s44, 31
	s_lshl_b64 s[48:49], s[44:45], 19
	s_add_u32 s48, s22, s48
	s_addc_u32 s49, s23, s49
	s_and_b64 s[50:51], s[10:11], exec
	s_cselect_b32 s45, s49, s55
	s_cselect_b32 s75, s48, s54
	s_ashr_i32 s43, s42, 31
	s_lshl_b64 s[50:51], s[42:43], 19
	v_readlane_b32 s3, v250, 18
	s_add_u32 s50, s3, s50
	v_readlane_b32 s3, v250, 19
	s_addc_u32 s51, s3, s51
	s_and_b64 s[58:59], s[10:11], exec
	s_cselect_b32 s43, s51, s57
	s_cselect_b32 s76, s50, s56
	s_add_u32 s54, s54, 0x40080
	s_addc_u32 s55, s55, 0
	s_add_u32 s77, s56, 0x100
	s_addc_u32 s82, s57, 0
	s_mov_b32 s83, -2
	ds_read_b128 v[144:147], v155
	ds_read_b128 v[148:151], v155 offset:1024
	ds_read_b128 v[160:163], v155 offset:2048
	ds_read_b128 v[164:167], v155 offset:3072
	ds_read_b128 v[168:171], v156
	ds_read_b128 v[172:175], v156 offset:1024
	ds_read_b128 v[176:179], v156 offset:2048
	ds_read_b128 v[182:185], v156 offset:3072
	s_add_u32 s3, s54, 0xfffc0080
	s_addc_u32 s33, s55, -1
	s_cmp_eq_u32 s83, 12
	s_cselect_b32 s59, s45, s33
	s_cselect_b32 s58, s75, s3
	s_cselect_b32 s57, s43, s82
	s_cselect_b32 s56, s76, s77
	v_lshl_add_u64 v[202:203], s[54:55], 0, v[136:137]
	s_add_i32 m0, s34, 0xc000
	ds_read_b128 v[186:189], v157
	ds_read_b128 v[190:193], v157 offset:1024
	ds_read_b128 v[194:197], v157 offset:2048
	ds_read_b128 v[198:201], v157 offset:3072
	ds_read_b128 v[208:211], v157 offset:4096
	ds_read_b128 v[212:215], v157 offset:5120
	ds_read_b128 v[216:219], v157 offset:6144
	ds_read_b128 v[220:223], v157 offset:7168
	global_load_lds_dwordx4 v[202:203], off
	v_lshl_add_u64 v[202:203], s[54:55], 0, v[138:139]
	s_add_i32 m0, s34, 0xe000
	s_nop 0
	global_load_lds_dwordx4 v[202:203], off
	s_waitcnt vmcnt(8)
	s_waitcnt lgkmcnt(0)
	s_barrier
	s_setprio 1
	s_waitcnt lgkmcnt(0)
	v_mfma_f32_16x16x32_bf16 v[124:127], v[144:147], v[186:189], 0
	v_mfma_f32_16x16x32_bf16 v[120:123], v[160:163], v[186:189], 0
	v_mfma_f32_16x16x32_bf16 v[108:111], v[144:147], v[194:197], 0
	v_mfma_f32_16x16x32_bf16 v[104:107], v[160:163], v[194:197], 0
	v_mfma_f32_16x16x32_bf16 v[92:95], v[144:147], v[208:211], 0
	v_mfma_f32_16x16x32_bf16 v[88:91], v[160:163], v[208:211], 0
	v_mfma_f32_16x16x32_bf16 v[76:79], v[144:147], v[216:219], 0
	v_mfma_f32_16x16x32_bf16 v[72:75], v[160:163], v[216:219], 0
	v_mfma_f32_16x16x32_bf16 v[124:127], v[148:151], v[190:193], v[124:127]
	v_mfma_f32_16x16x32_bf16 v[120:123], v[164:167], v[190:193], v[120:123]
	v_mfma_f32_16x16x32_bf16 v[108:111], v[148:151], v[198:201], v[108:111]
	v_mfma_f32_16x16x32_bf16 v[104:107], v[164:167], v[198:201], v[104:107]
	v_mfma_f32_16x16x32_bf16 v[92:95], v[148:151], v[212:215], v[92:95]
	v_mfma_f32_16x16x32_bf16 v[88:91], v[164:167], v[212:215], v[88:91]
	v_mfma_f32_16x16x32_bf16 v[76:79], v[148:151], v[220:223], v[76:79]
	v_mfma_f32_16x16x32_bf16 v[72:75], v[164:167], v[220:223], v[72:75]
	s_setprio 0
	s_setprio 1
	v_mfma_f32_16x16x32_bf16 v[116:119], v[168:171], v[186:189], 0
	v_mfma_f32_16x16x32_bf16 v[112:115], v[176:179], v[186:189], 0
	v_mfma_f32_16x16x32_bf16 v[100:103], v[168:171], v[194:197], 0
	v_mfma_f32_16x16x32_bf16 v[96:99], v[176:179], v[194:197], 0
	v_mfma_f32_16x16x32_bf16 v[84:87], v[168:171], v[208:211], 0
	v_mfma_f32_16x16x32_bf16 v[80:83], v[176:179], v[208:211], 0
	v_mfma_f32_16x16x32_bf16 v[68:71], v[168:171], v[216:219], 0
	v_mfma_f32_16x16x32_bf16 v[64:67], v[176:179], v[216:219], 0
	v_mfma_f32_16x16x32_bf16 v[116:119], v[172:175], v[190:193], v[116:119]
	v_mfma_f32_16x16x32_bf16 v[112:115], v[182:185], v[190:193], v[112:115]
	v_mfma_f32_16x16x32_bf16 v[100:103], v[172:175], v[198:201], v[100:103]
	v_mfma_f32_16x16x32_bf16 v[96:99], v[182:185], v[198:201], v[96:99]
	v_mfma_f32_16x16x32_bf16 v[84:87], v[172:175], v[212:215], v[84:87]
	v_mfma_f32_16x16x32_bf16 v[80:83], v[182:185], v[212:215], v[80:83]
	v_mfma_f32_16x16x32_bf16 v[68:71], v[172:175], v[220:223], v[68:71]
	v_mfma_f32_16x16x32_bf16 v[64:67], v[182:185], v[220:223], v[64:67]
	s_setprio 0
	s_barrier
	s_add_i32 s3, s65, s14
	v_lshl_add_u64 v[202:203], s[56:57], 0, v[132:133]
	s_mov_b32 m0, s3
	ds_read_b128 v[186:189], v157 offset:16384
	ds_read_b128 v[190:193], v157 offset:17408
	ds_read_b128 v[194:197], v157 offset:18432
	ds_read_b128 v[198:201], v157 offset:19456
	ds_read_b128 v[208:211], v157 offset:20480
	ds_read_b128 v[212:215], v157 offset:21504
	ds_read_b128 v[216:219], v157 offset:22528
	ds_read_b128 v[220:223], v157 offset:23552
	global_load_lds_dwordx4 v[202:203], off
	s_add_i32 m0, s3, 0x2000
	s_add_u32 s78, s56, 0x40000
	v_lshl_add_u64 v[224:225], s[56:57], 0, v[128:129]
	s_addc_u32 s79, s57, 0
	s_add_i32 s3, s66, s14
	global_load_lds_dwordx4 v[224:225], off
	v_lshl_add_u64 v[226:227], s[78:79], 0, v[132:133]
	s_mov_b32 m0, s3
	global_load_lds_dwordx4 v[226:227], off
	v_lshl_add_u64 v[226:227], s[78:79], 0, v[128:129]
	s_add_i32 m0, s3, 0x2000
	s_nop 0
	global_load_lds_dwordx4 v[226:227], off
	s_waitcnt vmcnt(6)
	s_waitcnt lgkmcnt(0)
	s_barrier
; #define PG8_STAGE(bufoff, gbase, voff) do { _Pragma("unroll") for (int _i = 0; _i < 2; ++_i) \
;         __builtin_amdgcn_global_load_lds((const unsigned*)((const char*)(gbase) + (voff)[_i]), (PG8_LAS unsigned*)(lds + (bufoff) + ldsw + _i * 8192), 16, 0, 0); } while (0)
; #define PG8_LDA(dst, b, h) do { _Pragma("unroll") for (int m = 0; m < 4; ++m) _Pragma("unroll") for (int k = 0; k < 2; ++k) dst[m][k] = *(const PG8_LAS bf16x8*)(lds + PG8_SA(b, h) + aoff + m * 2048 + k * 1024); } while (0)
; #define PG8_LDB(dst, b, h) do { _Pragma("unroll") for (int n = 0; n < 2; ++n) _Pragma("unroll") for (int k = 0; k < 2; ++k) dst[n][k] = *(const PG8_LAS bf16x8*)(lds + PG8_SB(b, h) + boff + n * 2048 + k * 1024); } while (0)
; #define PG8_MMA(ai, bj, At, Bt) do { __builtin_amdgcn_s_setprio(1); _Pragma("unroll") for (int m = 0; m < 4; ++m) _Pragma("unroll") for (int n = 0; n < 2; ++n) _Pragma("unroll") for (int k = 0; k < 2; ++k) \
;         acc[ai][bj][m][n] = __builtin_amdgcn_mfma_f32_16x16x32_bf16(Bt[n][k], At[m][k], acc[ai][bj][m][n], 0, 0, 0); __builtin_amdgcn_s_setprio(0); } while (0)
; #define PG8_WAIT_V(n) asm volatile("s_waitcnt vmcnt(" #n ")" ::: "memory")
; #define PG8_WAIT_L(n) asm volatile("s_waitcnt lgkmcnt(" #n ")" ::: "memory")
; #define PG8_BAR __builtin_amdgcn_s_barrier()
; #define PG8_SCHED __builtin_amdgcn_sched_barrier(0)
; template <class Epi, class Sched, bool ALIGN_EPI = false, bool SP2 = false>
; __device__ __forceinline__ void gemm_phase(PG8_LAS unsigned char* lds, const Gemm g, const Sched& S, const Epi& E) {
;     ...
;             PG8_WAIT_V(8); PG8_WAIT_L(0); PG8_BAR; PG8_MMA(1, 0, At, B0); PG8_MMA(1, 1, At, B1); PG8_BAR; PG8_SCHED;
;             PG8_LDB(B0, 1, 0); PG8_LDB(B1, 1, 1); PG8_SCHED; PG8_LDA(At, 1, 0); PG8_STAGE(PG8_SA(0, 1), a2 + hstep, voffA);
;             PG8_WAIT_V(8); PG8_WAIT_L(0); PG8_BAR; PG8_MMA(0, 0, At, B0); PG8_MMA(0, 1, At, B1); PG8_BAR; PG8_SCHED;
	s_setprio 1
	s_waitcnt lgkmcnt(0)
	v_mfma_f32_16x16x32_bf16 v[60:63], v[144:147], v[186:189], 0
	v_mfma_f32_16x16x32_bf16 v[56:59], v[160:163], v[186:189], 0
	v_mfma_f32_16x16x32_bf16 v[44:47], v[144:147], v[194:197], 0
	v_mfma_f32_16x16x32_bf16 v[40:43], v[160:163], v[194:197], 0
	v_mfma_f32_16x16x32_bf16 v[28:31], v[144:147], v[208:211], 0
	v_mfma_f32_16x16x32_bf16 v[24:27], v[160:163], v[208:211], 0
	v_mfma_f32_16x16x32_bf16 v[12:15], v[144:147], v[216:219], 0
	v_mfma_f32_16x16x32_bf16 v[8:11], v[160:163], v[216:219], 0
	v_mfma_f32_16x16x32_bf16 v[60:63], v[148:151], v[190:193], v[60:63]
	v_mfma_f32_16x16x32_bf16 v[56:59], v[164:167], v[190:193], v[56:59]
	v_mfma_f32_16x16x32_bf16 v[44:47], v[148:151], v[198:201], v[44:47]
	v_mfma_f32_16x16x32_bf16 v[40:43], v[164:167], v[198:201], v[40:43]
	v_lshl_add_u64 v[226:227], s[58:59], 0, v[134:135]
	s_mov_b32 m0, s34
	s_nop 0
	global_load_lds_dwordx4 v[226:227], off
	v_mfma_f32_16x16x32_bf16 v[28:31], v[148:151], v[212:215], v[28:31]
	v_mfma_f32_16x16x32_bf16 v[24:27], v[164:167], v[212:215], v[24:27]
	v_mfma_f32_16x16x32_bf16 v[12:15], v[148:151], v[220:223], v[12:15]
	v_mfma_f32_16x16x32_bf16 v[8:11], v[164:167], v[220:223], v[8:11]
	s_setprio 0
	s_setprio 1
	v_mfma_f32_16x16x32_bf16 v[52:55], v[168:171], v[186:189], 0
	v_mfma_f32_16x16x32_bf16 v[48:51], v[176:179], v[186:189], 0
	v_mfma_f32_16x16x32_bf16 v[36:39], v[168:171], v[194:197], 0
	v_mfma_f32_16x16x32_bf16 v[32:35], v[176:179], v[194:197], 0
	v_mfma_f32_16x16x32_bf16 v[20:23], v[168:171], v[208:211], 0
	v_mfma_f32_16x16x32_bf16 v[16:19], v[176:179], v[208:211], 0
	v_mfma_f32_16x16x32_bf16 v[4:7], v[168:171], v[216:219], 0
	v_mfma_f32_16x16x32_bf16 v[0:3], v[176:179], v[216:219], 0
	v_mfma_f32_16x16x32_bf16 v[52:55], v[172:175], v[190:193], v[52:55]
	v_mfma_f32_16x16x32_bf16 v[48:51], v[182:185], v[190:193], v[48:51]
	v_mfma_f32_16x16x32_bf16 v[36:39], v[172:175], v[198:201], v[36:39]
	v_mfma_f32_16x16x32_bf16 v[32:35], v[182:185], v[198:201], v[32:35]
	v_lshl_add_u64 v[228:229], s[58:59], 0, v[130:131]
	s_mov_b32 m0, s53
	s_nop 0
	global_load_lds_dwordx4 v[228:229], off
	v_mfma_f32_16x16x32_bf16 v[20:23], v[172:175], v[212:215], v[20:23]
	v_mfma_f32_16x16x32_bf16 v[16:19], v[182:185], v[212:215], v[16:19]
	v_mfma_f32_16x16x32_bf16 v[4:7], v[172:175], v[220:223], v[4:7]
	v_mfma_f32_16x16x32_bf16 v[0:3], v[182:185], v[220:223], v[0:3]
	s_setprio 0
	s_barrier
	s_add_i32 s3, 0, 0x18000
	v_add_u32_e32 v159, s3, v153
	s_add_i32 s33, 0, 0x1c000
	ds_read_b128 v[144:147], v159
	ds_read_b128 v[148:151], v159 offset:1024
	ds_read_b128 v[160:163], v159 offset:2048
	ds_read_b128 v[164:167], v159 offset:3072
	v_add_u32_e32 v159, s33, v153
	ds_read_b128 v[168:171], v159
	ds_read_b128 v[172:175], v159 offset:1024
	ds_read_b128 v[176:179], v159 offset:2048
	ds_read_b128 v[182:185], v159 offset:3072
	s_add_u32 s58, s58, 0x40000
	s_addc_u32 s59, s59, 0
	s_mov_b32 m0, s60
	v_lshl_add_u64 v[230:231], s[58:59], 0, v[134:135]
	ds_read_b128 v[186:189], v157 offset:32768
	ds_read_b128 v[190:193], v157 offset:33792
	ds_read_b128 v[194:197], v157 offset:34816
	ds_read_b128 v[198:201], v157 offset:35840
	ds_read_b128 v[208:211], v157 offset:36864
	ds_read_b128 v[212:215], v157 offset:37888
	ds_read_b128 v[216:219], v157 offset:38912
	ds_read_b128 v[220:223], v157 offset:39936
	global_load_lds_dwordx4 v[230:231], off
	v_lshl_add_u64 v[230:231], s[58:59], 0, v[130:131]
	s_mov_b32 m0, s61
	s_nop 0
	global_load_lds_dwordx4 v[230:231], off
	s_waitcnt vmcnt(8)
	s_waitcnt lgkmcnt(0)
	s_barrier
	s_setprio 1
	s_waitcnt lgkmcnt(0)
	v_mfma_f32_16x16x32_bf16 v[124:127], v[144:147], v[186:189], v[124:127]
	v_mfma_f32_16x16x32_bf16 v[120:123], v[160:163], v[186:189], v[120:123]
	v_mfma_f32_16x16x32_bf16 v[108:111], v[144:147], v[194:197], v[108:111]
	v_mfma_f32_16x16x32_bf16 v[104:107], v[160:163], v[194:197], v[104:107]
	v_mfma_f32_16x16x32_bf16 v[92:95], v[144:147], v[208:211], v[92:95]
	v_mfma_f32_16x16x32_bf16 v[88:91], v[160:163], v[208:211], v[88:91]
	v_mfma_f32_16x16x32_bf16 v[76:79], v[144:147], v[216:219], v[76:79]
	v_mfma_f32_16x16x32_bf16 v[72:75], v[160:163], v[216:219], v[72:75]
	v_mfma_f32_16x16x32_bf16 v[124:127], v[148:151], v[190:193], v[124:127]
	v_mfma_f32_16x16x32_bf16 v[120:123], v[164:167], v[190:193], v[120:123]
	v_mfma_f32_16x16x32_bf16 v[108:111], v[148:151], v[198:201], v[108:111]
	v_mfma_f32_16x16x32_bf16 v[104:107], v[164:167], v[198:201], v[104:107]
	v_mfma_f32_16x16x32_bf16 v[92:95], v[148:151], v[212:215], v[92:95]
	v_mfma_f32_16x16x32_bf16 v[88:91], v[164:167], v[212:215], v[88:91]
	v_mfma_f32_16x16x32_bf16 v[76:79], v[148:151], v[220:223], v[76:79]
	v_mfma_f32_16x16x32_bf16 v[72:75], v[164:167], v[220:223], v[72:75]
	s_setprio 0
	s_setprio 1
	v_mfma_f32_16x16x32_bf16 v[116:119], v[168:171], v[186:189], v[116:119]
	v_mfma_f32_16x16x32_bf16 v[112:115], v[176:179], v[186:189], v[112:115]
	v_mfma_f32_16x16x32_bf16 v[100:103], v[168:171], v[194:197], v[100:103]
	v_mfma_f32_16x16x32_bf16 v[96:99], v[176:179], v[194:197], v[96:99]
	v_mfma_f32_16x16x32_bf16 v[84:87], v[168:171], v[208:211], v[84:87]
	v_mfma_f32_16x16x32_bf16 v[80:83], v[176:179], v[208:211], v[80:83]
	v_mfma_f32_16x16x32_bf16 v[68:71], v[168:171], v[216:219], v[68:71]
	v_mfma_f32_16x16x32_bf16 v[64:67], v[176:179], v[216:219], v[64:67]
	v_mfma_f32_16x16x32_bf16 v[116:119], v[172:175], v[190:193], v[116:119]
	v_mfma_f32_16x16x32_bf16 v[112:115], v[182:185], v[190:193], v[112:115]
	v_mfma_f32_16x16x32_bf16 v[100:103], v[172:175], v[198:201], v[100:103]
	v_mfma_f32_16x16x32_bf16 v[96:99], v[182:185], v[198:201], v[96:99]
	v_mfma_f32_16x16x32_bf16 v[84:87], v[172:175], v[212:215], v[84:87]
	v_mfma_f32_16x16x32_bf16 v[80:83], v[182:185], v[212:215], v[80:83]
	v_mfma_f32_16x16x32_bf16 v[68:71], v[172:175], v[220:223], v[68:71]
	v_mfma_f32_16x16x32_bf16 v[64:67], v[182:185], v[220:223], v[64:67]
	s_setprio 0
	s_barrier
; #define PG8_STAGE(bufoff, gbase, voff) do { _Pragma("unroll") for (int _i = 0; _i < 2; ++_i) \
;         __builtin_amdgcn_global_load_lds((const unsigned*)((const char*)(gbase) + (voff)[_i]), (PG8_LAS unsigned*)(lds + (bufoff) + ldsw + _i * 8192), 16, 0, 0); } while (0)
; #define PG8_LDA(dst, b, h) do { _Pragma("unroll") for (int m = 0; m < 4; ++m) _Pragma("unroll") for (int k = 0; k < 2; ++k) dst[m][k] = *(const PG8_LAS bf16x8*)(lds + PG8_SA(b, h) + aoff + m * 2048 + k * 1024); } while (0)
; #define PG8_LDB(dst, b, h) do { _Pragma("unroll") for (int n = 0; n < 2; ++n) _Pragma("unroll") for (int k = 0; k < 2; ++k) dst[n][k] = *(const PG8_LAS bf16x8*)(lds + PG8_SB(b, h) + boff + n * 2048 + k * 1024); } while (0)
; #define PG8_MMA(ai, bj, At, Bt) do { __builtin_amdgcn_s_setprio(1); _Pragma("unroll") for (int m = 0; m < 4; ++m) _Pragma("unroll") for (int n = 0; n < 2; ++n) _Pragma("unroll") for (int k = 0; k < 2; ++k) \
;         acc[ai][bj][m][n] = __builtin_amdgcn_mfma_f32_16x16x32_bf16(Bt[n][k], At[m][k], acc[ai][bj][m][n], 0, 0, 0); __builtin_amdgcn_s_setprio(0); } while (0)
; #define PG8_WAIT_V(n) asm volatile("s_waitcnt vmcnt(" #n ")" ::: "memory")
; template <class Epi, class Sched, bool ALIGN_EPI = false, bool SP2 = false>
; __device__ __forceinline__ void gemm_phase(PG8_LAS unsigned char* lds, const Gemm g, const Sched& S, const Epi& E) {
;     ...
;             PG8_LDB(B0, 0, 0); PG8_LDB(B1, 0, 1); PG8_SCHED; PG8_LDA(At, 0, 0); PG8_STAGE(PG8_SA(1, 1), a1 + hstep, voffA);
;             PG8_WAIT_V(8); PG8_WAIT_L(0); PG8_BAR; PG8_MMA(0, 0, At, B0); PG8_MMA(0, 1, At, B1); PG8_BAR; PG8_SCHED;
;             PG8_LDA(At, 0, 1); PG8_STAGE(PG8_SB(0, 0), b2, voffB); PG8_STAGE(PG8_SB(0, 1), b2 + hstep, voffB); PG8_STAGE(PG8_SA(0, 0), a2, voffA);
;             PG8_WAIT_V(8); PG8_WAIT_L(0); PG8_BAR; PG8_MMA(1, 0, At, B0); PG8_MMA(1, 1, At, B1); PG8_BAR; PG8_SCHED;
;             PG8_LDB(B0, 1, 0); PG8_LDB(B1, 1, 1); PG8_SCHED; PG8_LDA(At, 1, 0); PG8_STAGE(PG8_SA(0, 1), a2 + hstep, voffA);
;             PG8_WAIT_V(8); PG8_WAIT_L(0); PG8_BAR; PG8_MMA(0, 0, At, B0); PG8_MMA(0, 1, At, B1); PG8_BAR; PG8_SCHED;
;             PG8_LDA(At, 1, 1); PG8_STAGE(PG8_SB(1, 0), b3, voffB); PG8_STAGE(PG8_SB(1, 1), b3 + hstep, voffB); PG8_STAGE(PG8_SA(1, 0), a3, voffA);
;             PG8_WAIT_V(8); PG8_WAIT_L(0); PG8_BAR; PG8_MMA(1, 0, At, B0); PG8_MMA(1, 1, At, B1); PG8_BAR; PG8_SCHED;
	s_add_i32 s3, s3, s14
	v_lshl_add_u64 v[202:203], v[202:203], 0, s[36:37]
	s_mov_b32 m0, s3
	ds_read_b128 v[186:189], v157 offset:49152
	ds_read_b128 v[190:193], v157 offset:50176
	ds_read_b128 v[194:197], v157 offset:51200
	ds_read_b128 v[198:201], v157 offset:52224
	ds_read_b128 v[208:211], v157 offset:53248
	ds_read_b128 v[212:215], v157 offset:54272
	ds_read_b128 v[216:219], v157 offset:55296
	ds_read_b128 v[220:223], v157 offset:56320
	global_load_lds_dwordx4 v[202:203], off
	s_add_i32 m0, s3, 0x2000
	s_add_u32 s56, s56, 0x40080
	v_lshl_add_u64 v[202:203], v[224:225], 0, s[36:37]
	s_addc_u32 s57, s57, 0
	s_add_i32 s3, s33, s14
	global_load_lds_dwordx4 v[202:203], off
	v_lshl_add_u64 v[202:203], s[56:57], 0, v[132:133]
	s_mov_b32 m0, s3
	s_nop 0
	global_load_lds_dwordx4 v[202:203], off
	v_lshl_add_u64 v[202:203], s[56:57], 0, v[128:129]
	s_add_i32 m0, s3, 0x2000
	s_nop 0
	global_load_lds_dwordx4 v[202:203], off
	s_waitcnt vmcnt(6)
	s_waitcnt lgkmcnt(0)
	s_barrier
	s_setprio 1
	s_waitcnt lgkmcnt(0)
	v_mfma_f32_16x16x32_bf16 v[60:63], v[144:147], v[186:189], v[60:63]
	v_mfma_f32_16x16x32_bf16 v[56:59], v[160:163], v[186:189], v[56:59]
	v_mfma_f32_16x16x32_bf16 v[44:47], v[144:147], v[194:197], v[44:47]
	v_mfma_f32_16x16x32_bf16 v[40:43], v[160:163], v[194:197], v[40:43]
	v_mfma_f32_16x16x32_bf16 v[28:31], v[144:147], v[208:211], v[28:31]
	v_mfma_f32_16x16x32_bf16 v[24:27], v[160:163], v[208:211], v[24:27]
	v_mfma_f32_16x16x32_bf16 v[12:15], v[144:147], v[216:219], v[12:15]
	v_mfma_f32_16x16x32_bf16 v[8:11], v[160:163], v[216:219], v[8:11]
	v_mfma_f32_16x16x32_bf16 v[60:63], v[148:151], v[190:193], v[60:63]
	v_mfma_f32_16x16x32_bf16 v[56:59], v[164:167], v[190:193], v[56:59]
	v_mfma_f32_16x16x32_bf16 v[44:47], v[148:151], v[198:201], v[44:47]
	v_mfma_f32_16x16x32_bf16 v[40:43], v[164:167], v[198:201], v[40:43]
	v_lshl_add_u64 v[202:203], v[226:227], 0, s[36:37]
	s_mov_b32 m0, s63
	s_nop 0
	global_load_lds_dwordx4 v[202:203], off
	v_mfma_f32_16x16x32_bf16 v[28:31], v[148:151], v[212:215], v[28:31]
	v_mfma_f32_16x16x32_bf16 v[24:27], v[164:167], v[212:215], v[24:27]
	v_mfma_f32_16x16x32_bf16 v[12:15], v[148:151], v[220:223], v[12:15]
	v_mfma_f32_16x16x32_bf16 v[8:11], v[164:167], v[220:223], v[8:11]
	s_setprio 0
	s_setprio 1
	v_mfma_f32_16x16x32_bf16 v[52:55], v[168:171], v[186:189], v[52:55]
	v_mfma_f32_16x16x32_bf16 v[48:51], v[176:179], v[186:189], v[48:51]
	v_mfma_f32_16x16x32_bf16 v[36:39], v[168:171], v[194:197], v[36:39]
	v_mfma_f32_16x16x32_bf16 v[32:35], v[176:179], v[194:197], v[32:35]
	v_mfma_f32_16x16x32_bf16 v[20:23], v[168:171], v[208:211], v[20:23]
	v_mfma_f32_16x16x32_bf16 v[16:19], v[176:179], v[208:211], v[16:19]
	v_mfma_f32_16x16x32_bf16 v[4:7], v[168:171], v[216:219], v[4:7]
	v_mfma_f32_16x16x32_bf16 v[0:3], v[176:179], v[216:219], v[0:3]
	v_mfma_f32_16x16x32_bf16 v[52:55], v[172:175], v[190:193], v[52:55]
	v_mfma_f32_16x16x32_bf16 v[48:51], v[182:185], v[190:193], v[48:51]
	v_mfma_f32_16x16x32_bf16 v[36:39], v[172:175], v[198:201], v[36:39]
	v_mfma_f32_16x16x32_bf16 v[32:35], v[182:185], v[198:201], v[32:35]
	v_lshl_add_u64 v[202:203], v[228:229], 0, s[36:37]
	s_mov_b32 m0, s64
	s_nop 0
	global_load_lds_dwordx4 v[202:203], off
	v_mfma_f32_16x16x32_bf16 v[20:23], v[172:175], v[212:215], v[20:23]
	v_mfma_f32_16x16x32_bf16 v[16:19], v[182:185], v[212:215], v[16:19]
	v_mfma_f32_16x16x32_bf16 v[4:7], v[172:175], v[220:223], v[4:7]
	v_mfma_f32_16x16x32_bf16 v[0:3], v[182:185], v[220:223], v[0:3]
	s_setprio 0
	s_barrier
	s_add_i32 s83, s83, 2
	s_add_u32 s54, s54, 0x100
	s_addc_u32 s55, s55, 0
	s_add_u32 s77, s77, 0x100
	s_addc_u32 s82, s82, 0
.LBB0_957:
	ds_read_b128 v[144:147], v155
	ds_read_b128 v[148:151], v155 offset:1024
	ds_read_b128 v[160:163], v155 offset:2048
	ds_read_b128 v[164:167], v155 offset:3072
	ds_read_b128 v[168:171], v156
	ds_read_b128 v[172:175], v156 offset:1024
	ds_read_b128 v[176:179], v156 offset:2048
	ds_read_b128 v[182:185], v156 offset:3072
	s_add_u32 s3, s54, 0xfffc0080
	s_addc_u32 s33, s55, -1
	s_cmp_eq_u32 s83, 12
	s_cselect_b32 s59, s45, s33
	s_cselect_b32 s58, s75, s3
	s_cselect_b32 s57, s43, s82
	s_cselect_b32 s56, s76, s77
	v_lshl_add_u64 v[202:203], s[54:55], 0, v[136:137]
	s_add_i32 m0, s34, 0xc000
	ds_read_b128 v[186:189], v157
	ds_read_b128 v[190:193], v157 offset:1024
	ds_read_b128 v[194:197], v157 offset:2048
	ds_read_b128 v[198:201], v157 offset:3072
	ds_read_b128 v[208:211], v157 offset:4096
	ds_read_b128 v[212:215], v157 offset:5120
	ds_read_b128 v[216:219], v157 offset:6144
	ds_read_b128 v[220:223], v157 offset:7168
	global_load_lds_dwordx4 v[202:203], off
	v_lshl_add_u64 v[202:203], s[54:55], 0, v[138:139]
	s_add_i32 m0, s34, 0xe000
	s_nop 0
	global_load_lds_dwordx4 v[202:203], off
	s_waitcnt vmcnt(8)
	s_waitcnt lgkmcnt(0)
	s_barrier
; #define PG8_STAGE(bufoff, gbase, voff) do { _Pragma("unroll") for (int _i = 0; _i < 2; ++_i) \
;         __builtin_amdgcn_global_load_lds((const unsigned*)((const char*)(gbase) + (voff)[_i]), (PG8_LAS unsigned*)(lds + (bufoff) + ldsw + _i * 8192), 16, 0, 0); } while (0)
; #define PG8_LDA(dst, b, h) do { _Pragma("unroll") for (int m = 0; m < 4; ++m) _Pragma("unroll") for (int k = 0; k < 2; ++k) dst[m][k] = *(const PG8_LAS bf16x8*)(lds + PG8_SA(b, h) + aoff + m * 2048 + k * 1024); } while (0)
; #define PG8_MMA(ai, bj, At, Bt) do { __builtin_amdgcn_s_setprio(1); _Pragma("unroll") for (int m = 0; m < 4; ++m) _Pragma("unroll") for (int n = 0; n < 2; ++n) _Pragma("unroll") for (int k = 0; k < 2; ++k) \
;         acc[ai][bj][m][n] = __builtin_amdgcn_mfma_f32_16x16x32_bf16(Bt[n][k], At[m][k], acc[ai][bj][m][n], 0, 0, 0); __builtin_amdgcn_s_setprio(0); } while (0)
; #define PG8_WAIT_V(n) asm volatile("s_waitcnt vmcnt(" #n ")" ::: "memory")
; #define PG8_WAIT_L(n) asm volatile("s_waitcnt lgkmcnt(" #n ")" ::: "memory")
; #define PG8_BAR __builtin_amdgcn_s_barrier()
; #define PG8_SCHED __builtin_amdgcn_sched_barrier(0)
; template <class Epi, class Sched, bool ALIGN_EPI = false, bool SP2 = false>
; __device__ __forceinline__ void gemm_phase(PG8_LAS unsigned char* lds, const Gemm g, const Sched& S, const Epi& E) {
;     ...
;             PG8_WAIT_V(8); PG8_WAIT_L(0); PG8_BAR; PG8_MMA(0, 0, At, B0); PG8_MMA(0, 1, At, B1); PG8_BAR; PG8_SCHED;
;             PG8_LDA(At, 0, 1); PG8_STAGE(PG8_SB(0, 0), b2, voffB); PG8_STAGE(PG8_SB(0, 1), b2 + hstep, voffB); PG8_STAGE(PG8_SA(0, 0), a2, voffA);
;             PG8_WAIT_V(8); PG8_WAIT_L(0); PG8_BAR; PG8_MMA(1, 0, At, B0); PG8_MMA(1, 1, At, B1); PG8_BAR; PG8_SCHED;
	s_setprio 1
	s_waitcnt lgkmcnt(0)
	v_mfma_f32_16x16x32_bf16 v[124:127], v[144:147], v[186:189], v[124:127]
	v_mfma_f32_16x16x32_bf16 v[120:123], v[160:163], v[186:189], v[120:123]
	v_mfma_f32_16x16x32_bf16 v[108:111], v[144:147], v[194:197], v[108:111]
	v_mfma_f32_16x16x32_bf16 v[104:107], v[160:163], v[194:197], v[104:107]
	v_mfma_f32_16x16x32_bf16 v[92:95], v[144:147], v[208:211], v[92:95]
	v_mfma_f32_16x16x32_bf16 v[88:91], v[160:163], v[208:211], v[88:91]
	v_mfma_f32_16x16x32_bf16 v[76:79], v[144:147], v[216:219], v[76:79]
	v_mfma_f32_16x16x32_bf16 v[72:75], v[160:163], v[216:219], v[72:75]
	v_mfma_f32_16x16x32_bf16 v[124:127], v[148:151], v[190:193], v[124:127]
	v_mfma_f32_16x16x32_bf16 v[120:123], v[164:167], v[190:193], v[120:123]
	v_mfma_f32_16x16x32_bf16 v[108:111], v[148:151], v[198:201], v[108:111]
	v_mfma_f32_16x16x32_bf16 v[104:107], v[164:167], v[198:201], v[104:107]
	v_mfma_f32_16x16x32_bf16 v[92:95], v[148:151], v[212:215], v[92:95]
	v_mfma_f32_16x16x32_bf16 v[88:91], v[164:167], v[212:215], v[88:91]
	v_mfma_f32_16x16x32_bf16 v[76:79], v[148:151], v[220:223], v[76:79]
	v_mfma_f32_16x16x32_bf16 v[72:75], v[164:167], v[220:223], v[72:75]
	s_setprio 0
	s_setprio 1
	v_mfma_f32_16x16x32_bf16 v[116:119], v[168:171], v[186:189], v[116:119]
	v_mfma_f32_16x16x32_bf16 v[112:115], v[176:179], v[186:189], v[112:115]
	v_mfma_f32_16x16x32_bf16 v[100:103], v[168:171], v[194:197], v[100:103]
	v_mfma_f32_16x16x32_bf16 v[96:99], v[176:179], v[194:197], v[96:99]
	v_mfma_f32_16x16x32_bf16 v[84:87], v[168:171], v[208:211], v[84:87]
	v_mfma_f32_16x16x32_bf16 v[80:83], v[176:179], v[208:211], v[80:83]
	v_mfma_f32_16x16x32_bf16 v[68:71], v[168:171], v[216:219], v[68:71]
	v_mfma_f32_16x16x32_bf16 v[64:67], v[176:179], v[216:219], v[64:67]
	v_mfma_f32_16x16x32_bf16 v[116:119], v[172:175], v[190:193], v[116:119]
	v_mfma_f32_16x16x32_bf16 v[112:115], v[182:185], v[190:193], v[112:115]
	v_mfma_f32_16x16x32_bf16 v[100:103], v[172:175], v[198:201], v[100:103]
	v_mfma_f32_16x16x32_bf16 v[96:99], v[182:185], v[198:201], v[96:99]
	v_mfma_f32_16x16x32_bf16 v[84:87], v[172:175], v[212:215], v[84:87]
	v_mfma_f32_16x16x32_bf16 v[80:83], v[182:185], v[212:215], v[80:83]
	v_mfma_f32_16x16x32_bf16 v[68:71], v[172:175], v[220:223], v[68:71]
	v_mfma_f32_16x16x32_bf16 v[64:67], v[182:185], v[220:223], v[64:67]
	s_setprio 0
	s_barrier
	s_add_i32 s3, s65, s14
	v_lshl_add_u64 v[202:203], s[56:57], 0, v[132:133]
	s_mov_b32 m0, s3
	ds_read_b128 v[186:189], v157 offset:16384
	ds_read_b128 v[190:193], v157 offset:17408
	ds_read_b128 v[194:197], v157 offset:18432
	ds_read_b128 v[198:201], v157 offset:19456
	ds_read_b128 v[208:211], v157 offset:20480
	ds_read_b128 v[212:215], v157 offset:21504
	ds_read_b128 v[216:219], v157 offset:22528
	ds_read_b128 v[220:223], v157 offset:23552
	global_load_lds_dwordx4 v[202:203], off
	s_add_i32 m0, s3, 0x2000
	s_add_u32 s78, s56, 0x40000
	v_lshl_add_u64 v[224:225], s[56:57], 0, v[128:129]
	s_addc_u32 s79, s57, 0
	s_add_i32 s3, s66, s14
	global_load_lds_dwordx4 v[224:225], off
	v_lshl_add_u64 v[226:227], s[78:79], 0, v[132:133]
	s_mov_b32 m0, s3
	global_load_lds_dwordx4 v[226:227], off
	v_lshl_add_u64 v[226:227], s[78:79], 0, v[128:129]
	s_add_i32 m0, s3, 0x2000
	s_nop 0
	global_load_lds_dwordx4 v[226:227], off
	s_waitcnt vmcnt(6)
	s_waitcnt lgkmcnt(0)
	s_barrier
	s_setprio 1
	s_waitcnt lgkmcnt(0)
	v_mfma_f32_16x16x32_bf16 v[60:63], v[144:147], v[186:189], v[60:63]
	v_mfma_f32_16x16x32_bf16 v[56:59], v[160:163], v[186:189], v[56:59]
	v_mfma_f32_16x16x32_bf16 v[44:47], v[144:147], v[194:197], v[44:47]
	v_mfma_f32_16x16x32_bf16 v[40:43], v[160:163], v[194:197], v[40:43]
	v_mfma_f32_16x16x32_bf16 v[28:31], v[144:147], v[208:211], v[28:31]
	v_mfma_f32_16x16x32_bf16 v[24:27], v[160:163], v[208:211], v[24:27]
	v_mfma_f32_16x16x32_bf16 v[12:15], v[144:147], v[216:219], v[12:15]
	v_mfma_f32_16x16x32_bf16 v[8:11], v[160:163], v[216:219], v[8:11]
	v_mfma_f32_16x16x32_bf16 v[60:63], v[148:151], v[190:193], v[60:63]
	v_mfma_f32_16x16x32_bf16 v[56:59], v[164:167], v[190:193], v[56:59]
	v_mfma_f32_16x16x32_bf16 v[44:47], v[148:151], v[198:201], v[44:47]
	v_mfma_f32_16x16x32_bf16 v[40:43], v[164:167], v[198:201], v[40:43]
	v_lshl_add_u64 v[226:227], s[58:59], 0, v[134:135]
	s_mov_b32 m0, s34
	s_nop 0
	global_load_lds_dwordx4 v[226:227], off
	v_mfma_f32_16x16x32_bf16 v[28:31], v[148:151], v[212:215], v[28:31]
	v_mfma_f32_16x16x32_bf16 v[24:27], v[164:167], v[212:215], v[24:27]
	v_mfma_f32_16x16x32_bf16 v[12:15], v[148:151], v[220:223], v[12:15]
	v_mfma_f32_16x16x32_bf16 v[8:11], v[164:167], v[220:223], v[8:11]
	s_setprio 0
	s_setprio 1
	v_mfma_f32_16x16x32_bf16 v[52:55], v[168:171], v[186:189], v[52:55]
	v_mfma_f32_16x16x32_bf16 v[48:51], v[176:179], v[186:189], v[48:51]
	v_mfma_f32_16x16x32_bf16 v[36:39], v[168:171], v[194:197], v[36:39]
	v_mfma_f32_16x16x32_bf16 v[32:35], v[176:179], v[194:197], v[32:35]
	v_mfma_f32_16x16x32_bf16 v[20:23], v[168:171], v[208:211], v[20:23]
	v_mfma_f32_16x16x32_bf16 v[16:19], v[176:179], v[208:211], v[16:19]
	v_mfma_f32_16x16x32_bf16 v[4:7], v[168:171], v[216:219], v[4:7]
	v_mfma_f32_16x16x32_bf16 v[0:3], v[176:179], v[216:219], v[0:3]
	v_mfma_f32_16x16x32_bf16 v[52:55], v[172:175], v[190:193], v[52:55]
	v_mfma_f32_16x16x32_bf16 v[48:51], v[182:185], v[190:193], v[48:51]
	v_mfma_f32_16x16x32_bf16 v[36:39], v[172:175], v[198:201], v[36:39]
	v_mfma_f32_16x16x32_bf16 v[32:35], v[182:185], v[198:201], v[32:35]
	v_lshl_add_u64 v[228:229], s[58:59], 0, v[130:131]
	s_mov_b32 m0, s53
	s_nop 0
	global_load_lds_dwordx4 v[228:229], off
	v_mfma_f32_16x16x32_bf16 v[20:23], v[172:175], v[212:215], v[20:23]
	v_mfma_f32_16x16x32_bf16 v[16:19], v[182:185], v[212:215], v[16:19]
	v_mfma_f32_16x16x32_bf16 v[4:7], v[172:175], v[220:223], v[4:7]
	v_mfma_f32_16x16x32_bf16 v[0:3], v[182:185], v[220:223], v[0:3]
	s_setprio 0
	s_barrier
; #define PG8_STAGE(bufoff, gbase, voff) do { _Pragma("unroll") for (int _i = 0; _i < 2; ++_i) \
;         __builtin_amdgcn_global_load_lds((const unsigned*)((const char*)(gbase) + (voff)[_i]), (PG8_LAS unsigned*)(lds + (bufoff) + ldsw + _i * 8192), 16, 0, 0); } while (0)
; #define PG8_LDA(dst, b, h) do { _Pragma("unroll") for (int m = 0; m < 4; ++m) _Pragma("unroll") for (int k = 0; k < 2; ++k) dst[m][k] = *(const PG8_LAS bf16x8*)(lds + PG8_SA(b, h) + aoff + m * 2048 + k * 1024); } while (0)
; #define PG8_LDB(dst, b, h) do { _Pragma("unroll") for (int n = 0; n < 2; ++n) _Pragma("unroll") for (int k = 0; k < 2; ++k) dst[n][k] = *(const PG8_LAS bf16x8*)(lds + PG8_SB(b, h) + boff + n * 2048 + k * 1024); } while (0)
; #define PG8_MMA(ai, bj, At, Bt) do { __builtin_amdgcn_s_setprio(1); _Pragma("unroll") for (int m = 0; m < 4; ++m) _Pragma("unroll") for (int n = 0; n < 2; ++n) _Pragma("unroll") for (int k = 0; k < 2; ++k) \
;         acc[ai][bj][m][n] = __builtin_amdgcn_mfma_f32_16x16x32_bf16(Bt[n][k], At[m][k], acc[ai][bj][m][n], 0, 0, 0); __builtin_amdgcn_s_setprio(0); } while (0)
; #define PG8_WAIT_V(n) asm volatile("s_waitcnt vmcnt(" #n ")" ::: "memory")
; #define PG8_WAIT_L(n) asm volatile("s_waitcnt lgkmcnt(" #n ")" ::: "memory")
; #define PG8_BAR __builtin_amdgcn_s_barrier()
; #define PG8_SCHED __builtin_amdgcn_sched_barrier(0)
; template <class Epi, class Sched, bool ALIGN_EPI = false, bool SP2 = false>
; __device__ __forceinline__ void gemm_phase(PG8_LAS unsigned char* lds, const Gemm g, const Sched& S, const Epi& E) {
;     ...
;             PG8_LDB(B0, 1, 0); PG8_LDB(B1, 1, 1); PG8_SCHED; PG8_LDA(At, 1, 0); PG8_STAGE(PG8_SA(0, 1), a2 + hstep, voffA);
;             PG8_WAIT_V(8); PG8_WAIT_L(0); PG8_BAR; PG8_MMA(0, 0, At, B0); PG8_MMA(0, 1, At, B1); PG8_BAR; PG8_SCHED;
	s_add_i32 s3, 0, 0x18000
	v_add_u32_e32 v159, s3, v153
	s_add_i32 s33, 0, 0x1c000
	ds_read_b128 v[144:147], v159
	ds_read_b128 v[148:151], v159 offset:1024
	ds_read_b128 v[160:163], v159 offset:2048
	ds_read_b128 v[164:167], v159 offset:3072
	v_add_u32_e32 v159, s33, v153
	ds_read_b128 v[168:171], v159
	ds_read_b128 v[172:175], v159 offset:1024
	ds_read_b128 v[176:179], v159 offset:2048
	ds_read_b128 v[182:185], v159 offset:3072
	s_add_u32 s58, s58, 0x40000
	s_addc_u32 s59, s59, 0
	s_mov_b32 m0, s60
	v_lshl_add_u64 v[230:231], s[58:59], 0, v[134:135]
	ds_read_b128 v[186:189], v157 offset:32768
	ds_read_b128 v[190:193], v157 offset:33792
	ds_read_b128 v[194:197], v157 offset:34816
	ds_read_b128 v[198:201], v157 offset:35840
	ds_read_b128 v[208:211], v157 offset:36864
	ds_read_b128 v[212:215], v157 offset:37888
	ds_read_b128 v[216:219], v157 offset:38912
	ds_read_b128 v[220:223], v157 offset:39936
	global_load_lds_dwordx4 v[230:231], off
	v_lshl_add_u64 v[230:231], s[58:59], 0, v[130:131]
	s_mov_b32 m0, s61
	s_nop 0
	global_load_lds_dwordx4 v[230:231], off
	s_waitcnt vmcnt(8)
	s_waitcnt lgkmcnt(0)
	s_barrier
	s_setprio 1
	s_waitcnt lgkmcnt(0)
	v_mfma_f32_16x16x32_bf16 v[124:127], v[144:147], v[186:189], v[124:127]
	v_mfma_f32_16x16x32_bf16 v[120:123], v[160:163], v[186:189], v[120:123]
	v_mfma_f32_16x16x32_bf16 v[108:111], v[144:147], v[194:197], v[108:111]
	v_mfma_f32_16x16x32_bf16 v[104:107], v[160:163], v[194:197], v[104:107]
	v_mfma_f32_16x16x32_bf16 v[92:95], v[144:147], v[208:211], v[92:95]
	v_mfma_f32_16x16x32_bf16 v[88:91], v[160:163], v[208:211], v[88:91]
	v_mfma_f32_16x16x32_bf16 v[76:79], v[144:147], v[216:219], v[76:79]
	v_mfma_f32_16x16x32_bf16 v[72:75], v[160:163], v[216:219], v[72:75]
	v_mfma_f32_16x16x32_bf16 v[124:127], v[148:151], v[190:193], v[124:127]
	v_mfma_f32_16x16x32_bf16 v[120:123], v[164:167], v[190:193], v[120:123]
	v_mfma_f32_16x16x32_bf16 v[108:111], v[148:151], v[198:201], v[108:111]
	v_mfma_f32_16x16x32_bf16 v[104:107], v[164:167], v[198:201], v[104:107]
	v_mfma_f32_16x16x32_bf16 v[92:95], v[148:151], v[212:215], v[92:95]
	v_mfma_f32_16x16x32_bf16 v[88:91], v[164:167], v[212:215], v[88:91]
	v_mfma_f32_16x16x32_bf16 v[76:79], v[148:151], v[220:223], v[76:79]
	v_mfma_f32_16x16x32_bf16 v[72:75], v[164:167], v[220:223], v[72:75]
	s_setprio 0
	s_setprio 1
	v_mfma_f32_16x16x32_bf16 v[116:119], v[168:171], v[186:189], v[116:119]
	v_mfma_f32_16x16x32_bf16 v[112:115], v[176:179], v[186:189], v[112:115]
	v_mfma_f32_16x16x32_bf16 v[100:103], v[168:171], v[194:197], v[100:103]
	v_mfma_f32_16x16x32_bf16 v[96:99], v[176:179], v[194:197], v[96:99]
	v_mfma_f32_16x16x32_bf16 v[84:87], v[168:171], v[208:211], v[84:87]
	v_mfma_f32_16x16x32_bf16 v[80:83], v[176:179], v[208:211], v[80:83]
	v_mfma_f32_16x16x32_bf16 v[68:71], v[168:171], v[216:219], v[68:71]
	v_mfma_f32_16x16x32_bf16 v[64:67], v[176:179], v[216:219], v[64:67]
	v_mfma_f32_16x16x32_bf16 v[116:119], v[172:175], v[190:193], v[116:119]
	v_mfma_f32_16x16x32_bf16 v[112:115], v[182:185], v[190:193], v[112:115]
	v_mfma_f32_16x16x32_bf16 v[100:103], v[172:175], v[198:201], v[100:103]
	v_mfma_f32_16x16x32_bf16 v[96:99], v[182:185], v[198:201], v[96:99]
	v_mfma_f32_16x16x32_bf16 v[84:87], v[172:175], v[212:215], v[84:87]
	v_mfma_f32_16x16x32_bf16 v[80:83], v[182:185], v[212:215], v[80:83]
	v_mfma_f32_16x16x32_bf16 v[68:71], v[172:175], v[220:223], v[68:71]
	v_mfma_f32_16x16x32_bf16 v[64:67], v[182:185], v[220:223], v[64:67]
	s_setprio 0
	s_barrier
; #define PG8_STAGE(bufoff, gbase, voff) do { _Pragma("unroll") for (int _i = 0; _i < 2; ++_i) \
;         __builtin_amdgcn_global_load_lds((const unsigned*)((const char*)(gbase) + (voff)[_i]), (PG8_LAS unsigned*)(lds + (bufoff) + ldsw + _i * 8192), 16, 0, 0); } while (0)
; #define PG8_LDA(dst, b, h) do { _Pragma("unroll") for (int m = 0; m < 4; ++m) _Pragma("unroll") for (int k = 0; k < 2; ++k) dst[m][k] = *(const PG8_LAS bf16x8*)(lds + PG8_SA(b, h) + aoff + m * 2048 + k * 1024); } while (0)
; #define PG8_MMA(ai, bj, At, Bt) do { __builtin_amdgcn_s_setprio(1); _Pragma("unroll") for (int m = 0; m < 4; ++m) _Pragma("unroll") for (int n = 0; n < 2; ++n) _Pragma("unroll") for (int k = 0; k < 2; ++k) \
;         acc[ai][bj][m][n] = __builtin_amdgcn_mfma_f32_16x16x32_bf16(Bt[n][k], At[m][k], acc[ai][bj][m][n], 0, 0, 0); __builtin_amdgcn_s_setprio(0); } while (0)
; #define PG8_WAIT_V(n) asm volatile("s_waitcnt vmcnt(" #n ")" ::: "memory")
; #define PG8_WAIT_L(n) asm volatile("s_waitcnt lgkmcnt(" #n ")" ::: "memory")
; #define PG8_BAR __builtin_amdgcn_s_barrier()
; #define PG8_SCHED __builtin_amdgcn_sched_barrier(0)
;     __device__ __forceinline__ void operator()(const f32x4 (&acc)[2][2][4][2], const Unit& u, int wr, int wc, int fr, int fq) const {
;     ...
;             for (int m = 0; m < 4; ++m) { const int row = row0 + ai * HALF + m * 16; const float rs = row_rs(ss, row);
; template <class Epi, class Sched, bool ALIGN_EPI = false, bool SP2 = false>
; __device__ __forceinline__ void gemm_phase(PG8_LAS unsigned char* lds, const Gemm g, const Sched& S, const Epi& E) {
;     ...
;             PG8_LDA(At, 1, 1); PG8_STAGE(PG8_SB(1, 0), b3, voffB); PG8_STAGE(PG8_SB(1, 1), b3 + hstep, voffB); PG8_STAGE(PG8_SA(1, 0), a3, voffA);
;             PG8_WAIT_V(8); PG8_WAIT_L(0); PG8_BAR; PG8_MMA(1, 0, At, B0); PG8_MMA(1, 1, At, B1); PG8_BAR; PG8_SCHED;
	s_add_i32 s3, s3, s14
	v_lshl_add_u64 v[202:203], v[202:203], 0, s[36:37]
	s_mov_b32 m0, s3
	ds_read_b128 v[186:189], v157 offset:49152
	ds_read_b128 v[190:193], v157 offset:50176
	ds_read_b128 v[194:197], v157 offset:51200
	ds_read_b128 v[198:201], v157 offset:52224
	ds_read_b128 v[208:211], v157 offset:53248
	ds_read_b128 v[212:215], v157 offset:54272
	ds_read_b128 v[216:219], v157 offset:55296
	ds_read_b128 v[220:223], v157 offset:56320
	global_load_lds_dwordx4 v[202:203], off
	s_add_i32 m0, s3, 0x2000
	s_add_u32 s56, s56, 0x40080
	v_lshl_add_u64 v[202:203], v[224:225], 0, s[36:37]
	s_addc_u32 s57, s57, 0
	s_add_i32 s3, s33, s14
	global_load_lds_dwordx4 v[202:203], off
	v_lshl_add_u64 v[202:203], s[56:57], 0, v[132:133]
	s_mov_b32 m0, s3
	s_nop 0
	global_load_lds_dwordx4 v[202:203], off
	v_lshl_add_u64 v[202:203], s[56:57], 0, v[128:129]
	s_add_i32 m0, s3, 0x2000
	s_nop 0
	global_load_lds_dwordx4 v[202:203], off
	s_waitcnt vmcnt(6)
	s_waitcnt lgkmcnt(0)
	s_barrier
	s_setprio 1
	s_waitcnt lgkmcnt(0)
	v_mfma_f32_16x16x32_bf16 v[60:63], v[144:147], v[186:189], v[60:63]
	v_mfma_f32_16x16x32_bf16 v[56:59], v[160:163], v[186:189], v[56:59]
	v_mfma_f32_16x16x32_bf16 v[44:47], v[144:147], v[194:197], v[44:47]
	v_mfma_f32_16x16x32_bf16 v[40:43], v[160:163], v[194:197], v[40:43]
	v_mfma_f32_16x16x32_bf16 v[28:31], v[144:147], v[208:211], v[28:31]
	v_mfma_f32_16x16x32_bf16 v[24:27], v[160:163], v[208:211], v[24:27]
	v_mfma_f32_16x16x32_bf16 v[12:15], v[144:147], v[216:219], v[12:15]
	v_mfma_f32_16x16x32_bf16 v[8:11], v[160:163], v[216:219], v[8:11]
	v_mfma_f32_16x16x32_bf16 v[60:63], v[148:151], v[190:193], v[60:63]
	v_mfma_f32_16x16x32_bf16 v[56:59], v[164:167], v[190:193], v[56:59]
	v_mfma_f32_16x16x32_bf16 v[44:47], v[148:151], v[198:201], v[44:47]
	v_mfma_f32_16x16x32_bf16 v[40:43], v[164:167], v[198:201], v[40:43]
	v_lshl_add_u64 v[202:203], v[226:227], 0, s[36:37]
	s_mov_b32 m0, s63
	s_nop 0
	global_load_lds_dwordx4 v[202:203], off
	v_mfma_f32_16x16x32_bf16 v[28:31], v[148:151], v[212:215], v[28:31]
	v_mfma_f32_16x16x32_bf16 v[24:27], v[164:167], v[212:215], v[24:27]
	v_mfma_f32_16x16x32_bf16 v[12:15], v[148:151], v[220:223], v[12:15]
	v_mfma_f32_16x16x32_bf16 v[8:11], v[164:167], v[220:223], v[8:11]
	s_setprio 0
	s_setprio 1
	v_mfma_f32_16x16x32_bf16 v[52:55], v[168:171], v[186:189], v[52:55]
	v_mfma_f32_16x16x32_bf16 v[48:51], v[176:179], v[186:189], v[48:51]
	v_mfma_f32_16x16x32_bf16 v[36:39], v[168:171], v[194:197], v[36:39]
	v_mfma_f32_16x16x32_bf16 v[32:35], v[176:179], v[194:197], v[32:35]
	v_mfma_f32_16x16x32_bf16 v[20:23], v[168:171], v[208:211], v[20:23]
	v_mfma_f32_16x16x32_bf16 v[16:19], v[176:179], v[208:211], v[16:19]
	v_mfma_f32_16x16x32_bf16 v[4:7], v[168:171], v[216:219], v[4:7]
	v_mfma_f32_16x16x32_bf16 v[0:3], v[176:179], v[216:219], v[0:3]
	v_mfma_f32_16x16x32_bf16 v[52:55], v[172:175], v[190:193], v[52:55]
	v_mfma_f32_16x16x32_bf16 v[48:51], v[182:185], v[190:193], v[48:51]
	v_mfma_f32_16x16x32_bf16 v[36:39], v[172:175], v[198:201], v[36:39]
	v_mfma_f32_16x16x32_bf16 v[32:35], v[182:185], v[198:201], v[32:35]
	v_lshl_add_u64 v[202:203], v[228:229], 0, s[36:37]
	s_mov_b32 m0, s64
	s_nop 0
	global_load_lds_dwordx4 v[202:203], off
	v_mfma_f32_16x16x32_bf16 v[20:23], v[172:175], v[212:215], v[20:23]
	v_mfma_f32_16x16x32_bf16 v[16:19], v[182:185], v[212:215], v[16:19]
	v_mfma_f32_16x16x32_bf16 v[4:7], v[172:175], v[220:223], v[4:7]
	v_mfma_f32_16x16x32_bf16 v[0:3], v[182:185], v[220:223], v[0:3]
	s_setprio 0
	s_barrier
	s_add_i32 s83, s83, 2
	s_add_u32 s54, s54, 0x100
	s_addc_u32 s55, s55, 0
	s_add_u32 s77, s77, 0x100
	s_addc_u32 s82, s82, 0
	s_cmp_gt_u32 s83, 13
	s_cbranch_scc0 .LBB0_957
	v_lshl_add_u32 v144, s52, 8, v152
	v_ashrrev_i32_e32 v145, 31, v144
	v_lshl_add_u64 v[150:151], v[144:145], 3, s[0:1]
	global_load_dwordx2 v[182:183], v[150:151], off
	global_load_dwordx2 v[184:185], v[150:151], off offset:128
	global_load_dwordx2 v[186:187], v[150:151], off offset:256
	global_load_dwordx2 v[188:189], v[150:151], off offset:384
	global_load_dwordx2 v[190:191], v[150:151], off offset:1024
	global_load_dwordx2 v[192:193], v[150:151], off offset:1152
	global_load_dwordx2 v[194:195], v[150:151], off offset:1280
	global_load_dwordx2 v[196:197], v[150:151], off offset:1408
	s_and_b64 vcc, exec, s[38:39]
	s_cbranch_vccz .LBB0_960
	s_barrier

; #define PG8_STAGE(bufoff, gbase, voff) do { _Pragma("unroll") for (int _i = 0; _i < 2; ++_i) \
;         __builtin_amdgcn_global_load_lds((const unsigned*)((const char*)(gbase) + (voff)[_i]), (PG8_LAS unsigned*)(lds + (bufoff) + ldsw + _i * 8192), 16, 0, 0); } while (0)
; #define PG8_LDA(dst, b, h) do { _Pragma("unroll") for (int m = 0; m < 4; ++m) _Pragma("unroll") for (int k = 0; k < 2; ++k) dst[m][k] = *(const PG8_LAS bf16x8*)(lds + PG8_SA(b, h) + aoff + m * 2048 + k * 1024); } while (0)
; #define PG8_LDB(dst, b, h) do { _Pragma("unroll") for (int n = 0; n < 2; ++n) _Pragma("unroll") for (int k = 0; k < 2; ++k) dst[n][k] = *(const PG8_LAS bf16x8*)(lds + PG8_SB(b, h) + boff + n * 2048 + k * 1024); } while (0)
; #define PG8_MMA(ai, bj, At, Bt) do { __builtin_amdgcn_s_setprio(1); _Pragma("unroll") for (int m = 0; m < 4; ++m) _Pragma("unroll") for (int n = 0; n < 2; ++n) _Pragma("unroll") for (int k = 0; k < 2; ++k) \
;         acc[ai][bj][m][n] = __builtin_amdgcn_mfma_f32_16x16x32_bf16(Bt[n][k], At[m][k], acc[ai][bj][m][n], 0, 0, 0); __builtin_amdgcn_s_setprio(0); } while (0)
; #define PG8_BAR __builtin_amdgcn_s_barrier()
; template <class Epi, class Sched, bool ALIGN_EPI = false, bool SP2 = false>
; __device__ __forceinline__ void gemm_phase(PG8_LAS unsigned char* lds, const Gemm g, const Sched& S, const Epi& E) {
;     ...
;         const bool has_next = S.next(ui + 1, nxt);
;         const char* nA = has_next ? (const char*)g.A + (size_t)nxt.pm * tstep : cA; const char* nB = has_next ? (const char*)g.Bt + (size_t)nxt.pn * tstep : cB;
;         for (int t = 0; t < nt; t += 2) {
;             const bool last = (t == nt - 2);
;             const char* a1 = cA + (size_t)(t + 1) * kstep;
;             const char* a2 = last ? nA : cA + (size_t)(t + 2) * kstep; const char* b2 = last ? nB : cB + (size_t)(t + 2) * kstep;
;             const char* a3 = a2 + kstep; const char* b3 = b2 + kstep;
;             if (last && has_next) S.a_ready(nxt);
;             if constexpr (SP2) {
;             PG8_LDB(B0, 0, 0); PG8_LDB(B1, 0, 1); PG8_SCHED; PG8_LDA(At, 0, 0); PG8_STAGE(PG8_SA(1, 1), a1 + hstep, voffA);
;             PG8_WAIT_V(8); PG8_WAIT_L(0); PG8_BAR; PG8_MMA(0, 0, At, B0); PG8_MMA(0, 1, At, B1); PG8_BAR; PG8_SCHED;
;             PG8_LDA(At, 0, 1); PG8_STAGE(PG8_SB(0, 0), b2, voffB); PG8_STAGE(PG8_SB(0, 1), b2 + hstep, voffB); PG8_STAGE(PG8_SA(0, 0), a2, voffA);
.LBB0_1034:
	s_add_u32 s75, s52, 0x100
	s_addc_u32 s76, s53, 0
	s_mov_b32 s77, -2
	s_waitcnt lgkmcnt(0)
	ds_read_b128 v[144:147], v151
	ds_read_b128 v[156:159], v151 offset:1024
	ds_read_b128 v[160:163], v151 offset:2048
	ds_read_b128 v[164:167], v151 offset:3072
	ds_read_b128 v[168:171], v152
	ds_read_b128 v[172:175], v152 offset:1024
	ds_read_b128 v[176:179], v152 offset:2048
	ds_read_b128 v[182:185], v152 offset:3072
	s_add_u32 s52, s50, 0x100
	s_addc_u32 s53, s51, 0
	s_cmp_eq_u32 s77, 40
	s_cselect_b32 s57, s1, s53
	s_cselect_b32 s56, s0, s52
	s_cselect_b32 s55, s49, s76
	s_cselect_b32 s54, s48, s75
	v_lshl_add_u64 v[202:203], s[50:51], 0, v[136:137]
	s_add_i32 m0, s14, 0xc000
	ds_read_b128 v[186:189], v153
	ds_read_b128 v[190:193], v153 offset:1024
	ds_read_b128 v[194:197], v153 offset:2048
	ds_read_b128 v[198:201], v153 offset:3072
	ds_read_b128 v[208:211], v153 offset:4096
	ds_read_b128 v[212:215], v153 offset:5120
	ds_read_b128 v[216:219], v153 offset:6144
	ds_read_b128 v[220:223], v153 offset:7168
	global_load_lds_dwordx4 v[202:203], off
	v_lshl_add_u64 v[202:203], s[50:51], 0, v[138:139]
	s_add_i32 m0, s14, 0xe000
	s_nop 0
	global_load_lds_dwordx4 v[202:203], off
	s_waitcnt vmcnt(8)
	s_waitcnt lgkmcnt(0)
	s_barrier
	s_setprio 1
	s_waitcnt lgkmcnt(0)
	v_mfma_f32_16x16x32_bf16 v[124:127], v[144:147], v[186:189], 0
	v_mfma_f32_16x16x32_bf16 v[120:123], v[160:163], v[186:189], 0
	v_mfma_f32_16x16x32_bf16 v[108:111], v[144:147], v[194:197], 0
	v_mfma_f32_16x16x32_bf16 v[104:107], v[160:163], v[194:197], 0
	v_mfma_f32_16x16x32_bf16 v[92:95], v[144:147], v[208:211], 0
	v_mfma_f32_16x16x32_bf16 v[88:91], v[160:163], v[208:211], 0
	v_mfma_f32_16x16x32_bf16 v[76:79], v[144:147], v[216:219], 0
	v_mfma_f32_16x16x32_bf16 v[72:75], v[160:163], v[216:219], 0
	v_mfma_f32_16x16x32_bf16 v[124:127], v[156:159], v[190:193], v[124:127]
	v_mfma_f32_16x16x32_bf16 v[120:123], v[164:167], v[190:193], v[120:123]
	v_mfma_f32_16x16x32_bf16 v[108:111], v[156:159], v[198:201], v[108:111]
	v_mfma_f32_16x16x32_bf16 v[104:107], v[164:167], v[198:201], v[104:107]
	v_mfma_f32_16x16x32_bf16 v[92:95], v[156:159], v[212:215], v[92:95]
	v_mfma_f32_16x16x32_bf16 v[88:91], v[164:167], v[212:215], v[88:91]
	v_mfma_f32_16x16x32_bf16 v[76:79], v[156:159], v[220:223], v[76:79]
	v_mfma_f32_16x16x32_bf16 v[72:75], v[164:167], v[220:223], v[72:75]
	s_setprio 0
	s_setprio 1
	v_mfma_f32_16x16x32_bf16 v[116:119], v[168:171], v[186:189], 0
	v_mfma_f32_16x16x32_bf16 v[112:115], v[176:179], v[186:189], 0
	v_mfma_f32_16x16x32_bf16 v[100:103], v[168:171], v[194:197], 0
	v_mfma_f32_16x16x32_bf16 v[96:99], v[176:179], v[194:197], 0
	v_mfma_f32_16x16x32_bf16 v[84:87], v[168:171], v[208:211], 0
	v_mfma_f32_16x16x32_bf16 v[80:83], v[176:179], v[208:211], 0
	v_mfma_f32_16x16x32_bf16 v[68:71], v[168:171], v[216:219], 0
	v_mfma_f32_16x16x32_bf16 v[64:67], v[176:179], v[216:219], 0
	v_mfma_f32_16x16x32_bf16 v[116:119], v[172:175], v[190:193], v[116:119]
	v_mfma_f32_16x16x32_bf16 v[112:115], v[182:185], v[190:193], v[112:115]
	v_mfma_f32_16x16x32_bf16 v[100:103], v[172:175], v[198:201], v[100:103]
	v_mfma_f32_16x16x32_bf16 v[96:99], v[182:185], v[198:201], v[96:99]
	v_mfma_f32_16x16x32_bf16 v[84:87], v[172:175], v[212:215], v[84:87]
	v_mfma_f32_16x16x32_bf16 v[80:83], v[182:185], v[212:215], v[80:83]
	v_mfma_f32_16x16x32_bf16 v[68:71], v[172:175], v[220:223], v[68:71]
	v_mfma_f32_16x16x32_bf16 v[64:67], v[182:185], v[220:223], v[64:67]
	s_setprio 0
	s_barrier
	s_add_i32 s50, s61, s3
	v_lshl_add_u64 v[202:203], s[54:55], 0, v[130:131]
	s_mov_b32 m0, s50
	ds_read_b128 v[186:189], v153 offset:16384
	ds_read_b128 v[190:193], v153 offset:17408
	ds_read_b128 v[194:197], v153 offset:18432
	ds_read_b128 v[198:201], v153 offset:19456
	ds_read_b128 v[208:211], v153 offset:20480
	ds_read_b128 v[212:215], v153 offset:21504
	ds_read_b128 v[216:219], v153 offset:22528
	ds_read_b128 v[220:223], v153 offset:23552
	global_load_lds_dwordx4 v[202:203], off
	s_add_i32 m0, s50, 0x2000
	s_add_u32 s50, s54, 0xb0000
	v_lshl_add_u64 v[224:225], s[54:55], 0, v[134:135]
	s_addc_u32 s51, s55, 0
	s_add_i32 s78, s62, s3
	global_load_lds_dwordx4 v[224:225], off
	v_lshl_add_u64 v[226:227], s[50:51], 0, v[130:131]
	s_mov_b32 m0, s78
	global_load_lds_dwordx4 v[226:227], off
	v_lshl_add_u64 v[226:227], s[50:51], 0, v[134:135]
	s_add_i32 m0, s78, 0x2000
	s_nop 0
	global_load_lds_dwordx4 v[226:227], off
	s_waitcnt vmcnt(6)
	s_waitcnt lgkmcnt(0)
	s_barrier
; #define PG8_STAGE(bufoff, gbase, voff) do { _Pragma("unroll") for (int _i = 0; _i < 2; ++_i) \
;         __builtin_amdgcn_global_load_lds((const unsigned*)((const char*)(gbase) + (voff)[_i]), (PG8_LAS unsigned*)(lds + (bufoff) + ldsw + _i * 8192), 16, 0, 0); } while (0)
; #define PG8_LDA(dst, b, h) do { _Pragma("unroll") for (int m = 0; m < 4; ++m) _Pragma("unroll") for (int k = 0; k < 2; ++k) dst[m][k] = *(const PG8_LAS bf16x8*)(lds + PG8_SA(b, h) + aoff + m * 2048 + k * 1024); } while (0)
; #define PG8_LDB(dst, b, h) do { _Pragma("unroll") for (int n = 0; n < 2; ++n) _Pragma("unroll") for (int k = 0; k < 2; ++k) dst[n][k] = *(const PG8_LAS bf16x8*)(lds + PG8_SB(b, h) + boff + n * 2048 + k * 1024); } while (0)
; #define PG8_MMA(ai, bj, At, Bt) do { __builtin_amdgcn_s_setprio(1); _Pragma("unroll") for (int m = 0; m < 4; ++m) _Pragma("unroll") for (int n = 0; n < 2; ++n) _Pragma("unroll") for (int k = 0; k < 2; ++k) \
;         acc[ai][bj][m][n] = __builtin_amdgcn_mfma_f32_16x16x32_bf16(Bt[n][k], At[m][k], acc[ai][bj][m][n], 0, 0, 0); __builtin_amdgcn_s_setprio(0); } while (0)
; #define PG8_WAIT_V(n) asm volatile("s_waitcnt vmcnt(" #n ")" ::: "memory")
; #define PG8_WAIT_L(n) asm volatile("s_waitcnt lgkmcnt(" #n ")" ::: "memory")
; #define PG8_BAR __builtin_amdgcn_s_barrier()
; #define PG8_SCHED __builtin_amdgcn_sched_barrier(0)
; template <class Epi, class Sched, bool ALIGN_EPI = false, bool SP2 = false>
; __device__ __forceinline__ void gemm_phase(PG8_LAS unsigned char* lds, const Gemm g, const Sched& S, const Epi& E) {
;     ...
;             PG8_WAIT_V(8); PG8_WAIT_L(0); PG8_BAR; PG8_MMA(1, 0, At, B0); PG8_MMA(1, 1, At, B1); PG8_BAR; PG8_SCHED;
;             PG8_LDB(B0, 1, 0); PG8_LDB(B1, 1, 1); PG8_SCHED; PG8_LDA(At, 1, 0); PG8_STAGE(PG8_SA(0, 1), a2 + hstep, voffA);
;             PG8_WAIT_V(8); PG8_WAIT_L(0); PG8_BAR; PG8_MMA(0, 0, At, B0); PG8_MMA(0, 1, At, B1); PG8_BAR; PG8_SCHED;
	s_setprio 1
	s_waitcnt lgkmcnt(0)
	v_mfma_f32_16x16x32_bf16 v[60:63], v[144:147], v[186:189], 0
	v_mfma_f32_16x16x32_bf16 v[56:59], v[160:163], v[186:189], 0
	v_mfma_f32_16x16x32_bf16 v[44:47], v[144:147], v[194:197], 0
	v_mfma_f32_16x16x32_bf16 v[40:43], v[160:163], v[194:197], 0
	v_mfma_f32_16x16x32_bf16 v[28:31], v[144:147], v[208:211], 0
	v_mfma_f32_16x16x32_bf16 v[24:27], v[160:163], v[208:211], 0
	v_mfma_f32_16x16x32_bf16 v[12:15], v[144:147], v[216:219], 0
	v_mfma_f32_16x16x32_bf16 v[8:11], v[160:163], v[216:219], 0
	v_mfma_f32_16x16x32_bf16 v[60:63], v[156:159], v[190:193], v[60:63]
	v_mfma_f32_16x16x32_bf16 v[56:59], v[164:167], v[190:193], v[56:59]
	v_mfma_f32_16x16x32_bf16 v[44:47], v[156:159], v[198:201], v[44:47]
	v_mfma_f32_16x16x32_bf16 v[40:43], v[164:167], v[198:201], v[40:43]
	v_lshl_add_u64 v[226:227], s[56:57], 0, v[128:129]
	s_mov_b32 m0, s14
	s_nop 0
	global_load_lds_dwordx4 v[226:227], off
	v_mfma_f32_16x16x32_bf16 v[28:31], v[156:159], v[212:215], v[28:31]
	v_mfma_f32_16x16x32_bf16 v[24:27], v[164:167], v[212:215], v[24:27]
	v_mfma_f32_16x16x32_bf16 v[12:15], v[156:159], v[220:223], v[12:15]
	v_mfma_f32_16x16x32_bf16 v[8:11], v[164:167], v[220:223], v[8:11]
	s_setprio 0
	s_setprio 1
	v_mfma_f32_16x16x32_bf16 v[52:55], v[168:171], v[186:189], 0
	v_mfma_f32_16x16x32_bf16 v[48:51], v[176:179], v[186:189], 0
	v_mfma_f32_16x16x32_bf16 v[36:39], v[168:171], v[194:197], 0
	v_mfma_f32_16x16x32_bf16 v[32:35], v[176:179], v[194:197], 0
	v_mfma_f32_16x16x32_bf16 v[20:23], v[168:171], v[208:211], 0
	v_mfma_f32_16x16x32_bf16 v[16:19], v[176:179], v[208:211], 0
	v_mfma_f32_16x16x32_bf16 v[4:7], v[168:171], v[216:219], 0
	v_mfma_f32_16x16x32_bf16 v[0:3], v[176:179], v[216:219], 0
	v_mfma_f32_16x16x32_bf16 v[52:55], v[172:175], v[190:193], v[52:55]
	v_mfma_f32_16x16x32_bf16 v[48:51], v[182:185], v[190:193], v[48:51]
	v_mfma_f32_16x16x32_bf16 v[36:39], v[172:175], v[198:201], v[36:39]
	v_mfma_f32_16x16x32_bf16 v[32:35], v[182:185], v[198:201], v[32:35]
	v_lshl_add_u64 v[228:229], s[56:57], 0, v[132:133]
	s_mov_b32 m0, s15
	s_nop 0
	global_load_lds_dwordx4 v[228:229], off
	v_mfma_f32_16x16x32_bf16 v[20:23], v[172:175], v[212:215], v[20:23]
	v_mfma_f32_16x16x32_bf16 v[16:19], v[182:185], v[212:215], v[16:19]
	v_mfma_f32_16x16x32_bf16 v[4:7], v[172:175], v[220:223], v[4:7]
	v_mfma_f32_16x16x32_bf16 v[0:3], v[182:185], v[220:223], v[0:3]
	s_setprio 0
	s_barrier
	s_add_i32 s78, 0, 0x18000
	v_add_u32_e32 v155, s78, v149
	s_add_i32 s79, 0, 0x1c000
	ds_read_b128 v[144:147], v155
	ds_read_b128 v[156:159], v155 offset:1024
	ds_read_b128 v[160:163], v155 offset:2048
	ds_read_b128 v[164:167], v155 offset:3072
	v_add_u32_e32 v155, s79, v149
	ds_read_b128 v[168:171], v155
	ds_read_b128 v[172:175], v155 offset:1024
	ds_read_b128 v[176:179], v155 offset:2048
	ds_read_b128 v[182:185], v155 offset:3072
	s_add_u32 s50, s56, 0xb0000
	s_addc_u32 s51, s57, 0
	s_mov_b32 m0, s33
	v_lshl_add_u64 v[230:231], s[50:51], 0, v[128:129]
	ds_read_b128 v[186:189], v153 offset:32768
	ds_read_b128 v[190:193], v153 offset:33792
	ds_read_b128 v[194:197], v153 offset:34816
	ds_read_b128 v[198:201], v153 offset:35840
	ds_read_b128 v[208:211], v153 offset:36864
	ds_read_b128 v[212:215], v153 offset:37888
	ds_read_b128 v[216:219], v153 offset:38912
	ds_read_b128 v[220:223], v153 offset:39936
	global_load_lds_dwordx4 v[230:231], off
	v_lshl_add_u64 v[230:231], s[50:51], 0, v[132:133]
	s_mov_b32 m0, s34
	s_nop 0
	global_load_lds_dwordx4 v[230:231], off
	s_waitcnt vmcnt(8)
	s_waitcnt lgkmcnt(0)
	s_barrier
	s_setprio 1
	s_waitcnt lgkmcnt(0)
	v_mfma_f32_16x16x32_bf16 v[124:127], v[144:147], v[186:189], v[124:127]
	v_mfma_f32_16x16x32_bf16 v[120:123], v[160:163], v[186:189], v[120:123]
	v_mfma_f32_16x16x32_bf16 v[108:111], v[144:147], v[194:197], v[108:111]
	v_mfma_f32_16x16x32_bf16 v[104:107], v[160:163], v[194:197], v[104:107]
	v_mfma_f32_16x16x32_bf16 v[92:95], v[144:147], v[208:211], v[92:95]
	v_mfma_f32_16x16x32_bf16 v[88:91], v[160:163], v[208:211], v[88:91]
	v_mfma_f32_16x16x32_bf16 v[76:79], v[144:147], v[216:219], v[76:79]
	v_mfma_f32_16x16x32_bf16 v[72:75], v[160:163], v[216:219], v[72:75]
	v_mfma_f32_16x16x32_bf16 v[124:127], v[156:159], v[190:193], v[124:127]
	v_mfma_f32_16x16x32_bf16 v[120:123], v[164:167], v[190:193], v[120:123]
	v_mfma_f32_16x16x32_bf16 v[108:111], v[156:159], v[198:201], v[108:111]
	v_mfma_f32_16x16x32_bf16 v[104:107], v[164:167], v[198:201], v[104:107]
	v_mfma_f32_16x16x32_bf16 v[92:95], v[156:159], v[212:215], v[92:95]
	v_mfma_f32_16x16x32_bf16 v[88:91], v[164:167], v[212:215], v[88:91]
	v_mfma_f32_16x16x32_bf16 v[76:79], v[156:159], v[220:223], v[76:79]
	v_mfma_f32_16x16x32_bf16 v[72:75], v[164:167], v[220:223], v[72:75]
	s_setprio 0
	s_setprio 1
	v_mfma_f32_16x16x32_bf16 v[116:119], v[168:171], v[186:189], v[116:119]
	v_mfma_f32_16x16x32_bf16 v[112:115], v[176:179], v[186:189], v[112:115]
	v_mfma_f32_16x16x32_bf16 v[100:103], v[168:171], v[194:197], v[100:103]
	v_mfma_f32_16x16x32_bf16 v[96:99], v[176:179], v[194:197], v[96:99]
	v_mfma_f32_16x16x32_bf16 v[84:87], v[168:171], v[208:211], v[84:87]
	v_mfma_f32_16x16x32_bf16 v[80:83], v[176:179], v[208:211], v[80:83]
	v_mfma_f32_16x16x32_bf16 v[68:71], v[168:171], v[216:219], v[68:71]
	v_mfma_f32_16x16x32_bf16 v[64:67], v[176:179], v[216:219], v[64:67]
	v_mfma_f32_16x16x32_bf16 v[116:119], v[172:175], v[190:193], v[116:119]
	v_mfma_f32_16x16x32_bf16 v[112:115], v[182:185], v[190:193], v[112:115]
	v_mfma_f32_16x16x32_bf16 v[100:103], v[172:175], v[198:201], v[100:103]
	v_mfma_f32_16x16x32_bf16 v[96:99], v[182:185], v[198:201], v[96:99]
	v_mfma_f32_16x16x32_bf16 v[84:87], v[172:175], v[212:215], v[84:87]
	v_mfma_f32_16x16x32_bf16 v[80:83], v[182:185], v[212:215], v[80:83]
	v_mfma_f32_16x16x32_bf16 v[68:71], v[172:175], v[220:223], v[68:71]
	v_mfma_f32_16x16x32_bf16 v[64:67], v[182:185], v[220:223], v[64:67]
	s_setprio 0
	s_barrier
; #define PG8_STAGE(bufoff, gbase, voff) do { _Pragma("unroll") for (int _i = 0; _i < 2; ++_i) \
;         __builtin_amdgcn_global_load_lds((const unsigned*)((const char*)(gbase) + (voff)[_i]), (PG8_LAS unsigned*)(lds + (bufoff) + ldsw + _i * 8192), 16, 0, 0); } while (0)
; #define PG8_LDA(dst, b, h) do { _Pragma("unroll") for (int m = 0; m < 4; ++m) _Pragma("unroll") for (int k = 0; k < 2; ++k) dst[m][k] = *(const PG8_LAS bf16x8*)(lds + PG8_SA(b, h) + aoff + m * 2048 + k * 1024); } while (0)
; #define PG8_LDB(dst, b, h) do { _Pragma("unroll") for (int n = 0; n < 2; ++n) _Pragma("unroll") for (int k = 0; k < 2; ++k) dst[n][k] = *(const PG8_LAS bf16x8*)(lds + PG8_SB(b, h) + boff + n * 2048 + k * 1024); } while (0)
; #define PG8_MMA(ai, bj, At, Bt) do { __builtin_amdgcn_s_setprio(1); _Pragma("unroll") for (int m = 0; m < 4; ++m) _Pragma("unroll") for (int n = 0; n < 2; ++n) _Pragma("unroll") for (int k = 0; k < 2; ++k) \
;         acc[ai][bj][m][n] = __builtin_amdgcn_mfma_f32_16x16x32_bf16(Bt[n][k], At[m][k], acc[ai][bj][m][n], 0, 0, 0); __builtin_amdgcn_s_setprio(0); } while (0)
; #define PG8_WAIT_V(n) asm volatile("s_waitcnt vmcnt(" #n ")" ::: "memory")
; template <class Epi, class Sched, bool ALIGN_EPI = false, bool SP2 = false>
; __device__ __forceinline__ void gemm_phase(PG8_LAS unsigned char* lds, const Gemm g, const Sched& S, const Epi& E) {
;     ...
;             PG8_LDB(B0, 0, 0); PG8_LDB(B1, 0, 1); PG8_SCHED; PG8_LDA(At, 0, 0); PG8_STAGE(PG8_SA(1, 1), a1 + hstep, voffA);
;             PG8_WAIT_V(8); PG8_WAIT_L(0); PG8_BAR; PG8_MMA(0, 0, At, B0); PG8_MMA(0, 1, At, B1); PG8_BAR; PG8_SCHED;
;             PG8_LDA(At, 0, 1); PG8_STAGE(PG8_SB(0, 0), b2, voffB); PG8_STAGE(PG8_SB(0, 1), b2 + hstep, voffB); PG8_STAGE(PG8_SA(0, 0), a2, voffA);
;             PG8_WAIT_V(8); PG8_WAIT_L(0); PG8_BAR; PG8_MMA(1, 0, At, B0); PG8_MMA(1, 1, At, B1); PG8_BAR; PG8_SCHED;
;             PG8_LDB(B0, 1, 0); PG8_LDB(B1, 1, 1); PG8_SCHED; PG8_LDA(At, 1, 0); PG8_STAGE(PG8_SA(0, 1), a2 + hstep, voffA);
;             PG8_WAIT_V(8); PG8_WAIT_L(0); PG8_BAR; PG8_MMA(0, 0, At, B0); PG8_MMA(0, 1, At, B1); PG8_BAR; PG8_SCHED;
;             PG8_LDA(At, 1, 1); PG8_STAGE(PG8_SB(1, 0), b3, voffB); PG8_STAGE(PG8_SB(1, 1), b3 + hstep, voffB); PG8_STAGE(PG8_SA(1, 0), a3, voffA);
;             PG8_WAIT_V(8); PG8_WAIT_L(0); PG8_BAR; PG8_MMA(1, 0, At, B0); PG8_MMA(1, 1, At, B1); PG8_BAR; PG8_SCHED;
	s_add_i32 s50, s78, s3
	v_lshl_add_u64 v[202:203], v[202:203], 0, s[42:43]
	s_mov_b32 m0, s50
	ds_read_b128 v[186:189], v153 offset:49152
	ds_read_b128 v[190:193], v153 offset:50176
	ds_read_b128 v[194:197], v153 offset:51200
	ds_read_b128 v[198:201], v153 offset:52224
	ds_read_b128 v[208:211], v153 offset:53248
	ds_read_b128 v[212:215], v153 offset:54272
	ds_read_b128 v[216:219], v153 offset:55296
	ds_read_b128 v[220:223], v153 offset:56320
	global_load_lds_dwordx4 v[202:203], off
	s_add_i32 m0, s50, 0x2000
	s_add_u32 s50, s54, 0xb0080
	v_lshl_add_u64 v[202:203], v[224:225], 0, s[42:43]
	s_addc_u32 s51, s55, 0
	s_add_i32 s54, s79, s3
	global_load_lds_dwordx4 v[202:203], off
	v_lshl_add_u64 v[202:203], s[50:51], 0, v[130:131]
	s_mov_b32 m0, s54
	s_nop 0
	global_load_lds_dwordx4 v[202:203], off
	v_lshl_add_u64 v[202:203], s[50:51], 0, v[134:135]
	s_add_i32 m0, s54, 0x2000
	s_nop 0
	global_load_lds_dwordx4 v[202:203], off
	s_waitcnt vmcnt(6)
	s_waitcnt lgkmcnt(0)
	s_barrier
	s_setprio 1
	s_waitcnt lgkmcnt(0)
	v_mfma_f32_16x16x32_bf16 v[60:63], v[144:147], v[186:189], v[60:63]
	v_mfma_f32_16x16x32_bf16 v[56:59], v[160:163], v[186:189], v[56:59]
	v_mfma_f32_16x16x32_bf16 v[44:47], v[144:147], v[194:197], v[44:47]
	v_mfma_f32_16x16x32_bf16 v[40:43], v[160:163], v[194:197], v[40:43]
	v_mfma_f32_16x16x32_bf16 v[28:31], v[144:147], v[208:211], v[28:31]
	v_mfma_f32_16x16x32_bf16 v[24:27], v[160:163], v[208:211], v[24:27]
	v_mfma_f32_16x16x32_bf16 v[12:15], v[144:147], v[216:219], v[12:15]
	v_mfma_f32_16x16x32_bf16 v[8:11], v[160:163], v[216:219], v[8:11]
	v_mfma_f32_16x16x32_bf16 v[60:63], v[156:159], v[190:193], v[60:63]
	v_mfma_f32_16x16x32_bf16 v[56:59], v[164:167], v[190:193], v[56:59]
	v_mfma_f32_16x16x32_bf16 v[44:47], v[156:159], v[198:201], v[44:47]
	v_mfma_f32_16x16x32_bf16 v[40:43], v[164:167], v[198:201], v[40:43]
	v_lshl_add_u64 v[202:203], v[226:227], 0, s[42:43]
	s_mov_b32 m0, s59
	s_nop 0
	global_load_lds_dwordx4 v[202:203], off
	v_mfma_f32_16x16x32_bf16 v[28:31], v[156:159], v[212:215], v[28:31]
	v_mfma_f32_16x16x32_bf16 v[24:27], v[164:167], v[212:215], v[24:27]
	v_mfma_f32_16x16x32_bf16 v[12:15], v[156:159], v[220:223], v[12:15]
	v_mfma_f32_16x16x32_bf16 v[8:11], v[164:167], v[220:223], v[8:11]
	s_setprio 0
	s_setprio 1
	v_mfma_f32_16x16x32_bf16 v[52:55], v[168:171], v[186:189], v[52:55]
	v_mfma_f32_16x16x32_bf16 v[48:51], v[176:179], v[186:189], v[48:51]
	v_mfma_f32_16x16x32_bf16 v[36:39], v[168:171], v[194:197], v[36:39]
	v_mfma_f32_16x16x32_bf16 v[32:35], v[176:179], v[194:197], v[32:35]
	v_mfma_f32_16x16x32_bf16 v[20:23], v[168:171], v[208:211], v[20:23]
	v_mfma_f32_16x16x32_bf16 v[16:19], v[176:179], v[208:211], v[16:19]
	v_mfma_f32_16x16x32_bf16 v[4:7], v[168:171], v[216:219], v[4:7]
	v_mfma_f32_16x16x32_bf16 v[0:3], v[176:179], v[216:219], v[0:3]
	v_mfma_f32_16x16x32_bf16 v[52:55], v[172:175], v[190:193], v[52:55]
	v_mfma_f32_16x16x32_bf16 v[48:51], v[182:185], v[190:193], v[48:51]
	v_mfma_f32_16x16x32_bf16 v[36:39], v[172:175], v[198:201], v[36:39]
	v_mfma_f32_16x16x32_bf16 v[32:35], v[182:185], v[198:201], v[32:35]
	v_lshl_add_u64 v[202:203], v[228:229], 0, s[42:43]
	s_mov_b32 m0, s60
	s_nop 0
	global_load_lds_dwordx4 v[202:203], off
	v_mfma_f32_16x16x32_bf16 v[20:23], v[172:175], v[212:215], v[20:23]
	v_mfma_f32_16x16x32_bf16 v[16:19], v[182:185], v[212:215], v[16:19]
	v_mfma_f32_16x16x32_bf16 v[4:7], v[172:175], v[220:223], v[4:7]
	v_mfma_f32_16x16x32_bf16 v[0:3], v[182:185], v[220:223], v[0:3]
	s_setprio 0
	s_barrier
	s_add_i32 s77, s77, 2
	s_add_u32 s75, s75, 0x100
	s_addc_u32 s76, s76, 0
	s_mov_b64 s[50:51], s[52:53]
.LBB0_1035:
	ds_read_b128 v[144:147], v151
	ds_read_b128 v[156:159], v151 offset:1024
	ds_read_b128 v[160:163], v151 offset:2048
	ds_read_b128 v[164:167], v151 offset:3072
	ds_read_b128 v[168:171], v152
	ds_read_b128 v[172:175], v152 offset:1024
	ds_read_b128 v[176:179], v152 offset:2048
	ds_read_b128 v[182:185], v152 offset:3072
	s_add_u32 s52, s50, 0x100
	s_addc_u32 s53, s51, 0
	s_cmp_eq_u32 s77, 40
	s_cselect_b32 s57, s1, s53
	s_cselect_b32 s56, s0, s52
	s_cselect_b32 s55, s49, s76
	s_cselect_b32 s54, s48, s75
	v_lshl_add_u64 v[202:203], s[50:51], 0, v[136:137]
	s_add_i32 m0, s14, 0xc000
	ds_read_b128 v[186:189], v153
	ds_read_b128 v[190:193], v153 offset:1024
	ds_read_b128 v[194:197], v153 offset:2048
	ds_read_b128 v[198:201], v153 offset:3072
	ds_read_b128 v[208:211], v153 offset:4096
	ds_read_b128 v[212:215], v153 offset:5120
	ds_read_b128 v[216:219], v153 offset:6144
	ds_read_b128 v[220:223], v153 offset:7168
	global_load_lds_dwordx4 v[202:203], off
	v_lshl_add_u64 v[202:203], s[50:51], 0, v[138:139]
	s_add_i32 m0, s14, 0xe000
	s_nop 0
	global_load_lds_dwordx4 v[202:203], off
	s_waitcnt vmcnt(8)
	s_waitcnt lgkmcnt(0)
	s_barrier
; #define PG8_STAGE(bufoff, gbase, voff) do { _Pragma("unroll") for (int _i = 0; _i < 2; ++_i) \
;         __builtin_amdgcn_global_load_lds((const unsigned*)((const char*)(gbase) + (voff)[_i]), (PG8_LAS unsigned*)(lds + (bufoff) + ldsw + _i * 8192), 16, 0, 0); } while (0)
; #define PG8_LDA(dst, b, h) do { _Pragma("unroll") for (int m = 0; m < 4; ++m) _Pragma("unroll") for (int k = 0; k < 2; ++k) dst[m][k] = *(const PG8_LAS bf16x8*)(lds + PG8_SA(b, h) + aoff + m * 2048 + k * 1024); } while (0)
; #define PG8_MMA(ai, bj, At, Bt) do { __builtin_amdgcn_s_setprio(1); _Pragma("unroll") for (int m = 0; m < 4; ++m) _Pragma("unroll") for (int n = 0; n < 2; ++n) _Pragma("unroll") for (int k = 0; k < 2; ++k) \
;         acc[ai][bj][m][n] = __builtin_amdgcn_mfma_f32_16x16x32_bf16(Bt[n][k], At[m][k], acc[ai][bj][m][n], 0, 0, 0); __builtin_amdgcn_s_setprio(0); } while (0)
; #define PG8_WAIT_V(n) asm volatile("s_waitcnt vmcnt(" #n ")" ::: "memory")
; #define PG8_WAIT_L(n) asm volatile("s_waitcnt lgkmcnt(" #n ")" ::: "memory")
; #define PG8_BAR __builtin_amdgcn_s_barrier()
; #define PG8_SCHED __builtin_amdgcn_sched_barrier(0)
; template <class Epi, class Sched, bool ALIGN_EPI = false, bool SP2 = false>
; __device__ __forceinline__ void gemm_phase(PG8_LAS unsigned char* lds, const Gemm g, const Sched& S, const Epi& E) {
;     ...
;             PG8_WAIT_V(8); PG8_WAIT_L(0); PG8_BAR; PG8_MMA(0, 0, At, B0); PG8_MMA(0, 1, At, B1); PG8_BAR; PG8_SCHED;
;             PG8_LDA(At, 0, 1); PG8_STAGE(PG8_SB(0, 0), b2, voffB); PG8_STAGE(PG8_SB(0, 1), b2 + hstep, voffB); PG8_STAGE(PG8_SA(0, 0), a2, voffA);
;             PG8_WAIT_V(8); PG8_WAIT_L(0); PG8_BAR; PG8_MMA(1, 0, At, B0); PG8_MMA(1, 1, At, B1); PG8_BAR; PG8_SCHED;
	s_setprio 1
	s_waitcnt lgkmcnt(0)
	v_mfma_f32_16x16x32_bf16 v[124:127], v[144:147], v[186:189], v[124:127]
	v_mfma_f32_16x16x32_bf16 v[120:123], v[160:163], v[186:189], v[120:123]
	v_mfma_f32_16x16x32_bf16 v[108:111], v[144:147], v[194:197], v[108:111]
	v_mfma_f32_16x16x32_bf16 v[104:107], v[160:163], v[194:197], v[104:107]
	v_mfma_f32_16x16x32_bf16 v[92:95], v[144:147], v[208:211], v[92:95]
	v_mfma_f32_16x16x32_bf16 v[88:91], v[160:163], v[208:211], v[88:91]
	v_mfma_f32_16x16x32_bf16 v[76:79], v[144:147], v[216:219], v[76:79]
	v_mfma_f32_16x16x32_bf16 v[72:75], v[160:163], v[216:219], v[72:75]
	v_mfma_f32_16x16x32_bf16 v[124:127], v[156:159], v[190:193], v[124:127]
	v_mfma_f32_16x16x32_bf16 v[120:123], v[164:167], v[190:193], v[120:123]
	v_mfma_f32_16x16x32_bf16 v[108:111], v[156:159], v[198:201], v[108:111]
	v_mfma_f32_16x16x32_bf16 v[104:107], v[164:167], v[198:201], v[104:107]
	v_mfma_f32_16x16x32_bf16 v[92:95], v[156:159], v[212:215], v[92:95]
	v_mfma_f32_16x16x32_bf16 v[88:91], v[164:167], v[212:215], v[88:91]
	v_mfma_f32_16x16x32_bf16 v[76:79], v[156:159], v[220:223], v[76:79]
	v_mfma_f32_16x16x32_bf16 v[72:75], v[164:167], v[220:223], v[72:75]
	s_setprio 0
	s_setprio 1
	v_mfma_f32_16x16x32_bf16 v[116:119], v[168:171], v[186:189], v[116:119]
	v_mfma_f32_16x16x32_bf16 v[112:115], v[176:179], v[186:189], v[112:115]
	v_mfma_f32_16x16x32_bf16 v[100:103], v[168:171], v[194:197], v[100:103]
	v_mfma_f32_16x16x32_bf16 v[96:99], v[176:179], v[194:197], v[96:99]
	v_mfma_f32_16x16x32_bf16 v[84:87], v[168:171], v[208:211], v[84:87]
	v_mfma_f32_16x16x32_bf16 v[80:83], v[176:179], v[208:211], v[80:83]
	v_mfma_f32_16x16x32_bf16 v[68:71], v[168:171], v[216:219], v[68:71]
	v_mfma_f32_16x16x32_bf16 v[64:67], v[176:179], v[216:219], v[64:67]
	v_mfma_f32_16x16x32_bf16 v[116:119], v[172:175], v[190:193], v[116:119]
	v_mfma_f32_16x16x32_bf16 v[112:115], v[182:185], v[190:193], v[112:115]
	v_mfma_f32_16x16x32_bf16 v[100:103], v[172:175], v[198:201], v[100:103]
	v_mfma_f32_16x16x32_bf16 v[96:99], v[182:185], v[198:201], v[96:99]
	v_mfma_f32_16x16x32_bf16 v[84:87], v[172:175], v[212:215], v[84:87]
	v_mfma_f32_16x16x32_bf16 v[80:83], v[182:185], v[212:215], v[80:83]
	v_mfma_f32_16x16x32_bf16 v[68:71], v[172:175], v[220:223], v[68:71]
	v_mfma_f32_16x16x32_bf16 v[64:67], v[182:185], v[220:223], v[64:67]
	s_setprio 0
	s_barrier
	s_add_i32 s50, s61, s3
	v_lshl_add_u64 v[202:203], s[54:55], 0, v[130:131]
	s_mov_b32 m0, s50
	ds_read_b128 v[186:189], v153 offset:16384
	ds_read_b128 v[190:193], v153 offset:17408
	ds_read_b128 v[194:197], v153 offset:18432
	ds_read_b128 v[198:201], v153 offset:19456
	ds_read_b128 v[208:211], v153 offset:20480
	ds_read_b128 v[212:215], v153 offset:21504
	ds_read_b128 v[216:219], v153 offset:22528
	ds_read_b128 v[220:223], v153 offset:23552
	global_load_lds_dwordx4 v[202:203], off
	s_add_i32 m0, s50, 0x2000
	s_add_u32 s50, s54, 0xb0000
	v_lshl_add_u64 v[224:225], s[54:55], 0, v[134:135]
	s_addc_u32 s51, s55, 0
	s_add_i32 s78, s62, s3
	global_load_lds_dwordx4 v[224:225], off
	v_lshl_add_u64 v[226:227], s[50:51], 0, v[130:131]
	s_mov_b32 m0, s78
	global_load_lds_dwordx4 v[226:227], off
	v_lshl_add_u64 v[226:227], s[50:51], 0, v[134:135]
	s_add_i32 m0, s78, 0x2000
	s_nop 0
	global_load_lds_dwordx4 v[226:227], off
	s_waitcnt vmcnt(6)
	s_waitcnt lgkmcnt(0)
	s_barrier
	s_setprio 1
	s_waitcnt lgkmcnt(0)
	v_mfma_f32_16x16x32_bf16 v[60:63], v[144:147], v[186:189], v[60:63]
	v_mfma_f32_16x16x32_bf16 v[56:59], v[160:163], v[186:189], v[56:59]
	v_mfma_f32_16x16x32_bf16 v[44:47], v[144:147], v[194:197], v[44:47]
	v_mfma_f32_16x16x32_bf16 v[40:43], v[160:163], v[194:197], v[40:43]
	v_mfma_f32_16x16x32_bf16 v[28:31], v[144:147], v[208:211], v[28:31]
	v_mfma_f32_16x16x32_bf16 v[24:27], v[160:163], v[208:211], v[24:27]
	v_mfma_f32_16x16x32_bf16 v[12:15], v[144:147], v[216:219], v[12:15]
	v_mfma_f32_16x16x32_bf16 v[8:11], v[160:163], v[216:219], v[8:11]
	v_mfma_f32_16x16x32_bf16 v[60:63], v[156:159], v[190:193], v[60:63]
	v_mfma_f32_16x16x32_bf16 v[56:59], v[164:167], v[190:193], v[56:59]
	v_mfma_f32_16x16x32_bf16 v[44:47], v[156:159], v[198:201], v[44:47]
	v_mfma_f32_16x16x32_bf16 v[40:43], v[164:167], v[198:201], v[40:43]
	v_lshl_add_u64 v[226:227], s[56:57], 0, v[128:129]
	s_mov_b32 m0, s14
	s_nop 0
	global_load_lds_dwordx4 v[226:227], off
	v_mfma_f32_16x16x32_bf16 v[28:31], v[156:159], v[212:215], v[28:31]
	v_mfma_f32_16x16x32_bf16 v[24:27], v[164:167], v[212:215], v[24:27]
	v_mfma_f32_16x16x32_bf16 v[12:15], v[156:159], v[220:223], v[12:15]
	v_mfma_f32_16x16x32_bf16 v[8:11], v[164:167], v[220:223], v[8:11]
	s_setprio 0
	s_setprio 1
	v_mfma_f32_16x16x32_bf16 v[52:55], v[168:171], v[186:189], v[52:55]
	v_mfma_f32_16x16x32_bf16 v[48:51], v[176:179], v[186:189], v[48:51]
	v_mfma_f32_16x16x32_bf16 v[36:39], v[168:171], v[194:197], v[36:39]
	v_mfma_f32_16x16x32_bf16 v[32:35], v[176:179], v[194:197], v[32:35]
	v_mfma_f32_16x16x32_bf16 v[20:23], v[168:171], v[208:211], v[20:23]
	v_mfma_f32_16x16x32_bf16 v[16:19], v[176:179], v[208:211], v[16:19]
	v_mfma_f32_16x16x32_bf16 v[4:7], v[168:171], v[216:219], v[4:7]
	v_mfma_f32_16x16x32_bf16 v[0:3], v[176:179], v[216:219], v[0:3]
	v_mfma_f32_16x16x32_bf16 v[52:55], v[172:175], v[190:193], v[52:55]
	v_mfma_f32_16x16x32_bf16 v[48:51], v[182:185], v[190:193], v[48:51]
	v_mfma_f32_16x16x32_bf16 v[36:39], v[172:175], v[198:201], v[36:39]
	v_mfma_f32_16x16x32_bf16 v[32:35], v[182:185], v[198:201], v[32:35]
	v_lshl_add_u64 v[228:229], s[56:57], 0, v[132:133]
	s_mov_b32 m0, s15
	s_nop 0
	global_load_lds_dwordx4 v[228:229], off
	v_mfma_f32_16x16x32_bf16 v[20:23], v[172:175], v[212:215], v[20:23]
	v_mfma_f32_16x16x32_bf16 v[16:19], v[182:185], v[212:215], v[16:19]
	v_mfma_f32_16x16x32_bf16 v[4:7], v[172:175], v[220:223], v[4:7]
	v_mfma_f32_16x16x32_bf16 v[0:3], v[182:185], v[220:223], v[0:3]
	s_setprio 0
	s_barrier
; #define PG8_STAGE(bufoff, gbase, voff) do { _Pragma("unroll") for (int _i = 0; _i < 2; ++_i) \
;         __builtin_amdgcn_global_load_lds((const unsigned*)((const char*)(gbase) + (voff)[_i]), (PG8_LAS unsigned*)(lds + (bufoff) + ldsw + _i * 8192), 16, 0, 0); } while (0)
; #define PG8_LDA(dst, b, h) do { _Pragma("unroll") for (int m = 0; m < 4; ++m) _Pragma("unroll") for (int k = 0; k < 2; ++k) dst[m][k] = *(const PG8_LAS bf16x8*)(lds + PG8_SA(b, h) + aoff + m * 2048 + k * 1024); } while (0)
; #define PG8_LDB(dst, b, h) do { _Pragma("unroll") for (int n = 0; n < 2; ++n) _Pragma("unroll") for (int k = 0; k < 2; ++k) dst[n][k] = *(const PG8_LAS bf16x8*)(lds + PG8_SB(b, h) + boff + n * 2048 + k * 1024); } while (0)
; #define PG8_MMA(ai, bj, At, Bt) do { __builtin_amdgcn_s_setprio(1); _Pragma("unroll") for (int m = 0; m < 4; ++m) _Pragma("unroll") for (int n = 0; n < 2; ++n) _Pragma("unroll") for (int k = 0; k < 2; ++k) \
;         acc[ai][bj][m][n] = __builtin_amdgcn_mfma_f32_16x16x32_bf16(Bt[n][k], At[m][k], acc[ai][bj][m][n], 0, 0, 0); __builtin_amdgcn_s_setprio(0); } while (0)
; #define PG8_WAIT_V(n) asm volatile("s_waitcnt vmcnt(" #n ")" ::: "memory")
; #define PG8_WAIT_L(n) asm volatile("s_waitcnt lgkmcnt(" #n ")" ::: "memory")
; #define PG8_BAR __builtin_amdgcn_s_barrier()
; #define PG8_SCHED __builtin_amdgcn_sched_barrier(0)
; template <class Epi, class Sched, bool ALIGN_EPI = false, bool SP2 = false>
; __device__ __forceinline__ void gemm_phase(PG8_LAS unsigned char* lds, const Gemm g, const Sched& S, const Epi& E) {
;     ...
;             PG8_LDB(B0, 1, 0); PG8_LDB(B1, 1, 1); PG8_SCHED; PG8_LDA(At, 1, 0); PG8_STAGE(PG8_SA(0, 1), a2 + hstep, voffA);
;             PG8_WAIT_V(8); PG8_WAIT_L(0); PG8_BAR; PG8_MMA(0, 0, At, B0); PG8_MMA(0, 1, At, B1); PG8_BAR; PG8_SCHED;
	s_add_i32 s78, 0, 0x18000
	v_add_u32_e32 v155, s78, v149
	s_add_i32 s79, 0, 0x1c000
	ds_read_b128 v[144:147], v155
	ds_read_b128 v[156:159], v155 offset:1024
	ds_read_b128 v[160:163], v155 offset:2048
	ds_read_b128 v[164:167], v155 offset:3072
	v_add_u32_e32 v155, s79, v149
	ds_read_b128 v[168:171], v155
	ds_read_b128 v[172:175], v155 offset:1024
	ds_read_b128 v[176:179], v155 offset:2048
	ds_read_b128 v[182:185], v155 offset:3072
	s_add_u32 s50, s56, 0xb0000
	s_addc_u32 s51, s57, 0
	s_mov_b32 m0, s33
	v_lshl_add_u64 v[230:231], s[50:51], 0, v[128:129]
	ds_read_b128 v[186:189], v153 offset:32768
	ds_read_b128 v[190:193], v153 offset:33792
	ds_read_b128 v[194:197], v153 offset:34816
	ds_read_b128 v[198:201], v153 offset:35840
	ds_read_b128 v[208:211], v153 offset:36864
	ds_read_b128 v[212:215], v153 offset:37888
	ds_read_b128 v[216:219], v153 offset:38912
	ds_read_b128 v[220:223], v153 offset:39936
	global_load_lds_dwordx4 v[230:231], off
	v_lshl_add_u64 v[230:231], s[50:51], 0, v[132:133]
	s_mov_b32 m0, s34
	s_nop 0
	global_load_lds_dwordx4 v[230:231], off
	s_waitcnt vmcnt(8)
	s_waitcnt lgkmcnt(0)
	s_barrier
	s_setprio 1
	s_waitcnt lgkmcnt(0)
	v_mfma_f32_16x16x32_bf16 v[124:127], v[144:147], v[186:189], v[124:127]
	v_mfma_f32_16x16x32_bf16 v[120:123], v[160:163], v[186:189], v[120:123]
	v_mfma_f32_16x16x32_bf16 v[108:111], v[144:147], v[194:197], v[108:111]
	v_mfma_f32_16x16x32_bf16 v[104:107], v[160:163], v[194:197], v[104:107]
	v_mfma_f32_16x16x32_bf16 v[92:95], v[144:147], v[208:211], v[92:95]
	v_mfma_f32_16x16x32_bf16 v[88:91], v[160:163], v[208:211], v[88:91]
	v_mfma_f32_16x16x32_bf16 v[76:79], v[144:147], v[216:219], v[76:79]
	v_mfma_f32_16x16x32_bf16 v[72:75], v[160:163], v[216:219], v[72:75]
	v_mfma_f32_16x16x32_bf16 v[124:127], v[156:159], v[190:193], v[124:127]
	v_mfma_f32_16x16x32_bf16 v[120:123], v[164:167], v[190:193], v[120:123]
	v_mfma_f32_16x16x32_bf16 v[108:111], v[156:159], v[198:201], v[108:111]
	v_mfma_f32_16x16x32_bf16 v[104:107], v[164:167], v[198:201], v[104:107]
	v_mfma_f32_16x16x32_bf16 v[92:95], v[156:159], v[212:215], v[92:95]
	v_mfma_f32_16x16x32_bf16 v[88:91], v[164:167], v[212:215], v[88:91]
	v_mfma_f32_16x16x32_bf16 v[76:79], v[156:159], v[220:223], v[76:79]
	v_mfma_f32_16x16x32_bf16 v[72:75], v[164:167], v[220:223], v[72:75]
	s_setprio 0
	s_setprio 1
	v_mfma_f32_16x16x32_bf16 v[116:119], v[168:171], v[186:189], v[116:119]
	v_mfma_f32_16x16x32_bf16 v[112:115], v[176:179], v[186:189], v[112:115]
	v_mfma_f32_16x16x32_bf16 v[100:103], v[168:171], v[194:197], v[100:103]
	v_mfma_f32_16x16x32_bf16 v[96:99], v[176:179], v[194:197], v[96:99]
	v_mfma_f32_16x16x32_bf16 v[84:87], v[168:171], v[208:211], v[84:87]
	v_mfma_f32_16x16x32_bf16 v[80:83], v[176:179], v[208:211], v[80:83]
	v_mfma_f32_16x16x32_bf16 v[68:71], v[168:171], v[216:219], v[68:71]
	v_mfma_f32_16x16x32_bf16 v[64:67], v[176:179], v[216:219], v[64:67]
	v_mfma_f32_16x16x32_bf16 v[116:119], v[172:175], v[190:193], v[116:119]
	v_mfma_f32_16x16x32_bf16 v[112:115], v[182:185], v[190:193], v[112:115]
	v_mfma_f32_16x16x32_bf16 v[100:103], v[172:175], v[198:201], v[100:103]
	v_mfma_f32_16x16x32_bf16 v[96:99], v[182:185], v[198:201], v[96:99]
	v_mfma_f32_16x16x32_bf16 v[84:87], v[172:175], v[212:215], v[84:87]
	v_mfma_f32_16x16x32_bf16 v[80:83], v[182:185], v[212:215], v[80:83]
	v_mfma_f32_16x16x32_bf16 v[68:71], v[172:175], v[220:223], v[68:71]
	v_mfma_f32_16x16x32_bf16 v[64:67], v[182:185], v[220:223], v[64:67]
	s_setprio 0
	s_barrier
; #define PG8_STAGE(bufoff, gbase, voff) do { _Pragma("unroll") for (int _i = 0; _i < 2; ++_i) \
;         __builtin_amdgcn_global_load_lds((const unsigned*)((const char*)(gbase) + (voff)[_i]), (PG8_LAS unsigned*)(lds + (bufoff) + ldsw + _i * 8192), 16, 0, 0); } while (0)
; #define PG8_LDA(dst, b, h) do { _Pragma("unroll") for (int m = 0; m < 4; ++m) _Pragma("unroll") for (int k = 0; k < 2; ++k) dst[m][k] = *(const PG8_LAS bf16x8*)(lds + PG8_SA(b, h) + aoff + m * 2048 + k * 1024); } while (0)
; #define PG8_MMA(ai, bj, At, Bt) do { __builtin_amdgcn_s_setprio(1); _Pragma("unroll") for (int m = 0; m < 4; ++m) _Pragma("unroll") for (int n = 0; n < 2; ++n) _Pragma("unroll") for (int k = 0; k < 2; ++k) \
;         acc[ai][bj][m][n] = __builtin_amdgcn_mfma_f32_16x16x32_bf16(Bt[n][k], At[m][k], acc[ai][bj][m][n], 0, 0, 0); __builtin_amdgcn_s_setprio(0); } while (0)
; #define PG8_WAIT_V(n) asm volatile("s_waitcnt vmcnt(" #n ")" ::: "memory")
; #define PG8_WAIT_L(n) asm volatile("s_waitcnt lgkmcnt(" #n ")" ::: "memory")
; #define PG8_BAR __builtin_amdgcn_s_barrier()
; #define PG8_SCHED __builtin_amdgcn_sched_barrier(0)
; template <class Epi, class Sched, bool ALIGN_EPI = false, bool SP2 = false>
; __device__ __forceinline__ void gemm_phase(PG8_LAS unsigned char* lds, const Gemm g, const Sched& S, const Epi& E) {
;     ...
;             PG8_LDA(At, 1, 1); PG8_STAGE(PG8_SB(1, 0), b3, voffB); PG8_STAGE(PG8_SB(1, 1), b3 + hstep, voffB); PG8_STAGE(PG8_SA(1, 0), a3, voffA);
;             PG8_WAIT_V(8); PG8_WAIT_L(0); PG8_BAR; PG8_MMA(1, 0, At, B0); PG8_MMA(1, 1, At, B1); PG8_BAR; PG8_SCHED;
;     ...
;         if constexpr (ALIGN_EPI) { if (wr == 0) PG8_BAR; }
	s_add_i32 s50, s78, s3
	v_lshl_add_u64 v[202:203], v[202:203], 0, s[42:43]
	s_mov_b32 m0, s50
	ds_read_b128 v[186:189], v153 offset:49152
	ds_read_b128 v[190:193], v153 offset:50176
	ds_read_b128 v[194:197], v153 offset:51200
	ds_read_b128 v[198:201], v153 offset:52224
	ds_read_b128 v[208:211], v153 offset:53248
	ds_read_b128 v[212:215], v153 offset:54272
	ds_read_b128 v[216:219], v153 offset:55296
	ds_read_b128 v[220:223], v153 offset:56320
	global_load_lds_dwordx4 v[202:203], off
	s_add_i32 m0, s50, 0x2000
	s_add_u32 s50, s54, 0xb0080
	v_lshl_add_u64 v[202:203], v[224:225], 0, s[42:43]
	s_addc_u32 s51, s55, 0
	s_add_i32 s54, s79, s3
	global_load_lds_dwordx4 v[202:203], off
	v_lshl_add_u64 v[202:203], s[50:51], 0, v[130:131]
	s_mov_b32 m0, s54
	s_nop 0
	global_load_lds_dwordx4 v[202:203], off
	v_lshl_add_u64 v[202:203], s[50:51], 0, v[134:135]
	s_add_i32 m0, s54, 0x2000
	s_nop 0
	global_load_lds_dwordx4 v[202:203], off
	s_waitcnt vmcnt(6)
	s_waitcnt lgkmcnt(0)
	s_barrier
	s_setprio 1
	s_waitcnt lgkmcnt(0)
	v_mfma_f32_16x16x32_bf16 v[60:63], v[144:147], v[186:189], v[60:63]
	v_mfma_f32_16x16x32_bf16 v[56:59], v[160:163], v[186:189], v[56:59]
	v_mfma_f32_16x16x32_bf16 v[44:47], v[144:147], v[194:197], v[44:47]
	v_mfma_f32_16x16x32_bf16 v[40:43], v[160:163], v[194:197], v[40:43]
	v_mfma_f32_16x16x32_bf16 v[28:31], v[144:147], v[208:211], v[28:31]
	v_mfma_f32_16x16x32_bf16 v[24:27], v[160:163], v[208:211], v[24:27]
	v_mfma_f32_16x16x32_bf16 v[12:15], v[144:147], v[216:219], v[12:15]
	v_mfma_f32_16x16x32_bf16 v[8:11], v[160:163], v[216:219], v[8:11]
	v_mfma_f32_16x16x32_bf16 v[60:63], v[156:159], v[190:193], v[60:63]
	v_mfma_f32_16x16x32_bf16 v[56:59], v[164:167], v[190:193], v[56:59]
	v_mfma_f32_16x16x32_bf16 v[44:47], v[156:159], v[198:201], v[44:47]
	v_mfma_f32_16x16x32_bf16 v[40:43], v[164:167], v[198:201], v[40:43]
	v_lshl_add_u64 v[202:203], v[226:227], 0, s[42:43]
	s_mov_b32 m0, s59
	s_nop 0
	global_load_lds_dwordx4 v[202:203], off
	v_mfma_f32_16x16x32_bf16 v[28:31], v[156:159], v[212:215], v[28:31]
	v_mfma_f32_16x16x32_bf16 v[24:27], v[164:167], v[212:215], v[24:27]
	v_mfma_f32_16x16x32_bf16 v[12:15], v[156:159], v[220:223], v[12:15]
	v_mfma_f32_16x16x32_bf16 v[8:11], v[164:167], v[220:223], v[8:11]
	s_setprio 0
	s_setprio 1
	v_mfma_f32_16x16x32_bf16 v[52:55], v[168:171], v[186:189], v[52:55]
	v_mfma_f32_16x16x32_bf16 v[48:51], v[176:179], v[186:189], v[48:51]
	v_mfma_f32_16x16x32_bf16 v[36:39], v[168:171], v[194:197], v[36:39]
	v_mfma_f32_16x16x32_bf16 v[32:35], v[176:179], v[194:197], v[32:35]
	v_mfma_f32_16x16x32_bf16 v[20:23], v[168:171], v[208:211], v[20:23]
	v_mfma_f32_16x16x32_bf16 v[16:19], v[176:179], v[208:211], v[16:19]
	v_mfma_f32_16x16x32_bf16 v[4:7], v[168:171], v[216:219], v[4:7]
	v_mfma_f32_16x16x32_bf16 v[0:3], v[176:179], v[216:219], v[0:3]
	v_mfma_f32_16x16x32_bf16 v[52:55], v[172:175], v[190:193], v[52:55]
	v_mfma_f32_16x16x32_bf16 v[48:51], v[182:185], v[190:193], v[48:51]
	v_mfma_f32_16x16x32_bf16 v[36:39], v[172:175], v[198:201], v[36:39]
	v_mfma_f32_16x16x32_bf16 v[32:35], v[182:185], v[198:201], v[32:35]
	v_lshl_add_u64 v[202:203], v[228:229], 0, s[42:43]
	s_mov_b32 m0, s60
	s_nop 0
	global_load_lds_dwordx4 v[202:203], off
	v_mfma_f32_16x16x32_bf16 v[20:23], v[172:175], v[212:215], v[20:23]
	v_mfma_f32_16x16x32_bf16 v[16:19], v[182:185], v[212:215], v[16:19]
	v_mfma_f32_16x16x32_bf16 v[4:7], v[172:175], v[220:223], v[4:7]
	v_mfma_f32_16x16x32_bf16 v[0:3], v[182:185], v[220:223], v[0:3]
	s_setprio 0
	s_barrier
	s_add_i32 s77, s77, 2
	s_add_u32 s75, s75, 0x100
	s_addc_u32 s76, s76, 0
	s_cmp_gt_u32 s77, 41
	s_mov_b64 s[50:51], s[52:53]
	s_cbranch_scc0 .LBB0_1035
	s_and_b64 vcc, exec, s[44:45]
	s_cbranch_vccz .LBB0_1038
	s_barrier

; #define PG8_STAGE(bufoff, gbase, voff) do { _Pragma("unroll") for (int _i = 0; _i < 2; ++_i) \
;         __builtin_amdgcn_global_load_lds((const unsigned*)((const char*)(gbase) + (voff)[_i]), (PG8_LAS unsigned*)(lds + (bufoff) + ldsw + _i * 8192), 16, 0, 0); } while (0)
; #define PG8_LDA(dst, b, h) do { _Pragma("unroll") for (int m = 0; m < 4; ++m) _Pragma("unroll") for (int k = 0; k < 2; ++k) dst[m][k] = *(const PG8_LAS bf16x8*)(lds + PG8_SA(b, h) + aoff + m * 2048 + k * 1024); } while (0)
; #define PG8_LDB(dst, b, h) do { _Pragma("unroll") for (int n = 0; n < 2; ++n) _Pragma("unroll") for (int k = 0; k < 2; ++k) dst[n][k] = *(const PG8_LAS bf16x8*)(lds + PG8_SB(b, h) + boff + n * 2048 + k * 1024); } while (0)
; #define PG8_MMA(ai, bj, At, Bt) do { __builtin_amdgcn_s_setprio(1); _Pragma("unroll") for (int m = 0; m < 4; ++m) _Pragma("unroll") for (int n = 0; n < 2; ++n) _Pragma("unroll") for (int k = 0; k < 2; ++k) \
;         acc[ai][bj][m][n] = __builtin_amdgcn_mfma_f32_16x16x32_bf16(Bt[n][k], At[m][k], acc[ai][bj][m][n], 0, 0, 0); __builtin_amdgcn_s_setprio(0); } while (0)
; #define PG8_BAR __builtin_amdgcn_s_barrier()
; template <class Epi, class Sched, bool ALIGN_EPI = false, bool SP2 = false>
; __device__ __forceinline__ void gemm_phase(PG8_LAS unsigned char* lds, const Gemm g, const Sched& S, const Epi& E) {
;     ...
;         const bool has_next = S.next(ui + 1, nxt);
;         const char* nA = has_next ? (const char*)g.A + (size_t)nxt.pm * tstep : cA; const char* nB = has_next ? (const char*)g.Bt + (size_t)nxt.pn * tstep : cB;
;         for (int t = 0; t < nt; t += 2) {
;             const bool last = (t == nt - 2);
;             const char* a1 = cA + (size_t)(t + 1) * kstep;
;             const char* a2 = last ? nA : cA + (size_t)(t + 2) * kstep; const char* b2 = last ? nB : cB + (size_t)(t + 2) * kstep;
;             const char* a3 = a2 + kstep; const char* b3 = b2 + kstep;
;             if (last && has_next) S.a_ready(nxt);
;             if constexpr (SP2) {
;             PG8_LDB(B0, 0, 0); PG8_LDB(B1, 0, 1); PG8_SCHED; PG8_LDA(At, 0, 0); PG8_STAGE(PG8_SA(1, 1), a1 + hstep, voffA);
;             PG8_WAIT_V(8); PG8_WAIT_L(0); PG8_BAR; PG8_MMA(0, 0, At, B0); PG8_MMA(0, 1, At, B1); PG8_BAR; PG8_SCHED;
;             PG8_LDA(At, 0, 1); PG8_STAGE(PG8_SB(0, 0), b2, voffB); PG8_STAGE(PG8_SB(0, 1), b2 + hstep, voffB); PG8_STAGE(PG8_SA(0, 0), a2, voffA);
.LBB0_1118:
	s_ashr_i32 s45, s44, 31
	s_lshl_b64 s[48:49], s[44:45], 19
	s_add_u32 s48, s22, s48
	s_addc_u32 s49, s23, s49
	s_and_b64 s[50:51], s[10:11], exec
	s_cselect_b32 s45, s49, s55
	s_cselect_b32 s76, s48, s54
	s_ashr_i32 s43, s42, 31
	s_lshl_b64 s[50:51], s[42:43], 19
	s_add_u32 s50, s14, s50
	s_addc_u32 s51, s15, s51
	s_and_b64 s[58:59], s[10:11], exec
	s_cselect_b32 s43, s51, s57
	s_cselect_b32 s77, s50, s56
	s_add_u32 s54, s54, 0x40080
	s_addc_u32 s55, s55, 0
	s_add_u32 s82, s56, 0x100
	s_addc_u32 s83, s57, 0
	s_mov_b32 s84, -2
	ds_read_b128 v[144:147], v155
	ds_read_b128 v[148:151], v155 offset:1024
	ds_read_b128 v[160:163], v155 offset:2048
	ds_read_b128 v[164:167], v155 offset:3072
	ds_read_b128 v[168:171], v156
	ds_read_b128 v[172:175], v156 offset:1024
	ds_read_b128 v[176:179], v156 offset:2048
	ds_read_b128 v[182:185], v156 offset:3072
	s_add_u32 s56, s54, 0xfffc0080
	s_addc_u32 s57, s55, -1
	s_cmp_eq_u32 s84, 12
	s_cselect_b32 s59, s45, s57
	s_cselect_b32 s58, s76, s56
	s_cselect_b32 s57, s43, s83
	s_cselect_b32 s56, s77, s82
	v_lshl_add_u64 v[224:225], s[54:55], 0, v[136:137]
	s_add_i32 m0, s53, 0xc000
	ds_read_b128 v[186:189], v157
	ds_read_b128 v[190:193], v157 offset:1024
	ds_read_b128 v[194:197], v157 offset:2048
	ds_read_b128 v[198:201], v157 offset:3072
	ds_read_b128 v[208:211], v157 offset:4096
	ds_read_b128 v[212:215], v157 offset:5120
	ds_read_b128 v[216:219], v157 offset:6144
	ds_read_b128 v[220:223], v157 offset:7168
	global_load_lds_dwordx4 v[224:225], off
	v_lshl_add_u64 v[224:225], s[54:55], 0, v[138:139]
	s_add_i32 m0, s53, 0xe000
	s_nop 0
	global_load_lds_dwordx4 v[224:225], off
	s_waitcnt vmcnt(8)
	s_waitcnt lgkmcnt(0)
	s_barrier
	s_setprio 1
	s_waitcnt lgkmcnt(0)
	v_mfma_f32_16x16x32_bf16 v[124:127], v[144:147], v[186:189], 0
	v_mfma_f32_16x16x32_bf16 v[120:123], v[160:163], v[186:189], 0
	v_mfma_f32_16x16x32_bf16 v[108:111], v[144:147], v[194:197], 0
	v_mfma_f32_16x16x32_bf16 v[104:107], v[160:163], v[194:197], 0
	v_mfma_f32_16x16x32_bf16 v[92:95], v[144:147], v[208:211], 0
	v_mfma_f32_16x16x32_bf16 v[88:91], v[160:163], v[208:211], 0
	v_mfma_f32_16x16x32_bf16 v[76:79], v[144:147], v[216:219], 0
	v_mfma_f32_16x16x32_bf16 v[72:75], v[160:163], v[216:219], 0
	v_mfma_f32_16x16x32_bf16 v[124:127], v[148:151], v[190:193], v[124:127]
	v_mfma_f32_16x16x32_bf16 v[120:123], v[164:167], v[190:193], v[120:123]
	v_mfma_f32_16x16x32_bf16 v[108:111], v[148:151], v[198:201], v[108:111]
	v_mfma_f32_16x16x32_bf16 v[104:107], v[164:167], v[198:201], v[104:107]
	v_mfma_f32_16x16x32_bf16 v[92:95], v[148:151], v[212:215], v[92:95]
	v_mfma_f32_16x16x32_bf16 v[88:91], v[164:167], v[212:215], v[88:91]
	v_mfma_f32_16x16x32_bf16 v[76:79], v[148:151], v[220:223], v[76:79]
	v_mfma_f32_16x16x32_bf16 v[72:75], v[164:167], v[220:223], v[72:75]
	s_setprio 0
	s_setprio 1
	v_mfma_f32_16x16x32_bf16 v[116:119], v[168:171], v[186:189], 0
	v_mfma_f32_16x16x32_bf16 v[112:115], v[176:179], v[186:189], 0
	v_mfma_f32_16x16x32_bf16 v[100:103], v[168:171], v[194:197], 0
	v_mfma_f32_16x16x32_bf16 v[96:99], v[176:179], v[194:197], 0
	v_mfma_f32_16x16x32_bf16 v[84:87], v[168:171], v[208:211], 0
	v_mfma_f32_16x16x32_bf16 v[80:83], v[176:179], v[208:211], 0
	v_mfma_f32_16x16x32_bf16 v[68:71], v[168:171], v[216:219], 0
	v_mfma_f32_16x16x32_bf16 v[64:67], v[176:179], v[216:219], 0
	v_mfma_f32_16x16x32_bf16 v[116:119], v[172:175], v[190:193], v[116:119]
	v_mfma_f32_16x16x32_bf16 v[112:115], v[182:185], v[190:193], v[112:115]
	v_mfma_f32_16x16x32_bf16 v[100:103], v[172:175], v[198:201], v[100:103]
	v_mfma_f32_16x16x32_bf16 v[96:99], v[182:185], v[198:201], v[96:99]
	v_mfma_f32_16x16x32_bf16 v[84:87], v[172:175], v[212:215], v[84:87]
	v_mfma_f32_16x16x32_bf16 v[80:83], v[182:185], v[212:215], v[80:83]
	v_mfma_f32_16x16x32_bf16 v[68:71], v[172:175], v[220:223], v[68:71]
	v_mfma_f32_16x16x32_bf16 v[64:67], v[182:185], v[220:223], v[64:67]
	s_setprio 0
	s_barrier
	s_add_i32 s78, s66, s33
	v_lshl_add_u64 v[224:225], s[56:57], 0, v[132:133]
	s_mov_b32 m0, s78
	ds_read_b128 v[186:189], v157 offset:16384
	ds_read_b128 v[190:193], v157 offset:17408
	ds_read_b128 v[194:197], v157 offset:18432
	ds_read_b128 v[198:201], v157 offset:19456
	ds_read_b128 v[208:211], v157 offset:20480
	ds_read_b128 v[212:215], v157 offset:21504
	ds_read_b128 v[216:219], v157 offset:22528
	ds_read_b128 v[220:223], v157 offset:23552
	global_load_lds_dwordx4 v[224:225], off
	s_add_i32 m0, s78, 0x2000
	s_add_u32 s78, s56, 0x40000
	v_lshl_add_u64 v[226:227], s[56:57], 0, v[128:129]
	s_addc_u32 s79, s57, 0
	s_add_i32 s85, s67, s33
	global_load_lds_dwordx4 v[226:227], off
	v_lshl_add_u64 v[228:229], s[78:79], 0, v[132:133]
	s_mov_b32 m0, s85
	global_load_lds_dwordx4 v[228:229], off
	v_lshl_add_u64 v[228:229], s[78:79], 0, v[128:129]
	s_add_i32 m0, s85, 0x2000
	s_nop 0
	global_load_lds_dwordx4 v[228:229], off
	s_waitcnt vmcnt(6)
	s_waitcnt lgkmcnt(0)
	s_barrier
; #define PG8_STAGE(bufoff, gbase, voff) do { _Pragma("unroll") for (int _i = 0; _i < 2; ++_i) \
;         __builtin_amdgcn_global_load_lds((const unsigned*)((const char*)(gbase) + (voff)[_i]), (PG8_LAS unsigned*)(lds + (bufoff) + ldsw + _i * 8192), 16, 0, 0); } while (0)
; #define PG8_LDA(dst, b, h) do { _Pragma("unroll") for (int m = 0; m < 4; ++m) _Pragma("unroll") for (int k = 0; k < 2; ++k) dst[m][k] = *(const PG8_LAS bf16x8*)(lds + PG8_SA(b, h) + aoff + m * 2048 + k * 1024); } while (0)
; #define PG8_LDB(dst, b, h) do { _Pragma("unroll") for (int n = 0; n < 2; ++n) _Pragma("unroll") for (int k = 0; k < 2; ++k) dst[n][k] = *(const PG8_LAS bf16x8*)(lds + PG8_SB(b, h) + boff + n * 2048 + k * 1024); } while (0)
; #define PG8_MMA(ai, bj, At, Bt) do { __builtin_amdgcn_s_setprio(1); _Pragma("unroll") for (int m = 0; m < 4; ++m) _Pragma("unroll") for (int n = 0; n < 2; ++n) _Pragma("unroll") for (int k = 0; k < 2; ++k) \
;         acc[ai][bj][m][n] = __builtin_amdgcn_mfma_f32_16x16x32_bf16(Bt[n][k], At[m][k], acc[ai][bj][m][n], 0, 0, 0); __builtin_amdgcn_s_setprio(0); } while (0)
; #define PG8_WAIT_V(n) asm volatile("s_waitcnt vmcnt(" #n ")" ::: "memory")
; #define PG8_WAIT_L(n) asm volatile("s_waitcnt lgkmcnt(" #n ")" ::: "memory")
; #define PG8_BAR __builtin_amdgcn_s_barrier()
; #define PG8_SCHED __builtin_amdgcn_sched_barrier(0)
; template <class Epi, class Sched, bool ALIGN_EPI = false, bool SP2 = false>
; __device__ __forceinline__ void gemm_phase(PG8_LAS unsigned char* lds, const Gemm g, const Sched& S, const Epi& E) {
;     ...
;             PG8_WAIT_V(8); PG8_WAIT_L(0); PG8_BAR; PG8_MMA(1, 0, At, B0); PG8_MMA(1, 1, At, B1); PG8_BAR; PG8_SCHED;
;             PG8_LDB(B0, 1, 0); PG8_LDB(B1, 1, 1); PG8_SCHED; PG8_LDA(At, 1, 0); PG8_STAGE(PG8_SA(0, 1), a2 + hstep, voffA);
;             PG8_WAIT_V(8); PG8_WAIT_L(0); PG8_BAR; PG8_MMA(0, 0, At, B0); PG8_MMA(0, 1, At, B1); PG8_BAR; PG8_SCHED;
	s_setprio 1
	s_waitcnt lgkmcnt(0)
	v_mfma_f32_16x16x32_bf16 v[60:63], v[144:147], v[186:189], 0
	v_mfma_f32_16x16x32_bf16 v[56:59], v[160:163], v[186:189], 0
	v_mfma_f32_16x16x32_bf16 v[44:47], v[144:147], v[194:197], 0
	v_mfma_f32_16x16x32_bf16 v[40:43], v[160:163], v[194:197], 0
	v_mfma_f32_16x16x32_bf16 v[28:31], v[144:147], v[208:211], 0
	v_mfma_f32_16x16x32_bf16 v[24:27], v[160:163], v[208:211], 0
	v_mfma_f32_16x16x32_bf16 v[12:15], v[144:147], v[216:219], 0
	v_mfma_f32_16x16x32_bf16 v[8:11], v[160:163], v[216:219], 0
	v_mfma_f32_16x16x32_bf16 v[60:63], v[148:151], v[190:193], v[60:63]
	v_mfma_f32_16x16x32_bf16 v[56:59], v[164:167], v[190:193], v[56:59]
	v_mfma_f32_16x16x32_bf16 v[44:47], v[148:151], v[198:201], v[44:47]
	v_mfma_f32_16x16x32_bf16 v[40:43], v[164:167], v[198:201], v[40:43]
	v_lshl_add_u64 v[228:229], s[58:59], 0, v[134:135]
	s_mov_b32 m0, s53
	s_nop 0
	global_load_lds_dwordx4 v[228:229], off
	v_mfma_f32_16x16x32_bf16 v[28:31], v[148:151], v[212:215], v[28:31]
	v_mfma_f32_16x16x32_bf16 v[24:27], v[164:167], v[212:215], v[24:27]
	v_mfma_f32_16x16x32_bf16 v[12:15], v[148:151], v[220:223], v[12:15]
	v_mfma_f32_16x16x32_bf16 v[8:11], v[164:167], v[220:223], v[8:11]
	s_setprio 0
	s_setprio 1
	v_mfma_f32_16x16x32_bf16 v[52:55], v[168:171], v[186:189], 0
	v_mfma_f32_16x16x32_bf16 v[48:51], v[176:179], v[186:189], 0
	v_mfma_f32_16x16x32_bf16 v[36:39], v[168:171], v[194:197], 0
	v_mfma_f32_16x16x32_bf16 v[32:35], v[176:179], v[194:197], 0
	v_mfma_f32_16x16x32_bf16 v[20:23], v[168:171], v[208:211], 0
	v_mfma_f32_16x16x32_bf16 v[16:19], v[176:179], v[208:211], 0
	v_mfma_f32_16x16x32_bf16 v[4:7], v[168:171], v[216:219], 0
	v_mfma_f32_16x16x32_bf16 v[0:3], v[176:179], v[216:219], 0
	v_mfma_f32_16x16x32_bf16 v[52:55], v[172:175], v[190:193], v[52:55]
	v_mfma_f32_16x16x32_bf16 v[48:51], v[182:185], v[190:193], v[48:51]
	v_mfma_f32_16x16x32_bf16 v[36:39], v[172:175], v[198:201], v[36:39]
	v_mfma_f32_16x16x32_bf16 v[32:35], v[182:185], v[198:201], v[32:35]
	v_lshl_add_u64 v[230:231], s[58:59], 0, v[130:131]
	s_mov_b32 m0, s60
	s_nop 0
	global_load_lds_dwordx4 v[230:231], off
	v_mfma_f32_16x16x32_bf16 v[20:23], v[172:175], v[212:215], v[20:23]
	v_mfma_f32_16x16x32_bf16 v[16:19], v[182:185], v[212:215], v[16:19]
	v_mfma_f32_16x16x32_bf16 v[4:7], v[172:175], v[220:223], v[4:7]
	v_mfma_f32_16x16x32_bf16 v[0:3], v[182:185], v[220:223], v[0:3]
	s_setprio 0
	s_barrier
	s_add_i32 s78, 0, 0x18000
	v_add_u32_e32 v159, s78, v153
	s_add_i32 s79, 0, 0x1c000
	ds_read_b128 v[144:147], v159
	ds_read_b128 v[148:151], v159 offset:1024
	ds_read_b128 v[160:163], v159 offset:2048
	ds_read_b128 v[164:167], v159 offset:3072
	v_add_u32_e32 v159, s79, v153
	ds_read_b128 v[168:171], v159
	ds_read_b128 v[172:175], v159 offset:1024
	ds_read_b128 v[176:179], v159 offset:2048
	ds_read_b128 v[182:185], v159 offset:3072
	s_add_u32 s58, s58, 0x40000
	s_addc_u32 s59, s59, 0
	s_mov_b32 m0, s61
	v_lshl_add_u64 v[232:233], s[58:59], 0, v[134:135]
	ds_read_b128 v[186:189], v157 offset:32768
	ds_read_b128 v[190:193], v157 offset:33792
	ds_read_b128 v[194:197], v157 offset:34816
	ds_read_b128 v[198:201], v157 offset:35840
	ds_read_b128 v[208:211], v157 offset:36864
	ds_read_b128 v[212:215], v157 offset:37888
	ds_read_b128 v[216:219], v157 offset:38912
	ds_read_b128 v[220:223], v157 offset:39936
	global_load_lds_dwordx4 v[232:233], off
	v_lshl_add_u64 v[232:233], s[58:59], 0, v[130:131]
	s_mov_b32 m0, s62
	s_nop 0
	global_load_lds_dwordx4 v[232:233], off
	s_waitcnt vmcnt(8)
	s_waitcnt lgkmcnt(0)
	s_barrier
	s_setprio 1
	s_waitcnt lgkmcnt(0)
	v_mfma_f32_16x16x32_bf16 v[124:127], v[144:147], v[186:189], v[124:127]
	v_mfma_f32_16x16x32_bf16 v[120:123], v[160:163], v[186:189], v[120:123]
	v_mfma_f32_16x16x32_bf16 v[108:111], v[144:147], v[194:197], v[108:111]
	v_mfma_f32_16x16x32_bf16 v[104:107], v[160:163], v[194:197], v[104:107]
	v_mfma_f32_16x16x32_bf16 v[92:95], v[144:147], v[208:211], v[92:95]
	v_mfma_f32_16x16x32_bf16 v[88:91], v[160:163], v[208:211], v[88:91]
	v_mfma_f32_16x16x32_bf16 v[76:79], v[144:147], v[216:219], v[76:79]
	v_mfma_f32_16x16x32_bf16 v[72:75], v[160:163], v[216:219], v[72:75]
	v_mfma_f32_16x16x32_bf16 v[124:127], v[148:151], v[190:193], v[124:127]
	v_mfma_f32_16x16x32_bf16 v[120:123], v[164:167], v[190:193], v[120:123]
	v_mfma_f32_16x16x32_bf16 v[108:111], v[148:151], v[198:201], v[108:111]
	v_mfma_f32_16x16x32_bf16 v[104:107], v[164:167], v[198:201], v[104:107]
	v_mfma_f32_16x16x32_bf16 v[92:95], v[148:151], v[212:215], v[92:95]
	v_mfma_f32_16x16x32_bf16 v[88:91], v[164:167], v[212:215], v[88:91]
	v_mfma_f32_16x16x32_bf16 v[76:79], v[148:151], v[220:223], v[76:79]
	v_mfma_f32_16x16x32_bf16 v[72:75], v[164:167], v[220:223], v[72:75]
	s_setprio 0
	s_setprio 1
	v_mfma_f32_16x16x32_bf16 v[116:119], v[168:171], v[186:189], v[116:119]
	v_mfma_f32_16x16x32_bf16 v[112:115], v[176:179], v[186:189], v[112:115]
	v_mfma_f32_16x16x32_bf16 v[100:103], v[168:171], v[194:197], v[100:103]
	v_mfma_f32_16x16x32_bf16 v[96:99], v[176:179], v[194:197], v[96:99]
	v_mfma_f32_16x16x32_bf16 v[84:87], v[168:171], v[208:211], v[84:87]
	v_mfma_f32_16x16x32_bf16 v[80:83], v[176:179], v[208:211], v[80:83]
	v_mfma_f32_16x16x32_bf16 v[68:71], v[168:171], v[216:219], v[68:71]
	v_mfma_f32_16x16x32_bf16 v[64:67], v[176:179], v[216:219], v[64:67]
	v_mfma_f32_16x16x32_bf16 v[116:119], v[172:175], v[190:193], v[116:119]
	v_mfma_f32_16x16x32_bf16 v[112:115], v[182:185], v[190:193], v[112:115]
	v_mfma_f32_16x16x32_bf16 v[100:103], v[172:175], v[198:201], v[100:103]
	v_mfma_f32_16x16x32_bf16 v[96:99], v[182:185], v[198:201], v[96:99]
	v_mfma_f32_16x16x32_bf16 v[84:87], v[172:175], v[212:215], v[84:87]
	v_mfma_f32_16x16x32_bf16 v[80:83], v[182:185], v[212:215], v[80:83]
	v_mfma_f32_16x16x32_bf16 v[68:71], v[172:175], v[220:223], v[68:71]
	v_mfma_f32_16x16x32_bf16 v[64:67], v[182:185], v[220:223], v[64:67]
	s_setprio 0
	s_barrier
; #define PG8_STAGE(bufoff, gbase, voff) do { _Pragma("unroll") for (int _i = 0; _i < 2; ++_i) \
;         __builtin_amdgcn_global_load_lds((const unsigned*)((const char*)(gbase) + (voff)[_i]), (PG8_LAS unsigned*)(lds + (bufoff) + ldsw + _i * 8192), 16, 0, 0); } while (0)
; #define PG8_LDA(dst, b, h) do { _Pragma("unroll") for (int m = 0; m < 4; ++m) _Pragma("unroll") for (int k = 0; k < 2; ++k) dst[m][k] = *(const PG8_LAS bf16x8*)(lds + PG8_SA(b, h) + aoff + m * 2048 + k * 1024); } while (0)
; #define PG8_LDB(dst, b, h) do { _Pragma("unroll") for (int n = 0; n < 2; ++n) _Pragma("unroll") for (int k = 0; k < 2; ++k) dst[n][k] = *(const PG8_LAS bf16x8*)(lds + PG8_SB(b, h) + boff + n * 2048 + k * 1024); } while (0)
; #define PG8_MMA(ai, bj, At, Bt) do { __builtin_amdgcn_s_setprio(1); _Pragma("unroll") for (int m = 0; m < 4; ++m) _Pragma("unroll") for (int n = 0; n < 2; ++n) _Pragma("unroll") for (int k = 0; k < 2; ++k) \
;         acc[ai][bj][m][n] = __builtin_amdgcn_mfma_f32_16x16x32_bf16(Bt[n][k], At[m][k], acc[ai][bj][m][n], 0, 0, 0); __builtin_amdgcn_s_setprio(0); } while (0)
; #define PG8_WAIT_V(n) asm volatile("s_waitcnt vmcnt(" #n ")" ::: "memory")
; template <class Epi, class Sched, bool ALIGN_EPI = false, bool SP2 = false>
; __device__ __forceinline__ void gemm_phase(PG8_LAS unsigned char* lds, const Gemm g, const Sched& S, const Epi& E) {
;     ...
;             PG8_LDB(B0, 0, 0); PG8_LDB(B1, 0, 1); PG8_SCHED; PG8_LDA(At, 0, 0); PG8_STAGE(PG8_SA(1, 1), a1 + hstep, voffA);
;             PG8_WAIT_V(8); PG8_WAIT_L(0); PG8_BAR; PG8_MMA(0, 0, At, B0); PG8_MMA(0, 1, At, B1); PG8_BAR; PG8_SCHED;
;             PG8_LDA(At, 0, 1); PG8_STAGE(PG8_SB(0, 0), b2, voffB); PG8_STAGE(PG8_SB(0, 1), b2 + hstep, voffB); PG8_STAGE(PG8_SA(0, 0), a2, voffA);
;             PG8_WAIT_V(8); PG8_WAIT_L(0); PG8_BAR; PG8_MMA(1, 0, At, B0); PG8_MMA(1, 1, At, B1); PG8_BAR; PG8_SCHED;
;             PG8_LDB(B0, 1, 0); PG8_LDB(B1, 1, 1); PG8_SCHED; PG8_LDA(At, 1, 0); PG8_STAGE(PG8_SA(0, 1), a2 + hstep, voffA);
;             PG8_WAIT_V(8); PG8_WAIT_L(0); PG8_BAR; PG8_MMA(0, 0, At, B0); PG8_MMA(0, 1, At, B1); PG8_BAR; PG8_SCHED;
;             PG8_LDA(At, 1, 1); PG8_STAGE(PG8_SB(1, 0), b3, voffB); PG8_STAGE(PG8_SB(1, 1), b3 + hstep, voffB); PG8_STAGE(PG8_SA(1, 0), a3, voffA);
;             PG8_WAIT_V(8); PG8_WAIT_L(0); PG8_BAR; PG8_MMA(1, 0, At, B0); PG8_MMA(1, 1, At, B1); PG8_BAR; PG8_SCHED;
	s_add_i32 s58, s78, s33
	v_lshl_add_u64 v[224:225], v[224:225], 0, s[12:13]
	s_mov_b32 m0, s58
	ds_read_b128 v[186:189], v157 offset:49152
	ds_read_b128 v[190:193], v157 offset:50176
	ds_read_b128 v[194:197], v157 offset:51200
	ds_read_b128 v[198:201], v157 offset:52224
	ds_read_b128 v[208:211], v157 offset:53248
	ds_read_b128 v[212:215], v157 offset:54272
	ds_read_b128 v[216:219], v157 offset:55296
	ds_read_b128 v[220:223], v157 offset:56320
	global_load_lds_dwordx4 v[224:225], off
	s_add_i32 m0, s58, 0x2000
	s_add_u32 s56, s56, 0x40080
	v_lshl_add_u64 v[224:225], v[226:227], 0, s[12:13]
	s_addc_u32 s57, s57, 0
	s_add_i32 s58, s79, s33
	global_load_lds_dwordx4 v[224:225], off
	v_lshl_add_u64 v[224:225], s[56:57], 0, v[132:133]
	s_mov_b32 m0, s58
	s_nop 0
	global_load_lds_dwordx4 v[224:225], off
	v_lshl_add_u64 v[224:225], s[56:57], 0, v[128:129]
	s_add_i32 m0, s58, 0x2000
	s_nop 0
	global_load_lds_dwordx4 v[224:225], off
	s_waitcnt vmcnt(6)
	s_waitcnt lgkmcnt(0)
	s_barrier
	s_setprio 1
	s_waitcnt lgkmcnt(0)
	v_mfma_f32_16x16x32_bf16 v[60:63], v[144:147], v[186:189], v[60:63]
	v_mfma_f32_16x16x32_bf16 v[56:59], v[160:163], v[186:189], v[56:59]
	v_mfma_f32_16x16x32_bf16 v[44:47], v[144:147], v[194:197], v[44:47]
	v_mfma_f32_16x16x32_bf16 v[40:43], v[160:163], v[194:197], v[40:43]
	v_mfma_f32_16x16x32_bf16 v[28:31], v[144:147], v[208:211], v[28:31]
	v_mfma_f32_16x16x32_bf16 v[24:27], v[160:163], v[208:211], v[24:27]
	v_mfma_f32_16x16x32_bf16 v[12:15], v[144:147], v[216:219], v[12:15]
	v_mfma_f32_16x16x32_bf16 v[8:11], v[160:163], v[216:219], v[8:11]
	v_mfma_f32_16x16x32_bf16 v[60:63], v[148:151], v[190:193], v[60:63]
	v_mfma_f32_16x16x32_bf16 v[56:59], v[164:167], v[190:193], v[56:59]
	v_mfma_f32_16x16x32_bf16 v[44:47], v[148:151], v[198:201], v[44:47]
	v_mfma_f32_16x16x32_bf16 v[40:43], v[164:167], v[198:201], v[40:43]
	v_lshl_add_u64 v[224:225], v[228:229], 0, s[12:13]
	s_mov_b32 m0, s64
	s_nop 0
	global_load_lds_dwordx4 v[224:225], off
	v_mfma_f32_16x16x32_bf16 v[28:31], v[148:151], v[212:215], v[28:31]
	v_mfma_f32_16x16x32_bf16 v[24:27], v[164:167], v[212:215], v[24:27]
	v_mfma_f32_16x16x32_bf16 v[12:15], v[148:151], v[220:223], v[12:15]
	v_mfma_f32_16x16x32_bf16 v[8:11], v[164:167], v[220:223], v[8:11]
	s_setprio 0
	s_setprio 1
	v_mfma_f32_16x16x32_bf16 v[52:55], v[168:171], v[186:189], v[52:55]
	v_mfma_f32_16x16x32_bf16 v[48:51], v[176:179], v[186:189], v[48:51]
	v_mfma_f32_16x16x32_bf16 v[36:39], v[168:171], v[194:197], v[36:39]
	v_mfma_f32_16x16x32_bf16 v[32:35], v[176:179], v[194:197], v[32:35]
	v_mfma_f32_16x16x32_bf16 v[20:23], v[168:171], v[208:211], v[20:23]
	v_mfma_f32_16x16x32_bf16 v[16:19], v[176:179], v[208:211], v[16:19]
	v_mfma_f32_16x16x32_bf16 v[4:7], v[168:171], v[216:219], v[4:7]
	v_mfma_f32_16x16x32_bf16 v[0:3], v[176:179], v[216:219], v[0:3]
	v_mfma_f32_16x16x32_bf16 v[52:55], v[172:175], v[190:193], v[52:55]
	v_mfma_f32_16x16x32_bf16 v[48:51], v[182:185], v[190:193], v[48:51]
	v_mfma_f32_16x16x32_bf16 v[36:39], v[172:175], v[198:201], v[36:39]
	v_mfma_f32_16x16x32_bf16 v[32:35], v[182:185], v[198:201], v[32:35]
	v_lshl_add_u64 v[224:225], v[230:231], 0, s[12:13]
	s_mov_b32 m0, s65
	s_nop 0
	global_load_lds_dwordx4 v[224:225], off
	v_mfma_f32_16x16x32_bf16 v[20:23], v[172:175], v[212:215], v[20:23]
	v_mfma_f32_16x16x32_bf16 v[16:19], v[182:185], v[212:215], v[16:19]
	v_mfma_f32_16x16x32_bf16 v[4:7], v[172:175], v[220:223], v[4:7]
	v_mfma_f32_16x16x32_bf16 v[0:3], v[182:185], v[220:223], v[0:3]
	s_setprio 0
	s_barrier
	s_add_i32 s84, s84, 2
	s_add_u32 s54, s54, 0x100
	s_addc_u32 s55, s55, 0
	s_add_u32 s82, s82, 0x100
	s_addc_u32 s83, s83, 0
.LBB0_1119:
	ds_read_b128 v[144:147], v155
	ds_read_b128 v[148:151], v155 offset:1024
	ds_read_b128 v[160:163], v155 offset:2048
	ds_read_b128 v[164:167], v155 offset:3072
	ds_read_b128 v[168:171], v156
	ds_read_b128 v[172:175], v156 offset:1024
	ds_read_b128 v[176:179], v156 offset:2048
	ds_read_b128 v[182:185], v156 offset:3072
	s_add_u32 s56, s54, 0xfffc0080
	s_addc_u32 s57, s55, -1
	s_cmp_eq_u32 s84, 12
	s_cselect_b32 s59, s45, s57
	s_cselect_b32 s58, s76, s56
	s_cselect_b32 s57, s43, s83
	s_cselect_b32 s56, s77, s82
	v_lshl_add_u64 v[224:225], s[54:55], 0, v[136:137]
	s_add_i32 m0, s53, 0xc000
	ds_read_b128 v[186:189], v157
	ds_read_b128 v[190:193], v157 offset:1024
	ds_read_b128 v[194:197], v157 offset:2048
	ds_read_b128 v[198:201], v157 offset:3072
	ds_read_b128 v[208:211], v157 offset:4096
	ds_read_b128 v[212:215], v157 offset:5120
	ds_read_b128 v[216:219], v157 offset:6144
	ds_read_b128 v[220:223], v157 offset:7168
	global_load_lds_dwordx4 v[224:225], off
	v_lshl_add_u64 v[224:225], s[54:55], 0, v[138:139]
	s_add_i32 m0, s53, 0xe000
	s_nop 0
	global_load_lds_dwordx4 v[224:225], off
	s_waitcnt vmcnt(8)
	s_waitcnt lgkmcnt(0)
	s_barrier
; #define PG8_STAGE(bufoff, gbase, voff) do { _Pragma("unroll") for (int _i = 0; _i < 2; ++_i) \
;         __builtin_amdgcn_global_load_lds((const unsigned*)((const char*)(gbase) + (voff)[_i]), (PG8_LAS unsigned*)(lds + (bufoff) + ldsw + _i * 8192), 16, 0, 0); } while (0)
; #define PG8_LDA(dst, b, h) do { _Pragma("unroll") for (int m = 0; m < 4; ++m) _Pragma("unroll") for (int k = 0; k < 2; ++k) dst[m][k] = *(const PG8_LAS bf16x8*)(lds + PG8_SA(b, h) + aoff + m * 2048 + k * 1024); } while (0)
; #define PG8_MMA(ai, bj, At, Bt) do { __builtin_amdgcn_s_setprio(1); _Pragma("unroll") for (int m = 0; m < 4; ++m) _Pragma("unroll") for (int n = 0; n < 2; ++n) _Pragma("unroll") for (int k = 0; k < 2; ++k) \
;         acc[ai][bj][m][n] = __builtin_amdgcn_mfma_f32_16x16x32_bf16(Bt[n][k], At[m][k], acc[ai][bj][m][n], 0, 0, 0); __builtin_amdgcn_s_setprio(0); } while (0)
; #define PG8_WAIT_V(n) asm volatile("s_waitcnt vmcnt(" #n ")" ::: "memory")
; #define PG8_WAIT_L(n) asm volatile("s_waitcnt lgkmcnt(" #n ")" ::: "memory")
; #define PG8_BAR __builtin_amdgcn_s_barrier()
; #define PG8_SCHED __builtin_amdgcn_sched_barrier(0)
; template <class Epi, class Sched, bool ALIGN_EPI = false, bool SP2 = false>
; __device__ __forceinline__ void gemm_phase(PG8_LAS unsigned char* lds, const Gemm g, const Sched& S, const Epi& E) {
;     ...
;             PG8_WAIT_V(8); PG8_WAIT_L(0); PG8_BAR; PG8_MMA(0, 0, At, B0); PG8_MMA(0, 1, At, B1); PG8_BAR; PG8_SCHED;
;             PG8_LDA(At, 0, 1); PG8_STAGE(PG8_SB(0, 0), b2, voffB); PG8_STAGE(PG8_SB(0, 1), b2 + hstep, voffB); PG8_STAGE(PG8_SA(0, 0), a2, voffA);
;             PG8_WAIT_V(8); PG8_WAIT_L(0); PG8_BAR; PG8_MMA(1, 0, At, B0); PG8_MMA(1, 1, At, B1); PG8_BAR; PG8_SCHED;
	s_setprio 1
	s_waitcnt lgkmcnt(0)
	v_mfma_f32_16x16x32_bf16 v[124:127], v[144:147], v[186:189], v[124:127]
	v_mfma_f32_16x16x32_bf16 v[120:123], v[160:163], v[186:189], v[120:123]
	v_mfma_f32_16x16x32_bf16 v[108:111], v[144:147], v[194:197], v[108:111]
	v_mfma_f32_16x16x32_bf16 v[104:107], v[160:163], v[194:197], v[104:107]
	v_mfma_f32_16x16x32_bf16 v[92:95], v[144:147], v[208:211], v[92:95]
	v_mfma_f32_16x16x32_bf16 v[88:91], v[160:163], v[208:211], v[88:91]
	v_mfma_f32_16x16x32_bf16 v[76:79], v[144:147], v[216:219], v[76:79]
	v_mfma_f32_16x16x32_bf16 v[72:75], v[160:163], v[216:219], v[72:75]
	v_mfma_f32_16x16x32_bf16 v[124:127], v[148:151], v[190:193], v[124:127]
	v_mfma_f32_16x16x32_bf16 v[120:123], v[164:167], v[190:193], v[120:123]
	v_mfma_f32_16x16x32_bf16 v[108:111], v[148:151], v[198:201], v[108:111]
	v_mfma_f32_16x16x32_bf16 v[104:107], v[164:167], v[198:201], v[104:107]
	v_mfma_f32_16x16x32_bf16 v[92:95], v[148:151], v[212:215], v[92:95]
	v_mfma_f32_16x16x32_bf16 v[88:91], v[164:167], v[212:215], v[88:91]
	v_mfma_f32_16x16x32_bf16 v[76:79], v[148:151], v[220:223], v[76:79]
	v_mfma_f32_16x16x32_bf16 v[72:75], v[164:167], v[220:223], v[72:75]
	s_setprio 0
	s_setprio 1
	v_mfma_f32_16x16x32_bf16 v[116:119], v[168:171], v[186:189], v[116:119]
	v_mfma_f32_16x16x32_bf16 v[112:115], v[176:179], v[186:189], v[112:115]
	v_mfma_f32_16x16x32_bf16 v[100:103], v[168:171], v[194:197], v[100:103]
	v_mfma_f32_16x16x32_bf16 v[96:99], v[176:179], v[194:197], v[96:99]
	v_mfma_f32_16x16x32_bf16 v[84:87], v[168:171], v[208:211], v[84:87]
	v_mfma_f32_16x16x32_bf16 v[80:83], v[176:179], v[208:211], v[80:83]
	v_mfma_f32_16x16x32_bf16 v[68:71], v[168:171], v[216:219], v[68:71]
	v_mfma_f32_16x16x32_bf16 v[64:67], v[176:179], v[216:219], v[64:67]
	v_mfma_f32_16x16x32_bf16 v[116:119], v[172:175], v[190:193], v[116:119]
	v_mfma_f32_16x16x32_bf16 v[112:115], v[182:185], v[190:193], v[112:115]
	v_mfma_f32_16x16x32_bf16 v[100:103], v[172:175], v[198:201], v[100:103]
	v_mfma_f32_16x16x32_bf16 v[96:99], v[182:185], v[198:201], v[96:99]
	v_mfma_f32_16x16x32_bf16 v[84:87], v[172:175], v[212:215], v[84:87]
	v_mfma_f32_16x16x32_bf16 v[80:83], v[182:185], v[212:215], v[80:83]
	v_mfma_f32_16x16x32_bf16 v[68:71], v[172:175], v[220:223], v[68:71]
	v_mfma_f32_16x16x32_bf16 v[64:67], v[182:185], v[220:223], v[64:67]
	s_setprio 0
	s_barrier
	s_add_i32 s78, s66, s33
	v_lshl_add_u64 v[224:225], s[56:57], 0, v[132:133]
	s_mov_b32 m0, s78
	ds_read_b128 v[186:189], v157 offset:16384
	ds_read_b128 v[190:193], v157 offset:17408
	ds_read_b128 v[194:197], v157 offset:18432
	ds_read_b128 v[198:201], v157 offset:19456
	ds_read_b128 v[208:211], v157 offset:20480
	ds_read_b128 v[212:215], v157 offset:21504
	ds_read_b128 v[216:219], v157 offset:22528
	ds_read_b128 v[220:223], v157 offset:23552
	global_load_lds_dwordx4 v[224:225], off
	s_add_i32 m0, s78, 0x2000
	s_add_u32 s78, s56, 0x40000
	v_lshl_add_u64 v[226:227], s[56:57], 0, v[128:129]
	s_addc_u32 s79, s57, 0
	s_add_i32 s85, s67, s33
	global_load_lds_dwordx4 v[226:227], off
	v_lshl_add_u64 v[228:229], s[78:79], 0, v[132:133]
	s_mov_b32 m0, s85
	global_load_lds_dwordx4 v[228:229], off
	v_lshl_add_u64 v[228:229], s[78:79], 0, v[128:129]
	s_add_i32 m0, s85, 0x2000
	s_nop 0
	global_load_lds_dwordx4 v[228:229], off
	s_waitcnt vmcnt(6)
	s_waitcnt lgkmcnt(0)
	s_barrier
	s_setprio 1
	s_waitcnt lgkmcnt(0)
	v_mfma_f32_16x16x32_bf16 v[60:63], v[144:147], v[186:189], v[60:63]
	v_mfma_f32_16x16x32_bf16 v[56:59], v[160:163], v[186:189], v[56:59]
	v_mfma_f32_16x16x32_bf16 v[44:47], v[144:147], v[194:197], v[44:47]
	v_mfma_f32_16x16x32_bf16 v[40:43], v[160:163], v[194:197], v[40:43]
	v_mfma_f32_16x16x32_bf16 v[28:31], v[144:147], v[208:211], v[28:31]
	v_mfma_f32_16x16x32_bf16 v[24:27], v[160:163], v[208:211], v[24:27]
	v_mfma_f32_16x16x32_bf16 v[12:15], v[144:147], v[216:219], v[12:15]
	v_mfma_f32_16x16x32_bf16 v[8:11], v[160:163], v[216:219], v[8:11]
	v_mfma_f32_16x16x32_bf16 v[60:63], v[148:151], v[190:193], v[60:63]
	v_mfma_f32_16x16x32_bf16 v[56:59], v[164:167], v[190:193], v[56:59]
	v_mfma_f32_16x16x32_bf16 v[44:47], v[148:151], v[198:201], v[44:47]
	v_mfma_f32_16x16x32_bf16 v[40:43], v[164:167], v[198:201], v[40:43]
	v_lshl_add_u64 v[228:229], s[58:59], 0, v[134:135]
	s_mov_b32 m0, s53
	s_nop 0
	global_load_lds_dwordx4 v[228:229], off
	v_mfma_f32_16x16x32_bf16 v[28:31], v[148:151], v[212:215], v[28:31]
	v_mfma_f32_16x16x32_bf16 v[24:27], v[164:167], v[212:215], v[24:27]
	v_mfma_f32_16x16x32_bf16 v[12:15], v[148:151], v[220:223], v[12:15]
	v_mfma_f32_16x16x32_bf16 v[8:11], v[164:167], v[220:223], v[8:11]
	s_setprio 0
	s_setprio 1
	v_mfma_f32_16x16x32_bf16 v[52:55], v[168:171], v[186:189], v[52:55]
	v_mfma_f32_16x16x32_bf16 v[48:51], v[176:179], v[186:189], v[48:51]
	v_mfma_f32_16x16x32_bf16 v[36:39], v[168:171], v[194:197], v[36:39]
	v_mfma_f32_16x16x32_bf16 v[32:35], v[176:179], v[194:197], v[32:35]
	v_mfma_f32_16x16x32_bf16 v[20:23], v[168:171], v[208:211], v[20:23]
	v_mfma_f32_16x16x32_bf16 v[16:19], v[176:179], v[208:211], v[16:19]
	v_mfma_f32_16x16x32_bf16 v[4:7], v[168:171], v[216:219], v[4:7]
	v_mfma_f32_16x16x32_bf16 v[0:3], v[176:179], v[216:219], v[0:3]
	v_mfma_f32_16x16x32_bf16 v[52:55], v[172:175], v[190:193], v[52:55]
	v_mfma_f32_16x16x32_bf16 v[48:51], v[182:185], v[190:193], v[48:51]
	v_mfma_f32_16x16x32_bf16 v[36:39], v[172:175], v[198:201], v[36:39]
	v_mfma_f32_16x16x32_bf16 v[32:35], v[182:185], v[198:201], v[32:35]
	v_lshl_add_u64 v[230:231], s[58:59], 0, v[130:131]
	s_mov_b32 m0, s60
	s_nop 0
	global_load_lds_dwordx4 v[230:231], off
	v_mfma_f32_16x16x32_bf16 v[20:23], v[172:175], v[212:215], v[20:23]
	v_mfma_f32_16x16x32_bf16 v[16:19], v[182:185], v[212:215], v[16:19]
	v_mfma_f32_16x16x32_bf16 v[4:7], v[172:175], v[220:223], v[4:7]
	v_mfma_f32_16x16x32_bf16 v[0:3], v[182:185], v[220:223], v[0:3]
	s_setprio 0
	s_barrier
; #define PG8_STAGE(bufoff, gbase, voff) do { _Pragma("unroll") for (int _i = 0; _i < 2; ++_i) \
;         __builtin_amdgcn_global_load_lds((const unsigned*)((const char*)(gbase) + (voff)[_i]), (PG8_LAS unsigned*)(lds + (bufoff) + ldsw + _i * 8192), 16, 0, 0); } while (0)
; #define PG8_LDA(dst, b, h) do { _Pragma("unroll") for (int m = 0; m < 4; ++m) _Pragma("unroll") for (int k = 0; k < 2; ++k) dst[m][k] = *(const PG8_LAS bf16x8*)(lds + PG8_SA(b, h) + aoff + m * 2048 + k * 1024); } while (0)
; #define PG8_LDB(dst, b, h) do { _Pragma("unroll") for (int n = 0; n < 2; ++n) _Pragma("unroll") for (int k = 0; k < 2; ++k) dst[n][k] = *(const PG8_LAS bf16x8*)(lds + PG8_SB(b, h) + boff + n * 2048 + k * 1024); } while (0)
; #define PG8_MMA(ai, bj, At, Bt) do { __builtin_amdgcn_s_setprio(1); _Pragma("unroll") for (int m = 0; m < 4; ++m) _Pragma("unroll") for (int n = 0; n < 2; ++n) _Pragma("unroll") for (int k = 0; k < 2; ++k) \
;         acc[ai][bj][m][n] = __builtin_amdgcn_mfma_f32_16x16x32_bf16(Bt[n][k], At[m][k], acc[ai][bj][m][n], 0, 0, 0); __builtin_amdgcn_s_setprio(0); } while (0)
; #define PG8_WAIT_V(n) asm volatile("s_waitcnt vmcnt(" #n ")" ::: "memory")
; #define PG8_WAIT_L(n) asm volatile("s_waitcnt lgkmcnt(" #n ")" ::: "memory")
; #define PG8_BAR __builtin_amdgcn_s_barrier()
; #define PG8_SCHED __builtin_amdgcn_sched_barrier(0)
; template <class Epi, class Sched, bool ALIGN_EPI = false, bool SP2 = false>
; __device__ __forceinline__ void gemm_phase(PG8_LAS unsigned char* lds, const Gemm g, const Sched& S, const Epi& E) {
;     ...
;             PG8_LDB(B0, 1, 0); PG8_LDB(B1, 1, 1); PG8_SCHED; PG8_LDA(At, 1, 0); PG8_STAGE(PG8_SA(0, 1), a2 + hstep, voffA);
;             PG8_WAIT_V(8); PG8_WAIT_L(0); PG8_BAR; PG8_MMA(0, 0, At, B0); PG8_MMA(0, 1, At, B1); PG8_BAR; PG8_SCHED;
	s_add_i32 s78, 0, 0x18000
	v_add_u32_e32 v159, s78, v153
	s_add_i32 s79, 0, 0x1c000
	ds_read_b128 v[144:147], v159
	ds_read_b128 v[148:151], v159 offset:1024
	ds_read_b128 v[160:163], v159 offset:2048
	ds_read_b128 v[164:167], v159 offset:3072
	v_add_u32_e32 v159, s79, v153
	ds_read_b128 v[168:171], v159
	ds_read_b128 v[172:175], v159 offset:1024
	ds_read_b128 v[176:179], v159 offset:2048
	ds_read_b128 v[182:185], v159 offset:3072
	s_add_u32 s58, s58, 0x40000
	s_addc_u32 s59, s59, 0
	s_mov_b32 m0, s61
	v_lshl_add_u64 v[232:233], s[58:59], 0, v[134:135]
	ds_read_b128 v[186:189], v157 offset:32768
	ds_read_b128 v[190:193], v157 offset:33792
	ds_read_b128 v[194:197], v157 offset:34816
	ds_read_b128 v[198:201], v157 offset:35840
	ds_read_b128 v[208:211], v157 offset:36864
	ds_read_b128 v[212:215], v157 offset:37888
	ds_read_b128 v[216:219], v157 offset:38912
	ds_read_b128 v[220:223], v157 offset:39936
	global_load_lds_dwordx4 v[232:233], off
	v_lshl_add_u64 v[232:233], s[58:59], 0, v[130:131]
	s_mov_b32 m0, s62
	s_nop 0
	global_load_lds_dwordx4 v[232:233], off
	s_waitcnt vmcnt(8)
	s_waitcnt lgkmcnt(0)
	s_barrier
	s_setprio 1
	s_waitcnt lgkmcnt(0)
	v_mfma_f32_16x16x32_bf16 v[124:127], v[144:147], v[186:189], v[124:127]
	v_mfma_f32_16x16x32_bf16 v[120:123], v[160:163], v[186:189], v[120:123]
	v_mfma_f32_16x16x32_bf16 v[108:111], v[144:147], v[194:197], v[108:111]
	v_mfma_f32_16x16x32_bf16 v[104:107], v[160:163], v[194:197], v[104:107]
	v_mfma_f32_16x16x32_bf16 v[92:95], v[144:147], v[208:211], v[92:95]
	v_mfma_f32_16x16x32_bf16 v[88:91], v[160:163], v[208:211], v[88:91]
	v_mfma_f32_16x16x32_bf16 v[76:79], v[144:147], v[216:219], v[76:79]
	v_mfma_f32_16x16x32_bf16 v[72:75], v[160:163], v[216:219], v[72:75]
	v_mfma_f32_16x16x32_bf16 v[124:127], v[148:151], v[190:193], v[124:127]
	v_mfma_f32_16x16x32_bf16 v[120:123], v[164:167], v[190:193], v[120:123]
	v_mfma_f32_16x16x32_bf16 v[108:111], v[148:151], v[198:201], v[108:111]
	v_mfma_f32_16x16x32_bf16 v[104:107], v[164:167], v[198:201], v[104:107]
	v_mfma_f32_16x16x32_bf16 v[92:95], v[148:151], v[212:215], v[92:95]
	v_mfma_f32_16x16x32_bf16 v[88:91], v[164:167], v[212:215], v[88:91]
	v_mfma_f32_16x16x32_bf16 v[76:79], v[148:151], v[220:223], v[76:79]
	v_mfma_f32_16x16x32_bf16 v[72:75], v[164:167], v[220:223], v[72:75]
	s_setprio 0
	s_setprio 1
	v_mfma_f32_16x16x32_bf16 v[116:119], v[168:171], v[186:189], v[116:119]
	v_mfma_f32_16x16x32_bf16 v[112:115], v[176:179], v[186:189], v[112:115]
	v_mfma_f32_16x16x32_bf16 v[100:103], v[168:171], v[194:197], v[100:103]
	v_mfma_f32_16x16x32_bf16 v[96:99], v[176:179], v[194:197], v[96:99]
	v_mfma_f32_16x16x32_bf16 v[84:87], v[168:171], v[208:211], v[84:87]
	v_mfma_f32_16x16x32_bf16 v[80:83], v[176:179], v[208:211], v[80:83]
	v_mfma_f32_16x16x32_bf16 v[68:71], v[168:171], v[216:219], v[68:71]
	v_mfma_f32_16x16x32_bf16 v[64:67], v[176:179], v[216:219], v[64:67]
	v_mfma_f32_16x16x32_bf16 v[116:119], v[172:175], v[190:193], v[116:119]
	v_mfma_f32_16x16x32_bf16 v[112:115], v[182:185], v[190:193], v[112:115]
	v_mfma_f32_16x16x32_bf16 v[100:103], v[172:175], v[198:201], v[100:103]
	v_mfma_f32_16x16x32_bf16 v[96:99], v[182:185], v[198:201], v[96:99]
	v_mfma_f32_16x16x32_bf16 v[84:87], v[172:175], v[212:215], v[84:87]
	v_mfma_f32_16x16x32_bf16 v[80:83], v[182:185], v[212:215], v[80:83]
	v_mfma_f32_16x16x32_bf16 v[68:71], v[172:175], v[220:223], v[68:71]
	v_mfma_f32_16x16x32_bf16 v[64:67], v[182:185], v[220:223], v[64:67]
	s_setprio 0
	s_barrier
; #define PG8_STAGE(bufoff, gbase, voff) do { _Pragma("unroll") for (int _i = 0; _i < 2; ++_i) \
;         __builtin_amdgcn_global_load_lds((const unsigned*)((const char*)(gbase) + (voff)[_i]), (PG8_LAS unsigned*)(lds + (bufoff) + ldsw + _i * 8192), 16, 0, 0); } while (0)
; #define PG8_LDA(dst, b, h) do { _Pragma("unroll") for (int m = 0; m < 4; ++m) _Pragma("unroll") for (int k = 0; k < 2; ++k) dst[m][k] = *(const PG8_LAS bf16x8*)(lds + PG8_SA(b, h) + aoff + m * 2048 + k * 1024); } while (0)
; #define PG8_MMA(ai, bj, At, Bt) do { __builtin_amdgcn_s_setprio(1); _Pragma("unroll") for (int m = 0; m < 4; ++m) _Pragma("unroll") for (int n = 0; n < 2; ++n) _Pragma("unroll") for (int k = 0; k < 2; ++k) \
;         acc[ai][bj][m][n] = __builtin_amdgcn_mfma_f32_16x16x32_bf16(Bt[n][k], At[m][k], acc[ai][bj][m][n], 0, 0, 0); __builtin_amdgcn_s_setprio(0); } while (0)
; #define PG8_WAIT_V(n) asm volatile("s_waitcnt vmcnt(" #n ")" ::: "memory")
; #define PG8_WAIT_L(n) asm volatile("s_waitcnt lgkmcnt(" #n ")" ::: "memory")
; #define PG8_BAR __builtin_amdgcn_s_barrier()
; #define PG8_SCHED __builtin_amdgcn_sched_barrier(0)
;     __device__ __forceinline__ void operator()(const f32x4 (&acc)[2][2][4][2], const Unit& u, int wr, int wc, int fr, int fq) const {
;     ...
;             for (int m = 0; m < 4; ++m) { const int row = row0 + ai * HALF + m * 16; const float rs = row_rs(ss, row);
; template <class Epi, class Sched, bool ALIGN_EPI = false, bool SP2 = false>
; __device__ __forceinline__ void gemm_phase(PG8_LAS unsigned char* lds, const Gemm g, const Sched& S, const Epi& E) {
;     ...
;             PG8_LDA(At, 1, 1); PG8_STAGE(PG8_SB(1, 0), b3, voffB); PG8_STAGE(PG8_SB(1, 1), b3 + hstep, voffB); PG8_STAGE(PG8_SA(1, 0), a3, voffA);
;             PG8_WAIT_V(8); PG8_WAIT_L(0); PG8_BAR; PG8_MMA(1, 0, At, B0); PG8_MMA(1, 1, At, B1); PG8_BAR; PG8_SCHED;
	s_add_i32 s58, s78, s33
	v_lshl_add_u64 v[224:225], v[224:225], 0, s[12:13]
	s_mov_b32 m0, s58
	ds_read_b128 v[186:189], v157 offset:49152
	ds_read_b128 v[190:193], v157 offset:50176
	ds_read_b128 v[194:197], v157 offset:51200
	ds_read_b128 v[198:201], v157 offset:52224
	ds_read_b128 v[208:211], v157 offset:53248
	ds_read_b128 v[212:215], v157 offset:54272
	ds_read_b128 v[216:219], v157 offset:55296
	ds_read_b128 v[220:223], v157 offset:56320
	global_load_lds_dwordx4 v[224:225], off
	s_add_i32 m0, s58, 0x2000
	s_add_u32 s56, s56, 0x40080
	v_lshl_add_u64 v[224:225], v[226:227], 0, s[12:13]
	s_addc_u32 s57, s57, 0
	s_add_i32 s58, s79, s33
	global_load_lds_dwordx4 v[224:225], off
	v_lshl_add_u64 v[224:225], s[56:57], 0, v[132:133]
	s_mov_b32 m0, s58
	s_nop 0
	global_load_lds_dwordx4 v[224:225], off
	v_lshl_add_u64 v[224:225], s[56:57], 0, v[128:129]
	s_add_i32 m0, s58, 0x2000
	s_nop 0
	global_load_lds_dwordx4 v[224:225], off
	s_waitcnt vmcnt(6)
	s_waitcnt lgkmcnt(0)
	s_barrier
	s_setprio 1
	s_waitcnt lgkmcnt(0)
	v_mfma_f32_16x16x32_bf16 v[60:63], v[144:147], v[186:189], v[60:63]
	v_mfma_f32_16x16x32_bf16 v[56:59], v[160:163], v[186:189], v[56:59]
	v_mfma_f32_16x16x32_bf16 v[44:47], v[144:147], v[194:197], v[44:47]
	v_mfma_f32_16x16x32_bf16 v[40:43], v[160:163], v[194:197], v[40:43]
	v_mfma_f32_16x16x32_bf16 v[28:31], v[144:147], v[208:211], v[28:31]
	v_mfma_f32_16x16x32_bf16 v[24:27], v[160:163], v[208:211], v[24:27]
	v_mfma_f32_16x16x32_bf16 v[12:15], v[144:147], v[216:219], v[12:15]
	v_mfma_f32_16x16x32_bf16 v[8:11], v[160:163], v[216:219], v[8:11]
	v_mfma_f32_16x16x32_bf16 v[60:63], v[148:151], v[190:193], v[60:63]
	v_mfma_f32_16x16x32_bf16 v[56:59], v[164:167], v[190:193], v[56:59]
	v_mfma_f32_16x16x32_bf16 v[44:47], v[148:151], v[198:201], v[44:47]
	v_mfma_f32_16x16x32_bf16 v[40:43], v[164:167], v[198:201], v[40:43]
	v_lshl_add_u64 v[224:225], v[228:229], 0, s[12:13]
	s_mov_b32 m0, s64
	s_nop 0
	global_load_lds_dwordx4 v[224:225], off
	v_mfma_f32_16x16x32_bf16 v[28:31], v[148:151], v[212:215], v[28:31]
	v_mfma_f32_16x16x32_bf16 v[24:27], v[164:167], v[212:215], v[24:27]
	v_mfma_f32_16x16x32_bf16 v[12:15], v[148:151], v[220:223], v[12:15]
	v_mfma_f32_16x16x32_bf16 v[8:11], v[164:167], v[220:223], v[8:11]
	s_setprio 0
	s_setprio 1
	v_mfma_f32_16x16x32_bf16 v[52:55], v[168:171], v[186:189], v[52:55]
	v_mfma_f32_16x16x32_bf16 v[48:51], v[176:179], v[186:189], v[48:51]
	v_mfma_f32_16x16x32_bf16 v[36:39], v[168:171], v[194:197], v[36:39]
	v_mfma_f32_16x16x32_bf16 v[32:35], v[176:179], v[194:197], v[32:35]
	v_mfma_f32_16x16x32_bf16 v[20:23], v[168:171], v[208:211], v[20:23]
	v_mfma_f32_16x16x32_bf16 v[16:19], v[176:179], v[208:211], v[16:19]
	v_mfma_f32_16x16x32_bf16 v[4:7], v[168:171], v[216:219], v[4:7]
	v_mfma_f32_16x16x32_bf16 v[0:3], v[176:179], v[216:219], v[0:3]
	v_mfma_f32_16x16x32_bf16 v[52:55], v[172:175], v[190:193], v[52:55]
	v_mfma_f32_16x16x32_bf16 v[48:51], v[182:185], v[190:193], v[48:51]
	v_mfma_f32_16x16x32_bf16 v[36:39], v[172:175], v[198:201], v[36:39]
	v_mfma_f32_16x16x32_bf16 v[32:35], v[182:185], v[198:201], v[32:35]
	v_lshl_add_u64 v[224:225], v[230:231], 0, s[12:13]
	s_mov_b32 m0, s65
	s_nop 0
	global_load_lds_dwordx4 v[224:225], off
	v_mfma_f32_16x16x32_bf16 v[20:23], v[172:175], v[212:215], v[20:23]
	v_mfma_f32_16x16x32_bf16 v[16:19], v[182:185], v[212:215], v[16:19]
	v_mfma_f32_16x16x32_bf16 v[4:7], v[172:175], v[220:223], v[4:7]
	v_mfma_f32_16x16x32_bf16 v[0:3], v[182:185], v[220:223], v[0:3]
	s_setprio 0
	s_barrier
	s_add_i32 s84, s84, 2
	s_add_u32 s54, s54, 0x100
	s_addc_u32 s55, s55, 0
	s_add_u32 s82, s82, 0x100
	s_addc_u32 s83, s83, 0
	s_cmp_gt_u32 s84, 13
	s_cbranch_scc0 .LBB0_1119
	v_lshl_add_u32 v144, s52, 8, v152
	v_ashrrev_i32_e32 v145, 31, v144
	v_lshl_add_u64 v[150:151], v[144:145], 3, s[36:37]
	global_load_dwordx2 v[182:183], v[150:151], off
	global_load_dwordx2 v[184:185], v[150:151], off offset:128
	global_load_dwordx2 v[186:187], v[150:151], off offset:256
	global_load_dwordx2 v[188:189], v[150:151], off offset:384
	global_load_dwordx2 v[190:191], v[150:151], off offset:1024
	global_load_dwordx2 v[192:193], v[150:151], off offset:1152
	global_load_dwordx2 v[194:195], v[150:151], off offset:1280
	global_load_dwordx2 v[196:197], v[150:151], off offset:1408
	s_and_b64 vcc, exec, s[38:39]
	s_cbranch_vccz .LBB0_1122
	s_barrier

; #define PG8_STAGE(bufoff, gbase, voff) do { _Pragma("unroll") for (int _i = 0; _i < 2; ++_i) \
;         __builtin_amdgcn_global_load_lds((const unsigned*)((const char*)(gbase) + (voff)[_i]), (PG8_LAS unsigned*)(lds + (bufoff) + ldsw + _i * 8192), 16, 0, 0); } while (0)
; #define PG8_LDA(dst, b, h) do { _Pragma("unroll") for (int m = 0; m < 4; ++m) _Pragma("unroll") for (int k = 0; k < 2; ++k) dst[m][k] = *(const PG8_LAS bf16x8*)(lds + PG8_SA(b, h) + aoff + m * 2048 + k * 1024); } while (0)
; #define PG8_LDB(dst, b, h) do { _Pragma("unroll") for (int n = 0; n < 2; ++n) _Pragma("unroll") for (int k = 0; k < 2; ++k) dst[n][k] = *(const PG8_LAS bf16x8*)(lds + PG8_SB(b, h) + boff + n * 2048 + k * 1024); } while (0)
; #define PG8_MMA(ai, bj, At, Bt) do { __builtin_amdgcn_s_setprio(1); _Pragma("unroll") for (int m = 0; m < 4; ++m) _Pragma("unroll") for (int n = 0; n < 2; ++n) _Pragma("unroll") for (int k = 0; k < 2; ++k) \
;         acc[ai][bj][m][n] = __builtin_amdgcn_mfma_f32_16x16x32_bf16(Bt[n][k], At[m][k], acc[ai][bj][m][n], 0, 0, 0); __builtin_amdgcn_s_setprio(0); } while (0)
; #define PG8_BAR __builtin_amdgcn_s_barrier()
; template <class Epi, class Sched, bool ALIGN_EPI = false, bool SP2 = false>
; __device__ __forceinline__ void gemm_phase(PG8_LAS unsigned char* lds, const Gemm g, const Sched& S, const Epi& E) {
;     ...
;         const bool has_next = S.next(ui + 1, nxt);
;         const char* nA = has_next ? (const char*)g.A + (size_t)nxt.pm * tstep : cA; const char* nB = has_next ? (const char*)g.Bt + (size_t)nxt.pn * tstep : cB;
;         for (int t = 0; t < nt; t += 2) {
;             const bool last = (t == nt - 2);
;             const char* a1 = cA + (size_t)(t + 1) * kstep;
;             const char* a2 = last ? nA : cA + (size_t)(t + 2) * kstep; const char* b2 = last ? nB : cB + (size_t)(t + 2) * kstep;
;             const char* a3 = a2 + kstep; const char* b3 = b2 + kstep;
;             if (last && has_next) S.a_ready(nxt);
;             if constexpr (SP2) {
;             PG8_LDB(B0, 0, 0); PG8_LDB(B1, 0, 1); PG8_SCHED; PG8_LDA(At, 0, 0); PG8_STAGE(PG8_SA(1, 1), a1 + hstep, voffA);
;             PG8_WAIT_V(8); PG8_WAIT_L(0); PG8_BAR; PG8_MMA(0, 0, At, B0); PG8_MMA(0, 1, At, B1); PG8_BAR; PG8_SCHED;
;             PG8_LDA(At, 0, 1); PG8_STAGE(PG8_SB(0, 0), b2, voffB); PG8_STAGE(PG8_SB(0, 1), b2 + hstep, voffB); PG8_STAGE(PG8_SA(0, 0), a2, voffA);
.LBB0_1196:
	s_add_u32 s82, s52, 0x100
	s_addc_u32 s83, s53, 0
	s_mov_b32 s84, -2
	s_waitcnt lgkmcnt(0)
	ds_read_b128 v[144:147], v151
	ds_read_b128 v[156:159], v151 offset:1024
	ds_read_b128 v[160:163], v151 offset:2048
	ds_read_b128 v[164:167], v151 offset:3072
	ds_read_b128 v[168:171], v152
	ds_read_b128 v[172:175], v152 offset:1024
	ds_read_b128 v[176:179], v152 offset:2048
	ds_read_b128 v[182:185], v152 offset:3072
	s_add_u32 s52, s50, 0x100
	s_addc_u32 s53, s51, 0
	s_cmp_eq_u32 s84, 40
	s_cselect_b32 s57, s1, s53
	s_cselect_b32 s56, s0, s52
	s_cselect_b32 s55, s49, s83
	s_cselect_b32 s54, s48, s82
	v_lshl_add_u64 v[224:225], s[50:51], 0, v[136:137]
	s_add_i32 m0, s34, 0xc000
	ds_read_b128 v[186:189], v153
	ds_read_b128 v[190:193], v153 offset:1024
	ds_read_b128 v[194:197], v153 offset:2048
	ds_read_b128 v[198:201], v153 offset:3072
	ds_read_b128 v[208:211], v153 offset:4096
	ds_read_b128 v[212:215], v153 offset:5120
	ds_read_b128 v[216:219], v153 offset:6144
	ds_read_b128 v[220:223], v153 offset:7168
	global_load_lds_dwordx4 v[224:225], off
	v_lshl_add_u64 v[224:225], s[50:51], 0, v[138:139]
	s_add_i32 m0, s34, 0xe000
	s_nop 0
	global_load_lds_dwordx4 v[224:225], off
	s_waitcnt vmcnt(8)
	s_waitcnt lgkmcnt(0)
	s_barrier
	s_setprio 1
	s_waitcnt lgkmcnt(0)
	v_mfma_f32_16x16x32_bf16 v[124:127], v[144:147], v[186:189], 0
	v_mfma_f32_16x16x32_bf16 v[120:123], v[160:163], v[186:189], 0
	v_mfma_f32_16x16x32_bf16 v[108:111], v[144:147], v[194:197], 0
	v_mfma_f32_16x16x32_bf16 v[104:107], v[160:163], v[194:197], 0
	v_mfma_f32_16x16x32_bf16 v[92:95], v[144:147], v[208:211], 0
	v_mfma_f32_16x16x32_bf16 v[88:91], v[160:163], v[208:211], 0
	v_mfma_f32_16x16x32_bf16 v[76:79], v[144:147], v[216:219], 0
	v_mfma_f32_16x16x32_bf16 v[72:75], v[160:163], v[216:219], 0
	v_mfma_f32_16x16x32_bf16 v[124:127], v[156:159], v[190:193], v[124:127]
	v_mfma_f32_16x16x32_bf16 v[120:123], v[164:167], v[190:193], v[120:123]
	v_mfma_f32_16x16x32_bf16 v[108:111], v[156:159], v[198:201], v[108:111]
	v_mfma_f32_16x16x32_bf16 v[104:107], v[164:167], v[198:201], v[104:107]
	v_mfma_f32_16x16x32_bf16 v[92:95], v[156:159], v[212:215], v[92:95]
	v_mfma_f32_16x16x32_bf16 v[88:91], v[164:167], v[212:215], v[88:91]
	v_mfma_f32_16x16x32_bf16 v[76:79], v[156:159], v[220:223], v[76:79]
	v_mfma_f32_16x16x32_bf16 v[72:75], v[164:167], v[220:223], v[72:75]
	s_setprio 0
	s_setprio 1
	v_mfma_f32_16x16x32_bf16 v[116:119], v[168:171], v[186:189], 0
	v_mfma_f32_16x16x32_bf16 v[112:115], v[176:179], v[186:189], 0
	v_mfma_f32_16x16x32_bf16 v[100:103], v[168:171], v[194:197], 0
	v_mfma_f32_16x16x32_bf16 v[96:99], v[176:179], v[194:197], 0
	v_mfma_f32_16x16x32_bf16 v[84:87], v[168:171], v[208:211], 0
	v_mfma_f32_16x16x32_bf16 v[80:83], v[176:179], v[208:211], 0
	v_mfma_f32_16x16x32_bf16 v[68:71], v[168:171], v[216:219], 0
	v_mfma_f32_16x16x32_bf16 v[64:67], v[176:179], v[216:219], 0
	v_mfma_f32_16x16x32_bf16 v[116:119], v[172:175], v[190:193], v[116:119]
	v_mfma_f32_16x16x32_bf16 v[112:115], v[182:185], v[190:193], v[112:115]
	v_mfma_f32_16x16x32_bf16 v[100:103], v[172:175], v[198:201], v[100:103]
	v_mfma_f32_16x16x32_bf16 v[96:99], v[182:185], v[198:201], v[96:99]
	v_mfma_f32_16x16x32_bf16 v[84:87], v[172:175], v[212:215], v[84:87]
	v_mfma_f32_16x16x32_bf16 v[80:83], v[182:185], v[212:215], v[80:83]
	v_mfma_f32_16x16x32_bf16 v[68:71], v[172:175], v[220:223], v[68:71]
	v_mfma_f32_16x16x32_bf16 v[64:67], v[182:185], v[220:223], v[64:67]
	s_setprio 0
	s_barrier
	s_add_i32 s50, s64, s33
	v_lshl_add_u64 v[224:225], s[54:55], 0, v[130:131]
	s_mov_b32 m0, s50
	ds_read_b128 v[186:189], v153 offset:16384
	ds_read_b128 v[190:193], v153 offset:17408
	ds_read_b128 v[194:197], v153 offset:18432
	ds_read_b128 v[198:201], v153 offset:19456
	ds_read_b128 v[208:211], v153 offset:20480
	ds_read_b128 v[212:215], v153 offset:21504
	ds_read_b128 v[216:219], v153 offset:22528
	ds_read_b128 v[220:223], v153 offset:23552
	global_load_lds_dwordx4 v[224:225], off
	s_add_i32 m0, s50, 0x2000
	s_add_u32 s50, s54, 0xb0000
	v_lshl_add_u64 v[226:227], s[54:55], 0, v[134:135]
	s_addc_u32 s51, s55, 0
	s_add_i32 s78, s65, s33
	global_load_lds_dwordx4 v[226:227], off
	v_lshl_add_u64 v[228:229], s[50:51], 0, v[130:131]
	s_mov_b32 m0, s78
	global_load_lds_dwordx4 v[228:229], off
	v_lshl_add_u64 v[228:229], s[50:51], 0, v[134:135]
	s_add_i32 m0, s78, 0x2000
	s_nop 0
	global_load_lds_dwordx4 v[228:229], off
	s_waitcnt vmcnt(6)
	s_waitcnt lgkmcnt(0)
	s_barrier
; #define PG8_STAGE(bufoff, gbase, voff) do { _Pragma("unroll") for (int _i = 0; _i < 2; ++_i) \
;         __builtin_amdgcn_global_load_lds((const unsigned*)((const char*)(gbase) + (voff)[_i]), (PG8_LAS unsigned*)(lds + (bufoff) + ldsw + _i * 8192), 16, 0, 0); } while (0)
; #define PG8_LDA(dst, b, h) do { _Pragma("unroll") for (int m = 0; m < 4; ++m) _Pragma("unroll") for (int k = 0; k < 2; ++k) dst[m][k] = *(const PG8_LAS bf16x8*)(lds + PG8_SA(b, h) + aoff + m * 2048 + k * 1024); } while (0)
; #define PG8_LDB(dst, b, h) do { _Pragma("unroll") for (int n = 0; n < 2; ++n) _Pragma("unroll") for (int k = 0; k < 2; ++k) dst[n][k] = *(const PG8_LAS bf16x8*)(lds + PG8_SB(b, h) + boff + n * 2048 + k * 1024); } while (0)
; #define PG8_MMA(ai, bj, At, Bt) do { __builtin_amdgcn_s_setprio(1); _Pragma("unroll") for (int m = 0; m < 4; ++m) _Pragma("unroll") for (int n = 0; n < 2; ++n) _Pragma("unroll") for (int k = 0; k < 2; ++k) \
;         acc[ai][bj][m][n] = __builtin_amdgcn_mfma_f32_16x16x32_bf16(Bt[n][k], At[m][k], acc[ai][bj][m][n], 0, 0, 0); __builtin_amdgcn_s_setprio(0); } while (0)
; #define PG8_WAIT_V(n) asm volatile("s_waitcnt vmcnt(" #n ")" ::: "memory")
; template <class Epi, class Sched, bool ALIGN_EPI = false, bool SP2 = false>
; __device__ __forceinline__ void gemm_phase(PG8_LAS unsigned char* lds, const Gemm g, const Sched& S, const Epi& E) {
;     ...
;             PG8_LDB(B0, 0, 0); PG8_LDB(B1, 0, 1); PG8_SCHED; PG8_LDA(At, 0, 0); PG8_STAGE(PG8_SA(1, 1), a1 + hstep, voffA);
;             PG8_WAIT_V(8); PG8_WAIT_L(0); PG8_BAR; PG8_MMA(0, 0, At, B0); PG8_MMA(0, 1, At, B1); PG8_BAR; PG8_SCHED;
;             PG8_LDA(At, 0, 1); PG8_STAGE(PG8_SB(0, 0), b2, voffB); PG8_STAGE(PG8_SB(0, 1), b2 + hstep, voffB); PG8_STAGE(PG8_SA(0, 0), a2, voffA);
;             PG8_WAIT_V(8); PG8_WAIT_L(0); PG8_BAR; PG8_MMA(1, 0, At, B0); PG8_MMA(1, 1, At, B1); PG8_BAR; PG8_SCHED;
;             PG8_LDB(B0, 1, 0); PG8_LDB(B1, 1, 1); PG8_SCHED; PG8_LDA(At, 1, 0); PG8_STAGE(PG8_SA(0, 1), a2 + hstep, voffA);
;             PG8_WAIT_V(8); PG8_WAIT_L(0); PG8_BAR; PG8_MMA(0, 0, At, B0); PG8_MMA(0, 1, At, B1); PG8_BAR; PG8_SCHED;
;             PG8_LDA(At, 1, 1); PG8_STAGE(PG8_SB(1, 0), b3, voffB); PG8_STAGE(PG8_SB(1, 1), b3 + hstep, voffB); PG8_STAGE(PG8_SA(1, 0), a3, voffA);
;             PG8_WAIT_V(8); PG8_WAIT_L(0); PG8_BAR; PG8_MMA(1, 0, At, B0); PG8_MMA(1, 1, At, B1); PG8_BAR; PG8_SCHED;
	s_setprio 1
	s_waitcnt lgkmcnt(0)
	v_mfma_f32_16x16x32_bf16 v[60:63], v[144:147], v[186:189], 0
	v_mfma_f32_16x16x32_bf16 v[56:59], v[160:163], v[186:189], 0
	v_mfma_f32_16x16x32_bf16 v[44:47], v[144:147], v[194:197], 0
	v_mfma_f32_16x16x32_bf16 v[40:43], v[160:163], v[194:197], 0
	v_mfma_f32_16x16x32_bf16 v[28:31], v[144:147], v[208:211], 0
	v_mfma_f32_16x16x32_bf16 v[24:27], v[160:163], v[208:211], 0
	v_mfma_f32_16x16x32_bf16 v[12:15], v[144:147], v[216:219], 0
	v_mfma_f32_16x16x32_bf16 v[8:11], v[160:163], v[216:219], 0
	v_mfma_f32_16x16x32_bf16 v[60:63], v[156:159], v[190:193], v[60:63]
	v_mfma_f32_16x16x32_bf16 v[56:59], v[164:167], v[190:193], v[56:59]
	v_mfma_f32_16x16x32_bf16 v[44:47], v[156:159], v[198:201], v[44:47]
	v_mfma_f32_16x16x32_bf16 v[40:43], v[164:167], v[198:201], v[40:43]
	v_lshl_add_u64 v[228:229], s[56:57], 0, v[128:129]
	s_mov_b32 m0, s34
	s_nop 0
	global_load_lds_dwordx4 v[228:229], off
	v_mfma_f32_16x16x32_bf16 v[28:31], v[156:159], v[212:215], v[28:31]
	v_mfma_f32_16x16x32_bf16 v[24:27], v[164:167], v[212:215], v[24:27]
	v_mfma_f32_16x16x32_bf16 v[12:15], v[156:159], v[220:223], v[12:15]
	v_mfma_f32_16x16x32_bf16 v[8:11], v[164:167], v[220:223], v[8:11]
	s_setprio 0
	s_setprio 1
	v_mfma_f32_16x16x32_bf16 v[52:55], v[168:171], v[186:189], 0
	v_mfma_f32_16x16x32_bf16 v[48:51], v[176:179], v[186:189], 0
	v_mfma_f32_16x16x32_bf16 v[36:39], v[168:171], v[194:197], 0
	v_mfma_f32_16x16x32_bf16 v[32:35], v[176:179], v[194:197], 0
	v_mfma_f32_16x16x32_bf16 v[20:23], v[168:171], v[208:211], 0
	v_mfma_f32_16x16x32_bf16 v[16:19], v[176:179], v[208:211], 0
	v_mfma_f32_16x16x32_bf16 v[4:7], v[168:171], v[216:219], 0
	v_mfma_f32_16x16x32_bf16 v[0:3], v[176:179], v[216:219], 0
	v_mfma_f32_16x16x32_bf16 v[52:55], v[172:175], v[190:193], v[52:55]
	v_mfma_f32_16x16x32_bf16 v[48:51], v[182:185], v[190:193], v[48:51]
	v_mfma_f32_16x16x32_bf16 v[36:39], v[172:175], v[198:201], v[36:39]
	v_mfma_f32_16x16x32_bf16 v[32:35], v[182:185], v[198:201], v[32:35]
	v_lshl_add_u64 v[230:231], s[56:57], 0, v[132:133]
	s_mov_b32 m0, s58
	s_nop 0
	global_load_lds_dwordx4 v[230:231], off
	v_mfma_f32_16x16x32_bf16 v[20:23], v[172:175], v[212:215], v[20:23]
	v_mfma_f32_16x16x32_bf16 v[16:19], v[182:185], v[212:215], v[16:19]
	v_mfma_f32_16x16x32_bf16 v[4:7], v[172:175], v[220:223], v[4:7]
	v_mfma_f32_16x16x32_bf16 v[0:3], v[182:185], v[220:223], v[0:3]
	s_setprio 0
	s_barrier
	s_add_i32 s78, 0, 0x18000
	v_add_u32_e32 v155, s78, v149
	s_add_i32 s79, 0, 0x1c000
	ds_read_b128 v[144:147], v155
	ds_read_b128 v[156:159], v155 offset:1024
	ds_read_b128 v[160:163], v155 offset:2048
	ds_read_b128 v[164:167], v155 offset:3072
	v_add_u32_e32 v155, s79, v149
	ds_read_b128 v[168:171], v155
	ds_read_b128 v[172:175], v155 offset:1024
	ds_read_b128 v[176:179], v155 offset:2048
	ds_read_b128 v[182:185], v155 offset:3072
	s_add_u32 s50, s56, 0xb0000
	s_addc_u32 s51, s57, 0
	s_mov_b32 m0, s59
	v_lshl_add_u64 v[232:233], s[50:51], 0, v[128:129]
	ds_read_b128 v[186:189], v153 offset:32768
	ds_read_b128 v[190:193], v153 offset:33792
	ds_read_b128 v[194:197], v153 offset:34816
	ds_read_b128 v[198:201], v153 offset:35840
	ds_read_b128 v[208:211], v153 offset:36864
	ds_read_b128 v[212:215], v153 offset:37888
	ds_read_b128 v[216:219], v153 offset:38912
	ds_read_b128 v[220:223], v153 offset:39936
	global_load_lds_dwordx4 v[232:233], off
	v_lshl_add_u64 v[232:233], s[50:51], 0, v[132:133]
	s_mov_b32 m0, s60
	s_nop 0
	global_load_lds_dwordx4 v[232:233], off
	s_waitcnt vmcnt(8)
	s_waitcnt lgkmcnt(0)
	s_barrier
	s_setprio 1
	s_waitcnt lgkmcnt(0)
	v_mfma_f32_16x16x32_bf16 v[124:127], v[144:147], v[186:189], v[124:127]
	v_mfma_f32_16x16x32_bf16 v[120:123], v[160:163], v[186:189], v[120:123]
	v_mfma_f32_16x16x32_bf16 v[108:111], v[144:147], v[194:197], v[108:111]
	v_mfma_f32_16x16x32_bf16 v[104:107], v[160:163], v[194:197], v[104:107]
	v_mfma_f32_16x16x32_bf16 v[92:95], v[144:147], v[208:211], v[92:95]
	v_mfma_f32_16x16x32_bf16 v[88:91], v[160:163], v[208:211], v[88:91]
	v_mfma_f32_16x16x32_bf16 v[76:79], v[144:147], v[216:219], v[76:79]
	v_mfma_f32_16x16x32_bf16 v[72:75], v[160:163], v[216:219], v[72:75]
	v_mfma_f32_16x16x32_bf16 v[124:127], v[156:159], v[190:193], v[124:127]
	v_mfma_f32_16x16x32_bf16 v[120:123], v[164:167], v[190:193], v[120:123]
	v_mfma_f32_16x16x32_bf16 v[108:111], v[156:159], v[198:201], v[108:111]
	v_mfma_f32_16x16x32_bf16 v[104:107], v[164:167], v[198:201], v[104:107]
	v_mfma_f32_16x16x32_bf16 v[92:95], v[156:159], v[212:215], v[92:95]
	v_mfma_f32_16x16x32_bf16 v[88:91], v[164:167], v[212:215], v[88:91]
	v_mfma_f32_16x16x32_bf16 v[76:79], v[156:159], v[220:223], v[76:79]
	v_mfma_f32_16x16x32_bf16 v[72:75], v[164:167], v[220:223], v[72:75]
	s_setprio 0
	s_setprio 1
	v_mfma_f32_16x16x32_bf16 v[116:119], v[168:171], v[186:189], v[116:119]
	v_mfma_f32_16x16x32_bf16 v[112:115], v[176:179], v[186:189], v[112:115]
	v_mfma_f32_16x16x32_bf16 v[100:103], v[168:171], v[194:197], v[100:103]
	v_mfma_f32_16x16x32_bf16 v[96:99], v[176:179], v[194:197], v[96:99]
	v_mfma_f32_16x16x32_bf16 v[84:87], v[168:171], v[208:211], v[84:87]
	v_mfma_f32_16x16x32_bf16 v[80:83], v[176:179], v[208:211], v[80:83]
	v_mfma_f32_16x16x32_bf16 v[68:71], v[168:171], v[216:219], v[68:71]
	v_mfma_f32_16x16x32_bf16 v[64:67], v[176:179], v[216:219], v[64:67]
	v_mfma_f32_16x16x32_bf16 v[116:119], v[172:175], v[190:193], v[116:119]
	v_mfma_f32_16x16x32_bf16 v[112:115], v[182:185], v[190:193], v[112:115]
	v_mfma_f32_16x16x32_bf16 v[100:103], v[172:175], v[198:201], v[100:103]
	v_mfma_f32_16x16x32_bf16 v[96:99], v[182:185], v[198:201], v[96:99]
	v_mfma_f32_16x16x32_bf16 v[84:87], v[172:175], v[212:215], v[84:87]
	v_mfma_f32_16x16x32_bf16 v[80:83], v[182:185], v[212:215], v[80:83]
	v_mfma_f32_16x16x32_bf16 v[68:71], v[172:175], v[220:223], v[68:71]
	v_mfma_f32_16x16x32_bf16 v[64:67], v[182:185], v[220:223], v[64:67]
	s_setprio 0
	s_barrier
; #define PG8_STAGE(bufoff, gbase, voff) do { _Pragma("unroll") for (int _i = 0; _i < 2; ++_i) \
;         __builtin_amdgcn_global_load_lds((const unsigned*)((const char*)(gbase) + (voff)[_i]), (PG8_LAS unsigned*)(lds + (bufoff) + ldsw + _i * 8192), 16, 0, 0); } while (0)
; #define PG8_LDA(dst, b, h) do { _Pragma("unroll") for (int m = 0; m < 4; ++m) _Pragma("unroll") for (int k = 0; k < 2; ++k) dst[m][k] = *(const PG8_LAS bf16x8*)(lds + PG8_SA(b, h) + aoff + m * 2048 + k * 1024); } while (0)
; #define PG8_WAIT_V(n) asm volatile("s_waitcnt vmcnt(" #n ")" ::: "memory")
; #define PG8_WAIT_L(n) asm volatile("s_waitcnt lgkmcnt(" #n ")" ::: "memory")
; template <class Epi, class Sched, bool ALIGN_EPI = false, bool SP2 = false>
; __device__ __forceinline__ void gemm_phase(PG8_LAS unsigned char* lds, const Gemm g, const Sched& S, const Epi& E) {
;     ...
;         const bool has_next = S.next(ui + 1, nxt);
;         const char* nA = has_next ? (const char*)g.A + (size_t)nxt.pm * tstep : cA; const char* nB = has_next ? (const char*)g.Bt + (size_t)nxt.pn * tstep : cB;
;         for (int t = 0; t < nt; t += 2) {
;             const bool last = (t == nt - 2);
;             const char* a1 = cA + (size_t)(t + 1) * kstep;
;             const char* a2 = last ? nA : cA + (size_t)(t + 2) * kstep; const char* b2 = last ? nB : cB + (size_t)(t + 2) * kstep;
;     ...
;             PG8_LDB(B0, 0, 0); PG8_LDB(B1, 0, 1); PG8_SCHED; PG8_LDA(At, 0, 0); PG8_STAGE(PG8_SA(1, 1), a1 + hstep, voffA);
;             PG8_WAIT_V(8); PG8_WAIT_L(0); PG8_BAR; PG8_MMA(0, 0, At, B0); PG8_MMA(0, 1, At, B1); PG8_BAR; PG8_SCHED;
;             PG8_LDA(At, 0, 1); PG8_STAGE(PG8_SB(0, 0), b2, voffB); PG8_STAGE(PG8_SB(0, 1), b2 + hstep, voffB); PG8_STAGE(PG8_SA(0, 0), a2, voffA);
;             PG8_WAIT_V(8); PG8_WAIT_L(0); PG8_BAR; PG8_MMA(1, 0, At, B0); PG8_MMA(1, 1, At, B1); PG8_BAR; PG8_SCHED;
;             PG8_LDB(B0, 1, 0); PG8_LDB(B1, 1, 1); PG8_SCHED; PG8_LDA(At, 1, 0); PG8_STAGE(PG8_SA(0, 1), a2 + hstep, voffA);
;             PG8_WAIT_V(8); PG8_WAIT_L(0); PG8_BAR; PG8_MMA(0, 0, At, B0); PG8_MMA(0, 1, At, B1); PG8_BAR; PG8_SCHED;
;             PG8_LDA(At, 1, 1); PG8_STAGE(PG8_SB(1, 0), b3, voffB); PG8_STAGE(PG8_SB(1, 1), b3 + hstep, voffB); PG8_STAGE(PG8_SA(1, 0), a3, voffA);
;             PG8_WAIT_V(8); PG8_WAIT_L(0); PG8_BAR; PG8_MMA(1, 0, At, B0); PG8_MMA(1, 1, At, B1); PG8_BAR; PG8_SCHED;
	s_add_i32 s50, s78, s33
	v_lshl_add_u64 v[224:225], v[224:225], 0, s[42:43]
	s_mov_b32 m0, s50
	ds_read_b128 v[186:189], v153 offset:49152
	ds_read_b128 v[190:193], v153 offset:50176
	ds_read_b128 v[194:197], v153 offset:51200
	ds_read_b128 v[198:201], v153 offset:52224
	ds_read_b128 v[208:211], v153 offset:53248
	ds_read_b128 v[212:215], v153 offset:54272
	ds_read_b128 v[216:219], v153 offset:55296
	ds_read_b128 v[220:223], v153 offset:56320
	global_load_lds_dwordx4 v[224:225], off
	s_add_i32 m0, s50, 0x2000
	s_add_u32 s50, s54, 0xb0080
	v_lshl_add_u64 v[224:225], v[226:227], 0, s[42:43]
	s_addc_u32 s51, s55, 0
	s_add_i32 s54, s79, s33
	global_load_lds_dwordx4 v[224:225], off
	v_lshl_add_u64 v[224:225], s[50:51], 0, v[130:131]
	s_mov_b32 m0, s54
	s_nop 0
	global_load_lds_dwordx4 v[224:225], off
	v_lshl_add_u64 v[224:225], s[50:51], 0, v[134:135]
	s_add_i32 m0, s54, 0x2000
	s_nop 0
	global_load_lds_dwordx4 v[224:225], off
	s_waitcnt vmcnt(6)
	s_waitcnt lgkmcnt(0)
	s_barrier
	s_setprio 1
	s_waitcnt lgkmcnt(0)
	v_mfma_f32_16x16x32_bf16 v[60:63], v[144:147], v[186:189], v[60:63]
	v_mfma_f32_16x16x32_bf16 v[56:59], v[160:163], v[186:189], v[56:59]
	v_mfma_f32_16x16x32_bf16 v[44:47], v[144:147], v[194:197], v[44:47]
	v_mfma_f32_16x16x32_bf16 v[40:43], v[160:163], v[194:197], v[40:43]
	v_mfma_f32_16x16x32_bf16 v[28:31], v[144:147], v[208:211], v[28:31]
	v_mfma_f32_16x16x32_bf16 v[24:27], v[160:163], v[208:211], v[24:27]
	v_mfma_f32_16x16x32_bf16 v[12:15], v[144:147], v[216:219], v[12:15]
	v_mfma_f32_16x16x32_bf16 v[8:11], v[160:163], v[216:219], v[8:11]
	v_mfma_f32_16x16x32_bf16 v[60:63], v[156:159], v[190:193], v[60:63]
	v_mfma_f32_16x16x32_bf16 v[56:59], v[164:167], v[190:193], v[56:59]
	v_mfma_f32_16x16x32_bf16 v[44:47], v[156:159], v[198:201], v[44:47]
	v_mfma_f32_16x16x32_bf16 v[40:43], v[164:167], v[198:201], v[40:43]
	v_lshl_add_u64 v[224:225], v[228:229], 0, s[42:43]
	s_mov_b32 m0, s62
	s_nop 0
	global_load_lds_dwordx4 v[224:225], off
	v_mfma_f32_16x16x32_bf16 v[28:31], v[156:159], v[212:215], v[28:31]
	v_mfma_f32_16x16x32_bf16 v[24:27], v[164:167], v[212:215], v[24:27]
	v_mfma_f32_16x16x32_bf16 v[12:15], v[156:159], v[220:223], v[12:15]
	v_mfma_f32_16x16x32_bf16 v[8:11], v[164:167], v[220:223], v[8:11]
	s_setprio 0
	s_setprio 1
	v_mfma_f32_16x16x32_bf16 v[52:55], v[168:171], v[186:189], v[52:55]
	v_mfma_f32_16x16x32_bf16 v[48:51], v[176:179], v[186:189], v[48:51]
	v_mfma_f32_16x16x32_bf16 v[36:39], v[168:171], v[194:197], v[36:39]
	v_mfma_f32_16x16x32_bf16 v[32:35], v[176:179], v[194:197], v[32:35]
	v_mfma_f32_16x16x32_bf16 v[20:23], v[168:171], v[208:211], v[20:23]
	v_mfma_f32_16x16x32_bf16 v[16:19], v[176:179], v[208:211], v[16:19]
	v_mfma_f32_16x16x32_bf16 v[4:7], v[168:171], v[216:219], v[4:7]
	v_mfma_f32_16x16x32_bf16 v[0:3], v[176:179], v[216:219], v[0:3]
	v_mfma_f32_16x16x32_bf16 v[52:55], v[172:175], v[190:193], v[52:55]
	v_mfma_f32_16x16x32_bf16 v[48:51], v[182:185], v[190:193], v[48:51]
	v_mfma_f32_16x16x32_bf16 v[36:39], v[172:175], v[198:201], v[36:39]
	v_mfma_f32_16x16x32_bf16 v[32:35], v[182:185], v[198:201], v[32:35]
	v_lshl_add_u64 v[224:225], v[230:231], 0, s[42:43]
	s_mov_b32 m0, s63
	s_nop 0
	global_load_lds_dwordx4 v[224:225], off
	v_mfma_f32_16x16x32_bf16 v[20:23], v[172:175], v[212:215], v[20:23]
	v_mfma_f32_16x16x32_bf16 v[16:19], v[182:185], v[212:215], v[16:19]
	v_mfma_f32_16x16x32_bf16 v[4:7], v[172:175], v[220:223], v[4:7]
	v_mfma_f32_16x16x32_bf16 v[0:3], v[182:185], v[220:223], v[0:3]
	s_setprio 0
	s_barrier
	s_add_i32 s84, s84, 2
	s_add_u32 s82, s82, 0x100
	s_addc_u32 s83, s83, 0
	s_mov_b64 s[50:51], s[52:53]
.LBB0_1197:
	ds_read_b128 v[144:147], v151
	ds_read_b128 v[156:159], v151 offset:1024
	ds_read_b128 v[160:163], v151 offset:2048
	ds_read_b128 v[164:167], v151 offset:3072
	ds_read_b128 v[168:171], v152
	ds_read_b128 v[172:175], v152 offset:1024
	ds_read_b128 v[176:179], v152 offset:2048
	ds_read_b128 v[182:185], v152 offset:3072
	s_add_u32 s52, s50, 0x100
	s_addc_u32 s53, s51, 0
	s_cmp_eq_u32 s84, 40
	s_cselect_b32 s57, s1, s53
	s_cselect_b32 s56, s0, s52
	s_cselect_b32 s55, s49, s83
	s_cselect_b32 s54, s48, s82
	v_lshl_add_u64 v[224:225], s[50:51], 0, v[136:137]
	s_add_i32 m0, s34, 0xc000
	ds_read_b128 v[186:189], v153
	ds_read_b128 v[190:193], v153 offset:1024
	ds_read_b128 v[194:197], v153 offset:2048
	ds_read_b128 v[198:201], v153 offset:3072
	ds_read_b128 v[208:211], v153 offset:4096
	ds_read_b128 v[212:215], v153 offset:5120
	ds_read_b128 v[216:219], v153 offset:6144
	ds_read_b128 v[220:223], v153 offset:7168
	global_load_lds_dwordx4 v[224:225], off
	v_lshl_add_u64 v[224:225], s[50:51], 0, v[138:139]
	s_add_i32 m0, s34, 0xe000
	s_nop 0
	global_load_lds_dwordx4 v[224:225], off
	s_waitcnt vmcnt(8)
	s_waitcnt lgkmcnt(0)
	s_barrier
; #define PG8_STAGE(bufoff, gbase, voff) do { _Pragma("unroll") for (int _i = 0; _i < 2; ++_i) \
;         __builtin_amdgcn_global_load_lds((const unsigned*)((const char*)(gbase) + (voff)[_i]), (PG8_LAS unsigned*)(lds + (bufoff) + ldsw + _i * 8192), 16, 0, 0); } while (0)
; #define PG8_LDA(dst, b, h) do { _Pragma("unroll") for (int m = 0; m < 4; ++m) _Pragma("unroll") for (int k = 0; k < 2; ++k) dst[m][k] = *(const PG8_LAS bf16x8*)(lds + PG8_SA(b, h) + aoff + m * 2048 + k * 1024); } while (0)
; #define PG8_LDB(dst, b, h) do { _Pragma("unroll") for (int n = 0; n < 2; ++n) _Pragma("unroll") for (int k = 0; k < 2; ++k) dst[n][k] = *(const PG8_LAS bf16x8*)(lds + PG8_SB(b, h) + boff + n * 2048 + k * 1024); } while (0)
; #define PG8_MMA(ai, bj, At, Bt) do { __builtin_amdgcn_s_setprio(1); _Pragma("unroll") for (int m = 0; m < 4; ++m) _Pragma("unroll") for (int n = 0; n < 2; ++n) _Pragma("unroll") for (int k = 0; k < 2; ++k) \
;         acc[ai][bj][m][n] = __builtin_amdgcn_mfma_f32_16x16x32_bf16(Bt[n][k], At[m][k], acc[ai][bj][m][n], 0, 0, 0); __builtin_amdgcn_s_setprio(0); } while (0)
; #define PG8_WAIT_V(n) asm volatile("s_waitcnt vmcnt(" #n ")" ::: "memory")
; #define PG8_WAIT_L(n) asm volatile("s_waitcnt lgkmcnt(" #n ")" ::: "memory")
; #define PG8_BAR __builtin_amdgcn_s_barrier()
; #define PG8_SCHED __builtin_amdgcn_sched_barrier(0)
; template <class Epi, class Sched, bool ALIGN_EPI = false, bool SP2 = false>
; __device__ __forceinline__ void gemm_phase(PG8_LAS unsigned char* lds, const Gemm g, const Sched& S, const Epi& E) {
;     ...
;             PG8_LDB(B0, 0, 0); PG8_LDB(B1, 0, 1); PG8_SCHED; PG8_LDA(At, 0, 0); PG8_STAGE(PG8_SA(1, 1), a1 + hstep, voffA);
;             PG8_WAIT_V(8); PG8_WAIT_L(0); PG8_BAR; PG8_MMA(0, 0, At, B0); PG8_MMA(0, 1, At, B1); PG8_BAR; PG8_SCHED;
;             PG8_LDA(At, 0, 1); PG8_STAGE(PG8_SB(0, 0), b2, voffB); PG8_STAGE(PG8_SB(0, 1), b2 + hstep, voffB); PG8_STAGE(PG8_SA(0, 0), a2, voffA);
;             PG8_WAIT_V(8); PG8_WAIT_L(0); PG8_BAR; PG8_MMA(1, 0, At, B0); PG8_MMA(1, 1, At, B1); PG8_BAR; PG8_SCHED;
	s_setprio 1
	s_waitcnt lgkmcnt(0)
	v_mfma_f32_16x16x32_bf16 v[124:127], v[144:147], v[186:189], v[124:127]
	v_mfma_f32_16x16x32_bf16 v[120:123], v[160:163], v[186:189], v[120:123]
	v_mfma_f32_16x16x32_bf16 v[108:111], v[144:147], v[194:197], v[108:111]
	v_mfma_f32_16x16x32_bf16 v[104:107], v[160:163], v[194:197], v[104:107]
	v_mfma_f32_16x16x32_bf16 v[92:95], v[144:147], v[208:211], v[92:95]
	v_mfma_f32_16x16x32_bf16 v[88:91], v[160:163], v[208:211], v[88:91]
	v_mfma_f32_16x16x32_bf16 v[76:79], v[144:147], v[216:219], v[76:79]
	v_mfma_f32_16x16x32_bf16 v[72:75], v[160:163], v[216:219], v[72:75]
	v_mfma_f32_16x16x32_bf16 v[124:127], v[156:159], v[190:193], v[124:127]
	v_mfma_f32_16x16x32_bf16 v[120:123], v[164:167], v[190:193], v[120:123]
	v_mfma_f32_16x16x32_bf16 v[108:111], v[156:159], v[198:201], v[108:111]
	v_mfma_f32_16x16x32_bf16 v[104:107], v[164:167], v[198:201], v[104:107]
	v_mfma_f32_16x16x32_bf16 v[92:95], v[156:159], v[212:215], v[92:95]
	v_mfma_f32_16x16x32_bf16 v[88:91], v[164:167], v[212:215], v[88:91]
	v_mfma_f32_16x16x32_bf16 v[76:79], v[156:159], v[220:223], v[76:79]
	v_mfma_f32_16x16x32_bf16 v[72:75], v[164:167], v[220:223], v[72:75]
	s_setprio 0
	s_setprio 1
	v_mfma_f32_16x16x32_bf16 v[116:119], v[168:171], v[186:189], v[116:119]
	v_mfma_f32_16x16x32_bf16 v[112:115], v[176:179], v[186:189], v[112:115]
	v_mfma_f32_16x16x32_bf16 v[100:103], v[168:171], v[194:197], v[100:103]
	v_mfma_f32_16x16x32_bf16 v[96:99], v[176:179], v[194:197], v[96:99]
	v_mfma_f32_16x16x32_bf16 v[84:87], v[168:171], v[208:211], v[84:87]
	v_mfma_f32_16x16x32_bf16 v[80:83], v[176:179], v[208:211], v[80:83]
	v_mfma_f32_16x16x32_bf16 v[68:71], v[168:171], v[216:219], v[68:71]
	v_mfma_f32_16x16x32_bf16 v[64:67], v[176:179], v[216:219], v[64:67]
	v_mfma_f32_16x16x32_bf16 v[116:119], v[172:175], v[190:193], v[116:119]
	v_mfma_f32_16x16x32_bf16 v[112:115], v[182:185], v[190:193], v[112:115]
	v_mfma_f32_16x16x32_bf16 v[100:103], v[172:175], v[198:201], v[100:103]
	v_mfma_f32_16x16x32_bf16 v[96:99], v[182:185], v[198:201], v[96:99]
	v_mfma_f32_16x16x32_bf16 v[84:87], v[172:175], v[212:215], v[84:87]
	v_mfma_f32_16x16x32_bf16 v[80:83], v[182:185], v[212:215], v[80:83]
	v_mfma_f32_16x16x32_bf16 v[68:71], v[172:175], v[220:223], v[68:71]
	v_mfma_f32_16x16x32_bf16 v[64:67], v[182:185], v[220:223], v[64:67]
	s_setprio 0
	s_barrier
	s_add_i32 s50, s64, s33
	v_lshl_add_u64 v[224:225], s[54:55], 0, v[130:131]
	s_mov_b32 m0, s50
	ds_read_b128 v[186:189], v153 offset:16384
	ds_read_b128 v[190:193], v153 offset:17408
	ds_read_b128 v[194:197], v153 offset:18432
	ds_read_b128 v[198:201], v153 offset:19456
	ds_read_b128 v[208:211], v153 offset:20480
	ds_read_b128 v[212:215], v153 offset:21504
	ds_read_b128 v[216:219], v153 offset:22528
	ds_read_b128 v[220:223], v153 offset:23552
	global_load_lds_dwordx4 v[224:225], off
	s_add_i32 m0, s50, 0x2000
	s_add_u32 s50, s54, 0xb0000
	v_lshl_add_u64 v[226:227], s[54:55], 0, v[134:135]
	s_addc_u32 s51, s55, 0
	s_add_i32 s78, s65, s33
	global_load_lds_dwordx4 v[226:227], off
	v_lshl_add_u64 v[228:229], s[50:51], 0, v[130:131]
	s_mov_b32 m0, s78
	global_load_lds_dwordx4 v[228:229], off
	v_lshl_add_u64 v[228:229], s[50:51], 0, v[134:135]
	s_add_i32 m0, s78, 0x2000
	s_nop 0
	global_load_lds_dwordx4 v[228:229], off
	s_waitcnt vmcnt(6)
	s_waitcnt lgkmcnt(0)
	s_barrier
	s_setprio 1
	s_waitcnt lgkmcnt(0)
	v_mfma_f32_16x16x32_bf16 v[60:63], v[144:147], v[186:189], v[60:63]
	v_mfma_f32_16x16x32_bf16 v[56:59], v[160:163], v[186:189], v[56:59]
	v_mfma_f32_16x16x32_bf16 v[44:47], v[144:147], v[194:197], v[44:47]
	v_mfma_f32_16x16x32_bf16 v[40:43], v[160:163], v[194:197], v[40:43]
	v_mfma_f32_16x16x32_bf16 v[28:31], v[144:147], v[208:211], v[28:31]
	v_mfma_f32_16x16x32_bf16 v[24:27], v[160:163], v[208:211], v[24:27]
	v_mfma_f32_16x16x32_bf16 v[12:15], v[144:147], v[216:219], v[12:15]
	v_mfma_f32_16x16x32_bf16 v[8:11], v[160:163], v[216:219], v[8:11]
	v_mfma_f32_16x16x32_bf16 v[60:63], v[156:159], v[190:193], v[60:63]
	v_mfma_f32_16x16x32_bf16 v[56:59], v[164:167], v[190:193], v[56:59]
	v_mfma_f32_16x16x32_bf16 v[44:47], v[156:159], v[198:201], v[44:47]
	v_mfma_f32_16x16x32_bf16 v[40:43], v[164:167], v[198:201], v[40:43]
	v_lshl_add_u64 v[228:229], s[56:57], 0, v[128:129]
	s_mov_b32 m0, s34
	s_nop 0
	global_load_lds_dwordx4 v[228:229], off
	v_mfma_f32_16x16x32_bf16 v[28:31], v[156:159], v[212:215], v[28:31]
	v_mfma_f32_16x16x32_bf16 v[24:27], v[164:167], v[212:215], v[24:27]
	v_mfma_f32_16x16x32_bf16 v[12:15], v[156:159], v[220:223], v[12:15]
	v_mfma_f32_16x16x32_bf16 v[8:11], v[164:167], v[220:223], v[8:11]
	s_setprio 0
	s_setprio 1
	v_mfma_f32_16x16x32_bf16 v[52:55], v[168:171], v[186:189], v[52:55]
	v_mfma_f32_16x16x32_bf16 v[48:51], v[176:179], v[186:189], v[48:51]
	v_mfma_f32_16x16x32_bf16 v[36:39], v[168:171], v[194:197], v[36:39]
	v_mfma_f32_16x16x32_bf16 v[32:35], v[176:179], v[194:197], v[32:35]
	v_mfma_f32_16x16x32_bf16 v[20:23], v[168:171], v[208:211], v[20:23]
	v_mfma_f32_16x16x32_bf16 v[16:19], v[176:179], v[208:211], v[16:19]
	v_mfma_f32_16x16x32_bf16 v[4:7], v[168:171], v[216:219], v[4:7]
	v_mfma_f32_16x16x32_bf16 v[0:3], v[176:179], v[216:219], v[0:3]
	v_mfma_f32_16x16x32_bf16 v[52:55], v[172:175], v[190:193], v[52:55]
	v_mfma_f32_16x16x32_bf16 v[48:51], v[182:185], v[190:193], v[48:51]
	v_mfma_f32_16x16x32_bf16 v[36:39], v[172:175], v[198:201], v[36:39]
	v_mfma_f32_16x16x32_bf16 v[32:35], v[182:185], v[198:201], v[32:35]
	v_lshl_add_u64 v[230:231], s[56:57], 0, v[132:133]
	s_mov_b32 m0, s58
	s_nop 0
	global_load_lds_dwordx4 v[230:231], off
	v_mfma_f32_16x16x32_bf16 v[20:23], v[172:175], v[212:215], v[20:23]
	v_mfma_f32_16x16x32_bf16 v[16:19], v[182:185], v[212:215], v[16:19]
	v_mfma_f32_16x16x32_bf16 v[4:7], v[172:175], v[220:223], v[4:7]
	v_mfma_f32_16x16x32_bf16 v[0:3], v[182:185], v[220:223], v[0:3]
	s_setprio 0
	s_barrier
; #define PG8_STAGE(bufoff, gbase, voff) do { _Pragma("unroll") for (int _i = 0; _i < 2; ++_i) \
;         __builtin_amdgcn_global_load_lds((const unsigned*)((const char*)(gbase) + (voff)[_i]), (PG8_LAS unsigned*)(lds + (bufoff) + ldsw + _i * 8192), 16, 0, 0); } while (0)
; #define PG8_LDA(dst, b, h) do { _Pragma("unroll") for (int m = 0; m < 4; ++m) _Pragma("unroll") for (int k = 0; k < 2; ++k) dst[m][k] = *(const PG8_LAS bf16x8*)(lds + PG8_SA(b, h) + aoff + m * 2048 + k * 1024); } while (0)
; #define PG8_LDB(dst, b, h) do { _Pragma("unroll") for (int n = 0; n < 2; ++n) _Pragma("unroll") for (int k = 0; k < 2; ++k) dst[n][k] = *(const PG8_LAS bf16x8*)(lds + PG8_SB(b, h) + boff + n * 2048 + k * 1024); } while (0)
; #define PG8_MMA(ai, bj, At, Bt) do { __builtin_amdgcn_s_setprio(1); _Pragma("unroll") for (int m = 0; m < 4; ++m) _Pragma("unroll") for (int n = 0; n < 2; ++n) _Pragma("unroll") for (int k = 0; k < 2; ++k) \
;         acc[ai][bj][m][n] = __builtin_amdgcn_mfma_f32_16x16x32_bf16(Bt[n][k], At[m][k], acc[ai][bj][m][n], 0, 0, 0); __builtin_amdgcn_s_setprio(0); } while (0)
; #define PG8_WAIT_V(n) asm volatile("s_waitcnt vmcnt(" #n ")" ::: "memory")
; #define PG8_WAIT_L(n) asm volatile("s_waitcnt lgkmcnt(" #n ")" ::: "memory")
; #define PG8_BAR __builtin_amdgcn_s_barrier()
; #define PG8_SCHED __builtin_amdgcn_sched_barrier(0)
; template <class Epi, class Sched, bool ALIGN_EPI = false, bool SP2 = false>
; __device__ __forceinline__ void gemm_phase(PG8_LAS unsigned char* lds, const Gemm g, const Sched& S, const Epi& E) {
;     ...
;             PG8_LDB(B0, 1, 0); PG8_LDB(B1, 1, 1); PG8_SCHED; PG8_LDA(At, 1, 0); PG8_STAGE(PG8_SA(0, 1), a2 + hstep, voffA);
;             PG8_WAIT_V(8); PG8_WAIT_L(0); PG8_BAR; PG8_MMA(0, 0, At, B0); PG8_MMA(0, 1, At, B1); PG8_BAR; PG8_SCHED;
	s_add_i32 s78, 0, 0x18000
	v_add_u32_e32 v155, s78, v149
	s_add_i32 s79, 0, 0x1c000
	ds_read_b128 v[144:147], v155
	ds_read_b128 v[156:159], v155 offset:1024
	ds_read_b128 v[160:163], v155 offset:2048
	ds_read_b128 v[164:167], v155 offset:3072
	v_add_u32_e32 v155, s79, v149
	ds_read_b128 v[168:171], v155
	ds_read_b128 v[172:175], v155 offset:1024
	ds_read_b128 v[176:179], v155 offset:2048
	ds_read_b128 v[182:185], v155 offset:3072
	s_add_u32 s50, s56, 0xb0000
	s_addc_u32 s51, s57, 0
	s_mov_b32 m0, s59
	v_lshl_add_u64 v[232:233], s[50:51], 0, v[128:129]
	ds_read_b128 v[186:189], v153 offset:32768
	ds_read_b128 v[190:193], v153 offset:33792
	ds_read_b128 v[194:197], v153 offset:34816
	ds_read_b128 v[198:201], v153 offset:35840
	ds_read_b128 v[208:211], v153 offset:36864
	ds_read_b128 v[212:215], v153 offset:37888
	ds_read_b128 v[216:219], v153 offset:38912
	ds_read_b128 v[220:223], v153 offset:39936
	global_load_lds_dwordx4 v[232:233], off
	v_lshl_add_u64 v[232:233], s[50:51], 0, v[132:133]
	s_mov_b32 m0, s60
	s_nop 0
	global_load_lds_dwordx4 v[232:233], off
	s_waitcnt vmcnt(8)
	s_waitcnt lgkmcnt(0)
	s_barrier
	s_setprio 1
	s_waitcnt lgkmcnt(0)
	v_mfma_f32_16x16x32_bf16 v[124:127], v[144:147], v[186:189], v[124:127]
	v_mfma_f32_16x16x32_bf16 v[120:123], v[160:163], v[186:189], v[120:123]
	v_mfma_f32_16x16x32_bf16 v[108:111], v[144:147], v[194:197], v[108:111]
	v_mfma_f32_16x16x32_bf16 v[104:107], v[160:163], v[194:197], v[104:107]
	v_mfma_f32_16x16x32_bf16 v[92:95], v[144:147], v[208:211], v[92:95]
	v_mfma_f32_16x16x32_bf16 v[88:91], v[160:163], v[208:211], v[88:91]
	v_mfma_f32_16x16x32_bf16 v[76:79], v[144:147], v[216:219], v[76:79]
	v_mfma_f32_16x16x32_bf16 v[72:75], v[160:163], v[216:219], v[72:75]
	v_mfma_f32_16x16x32_bf16 v[124:127], v[156:159], v[190:193], v[124:127]
	v_mfma_f32_16x16x32_bf16 v[120:123], v[164:167], v[190:193], v[120:123]
	v_mfma_f32_16x16x32_bf16 v[108:111], v[156:159], v[198:201], v[108:111]
	v_mfma_f32_16x16x32_bf16 v[104:107], v[164:167], v[198:201], v[104:107]
	v_mfma_f32_16x16x32_bf16 v[92:95], v[156:159], v[212:215], v[92:95]
	v_mfma_f32_16x16x32_bf16 v[88:91], v[164:167], v[212:215], v[88:91]
	v_mfma_f32_16x16x32_bf16 v[76:79], v[156:159], v[220:223], v[76:79]
	v_mfma_f32_16x16x32_bf16 v[72:75], v[164:167], v[220:223], v[72:75]
	s_setprio 0
	s_setprio 1
	v_mfma_f32_16x16x32_bf16 v[116:119], v[168:171], v[186:189], v[116:119]
	v_mfma_f32_16x16x32_bf16 v[112:115], v[176:179], v[186:189], v[112:115]
	v_mfma_f32_16x16x32_bf16 v[100:103], v[168:171], v[194:197], v[100:103]
	v_mfma_f32_16x16x32_bf16 v[96:99], v[176:179], v[194:197], v[96:99]
	v_mfma_f32_16x16x32_bf16 v[84:87], v[168:171], v[208:211], v[84:87]
	v_mfma_f32_16x16x32_bf16 v[80:83], v[176:179], v[208:211], v[80:83]
	v_mfma_f32_16x16x32_bf16 v[68:71], v[168:171], v[216:219], v[68:71]
	v_mfma_f32_16x16x32_bf16 v[64:67], v[176:179], v[216:219], v[64:67]
	v_mfma_f32_16x16x32_bf16 v[116:119], v[172:175], v[190:193], v[116:119]
	v_mfma_f32_16x16x32_bf16 v[112:115], v[182:185], v[190:193], v[112:115]
	v_mfma_f32_16x16x32_bf16 v[100:103], v[172:175], v[198:201], v[100:103]
	v_mfma_f32_16x16x32_bf16 v[96:99], v[182:185], v[198:201], v[96:99]
	v_mfma_f32_16x16x32_bf16 v[84:87], v[172:175], v[212:215], v[84:87]
	v_mfma_f32_16x16x32_bf16 v[80:83], v[182:185], v[212:215], v[80:83]
	v_mfma_f32_16x16x32_bf16 v[68:71], v[172:175], v[220:223], v[68:71]
	v_mfma_f32_16x16x32_bf16 v[64:67], v[182:185], v[220:223], v[64:67]
	s_setprio 0
	s_barrier
; #define PG8_STAGE(bufoff, gbase, voff) do { _Pragma("unroll") for (int _i = 0; _i < 2; ++_i) \
;         __builtin_amdgcn_global_load_lds((const unsigned*)((const char*)(gbase) + (voff)[_i]), (PG8_LAS unsigned*)(lds + (bufoff) + ldsw + _i * 8192), 16, 0, 0); } while (0)
; #define PG8_LDA(dst, b, h) do { _Pragma("unroll") for (int m = 0; m < 4; ++m) _Pragma("unroll") for (int k = 0; k < 2; ++k) dst[m][k] = *(const PG8_LAS bf16x8*)(lds + PG8_SA(b, h) + aoff + m * 2048 + k * 1024); } while (0)
; #define PG8_MMA(ai, bj, At, Bt) do { __builtin_amdgcn_s_setprio(1); _Pragma("unroll") for (int m = 0; m < 4; ++m) _Pragma("unroll") for (int n = 0; n < 2; ++n) _Pragma("unroll") for (int k = 0; k < 2; ++k) \
;         acc[ai][bj][m][n] = __builtin_amdgcn_mfma_f32_16x16x32_bf16(Bt[n][k], At[m][k], acc[ai][bj][m][n], 0, 0, 0); __builtin_amdgcn_s_setprio(0); } while (0)
; #define PG8_WAIT_V(n) asm volatile("s_waitcnt vmcnt(" #n ")" ::: "memory")
; #define PG8_WAIT_L(n) asm volatile("s_waitcnt lgkmcnt(" #n ")" ::: "memory")
; #define PG8_BAR __builtin_amdgcn_s_barrier()
; #define PG8_SCHED __builtin_amdgcn_sched_barrier(0)
; template <class Epi, class Sched, bool ALIGN_EPI = false, bool SP2 = false>
; __device__ __forceinline__ void gemm_phase(PG8_LAS unsigned char* lds, const Gemm g, const Sched& S, const Epi& E) {
;     ...
;             PG8_LDA(At, 1, 1); PG8_STAGE(PG8_SB(1, 0), b3, voffB); PG8_STAGE(PG8_SB(1, 1), b3 + hstep, voffB); PG8_STAGE(PG8_SA(1, 0), a3, voffA);
;             PG8_WAIT_V(8); PG8_WAIT_L(0); PG8_BAR; PG8_MMA(1, 0, At, B0); PG8_MMA(1, 1, At, B1); PG8_BAR; PG8_SCHED;
;     ...
;         if constexpr (ALIGN_EPI) { if (wr == 0) PG8_BAR; }
	s_add_i32 s50, s78, s33
	v_lshl_add_u64 v[224:225], v[224:225], 0, s[42:43]
	s_mov_b32 m0, s50
	ds_read_b128 v[186:189], v153 offset:49152
	ds_read_b128 v[190:193], v153 offset:50176
	ds_read_b128 v[194:197], v153 offset:51200
	ds_read_b128 v[198:201], v153 offset:52224
	ds_read_b128 v[208:211], v153 offset:53248
	ds_read_b128 v[212:215], v153 offset:54272
	ds_read_b128 v[216:219], v153 offset:55296
	ds_read_b128 v[220:223], v153 offset:56320
	global_load_lds_dwordx4 v[224:225], off
	s_add_i32 m0, s50, 0x2000
	s_add_u32 s50, s54, 0xb0080
	v_lshl_add_u64 v[224:225], v[226:227], 0, s[42:43]
	s_addc_u32 s51, s55, 0
	s_add_i32 s54, s79, s33
	global_load_lds_dwordx4 v[224:225], off
	v_lshl_add_u64 v[224:225], s[50:51], 0, v[130:131]
	s_mov_b32 m0, s54
	s_nop 0
	global_load_lds_dwordx4 v[224:225], off
	v_lshl_add_u64 v[224:225], s[50:51], 0, v[134:135]
	s_add_i32 m0, s54, 0x2000
	s_nop 0
	global_load_lds_dwordx4 v[224:225], off
	s_waitcnt vmcnt(6)
	s_waitcnt lgkmcnt(0)
	s_barrier
	s_setprio 1
	s_waitcnt lgkmcnt(0)
	v_mfma_f32_16x16x32_bf16 v[60:63], v[144:147], v[186:189], v[60:63]
	v_mfma_f32_16x16x32_bf16 v[56:59], v[160:163], v[186:189], v[56:59]
	v_mfma_f32_16x16x32_bf16 v[44:47], v[144:147], v[194:197], v[44:47]
	v_mfma_f32_16x16x32_bf16 v[40:43], v[160:163], v[194:197], v[40:43]
	v_mfma_f32_16x16x32_bf16 v[28:31], v[144:147], v[208:211], v[28:31]
	v_mfma_f32_16x16x32_bf16 v[24:27], v[160:163], v[208:211], v[24:27]
	v_mfma_f32_16x16x32_bf16 v[12:15], v[144:147], v[216:219], v[12:15]
	v_mfma_f32_16x16x32_bf16 v[8:11], v[160:163], v[216:219], v[8:11]
	v_mfma_f32_16x16x32_bf16 v[60:63], v[156:159], v[190:193], v[60:63]
	v_mfma_f32_16x16x32_bf16 v[56:59], v[164:167], v[190:193], v[56:59]
	v_mfma_f32_16x16x32_bf16 v[44:47], v[156:159], v[198:201], v[44:47]
	v_mfma_f32_16x16x32_bf16 v[40:43], v[164:167], v[198:201], v[40:43]
	v_lshl_add_u64 v[224:225], v[228:229], 0, s[42:43]
	s_mov_b32 m0, s62
	s_nop 0
	global_load_lds_dwordx4 v[224:225], off
	v_mfma_f32_16x16x32_bf16 v[28:31], v[156:159], v[212:215], v[28:31]
	v_mfma_f32_16x16x32_bf16 v[24:27], v[164:167], v[212:215], v[24:27]
	v_mfma_f32_16x16x32_bf16 v[12:15], v[156:159], v[220:223], v[12:15]
	v_mfma_f32_16x16x32_bf16 v[8:11], v[164:167], v[220:223], v[8:11]
	s_setprio 0
	s_setprio 1
	v_mfma_f32_16x16x32_bf16 v[52:55], v[168:171], v[186:189], v[52:55]
	v_mfma_f32_16x16x32_bf16 v[48:51], v[176:179], v[186:189], v[48:51]
	v_mfma_f32_16x16x32_bf16 v[36:39], v[168:171], v[194:197], v[36:39]
	v_mfma_f32_16x16x32_bf16 v[32:35], v[176:179], v[194:197], v[32:35]
	v_mfma_f32_16x16x32_bf16 v[20:23], v[168:171], v[208:211], v[20:23]
	v_mfma_f32_16x16x32_bf16 v[16:19], v[176:179], v[208:211], v[16:19]
	v_mfma_f32_16x16x32_bf16 v[4:7], v[168:171], v[216:219], v[4:7]
	v_mfma_f32_16x16x32_bf16 v[0:3], v[176:179], v[216:219], v[0:3]
	v_mfma_f32_16x16x32_bf16 v[52:55], v[172:175], v[190:193], v[52:55]
	v_mfma_f32_16x16x32_bf16 v[48:51], v[182:185], v[190:193], v[48:51]
	v_mfma_f32_16x16x32_bf16 v[36:39], v[172:175], v[198:201], v[36:39]
	v_mfma_f32_16x16x32_bf16 v[32:35], v[182:185], v[198:201], v[32:35]
	v_lshl_add_u64 v[224:225], v[230:231], 0, s[42:43]
	s_mov_b32 m0, s63
	s_nop 0
	global_load_lds_dwordx4 v[224:225], off
	v_mfma_f32_16x16x32_bf16 v[20:23], v[172:175], v[212:215], v[20:23]
	v_mfma_f32_16x16x32_bf16 v[16:19], v[182:185], v[212:215], v[16:19]
	v_mfma_f32_16x16x32_bf16 v[4:7], v[172:175], v[220:223], v[4:7]
	v_mfma_f32_16x16x32_bf16 v[0:3], v[182:185], v[220:223], v[0:3]
	s_setprio 0
	s_barrier
	s_add_i32 s84, s84, 2
	s_add_u32 s82, s82, 0x100
	s_addc_u32 s83, s83, 0
	s_cmp_gt_u32 s84, 41
	s_mov_b64 s[50:51], s[52:53]
	s_cbranch_scc0 .LBB0_1197
	s_and_b64 vcc, exec, s[44:45]
	s_cbranch_vccz .LBB0_1200
	s_barrier

; #define PG8_STAGE(bufoff, gbase, voff) do { _Pragma("unroll") for (int _i = 0; _i < 2; ++_i) \
;         __builtin_amdgcn_global_load_lds((const unsigned*)((const char*)(gbase) + (voff)[_i]), (PG8_LAS unsigned*)(lds + (bufoff) + ldsw + _i * 8192), 16, 0, 0); } while (0)
; #define PG8_LDA(dst, b, h) do { _Pragma("unroll") for (int m = 0; m < 4; ++m) _Pragma("unroll") for (int k = 0; k < 2; ++k) dst[m][k] = *(const PG8_LAS bf16x8*)(lds + PG8_SA(b, h) + aoff + m * 2048 + k * 1024); } while (0)
; #define PG8_LDB(dst, b, h) do { _Pragma("unroll") for (int n = 0; n < 2; ++n) _Pragma("unroll") for (int k = 0; k < 2; ++k) dst[n][k] = *(const PG8_LAS bf16x8*)(lds + PG8_SB(b, h) + boff + n * 2048 + k * 1024); } while (0)
; #define PG8_MMA(ai, bj, At, Bt) do { __builtin_amdgcn_s_setprio(1); _Pragma("unroll") for (int m = 0; m < 4; ++m) _Pragma("unroll") for (int n = 0; n < 2; ++n) _Pragma("unroll") for (int k = 0; k < 2; ++k) \
;         acc[ai][bj][m][n] = __builtin_amdgcn_mfma_f32_16x16x32_bf16(Bt[n][k], At[m][k], acc[ai][bj][m][n], 0, 0, 0); __builtin_amdgcn_s_setprio(0); } while (0)
; #define PG8_BAR __builtin_amdgcn_s_barrier()
; template <class Epi, class Sched, bool ALIGN_EPI = false, bool SP2 = false>
; __device__ __forceinline__ void gemm_phase(PG8_LAS unsigned char* lds, const Gemm g, const Sched& S, const Epi& E) {
;     ...
;         const bool has_next = S.next(ui + 1, nxt);
;         const char* nA = has_next ? (const char*)g.A + (size_t)nxt.pm * tstep : cA; const char* nB = has_next ? (const char*)g.Bt + (size_t)nxt.pn * tstep : cB;
;         for (int t = 0; t < nt; t += 2) {
;             const bool last = (t == nt - 2);
;             const char* a1 = cA + (size_t)(t + 1) * kstep;
;             const char* a2 = last ? nA : cA + (size_t)(t + 2) * kstep; const char* b2 = last ? nB : cB + (size_t)(t + 2) * kstep;
;             const char* a3 = a2 + kstep; const char* b3 = b2 + kstep;
;             if (last && has_next) S.a_ready(nxt);
;             if constexpr (SP2) {
;             PG8_LDB(B0, 0, 0); PG8_LDB(B1, 0, 1); PG8_SCHED; PG8_LDA(At, 0, 0); PG8_STAGE(PG8_SA(1, 1), a1 + hstep, voffA);
;             PG8_WAIT_V(8); PG8_WAIT_L(0); PG8_BAR; PG8_MMA(0, 0, At, B0); PG8_MMA(0, 1, At, B1); PG8_BAR; PG8_SCHED;
;             PG8_LDA(At, 0, 1); PG8_STAGE(PG8_SB(0, 0), b2, voffB); PG8_STAGE(PG8_SB(0, 1), b2 + hstep, voffB); PG8_STAGE(PG8_SA(0, 0), a2, voffA);
.LBB0_1286:
	s_ashr_i32 s51, s50, 31
	s_lshl_b64 s[52:53], s[50:51], 19
	s_add_u32 s52, s22, s52
	s_addc_u32 s53, s23, s53
	s_and_b64 s[54:55], s[12:13], exec
	s_cselect_b32 s51, s53, s59
	s_cselect_b32 s61, s52, s58
	s_ashr_i32 s49, s48, 31
	s_lshl_b64 s[54:55], s[48:49], 19
	v_readlane_b32 s64, v250, 9
	v_readlane_b32 s65, v250, 10
	s_add_u32 s54, s64, s54
	s_addc_u32 s55, s65, s55
	s_and_b64 s[64:65], s[12:13], exec
	s_cselect_b32 s49, s55, s63
	s_cselect_b32 s87, s54, s62
	s_add_u32 s58, s58, 0x40080
	s_addc_u32 s59, s59, 0
	s_add_u32 s88, s62, 0x100
	s_addc_u32 s89, s63, 0
	s_mov_b32 s90, -2
	s_waitcnt lgkmcnt(0)
	ds_read_b128 v[128:131], v181
	ds_read_b128 v[160:163], v181 offset:1024
	ds_read_b128 v[164:167], v181 offset:2048
	ds_read_b128 v[168:171], v181 offset:3072
	ds_read_b128 v[172:175], v203
	ds_read_b128 v[176:179], v203 offset:1024
	ds_read_b128 v[182:185], v203 offset:2048
	ds_read_b128 v[186:189], v203 offset:3072
	s_add_u32 s62, s58, 0xfffc0080
	s_addc_u32 s63, s59, -1
	s_cmp_eq_u32 s90, 12
	s_cselect_b32 s65, s51, s63
	s_cselect_b32 s64, s61, s62
	s_cselect_b32 s63, s49, s89
	s_cselect_b32 s62, s87, s88
	v_lshl_add_u64 v[232:233], s[58:59], 0, v[152:153]
	s_add_i32 m0, s15, 0xc000
	ds_read_b128 v[190:193], v208
	ds_read_b128 v[194:197], v208 offset:1024
	ds_read_b128 v[198:201], v208 offset:2048
	ds_read_b128 v[212:215], v208 offset:3072
	ds_read_b128 v[216:219], v208 offset:4096
	ds_read_b128 v[220:223], v208 offset:5120
	ds_read_b128 v[224:227], v208 offset:6144
	ds_read_b128 v[228:231], v208 offset:7168
	global_load_lds_dwordx4 v[232:233], off
	v_lshl_add_u64 v[232:233], s[58:59], 0, v[154:155]
	s_add_i32 m0, s15, 0xe000
	s_nop 0
	global_load_lds_dwordx4 v[232:233], off
	s_waitcnt vmcnt(8)
	s_waitcnt lgkmcnt(0)
	s_barrier
	s_setprio 1
	s_waitcnt lgkmcnt(0)
	v_mfma_f32_16x16x32_bf16 v[124:127], v[128:131], v[190:193], 0
	v_mfma_f32_16x16x32_bf16 v[120:123], v[164:167], v[190:193], 0
	v_mfma_f32_16x16x32_bf16 v[116:119], v[128:131], v[198:201], 0
	v_mfma_f32_16x16x32_bf16 v[112:115], v[164:167], v[198:201], 0
	v_mfma_f32_16x16x32_bf16 v[108:111], v[128:131], v[216:219], 0
	v_mfma_f32_16x16x32_bf16 v[104:107], v[164:167], v[216:219], 0
	v_mfma_f32_16x16x32_bf16 v[100:103], v[128:131], v[224:227], 0
	v_mfma_f32_16x16x32_bf16 v[96:99], v[164:167], v[224:227], 0
	v_mfma_f32_16x16x32_bf16 v[124:127], v[160:163], v[194:197], v[124:127]
	v_mfma_f32_16x16x32_bf16 v[120:123], v[168:171], v[194:197], v[120:123]
	v_mfma_f32_16x16x32_bf16 v[116:119], v[160:163], v[212:215], v[116:119]
	v_mfma_f32_16x16x32_bf16 v[112:115], v[168:171], v[212:215], v[112:115]
	v_mfma_f32_16x16x32_bf16 v[108:111], v[160:163], v[220:223], v[108:111]
	v_mfma_f32_16x16x32_bf16 v[104:107], v[168:171], v[220:223], v[104:107]
	v_mfma_f32_16x16x32_bf16 v[100:103], v[160:163], v[228:231], v[100:103]
	v_mfma_f32_16x16x32_bf16 v[96:99], v[168:171], v[228:231], v[96:99]
	s_setprio 0
	s_setprio 1
	v_mfma_f32_16x16x32_bf16 v[60:63], v[172:175], v[190:193], 0
	v_mfma_f32_16x16x32_bf16 v[56:59], v[182:185], v[190:193], 0
	v_mfma_f32_16x16x32_bf16 v[52:55], v[172:175], v[198:201], 0
	v_mfma_f32_16x16x32_bf16 v[48:51], v[182:185], v[198:201], 0
	v_mfma_f32_16x16x32_bf16 v[44:47], v[172:175], v[216:219], 0
	v_mfma_f32_16x16x32_bf16 v[40:43], v[182:185], v[216:219], 0
	v_mfma_f32_16x16x32_bf16 v[36:39], v[172:175], v[224:227], 0
	v_mfma_f32_16x16x32_bf16 v[32:35], v[182:185], v[224:227], 0
	v_mfma_f32_16x16x32_bf16 v[60:63], v[176:179], v[194:197], v[60:63]
	v_mfma_f32_16x16x32_bf16 v[56:59], v[186:189], v[194:197], v[56:59]
	v_mfma_f32_16x16x32_bf16 v[52:55], v[176:179], v[212:215], v[52:55]
	v_mfma_f32_16x16x32_bf16 v[48:51], v[186:189], v[212:215], v[48:51]
	v_mfma_f32_16x16x32_bf16 v[44:47], v[176:179], v[220:223], v[44:47]
	v_mfma_f32_16x16x32_bf16 v[40:43], v[186:189], v[220:223], v[40:43]
	v_mfma_f32_16x16x32_bf16 v[36:39], v[176:179], v[228:231], v[36:39]
	v_mfma_f32_16x16x32_bf16 v[32:35], v[186:189], v[228:231], v[32:35]
	s_setprio 0
	s_barrier
	s_add_i32 s78, s75, s14
	v_lshl_add_u64 v[232:233], s[62:63], 0, v[134:135]
	s_mov_b32 m0, s78
	ds_read_b128 v[190:193], v208 offset:16384
	ds_read_b128 v[194:197], v208 offset:17408
	ds_read_b128 v[198:201], v208 offset:18432
	ds_read_b128 v[212:215], v208 offset:19456
	ds_read_b128 v[216:219], v208 offset:20480
	ds_read_b128 v[220:223], v208 offset:21504
	ds_read_b128 v[224:227], v208 offset:22528
	ds_read_b128 v[228:231], v208 offset:23552
	global_load_lds_dwordx4 v[232:233], off
	s_add_i32 m0, s78, 0x2000
	s_add_u32 s78, s62, 0x40000
	v_lshl_add_u64 v[234:235], s[62:63], 0, v[138:139]
	s_addc_u32 s79, s63, 0
	s_add_i32 s91, s76, s14
	global_load_lds_dwordx4 v[234:235], off
	v_lshl_add_u64 v[236:237], s[78:79], 0, v[134:135]
	s_mov_b32 m0, s91
	global_load_lds_dwordx4 v[236:237], off
	v_lshl_add_u64 v[236:237], s[78:79], 0, v[138:139]
	s_add_i32 m0, s91, 0x2000
	s_nop 0
	global_load_lds_dwordx4 v[236:237], off
	s_waitcnt vmcnt(6)
	s_waitcnt lgkmcnt(0)
	s_barrier
; #define PG8_STAGE(bufoff, gbase, voff) do { _Pragma("unroll") for (int _i = 0; _i < 2; ++_i) \
;         __builtin_amdgcn_global_load_lds((const unsigned*)((const char*)(gbase) + (voff)[_i]), (PG8_LAS unsigned*)(lds + (bufoff) + ldsw + _i * 8192), 16, 0, 0); } while (0)
; #define PG8_LDA(dst, b, h) do { _Pragma("unroll") for (int m = 0; m < 4; ++m) _Pragma("unroll") for (int k = 0; k < 2; ++k) dst[m][k] = *(const PG8_LAS bf16x8*)(lds + PG8_SA(b, h) + aoff + m * 2048 + k * 1024); } while (0)
; #define PG8_LDB(dst, b, h) do { _Pragma("unroll") for (int n = 0; n < 2; ++n) _Pragma("unroll") for (int k = 0; k < 2; ++k) dst[n][k] = *(const PG8_LAS bf16x8*)(lds + PG8_SB(b, h) + boff + n * 2048 + k * 1024); } while (0)
; #define PG8_MMA(ai, bj, At, Bt) do { __builtin_amdgcn_s_setprio(1); _Pragma("unroll") for (int m = 0; m < 4; ++m) _Pragma("unroll") for (int n = 0; n < 2; ++n) _Pragma("unroll") for (int k = 0; k < 2; ++k) \
;         acc[ai][bj][m][n] = __builtin_amdgcn_mfma_f32_16x16x32_bf16(Bt[n][k], At[m][k], acc[ai][bj][m][n], 0, 0, 0); __builtin_amdgcn_s_setprio(0); } while (0)
; #define PG8_WAIT_V(n) asm volatile("s_waitcnt vmcnt(" #n ")" ::: "memory")
; #define PG8_WAIT_L(n) asm volatile("s_waitcnt lgkmcnt(" #n ")" ::: "memory")
; #define PG8_BAR __builtin_amdgcn_s_barrier()
; #define PG8_SCHED __builtin_amdgcn_sched_barrier(0)
; template <class Epi, class Sched, bool ALIGN_EPI = false, bool SP2 = false>
; __device__ __forceinline__ void gemm_phase(PG8_LAS unsigned char* lds, const Gemm g, const Sched& S, const Epi& E) {
;     ...
;             PG8_LDA(At, 0, 1); PG8_STAGE(PG8_SB(0, 0), b2, voffB); PG8_STAGE(PG8_SB(0, 1), b2 + hstep, voffB); PG8_STAGE(PG8_SA(0, 0), a2, voffA);
;             PG8_WAIT_V(8); PG8_WAIT_L(0); PG8_BAR; PG8_MMA(1, 0, At, B0); PG8_MMA(1, 1, At, B1); PG8_BAR; PG8_SCHED;
;             PG8_LDB(B0, 1, 0); PG8_LDB(B1, 1, 1); PG8_SCHED; PG8_LDA(At, 1, 0); PG8_STAGE(PG8_SA(0, 1), a2 + hstep, voffA);
;             PG8_WAIT_V(8); PG8_WAIT_L(0); PG8_BAR; PG8_MMA(0, 0, At, B0); PG8_MMA(0, 1, At, B1); PG8_BAR; PG8_SCHED;
	s_setprio 1
	s_waitcnt lgkmcnt(0)
	v_mfma_f32_16x16x32_bf16 v[92:95], v[128:131], v[190:193], 0
	v_mfma_f32_16x16x32_bf16 v[88:91], v[164:167], v[190:193], 0
	v_mfma_f32_16x16x32_bf16 v[84:87], v[128:131], v[198:201], 0
	v_mfma_f32_16x16x32_bf16 v[80:83], v[164:167], v[198:201], 0
	v_mfma_f32_16x16x32_bf16 v[76:79], v[128:131], v[216:219], 0
	v_mfma_f32_16x16x32_bf16 v[72:75], v[164:167], v[216:219], 0
	v_mfma_f32_16x16x32_bf16 v[68:71], v[128:131], v[224:227], 0
	v_mfma_f32_16x16x32_bf16 v[64:67], v[164:167], v[224:227], 0
	v_mfma_f32_16x16x32_bf16 v[92:95], v[160:163], v[194:197], v[92:95]
	v_mfma_f32_16x16x32_bf16 v[88:91], v[168:171], v[194:197], v[88:91]
	v_mfma_f32_16x16x32_bf16 v[84:87], v[160:163], v[212:215], v[84:87]
	v_mfma_f32_16x16x32_bf16 v[80:83], v[168:171], v[212:215], v[80:83]
	v_lshl_add_u64 v[236:237], s[64:65], 0, v[132:133]
	s_mov_b32 m0, s15
	s_nop 0
	global_load_lds_dwordx4 v[236:237], off
	v_mfma_f32_16x16x32_bf16 v[76:79], v[160:163], v[220:223], v[76:79]
	v_mfma_f32_16x16x32_bf16 v[72:75], v[168:171], v[220:223], v[72:75]
	v_mfma_f32_16x16x32_bf16 v[68:71], v[160:163], v[228:231], v[68:71]
	v_mfma_f32_16x16x32_bf16 v[64:67], v[168:171], v[228:231], v[64:67]
	s_setprio 0
	s_setprio 1
	v_mfma_f32_16x16x32_bf16 v[28:31], v[172:175], v[190:193], 0
	v_mfma_f32_16x16x32_bf16 v[24:27], v[182:185], v[190:193], 0
	v_mfma_f32_16x16x32_bf16 v[20:23], v[172:175], v[198:201], 0
	v_mfma_f32_16x16x32_bf16 v[16:19], v[182:185], v[198:201], 0
	v_mfma_f32_16x16x32_bf16 v[12:15], v[172:175], v[216:219], 0
	v_mfma_f32_16x16x32_bf16 v[8:11], v[182:185], v[216:219], 0
	v_mfma_f32_16x16x32_bf16 v[4:7], v[172:175], v[224:227], 0
	v_mfma_f32_16x16x32_bf16 v[0:3], v[182:185], v[224:227], 0
	v_mfma_f32_16x16x32_bf16 v[28:31], v[176:179], v[194:197], v[28:31]
	v_mfma_f32_16x16x32_bf16 v[24:27], v[186:189], v[194:197], v[24:27]
	v_mfma_f32_16x16x32_bf16 v[20:23], v[176:179], v[212:215], v[20:23]
	v_mfma_f32_16x16x32_bf16 v[16:19], v[186:189], v[212:215], v[16:19]
	v_lshl_add_u64 v[238:239], s[64:65], 0, v[136:137]
	s_mov_b32 m0, s33
	s_nop 0
	global_load_lds_dwordx4 v[238:239], off
	v_mfma_f32_16x16x32_bf16 v[12:15], v[176:179], v[220:223], v[12:15]
	v_mfma_f32_16x16x32_bf16 v[8:11], v[186:189], v[220:223], v[8:11]
	v_mfma_f32_16x16x32_bf16 v[4:7], v[176:179], v[228:231], v[4:7]
	v_mfma_f32_16x16x32_bf16 v[0:3], v[186:189], v[228:231], v[0:3]
	s_setprio 0
	s_barrier
	s_add_i32 s78, 0, 0x18000
	v_add_u32_e32 v140, s78, v147
	s_add_i32 s79, 0, 0x1c000
	ds_read_b128 v[128:131], v140
	ds_read_b128 v[160:163], v140 offset:1024
	ds_read_b128 v[164:167], v140 offset:2048
	ds_read_b128 v[168:171], v140 offset:3072
	v_add_u32_e32 v140, s79, v147
	ds_read_b128 v[172:175], v140
	ds_read_b128 v[176:179], v140 offset:1024
	ds_read_b128 v[182:185], v140 offset:2048
	ds_read_b128 v[186:189], v140 offset:3072
	s_add_u32 s64, s64, 0x40000
	s_addc_u32 s65, s65, 0
	s_mov_b32 m0, s34
	v_lshl_add_u64 v[240:241], s[64:65], 0, v[132:133]
	ds_read_b128 v[190:193], v208 offset:32768
	ds_read_b128 v[194:197], v208 offset:33792
	ds_read_b128 v[198:201], v208 offset:34816
	ds_read_b128 v[212:215], v208 offset:35840
	ds_read_b128 v[216:219], v208 offset:36864
	ds_read_b128 v[220:223], v208 offset:37888
	ds_read_b128 v[224:227], v208 offset:38912
	ds_read_b128 v[228:231], v208 offset:39936
	global_load_lds_dwordx4 v[240:241], off
	v_lshl_add_u64 v[240:241], s[64:65], 0, v[136:137]
	s_mov_b32 m0, s57
	s_nop 0
	global_load_lds_dwordx4 v[240:241], off
	s_waitcnt vmcnt(8)
	s_waitcnt lgkmcnt(0)
	s_barrier
	s_setprio 1
	s_waitcnt lgkmcnt(0)
	v_mfma_f32_16x16x32_bf16 v[124:127], v[128:131], v[190:193], v[124:127]
	v_mfma_f32_16x16x32_bf16 v[120:123], v[164:167], v[190:193], v[120:123]
	v_mfma_f32_16x16x32_bf16 v[116:119], v[128:131], v[198:201], v[116:119]
	v_mfma_f32_16x16x32_bf16 v[112:115], v[164:167], v[198:201], v[112:115]
	v_mfma_f32_16x16x32_bf16 v[108:111], v[128:131], v[216:219], v[108:111]
	v_mfma_f32_16x16x32_bf16 v[104:107], v[164:167], v[216:219], v[104:107]
	v_mfma_f32_16x16x32_bf16 v[100:103], v[128:131], v[224:227], v[100:103]
	v_mfma_f32_16x16x32_bf16 v[96:99], v[164:167], v[224:227], v[96:99]
	v_mfma_f32_16x16x32_bf16 v[124:127], v[160:163], v[194:197], v[124:127]
	v_mfma_f32_16x16x32_bf16 v[120:123], v[168:171], v[194:197], v[120:123]
	v_mfma_f32_16x16x32_bf16 v[116:119], v[160:163], v[212:215], v[116:119]
	v_mfma_f32_16x16x32_bf16 v[112:115], v[168:171], v[212:215], v[112:115]
	v_mfma_f32_16x16x32_bf16 v[108:111], v[160:163], v[220:223], v[108:111]
	v_mfma_f32_16x16x32_bf16 v[104:107], v[168:171], v[220:223], v[104:107]
	v_mfma_f32_16x16x32_bf16 v[100:103], v[160:163], v[228:231], v[100:103]
	v_mfma_f32_16x16x32_bf16 v[96:99], v[168:171], v[228:231], v[96:99]
	s_setprio 0
	s_setprio 1
	v_mfma_f32_16x16x32_bf16 v[60:63], v[172:175], v[190:193], v[60:63]
	v_mfma_f32_16x16x32_bf16 v[56:59], v[182:185], v[190:193], v[56:59]
	v_mfma_f32_16x16x32_bf16 v[52:55], v[172:175], v[198:201], v[52:55]
	v_mfma_f32_16x16x32_bf16 v[48:51], v[182:185], v[198:201], v[48:51]
	v_mfma_f32_16x16x32_bf16 v[44:47], v[172:175], v[216:219], v[44:47]
	v_mfma_f32_16x16x32_bf16 v[40:43], v[182:185], v[216:219], v[40:43]
	v_mfma_f32_16x16x32_bf16 v[36:39], v[172:175], v[224:227], v[36:39]
	v_mfma_f32_16x16x32_bf16 v[32:35], v[182:185], v[224:227], v[32:35]
	v_mfma_f32_16x16x32_bf16 v[60:63], v[176:179], v[194:197], v[60:63]
	v_mfma_f32_16x16x32_bf16 v[56:59], v[186:189], v[194:197], v[56:59]
	v_mfma_f32_16x16x32_bf16 v[52:55], v[176:179], v[212:215], v[52:55]
	v_mfma_f32_16x16x32_bf16 v[48:51], v[186:189], v[212:215], v[48:51]
	v_mfma_f32_16x16x32_bf16 v[44:47], v[176:179], v[220:223], v[44:47]
	v_mfma_f32_16x16x32_bf16 v[40:43], v[186:189], v[220:223], v[40:43]
	v_mfma_f32_16x16x32_bf16 v[36:39], v[176:179], v[228:231], v[36:39]
	v_mfma_f32_16x16x32_bf16 v[32:35], v[186:189], v[228:231], v[32:35]
	s_setprio 0
	s_barrier
; #define PG8_STAGE(bufoff, gbase, voff) do { _Pragma("unroll") for (int _i = 0; _i < 2; ++_i) \
;         __builtin_amdgcn_global_load_lds((const unsigned*)((const char*)(gbase) + (voff)[_i]), (PG8_LAS unsigned*)(lds + (bufoff) + ldsw + _i * 8192), 16, 0, 0); } while (0)
; #define PG8_LDA(dst, b, h) do { _Pragma("unroll") for (int m = 0; m < 4; ++m) _Pragma("unroll") for (int k = 0; k < 2; ++k) dst[m][k] = *(const PG8_LAS bf16x8*)(lds + PG8_SA(b, h) + aoff + m * 2048 + k * 1024); } while (0)
; #define PG8_LDB(dst, b, h) do { _Pragma("unroll") for (int n = 0; n < 2; ++n) _Pragma("unroll") for (int k = 0; k < 2; ++k) dst[n][k] = *(const PG8_LAS bf16x8*)(lds + PG8_SB(b, h) + boff + n * 2048 + k * 1024); } while (0)
; #define PG8_MMA(ai, bj, At, Bt) do { __builtin_amdgcn_s_setprio(1); _Pragma("unroll") for (int m = 0; m < 4; ++m) _Pragma("unroll") for (int n = 0; n < 2; ++n) _Pragma("unroll") for (int k = 0; k < 2; ++k) \
;         acc[ai][bj][m][n] = __builtin_amdgcn_mfma_f32_16x16x32_bf16(Bt[n][k], At[m][k], acc[ai][bj][m][n], 0, 0, 0); __builtin_amdgcn_s_setprio(0); } while (0)
; template <class Epi, class Sched, bool ALIGN_EPI = false, bool SP2 = false>
; __device__ __forceinline__ void gemm_phase(PG8_LAS unsigned char* lds, const Gemm g, const Sched& S, const Epi& E) {
;     ...
;         for (int t = 0; t < nt; t += 2) {
;             const bool last = (t == nt - 2);
;             const char* a1 = cA + (size_t)(t + 1) * kstep;
;             const char* a2 = last ? nA : cA + (size_t)(t + 2) * kstep; const char* b2 = last ? nB : cB + (size_t)(t + 2) * kstep;
;             const char* a3 = a2 + kstep; const char* b3 = b2 + kstep;
;             if (last && has_next) S.a_ready(nxt);
;             if constexpr (SP2) {
;             PG8_LDB(B0, 0, 0); PG8_LDB(B1, 0, 1); PG8_SCHED; PG8_LDA(At, 0, 0); PG8_STAGE(PG8_SA(1, 1), a1 + hstep, voffA);
;             PG8_WAIT_V(8); PG8_WAIT_L(0); PG8_BAR; PG8_MMA(0, 0, At, B0); PG8_MMA(0, 1, At, B1); PG8_BAR; PG8_SCHED;
;             PG8_LDA(At, 0, 1); PG8_STAGE(PG8_SB(0, 0), b2, voffB); PG8_STAGE(PG8_SB(0, 1), b2 + hstep, voffB); PG8_STAGE(PG8_SA(0, 0), a2, voffA);
;     ...
;             PG8_LDA(At, 1, 1); PG8_STAGE(PG8_SB(1, 0), b3, voffB); PG8_STAGE(PG8_SB(1, 1), b3 + hstep, voffB); PG8_STAGE(PG8_SA(1, 0), a3, voffA);
;             PG8_WAIT_V(8); PG8_WAIT_L(0); PG8_BAR; PG8_MMA(1, 0, At, B0); PG8_MMA(1, 1, At, B1); PG8_BAR; PG8_SCHED;
	s_add_i32 s64, s78, s14
	v_lshl_add_u64 v[232:233], v[232:233], 0, s[42:43]
	s_mov_b32 m0, s64
	ds_read_b128 v[190:193], v208 offset:49152
	ds_read_b128 v[194:197], v208 offset:50176
	ds_read_b128 v[198:201], v208 offset:51200
	ds_read_b128 v[212:215], v208 offset:52224
	ds_read_b128 v[216:219], v208 offset:53248
	ds_read_b128 v[220:223], v208 offset:54272
	ds_read_b128 v[224:227], v208 offset:55296
	ds_read_b128 v[228:231], v208 offset:56320
	global_load_lds_dwordx4 v[232:233], off
	s_add_i32 m0, s64, 0x2000
	s_add_u32 s62, s62, 0x40080
	v_lshl_add_u64 v[232:233], v[234:235], 0, s[42:43]
	s_addc_u32 s63, s63, 0
	s_add_i32 s64, s79, s14
	global_load_lds_dwordx4 v[232:233], off
	v_lshl_add_u64 v[232:233], s[62:63], 0, v[134:135]
	s_mov_b32 m0, s64
	s_nop 0
	global_load_lds_dwordx4 v[232:233], off
	v_lshl_add_u64 v[232:233], s[62:63], 0, v[138:139]
	s_add_i32 m0, s64, 0x2000
	s_nop 0
	global_load_lds_dwordx4 v[232:233], off
	s_waitcnt vmcnt(6)
	s_waitcnt lgkmcnt(0)
	s_barrier
	s_setprio 1
	s_waitcnt lgkmcnt(0)
	v_mfma_f32_16x16x32_bf16 v[92:95], v[128:131], v[190:193], v[92:95]
	v_mfma_f32_16x16x32_bf16 v[88:91], v[164:167], v[190:193], v[88:91]
	v_mfma_f32_16x16x32_bf16 v[84:87], v[128:131], v[198:201], v[84:87]
	v_mfma_f32_16x16x32_bf16 v[80:83], v[164:167], v[198:201], v[80:83]
	v_mfma_f32_16x16x32_bf16 v[76:79], v[128:131], v[216:219], v[76:79]
	v_mfma_f32_16x16x32_bf16 v[72:75], v[164:167], v[216:219], v[72:75]
	v_mfma_f32_16x16x32_bf16 v[68:71], v[128:131], v[224:227], v[68:71]
	v_mfma_f32_16x16x32_bf16 v[64:67], v[164:167], v[224:227], v[64:67]
	v_mfma_f32_16x16x32_bf16 v[92:95], v[160:163], v[194:197], v[92:95]
	v_mfma_f32_16x16x32_bf16 v[88:91], v[168:171], v[194:197], v[88:91]
	v_mfma_f32_16x16x32_bf16 v[84:87], v[160:163], v[212:215], v[84:87]
	v_mfma_f32_16x16x32_bf16 v[80:83], v[168:171], v[212:215], v[80:83]
	v_lshl_add_u64 v[232:233], v[236:237], 0, s[42:43]
	s_mov_b32 m0, s67
	s_nop 0
	global_load_lds_dwordx4 v[232:233], off
	v_mfma_f32_16x16x32_bf16 v[76:79], v[160:163], v[220:223], v[76:79]
	v_mfma_f32_16x16x32_bf16 v[72:75], v[168:171], v[220:223], v[72:75]
	v_mfma_f32_16x16x32_bf16 v[68:71], v[160:163], v[228:231], v[68:71]
	v_mfma_f32_16x16x32_bf16 v[64:67], v[168:171], v[228:231], v[64:67]
	s_setprio 0
	s_setprio 1
	v_mfma_f32_16x16x32_bf16 v[28:31], v[172:175], v[190:193], v[28:31]
	v_mfma_f32_16x16x32_bf16 v[24:27], v[182:185], v[190:193], v[24:27]
	v_mfma_f32_16x16x32_bf16 v[20:23], v[172:175], v[198:201], v[20:23]
	v_mfma_f32_16x16x32_bf16 v[16:19], v[182:185], v[198:201], v[16:19]
	v_mfma_f32_16x16x32_bf16 v[12:15], v[172:175], v[216:219], v[12:15]
	v_mfma_f32_16x16x32_bf16 v[8:11], v[182:185], v[216:219], v[8:11]
	v_mfma_f32_16x16x32_bf16 v[4:7], v[172:175], v[224:227], v[4:7]
	v_mfma_f32_16x16x32_bf16 v[0:3], v[182:185], v[224:227], v[0:3]
	v_mfma_f32_16x16x32_bf16 v[28:31], v[176:179], v[194:197], v[28:31]
	v_mfma_f32_16x16x32_bf16 v[24:27], v[186:189], v[194:197], v[24:27]
	v_mfma_f32_16x16x32_bf16 v[20:23], v[176:179], v[212:215], v[20:23]
	v_mfma_f32_16x16x32_bf16 v[16:19], v[186:189], v[212:215], v[16:19]
	v_lshl_add_u64 v[232:233], v[238:239], 0, s[42:43]
	s_mov_b32 m0, s74
	s_nop 0
	global_load_lds_dwordx4 v[232:233], off
	v_mfma_f32_16x16x32_bf16 v[12:15], v[176:179], v[220:223], v[12:15]
	v_mfma_f32_16x16x32_bf16 v[8:11], v[186:189], v[220:223], v[8:11]
	v_mfma_f32_16x16x32_bf16 v[4:7], v[176:179], v[228:231], v[4:7]
	v_mfma_f32_16x16x32_bf16 v[0:3], v[186:189], v[228:231], v[0:3]
	s_setprio 0
	s_barrier
	s_add_i32 s90, s90, 2
	s_add_u32 s58, s58, 0x100
	s_addc_u32 s59, s59, 0
	s_add_u32 s88, s88, 0x100
	s_addc_u32 s89, s89, 0
.LBB0_1287:
	ds_read_b128 v[128:131], v181
	ds_read_b128 v[160:163], v181 offset:1024
	ds_read_b128 v[164:167], v181 offset:2048
	ds_read_b128 v[168:171], v181 offset:3072
	ds_read_b128 v[172:175], v203
	ds_read_b128 v[176:179], v203 offset:1024
	ds_read_b128 v[182:185], v203 offset:2048
	ds_read_b128 v[186:189], v203 offset:3072
	s_add_u32 s62, s58, 0xfffc0080
	s_addc_u32 s63, s59, -1
	s_cmp_eq_u32 s90, 12
	s_cselect_b32 s65, s51, s63
	s_cselect_b32 s64, s61, s62
	s_cselect_b32 s63, s49, s89
	s_cselect_b32 s62, s87, s88
	v_lshl_add_u64 v[232:233], s[58:59], 0, v[152:153]
	s_add_i32 m0, s15, 0xc000
	ds_read_b128 v[190:193], v208
	ds_read_b128 v[194:197], v208 offset:1024
	ds_read_b128 v[198:201], v208 offset:2048
	ds_read_b128 v[212:215], v208 offset:3072
	ds_read_b128 v[216:219], v208 offset:4096
	ds_read_b128 v[220:223], v208 offset:5120
	ds_read_b128 v[224:227], v208 offset:6144
	ds_read_b128 v[228:231], v208 offset:7168
	global_load_lds_dwordx4 v[232:233], off
	v_lshl_add_u64 v[232:233], s[58:59], 0, v[154:155]
	s_add_i32 m0, s15, 0xe000
	s_nop 0
	global_load_lds_dwordx4 v[232:233], off
	s_waitcnt vmcnt(8)
	s_waitcnt lgkmcnt(0)
	s_barrier
; #define PG8_STAGE(bufoff, gbase, voff) do { _Pragma("unroll") for (int _i = 0; _i < 2; ++_i) \
;         __builtin_amdgcn_global_load_lds((const unsigned*)((const char*)(gbase) + (voff)[_i]), (PG8_LAS unsigned*)(lds + (bufoff) + ldsw + _i * 8192), 16, 0, 0); } while (0)
; #define PG8_LDA(dst, b, h) do { _Pragma("unroll") for (int m = 0; m < 4; ++m) _Pragma("unroll") for (int k = 0; k < 2; ++k) dst[m][k] = *(const PG8_LAS bf16x8*)(lds + PG8_SA(b, h) + aoff + m * 2048 + k * 1024); } while (0)
; #define PG8_LDB(dst, b, h) do { _Pragma("unroll") for (int n = 0; n < 2; ++n) _Pragma("unroll") for (int k = 0; k < 2; ++k) dst[n][k] = *(const PG8_LAS bf16x8*)(lds + PG8_SB(b, h) + boff + n * 2048 + k * 1024); } while (0)
; #define PG8_MMA(ai, bj, At, Bt) do { __builtin_amdgcn_s_setprio(1); _Pragma("unroll") for (int m = 0; m < 4; ++m) _Pragma("unroll") for (int n = 0; n < 2; ++n) _Pragma("unroll") for (int k = 0; k < 2; ++k) \
;         acc[ai][bj][m][n] = __builtin_amdgcn_mfma_f32_16x16x32_bf16(Bt[n][k], At[m][k], acc[ai][bj][m][n], 0, 0, 0); __builtin_amdgcn_s_setprio(0); } while (0)
; #define PG8_WAIT_V(n) asm volatile("s_waitcnt vmcnt(" #n ")" ::: "memory")
; #define PG8_WAIT_L(n) asm volatile("s_waitcnt lgkmcnt(" #n ")" ::: "memory")
; #define PG8_BAR __builtin_amdgcn_s_barrier()
; #define PG8_SCHED __builtin_amdgcn_sched_barrier(0)
; template <class Epi, class Sched, bool ALIGN_EPI = false, bool SP2 = false>
; __device__ __forceinline__ void gemm_phase(PG8_LAS unsigned char* lds, const Gemm g, const Sched& S, const Epi& E) {
;     ...
;             PG8_LDB(B0, 0, 0); PG8_LDB(B1, 0, 1); PG8_SCHED; PG8_LDA(At, 0, 0); PG8_STAGE(PG8_SA(1, 1), a1 + hstep, voffA);
;             PG8_WAIT_V(8); PG8_WAIT_L(0); PG8_BAR; PG8_MMA(0, 0, At, B0); PG8_MMA(0, 1, At, B1); PG8_BAR; PG8_SCHED;
;             PG8_LDA(At, 0, 1); PG8_STAGE(PG8_SB(0, 0), b2, voffB); PG8_STAGE(PG8_SB(0, 1), b2 + hstep, voffB); PG8_STAGE(PG8_SA(0, 0), a2, voffA);
;             PG8_WAIT_V(8); PG8_WAIT_L(0); PG8_BAR; PG8_MMA(1, 0, At, B0); PG8_MMA(1, 1, At, B1); PG8_BAR; PG8_SCHED;
	s_setprio 1
	s_waitcnt lgkmcnt(0)
	v_mfma_f32_16x16x32_bf16 v[124:127], v[128:131], v[190:193], v[124:127]
	v_mfma_f32_16x16x32_bf16 v[120:123], v[164:167], v[190:193], v[120:123]
	v_mfma_f32_16x16x32_bf16 v[116:119], v[128:131], v[198:201], v[116:119]
	v_mfma_f32_16x16x32_bf16 v[112:115], v[164:167], v[198:201], v[112:115]
	v_mfma_f32_16x16x32_bf16 v[108:111], v[128:131], v[216:219], v[108:111]
	v_mfma_f32_16x16x32_bf16 v[104:107], v[164:167], v[216:219], v[104:107]
	v_mfma_f32_16x16x32_bf16 v[100:103], v[128:131], v[224:227], v[100:103]
	v_mfma_f32_16x16x32_bf16 v[96:99], v[164:167], v[224:227], v[96:99]
	v_mfma_f32_16x16x32_bf16 v[124:127], v[160:163], v[194:197], v[124:127]
	v_mfma_f32_16x16x32_bf16 v[120:123], v[168:171], v[194:197], v[120:123]
	v_mfma_f32_16x16x32_bf16 v[116:119], v[160:163], v[212:215], v[116:119]
	v_mfma_f32_16x16x32_bf16 v[112:115], v[168:171], v[212:215], v[112:115]
	v_mfma_f32_16x16x32_bf16 v[108:111], v[160:163], v[220:223], v[108:111]
	v_mfma_f32_16x16x32_bf16 v[104:107], v[168:171], v[220:223], v[104:107]
	v_mfma_f32_16x16x32_bf16 v[100:103], v[160:163], v[228:231], v[100:103]
	v_mfma_f32_16x16x32_bf16 v[96:99], v[168:171], v[228:231], v[96:99]
	s_setprio 0
	s_setprio 1
	v_mfma_f32_16x16x32_bf16 v[60:63], v[172:175], v[190:193], v[60:63]
	v_mfma_f32_16x16x32_bf16 v[56:59], v[182:185], v[190:193], v[56:59]
	v_mfma_f32_16x16x32_bf16 v[52:55], v[172:175], v[198:201], v[52:55]
	v_mfma_f32_16x16x32_bf16 v[48:51], v[182:185], v[198:201], v[48:51]
	v_mfma_f32_16x16x32_bf16 v[44:47], v[172:175], v[216:219], v[44:47]
	v_mfma_f32_16x16x32_bf16 v[40:43], v[182:185], v[216:219], v[40:43]
	v_mfma_f32_16x16x32_bf16 v[36:39], v[172:175], v[224:227], v[36:39]
	v_mfma_f32_16x16x32_bf16 v[32:35], v[182:185], v[224:227], v[32:35]
	v_mfma_f32_16x16x32_bf16 v[60:63], v[176:179], v[194:197], v[60:63]
	v_mfma_f32_16x16x32_bf16 v[56:59], v[186:189], v[194:197], v[56:59]
	v_mfma_f32_16x16x32_bf16 v[52:55], v[176:179], v[212:215], v[52:55]
	v_mfma_f32_16x16x32_bf16 v[48:51], v[186:189], v[212:215], v[48:51]
	v_mfma_f32_16x16x32_bf16 v[44:47], v[176:179], v[220:223], v[44:47]
	v_mfma_f32_16x16x32_bf16 v[40:43], v[186:189], v[220:223], v[40:43]
	v_mfma_f32_16x16x32_bf16 v[36:39], v[176:179], v[228:231], v[36:39]
	v_mfma_f32_16x16x32_bf16 v[32:35], v[186:189], v[228:231], v[32:35]
	s_setprio 0
	s_barrier
	s_add_i32 s78, s75, s14
	v_lshl_add_u64 v[232:233], s[62:63], 0, v[134:135]
	s_mov_b32 m0, s78
	ds_read_b128 v[190:193], v208 offset:16384
	ds_read_b128 v[194:197], v208 offset:17408
	ds_read_b128 v[198:201], v208 offset:18432
	ds_read_b128 v[212:215], v208 offset:19456
	ds_read_b128 v[216:219], v208 offset:20480
	ds_read_b128 v[220:223], v208 offset:21504
	ds_read_b128 v[224:227], v208 offset:22528
	ds_read_b128 v[228:231], v208 offset:23552
	global_load_lds_dwordx4 v[232:233], off
	s_add_i32 m0, s78, 0x2000
	s_add_u32 s78, s62, 0x40000
	v_lshl_add_u64 v[234:235], s[62:63], 0, v[138:139]
	s_addc_u32 s79, s63, 0
	s_add_i32 s91, s76, s14
	global_load_lds_dwordx4 v[234:235], off
	v_lshl_add_u64 v[236:237], s[78:79], 0, v[134:135]
	s_mov_b32 m0, s91
	global_load_lds_dwordx4 v[236:237], off
	v_lshl_add_u64 v[236:237], s[78:79], 0, v[138:139]
	s_add_i32 m0, s91, 0x2000
	s_nop 0
	global_load_lds_dwordx4 v[236:237], off
	s_waitcnt vmcnt(6)
	s_waitcnt lgkmcnt(0)
	s_barrier
	s_setprio 1
	s_waitcnt lgkmcnt(0)
	v_mfma_f32_16x16x32_bf16 v[92:95], v[128:131], v[190:193], v[92:95]
	v_mfma_f32_16x16x32_bf16 v[88:91], v[164:167], v[190:193], v[88:91]
	v_mfma_f32_16x16x32_bf16 v[84:87], v[128:131], v[198:201], v[84:87]
	v_mfma_f32_16x16x32_bf16 v[80:83], v[164:167], v[198:201], v[80:83]
	v_mfma_f32_16x16x32_bf16 v[76:79], v[128:131], v[216:219], v[76:79]
	v_mfma_f32_16x16x32_bf16 v[72:75], v[164:167], v[216:219], v[72:75]
	v_mfma_f32_16x16x32_bf16 v[68:71], v[128:131], v[224:227], v[68:71]
	v_mfma_f32_16x16x32_bf16 v[64:67], v[164:167], v[224:227], v[64:67]
	v_mfma_f32_16x16x32_bf16 v[92:95], v[160:163], v[194:197], v[92:95]
	v_mfma_f32_16x16x32_bf16 v[88:91], v[168:171], v[194:197], v[88:91]
	v_mfma_f32_16x16x32_bf16 v[84:87], v[160:163], v[212:215], v[84:87]
	v_mfma_f32_16x16x32_bf16 v[80:83], v[168:171], v[212:215], v[80:83]
	v_lshl_add_u64 v[236:237], s[64:65], 0, v[132:133]
	s_mov_b32 m0, s15
	s_nop 0
	global_load_lds_dwordx4 v[236:237], off
	v_mfma_f32_16x16x32_bf16 v[76:79], v[160:163], v[220:223], v[76:79]
	v_mfma_f32_16x16x32_bf16 v[72:75], v[168:171], v[220:223], v[72:75]
	v_mfma_f32_16x16x32_bf16 v[68:71], v[160:163], v[228:231], v[68:71]
	v_mfma_f32_16x16x32_bf16 v[64:67], v[168:171], v[228:231], v[64:67]
	s_setprio 0
	s_setprio 1
	v_mfma_f32_16x16x32_bf16 v[28:31], v[172:175], v[190:193], v[28:31]
	v_mfma_f32_16x16x32_bf16 v[24:27], v[182:185], v[190:193], v[24:27]
	v_mfma_f32_16x16x32_bf16 v[20:23], v[172:175], v[198:201], v[20:23]
	v_mfma_f32_16x16x32_bf16 v[16:19], v[182:185], v[198:201], v[16:19]
	v_mfma_f32_16x16x32_bf16 v[12:15], v[172:175], v[216:219], v[12:15]
	v_mfma_f32_16x16x32_bf16 v[8:11], v[182:185], v[216:219], v[8:11]
	v_mfma_f32_16x16x32_bf16 v[4:7], v[172:175], v[224:227], v[4:7]
	v_mfma_f32_16x16x32_bf16 v[0:3], v[182:185], v[224:227], v[0:3]
	v_mfma_f32_16x16x32_bf16 v[28:31], v[176:179], v[194:197], v[28:31]
	v_mfma_f32_16x16x32_bf16 v[24:27], v[186:189], v[194:197], v[24:27]
	v_mfma_f32_16x16x32_bf16 v[20:23], v[176:179], v[212:215], v[20:23]
	v_mfma_f32_16x16x32_bf16 v[16:19], v[186:189], v[212:215], v[16:19]
	v_lshl_add_u64 v[238:239], s[64:65], 0, v[136:137]
	s_mov_b32 m0, s33
	s_nop 0
	global_load_lds_dwordx4 v[238:239], off
	v_mfma_f32_16x16x32_bf16 v[12:15], v[176:179], v[220:223], v[12:15]
	v_mfma_f32_16x16x32_bf16 v[8:11], v[186:189], v[220:223], v[8:11]
	v_mfma_f32_16x16x32_bf16 v[4:7], v[176:179], v[228:231], v[4:7]
	v_mfma_f32_16x16x32_bf16 v[0:3], v[186:189], v[228:231], v[0:3]
	s_setprio 0
	s_barrier
; #define PG8_STAGE(bufoff, gbase, voff) do { _Pragma("unroll") for (int _i = 0; _i < 2; ++_i) \
;         __builtin_amdgcn_global_load_lds((const unsigned*)((const char*)(gbase) + (voff)[_i]), (PG8_LAS unsigned*)(lds + (bufoff) + ldsw + _i * 8192), 16, 0, 0); } while (0)
; #define PG8_LDA(dst, b, h) do { _Pragma("unroll") for (int m = 0; m < 4; ++m) _Pragma("unroll") for (int k = 0; k < 2; ++k) dst[m][k] = *(const PG8_LAS bf16x8*)(lds + PG8_SA(b, h) + aoff + m * 2048 + k * 1024); } while (0)
; #define PG8_LDB(dst, b, h) do { _Pragma("unroll") for (int n = 0; n < 2; ++n) _Pragma("unroll") for (int k = 0; k < 2; ++k) dst[n][k] = *(const PG8_LAS bf16x8*)(lds + PG8_SB(b, h) + boff + n * 2048 + k * 1024); } while (0)
; #define PG8_MMA(ai, bj, At, Bt) do { __builtin_amdgcn_s_setprio(1); _Pragma("unroll") for (int m = 0; m < 4; ++m) _Pragma("unroll") for (int n = 0; n < 2; ++n) _Pragma("unroll") for (int k = 0; k < 2; ++k) \
;         acc[ai][bj][m][n] = __builtin_amdgcn_mfma_f32_16x16x32_bf16(Bt[n][k], At[m][k], acc[ai][bj][m][n], 0, 0, 0); __builtin_amdgcn_s_setprio(0); } while (0)
; #define PG8_WAIT_V(n) asm volatile("s_waitcnt vmcnt(" #n ")" ::: "memory")
; #define PG8_WAIT_L(n) asm volatile("s_waitcnt lgkmcnt(" #n ")" ::: "memory")
; #define PG8_BAR __builtin_amdgcn_s_barrier()
; #define PG8_SCHED __builtin_amdgcn_sched_barrier(0)
; template <class Epi, class Sched, bool ALIGN_EPI = false, bool SP2 = false>
; __device__ __forceinline__ void gemm_phase(PG8_LAS unsigned char* lds, const Gemm g, const Sched& S, const Epi& E) {
;     ...
;             PG8_LDB(B0, 1, 0); PG8_LDB(B1, 1, 1); PG8_SCHED; PG8_LDA(At, 1, 0); PG8_STAGE(PG8_SA(0, 1), a2 + hstep, voffA);
;             PG8_WAIT_V(8); PG8_WAIT_L(0); PG8_BAR; PG8_MMA(0, 0, At, B0); PG8_MMA(0, 1, At, B1); PG8_BAR; PG8_SCHED;
	s_add_i32 s78, 0, 0x18000
	v_add_u32_e32 v140, s78, v147
	s_add_i32 s79, 0, 0x1c000
	ds_read_b128 v[128:131], v140
	ds_read_b128 v[160:163], v140 offset:1024
	ds_read_b128 v[164:167], v140 offset:2048
	ds_read_b128 v[168:171], v140 offset:3072
	v_add_u32_e32 v140, s79, v147
	ds_read_b128 v[172:175], v140
	ds_read_b128 v[176:179], v140 offset:1024
	ds_read_b128 v[182:185], v140 offset:2048
	ds_read_b128 v[186:189], v140 offset:3072
	s_add_u32 s64, s64, 0x40000
	s_addc_u32 s65, s65, 0
	s_mov_b32 m0, s34
	v_lshl_add_u64 v[240:241], s[64:65], 0, v[132:133]
	ds_read_b128 v[190:193], v208 offset:32768
	ds_read_b128 v[194:197], v208 offset:33792
	ds_read_b128 v[198:201], v208 offset:34816
	ds_read_b128 v[212:215], v208 offset:35840
	ds_read_b128 v[216:219], v208 offset:36864
	ds_read_b128 v[220:223], v208 offset:37888
	ds_read_b128 v[224:227], v208 offset:38912
	ds_read_b128 v[228:231], v208 offset:39936
	global_load_lds_dwordx4 v[240:241], off
	v_lshl_add_u64 v[240:241], s[64:65], 0, v[136:137]
	s_mov_b32 m0, s57
	s_nop 0
	global_load_lds_dwordx4 v[240:241], off
	s_waitcnt vmcnt(8)
	s_waitcnt lgkmcnt(0)
	s_barrier
	s_setprio 1
	s_waitcnt lgkmcnt(0)
	v_mfma_f32_16x16x32_bf16 v[124:127], v[128:131], v[190:193], v[124:127]
	v_mfma_f32_16x16x32_bf16 v[120:123], v[164:167], v[190:193], v[120:123]
	v_mfma_f32_16x16x32_bf16 v[116:119], v[128:131], v[198:201], v[116:119]
	v_mfma_f32_16x16x32_bf16 v[112:115], v[164:167], v[198:201], v[112:115]
	v_mfma_f32_16x16x32_bf16 v[108:111], v[128:131], v[216:219], v[108:111]
	v_mfma_f32_16x16x32_bf16 v[104:107], v[164:167], v[216:219], v[104:107]
	v_mfma_f32_16x16x32_bf16 v[100:103], v[128:131], v[224:227], v[100:103]
	v_mfma_f32_16x16x32_bf16 v[96:99], v[164:167], v[224:227], v[96:99]
	v_mfma_f32_16x16x32_bf16 v[124:127], v[160:163], v[194:197], v[124:127]
	v_mfma_f32_16x16x32_bf16 v[120:123], v[168:171], v[194:197], v[120:123]
	v_mfma_f32_16x16x32_bf16 v[116:119], v[160:163], v[212:215], v[116:119]
	v_mfma_f32_16x16x32_bf16 v[112:115], v[168:171], v[212:215], v[112:115]
	v_mfma_f32_16x16x32_bf16 v[108:111], v[160:163], v[220:223], v[108:111]
	v_mfma_f32_16x16x32_bf16 v[104:107], v[168:171], v[220:223], v[104:107]
	v_mfma_f32_16x16x32_bf16 v[100:103], v[160:163], v[228:231], v[100:103]
	v_mfma_f32_16x16x32_bf16 v[96:99], v[168:171], v[228:231], v[96:99]
	s_setprio 0
	s_setprio 1
	v_mfma_f32_16x16x32_bf16 v[60:63], v[172:175], v[190:193], v[60:63]
	v_mfma_f32_16x16x32_bf16 v[56:59], v[182:185], v[190:193], v[56:59]
	v_mfma_f32_16x16x32_bf16 v[52:55], v[172:175], v[198:201], v[52:55]
	v_mfma_f32_16x16x32_bf16 v[48:51], v[182:185], v[198:201], v[48:51]
	v_mfma_f32_16x16x32_bf16 v[44:47], v[172:175], v[216:219], v[44:47]
	v_mfma_f32_16x16x32_bf16 v[40:43], v[182:185], v[216:219], v[40:43]
	v_mfma_f32_16x16x32_bf16 v[36:39], v[172:175], v[224:227], v[36:39]
	v_mfma_f32_16x16x32_bf16 v[32:35], v[182:185], v[224:227], v[32:35]
	v_mfma_f32_16x16x32_bf16 v[60:63], v[176:179], v[194:197], v[60:63]
	v_mfma_f32_16x16x32_bf16 v[56:59], v[186:189], v[194:197], v[56:59]
	v_mfma_f32_16x16x32_bf16 v[52:55], v[176:179], v[212:215], v[52:55]
	v_mfma_f32_16x16x32_bf16 v[48:51], v[186:189], v[212:215], v[48:51]
	v_mfma_f32_16x16x32_bf16 v[44:47], v[176:179], v[220:223], v[44:47]
	v_mfma_f32_16x16x32_bf16 v[40:43], v[186:189], v[220:223], v[40:43]
	v_mfma_f32_16x16x32_bf16 v[36:39], v[176:179], v[228:231], v[36:39]
	v_mfma_f32_16x16x32_bf16 v[32:35], v[186:189], v[228:231], v[32:35]
	s_setprio 0
	s_barrier
; #define PG8_STAGE(bufoff, gbase, voff) do { _Pragma("unroll") for (int _i = 0; _i < 2; ++_i) \
;         __builtin_amdgcn_global_load_lds((const unsigned*)((const char*)(gbase) + (voff)[_i]), (PG8_LAS unsigned*)(lds + (bufoff) + ldsw + _i * 8192), 16, 0, 0); } while (0)
; #define PG8_LDA(dst, b, h) do { _Pragma("unroll") for (int m = 0; m < 4; ++m) _Pragma("unroll") for (int k = 0; k < 2; ++k) dst[m][k] = *(const PG8_LAS bf16x8*)(lds + PG8_SA(b, h) + aoff + m * 2048 + k * 1024); } while (0)
; #define PG8_MMA(ai, bj, At, Bt) do { __builtin_amdgcn_s_setprio(1); _Pragma("unroll") for (int m = 0; m < 4; ++m) _Pragma("unroll") for (int n = 0; n < 2; ++n) _Pragma("unroll") for (int k = 0; k < 2; ++k) \
;         acc[ai][bj][m][n] = __builtin_amdgcn_mfma_f32_16x16x32_bf16(Bt[n][k], At[m][k], acc[ai][bj][m][n], 0, 0, 0); __builtin_amdgcn_s_setprio(0); } while (0)
; #define PG8_WAIT_V(n) asm volatile("s_waitcnt vmcnt(" #n ")" ::: "memory")
; #define PG8_WAIT_L(n) asm volatile("s_waitcnt lgkmcnt(" #n ")" ::: "memory")
; #define PG8_BAR __builtin_amdgcn_s_barrier()
; #define PG8_SCHED __builtin_amdgcn_sched_barrier(0)
; template <class Epi, class Sched, bool ALIGN_EPI = false, bool SP2 = false>
; __device__ __forceinline__ void gemm_phase(PG8_LAS unsigned char* lds, const Gemm g, const Sched& S, const Epi& E) {
;     ...
;             PG8_LDA(At, 1, 1); PG8_STAGE(PG8_SB(1, 0), b3, voffB); PG8_STAGE(PG8_SB(1, 1), b3 + hstep, voffB); PG8_STAGE(PG8_SA(1, 0), a3, voffA);
;             PG8_WAIT_V(8); PG8_WAIT_L(0); PG8_BAR; PG8_MMA(1, 0, At, B0); PG8_MMA(1, 1, At, B1); PG8_BAR; PG8_SCHED;
;     ...
;         if constexpr (ALIGN_EPI) { if (wr == 0) PG8_BAR; }
	s_add_i32 s64, s78, s14
	v_lshl_add_u64 v[232:233], v[232:233], 0, s[42:43]
	s_mov_b32 m0, s64
	ds_read_b128 v[190:193], v208 offset:49152
	ds_read_b128 v[194:197], v208 offset:50176
	ds_read_b128 v[198:201], v208 offset:51200
	ds_read_b128 v[212:215], v208 offset:52224
	ds_read_b128 v[216:219], v208 offset:53248
	ds_read_b128 v[220:223], v208 offset:54272
	ds_read_b128 v[224:227], v208 offset:55296
	ds_read_b128 v[228:231], v208 offset:56320
	global_load_lds_dwordx4 v[232:233], off
	s_add_i32 m0, s64, 0x2000
	s_add_u32 s62, s62, 0x40080
	v_lshl_add_u64 v[232:233], v[234:235], 0, s[42:43]
	s_addc_u32 s63, s63, 0
	s_add_i32 s64, s79, s14
	global_load_lds_dwordx4 v[232:233], off
	v_lshl_add_u64 v[232:233], s[62:63], 0, v[134:135]
	s_mov_b32 m0, s64
	s_nop 0
	global_load_lds_dwordx4 v[232:233], off
	v_lshl_add_u64 v[232:233], s[62:63], 0, v[138:139]
	s_add_i32 m0, s64, 0x2000
	s_nop 0
	global_load_lds_dwordx4 v[232:233], off
	s_waitcnt vmcnt(6)
	s_waitcnt lgkmcnt(0)
	s_barrier
	s_setprio 1
	s_waitcnt lgkmcnt(0)
	v_mfma_f32_16x16x32_bf16 v[92:95], v[128:131], v[190:193], v[92:95]
	v_mfma_f32_16x16x32_bf16 v[88:91], v[164:167], v[190:193], v[88:91]
	v_mfma_f32_16x16x32_bf16 v[84:87], v[128:131], v[198:201], v[84:87]
	v_mfma_f32_16x16x32_bf16 v[80:83], v[164:167], v[198:201], v[80:83]
	v_mfma_f32_16x16x32_bf16 v[76:79], v[128:131], v[216:219], v[76:79]
	v_mfma_f32_16x16x32_bf16 v[72:75], v[164:167], v[216:219], v[72:75]
	v_mfma_f32_16x16x32_bf16 v[68:71], v[128:131], v[224:227], v[68:71]
	v_mfma_f32_16x16x32_bf16 v[64:67], v[164:167], v[224:227], v[64:67]
	v_mfma_f32_16x16x32_bf16 v[92:95], v[160:163], v[194:197], v[92:95]
	v_mfma_f32_16x16x32_bf16 v[88:91], v[168:171], v[194:197], v[88:91]
	v_mfma_f32_16x16x32_bf16 v[84:87], v[160:163], v[212:215], v[84:87]
	v_mfma_f32_16x16x32_bf16 v[80:83], v[168:171], v[212:215], v[80:83]
	v_lshl_add_u64 v[232:233], v[236:237], 0, s[42:43]
	s_mov_b32 m0, s67
	s_nop 0
	global_load_lds_dwordx4 v[232:233], off
	v_mfma_f32_16x16x32_bf16 v[76:79], v[160:163], v[220:223], v[76:79]
	v_mfma_f32_16x16x32_bf16 v[72:75], v[168:171], v[220:223], v[72:75]
	v_mfma_f32_16x16x32_bf16 v[68:71], v[160:163], v[228:231], v[68:71]
	v_mfma_f32_16x16x32_bf16 v[64:67], v[168:171], v[228:231], v[64:67]
	s_setprio 0
	s_setprio 1
	v_mfma_f32_16x16x32_bf16 v[28:31], v[172:175], v[190:193], v[28:31]
	v_mfma_f32_16x16x32_bf16 v[24:27], v[182:185], v[190:193], v[24:27]
	v_mfma_f32_16x16x32_bf16 v[20:23], v[172:175], v[198:201], v[20:23]
	v_mfma_f32_16x16x32_bf16 v[16:19], v[182:185], v[198:201], v[16:19]
	v_mfma_f32_16x16x32_bf16 v[12:15], v[172:175], v[216:219], v[12:15]
	v_mfma_f32_16x16x32_bf16 v[8:11], v[182:185], v[216:219], v[8:11]
	v_mfma_f32_16x16x32_bf16 v[4:7], v[172:175], v[224:227], v[4:7]
	v_mfma_f32_16x16x32_bf16 v[0:3], v[182:185], v[224:227], v[0:3]
	v_mfma_f32_16x16x32_bf16 v[28:31], v[176:179], v[194:197], v[28:31]
	v_mfma_f32_16x16x32_bf16 v[24:27], v[186:189], v[194:197], v[24:27]
	v_mfma_f32_16x16x32_bf16 v[20:23], v[176:179], v[212:215], v[20:23]
	v_mfma_f32_16x16x32_bf16 v[16:19], v[186:189], v[212:215], v[16:19]
	v_lshl_add_u64 v[232:233], v[238:239], 0, s[42:43]
	s_mov_b32 m0, s74
	s_nop 0
	global_load_lds_dwordx4 v[232:233], off
	v_mfma_f32_16x16x32_bf16 v[12:15], v[176:179], v[220:223], v[12:15]
	v_mfma_f32_16x16x32_bf16 v[8:11], v[186:189], v[220:223], v[8:11]
	v_mfma_f32_16x16x32_bf16 v[4:7], v[176:179], v[228:231], v[4:7]
	v_mfma_f32_16x16x32_bf16 v[0:3], v[186:189], v[228:231], v[0:3]
	s_setprio 0
	s_barrier
	s_add_i32 s90, s90, 2
	s_add_u32 s58, s58, 0x100
	s_addc_u32 s59, s59, 0
	s_add_u32 s88, s88, 0x100
	s_addc_u32 s89, s89, 0
	s_cmp_gt_u32 s90, 13
	s_cbranch_scc0 .LBB0_1287
	s_and_b64 vcc, exec, s[44:45]
	s_cbranch_vccz .LBB0_1290
	s_barrier

; #define PG8_STAGE(bufoff, gbase, voff) do { _Pragma("unroll") for (int _i = 0; _i < 2; ++_i) \
;         __builtin_amdgcn_global_load_lds((const unsigned*)((const char*)(gbase) + (voff)[_i]), (PG8_LAS unsigned*)(lds + (bufoff) + ldsw + _i * 8192), 16, 0, 0); } while (0)
; #define PG8_LDA(dst, b, h) do { _Pragma("unroll") for (int m = 0; m < 4; ++m) _Pragma("unroll") for (int k = 0; k < 2; ++k) dst[m][k] = *(const PG8_LAS bf16x8*)(lds + PG8_SA(b, h) + aoff + m * 2048 + k * 1024); } while (0)
; #define PG8_LDB(dst, b, h) do { _Pragma("unroll") for (int n = 0; n < 2; ++n) _Pragma("unroll") for (int k = 0; k < 2; ++k) dst[n][k] = *(const PG8_LAS bf16x8*)(lds + PG8_SB(b, h) + boff + n * 2048 + k * 1024); } while (0)
; #define PG8_MMA(ai, bj, At, Bt) do { __builtin_amdgcn_s_setprio(1); _Pragma("unroll") for (int m = 0; m < 4; ++m) _Pragma("unroll") for (int n = 0; n < 2; ++n) _Pragma("unroll") for (int k = 0; k < 2; ++k) \
;         acc[ai][bj][m][n] = __builtin_amdgcn_mfma_f32_16x16x32_bf16(Bt[n][k], At[m][k], acc[ai][bj][m][n], 0, 0, 0); __builtin_amdgcn_s_setprio(0); } while (0)
; #define PG8_BAR __builtin_amdgcn_s_barrier()
; template <class Epi, class Sched, bool ALIGN_EPI = false, bool SP2 = false>
; __device__ __forceinline__ void gemm_phase(PG8_LAS unsigned char* lds, const Gemm g, const Sched& S, const Epi& E) {
;     ...
;         const bool has_next = S.next(ui + 1, nxt);
;         const char* nA = has_next ? (const char*)g.A + (size_t)nxt.pm * tstep : cA; const char* nB = has_next ? (const char*)g.Bt + (size_t)nxt.pn * tstep : cB;
;         for (int t = 0; t < nt; t += 2) {
;             const bool last = (t == nt - 2);
;             const char* a1 = cA + (size_t)(t + 1) * kstep;
;             const char* a2 = last ? nA : cA + (size_t)(t + 2) * kstep; const char* b2 = last ? nB : cB + (size_t)(t + 2) * kstep;
;             const char* a3 = a2 + kstep; const char* b3 = b2 + kstep;
;             if (last && has_next) S.a_ready(nxt);
;             if constexpr (SP2) {
;             PG8_LDB(B0, 0, 0); PG8_LDB(B1, 0, 1); PG8_SCHED; PG8_LDA(At, 0, 0); PG8_STAGE(PG8_SA(1, 1), a1 + hstep, voffA);
;             PG8_WAIT_V(8); PG8_WAIT_L(0); PG8_BAR; PG8_MMA(0, 0, At, B0); PG8_MMA(0, 1, At, B1); PG8_BAR; PG8_SCHED;
;             PG8_LDA(At, 0, 1); PG8_STAGE(PG8_SB(0, 0), b2, voffB); PG8_STAGE(PG8_SB(0, 1), b2 + hstep, voffB); PG8_STAGE(PG8_SA(0, 0), a2, voffA);
.LBB0_1592:
	s_ashr_i32 s39, s38, 31
	s_lshl_b64 s[42:43], s[38:39], 19
	s_add_u32 s42, s40, s42
	s_addc_u32 s43, s41, s43
	s_and_b64 s[44:45], s[10:11], exec
	s_cselect_b32 s39, s43, s51
	s_cselect_b32 s47, s42, s50
	s_ashr_i32 s37, s36, 31
	s_lshl_b64 s[44:45], s[36:37], 19
	v_readlane_b32 s54, v250, 11
	v_readlane_b32 s55, v250, 12
	s_add_u32 s44, s54, s44
	s_addc_u32 s45, s55, s45
	s_and_b64 s[54:55], s[10:11], exec
	s_cselect_b32 s37, s45, s53
	s_cselect_b32 s64, s44, s52
	s_add_u32 s50, s50, 0x40080
	s_addc_u32 s51, s51, 0
	s_add_u32 s65, s52, 0x100
	s_addc_u32 s66, s53, 0
	s_mov_b32 s67, -2
	s_waitcnt lgkmcnt(0)
	ds_read_b128 v[146:149], v152
	ds_read_b128 v[156:159], v152 offset:1024
	ds_read_b128 v[160:163], v152 offset:2048
	ds_read_b128 v[164:167], v152 offset:3072
	ds_read_b128 v[168:171], v153
	ds_read_b128 v[172:175], v153 offset:1024
	ds_read_b128 v[180:183], v153 offset:2048
	ds_read_b128 v[184:187], v153 offset:3072
	s_add_u32 s52, s50, 0xfffc0080
	s_addc_u32 s53, s51, -1
	s_cmp_eq_u32 s67, 12
	s_cselect_b32 s55, s39, s53
	s_cselect_b32 s54, s47, s52
	s_cselect_b32 s53, s37, s66
	s_cselect_b32 s52, s64, s65
	v_lshl_add_u64 v[200:201], s[50:51], 0, v[136:137]
	s_add_i32 m0, s33, 0xc000
	ds_read_b128 v[188:191], v154
	ds_read_b128 v[192:195], v154 offset:1024
	ds_read_b128 v[196:199], v154 offset:2048
	ds_read_b128 v[206:209], v154 offset:3072
	ds_read_b128 v[210:213], v154 offset:4096
	ds_read_b128 v[214:217], v154 offset:5120
	ds_read_b128 v[218:221], v154 offset:6144
	ds_read_b128 v[222:225], v154 offset:7168
	global_load_lds_dwordx4 v[200:201], off
	v_lshl_add_u64 v[200:201], s[50:51], 0, v[138:139]
	s_add_i32 m0, s33, 0xe000
	s_nop 0
	global_load_lds_dwordx4 v[200:201], off
	s_waitcnt vmcnt(8)
	s_waitcnt lgkmcnt(0)
	s_barrier
	s_setprio 1
	s_waitcnt lgkmcnt(0)
	v_mfma_f32_16x16x32_bf16 v[124:127], v[146:149], v[188:191], 0
	v_mfma_f32_16x16x32_bf16 v[120:123], v[160:163], v[188:191], 0
	v_mfma_f32_16x16x32_bf16 v[108:111], v[146:149], v[196:199], 0
	v_mfma_f32_16x16x32_bf16 v[104:107], v[160:163], v[196:199], 0
	v_mfma_f32_16x16x32_bf16 v[92:95], v[146:149], v[210:213], 0
	v_mfma_f32_16x16x32_bf16 v[88:91], v[160:163], v[210:213], 0
	v_mfma_f32_16x16x32_bf16 v[76:79], v[146:149], v[218:221], 0
	v_mfma_f32_16x16x32_bf16 v[72:75], v[160:163], v[218:221], 0
	v_mfma_f32_16x16x32_bf16 v[124:127], v[156:159], v[192:195], v[124:127]
	v_mfma_f32_16x16x32_bf16 v[120:123], v[164:167], v[192:195], v[120:123]
	v_mfma_f32_16x16x32_bf16 v[108:111], v[156:159], v[206:209], v[108:111]
	v_mfma_f32_16x16x32_bf16 v[104:107], v[164:167], v[206:209], v[104:107]
	v_mfma_f32_16x16x32_bf16 v[92:95], v[156:159], v[214:217], v[92:95]
	v_mfma_f32_16x16x32_bf16 v[88:91], v[164:167], v[214:217], v[88:91]
	v_mfma_f32_16x16x32_bf16 v[76:79], v[156:159], v[222:225], v[76:79]
	v_mfma_f32_16x16x32_bf16 v[72:75], v[164:167], v[222:225], v[72:75]
	s_setprio 0
	s_setprio 1
	v_mfma_f32_16x16x32_bf16 v[116:119], v[168:171], v[188:191], 0
	v_mfma_f32_16x16x32_bf16 v[112:115], v[180:183], v[188:191], 0
	v_mfma_f32_16x16x32_bf16 v[100:103], v[168:171], v[196:199], 0
	v_mfma_f32_16x16x32_bf16 v[96:99], v[180:183], v[196:199], 0
	v_mfma_f32_16x16x32_bf16 v[84:87], v[168:171], v[210:213], 0
	v_mfma_f32_16x16x32_bf16 v[80:83], v[180:183], v[210:213], 0
	v_mfma_f32_16x16x32_bf16 v[68:71], v[168:171], v[218:221], 0
	v_mfma_f32_16x16x32_bf16 v[64:67], v[180:183], v[218:221], 0
	v_mfma_f32_16x16x32_bf16 v[116:119], v[172:175], v[192:195], v[116:119]
	v_mfma_f32_16x16x32_bf16 v[112:115], v[184:187], v[192:195], v[112:115]
	v_mfma_f32_16x16x32_bf16 v[100:103], v[172:175], v[206:209], v[100:103]
	v_mfma_f32_16x16x32_bf16 v[96:99], v[184:187], v[206:209], v[96:99]
	v_mfma_f32_16x16x32_bf16 v[84:87], v[172:175], v[214:217], v[84:87]
	v_mfma_f32_16x16x32_bf16 v[80:83], v[184:187], v[214:217], v[80:83]
	v_mfma_f32_16x16x32_bf16 v[68:71], v[172:175], v[222:225], v[68:71]
	v_mfma_f32_16x16x32_bf16 v[64:67], v[184:187], v[222:225], v[64:67]
	s_setprio 0
	s_barrier
	s_add_i32 s74, s60, s15
	v_lshl_add_u64 v[200:201], s[52:53], 0, v[130:131]
	s_mov_b32 m0, s74
	ds_read_b128 v[188:191], v154 offset:16384
	ds_read_b128 v[192:195], v154 offset:17408
	ds_read_b128 v[196:199], v154 offset:18432
	ds_read_b128 v[206:209], v154 offset:19456
	ds_read_b128 v[210:213], v154 offset:20480
	ds_read_b128 v[214:217], v154 offset:21504
	ds_read_b128 v[218:221], v154 offset:22528
	ds_read_b128 v[222:225], v154 offset:23552
	global_load_lds_dwordx4 v[200:201], off
	s_add_i32 m0, s74, 0x2000
	s_add_u32 s74, s52, 0x40000
	v_lshl_add_u64 v[226:227], s[52:53], 0, v[134:135]
	s_addc_u32 s75, s53, 0
	s_add_i32 s76, s61, s15
	global_load_lds_dwordx4 v[226:227], off
	v_lshl_add_u64 v[228:229], s[74:75], 0, v[130:131]
	s_mov_b32 m0, s76
	global_load_lds_dwordx4 v[228:229], off
	v_lshl_add_u64 v[228:229], s[74:75], 0, v[134:135]
	s_add_i32 m0, s76, 0x2000
	s_nop 0
	global_load_lds_dwordx4 v[228:229], off
	s_waitcnt vmcnt(6)
	s_waitcnt lgkmcnt(0)
	s_barrier
; #define PG8_STAGE(bufoff, gbase, voff) do { _Pragma("unroll") for (int _i = 0; _i < 2; ++_i) \
;         __builtin_amdgcn_global_load_lds((const unsigned*)((const char*)(gbase) + (voff)[_i]), (PG8_LAS unsigned*)(lds + (bufoff) + ldsw + _i * 8192), 16, 0, 0); } while (0)
; #define PG8_LDA(dst, b, h) do { _Pragma("unroll") for (int m = 0; m < 4; ++m) _Pragma("unroll") for (int k = 0; k < 2; ++k) dst[m][k] = *(const PG8_LAS bf16x8*)(lds + PG8_SA(b, h) + aoff + m * 2048 + k * 1024); } while (0)
; #define PG8_LDB(dst, b, h) do { _Pragma("unroll") for (int n = 0; n < 2; ++n) _Pragma("unroll") for (int k = 0; k < 2; ++k) dst[n][k] = *(const PG8_LAS bf16x8*)(lds + PG8_SB(b, h) + boff + n * 2048 + k * 1024); } while (0)
; #define PG8_MMA(ai, bj, At, Bt) do { __builtin_amdgcn_s_setprio(1); _Pragma("unroll") for (int m = 0; m < 4; ++m) _Pragma("unroll") for (int n = 0; n < 2; ++n) _Pragma("unroll") for (int k = 0; k < 2; ++k) \
;         acc[ai][bj][m][n] = __builtin_amdgcn_mfma_f32_16x16x32_bf16(Bt[n][k], At[m][k], acc[ai][bj][m][n], 0, 0, 0); __builtin_amdgcn_s_setprio(0); } while (0)
; #define PG8_WAIT_V(n) asm volatile("s_waitcnt vmcnt(" #n ")" ::: "memory")
; #define PG8_WAIT_L(n) asm volatile("s_waitcnt lgkmcnt(" #n ")" ::: "memory")
; #define PG8_BAR __builtin_amdgcn_s_barrier()
; #define PG8_SCHED __builtin_amdgcn_sched_barrier(0)
; template <class Epi, class Sched, bool ALIGN_EPI = false, bool SP2 = false>
; __device__ __forceinline__ void gemm_phase(PG8_LAS unsigned char* lds, const Gemm g, const Sched& S, const Epi& E) {
;     ...
;             PG8_LDA(At, 0, 1); PG8_STAGE(PG8_SB(0, 0), b2, voffB); PG8_STAGE(PG8_SB(0, 1), b2 + hstep, voffB); PG8_STAGE(PG8_SA(0, 0), a2, voffA);
;             PG8_WAIT_V(8); PG8_WAIT_L(0); PG8_BAR; PG8_MMA(1, 0, At, B0); PG8_MMA(1, 1, At, B1); PG8_BAR; PG8_SCHED;
;             PG8_LDB(B0, 1, 0); PG8_LDB(B1, 1, 1); PG8_SCHED; PG8_LDA(At, 1, 0); PG8_STAGE(PG8_SA(0, 1), a2 + hstep, voffA);
;             PG8_WAIT_V(8); PG8_WAIT_L(0); PG8_BAR; PG8_MMA(0, 0, At, B0); PG8_MMA(0, 1, At, B1); PG8_BAR; PG8_SCHED;
	s_setprio 1
	s_waitcnt lgkmcnt(0)
	v_mfma_f32_16x16x32_bf16 v[60:63], v[146:149], v[188:191], 0
	v_mfma_f32_16x16x32_bf16 v[56:59], v[160:163], v[188:191], 0
	v_mfma_f32_16x16x32_bf16 v[44:47], v[146:149], v[196:199], 0
	v_mfma_f32_16x16x32_bf16 v[40:43], v[160:163], v[196:199], 0
	v_mfma_f32_16x16x32_bf16 v[28:31], v[146:149], v[210:213], 0
	v_mfma_f32_16x16x32_bf16 v[24:27], v[160:163], v[210:213], 0
	v_mfma_f32_16x16x32_bf16 v[12:15], v[146:149], v[218:221], 0
	v_mfma_f32_16x16x32_bf16 v[8:11], v[160:163], v[218:221], 0
	v_mfma_f32_16x16x32_bf16 v[60:63], v[156:159], v[192:195], v[60:63]
	v_mfma_f32_16x16x32_bf16 v[56:59], v[164:167], v[192:195], v[56:59]
	v_mfma_f32_16x16x32_bf16 v[44:47], v[156:159], v[206:209], v[44:47]
	v_mfma_f32_16x16x32_bf16 v[40:43], v[164:167], v[206:209], v[40:43]
	v_lshl_add_u64 v[228:229], s[54:55], 0, v[128:129]
	s_mov_b32 m0, s33
	s_nop 0
	global_load_lds_dwordx4 v[228:229], off
	v_mfma_f32_16x16x32_bf16 v[28:31], v[156:159], v[214:217], v[28:31]
	v_mfma_f32_16x16x32_bf16 v[24:27], v[164:167], v[214:217], v[24:27]
	v_mfma_f32_16x16x32_bf16 v[12:15], v[156:159], v[222:225], v[12:15]
	v_mfma_f32_16x16x32_bf16 v[8:11], v[164:167], v[222:225], v[8:11]
	s_setprio 0
	s_setprio 1
	v_mfma_f32_16x16x32_bf16 v[52:55], v[168:171], v[188:191], 0
	v_mfma_f32_16x16x32_bf16 v[48:51], v[180:183], v[188:191], 0
	v_mfma_f32_16x16x32_bf16 v[36:39], v[168:171], v[196:199], 0
	v_mfma_f32_16x16x32_bf16 v[32:35], v[180:183], v[196:199], 0
	v_mfma_f32_16x16x32_bf16 v[20:23], v[168:171], v[210:213], 0
	v_mfma_f32_16x16x32_bf16 v[16:19], v[180:183], v[210:213], 0
	v_mfma_f32_16x16x32_bf16 v[4:7], v[168:171], v[218:221], 0
	v_mfma_f32_16x16x32_bf16 v[0:3], v[180:183], v[218:221], 0
	v_mfma_f32_16x16x32_bf16 v[52:55], v[172:175], v[192:195], v[52:55]
	v_mfma_f32_16x16x32_bf16 v[48:51], v[184:187], v[192:195], v[48:51]
	v_mfma_f32_16x16x32_bf16 v[36:39], v[172:175], v[206:209], v[36:39]
	v_mfma_f32_16x16x32_bf16 v[32:35], v[184:187], v[206:209], v[32:35]
	v_lshl_add_u64 v[230:231], s[54:55], 0, v[132:133]
	s_mov_b32 m0, s34
	s_nop 0
	global_load_lds_dwordx4 v[230:231], off
	v_mfma_f32_16x16x32_bf16 v[20:23], v[172:175], v[214:217], v[20:23]
	v_mfma_f32_16x16x32_bf16 v[16:19], v[184:187], v[214:217], v[16:19]
	v_mfma_f32_16x16x32_bf16 v[4:7], v[172:175], v[222:225], v[4:7]
	v_mfma_f32_16x16x32_bf16 v[0:3], v[184:187], v[222:225], v[0:3]
	s_setprio 0
	s_barrier
	s_add_i32 s74, 0, 0x18000
	s_add_i32 s75, 0, 0x1c000
	v_add_u32_e32 v164, s74, v150
	v_add_u32_e32 v179, s75, v150
	ds_read_b128 v[146:149], v164
	ds_read_b128 v[156:159], v164 offset:1024
	ds_read_b128 v[160:163], v164 offset:2048
	ds_read_b128 v[164:167], v164 offset:3072
	ds_read_b128 v[168:171], v179
	ds_read_b128 v[172:175], v179 offset:1024
	ds_read_b128 v[180:183], v179 offset:2048
	ds_read_b128 v[184:187], v179 offset:3072
	s_add_u32 s54, s54, 0x40000
	s_addc_u32 s55, s55, 0
	s_mov_b32 m0, s49
	v_lshl_add_u64 v[232:233], s[54:55], 0, v[128:129]
	ds_read_b128 v[188:191], v154 offset:32768
	ds_read_b128 v[192:195], v154 offset:33792
	ds_read_b128 v[196:199], v154 offset:34816
	ds_read_b128 v[206:209], v154 offset:35840
	ds_read_b128 v[210:213], v154 offset:36864
	ds_read_b128 v[214:217], v154 offset:37888
	ds_read_b128 v[218:221], v154 offset:38912
	ds_read_b128 v[222:225], v154 offset:39936
	global_load_lds_dwordx4 v[232:233], off
	v_lshl_add_u64 v[232:233], s[54:55], 0, v[132:133]
	s_mov_b32 m0, s56
	s_nop 0
	global_load_lds_dwordx4 v[232:233], off
	s_waitcnt vmcnt(8)
	s_waitcnt lgkmcnt(0)
	s_barrier
	s_setprio 1
	s_waitcnt lgkmcnt(0)
	v_mfma_f32_16x16x32_bf16 v[124:127], v[146:149], v[188:191], v[124:127]
	v_mfma_f32_16x16x32_bf16 v[120:123], v[160:163], v[188:191], v[120:123]
	v_mfma_f32_16x16x32_bf16 v[108:111], v[146:149], v[196:199], v[108:111]
	v_mfma_f32_16x16x32_bf16 v[104:107], v[160:163], v[196:199], v[104:107]
	v_mfma_f32_16x16x32_bf16 v[92:95], v[146:149], v[210:213], v[92:95]
	v_mfma_f32_16x16x32_bf16 v[88:91], v[160:163], v[210:213], v[88:91]
	v_mfma_f32_16x16x32_bf16 v[76:79], v[146:149], v[218:221], v[76:79]
	v_mfma_f32_16x16x32_bf16 v[72:75], v[160:163], v[218:221], v[72:75]
	v_mfma_f32_16x16x32_bf16 v[124:127], v[156:159], v[192:195], v[124:127]
	v_mfma_f32_16x16x32_bf16 v[120:123], v[164:167], v[192:195], v[120:123]
	v_mfma_f32_16x16x32_bf16 v[108:111], v[156:159], v[206:209], v[108:111]
	v_mfma_f32_16x16x32_bf16 v[104:107], v[164:167], v[206:209], v[104:107]
	v_mfma_f32_16x16x32_bf16 v[92:95], v[156:159], v[214:217], v[92:95]
	v_mfma_f32_16x16x32_bf16 v[88:91], v[164:167], v[214:217], v[88:91]
	v_mfma_f32_16x16x32_bf16 v[76:79], v[156:159], v[222:225], v[76:79]
	v_mfma_f32_16x16x32_bf16 v[72:75], v[164:167], v[222:225], v[72:75]
	s_setprio 0
	s_setprio 1
	v_mfma_f32_16x16x32_bf16 v[116:119], v[168:171], v[188:191], v[116:119]
	v_mfma_f32_16x16x32_bf16 v[112:115], v[180:183], v[188:191], v[112:115]
	v_mfma_f32_16x16x32_bf16 v[100:103], v[168:171], v[196:199], v[100:103]
	v_mfma_f32_16x16x32_bf16 v[96:99], v[180:183], v[196:199], v[96:99]
	v_mfma_f32_16x16x32_bf16 v[84:87], v[168:171], v[210:213], v[84:87]
	v_mfma_f32_16x16x32_bf16 v[80:83], v[180:183], v[210:213], v[80:83]
	v_mfma_f32_16x16x32_bf16 v[68:71], v[168:171], v[218:221], v[68:71]
	v_mfma_f32_16x16x32_bf16 v[64:67], v[180:183], v[218:221], v[64:67]
	v_mfma_f32_16x16x32_bf16 v[116:119], v[172:175], v[192:195], v[116:119]
	v_mfma_f32_16x16x32_bf16 v[112:115], v[184:187], v[192:195], v[112:115]
	v_mfma_f32_16x16x32_bf16 v[100:103], v[172:175], v[206:209], v[100:103]
	v_mfma_f32_16x16x32_bf16 v[96:99], v[184:187], v[206:209], v[96:99]
	v_mfma_f32_16x16x32_bf16 v[84:87], v[172:175], v[214:217], v[84:87]
	v_mfma_f32_16x16x32_bf16 v[80:83], v[184:187], v[214:217], v[80:83]
	v_mfma_f32_16x16x32_bf16 v[68:71], v[172:175], v[222:225], v[68:71]
	v_mfma_f32_16x16x32_bf16 v[64:67], v[184:187], v[222:225], v[64:67]
	s_setprio 0
	s_barrier
; #define PG8_STAGE(bufoff, gbase, voff) do { _Pragma("unroll") for (int _i = 0; _i < 2; ++_i) \
;         __builtin_amdgcn_global_load_lds((const unsigned*)((const char*)(gbase) + (voff)[_i]), (PG8_LAS unsigned*)(lds + (bufoff) + ldsw + _i * 8192), 16, 0, 0); } while (0)
; #define PG8_LDA(dst, b, h) do { _Pragma("unroll") for (int m = 0; m < 4; ++m) _Pragma("unroll") for (int k = 0; k < 2; ++k) dst[m][k] = *(const PG8_LAS bf16x8*)(lds + PG8_SA(b, h) + aoff + m * 2048 + k * 1024); } while (0)
; #define PG8_LDB(dst, b, h) do { _Pragma("unroll") for (int n = 0; n < 2; ++n) _Pragma("unroll") for (int k = 0; k < 2; ++k) dst[n][k] = *(const PG8_LAS bf16x8*)(lds + PG8_SB(b, h) + boff + n * 2048 + k * 1024); } while (0)
; #define PG8_MMA(ai, bj, At, Bt) do { __builtin_amdgcn_s_setprio(1); _Pragma("unroll") for (int m = 0; m < 4; ++m) _Pragma("unroll") for (int n = 0; n < 2; ++n) _Pragma("unroll") for (int k = 0; k < 2; ++k) \
;         acc[ai][bj][m][n] = __builtin_amdgcn_mfma_f32_16x16x32_bf16(Bt[n][k], At[m][k], acc[ai][bj][m][n], 0, 0, 0); __builtin_amdgcn_s_setprio(0); } while (0)
; template <class Epi, class Sched, bool ALIGN_EPI = false, bool SP2 = false>
; __device__ __forceinline__ void gemm_phase(PG8_LAS unsigned char* lds, const Gemm g, const Sched& S, const Epi& E) {
;     ...
;         for (int t = 0; t < nt; t += 2) {
;             const bool last = (t == nt - 2);
;             const char* a1 = cA + (size_t)(t + 1) * kstep;
;             const char* a2 = last ? nA : cA + (size_t)(t + 2) * kstep; const char* b2 = last ? nB : cB + (size_t)(t + 2) * kstep;
;             const char* a3 = a2 + kstep; const char* b3 = b2 + kstep;
;             if (last && has_next) S.a_ready(nxt);
;             if constexpr (SP2) {
;             PG8_LDB(B0, 0, 0); PG8_LDB(B1, 0, 1); PG8_SCHED; PG8_LDA(At, 0, 0); PG8_STAGE(PG8_SA(1, 1), a1 + hstep, voffA);
;             PG8_WAIT_V(8); PG8_WAIT_L(0); PG8_BAR; PG8_MMA(0, 0, At, B0); PG8_MMA(0, 1, At, B1); PG8_BAR; PG8_SCHED;
;             PG8_LDA(At, 0, 1); PG8_STAGE(PG8_SB(0, 0), b2, voffB); PG8_STAGE(PG8_SB(0, 1), b2 + hstep, voffB); PG8_STAGE(PG8_SA(0, 0), a2, voffA);
;     ...
;             PG8_LDA(At, 1, 1); PG8_STAGE(PG8_SB(1, 0), b3, voffB); PG8_STAGE(PG8_SB(1, 1), b3 + hstep, voffB); PG8_STAGE(PG8_SA(1, 0), a3, voffA);
;             PG8_WAIT_V(8); PG8_WAIT_L(0); PG8_BAR; PG8_MMA(1, 0, At, B0); PG8_MMA(1, 1, At, B1); PG8_BAR; PG8_SCHED;
	s_add_i32 s54, s74, s15
	v_lshl_add_u64 v[200:201], v[200:201], 0, s[26:27]
	s_mov_b32 m0, s54
	ds_read_b128 v[188:191], v154 offset:49152
	ds_read_b128 v[192:195], v154 offset:50176
	ds_read_b128 v[196:199], v154 offset:51200
	ds_read_b128 v[206:209], v154 offset:52224
	ds_read_b128 v[210:213], v154 offset:53248
	ds_read_b128 v[214:217], v154 offset:54272
	ds_read_b128 v[218:221], v154 offset:55296
	ds_read_b128 v[222:225], v154 offset:56320
	global_load_lds_dwordx4 v[200:201], off
	s_add_i32 m0, s54, 0x2000
	s_add_u32 s52, s52, 0x40080
	v_lshl_add_u64 v[200:201], v[226:227], 0, s[26:27]
	s_addc_u32 s53, s53, 0
	s_add_i32 s54, s75, s15
	global_load_lds_dwordx4 v[200:201], off
	v_lshl_add_u64 v[200:201], s[52:53], 0, v[130:131]
	s_mov_b32 m0, s54
	s_nop 0
	global_load_lds_dwordx4 v[200:201], off
	v_lshl_add_u64 v[200:201], s[52:53], 0, v[134:135]
	s_add_i32 m0, s54, 0x2000
	s_nop 0
	global_load_lds_dwordx4 v[200:201], off
	s_waitcnt vmcnt(6)
	s_waitcnt lgkmcnt(0)
	s_barrier
	s_setprio 1
	s_waitcnt lgkmcnt(0)
	v_mfma_f32_16x16x32_bf16 v[60:63], v[146:149], v[188:191], v[60:63]
	v_mfma_f32_16x16x32_bf16 v[56:59], v[160:163], v[188:191], v[56:59]
	v_mfma_f32_16x16x32_bf16 v[44:47], v[146:149], v[196:199], v[44:47]
	v_mfma_f32_16x16x32_bf16 v[40:43], v[160:163], v[196:199], v[40:43]
	v_mfma_f32_16x16x32_bf16 v[28:31], v[146:149], v[210:213], v[28:31]
	v_mfma_f32_16x16x32_bf16 v[24:27], v[160:163], v[210:213], v[24:27]
	v_mfma_f32_16x16x32_bf16 v[12:15], v[146:149], v[218:221], v[12:15]
	v_mfma_f32_16x16x32_bf16 v[8:11], v[160:163], v[218:221], v[8:11]
	v_mfma_f32_16x16x32_bf16 v[60:63], v[156:159], v[192:195], v[60:63]
	v_mfma_f32_16x16x32_bf16 v[56:59], v[164:167], v[192:195], v[56:59]
	v_mfma_f32_16x16x32_bf16 v[44:47], v[156:159], v[206:209], v[44:47]
	v_mfma_f32_16x16x32_bf16 v[40:43], v[164:167], v[206:209], v[40:43]
	v_lshl_add_u64 v[200:201], v[228:229], 0, s[26:27]
	s_mov_b32 m0, s58
	s_nop 0
	global_load_lds_dwordx4 v[200:201], off
	v_mfma_f32_16x16x32_bf16 v[28:31], v[156:159], v[214:217], v[28:31]
	v_mfma_f32_16x16x32_bf16 v[24:27], v[164:167], v[214:217], v[24:27]
	v_mfma_f32_16x16x32_bf16 v[12:15], v[156:159], v[222:225], v[12:15]
	v_mfma_f32_16x16x32_bf16 v[8:11], v[164:167], v[222:225], v[8:11]
	s_setprio 0
	s_setprio 1
	v_mfma_f32_16x16x32_bf16 v[52:55], v[168:171], v[188:191], v[52:55]
	v_mfma_f32_16x16x32_bf16 v[48:51], v[180:183], v[188:191], v[48:51]
	v_mfma_f32_16x16x32_bf16 v[36:39], v[168:171], v[196:199], v[36:39]
	v_mfma_f32_16x16x32_bf16 v[32:35], v[180:183], v[196:199], v[32:35]
	v_mfma_f32_16x16x32_bf16 v[20:23], v[168:171], v[210:213], v[20:23]
	v_mfma_f32_16x16x32_bf16 v[16:19], v[180:183], v[210:213], v[16:19]
	v_mfma_f32_16x16x32_bf16 v[4:7], v[168:171], v[218:221], v[4:7]
	v_mfma_f32_16x16x32_bf16 v[0:3], v[180:183], v[218:221], v[0:3]
	v_mfma_f32_16x16x32_bf16 v[52:55], v[172:175], v[192:195], v[52:55]
	v_mfma_f32_16x16x32_bf16 v[48:51], v[184:187], v[192:195], v[48:51]
	v_mfma_f32_16x16x32_bf16 v[36:39], v[172:175], v[206:209], v[36:39]
	v_mfma_f32_16x16x32_bf16 v[32:35], v[184:187], v[206:209], v[32:35]
	v_lshl_add_u64 v[200:201], v[230:231], 0, s[26:27]
	s_mov_b32 m0, s59
	s_nop 0
	global_load_lds_dwordx4 v[200:201], off
	v_mfma_f32_16x16x32_bf16 v[20:23], v[172:175], v[214:217], v[20:23]
	v_mfma_f32_16x16x32_bf16 v[16:19], v[184:187], v[214:217], v[16:19]
	v_mfma_f32_16x16x32_bf16 v[4:7], v[172:175], v[222:225], v[4:7]
	v_mfma_f32_16x16x32_bf16 v[0:3], v[184:187], v[222:225], v[0:3]
	s_setprio 0
	s_barrier
	s_add_i32 s67, s67, 2
	s_add_u32 s50, s50, 0x100
	s_addc_u32 s51, s51, 0
	s_add_u32 s65, s65, 0x100
	s_addc_u32 s66, s66, 0
.LBB0_1593:
	ds_read_b128 v[146:149], v152
	ds_read_b128 v[156:159], v152 offset:1024
	ds_read_b128 v[160:163], v152 offset:2048
	ds_read_b128 v[164:167], v152 offset:3072
	ds_read_b128 v[168:171], v153
	ds_read_b128 v[172:175], v153 offset:1024
	ds_read_b128 v[180:183], v153 offset:2048
	ds_read_b128 v[184:187], v153 offset:3072
	s_add_u32 s52, s50, 0xfffc0080
	s_addc_u32 s53, s51, -1
	s_cmp_eq_u32 s67, 12
	s_cselect_b32 s55, s39, s53
	s_cselect_b32 s54, s47, s52
	s_cselect_b32 s53, s37, s66
	s_cselect_b32 s52, s64, s65
	v_lshl_add_u64 v[200:201], s[50:51], 0, v[136:137]
	s_add_i32 m0, s33, 0xc000
	ds_read_b128 v[188:191], v154
	ds_read_b128 v[192:195], v154 offset:1024
	ds_read_b128 v[196:199], v154 offset:2048
	ds_read_b128 v[206:209], v154 offset:3072
	ds_read_b128 v[210:213], v154 offset:4096
	ds_read_b128 v[214:217], v154 offset:5120
	ds_read_b128 v[218:221], v154 offset:6144
	ds_read_b128 v[222:225], v154 offset:7168
	global_load_lds_dwordx4 v[200:201], off
	v_lshl_add_u64 v[200:201], s[50:51], 0, v[138:139]
	s_add_i32 m0, s33, 0xe000
	s_nop 0
	global_load_lds_dwordx4 v[200:201], off
	s_waitcnt vmcnt(8)
	s_waitcnt lgkmcnt(0)
	s_barrier
; #define PG8_STAGE(bufoff, gbase, voff) do { _Pragma("unroll") for (int _i = 0; _i < 2; ++_i) \
;         __builtin_amdgcn_global_load_lds((const unsigned*)((const char*)(gbase) + (voff)[_i]), (PG8_LAS unsigned*)(lds + (bufoff) + ldsw + _i * 8192), 16, 0, 0); } while (0)
; #define PG8_LDA(dst, b, h) do { _Pragma("unroll") for (int m = 0; m < 4; ++m) _Pragma("unroll") for (int k = 0; k < 2; ++k) dst[m][k] = *(const PG8_LAS bf16x8*)(lds + PG8_SA(b, h) + aoff + m * 2048 + k * 1024); } while (0)
; #define PG8_LDB(dst, b, h) do { _Pragma("unroll") for (int n = 0; n < 2; ++n) _Pragma("unroll") for (int k = 0; k < 2; ++k) dst[n][k] = *(const PG8_LAS bf16x8*)(lds + PG8_SB(b, h) + boff + n * 2048 + k * 1024); } while (0)
; #define PG8_MMA(ai, bj, At, Bt) do { __builtin_amdgcn_s_setprio(1); _Pragma("unroll") for (int m = 0; m < 4; ++m) _Pragma("unroll") for (int n = 0; n < 2; ++n) _Pragma("unroll") for (int k = 0; k < 2; ++k) \
;         acc[ai][bj][m][n] = __builtin_amdgcn_mfma_f32_16x16x32_bf16(Bt[n][k], At[m][k], acc[ai][bj][m][n], 0, 0, 0); __builtin_amdgcn_s_setprio(0); } while (0)
; #define PG8_WAIT_V(n) asm volatile("s_waitcnt vmcnt(" #n ")" ::: "memory")
; #define PG8_WAIT_L(n) asm volatile("s_waitcnt lgkmcnt(" #n ")" ::: "memory")
; #define PG8_BAR __builtin_amdgcn_s_barrier()
; #define PG8_SCHED __builtin_amdgcn_sched_barrier(0)
; template <class Epi, class Sched, bool ALIGN_EPI = false, bool SP2 = false>
; __device__ __forceinline__ void gemm_phase(PG8_LAS unsigned char* lds, const Gemm g, const Sched& S, const Epi& E) {
;     ...
;             PG8_LDB(B0, 0, 0); PG8_LDB(B1, 0, 1); PG8_SCHED; PG8_LDA(At, 0, 0); PG8_STAGE(PG8_SA(1, 1), a1 + hstep, voffA);
;             PG8_WAIT_V(8); PG8_WAIT_L(0); PG8_BAR; PG8_MMA(0, 0, At, B0); PG8_MMA(0, 1, At, B1); PG8_BAR; PG8_SCHED;
;             PG8_LDA(At, 0, 1); PG8_STAGE(PG8_SB(0, 0), b2, voffB); PG8_STAGE(PG8_SB(0, 1), b2 + hstep, voffB); PG8_STAGE(PG8_SA(0, 0), a2, voffA);
;             PG8_WAIT_V(8); PG8_WAIT_L(0); PG8_BAR; PG8_MMA(1, 0, At, B0); PG8_MMA(1, 1, At, B1); PG8_BAR; PG8_SCHED;
	s_setprio 1
	s_waitcnt lgkmcnt(0)
	v_mfma_f32_16x16x32_bf16 v[124:127], v[146:149], v[188:191], v[124:127]
	v_mfma_f32_16x16x32_bf16 v[120:123], v[160:163], v[188:191], v[120:123]
	v_mfma_f32_16x16x32_bf16 v[108:111], v[146:149], v[196:199], v[108:111]
	v_mfma_f32_16x16x32_bf16 v[104:107], v[160:163], v[196:199], v[104:107]
	v_mfma_f32_16x16x32_bf16 v[92:95], v[146:149], v[210:213], v[92:95]
	v_mfma_f32_16x16x32_bf16 v[88:91], v[160:163], v[210:213], v[88:91]
	v_mfma_f32_16x16x32_bf16 v[76:79], v[146:149], v[218:221], v[76:79]
	v_mfma_f32_16x16x32_bf16 v[72:75], v[160:163], v[218:221], v[72:75]
	v_mfma_f32_16x16x32_bf16 v[124:127], v[156:159], v[192:195], v[124:127]
	v_mfma_f32_16x16x32_bf16 v[120:123], v[164:167], v[192:195], v[120:123]
	v_mfma_f32_16x16x32_bf16 v[108:111], v[156:159], v[206:209], v[108:111]
	v_mfma_f32_16x16x32_bf16 v[104:107], v[164:167], v[206:209], v[104:107]
	v_mfma_f32_16x16x32_bf16 v[92:95], v[156:159], v[214:217], v[92:95]
	v_mfma_f32_16x16x32_bf16 v[88:91], v[164:167], v[214:217], v[88:91]
	v_mfma_f32_16x16x32_bf16 v[76:79], v[156:159], v[222:225], v[76:79]
	v_mfma_f32_16x16x32_bf16 v[72:75], v[164:167], v[222:225], v[72:75]
	s_setprio 0
	s_setprio 1
	v_mfma_f32_16x16x32_bf16 v[116:119], v[168:171], v[188:191], v[116:119]
	v_mfma_f32_16x16x32_bf16 v[112:115], v[180:183], v[188:191], v[112:115]
	v_mfma_f32_16x16x32_bf16 v[100:103], v[168:171], v[196:199], v[100:103]
	v_mfma_f32_16x16x32_bf16 v[96:99], v[180:183], v[196:199], v[96:99]
	v_mfma_f32_16x16x32_bf16 v[84:87], v[168:171], v[210:213], v[84:87]
	v_mfma_f32_16x16x32_bf16 v[80:83], v[180:183], v[210:213], v[80:83]
	v_mfma_f32_16x16x32_bf16 v[68:71], v[168:171], v[218:221], v[68:71]
	v_mfma_f32_16x16x32_bf16 v[64:67], v[180:183], v[218:221], v[64:67]
	v_mfma_f32_16x16x32_bf16 v[116:119], v[172:175], v[192:195], v[116:119]
	v_mfma_f32_16x16x32_bf16 v[112:115], v[184:187], v[192:195], v[112:115]
	v_mfma_f32_16x16x32_bf16 v[100:103], v[172:175], v[206:209], v[100:103]
	v_mfma_f32_16x16x32_bf16 v[96:99], v[184:187], v[206:209], v[96:99]
	v_mfma_f32_16x16x32_bf16 v[84:87], v[172:175], v[214:217], v[84:87]
	v_mfma_f32_16x16x32_bf16 v[80:83], v[184:187], v[214:217], v[80:83]
	v_mfma_f32_16x16x32_bf16 v[68:71], v[172:175], v[222:225], v[68:71]
	v_mfma_f32_16x16x32_bf16 v[64:67], v[184:187], v[222:225], v[64:67]
	s_setprio 0
	s_barrier
	s_add_i32 s74, s60, s15
	v_lshl_add_u64 v[200:201], s[52:53], 0, v[130:131]
	s_mov_b32 m0, s74
	ds_read_b128 v[188:191], v154 offset:16384
	ds_read_b128 v[192:195], v154 offset:17408
	ds_read_b128 v[196:199], v154 offset:18432
	ds_read_b128 v[206:209], v154 offset:19456
	ds_read_b128 v[210:213], v154 offset:20480
	ds_read_b128 v[214:217], v154 offset:21504
	ds_read_b128 v[218:221], v154 offset:22528
	ds_read_b128 v[222:225], v154 offset:23552
	global_load_lds_dwordx4 v[200:201], off
	s_add_i32 m0, s74, 0x2000
	s_add_u32 s74, s52, 0x40000
	v_lshl_add_u64 v[226:227], s[52:53], 0, v[134:135]
	s_addc_u32 s75, s53, 0
	s_add_i32 s76, s61, s15
	global_load_lds_dwordx4 v[226:227], off
	v_lshl_add_u64 v[228:229], s[74:75], 0, v[130:131]
	s_mov_b32 m0, s76
	global_load_lds_dwordx4 v[228:229], off
	v_lshl_add_u64 v[228:229], s[74:75], 0, v[134:135]
	s_add_i32 m0, s76, 0x2000
	s_nop 0
	global_load_lds_dwordx4 v[228:229], off
	s_waitcnt vmcnt(6)
	s_waitcnt lgkmcnt(0)
	s_barrier
	s_setprio 1
	s_waitcnt lgkmcnt(0)
	v_mfma_f32_16x16x32_bf16 v[60:63], v[146:149], v[188:191], v[60:63]
	v_mfma_f32_16x16x32_bf16 v[56:59], v[160:163], v[188:191], v[56:59]
	v_mfma_f32_16x16x32_bf16 v[44:47], v[146:149], v[196:199], v[44:47]
	v_mfma_f32_16x16x32_bf16 v[40:43], v[160:163], v[196:199], v[40:43]
	v_mfma_f32_16x16x32_bf16 v[28:31], v[146:149], v[210:213], v[28:31]
	v_mfma_f32_16x16x32_bf16 v[24:27], v[160:163], v[210:213], v[24:27]
	v_mfma_f32_16x16x32_bf16 v[12:15], v[146:149], v[218:221], v[12:15]
	v_mfma_f32_16x16x32_bf16 v[8:11], v[160:163], v[218:221], v[8:11]
	v_mfma_f32_16x16x32_bf16 v[60:63], v[156:159], v[192:195], v[60:63]
	v_mfma_f32_16x16x32_bf16 v[56:59], v[164:167], v[192:195], v[56:59]
	v_mfma_f32_16x16x32_bf16 v[44:47], v[156:159], v[206:209], v[44:47]
	v_mfma_f32_16x16x32_bf16 v[40:43], v[164:167], v[206:209], v[40:43]
	v_lshl_add_u64 v[228:229], s[54:55], 0, v[128:129]
	s_mov_b32 m0, s33
	s_nop 0
	global_load_lds_dwordx4 v[228:229], off
	v_mfma_f32_16x16x32_bf16 v[28:31], v[156:159], v[214:217], v[28:31]
	v_mfma_f32_16x16x32_bf16 v[24:27], v[164:167], v[214:217], v[24:27]
	v_mfma_f32_16x16x32_bf16 v[12:15], v[156:159], v[222:225], v[12:15]
	v_mfma_f32_16x16x32_bf16 v[8:11], v[164:167], v[222:225], v[8:11]
	s_setprio 0
	s_setprio 1
	v_mfma_f32_16x16x32_bf16 v[52:55], v[168:171], v[188:191], v[52:55]
	v_mfma_f32_16x16x32_bf16 v[48:51], v[180:183], v[188:191], v[48:51]
	v_mfma_f32_16x16x32_bf16 v[36:39], v[168:171], v[196:199], v[36:39]
	v_mfma_f32_16x16x32_bf16 v[32:35], v[180:183], v[196:199], v[32:35]
	v_mfma_f32_16x16x32_bf16 v[20:23], v[168:171], v[210:213], v[20:23]
	v_mfma_f32_16x16x32_bf16 v[16:19], v[180:183], v[210:213], v[16:19]
	v_mfma_f32_16x16x32_bf16 v[4:7], v[168:171], v[218:221], v[4:7]
	v_mfma_f32_16x16x32_bf16 v[0:3], v[180:183], v[218:221], v[0:3]
	v_mfma_f32_16x16x32_bf16 v[52:55], v[172:175], v[192:195], v[52:55]
	v_mfma_f32_16x16x32_bf16 v[48:51], v[184:187], v[192:195], v[48:51]
	v_mfma_f32_16x16x32_bf16 v[36:39], v[172:175], v[206:209], v[36:39]
	v_mfma_f32_16x16x32_bf16 v[32:35], v[184:187], v[206:209], v[32:35]
	v_lshl_add_u64 v[230:231], s[54:55], 0, v[132:133]
	s_mov_b32 m0, s34
	s_nop 0
	global_load_lds_dwordx4 v[230:231], off
	v_mfma_f32_16x16x32_bf16 v[20:23], v[172:175], v[214:217], v[20:23]
	v_mfma_f32_16x16x32_bf16 v[16:19], v[184:187], v[214:217], v[16:19]
	v_mfma_f32_16x16x32_bf16 v[4:7], v[172:175], v[222:225], v[4:7]
	v_mfma_f32_16x16x32_bf16 v[0:3], v[184:187], v[222:225], v[0:3]
	s_setprio 0
	s_barrier
; #define PG8_STAGE(bufoff, gbase, voff) do { _Pragma("unroll") for (int _i = 0; _i < 2; ++_i) \
;         __builtin_amdgcn_global_load_lds((const unsigned*)((const char*)(gbase) + (voff)[_i]), (PG8_LAS unsigned*)(lds + (bufoff) + ldsw + _i * 8192), 16, 0, 0); } while (0)
; #define PG8_LDA(dst, b, h) do { _Pragma("unroll") for (int m = 0; m < 4; ++m) _Pragma("unroll") for (int k = 0; k < 2; ++k) dst[m][k] = *(const PG8_LAS bf16x8*)(lds + PG8_SA(b, h) + aoff + m * 2048 + k * 1024); } while (0)
; #define PG8_LDB(dst, b, h) do { _Pragma("unroll") for (int n = 0; n < 2; ++n) _Pragma("unroll") for (int k = 0; k < 2; ++k) dst[n][k] = *(const PG8_LAS bf16x8*)(lds + PG8_SB(b, h) + boff + n * 2048 + k * 1024); } while (0)
; #define PG8_MMA(ai, bj, At, Bt) do { __builtin_amdgcn_s_setprio(1); _Pragma("unroll") for (int m = 0; m < 4; ++m) _Pragma("unroll") for (int n = 0; n < 2; ++n) _Pragma("unroll") for (int k = 0; k < 2; ++k) \
;         acc[ai][bj][m][n] = __builtin_amdgcn_mfma_f32_16x16x32_bf16(Bt[n][k], At[m][k], acc[ai][bj][m][n], 0, 0, 0); __builtin_amdgcn_s_setprio(0); } while (0)
; #define PG8_WAIT_V(n) asm volatile("s_waitcnt vmcnt(" #n ")" ::: "memory")
; #define PG8_WAIT_L(n) asm volatile("s_waitcnt lgkmcnt(" #n ")" ::: "memory")
; #define PG8_BAR __builtin_amdgcn_s_barrier()
; #define PG8_SCHED __builtin_amdgcn_sched_barrier(0)
; template <class Epi, class Sched, bool ALIGN_EPI = false, bool SP2 = false>
; __device__ __forceinline__ void gemm_phase(PG8_LAS unsigned char* lds, const Gemm g, const Sched& S, const Epi& E) {
;     ...
;             PG8_LDB(B0, 1, 0); PG8_LDB(B1, 1, 1); PG8_SCHED; PG8_LDA(At, 1, 0); PG8_STAGE(PG8_SA(0, 1), a2 + hstep, voffA);
;             PG8_WAIT_V(8); PG8_WAIT_L(0); PG8_BAR; PG8_MMA(0, 0, At, B0); PG8_MMA(0, 1, At, B1); PG8_BAR; PG8_SCHED;
	s_add_i32 s74, 0, 0x18000
	s_add_i32 s75, 0, 0x1c000
	v_add_u32_e32 v164, s74, v150
	v_add_u32_e32 v179, s75, v150
	ds_read_b128 v[146:149], v164
	ds_read_b128 v[156:159], v164 offset:1024
	ds_read_b128 v[160:163], v164 offset:2048
	ds_read_b128 v[164:167], v164 offset:3072
	ds_read_b128 v[168:171], v179
	ds_read_b128 v[172:175], v179 offset:1024
	ds_read_b128 v[180:183], v179 offset:2048
	ds_read_b128 v[184:187], v179 offset:3072
	s_add_u32 s54, s54, 0x40000
	s_addc_u32 s55, s55, 0
	s_mov_b32 m0, s49
	v_lshl_add_u64 v[232:233], s[54:55], 0, v[128:129]
	ds_read_b128 v[188:191], v154 offset:32768
	ds_read_b128 v[192:195], v154 offset:33792
	ds_read_b128 v[196:199], v154 offset:34816
	ds_read_b128 v[206:209], v154 offset:35840
	ds_read_b128 v[210:213], v154 offset:36864
	ds_read_b128 v[214:217], v154 offset:37888
	ds_read_b128 v[218:221], v154 offset:38912
	ds_read_b128 v[222:225], v154 offset:39936
	global_load_lds_dwordx4 v[232:233], off
	v_lshl_add_u64 v[232:233], s[54:55], 0, v[132:133]
	s_mov_b32 m0, s56
	s_nop 0
	global_load_lds_dwordx4 v[232:233], off
	s_waitcnt vmcnt(8)
	s_waitcnt lgkmcnt(0)
	s_barrier
	s_setprio 1
	s_waitcnt lgkmcnt(0)
	v_mfma_f32_16x16x32_bf16 v[124:127], v[146:149], v[188:191], v[124:127]
	v_mfma_f32_16x16x32_bf16 v[120:123], v[160:163], v[188:191], v[120:123]
	v_mfma_f32_16x16x32_bf16 v[108:111], v[146:149], v[196:199], v[108:111]
	v_mfma_f32_16x16x32_bf16 v[104:107], v[160:163], v[196:199], v[104:107]
	v_mfma_f32_16x16x32_bf16 v[92:95], v[146:149], v[210:213], v[92:95]
	v_mfma_f32_16x16x32_bf16 v[88:91], v[160:163], v[210:213], v[88:91]
	v_mfma_f32_16x16x32_bf16 v[76:79], v[146:149], v[218:221], v[76:79]
	v_mfma_f32_16x16x32_bf16 v[72:75], v[160:163], v[218:221], v[72:75]
	v_mfma_f32_16x16x32_bf16 v[124:127], v[156:159], v[192:195], v[124:127]
	v_mfma_f32_16x16x32_bf16 v[120:123], v[164:167], v[192:195], v[120:123]
	v_mfma_f32_16x16x32_bf16 v[108:111], v[156:159], v[206:209], v[108:111]
	v_mfma_f32_16x16x32_bf16 v[104:107], v[164:167], v[206:209], v[104:107]
	v_mfma_f32_16x16x32_bf16 v[92:95], v[156:159], v[214:217], v[92:95]
	v_mfma_f32_16x16x32_bf16 v[88:91], v[164:167], v[214:217], v[88:91]
	v_mfma_f32_16x16x32_bf16 v[76:79], v[156:159], v[222:225], v[76:79]
	v_mfma_f32_16x16x32_bf16 v[72:75], v[164:167], v[222:225], v[72:75]
	s_setprio 0
	s_setprio 1
	v_mfma_f32_16x16x32_bf16 v[116:119], v[168:171], v[188:191], v[116:119]
	v_mfma_f32_16x16x32_bf16 v[112:115], v[180:183], v[188:191], v[112:115]
	v_mfma_f32_16x16x32_bf16 v[100:103], v[168:171], v[196:199], v[100:103]
	v_mfma_f32_16x16x32_bf16 v[96:99], v[180:183], v[196:199], v[96:99]
	v_mfma_f32_16x16x32_bf16 v[84:87], v[168:171], v[210:213], v[84:87]
	v_mfma_f32_16x16x32_bf16 v[80:83], v[180:183], v[210:213], v[80:83]
	v_mfma_f32_16x16x32_bf16 v[68:71], v[168:171], v[218:221], v[68:71]
	v_mfma_f32_16x16x32_bf16 v[64:67], v[180:183], v[218:221], v[64:67]
	v_mfma_f32_16x16x32_bf16 v[116:119], v[172:175], v[192:195], v[116:119]
	v_mfma_f32_16x16x32_bf16 v[112:115], v[184:187], v[192:195], v[112:115]
	v_mfma_f32_16x16x32_bf16 v[100:103], v[172:175], v[206:209], v[100:103]
	v_mfma_f32_16x16x32_bf16 v[96:99], v[184:187], v[206:209], v[96:99]
	v_mfma_f32_16x16x32_bf16 v[84:87], v[172:175], v[214:217], v[84:87]
	v_mfma_f32_16x16x32_bf16 v[80:83], v[184:187], v[214:217], v[80:83]
	v_mfma_f32_16x16x32_bf16 v[68:71], v[172:175], v[222:225], v[68:71]
	v_mfma_f32_16x16x32_bf16 v[64:67], v[184:187], v[222:225], v[64:67]
	s_setprio 0
	s_barrier
; #define PG8_STAGE(bufoff, gbase, voff) do { _Pragma("unroll") for (int _i = 0; _i < 2; ++_i) \
;         __builtin_amdgcn_global_load_lds((const unsigned*)((const char*)(gbase) + (voff)[_i]), (PG8_LAS unsigned*)(lds + (bufoff) + ldsw + _i * 8192), 16, 0, 0); } while (0)
; #define PG8_LDA(dst, b, h) do { _Pragma("unroll") for (int m = 0; m < 4; ++m) _Pragma("unroll") for (int k = 0; k < 2; ++k) dst[m][k] = *(const PG8_LAS bf16x8*)(lds + PG8_SA(b, h) + aoff + m * 2048 + k * 1024); } while (0)
; #define PG8_MMA(ai, bj, At, Bt) do { __builtin_amdgcn_s_setprio(1); _Pragma("unroll") for (int m = 0; m < 4; ++m) _Pragma("unroll") for (int n = 0; n < 2; ++n) _Pragma("unroll") for (int k = 0; k < 2; ++k) \
;         acc[ai][bj][m][n] = __builtin_amdgcn_mfma_f32_16x16x32_bf16(Bt[n][k], At[m][k], acc[ai][bj][m][n], 0, 0, 0); __builtin_amdgcn_s_setprio(0); } while (0)
; #define PG8_WAIT_V(n) asm volatile("s_waitcnt vmcnt(" #n ")" ::: "memory")
; #define PG8_WAIT_L(n) asm volatile("s_waitcnt lgkmcnt(" #n ")" ::: "memory")
; #define PG8_BAR __builtin_amdgcn_s_barrier()
; #define PG8_SCHED __builtin_amdgcn_sched_barrier(0)
; template <class Epi, class Sched, bool ALIGN_EPI = false, bool SP2 = false>
; __device__ __forceinline__ void gemm_phase(PG8_LAS unsigned char* lds, const Gemm g, const Sched& S, const Epi& E) {
;     ...
;             PG8_LDA(At, 1, 1); PG8_STAGE(PG8_SB(1, 0), b3, voffB); PG8_STAGE(PG8_SB(1, 1), b3 + hstep, voffB); PG8_STAGE(PG8_SA(1, 0), a3, voffA);
;             PG8_WAIT_V(8); PG8_WAIT_L(0); PG8_BAR; PG8_MMA(1, 0, At, B0); PG8_MMA(1, 1, At, B1); PG8_BAR; PG8_SCHED;
;     ...
;         if constexpr (ALIGN_EPI) { if (wr == 0) PG8_BAR; }
	s_add_i32 s54, s74, s15
	v_lshl_add_u64 v[200:201], v[200:201], 0, s[26:27]
	s_mov_b32 m0, s54
	ds_read_b128 v[188:191], v154 offset:49152
	ds_read_b128 v[192:195], v154 offset:50176
	ds_read_b128 v[196:199], v154 offset:51200
	ds_read_b128 v[206:209], v154 offset:52224
	ds_read_b128 v[210:213], v154 offset:53248
	ds_read_b128 v[214:217], v154 offset:54272
	ds_read_b128 v[218:221], v154 offset:55296
	ds_read_b128 v[222:225], v154 offset:56320
	global_load_lds_dwordx4 v[200:201], off
	s_add_i32 m0, s54, 0x2000
	s_add_u32 s52, s52, 0x40080
	v_lshl_add_u64 v[200:201], v[226:227], 0, s[26:27]
	s_addc_u32 s53, s53, 0
	s_add_i32 s54, s75, s15
	global_load_lds_dwordx4 v[200:201], off
	v_lshl_add_u64 v[200:201], s[52:53], 0, v[130:131]
	s_mov_b32 m0, s54
	s_nop 0
	global_load_lds_dwordx4 v[200:201], off
	v_lshl_add_u64 v[200:201], s[52:53], 0, v[134:135]
	s_add_i32 m0, s54, 0x2000
	s_nop 0
	global_load_lds_dwordx4 v[200:201], off
	s_waitcnt vmcnt(6)
	s_waitcnt lgkmcnt(0)
	s_barrier
	s_setprio 1
	s_waitcnt lgkmcnt(0)
	v_mfma_f32_16x16x32_bf16 v[60:63], v[146:149], v[188:191], v[60:63]
	v_mfma_f32_16x16x32_bf16 v[56:59], v[160:163], v[188:191], v[56:59]
	v_mfma_f32_16x16x32_bf16 v[44:47], v[146:149], v[196:199], v[44:47]
	v_mfma_f32_16x16x32_bf16 v[40:43], v[160:163], v[196:199], v[40:43]
	v_mfma_f32_16x16x32_bf16 v[28:31], v[146:149], v[210:213], v[28:31]
	v_mfma_f32_16x16x32_bf16 v[24:27], v[160:163], v[210:213], v[24:27]
	v_mfma_f32_16x16x32_bf16 v[12:15], v[146:149], v[218:221], v[12:15]
	v_mfma_f32_16x16x32_bf16 v[8:11], v[160:163], v[218:221], v[8:11]
	v_mfma_f32_16x16x32_bf16 v[60:63], v[156:159], v[192:195], v[60:63]
	v_mfma_f32_16x16x32_bf16 v[56:59], v[164:167], v[192:195], v[56:59]
	v_mfma_f32_16x16x32_bf16 v[44:47], v[156:159], v[206:209], v[44:47]
	v_mfma_f32_16x16x32_bf16 v[40:43], v[164:167], v[206:209], v[40:43]
	v_lshl_add_u64 v[200:201], v[228:229], 0, s[26:27]
	s_mov_b32 m0, s58
	s_nop 0
	global_load_lds_dwordx4 v[200:201], off
	v_mfma_f32_16x16x32_bf16 v[28:31], v[156:159], v[214:217], v[28:31]
	v_mfma_f32_16x16x32_bf16 v[24:27], v[164:167], v[214:217], v[24:27]
	v_mfma_f32_16x16x32_bf16 v[12:15], v[156:159], v[222:225], v[12:15]
	v_mfma_f32_16x16x32_bf16 v[8:11], v[164:167], v[222:225], v[8:11]
	s_setprio 0
	s_setprio 1
	v_mfma_f32_16x16x32_bf16 v[52:55], v[168:171], v[188:191], v[52:55]
	v_mfma_f32_16x16x32_bf16 v[48:51], v[180:183], v[188:191], v[48:51]
	v_mfma_f32_16x16x32_bf16 v[36:39], v[168:171], v[196:199], v[36:39]
	v_mfma_f32_16x16x32_bf16 v[32:35], v[180:183], v[196:199], v[32:35]
	v_mfma_f32_16x16x32_bf16 v[20:23], v[168:171], v[210:213], v[20:23]
	v_mfma_f32_16x16x32_bf16 v[16:19], v[180:183], v[210:213], v[16:19]
	v_mfma_f32_16x16x32_bf16 v[4:7], v[168:171], v[218:221], v[4:7]
	v_mfma_f32_16x16x32_bf16 v[0:3], v[180:183], v[218:221], v[0:3]
	v_mfma_f32_16x16x32_bf16 v[52:55], v[172:175], v[192:195], v[52:55]
	v_mfma_f32_16x16x32_bf16 v[48:51], v[184:187], v[192:195], v[48:51]
	v_mfma_f32_16x16x32_bf16 v[36:39], v[172:175], v[206:209], v[36:39]
	v_mfma_f32_16x16x32_bf16 v[32:35], v[184:187], v[206:209], v[32:35]
	v_lshl_add_u64 v[200:201], v[230:231], 0, s[26:27]
	s_mov_b32 m0, s59
	s_nop 0
	global_load_lds_dwordx4 v[200:201], off
	v_mfma_f32_16x16x32_bf16 v[20:23], v[172:175], v[214:217], v[20:23]
	v_mfma_f32_16x16x32_bf16 v[16:19], v[184:187], v[214:217], v[16:19]
	v_mfma_f32_16x16x32_bf16 v[4:7], v[172:175], v[222:225], v[4:7]
	v_mfma_f32_16x16x32_bf16 v[0:3], v[184:187], v[222:225], v[0:3]
	s_setprio 0
	s_barrier
	s_add_i32 s67, s67, 2
	s_add_u32 s50, s50, 0x100
	s_addc_u32 s51, s51, 0
	s_add_u32 s65, s65, 0x100
	s_addc_u32 s66, s66, 0
	s_cmp_gt_u32 s67, 13
	s_cbranch_scc0 .LBB0_1593
	s_and_b64 vcc, exec, s[28:29]
	s_cbranch_vccz .LBB0_1596
	s_barrier

; #define PG8_STAGE(bufoff, gbase, voff) do { _Pragma("unroll") for (int _i = 0; _i < 2; ++_i) \
;         __builtin_amdgcn_global_load_lds((const unsigned*)((const char*)(gbase) + (voff)[_i]), (PG8_LAS unsigned*)(lds + (bufoff) + ldsw + _i * 8192), 16, 0, 0); } while (0)
; #define PG8_LDA(dst, b, h) do { _Pragma("unroll") for (int m = 0; m < 4; ++m) _Pragma("unroll") for (int k = 0; k < 2; ++k) dst[m][k] = *(const PG8_LAS bf16x8*)(lds + PG8_SA(b, h) + aoff + m * 2048 + k * 1024); } while (0)
; #define PG8_LDB(dst, b, h) do { _Pragma("unroll") for (int n = 0; n < 2; ++n) _Pragma("unroll") for (int k = 0; k < 2; ++k) dst[n][k] = *(const PG8_LAS bf16x8*)(lds + PG8_SB(b, h) + boff + n * 2048 + k * 1024); } while (0)
; #define PG8_MMA(ai, bj, At, Bt) do { __builtin_amdgcn_s_setprio(1); _Pragma("unroll") for (int m = 0; m < 4; ++m) _Pragma("unroll") for (int n = 0; n < 2; ++n) _Pragma("unroll") for (int k = 0; k < 2; ++k) \
;         acc[ai][bj][m][n] = __builtin_amdgcn_mfma_f32_16x16x32_bf16(Bt[n][k], At[m][k], acc[ai][bj][m][n], 0, 0, 0); __builtin_amdgcn_s_setprio(0); } while (0)
; #define PG8_BAR __builtin_amdgcn_s_barrier()
; template <class Epi, class Sched, bool ALIGN_EPI = false, bool SP2 = false>
; __device__ __forceinline__ void gemm_phase(PG8_LAS unsigned char* lds, const Gemm g, const Sched& S, const Epi& E) {
;     ...
;         const bool has_next = S.next(ui + 1, nxt);
;         const char* nA = has_next ? (const char*)g.A + (size_t)nxt.pm * tstep : cA; const char* nB = has_next ? (const char*)g.Bt + (size_t)nxt.pn * tstep : cB;
;         for (int t = 0; t < nt; t += 2) {
;             const bool last = (t == nt - 2);
;             const char* a1 = cA + (size_t)(t + 1) * kstep;
;             const char* a2 = last ? nA : cA + (size_t)(t + 2) * kstep; const char* b2 = last ? nB : cB + (size_t)(t + 2) * kstep;
;             const char* a3 = a2 + kstep; const char* b3 = b2 + kstep;
;             if (last && has_next) S.a_ready(nxt);
;             if constexpr (SP2) {
;             PG8_LDB(B0, 0, 0); PG8_LDB(B1, 0, 1); PG8_SCHED; PG8_LDA(At, 0, 0); PG8_STAGE(PG8_SA(1, 1), a1 + hstep, voffA);
;             PG8_WAIT_V(8); PG8_WAIT_L(0); PG8_BAR; PG8_MMA(0, 0, At, B0); PG8_MMA(0, 1, At, B1); PG8_BAR; PG8_SCHED;
;             PG8_LDA(At, 0, 1); PG8_STAGE(PG8_SB(0, 0), b2, voffB); PG8_STAGE(PG8_SB(0, 1), b2 + hstep, voffB); PG8_STAGE(PG8_SA(0, 0), a2, voffA);
.LBB0_1680:
	s_ashr_i32 s47, s46, 31
	s_lshl_b64 s[48:49], s[46:47], 19
	s_add_u32 s48, s22, s48
	s_addc_u32 s49, s23, s49
	s_and_b64 s[50:51], s[4:5], exec
	s_cselect_b32 s47, s49, s53
	s_cselect_b32 s77, s48, s52
	s_ashr_i32 s45, s44, 31
	s_lshl_b64 s[50:51], s[44:45], 19
	s_add_u32 s50, s15, s50
	s_addc_u32 s51, s33, s51
	s_and_b64 s[56:57], s[4:5], exec
	s_cselect_b32 s45, s51, s55
	s_cselect_b32 s78, s50, s54
	s_add_u32 s52, s52, 0x40080
	s_addc_u32 s53, s53, 0
	s_add_u32 s79, s54, 0x100
	s_addc_u32 s80, s55, 0
	s_mov_b32 s81, -2
	ds_read_b128 v[146:149], v152
	ds_read_b128 v[156:159], v152 offset:1024
	ds_read_b128 v[160:163], v152 offset:2048
	ds_read_b128 v[164:167], v152 offset:3072
	ds_read_b128 v[168:171], v153
	ds_read_b128 v[172:175], v153 offset:1024
	ds_read_b128 v[180:183], v153 offset:2048
	ds_read_b128 v[184:187], v153 offset:3072
	s_add_u32 s54, s52, 0xfffc0080
	s_addc_u32 s55, s53, -1
	s_cmp_eq_u32 s81, 12
	s_cselect_b32 s57, s47, s55
	s_cselect_b32 s56, s77, s54
	s_cselect_b32 s55, s45, s80
	s_cselect_b32 s54, s78, s79
	v_lshl_add_u64 v[200:201], s[52:53], 0, v[136:137]
	s_add_i32 m0, s58, 0xc000
	ds_read_b128 v[188:191], v154
	ds_read_b128 v[192:195], v154 offset:1024
	ds_read_b128 v[196:199], v154 offset:2048
	ds_read_b128 v[206:209], v154 offset:3072
	ds_read_b128 v[210:213], v154 offset:4096
	ds_read_b128 v[214:217], v154 offset:5120
	ds_read_b128 v[218:221], v154 offset:6144
	ds_read_b128 v[222:225], v154 offset:7168
	global_load_lds_dwordx4 v[200:201], off
	v_lshl_add_u64 v[200:201], s[52:53], 0, v[138:139]
	s_add_i32 m0, s58, 0xe000
	s_nop 0
	global_load_lds_dwordx4 v[200:201], off
	s_waitcnt vmcnt(8)
	s_waitcnt lgkmcnt(0)
	s_barrier
	s_setprio 1
	s_waitcnt lgkmcnt(0)
	v_mfma_f32_16x16x32_bf16 v[124:127], v[146:149], v[188:191], 0
	v_mfma_f32_16x16x32_bf16 v[120:123], v[160:163], v[188:191], 0
	v_mfma_f32_16x16x32_bf16 v[108:111], v[146:149], v[196:199], 0
	v_mfma_f32_16x16x32_bf16 v[104:107], v[160:163], v[196:199], 0
	v_mfma_f32_16x16x32_bf16 v[92:95], v[146:149], v[210:213], 0
	v_mfma_f32_16x16x32_bf16 v[88:91], v[160:163], v[210:213], 0
	v_mfma_f32_16x16x32_bf16 v[76:79], v[146:149], v[218:221], 0
	v_mfma_f32_16x16x32_bf16 v[72:75], v[160:163], v[218:221], 0
	v_mfma_f32_16x16x32_bf16 v[124:127], v[156:159], v[192:195], v[124:127]
	v_mfma_f32_16x16x32_bf16 v[120:123], v[164:167], v[192:195], v[120:123]
	v_mfma_f32_16x16x32_bf16 v[108:111], v[156:159], v[206:209], v[108:111]
	v_mfma_f32_16x16x32_bf16 v[104:107], v[164:167], v[206:209], v[104:107]
	v_mfma_f32_16x16x32_bf16 v[92:95], v[156:159], v[214:217], v[92:95]
	v_mfma_f32_16x16x32_bf16 v[88:91], v[164:167], v[214:217], v[88:91]
	v_mfma_f32_16x16x32_bf16 v[76:79], v[156:159], v[222:225], v[76:79]
	v_mfma_f32_16x16x32_bf16 v[72:75], v[164:167], v[222:225], v[72:75]
	s_setprio 0
	s_setprio 1
	v_mfma_f32_16x16x32_bf16 v[116:119], v[168:171], v[188:191], 0
	v_mfma_f32_16x16x32_bf16 v[112:115], v[180:183], v[188:191], 0
	v_mfma_f32_16x16x32_bf16 v[100:103], v[168:171], v[196:199], 0
	v_mfma_f32_16x16x32_bf16 v[96:99], v[180:183], v[196:199], 0
	v_mfma_f32_16x16x32_bf16 v[84:87], v[168:171], v[210:213], 0
	v_mfma_f32_16x16x32_bf16 v[80:83], v[180:183], v[210:213], 0
	v_mfma_f32_16x16x32_bf16 v[68:71], v[168:171], v[218:221], 0
	v_mfma_f32_16x16x32_bf16 v[64:67], v[180:183], v[218:221], 0
	v_mfma_f32_16x16x32_bf16 v[116:119], v[172:175], v[192:195], v[116:119]
	v_mfma_f32_16x16x32_bf16 v[112:115], v[184:187], v[192:195], v[112:115]
	v_mfma_f32_16x16x32_bf16 v[100:103], v[172:175], v[206:209], v[100:103]
	v_mfma_f32_16x16x32_bf16 v[96:99], v[184:187], v[206:209], v[96:99]
	v_mfma_f32_16x16x32_bf16 v[84:87], v[172:175], v[214:217], v[84:87]
	v_mfma_f32_16x16x32_bf16 v[80:83], v[184:187], v[214:217], v[80:83]
	v_mfma_f32_16x16x32_bf16 v[68:71], v[172:175], v[222:225], v[68:71]
	v_mfma_f32_16x16x32_bf16 v[64:67], v[184:187], v[222:225], v[64:67]
	s_setprio 0
	s_barrier
	s_add_i32 s82, s65, s34
	v_lshl_add_u64 v[200:201], s[54:55], 0, v[132:133]
	s_mov_b32 m0, s82
	ds_read_b128 v[188:191], v154 offset:16384
	ds_read_b128 v[192:195], v154 offset:17408
	ds_read_b128 v[196:199], v154 offset:18432
	ds_read_b128 v[206:209], v154 offset:19456
	ds_read_b128 v[210:213], v154 offset:20480
	ds_read_b128 v[214:217], v154 offset:21504
	ds_read_b128 v[218:221], v154 offset:22528
	ds_read_b128 v[222:225], v154 offset:23552
	global_load_lds_dwordx4 v[200:201], off
	s_add_i32 m0, s82, 0x2000
	s_add_u32 s82, s54, 0x40000
	v_lshl_add_u64 v[226:227], s[54:55], 0, v[128:129]
	s_addc_u32 s83, s55, 0
	s_add_i32 s84, s66, s34
	global_load_lds_dwordx4 v[226:227], off
	v_lshl_add_u64 v[228:229], s[82:83], 0, v[132:133]
	s_mov_b32 m0, s84
	global_load_lds_dwordx4 v[228:229], off
	v_lshl_add_u64 v[228:229], s[82:83], 0, v[128:129]
	s_add_i32 m0, s84, 0x2000
	s_nop 0
	global_load_lds_dwordx4 v[228:229], off
	s_waitcnt vmcnt(6)
	s_waitcnt lgkmcnt(0)
	s_barrier
; #define PG8_STAGE(bufoff, gbase, voff) do { _Pragma("unroll") for (int _i = 0; _i < 2; ++_i) \
;         __builtin_amdgcn_global_load_lds((const unsigned*)((const char*)(gbase) + (voff)[_i]), (PG8_LAS unsigned*)(lds + (bufoff) + ldsw + _i * 8192), 16, 0, 0); } while (0)
; #define PG8_LDA(dst, b, h) do { _Pragma("unroll") for (int m = 0; m < 4; ++m) _Pragma("unroll") for (int k = 0; k < 2; ++k) dst[m][k] = *(const PG8_LAS bf16x8*)(lds + PG8_SA(b, h) + aoff + m * 2048 + k * 1024); } while (0)
; #define PG8_LDB(dst, b, h) do { _Pragma("unroll") for (int n = 0; n < 2; ++n) _Pragma("unroll") for (int k = 0; k < 2; ++k) dst[n][k] = *(const PG8_LAS bf16x8*)(lds + PG8_SB(b, h) + boff + n * 2048 + k * 1024); } while (0)
; #define PG8_MMA(ai, bj, At, Bt) do { __builtin_amdgcn_s_setprio(1); _Pragma("unroll") for (int m = 0; m < 4; ++m) _Pragma("unroll") for (int n = 0; n < 2; ++n) _Pragma("unroll") for (int k = 0; k < 2; ++k) \
;         acc[ai][bj][m][n] = __builtin_amdgcn_mfma_f32_16x16x32_bf16(Bt[n][k], At[m][k], acc[ai][bj][m][n], 0, 0, 0); __builtin_amdgcn_s_setprio(0); } while (0)
; #define PG8_WAIT_V(n) asm volatile("s_waitcnt vmcnt(" #n ")" ::: "memory")
; #define PG8_WAIT_L(n) asm volatile("s_waitcnt lgkmcnt(" #n ")" ::: "memory")
; #define PG8_BAR __builtin_amdgcn_s_barrier()
; #define PG8_SCHED __builtin_amdgcn_sched_barrier(0)
; template <class Epi, class Sched, bool ALIGN_EPI = false, bool SP2 = false>
; __device__ __forceinline__ void gemm_phase(PG8_LAS unsigned char* lds, const Gemm g, const Sched& S, const Epi& E) {
;     ...
;             PG8_LDA(At, 0, 1); PG8_STAGE(PG8_SB(0, 0), b2, voffB); PG8_STAGE(PG8_SB(0, 1), b2 + hstep, voffB); PG8_STAGE(PG8_SA(0, 0), a2, voffA);
;             PG8_WAIT_V(8); PG8_WAIT_L(0); PG8_BAR; PG8_MMA(1, 0, At, B0); PG8_MMA(1, 1, At, B1); PG8_BAR; PG8_SCHED;
;             PG8_LDB(B0, 1, 0); PG8_LDB(B1, 1, 1); PG8_SCHED; PG8_LDA(At, 1, 0); PG8_STAGE(PG8_SA(0, 1), a2 + hstep, voffA);
;             PG8_WAIT_V(8); PG8_WAIT_L(0); PG8_BAR; PG8_MMA(0, 0, At, B0); PG8_MMA(0, 1, At, B1); PG8_BAR; PG8_SCHED;
	s_setprio 1
	s_waitcnt lgkmcnt(0)
	v_mfma_f32_16x16x32_bf16 v[60:63], v[146:149], v[188:191], 0
	v_mfma_f32_16x16x32_bf16 v[56:59], v[160:163], v[188:191], 0
	v_mfma_f32_16x16x32_bf16 v[44:47], v[146:149], v[196:199], 0
	v_mfma_f32_16x16x32_bf16 v[40:43], v[160:163], v[196:199], 0
	v_mfma_f32_16x16x32_bf16 v[28:31], v[146:149], v[210:213], 0
	v_mfma_f32_16x16x32_bf16 v[24:27], v[160:163], v[210:213], 0
	v_mfma_f32_16x16x32_bf16 v[12:15], v[146:149], v[218:221], 0
	v_mfma_f32_16x16x32_bf16 v[8:11], v[160:163], v[218:221], 0
	v_mfma_f32_16x16x32_bf16 v[60:63], v[156:159], v[192:195], v[60:63]
	v_mfma_f32_16x16x32_bf16 v[56:59], v[164:167], v[192:195], v[56:59]
	v_mfma_f32_16x16x32_bf16 v[44:47], v[156:159], v[206:209], v[44:47]
	v_mfma_f32_16x16x32_bf16 v[40:43], v[164:167], v[206:209], v[40:43]
	v_lshl_add_u64 v[228:229], s[56:57], 0, v[134:135]
	s_mov_b32 m0, s58
	s_nop 0
	global_load_lds_dwordx4 v[228:229], off
	v_mfma_f32_16x16x32_bf16 v[28:31], v[156:159], v[214:217], v[28:31]
	v_mfma_f32_16x16x32_bf16 v[24:27], v[164:167], v[214:217], v[24:27]
	v_mfma_f32_16x16x32_bf16 v[12:15], v[156:159], v[222:225], v[12:15]
	v_mfma_f32_16x16x32_bf16 v[8:11], v[164:167], v[222:225], v[8:11]
	s_setprio 0
	s_setprio 1
	v_mfma_f32_16x16x32_bf16 v[52:55], v[168:171], v[188:191], 0
	v_mfma_f32_16x16x32_bf16 v[48:51], v[180:183], v[188:191], 0
	v_mfma_f32_16x16x32_bf16 v[36:39], v[168:171], v[196:199], 0
	v_mfma_f32_16x16x32_bf16 v[32:35], v[180:183], v[196:199], 0
	v_mfma_f32_16x16x32_bf16 v[20:23], v[168:171], v[210:213], 0
	v_mfma_f32_16x16x32_bf16 v[16:19], v[180:183], v[210:213], 0
	v_mfma_f32_16x16x32_bf16 v[4:7], v[168:171], v[218:221], 0
	v_mfma_f32_16x16x32_bf16 v[0:3], v[180:183], v[218:221], 0
	v_mfma_f32_16x16x32_bf16 v[52:55], v[172:175], v[192:195], v[52:55]
	v_mfma_f32_16x16x32_bf16 v[48:51], v[184:187], v[192:195], v[48:51]
	v_mfma_f32_16x16x32_bf16 v[36:39], v[172:175], v[206:209], v[36:39]
	v_mfma_f32_16x16x32_bf16 v[32:35], v[184:187], v[206:209], v[32:35]
	v_lshl_add_u64 v[230:231], s[56:57], 0, v[130:131]
	s_mov_b32 m0, s59
	s_nop 0
	global_load_lds_dwordx4 v[230:231], off
	v_mfma_f32_16x16x32_bf16 v[20:23], v[172:175], v[214:217], v[20:23]
	v_mfma_f32_16x16x32_bf16 v[16:19], v[184:187], v[214:217], v[16:19]
	v_mfma_f32_16x16x32_bf16 v[4:7], v[172:175], v[222:225], v[4:7]
	v_mfma_f32_16x16x32_bf16 v[0:3], v[184:187], v[222:225], v[0:3]
	s_setprio 0
	s_barrier
	s_add_i32 s82, 0, 0x18000
	s_add_i32 s83, 0, 0x1c000
	v_add_u32_e32 v164, s82, v150
	v_add_u32_e32 v179, s83, v150
	ds_read_b128 v[146:149], v164
	ds_read_b128 v[156:159], v164 offset:1024
	ds_read_b128 v[160:163], v164 offset:2048
	ds_read_b128 v[164:167], v164 offset:3072
	ds_read_b128 v[168:171], v179
	ds_read_b128 v[172:175], v179 offset:1024
	ds_read_b128 v[180:183], v179 offset:2048
	ds_read_b128 v[184:187], v179 offset:3072
	s_add_u32 s56, s56, 0x40000
	s_addc_u32 s57, s57, 0
	s_mov_b32 m0, s60
	v_lshl_add_u64 v[232:233], s[56:57], 0, v[134:135]
	ds_read_b128 v[188:191], v154 offset:32768
	ds_read_b128 v[192:195], v154 offset:33792
	ds_read_b128 v[196:199], v154 offset:34816
	ds_read_b128 v[206:209], v154 offset:35840
	ds_read_b128 v[210:213], v154 offset:36864
	ds_read_b128 v[214:217], v154 offset:37888
	ds_read_b128 v[218:221], v154 offset:38912
	ds_read_b128 v[222:225], v154 offset:39936
	global_load_lds_dwordx4 v[232:233], off
	v_lshl_add_u64 v[232:233], s[56:57], 0, v[130:131]
	s_mov_b32 m0, s61
	s_nop 0
	global_load_lds_dwordx4 v[232:233], off
	s_waitcnt vmcnt(8)
	s_waitcnt lgkmcnt(0)
	s_barrier
	s_setprio 1
	s_waitcnt lgkmcnt(0)
	v_mfma_f32_16x16x32_bf16 v[124:127], v[146:149], v[188:191], v[124:127]
	v_mfma_f32_16x16x32_bf16 v[120:123], v[160:163], v[188:191], v[120:123]
	v_mfma_f32_16x16x32_bf16 v[108:111], v[146:149], v[196:199], v[108:111]
	v_mfma_f32_16x16x32_bf16 v[104:107], v[160:163], v[196:199], v[104:107]
	v_mfma_f32_16x16x32_bf16 v[92:95], v[146:149], v[210:213], v[92:95]
	v_mfma_f32_16x16x32_bf16 v[88:91], v[160:163], v[210:213], v[88:91]
	v_mfma_f32_16x16x32_bf16 v[76:79], v[146:149], v[218:221], v[76:79]
	v_mfma_f32_16x16x32_bf16 v[72:75], v[160:163], v[218:221], v[72:75]
	v_mfma_f32_16x16x32_bf16 v[124:127], v[156:159], v[192:195], v[124:127]
	v_mfma_f32_16x16x32_bf16 v[120:123], v[164:167], v[192:195], v[120:123]
	v_mfma_f32_16x16x32_bf16 v[108:111], v[156:159], v[206:209], v[108:111]
	v_mfma_f32_16x16x32_bf16 v[104:107], v[164:167], v[206:209], v[104:107]
	v_mfma_f32_16x16x32_bf16 v[92:95], v[156:159], v[214:217], v[92:95]
	v_mfma_f32_16x16x32_bf16 v[88:91], v[164:167], v[214:217], v[88:91]
	v_mfma_f32_16x16x32_bf16 v[76:79], v[156:159], v[222:225], v[76:79]
	v_mfma_f32_16x16x32_bf16 v[72:75], v[164:167], v[222:225], v[72:75]
	s_setprio 0
	s_setprio 1
	v_mfma_f32_16x16x32_bf16 v[116:119], v[168:171], v[188:191], v[116:119]
	v_mfma_f32_16x16x32_bf16 v[112:115], v[180:183], v[188:191], v[112:115]
	v_mfma_f32_16x16x32_bf16 v[100:103], v[168:171], v[196:199], v[100:103]
	v_mfma_f32_16x16x32_bf16 v[96:99], v[180:183], v[196:199], v[96:99]
	v_mfma_f32_16x16x32_bf16 v[84:87], v[168:171], v[210:213], v[84:87]
	v_mfma_f32_16x16x32_bf16 v[80:83], v[180:183], v[210:213], v[80:83]
	v_mfma_f32_16x16x32_bf16 v[68:71], v[168:171], v[218:221], v[68:71]
	v_mfma_f32_16x16x32_bf16 v[64:67], v[180:183], v[218:221], v[64:67]
	v_mfma_f32_16x16x32_bf16 v[116:119], v[172:175], v[192:195], v[116:119]
	v_mfma_f32_16x16x32_bf16 v[112:115], v[184:187], v[192:195], v[112:115]
	v_mfma_f32_16x16x32_bf16 v[100:103], v[172:175], v[206:209], v[100:103]
	v_mfma_f32_16x16x32_bf16 v[96:99], v[184:187], v[206:209], v[96:99]
	v_mfma_f32_16x16x32_bf16 v[84:87], v[172:175], v[214:217], v[84:87]
	v_mfma_f32_16x16x32_bf16 v[80:83], v[184:187], v[214:217], v[80:83]
	v_mfma_f32_16x16x32_bf16 v[68:71], v[172:175], v[222:225], v[68:71]
	v_mfma_f32_16x16x32_bf16 v[64:67], v[184:187], v[222:225], v[64:67]
	s_setprio 0
	s_barrier
; #define PG8_STAGE(bufoff, gbase, voff) do { _Pragma("unroll") for (int _i = 0; _i < 2; ++_i) \
;         __builtin_amdgcn_global_load_lds((const unsigned*)((const char*)(gbase) + (voff)[_i]), (PG8_LAS unsigned*)(lds + (bufoff) + ldsw + _i * 8192), 16, 0, 0); } while (0)
; #define PG8_LDA(dst, b, h) do { _Pragma("unroll") for (int m = 0; m < 4; ++m) _Pragma("unroll") for (int k = 0; k < 2; ++k) dst[m][k] = *(const PG8_LAS bf16x8*)(lds + PG8_SA(b, h) + aoff + m * 2048 + k * 1024); } while (0)
; #define PG8_LDB(dst, b, h) do { _Pragma("unroll") for (int n = 0; n < 2; ++n) _Pragma("unroll") for (int k = 0; k < 2; ++k) dst[n][k] = *(const PG8_LAS bf16x8*)(lds + PG8_SB(b, h) + boff + n * 2048 + k * 1024); } while (0)
; #define PG8_MMA(ai, bj, At, Bt) do { __builtin_amdgcn_s_setprio(1); _Pragma("unroll") for (int m = 0; m < 4; ++m) _Pragma("unroll") for (int n = 0; n < 2; ++n) _Pragma("unroll") for (int k = 0; k < 2; ++k) \
;         acc[ai][bj][m][n] = __builtin_amdgcn_mfma_f32_16x16x32_bf16(Bt[n][k], At[m][k], acc[ai][bj][m][n], 0, 0, 0); __builtin_amdgcn_s_setprio(0); } while (0)
; template <class Epi, class Sched, bool ALIGN_EPI = false, bool SP2 = false>
; __device__ __forceinline__ void gemm_phase(PG8_LAS unsigned char* lds, const Gemm g, const Sched& S, const Epi& E) {
;     ...
;         for (int t = 0; t < nt; t += 2) {
;             const bool last = (t == nt - 2);
;             const char* a1 = cA + (size_t)(t + 1) * kstep;
;             const char* a2 = last ? nA : cA + (size_t)(t + 2) * kstep; const char* b2 = last ? nB : cB + (size_t)(t + 2) * kstep;
;             const char* a3 = a2 + kstep; const char* b3 = b2 + kstep;
;             if (last && has_next) S.a_ready(nxt);
;             if constexpr (SP2) {
;             PG8_LDB(B0, 0, 0); PG8_LDB(B1, 0, 1); PG8_SCHED; PG8_LDA(At, 0, 0); PG8_STAGE(PG8_SA(1, 1), a1 + hstep, voffA);
;             PG8_WAIT_V(8); PG8_WAIT_L(0); PG8_BAR; PG8_MMA(0, 0, At, B0); PG8_MMA(0, 1, At, B1); PG8_BAR; PG8_SCHED;
;             PG8_LDA(At, 0, 1); PG8_STAGE(PG8_SB(0, 0), b2, voffB); PG8_STAGE(PG8_SB(0, 1), b2 + hstep, voffB); PG8_STAGE(PG8_SA(0, 0), a2, voffA);
;     ...
;             PG8_LDA(At, 1, 1); PG8_STAGE(PG8_SB(1, 0), b3, voffB); PG8_STAGE(PG8_SB(1, 1), b3 + hstep, voffB); PG8_STAGE(PG8_SA(1, 0), a3, voffA);
;             PG8_WAIT_V(8); PG8_WAIT_L(0); PG8_BAR; PG8_MMA(1, 0, At, B0); PG8_MMA(1, 1, At, B1); PG8_BAR; PG8_SCHED;
	s_add_i32 s56, s82, s34
	v_lshl_add_u64 v[200:201], v[200:201], 0, s[26:27]
	s_mov_b32 m0, s56
	ds_read_b128 v[188:191], v154 offset:49152
	ds_read_b128 v[192:195], v154 offset:50176
	ds_read_b128 v[196:199], v154 offset:51200
	ds_read_b128 v[206:209], v154 offset:52224
	ds_read_b128 v[210:213], v154 offset:53248
	ds_read_b128 v[214:217], v154 offset:54272
	ds_read_b128 v[218:221], v154 offset:55296
	ds_read_b128 v[222:225], v154 offset:56320
	global_load_lds_dwordx4 v[200:201], off
	s_add_i32 m0, s56, 0x2000
	s_add_u32 s54, s54, 0x40080
	v_lshl_add_u64 v[200:201], v[226:227], 0, s[26:27]
	s_addc_u32 s55, s55, 0
	s_add_i32 s56, s83, s34
	global_load_lds_dwordx4 v[200:201], off
	v_lshl_add_u64 v[200:201], s[54:55], 0, v[132:133]
	s_mov_b32 m0, s56
	s_nop 0
	global_load_lds_dwordx4 v[200:201], off
	v_lshl_add_u64 v[200:201], s[54:55], 0, v[128:129]
	s_add_i32 m0, s56, 0x2000
	s_nop 0
	global_load_lds_dwordx4 v[200:201], off
	s_waitcnt vmcnt(6)
	s_waitcnt lgkmcnt(0)
	s_barrier
	s_setprio 1
	s_waitcnt lgkmcnt(0)
	v_mfma_f32_16x16x32_bf16 v[60:63], v[146:149], v[188:191], v[60:63]
	v_mfma_f32_16x16x32_bf16 v[56:59], v[160:163], v[188:191], v[56:59]
	v_mfma_f32_16x16x32_bf16 v[44:47], v[146:149], v[196:199], v[44:47]
	v_mfma_f32_16x16x32_bf16 v[40:43], v[160:163], v[196:199], v[40:43]
	v_mfma_f32_16x16x32_bf16 v[28:31], v[146:149], v[210:213], v[28:31]
	v_mfma_f32_16x16x32_bf16 v[24:27], v[160:163], v[210:213], v[24:27]
	v_mfma_f32_16x16x32_bf16 v[12:15], v[146:149], v[218:221], v[12:15]
	v_mfma_f32_16x16x32_bf16 v[8:11], v[160:163], v[218:221], v[8:11]
	v_mfma_f32_16x16x32_bf16 v[60:63], v[156:159], v[192:195], v[60:63]
	v_mfma_f32_16x16x32_bf16 v[56:59], v[164:167], v[192:195], v[56:59]
	v_mfma_f32_16x16x32_bf16 v[44:47], v[156:159], v[206:209], v[44:47]
	v_mfma_f32_16x16x32_bf16 v[40:43], v[164:167], v[206:209], v[40:43]
	v_lshl_add_u64 v[200:201], v[228:229], 0, s[26:27]
	s_mov_b32 m0, s63
	s_nop 0
	global_load_lds_dwordx4 v[200:201], off
	v_mfma_f32_16x16x32_bf16 v[28:31], v[156:159], v[214:217], v[28:31]
	v_mfma_f32_16x16x32_bf16 v[24:27], v[164:167], v[214:217], v[24:27]
	v_mfma_f32_16x16x32_bf16 v[12:15], v[156:159], v[222:225], v[12:15]
	v_mfma_f32_16x16x32_bf16 v[8:11], v[164:167], v[222:225], v[8:11]
	s_setprio 0
	s_setprio 1
	v_mfma_f32_16x16x32_bf16 v[52:55], v[168:171], v[188:191], v[52:55]
	v_mfma_f32_16x16x32_bf16 v[48:51], v[180:183], v[188:191], v[48:51]
	v_mfma_f32_16x16x32_bf16 v[36:39], v[168:171], v[196:199], v[36:39]
	v_mfma_f32_16x16x32_bf16 v[32:35], v[180:183], v[196:199], v[32:35]
	v_mfma_f32_16x16x32_bf16 v[20:23], v[168:171], v[210:213], v[20:23]
	v_mfma_f32_16x16x32_bf16 v[16:19], v[180:183], v[210:213], v[16:19]
	v_mfma_f32_16x16x32_bf16 v[4:7], v[168:171], v[218:221], v[4:7]
	v_mfma_f32_16x16x32_bf16 v[0:3], v[180:183], v[218:221], v[0:3]
	v_mfma_f32_16x16x32_bf16 v[52:55], v[172:175], v[192:195], v[52:55]
	v_mfma_f32_16x16x32_bf16 v[48:51], v[184:187], v[192:195], v[48:51]
	v_mfma_f32_16x16x32_bf16 v[36:39], v[172:175], v[206:209], v[36:39]
	v_mfma_f32_16x16x32_bf16 v[32:35], v[184:187], v[206:209], v[32:35]
	v_lshl_add_u64 v[200:201], v[230:231], 0, s[26:27]
	s_mov_b32 m0, s64
	s_nop 0
	global_load_lds_dwordx4 v[200:201], off
	v_mfma_f32_16x16x32_bf16 v[20:23], v[172:175], v[214:217], v[20:23]
	v_mfma_f32_16x16x32_bf16 v[16:19], v[184:187], v[214:217], v[16:19]
	v_mfma_f32_16x16x32_bf16 v[4:7], v[172:175], v[222:225], v[4:7]
	v_mfma_f32_16x16x32_bf16 v[0:3], v[184:187], v[222:225], v[0:3]
	s_setprio 0
	s_barrier
	s_add_i32 s81, s81, 2
	s_add_u32 s52, s52, 0x100
	s_addc_u32 s53, s53, 0
	s_add_u32 s79, s79, 0x100
	s_addc_u32 s80, s80, 0
.LBB0_1681:
	ds_read_b128 v[146:149], v152
	ds_read_b128 v[156:159], v152 offset:1024
	ds_read_b128 v[160:163], v152 offset:2048
	ds_read_b128 v[164:167], v152 offset:3072
	ds_read_b128 v[168:171], v153
	ds_read_b128 v[172:175], v153 offset:1024
	ds_read_b128 v[180:183], v153 offset:2048
	ds_read_b128 v[184:187], v153 offset:3072
	s_add_u32 s54, s52, 0xfffc0080
	s_addc_u32 s55, s53, -1
	s_cmp_eq_u32 s81, 12
	s_cselect_b32 s57, s47, s55
	s_cselect_b32 s56, s77, s54
	s_cselect_b32 s55, s45, s80
	s_cselect_b32 s54, s78, s79
	v_lshl_add_u64 v[200:201], s[52:53], 0, v[136:137]
	s_add_i32 m0, s58, 0xc000
	ds_read_b128 v[188:191], v154
	ds_read_b128 v[192:195], v154 offset:1024
	ds_read_b128 v[196:199], v154 offset:2048
	ds_read_b128 v[206:209], v154 offset:3072
	ds_read_b128 v[210:213], v154 offset:4096
	ds_read_b128 v[214:217], v154 offset:5120
	ds_read_b128 v[218:221], v154 offset:6144
	ds_read_b128 v[222:225], v154 offset:7168
	global_load_lds_dwordx4 v[200:201], off
	v_lshl_add_u64 v[200:201], s[52:53], 0, v[138:139]
	s_add_i32 m0, s58, 0xe000
	s_nop 0
	global_load_lds_dwordx4 v[200:201], off
	s_waitcnt vmcnt(8)
	s_waitcnt lgkmcnt(0)
	s_barrier
; #define PG8_STAGE(bufoff, gbase, voff) do { _Pragma("unroll") for (int _i = 0; _i < 2; ++_i) \
;         __builtin_amdgcn_global_load_lds((const unsigned*)((const char*)(gbase) + (voff)[_i]), (PG8_LAS unsigned*)(lds + (bufoff) + ldsw + _i * 8192), 16, 0, 0); } while (0)
; #define PG8_LDA(dst, b, h) do { _Pragma("unroll") for (int m = 0; m < 4; ++m) _Pragma("unroll") for (int k = 0; k < 2; ++k) dst[m][k] = *(const PG8_LAS bf16x8*)(lds + PG8_SA(b, h) + aoff + m * 2048 + k * 1024); } while (0)
; #define PG8_LDB(dst, b, h) do { _Pragma("unroll") for (int n = 0; n < 2; ++n) _Pragma("unroll") for (int k = 0; k < 2; ++k) dst[n][k] = *(const PG8_LAS bf16x8*)(lds + PG8_SB(b, h) + boff + n * 2048 + k * 1024); } while (0)
; #define PG8_MMA(ai, bj, At, Bt) do { __builtin_amdgcn_s_setprio(1); _Pragma("unroll") for (int m = 0; m < 4; ++m) _Pragma("unroll") for (int n = 0; n < 2; ++n) _Pragma("unroll") for (int k = 0; k < 2; ++k) \
;         acc[ai][bj][m][n] = __builtin_amdgcn_mfma_f32_16x16x32_bf16(Bt[n][k], At[m][k], acc[ai][bj][m][n], 0, 0, 0); __builtin_amdgcn_s_setprio(0); } while (0)
; #define PG8_WAIT_V(n) asm volatile("s_waitcnt vmcnt(" #n ")" ::: "memory")
; #define PG8_WAIT_L(n) asm volatile("s_waitcnt lgkmcnt(" #n ")" ::: "memory")
; #define PG8_BAR __builtin_amdgcn_s_barrier()
; #define PG8_SCHED __builtin_amdgcn_sched_barrier(0)
; template <class Epi, class Sched, bool ALIGN_EPI = false, bool SP2 = false>
; __device__ __forceinline__ void gemm_phase(PG8_LAS unsigned char* lds, const Gemm g, const Sched& S, const Epi& E) {
;     ...
;             PG8_LDB(B0, 0, 0); PG8_LDB(B1, 0, 1); PG8_SCHED; PG8_LDA(At, 0, 0); PG8_STAGE(PG8_SA(1, 1), a1 + hstep, voffA);
;             PG8_WAIT_V(8); PG8_WAIT_L(0); PG8_BAR; PG8_MMA(0, 0, At, B0); PG8_MMA(0, 1, At, B1); PG8_BAR; PG8_SCHED;
;             PG8_LDA(At, 0, 1); PG8_STAGE(PG8_SB(0, 0), b2, voffB); PG8_STAGE(PG8_SB(0, 1), b2 + hstep, voffB); PG8_STAGE(PG8_SA(0, 0), a2, voffA);
;             PG8_WAIT_V(8); PG8_WAIT_L(0); PG8_BAR; PG8_MMA(1, 0, At, B0); PG8_MMA(1, 1, At, B1); PG8_BAR; PG8_SCHED;
	s_setprio 1
	s_waitcnt lgkmcnt(0)
	v_mfma_f32_16x16x32_bf16 v[124:127], v[146:149], v[188:191], v[124:127]
	v_mfma_f32_16x16x32_bf16 v[120:123], v[160:163], v[188:191], v[120:123]
	v_mfma_f32_16x16x32_bf16 v[108:111], v[146:149], v[196:199], v[108:111]
	v_mfma_f32_16x16x32_bf16 v[104:107], v[160:163], v[196:199], v[104:107]
	v_mfma_f32_16x16x32_bf16 v[92:95], v[146:149], v[210:213], v[92:95]
	v_mfma_f32_16x16x32_bf16 v[88:91], v[160:163], v[210:213], v[88:91]
	v_mfma_f32_16x16x32_bf16 v[76:79], v[146:149], v[218:221], v[76:79]
	v_mfma_f32_16x16x32_bf16 v[72:75], v[160:163], v[218:221], v[72:75]
	v_mfma_f32_16x16x32_bf16 v[124:127], v[156:159], v[192:195], v[124:127]
	v_mfma_f32_16x16x32_bf16 v[120:123], v[164:167], v[192:195], v[120:123]
	v_mfma_f32_16x16x32_bf16 v[108:111], v[156:159], v[206:209], v[108:111]
	v_mfma_f32_16x16x32_bf16 v[104:107], v[164:167], v[206:209], v[104:107]
	v_mfma_f32_16x16x32_bf16 v[92:95], v[156:159], v[214:217], v[92:95]
	v_mfma_f32_16x16x32_bf16 v[88:91], v[164:167], v[214:217], v[88:91]
	v_mfma_f32_16x16x32_bf16 v[76:79], v[156:159], v[222:225], v[76:79]
	v_mfma_f32_16x16x32_bf16 v[72:75], v[164:167], v[222:225], v[72:75]
	s_setprio 0
	s_setprio 1
	v_mfma_f32_16x16x32_bf16 v[116:119], v[168:171], v[188:191], v[116:119]
	v_mfma_f32_16x16x32_bf16 v[112:115], v[180:183], v[188:191], v[112:115]
	v_mfma_f32_16x16x32_bf16 v[100:103], v[168:171], v[196:199], v[100:103]
	v_mfma_f32_16x16x32_bf16 v[96:99], v[180:183], v[196:199], v[96:99]
	v_mfma_f32_16x16x32_bf16 v[84:87], v[168:171], v[210:213], v[84:87]
	v_mfma_f32_16x16x32_bf16 v[80:83], v[180:183], v[210:213], v[80:83]
	v_mfma_f32_16x16x32_bf16 v[68:71], v[168:171], v[218:221], v[68:71]
	v_mfma_f32_16x16x32_bf16 v[64:67], v[180:183], v[218:221], v[64:67]
	v_mfma_f32_16x16x32_bf16 v[116:119], v[172:175], v[192:195], v[116:119]
	v_mfma_f32_16x16x32_bf16 v[112:115], v[184:187], v[192:195], v[112:115]
	v_mfma_f32_16x16x32_bf16 v[100:103], v[172:175], v[206:209], v[100:103]
	v_mfma_f32_16x16x32_bf16 v[96:99], v[184:187], v[206:209], v[96:99]
	v_mfma_f32_16x16x32_bf16 v[84:87], v[172:175], v[214:217], v[84:87]
	v_mfma_f32_16x16x32_bf16 v[80:83], v[184:187], v[214:217], v[80:83]
	v_mfma_f32_16x16x32_bf16 v[68:71], v[172:175], v[222:225], v[68:71]
	v_mfma_f32_16x16x32_bf16 v[64:67], v[184:187], v[222:225], v[64:67]
	s_setprio 0
	s_barrier
	s_add_i32 s82, s65, s34
	v_lshl_add_u64 v[200:201], s[54:55], 0, v[132:133]
	s_mov_b32 m0, s82
	ds_read_b128 v[188:191], v154 offset:16384
	ds_read_b128 v[192:195], v154 offset:17408
	ds_read_b128 v[196:199], v154 offset:18432
	ds_read_b128 v[206:209], v154 offset:19456
	ds_read_b128 v[210:213], v154 offset:20480
	ds_read_b128 v[214:217], v154 offset:21504
	ds_read_b128 v[218:221], v154 offset:22528
	ds_read_b128 v[222:225], v154 offset:23552
	global_load_lds_dwordx4 v[200:201], off
	s_add_i32 m0, s82, 0x2000
	s_add_u32 s82, s54, 0x40000
	v_lshl_add_u64 v[226:227], s[54:55], 0, v[128:129]
	s_addc_u32 s83, s55, 0
	s_add_i32 s84, s66, s34
	global_load_lds_dwordx4 v[226:227], off
	v_lshl_add_u64 v[228:229], s[82:83], 0, v[132:133]
	s_mov_b32 m0, s84
	global_load_lds_dwordx4 v[228:229], off
	v_lshl_add_u64 v[228:229], s[82:83], 0, v[128:129]
	s_add_i32 m0, s84, 0x2000
	s_nop 0
	global_load_lds_dwordx4 v[228:229], off
	s_waitcnt vmcnt(6)
	s_waitcnt lgkmcnt(0)
	s_barrier
	s_setprio 1
	s_waitcnt lgkmcnt(0)
	v_mfma_f32_16x16x32_bf16 v[60:63], v[146:149], v[188:191], v[60:63]
	v_mfma_f32_16x16x32_bf16 v[56:59], v[160:163], v[188:191], v[56:59]
	v_mfma_f32_16x16x32_bf16 v[44:47], v[146:149], v[196:199], v[44:47]
	v_mfma_f32_16x16x32_bf16 v[40:43], v[160:163], v[196:199], v[40:43]
	v_mfma_f32_16x16x32_bf16 v[28:31], v[146:149], v[210:213], v[28:31]
	v_mfma_f32_16x16x32_bf16 v[24:27], v[160:163], v[210:213], v[24:27]
	v_mfma_f32_16x16x32_bf16 v[12:15], v[146:149], v[218:221], v[12:15]
	v_mfma_f32_16x16x32_bf16 v[8:11], v[160:163], v[218:221], v[8:11]
	v_mfma_f32_16x16x32_bf16 v[60:63], v[156:159], v[192:195], v[60:63]
	v_mfma_f32_16x16x32_bf16 v[56:59], v[164:167], v[192:195], v[56:59]
	v_mfma_f32_16x16x32_bf16 v[44:47], v[156:159], v[206:209], v[44:47]
	v_mfma_f32_16x16x32_bf16 v[40:43], v[164:167], v[206:209], v[40:43]
	v_lshl_add_u64 v[228:229], s[56:57], 0, v[134:135]
	s_mov_b32 m0, s58
	s_nop 0
	global_load_lds_dwordx4 v[228:229], off
	v_mfma_f32_16x16x32_bf16 v[28:31], v[156:159], v[214:217], v[28:31]
	v_mfma_f32_16x16x32_bf16 v[24:27], v[164:167], v[214:217], v[24:27]
	v_mfma_f32_16x16x32_bf16 v[12:15], v[156:159], v[222:225], v[12:15]
	v_mfma_f32_16x16x32_bf16 v[8:11], v[164:167], v[222:225], v[8:11]
	s_setprio 0
	s_setprio 1
	v_mfma_f32_16x16x32_bf16 v[52:55], v[168:171], v[188:191], v[52:55]
	v_mfma_f32_16x16x32_bf16 v[48:51], v[180:183], v[188:191], v[48:51]
	v_mfma_f32_16x16x32_bf16 v[36:39], v[168:171], v[196:199], v[36:39]
	v_mfma_f32_16x16x32_bf16 v[32:35], v[180:183], v[196:199], v[32:35]
	v_mfma_f32_16x16x32_bf16 v[20:23], v[168:171], v[210:213], v[20:23]
	v_mfma_f32_16x16x32_bf16 v[16:19], v[180:183], v[210:213], v[16:19]
	v_mfma_f32_16x16x32_bf16 v[4:7], v[168:171], v[218:221], v[4:7]
	v_mfma_f32_16x16x32_bf16 v[0:3], v[180:183], v[218:221], v[0:3]
	v_mfma_f32_16x16x32_bf16 v[52:55], v[172:175], v[192:195], v[52:55]
	v_mfma_f32_16x16x32_bf16 v[48:51], v[184:187], v[192:195], v[48:51]
	v_mfma_f32_16x16x32_bf16 v[36:39], v[172:175], v[206:209], v[36:39]
	v_mfma_f32_16x16x32_bf16 v[32:35], v[184:187], v[206:209], v[32:35]
	v_lshl_add_u64 v[230:231], s[56:57], 0, v[130:131]
	s_mov_b32 m0, s59
	s_nop 0
	global_load_lds_dwordx4 v[230:231], off
	v_mfma_f32_16x16x32_bf16 v[20:23], v[172:175], v[214:217], v[20:23]
	v_mfma_f32_16x16x32_bf16 v[16:19], v[184:187], v[214:217], v[16:19]
	v_mfma_f32_16x16x32_bf16 v[4:7], v[172:175], v[222:225], v[4:7]
	v_mfma_f32_16x16x32_bf16 v[0:3], v[184:187], v[222:225], v[0:3]
	s_setprio 0
	s_barrier
; #define PG8_STAGE(bufoff, gbase, voff) do { _Pragma("unroll") for (int _i = 0; _i < 2; ++_i) \
;         __builtin_amdgcn_global_load_lds((const unsigned*)((const char*)(gbase) + (voff)[_i]), (PG8_LAS unsigned*)(lds + (bufoff) + ldsw + _i * 8192), 16, 0, 0); } while (0)
; #define PG8_LDA(dst, b, h) do { _Pragma("unroll") for (int m = 0; m < 4; ++m) _Pragma("unroll") for (int k = 0; k < 2; ++k) dst[m][k] = *(const PG8_LAS bf16x8*)(lds + PG8_SA(b, h) + aoff + m * 2048 + k * 1024); } while (0)
; #define PG8_LDB(dst, b, h) do { _Pragma("unroll") for (int n = 0; n < 2; ++n) _Pragma("unroll") for (int k = 0; k < 2; ++k) dst[n][k] = *(const PG8_LAS bf16x8*)(lds + PG8_SB(b, h) + boff + n * 2048 + k * 1024); } while (0)
; #define PG8_MMA(ai, bj, At, Bt) do { __builtin_amdgcn_s_setprio(1); _Pragma("unroll") for (int m = 0; m < 4; ++m) _Pragma("unroll") for (int n = 0; n < 2; ++n) _Pragma("unroll") for (int k = 0; k < 2; ++k) \
;         acc[ai][bj][m][n] = __builtin_amdgcn_mfma_f32_16x16x32_bf16(Bt[n][k], At[m][k], acc[ai][bj][m][n], 0, 0, 0); __builtin_amdgcn_s_setprio(0); } while (0)
; #define PG8_WAIT_V(n) asm volatile("s_waitcnt vmcnt(" #n ")" ::: "memory")
; #define PG8_WAIT_L(n) asm volatile("s_waitcnt lgkmcnt(" #n ")" ::: "memory")
; #define PG8_BAR __builtin_amdgcn_s_barrier()
; #define PG8_SCHED __builtin_amdgcn_sched_barrier(0)
; template <class Epi, class Sched, bool ALIGN_EPI = false, bool SP2 = false>
; __device__ __forceinline__ void gemm_phase(PG8_LAS unsigned char* lds, const Gemm g, const Sched& S, const Epi& E) {
;     ...
;             PG8_LDB(B0, 1, 0); PG8_LDB(B1, 1, 1); PG8_SCHED; PG8_LDA(At, 1, 0); PG8_STAGE(PG8_SA(0, 1), a2 + hstep, voffA);
;             PG8_WAIT_V(8); PG8_WAIT_L(0); PG8_BAR; PG8_MMA(0, 0, At, B0); PG8_MMA(0, 1, At, B1); PG8_BAR; PG8_SCHED;
	s_add_i32 s82, 0, 0x18000
	s_add_i32 s83, 0, 0x1c000
	v_add_u32_e32 v164, s82, v150
	v_add_u32_e32 v179, s83, v150
	ds_read_b128 v[146:149], v164
	ds_read_b128 v[156:159], v164 offset:1024
	ds_read_b128 v[160:163], v164 offset:2048
	ds_read_b128 v[164:167], v164 offset:3072
	ds_read_b128 v[168:171], v179
	ds_read_b128 v[172:175], v179 offset:1024
	ds_read_b128 v[180:183], v179 offset:2048
	ds_read_b128 v[184:187], v179 offset:3072
	s_add_u32 s56, s56, 0x40000
	s_addc_u32 s57, s57, 0
	s_mov_b32 m0, s60
	v_lshl_add_u64 v[232:233], s[56:57], 0, v[134:135]
	ds_read_b128 v[188:191], v154 offset:32768
	ds_read_b128 v[192:195], v154 offset:33792
	ds_read_b128 v[196:199], v154 offset:34816
	ds_read_b128 v[206:209], v154 offset:35840
	ds_read_b128 v[210:213], v154 offset:36864
	ds_read_b128 v[214:217], v154 offset:37888
	ds_read_b128 v[218:221], v154 offset:38912
	ds_read_b128 v[222:225], v154 offset:39936
	global_load_lds_dwordx4 v[232:233], off
	v_lshl_add_u64 v[232:233], s[56:57], 0, v[130:131]
	s_mov_b32 m0, s61
	s_nop 0
	global_load_lds_dwordx4 v[232:233], off
	s_waitcnt vmcnt(8)
	s_waitcnt lgkmcnt(0)
	s_barrier
	s_setprio 1
	s_waitcnt lgkmcnt(0)
	v_mfma_f32_16x16x32_bf16 v[124:127], v[146:149], v[188:191], v[124:127]
	v_mfma_f32_16x16x32_bf16 v[120:123], v[160:163], v[188:191], v[120:123]
	v_mfma_f32_16x16x32_bf16 v[108:111], v[146:149], v[196:199], v[108:111]
	v_mfma_f32_16x16x32_bf16 v[104:107], v[160:163], v[196:199], v[104:107]
	v_mfma_f32_16x16x32_bf16 v[92:95], v[146:149], v[210:213], v[92:95]
	v_mfma_f32_16x16x32_bf16 v[88:91], v[160:163], v[210:213], v[88:91]
	v_mfma_f32_16x16x32_bf16 v[76:79], v[146:149], v[218:221], v[76:79]
	v_mfma_f32_16x16x32_bf16 v[72:75], v[160:163], v[218:221], v[72:75]
	v_mfma_f32_16x16x32_bf16 v[124:127], v[156:159], v[192:195], v[124:127]
	v_mfma_f32_16x16x32_bf16 v[120:123], v[164:167], v[192:195], v[120:123]
	v_mfma_f32_16x16x32_bf16 v[108:111], v[156:159], v[206:209], v[108:111]
	v_mfma_f32_16x16x32_bf16 v[104:107], v[164:167], v[206:209], v[104:107]
	v_mfma_f32_16x16x32_bf16 v[92:95], v[156:159], v[214:217], v[92:95]
	v_mfma_f32_16x16x32_bf16 v[88:91], v[164:167], v[214:217], v[88:91]
	v_mfma_f32_16x16x32_bf16 v[76:79], v[156:159], v[222:225], v[76:79]
	v_mfma_f32_16x16x32_bf16 v[72:75], v[164:167], v[222:225], v[72:75]
	s_setprio 0
	s_setprio 1
	v_mfma_f32_16x16x32_bf16 v[116:119], v[168:171], v[188:191], v[116:119]
	v_mfma_f32_16x16x32_bf16 v[112:115], v[180:183], v[188:191], v[112:115]
	v_mfma_f32_16x16x32_bf16 v[100:103], v[168:171], v[196:199], v[100:103]
	v_mfma_f32_16x16x32_bf16 v[96:99], v[180:183], v[196:199], v[96:99]
	v_mfma_f32_16x16x32_bf16 v[84:87], v[168:171], v[210:213], v[84:87]
	v_mfma_f32_16x16x32_bf16 v[80:83], v[180:183], v[210:213], v[80:83]
	v_mfma_f32_16x16x32_bf16 v[68:71], v[168:171], v[218:221], v[68:71]
	v_mfma_f32_16x16x32_bf16 v[64:67], v[180:183], v[218:221], v[64:67]
	v_mfma_f32_16x16x32_bf16 v[116:119], v[172:175], v[192:195], v[116:119]
	v_mfma_f32_16x16x32_bf16 v[112:115], v[184:187], v[192:195], v[112:115]
	v_mfma_f32_16x16x32_bf16 v[100:103], v[172:175], v[206:209], v[100:103]
	v_mfma_f32_16x16x32_bf16 v[96:99], v[184:187], v[206:209], v[96:99]
	v_mfma_f32_16x16x32_bf16 v[84:87], v[172:175], v[214:217], v[84:87]
	v_mfma_f32_16x16x32_bf16 v[80:83], v[184:187], v[214:217], v[80:83]
	v_mfma_f32_16x16x32_bf16 v[68:71], v[172:175], v[222:225], v[68:71]
	v_mfma_f32_16x16x32_bf16 v[64:67], v[184:187], v[222:225], v[64:67]
	s_setprio 0
	s_barrier
; #define PG8_STAGE(bufoff, gbase, voff) do { _Pragma("unroll") for (int _i = 0; _i < 2; ++_i) \
;         __builtin_amdgcn_global_load_lds((const unsigned*)((const char*)(gbase) + (voff)[_i]), (PG8_LAS unsigned*)(lds + (bufoff) + ldsw + _i * 8192), 16, 0, 0); } while (0)
; #define PG8_LDA(dst, b, h) do { _Pragma("unroll") for (int m = 0; m < 4; ++m) _Pragma("unroll") for (int k = 0; k < 2; ++k) dst[m][k] = *(const PG8_LAS bf16x8*)(lds + PG8_SA(b, h) + aoff + m * 2048 + k * 1024); } while (0)
; #define PG8_MMA(ai, bj, At, Bt) do { __builtin_amdgcn_s_setprio(1); _Pragma("unroll") for (int m = 0; m < 4; ++m) _Pragma("unroll") for (int n = 0; n < 2; ++n) _Pragma("unroll") for (int k = 0; k < 2; ++k) \
;         acc[ai][bj][m][n] = __builtin_amdgcn_mfma_f32_16x16x32_bf16(Bt[n][k], At[m][k], acc[ai][bj][m][n], 0, 0, 0); __builtin_amdgcn_s_setprio(0); } while (0)
; #define PG8_WAIT_V(n) asm volatile("s_waitcnt vmcnt(" #n ")" ::: "memory")
; #define PG8_WAIT_L(n) asm volatile("s_waitcnt lgkmcnt(" #n ")" ::: "memory")
; #define PG8_BAR __builtin_amdgcn_s_barrier()
; #define PG8_SCHED __builtin_amdgcn_sched_barrier(0)
; template <class Epi, class Sched, bool ALIGN_EPI = false, bool SP2 = false>
; __device__ __forceinline__ void gemm_phase(PG8_LAS unsigned char* lds, const Gemm g, const Sched& S, const Epi& E) {
;     ...
;             PG8_LDA(At, 1, 1); PG8_STAGE(PG8_SB(1, 0), b3, voffB); PG8_STAGE(PG8_SB(1, 1), b3 + hstep, voffB); PG8_STAGE(PG8_SA(1, 0), a3, voffA);
;             PG8_WAIT_V(8); PG8_WAIT_L(0); PG8_BAR; PG8_MMA(1, 0, At, B0); PG8_MMA(1, 1, At, B1); PG8_BAR; PG8_SCHED;
	s_add_i32 s56, s82, s34
	v_lshl_add_u64 v[200:201], v[200:201], 0, s[26:27]
	s_mov_b32 m0, s56
	ds_read_b128 v[188:191], v154 offset:49152
	ds_read_b128 v[192:195], v154 offset:50176
	ds_read_b128 v[196:199], v154 offset:51200
	ds_read_b128 v[206:209], v154 offset:52224
	ds_read_b128 v[210:213], v154 offset:53248
	ds_read_b128 v[214:217], v154 offset:54272
	ds_read_b128 v[218:221], v154 offset:55296
	ds_read_b128 v[222:225], v154 offset:56320
	global_load_lds_dwordx4 v[200:201], off
	s_add_i32 m0, s56, 0x2000
	s_add_u32 s54, s54, 0x40080
	v_lshl_add_u64 v[200:201], v[226:227], 0, s[26:27]
	s_addc_u32 s55, s55, 0
	s_add_i32 s56, s83, s34
	global_load_lds_dwordx4 v[200:201], off
	v_lshl_add_u64 v[200:201], s[54:55], 0, v[132:133]
	s_mov_b32 m0, s56
	s_nop 0
	global_load_lds_dwordx4 v[200:201], off
	v_lshl_add_u64 v[200:201], s[54:55], 0, v[128:129]
	s_add_i32 m0, s56, 0x2000
	s_nop 0
	global_load_lds_dwordx4 v[200:201], off
	s_waitcnt vmcnt(6)
	s_waitcnt lgkmcnt(0)
	s_barrier
	s_setprio 1
	s_waitcnt lgkmcnt(0)
	v_mfma_f32_16x16x32_bf16 v[60:63], v[146:149], v[188:191], v[60:63]
	v_mfma_f32_16x16x32_bf16 v[56:59], v[160:163], v[188:191], v[56:59]
	v_mfma_f32_16x16x32_bf16 v[44:47], v[146:149], v[196:199], v[44:47]
	v_mfma_f32_16x16x32_bf16 v[40:43], v[160:163], v[196:199], v[40:43]
	v_mfma_f32_16x16x32_bf16 v[28:31], v[146:149], v[210:213], v[28:31]
	v_mfma_f32_16x16x32_bf16 v[24:27], v[160:163], v[210:213], v[24:27]
	v_mfma_f32_16x16x32_bf16 v[12:15], v[146:149], v[218:221], v[12:15]
	v_mfma_f32_16x16x32_bf16 v[8:11], v[160:163], v[218:221], v[8:11]
	v_mfma_f32_16x16x32_bf16 v[60:63], v[156:159], v[192:195], v[60:63]
	v_mfma_f32_16x16x32_bf16 v[56:59], v[164:167], v[192:195], v[56:59]
	v_mfma_f32_16x16x32_bf16 v[44:47], v[156:159], v[206:209], v[44:47]
	v_mfma_f32_16x16x32_bf16 v[40:43], v[164:167], v[206:209], v[40:43]
	v_lshl_add_u64 v[200:201], v[228:229], 0, s[26:27]
	s_mov_b32 m0, s63
	s_nop 0
	global_load_lds_dwordx4 v[200:201], off
	v_mfma_f32_16x16x32_bf16 v[28:31], v[156:159], v[214:217], v[28:31]
	v_mfma_f32_16x16x32_bf16 v[24:27], v[164:167], v[214:217], v[24:27]
	v_mfma_f32_16x16x32_bf16 v[12:15], v[156:159], v[222:225], v[12:15]
	v_mfma_f32_16x16x32_bf16 v[8:11], v[164:167], v[222:225], v[8:11]
	s_setprio 0
	s_setprio 1
	v_mfma_f32_16x16x32_bf16 v[52:55], v[168:171], v[188:191], v[52:55]
	v_mfma_f32_16x16x32_bf16 v[48:51], v[180:183], v[188:191], v[48:51]
	v_mfma_f32_16x16x32_bf16 v[36:39], v[168:171], v[196:199], v[36:39]
	v_mfma_f32_16x16x32_bf16 v[32:35], v[180:183], v[196:199], v[32:35]
	v_mfma_f32_16x16x32_bf16 v[20:23], v[168:171], v[210:213], v[20:23]
	v_mfma_f32_16x16x32_bf16 v[16:19], v[180:183], v[210:213], v[16:19]
	v_mfma_f32_16x16x32_bf16 v[4:7], v[168:171], v[218:221], v[4:7]
	v_mfma_f32_16x16x32_bf16 v[0:3], v[180:183], v[218:221], v[0:3]
	v_mfma_f32_16x16x32_bf16 v[52:55], v[172:175], v[192:195], v[52:55]
	v_mfma_f32_16x16x32_bf16 v[48:51], v[184:187], v[192:195], v[48:51]
	v_mfma_f32_16x16x32_bf16 v[36:39], v[172:175], v[206:209], v[36:39]
	v_mfma_f32_16x16x32_bf16 v[32:35], v[184:187], v[206:209], v[32:35]
	v_lshl_add_u64 v[200:201], v[230:231], 0, s[26:27]
	s_mov_b32 m0, s64
	s_nop 0
	global_load_lds_dwordx4 v[200:201], off
	v_mfma_f32_16x16x32_bf16 v[20:23], v[172:175], v[214:217], v[20:23]
	v_mfma_f32_16x16x32_bf16 v[16:19], v[184:187], v[214:217], v[16:19]
	v_mfma_f32_16x16x32_bf16 v[4:7], v[172:175], v[222:225], v[4:7]
	v_mfma_f32_16x16x32_bf16 v[0:3], v[184:187], v[222:225], v[0:3]
	s_setprio 0
	s_barrier
	s_add_i32 s81, s81, 2
	s_add_u32 s52, s52, 0x100
	s_addc_u32 s53, s53, 0
	s_add_u32 s79, s79, 0x100
	s_addc_u32 s80, s80, 0
	s_cmp_gt_u32 s81, 13
	s_cbranch_scc0 .LBB0_1681
	s_and_b64 vcc, exec, s[28:29]
	s_cbranch_vccz .LBB0_1684
	s_barrier

; #define PG8_STAGE(bufoff, gbase, voff) do { _Pragma("unroll") for (int _i = 0; _i < 2; ++_i) \
;         __builtin_amdgcn_global_load_lds((const unsigned*)((const char*)(gbase) + (voff)[_i]), (PG8_LAS unsigned*)(lds + (bufoff) + ldsw + _i * 8192), 16, 0, 0); } while (0)
; #define PG8_LDA(dst, b, h) do { _Pragma("unroll") for (int m = 0; m < 4; ++m) _Pragma("unroll") for (int k = 0; k < 2; ++k) dst[m][k] = *(const PG8_LAS bf16x8*)(lds + PG8_SA(b, h) + aoff + m * 2048 + k * 1024); } while (0)
; #define PG8_LDB(dst, b, h) do { _Pragma("unroll") for (int n = 0; n < 2; ++n) _Pragma("unroll") for (int k = 0; k < 2; ++k) dst[n][k] = *(const PG8_LAS bf16x8*)(lds + PG8_SB(b, h) + boff + n * 2048 + k * 1024); } while (0)
; #define PG8_MMA(ai, bj, At, Bt) do { __builtin_amdgcn_s_setprio(1); _Pragma("unroll") for (int m = 0; m < 4; ++m) _Pragma("unroll") for (int n = 0; n < 2; ++n) _Pragma("unroll") for (int k = 0; k < 2; ++k) \
;         acc[ai][bj][m][n] = __builtin_amdgcn_mfma_f32_16x16x32_bf16(Bt[n][k], At[m][k], acc[ai][bj][m][n], 0, 0, 0); __builtin_amdgcn_s_setprio(0); } while (0)
; #define PG8_BAR __builtin_amdgcn_s_barrier()
; template <class Epi, class Sched, bool ALIGN_EPI = false, bool SP2 = false>
; __device__ __forceinline__ void gemm_phase(PG8_LAS unsigned char* lds, const Gemm g, const Sched& S, const Epi& E) {
;     ...
;         const bool has_next = S.next(ui + 1, nxt);
;         const char* nA = has_next ? (const char*)g.A + (size_t)nxt.pm * tstep : cA; const char* nB = has_next ? (const char*)g.Bt + (size_t)nxt.pn * tstep : cB;
;         for (int t = 0; t < nt; t += 2) {
;             const bool last = (t == nt - 2);
;             const char* a1 = cA + (size_t)(t + 1) * kstep;
;             const char* a2 = last ? nA : cA + (size_t)(t + 2) * kstep; const char* b2 = last ? nB : cB + (size_t)(t + 2) * kstep;
;             const char* a3 = a2 + kstep; const char* b3 = b2 + kstep;
;             if (last && has_next) S.a_ready(nxt);
;             if constexpr (SP2) {
;             PG8_LDB(B0, 0, 0); PG8_LDB(B1, 0, 1); PG8_SCHED; PG8_LDA(At, 0, 0); PG8_STAGE(PG8_SA(1, 1), a1 + hstep, voffA);
;             PG8_WAIT_V(8); PG8_WAIT_L(0); PG8_BAR; PG8_MMA(0, 0, At, B0); PG8_MMA(0, 1, At, B1); PG8_BAR; PG8_SCHED;
;             PG8_LDA(At, 0, 1); PG8_STAGE(PG8_SB(0, 0), b2, voffB); PG8_STAGE(PG8_SB(0, 1), b2 + hstep, voffB); PG8_STAGE(PG8_SA(0, 0), a2, voffA);
.LBB0_1815:
	s_ashr_i32 s29, s28, 31
	s_lshl_b64 s[36:37], s[28:29], 18
	s_add_u32 s36, s92, s36
	s_addc_u32 s37, s93, s37
	s_and_b64 s[38:39], s[6:7], exec
	s_cselect_b32 s29, s37, s45
	s_cselect_b32 s41, s36, s44
	s_ashr_i32 s27, s26, 31
	s_lshl_b64 s[38:39], s[26:27], 18
	s_add_u32 s38, s3, s38
	s_addc_u32 s39, s14, s39
	s_and_b64 s[48:49], s[6:7], exec
	s_cselect_b32 s27, s39, s47
	s_cselect_b32 s58, s38, s46
	s_add_u32 s44, s44, 0x20080
	s_addc_u32 s45, s45, 0
	s_add_u32 s59, s46, 0x100
	s_addc_u32 s60, s47, 0
	s_mov_b32 s61, -2
	s_waitcnt lgkmcnt(0)
	ds_read_b128 v[144:147], v151
	ds_read_b128 v[156:159], v151 offset:1024
	ds_read_b128 v[160:163], v151 offset:2048
	ds_read_b128 v[164:167], v151 offset:3072
	ds_read_b128 v[168:171], v152
	ds_read_b128 v[172:175], v152 offset:1024
	ds_read_b128 v[176:179], v152 offset:2048
	ds_read_b128 v[180:183], v152 offset:3072
	s_add_u32 s46, s44, 0xfffe0080
	s_addc_u32 s47, s45, -1
	s_cmp_eq_u32 s61, 4
	s_cselect_b32 s49, s29, s47
	s_cselect_b32 s48, s41, s46
	s_cselect_b32 s47, s27, s60
	s_cselect_b32 s46, s58, s59
	v_lshl_add_u64 v[218:219], s[44:45], 0, v[136:137]
	s_add_i32 m0, s33, 0xc000
	ds_read_b128 v[184:187], v153
	ds_read_b128 v[188:191], v153 offset:1024
	ds_read_b128 v[192:195], v153 offset:2048
	ds_read_b128 v[196:199], v153 offset:3072
	ds_read_b128 v[200:203], v153 offset:4096
	ds_read_b128 v[206:209], v153 offset:5120
	ds_read_b128 v[210:213], v153 offset:6144
	ds_read_b128 v[214:217], v153 offset:7168
	global_load_lds_dwordx4 v[218:219], off
	v_lshl_add_u64 v[218:219], s[44:45], 0, v[138:139]
	s_add_i32 m0, s33, 0xe000
	s_nop 0
	global_load_lds_dwordx4 v[218:219], off
	s_waitcnt vmcnt(8)
	s_waitcnt lgkmcnt(0)
	s_barrier
	s_setprio 1
	s_waitcnt lgkmcnt(0)
	v_mfma_f32_16x16x32_bf16 v[124:127], v[144:147], v[184:187], 0
	v_mfma_f32_16x16x32_bf16 v[120:123], v[160:163], v[184:187], 0
	v_mfma_f32_16x16x32_bf16 v[108:111], v[144:147], v[192:195], 0
	v_mfma_f32_16x16x32_bf16 v[104:107], v[160:163], v[192:195], 0
	v_mfma_f32_16x16x32_bf16 v[92:95], v[144:147], v[200:203], 0
	v_mfma_f32_16x16x32_bf16 v[88:91], v[160:163], v[200:203], 0
	v_mfma_f32_16x16x32_bf16 v[76:79], v[144:147], v[210:213], 0
	v_mfma_f32_16x16x32_bf16 v[72:75], v[160:163], v[210:213], 0
	v_mfma_f32_16x16x32_bf16 v[124:127], v[156:159], v[188:191], v[124:127]
	v_mfma_f32_16x16x32_bf16 v[120:123], v[164:167], v[188:191], v[120:123]
	v_mfma_f32_16x16x32_bf16 v[108:111], v[156:159], v[196:199], v[108:111]
	v_mfma_f32_16x16x32_bf16 v[104:107], v[164:167], v[196:199], v[104:107]
	v_mfma_f32_16x16x32_bf16 v[92:95], v[156:159], v[206:209], v[92:95]
	v_mfma_f32_16x16x32_bf16 v[88:91], v[164:167], v[206:209], v[88:91]
	v_mfma_f32_16x16x32_bf16 v[76:79], v[156:159], v[214:217], v[76:79]
	v_mfma_f32_16x16x32_bf16 v[72:75], v[164:167], v[214:217], v[72:75]
	s_setprio 0
	s_setprio 1
	v_mfma_f32_16x16x32_bf16 v[116:119], v[168:171], v[184:187], 0
	v_mfma_f32_16x16x32_bf16 v[112:115], v[176:179], v[184:187], 0
	v_mfma_f32_16x16x32_bf16 v[100:103], v[168:171], v[192:195], 0
	v_mfma_f32_16x16x32_bf16 v[96:99], v[176:179], v[192:195], 0
	v_mfma_f32_16x16x32_bf16 v[84:87], v[168:171], v[200:203], 0
	v_mfma_f32_16x16x32_bf16 v[80:83], v[176:179], v[200:203], 0
	v_mfma_f32_16x16x32_bf16 v[68:71], v[168:171], v[210:213], 0
	v_mfma_f32_16x16x32_bf16 v[64:67], v[176:179], v[210:213], 0
	v_mfma_f32_16x16x32_bf16 v[116:119], v[172:175], v[188:191], v[116:119]
	v_mfma_f32_16x16x32_bf16 v[112:115], v[180:183], v[188:191], v[112:115]
	v_mfma_f32_16x16x32_bf16 v[100:103], v[172:175], v[196:199], v[100:103]
	v_mfma_f32_16x16x32_bf16 v[96:99], v[180:183], v[196:199], v[96:99]
	v_mfma_f32_16x16x32_bf16 v[84:87], v[172:175], v[206:209], v[84:87]
	v_mfma_f32_16x16x32_bf16 v[80:83], v[180:183], v[206:209], v[80:83]
	v_mfma_f32_16x16x32_bf16 v[68:71], v[172:175], v[214:217], v[68:71]
	v_mfma_f32_16x16x32_bf16 v[64:67], v[180:183], v[214:217], v[64:67]
	s_setprio 0
	s_barrier
	s_add_i32 s62, s54, s15
	v_lshl_add_u64 v[218:219], s[46:47], 0, v[130:131]
	s_mov_b32 m0, s62
	ds_read_b128 v[184:187], v153 offset:16384
	ds_read_b128 v[188:191], v153 offset:17408
	ds_read_b128 v[192:195], v153 offset:18432
	ds_read_b128 v[196:199], v153 offset:19456
	ds_read_b128 v[200:203], v153 offset:20480
	ds_read_b128 v[206:209], v153 offset:21504
	ds_read_b128 v[210:213], v153 offset:22528
	ds_read_b128 v[214:217], v153 offset:23552
	global_load_lds_dwordx4 v[218:219], off
	s_add_i32 m0, s62, 0x2000
	s_add_u32 s62, s46, 0x20000
	v_lshl_add_u64 v[220:221], s[46:47], 0, v[134:135]
	s_addc_u32 s63, s47, 0
	s_add_i32 s64, s55, s15
	global_load_lds_dwordx4 v[220:221], off
	v_lshl_add_u64 v[222:223], s[62:63], 0, v[130:131]
	s_mov_b32 m0, s64
	global_load_lds_dwordx4 v[222:223], off
	v_lshl_add_u64 v[222:223], s[62:63], 0, v[134:135]
	s_add_i32 m0, s64, 0x2000
	s_nop 0
	global_load_lds_dwordx4 v[222:223], off
	s_waitcnt vmcnt(6)
	s_waitcnt lgkmcnt(0)
	s_barrier
; #define PG8_STAGE(bufoff, gbase, voff) do { _Pragma("unroll") for (int _i = 0; _i < 2; ++_i) \
;         __builtin_amdgcn_global_load_lds((const unsigned*)((const char*)(gbase) + (voff)[_i]), (PG8_LAS unsigned*)(lds + (bufoff) + ldsw + _i * 8192), 16, 0, 0); } while (0)
; #define PG8_LDA(dst, b, h) do { _Pragma("unroll") for (int m = 0; m < 4; ++m) _Pragma("unroll") for (int k = 0; k < 2; ++k) dst[m][k] = *(const PG8_LAS bf16x8*)(lds + PG8_SA(b, h) + aoff + m * 2048 + k * 1024); } while (0)
; #define PG8_LDB(dst, b, h) do { _Pragma("unroll") for (int n = 0; n < 2; ++n) _Pragma("unroll") for (int k = 0; k < 2; ++k) dst[n][k] = *(const PG8_LAS bf16x8*)(lds + PG8_SB(b, h) + boff + n * 2048 + k * 1024); } while (0)
; #define PG8_MMA(ai, bj, At, Bt) do { __builtin_amdgcn_s_setprio(1); _Pragma("unroll") for (int m = 0; m < 4; ++m) _Pragma("unroll") for (int n = 0; n < 2; ++n) _Pragma("unroll") for (int k = 0; k < 2; ++k) \
;         acc[ai][bj][m][n] = __builtin_amdgcn_mfma_f32_16x16x32_bf16(Bt[n][k], At[m][k], acc[ai][bj][m][n], 0, 0, 0); __builtin_amdgcn_s_setprio(0); } while (0)
; #define PG8_WAIT_V(n) asm volatile("s_waitcnt vmcnt(" #n ")" ::: "memory")
; #define PG8_WAIT_L(n) asm volatile("s_waitcnt lgkmcnt(" #n ")" ::: "memory")
; #define PG8_BAR __builtin_amdgcn_s_barrier()
; #define PG8_SCHED __builtin_amdgcn_sched_barrier(0)
; template <class Epi, class Sched, bool ALIGN_EPI = false, bool SP2 = false>
; __device__ __forceinline__ void gemm_phase(PG8_LAS unsigned char* lds, const Gemm g, const Sched& S, const Epi& E) {
;     ...
;             PG8_LDA(At, 0, 1); PG8_STAGE(PG8_SB(0, 0), b2, voffB); PG8_STAGE(PG8_SB(0, 1), b2 + hstep, voffB); PG8_STAGE(PG8_SA(0, 0), a2, voffA);
;             PG8_WAIT_V(8); PG8_WAIT_L(0); PG8_BAR; PG8_MMA(1, 0, At, B0); PG8_MMA(1, 1, At, B1); PG8_BAR; PG8_SCHED;
;             PG8_LDB(B0, 1, 0); PG8_LDB(B1, 1, 1); PG8_SCHED; PG8_LDA(At, 1, 0); PG8_STAGE(PG8_SA(0, 1), a2 + hstep, voffA);
;             PG8_WAIT_V(8); PG8_WAIT_L(0); PG8_BAR; PG8_MMA(0, 0, At, B0); PG8_MMA(0, 1, At, B1); PG8_BAR; PG8_SCHED;
	s_setprio 1
	s_waitcnt lgkmcnt(0)
	v_mfma_f32_16x16x32_bf16 v[60:63], v[144:147], v[184:187], 0
	v_mfma_f32_16x16x32_bf16 v[56:59], v[160:163], v[184:187], 0
	v_mfma_f32_16x16x32_bf16 v[44:47], v[144:147], v[192:195], 0
	v_mfma_f32_16x16x32_bf16 v[40:43], v[160:163], v[192:195], 0
	v_mfma_f32_16x16x32_bf16 v[28:31], v[144:147], v[200:203], 0
	v_mfma_f32_16x16x32_bf16 v[24:27], v[160:163], v[200:203], 0
	v_mfma_f32_16x16x32_bf16 v[12:15], v[144:147], v[210:213], 0
	v_mfma_f32_16x16x32_bf16 v[8:11], v[160:163], v[210:213], 0
	v_mfma_f32_16x16x32_bf16 v[60:63], v[156:159], v[188:191], v[60:63]
	v_mfma_f32_16x16x32_bf16 v[56:59], v[164:167], v[188:191], v[56:59]
	v_mfma_f32_16x16x32_bf16 v[44:47], v[156:159], v[196:199], v[44:47]
	v_mfma_f32_16x16x32_bf16 v[40:43], v[164:167], v[196:199], v[40:43]
	v_lshl_add_u64 v[222:223], s[48:49], 0, v[128:129]
	s_mov_b32 m0, s33
	s_nop 0
	global_load_lds_dwordx4 v[222:223], off
	v_mfma_f32_16x16x32_bf16 v[28:31], v[156:159], v[206:209], v[28:31]
	v_mfma_f32_16x16x32_bf16 v[24:27], v[164:167], v[206:209], v[24:27]
	v_mfma_f32_16x16x32_bf16 v[12:15], v[156:159], v[214:217], v[12:15]
	v_mfma_f32_16x16x32_bf16 v[8:11], v[164:167], v[214:217], v[8:11]
	s_setprio 0
	s_setprio 1
	v_mfma_f32_16x16x32_bf16 v[52:55], v[168:171], v[184:187], 0
	v_mfma_f32_16x16x32_bf16 v[48:51], v[176:179], v[184:187], 0
	v_mfma_f32_16x16x32_bf16 v[36:39], v[168:171], v[192:195], 0
	v_mfma_f32_16x16x32_bf16 v[32:35], v[176:179], v[192:195], 0
	v_mfma_f32_16x16x32_bf16 v[20:23], v[168:171], v[200:203], 0
	v_mfma_f32_16x16x32_bf16 v[16:19], v[176:179], v[200:203], 0
	v_mfma_f32_16x16x32_bf16 v[4:7], v[168:171], v[210:213], 0
	v_mfma_f32_16x16x32_bf16 v[0:3], v[176:179], v[210:213], 0
	v_mfma_f32_16x16x32_bf16 v[52:55], v[172:175], v[188:191], v[52:55]
	v_mfma_f32_16x16x32_bf16 v[48:51], v[180:183], v[188:191], v[48:51]
	v_mfma_f32_16x16x32_bf16 v[36:39], v[172:175], v[196:199], v[36:39]
	v_mfma_f32_16x16x32_bf16 v[32:35], v[180:183], v[196:199], v[32:35]
	v_lshl_add_u64 v[224:225], s[48:49], 0, v[132:133]
	s_mov_b32 m0, s34
	s_nop 0
	global_load_lds_dwordx4 v[224:225], off
	v_mfma_f32_16x16x32_bf16 v[20:23], v[172:175], v[206:209], v[20:23]
	v_mfma_f32_16x16x32_bf16 v[16:19], v[180:183], v[206:209], v[16:19]
	v_mfma_f32_16x16x32_bf16 v[4:7], v[172:175], v[214:217], v[4:7]
	v_mfma_f32_16x16x32_bf16 v[0:3], v[180:183], v[214:217], v[0:3]
	s_setprio 0
	s_barrier
	s_add_i32 s62, 0, 0x18000
	v_add_u32_e32 v155, s62, v149
	s_add_i32 s63, 0, 0x1c000
	ds_read_b128 v[144:147], v155
	ds_read_b128 v[156:159], v155 offset:1024
	ds_read_b128 v[160:163], v155 offset:2048
	ds_read_b128 v[164:167], v155 offset:3072
	v_add_u32_e32 v155, s63, v149
	ds_read_b128 v[168:171], v155
	ds_read_b128 v[172:175], v155 offset:1024
	ds_read_b128 v[176:179], v155 offset:2048
	ds_read_b128 v[180:183], v155 offset:3072
	s_add_u32 s48, s48, 0x20000
	s_addc_u32 s49, s49, 0
	s_mov_b32 m0, s43
	v_lshl_add_u64 v[226:227], s[48:49], 0, v[128:129]
	ds_read_b128 v[184:187], v153 offset:32768
	ds_read_b128 v[188:191], v153 offset:33792
	ds_read_b128 v[192:195], v153 offset:34816
	ds_read_b128 v[196:199], v153 offset:35840
	ds_read_b128 v[200:203], v153 offset:36864
	ds_read_b128 v[206:209], v153 offset:37888
	ds_read_b128 v[210:213], v153 offset:38912
	ds_read_b128 v[214:217], v153 offset:39936
	global_load_lds_dwordx4 v[226:227], off
	v_lshl_add_u64 v[226:227], s[48:49], 0, v[132:133]
	s_mov_b32 m0, s50
	s_nop 0
	global_load_lds_dwordx4 v[226:227], off
	s_waitcnt vmcnt(8)
	s_waitcnt lgkmcnt(0)
	s_barrier
	s_setprio 1
	s_waitcnt lgkmcnt(0)
	v_mfma_f32_16x16x32_bf16 v[124:127], v[144:147], v[184:187], v[124:127]
	v_mfma_f32_16x16x32_bf16 v[120:123], v[160:163], v[184:187], v[120:123]
	v_mfma_f32_16x16x32_bf16 v[108:111], v[144:147], v[192:195], v[108:111]
	v_mfma_f32_16x16x32_bf16 v[104:107], v[160:163], v[192:195], v[104:107]
	v_mfma_f32_16x16x32_bf16 v[92:95], v[144:147], v[200:203], v[92:95]
	v_mfma_f32_16x16x32_bf16 v[88:91], v[160:163], v[200:203], v[88:91]
	v_mfma_f32_16x16x32_bf16 v[76:79], v[144:147], v[210:213], v[76:79]
	v_mfma_f32_16x16x32_bf16 v[72:75], v[160:163], v[210:213], v[72:75]
	v_mfma_f32_16x16x32_bf16 v[124:127], v[156:159], v[188:191], v[124:127]
	v_mfma_f32_16x16x32_bf16 v[120:123], v[164:167], v[188:191], v[120:123]
	v_mfma_f32_16x16x32_bf16 v[108:111], v[156:159], v[196:199], v[108:111]
	v_mfma_f32_16x16x32_bf16 v[104:107], v[164:167], v[196:199], v[104:107]
	v_mfma_f32_16x16x32_bf16 v[92:95], v[156:159], v[206:209], v[92:95]
	v_mfma_f32_16x16x32_bf16 v[88:91], v[164:167], v[206:209], v[88:91]
	v_mfma_f32_16x16x32_bf16 v[76:79], v[156:159], v[214:217], v[76:79]
	v_mfma_f32_16x16x32_bf16 v[72:75], v[164:167], v[214:217], v[72:75]
	s_setprio 0
	s_setprio 1
	v_mfma_f32_16x16x32_bf16 v[116:119], v[168:171], v[184:187], v[116:119]
	v_mfma_f32_16x16x32_bf16 v[112:115], v[176:179], v[184:187], v[112:115]
	v_mfma_f32_16x16x32_bf16 v[100:103], v[168:171], v[192:195], v[100:103]
	v_mfma_f32_16x16x32_bf16 v[96:99], v[176:179], v[192:195], v[96:99]
	v_mfma_f32_16x16x32_bf16 v[84:87], v[168:171], v[200:203], v[84:87]
	v_mfma_f32_16x16x32_bf16 v[80:83], v[176:179], v[200:203], v[80:83]
	v_mfma_f32_16x16x32_bf16 v[68:71], v[168:171], v[210:213], v[68:71]
	v_mfma_f32_16x16x32_bf16 v[64:67], v[176:179], v[210:213], v[64:67]
	v_mfma_f32_16x16x32_bf16 v[116:119], v[172:175], v[188:191], v[116:119]
	v_mfma_f32_16x16x32_bf16 v[112:115], v[180:183], v[188:191], v[112:115]
	v_mfma_f32_16x16x32_bf16 v[100:103], v[172:175], v[196:199], v[100:103]
	v_mfma_f32_16x16x32_bf16 v[96:99], v[180:183], v[196:199], v[96:99]
	v_mfma_f32_16x16x32_bf16 v[84:87], v[172:175], v[206:209], v[84:87]
	v_mfma_f32_16x16x32_bf16 v[80:83], v[180:183], v[206:209], v[80:83]
	v_mfma_f32_16x16x32_bf16 v[68:71], v[172:175], v[214:217], v[68:71]
	v_mfma_f32_16x16x32_bf16 v[64:67], v[180:183], v[214:217], v[64:67]
	s_setprio 0
	s_barrier
; #define PG8_STAGE(bufoff, gbase, voff) do { _Pragma("unroll") for (int _i = 0; _i < 2; ++_i) \
;         __builtin_amdgcn_global_load_lds((const unsigned*)((const char*)(gbase) + (voff)[_i]), (PG8_LAS unsigned*)(lds + (bufoff) + ldsw + _i * 8192), 16, 0, 0); } while (0)
; #define PG8_LDA(dst, b, h) do { _Pragma("unroll") for (int m = 0; m < 4; ++m) _Pragma("unroll") for (int k = 0; k < 2; ++k) dst[m][k] = *(const PG8_LAS bf16x8*)(lds + PG8_SA(b, h) + aoff + m * 2048 + k * 1024); } while (0)
; #define PG8_LDB(dst, b, h) do { _Pragma("unroll") for (int n = 0; n < 2; ++n) _Pragma("unroll") for (int k = 0; k < 2; ++k) dst[n][k] = *(const PG8_LAS bf16x8*)(lds + PG8_SB(b, h) + boff + n * 2048 + k * 1024); } while (0)
; #define PG8_MMA(ai, bj, At, Bt) do { __builtin_amdgcn_s_setprio(1); _Pragma("unroll") for (int m = 0; m < 4; ++m) _Pragma("unroll") for (int n = 0; n < 2; ++n) _Pragma("unroll") for (int k = 0; k < 2; ++k) \
;         acc[ai][bj][m][n] = __builtin_amdgcn_mfma_f32_16x16x32_bf16(Bt[n][k], At[m][k], acc[ai][bj][m][n], 0, 0, 0); __builtin_amdgcn_s_setprio(0); } while (0)
; #define PG8_WAIT_V(n) asm volatile("s_waitcnt vmcnt(" #n ")" ::: "memory")
; template <class Epi, class Sched, bool ALIGN_EPI = false, bool SP2 = false>
; __device__ __forceinline__ void gemm_phase(PG8_LAS unsigned char* lds, const Gemm g, const Sched& S, const Epi& E) {
;     ...
;             PG8_LDB(B0, 0, 0); PG8_LDB(B1, 0, 1); PG8_SCHED; PG8_LDA(At, 0, 0); PG8_STAGE(PG8_SA(1, 1), a1 + hstep, voffA);
;             PG8_WAIT_V(8); PG8_WAIT_L(0); PG8_BAR; PG8_MMA(0, 0, At, B0); PG8_MMA(0, 1, At, B1); PG8_BAR; PG8_SCHED;
;             PG8_LDA(At, 0, 1); PG8_STAGE(PG8_SB(0, 0), b2, voffB); PG8_STAGE(PG8_SB(0, 1), b2 + hstep, voffB); PG8_STAGE(PG8_SA(0, 0), a2, voffA);
;             PG8_WAIT_V(8); PG8_WAIT_L(0); PG8_BAR; PG8_MMA(1, 0, At, B0); PG8_MMA(1, 1, At, B1); PG8_BAR; PG8_SCHED;
;             PG8_LDB(B0, 1, 0); PG8_LDB(B1, 1, 1); PG8_SCHED; PG8_LDA(At, 1, 0); PG8_STAGE(PG8_SA(0, 1), a2 + hstep, voffA);
;             PG8_WAIT_V(8); PG8_WAIT_L(0); PG8_BAR; PG8_MMA(0, 0, At, B0); PG8_MMA(0, 1, At, B1); PG8_BAR; PG8_SCHED;
;             PG8_LDA(At, 1, 1); PG8_STAGE(PG8_SB(1, 0), b3, voffB); PG8_STAGE(PG8_SB(1, 1), b3 + hstep, voffB); PG8_STAGE(PG8_SA(1, 0), a3, voffA);
;             PG8_WAIT_V(8); PG8_WAIT_L(0); PG8_BAR; PG8_MMA(1, 0, At, B0); PG8_MMA(1, 1, At, B1); PG8_BAR; PG8_SCHED;
	s_add_i32 s48, s62, s15
	v_lshl_add_u64 v[218:219], v[218:219], 0, s[12:13]
	s_mov_b32 m0, s48
	ds_read_b128 v[184:187], v153 offset:49152
	ds_read_b128 v[188:191], v153 offset:50176
	ds_read_b128 v[192:195], v153 offset:51200
	ds_read_b128 v[196:199], v153 offset:52224
	ds_read_b128 v[200:203], v153 offset:53248
	ds_read_b128 v[206:209], v153 offset:54272
	ds_read_b128 v[210:213], v153 offset:55296
	ds_read_b128 v[214:217], v153 offset:56320
	global_load_lds_dwordx4 v[218:219], off
	s_add_i32 m0, s48, 0x2000
	s_add_u32 s46, s46, 0x20080
	v_lshl_add_u64 v[218:219], v[220:221], 0, s[12:13]
	s_addc_u32 s47, s47, 0
	s_add_i32 s48, s63, s15
	global_load_lds_dwordx4 v[218:219], off
	v_lshl_add_u64 v[218:219], s[46:47], 0, v[130:131]
	s_mov_b32 m0, s48
	s_nop 0
	global_load_lds_dwordx4 v[218:219], off
	v_lshl_add_u64 v[218:219], s[46:47], 0, v[134:135]
	s_add_i32 m0, s48, 0x2000
	s_nop 0
	global_load_lds_dwordx4 v[218:219], off
	s_waitcnt vmcnt(6)
	s_waitcnt lgkmcnt(0)
	s_barrier
	s_setprio 1
	s_waitcnt lgkmcnt(0)
	v_mfma_f32_16x16x32_bf16 v[60:63], v[144:147], v[184:187], v[60:63]
	v_mfma_f32_16x16x32_bf16 v[56:59], v[160:163], v[184:187], v[56:59]
	v_mfma_f32_16x16x32_bf16 v[44:47], v[144:147], v[192:195], v[44:47]
	v_mfma_f32_16x16x32_bf16 v[40:43], v[160:163], v[192:195], v[40:43]
	v_mfma_f32_16x16x32_bf16 v[28:31], v[144:147], v[200:203], v[28:31]
	v_mfma_f32_16x16x32_bf16 v[24:27], v[160:163], v[200:203], v[24:27]
	v_mfma_f32_16x16x32_bf16 v[12:15], v[144:147], v[210:213], v[12:15]
	v_mfma_f32_16x16x32_bf16 v[8:11], v[160:163], v[210:213], v[8:11]
	v_mfma_f32_16x16x32_bf16 v[60:63], v[156:159], v[188:191], v[60:63]
	v_mfma_f32_16x16x32_bf16 v[56:59], v[164:167], v[188:191], v[56:59]
	v_mfma_f32_16x16x32_bf16 v[44:47], v[156:159], v[196:199], v[44:47]
	v_mfma_f32_16x16x32_bf16 v[40:43], v[164:167], v[196:199], v[40:43]
	v_lshl_add_u64 v[218:219], v[222:223], 0, s[12:13]
	s_mov_b32 m0, s52
	s_nop 0
	global_load_lds_dwordx4 v[218:219], off
	v_mfma_f32_16x16x32_bf16 v[28:31], v[156:159], v[206:209], v[28:31]
	v_mfma_f32_16x16x32_bf16 v[24:27], v[164:167], v[206:209], v[24:27]
	v_mfma_f32_16x16x32_bf16 v[12:15], v[156:159], v[214:217], v[12:15]
	v_mfma_f32_16x16x32_bf16 v[8:11], v[164:167], v[214:217], v[8:11]
	s_setprio 0
	s_setprio 1
	v_mfma_f32_16x16x32_bf16 v[52:55], v[168:171], v[184:187], v[52:55]
	v_mfma_f32_16x16x32_bf16 v[48:51], v[176:179], v[184:187], v[48:51]
	v_mfma_f32_16x16x32_bf16 v[36:39], v[168:171], v[192:195], v[36:39]
	v_mfma_f32_16x16x32_bf16 v[32:35], v[176:179], v[192:195], v[32:35]
	v_mfma_f32_16x16x32_bf16 v[20:23], v[168:171], v[200:203], v[20:23]
	v_mfma_f32_16x16x32_bf16 v[16:19], v[176:179], v[200:203], v[16:19]
	v_mfma_f32_16x16x32_bf16 v[4:7], v[168:171], v[210:213], v[4:7]
	v_mfma_f32_16x16x32_bf16 v[0:3], v[176:179], v[210:213], v[0:3]
	v_mfma_f32_16x16x32_bf16 v[52:55], v[172:175], v[188:191], v[52:55]
	v_mfma_f32_16x16x32_bf16 v[48:51], v[180:183], v[188:191], v[48:51]
	v_mfma_f32_16x16x32_bf16 v[36:39], v[172:175], v[196:199], v[36:39]
	v_mfma_f32_16x16x32_bf16 v[32:35], v[180:183], v[196:199], v[32:35]
	v_lshl_add_u64 v[218:219], v[224:225], 0, s[12:13]
	s_mov_b32 m0, s53
	s_nop 0
	global_load_lds_dwordx4 v[218:219], off
	v_mfma_f32_16x16x32_bf16 v[20:23], v[172:175], v[206:209], v[20:23]
	v_mfma_f32_16x16x32_bf16 v[16:19], v[180:183], v[206:209], v[16:19]
	v_mfma_f32_16x16x32_bf16 v[4:7], v[172:175], v[214:217], v[4:7]
	v_mfma_f32_16x16x32_bf16 v[0:3], v[180:183], v[214:217], v[0:3]
	s_setprio 0
	s_barrier
	s_add_i32 s61, s61, 2
	s_add_u32 s44, s44, 0x100
	s_addc_u32 s45, s45, 0
	s_add_u32 s59, s59, 0x100
	s_addc_u32 s60, s60, 0
.LBB0_1816:
	ds_read_b128 v[144:147], v151
	ds_read_b128 v[156:159], v151 offset:1024
	ds_read_b128 v[160:163], v151 offset:2048
	ds_read_b128 v[164:167], v151 offset:3072
	ds_read_b128 v[168:171], v152
	ds_read_b128 v[172:175], v152 offset:1024
	ds_read_b128 v[176:179], v152 offset:2048
	ds_read_b128 v[180:183], v152 offset:3072
	s_add_u32 s46, s44, 0xfffe0080
	s_addc_u32 s47, s45, -1
	s_cmp_eq_u32 s61, 4
	s_cselect_b32 s49, s29, s47
	s_cselect_b32 s48, s41, s46
	s_cselect_b32 s47, s27, s60
	s_cselect_b32 s46, s58, s59
	v_lshl_add_u64 v[218:219], s[44:45], 0, v[136:137]
	s_add_i32 m0, s33, 0xc000
	ds_read_b128 v[184:187], v153
	ds_read_b128 v[188:191], v153 offset:1024
	ds_read_b128 v[192:195], v153 offset:2048
	ds_read_b128 v[196:199], v153 offset:3072
	ds_read_b128 v[200:203], v153 offset:4096
	ds_read_b128 v[206:209], v153 offset:5120
	ds_read_b128 v[210:213], v153 offset:6144
	ds_read_b128 v[214:217], v153 offset:7168
	global_load_lds_dwordx4 v[218:219], off
	v_lshl_add_u64 v[218:219], s[44:45], 0, v[138:139]
	s_add_i32 m0, s33, 0xe000
	s_nop 0
	global_load_lds_dwordx4 v[218:219], off
	s_waitcnt vmcnt(8)
	s_waitcnt lgkmcnt(0)
	s_barrier
; #define PG8_STAGE(bufoff, gbase, voff) do { _Pragma("unroll") for (int _i = 0; _i < 2; ++_i) \
;         __builtin_amdgcn_global_load_lds((const unsigned*)((const char*)(gbase) + (voff)[_i]), (PG8_LAS unsigned*)(lds + (bufoff) + ldsw + _i * 8192), 16, 0, 0); } while (0)
; #define PG8_LDA(dst, b, h) do { _Pragma("unroll") for (int m = 0; m < 4; ++m) _Pragma("unroll") for (int k = 0; k < 2; ++k) dst[m][k] = *(const PG8_LAS bf16x8*)(lds + PG8_SA(b, h) + aoff + m * 2048 + k * 1024); } while (0)
; #define PG8_LDB(dst, b, h) do { _Pragma("unroll") for (int n = 0; n < 2; ++n) _Pragma("unroll") for (int k = 0; k < 2; ++k) dst[n][k] = *(const PG8_LAS bf16x8*)(lds + PG8_SB(b, h) + boff + n * 2048 + k * 1024); } while (0)
; #define PG8_MMA(ai, bj, At, Bt) do { __builtin_amdgcn_s_setprio(1); _Pragma("unroll") for (int m = 0; m < 4; ++m) _Pragma("unroll") for (int n = 0; n < 2; ++n) _Pragma("unroll") for (int k = 0; k < 2; ++k) \
;         acc[ai][bj][m][n] = __builtin_amdgcn_mfma_f32_16x16x32_bf16(Bt[n][k], At[m][k], acc[ai][bj][m][n], 0, 0, 0); __builtin_amdgcn_s_setprio(0); } while (0)
; #define PG8_WAIT_V(n) asm volatile("s_waitcnt vmcnt(" #n ")" ::: "memory")
; #define PG8_WAIT_L(n) asm volatile("s_waitcnt lgkmcnt(" #n ")" ::: "memory")
; #define PG8_BAR __builtin_amdgcn_s_barrier()
; #define PG8_SCHED __builtin_amdgcn_sched_barrier(0)
; template <class Epi, class Sched, bool ALIGN_EPI = false, bool SP2 = false>
; __device__ __forceinline__ void gemm_phase(PG8_LAS unsigned char* lds, const Gemm g, const Sched& S, const Epi& E) {
;     ...
;             PG8_LDB(B0, 0, 0); PG8_LDB(B1, 0, 1); PG8_SCHED; PG8_LDA(At, 0, 0); PG8_STAGE(PG8_SA(1, 1), a1 + hstep, voffA);
;             PG8_WAIT_V(8); PG8_WAIT_L(0); PG8_BAR; PG8_MMA(0, 0, At, B0); PG8_MMA(0, 1, At, B1); PG8_BAR; PG8_SCHED;
;             PG8_LDA(At, 0, 1); PG8_STAGE(PG8_SB(0, 0), b2, voffB); PG8_STAGE(PG8_SB(0, 1), b2 + hstep, voffB); PG8_STAGE(PG8_SA(0, 0), a2, voffA);
;             PG8_WAIT_V(8); PG8_WAIT_L(0); PG8_BAR; PG8_MMA(1, 0, At, B0); PG8_MMA(1, 1, At, B1); PG8_BAR; PG8_SCHED;
	s_setprio 1
	s_waitcnt lgkmcnt(0)
	v_mfma_f32_16x16x32_bf16 v[124:127], v[144:147], v[184:187], v[124:127]
	v_mfma_f32_16x16x32_bf16 v[120:123], v[160:163], v[184:187], v[120:123]
	v_mfma_f32_16x16x32_bf16 v[108:111], v[144:147], v[192:195], v[108:111]
	v_mfma_f32_16x16x32_bf16 v[104:107], v[160:163], v[192:195], v[104:107]
	v_mfma_f32_16x16x32_bf16 v[92:95], v[144:147], v[200:203], v[92:95]
	v_mfma_f32_16x16x32_bf16 v[88:91], v[160:163], v[200:203], v[88:91]
	v_mfma_f32_16x16x32_bf16 v[76:79], v[144:147], v[210:213], v[76:79]
	v_mfma_f32_16x16x32_bf16 v[72:75], v[160:163], v[210:213], v[72:75]
	v_mfma_f32_16x16x32_bf16 v[124:127], v[156:159], v[188:191], v[124:127]
	v_mfma_f32_16x16x32_bf16 v[120:123], v[164:167], v[188:191], v[120:123]
	v_mfma_f32_16x16x32_bf16 v[108:111], v[156:159], v[196:199], v[108:111]
	v_mfma_f32_16x16x32_bf16 v[104:107], v[164:167], v[196:199], v[104:107]
	v_mfma_f32_16x16x32_bf16 v[92:95], v[156:159], v[206:209], v[92:95]
	v_mfma_f32_16x16x32_bf16 v[88:91], v[164:167], v[206:209], v[88:91]
	v_mfma_f32_16x16x32_bf16 v[76:79], v[156:159], v[214:217], v[76:79]
	v_mfma_f32_16x16x32_bf16 v[72:75], v[164:167], v[214:217], v[72:75]
	s_setprio 0
	s_setprio 1
	v_mfma_f32_16x16x32_bf16 v[116:119], v[168:171], v[184:187], v[116:119]
	v_mfma_f32_16x16x32_bf16 v[112:115], v[176:179], v[184:187], v[112:115]
	v_mfma_f32_16x16x32_bf16 v[100:103], v[168:171], v[192:195], v[100:103]
	v_mfma_f32_16x16x32_bf16 v[96:99], v[176:179], v[192:195], v[96:99]
	v_mfma_f32_16x16x32_bf16 v[84:87], v[168:171], v[200:203], v[84:87]
	v_mfma_f32_16x16x32_bf16 v[80:83], v[176:179], v[200:203], v[80:83]
	v_mfma_f32_16x16x32_bf16 v[68:71], v[168:171], v[210:213], v[68:71]
	v_mfma_f32_16x16x32_bf16 v[64:67], v[176:179], v[210:213], v[64:67]
	v_mfma_f32_16x16x32_bf16 v[116:119], v[172:175], v[188:191], v[116:119]
	v_mfma_f32_16x16x32_bf16 v[112:115], v[180:183], v[188:191], v[112:115]
	v_mfma_f32_16x16x32_bf16 v[100:103], v[172:175], v[196:199], v[100:103]
	v_mfma_f32_16x16x32_bf16 v[96:99], v[180:183], v[196:199], v[96:99]
	v_mfma_f32_16x16x32_bf16 v[84:87], v[172:175], v[206:209], v[84:87]
	v_mfma_f32_16x16x32_bf16 v[80:83], v[180:183], v[206:209], v[80:83]
	v_mfma_f32_16x16x32_bf16 v[68:71], v[172:175], v[214:217], v[68:71]
	v_mfma_f32_16x16x32_bf16 v[64:67], v[180:183], v[214:217], v[64:67]
	s_setprio 0
	s_barrier
	s_add_i32 s62, s54, s15
	v_lshl_add_u64 v[218:219], s[46:47], 0, v[130:131]
	s_mov_b32 m0, s62
	ds_read_b128 v[184:187], v153 offset:16384
	ds_read_b128 v[188:191], v153 offset:17408
	ds_read_b128 v[192:195], v153 offset:18432
	ds_read_b128 v[196:199], v153 offset:19456
	ds_read_b128 v[200:203], v153 offset:20480
	ds_read_b128 v[206:209], v153 offset:21504
	ds_read_b128 v[210:213], v153 offset:22528
	ds_read_b128 v[214:217], v153 offset:23552
	global_load_lds_dwordx4 v[218:219], off
	s_add_i32 m0, s62, 0x2000
	s_add_u32 s62, s46, 0x20000
	v_lshl_add_u64 v[220:221], s[46:47], 0, v[134:135]
	s_addc_u32 s63, s47, 0
	s_add_i32 s64, s55, s15
	global_load_lds_dwordx4 v[220:221], off
	v_lshl_add_u64 v[222:223], s[62:63], 0, v[130:131]
	s_mov_b32 m0, s64
	global_load_lds_dwordx4 v[222:223], off
	v_lshl_add_u64 v[222:223], s[62:63], 0, v[134:135]
	s_add_i32 m0, s64, 0x2000
	s_nop 0
	global_load_lds_dwordx4 v[222:223], off
	s_waitcnt vmcnt(6)
	s_waitcnt lgkmcnt(0)
	s_barrier
	s_setprio 1
	s_waitcnt lgkmcnt(0)
	v_mfma_f32_16x16x32_bf16 v[60:63], v[144:147], v[184:187], v[60:63]
	v_mfma_f32_16x16x32_bf16 v[56:59], v[160:163], v[184:187], v[56:59]
	v_mfma_f32_16x16x32_bf16 v[44:47], v[144:147], v[192:195], v[44:47]
	v_mfma_f32_16x16x32_bf16 v[40:43], v[160:163], v[192:195], v[40:43]
	v_mfma_f32_16x16x32_bf16 v[28:31], v[144:147], v[200:203], v[28:31]
	v_mfma_f32_16x16x32_bf16 v[24:27], v[160:163], v[200:203], v[24:27]
	v_mfma_f32_16x16x32_bf16 v[12:15], v[144:147], v[210:213], v[12:15]
	v_mfma_f32_16x16x32_bf16 v[8:11], v[160:163], v[210:213], v[8:11]
	v_mfma_f32_16x16x32_bf16 v[60:63], v[156:159], v[188:191], v[60:63]
	v_mfma_f32_16x16x32_bf16 v[56:59], v[164:167], v[188:191], v[56:59]
	v_mfma_f32_16x16x32_bf16 v[44:47], v[156:159], v[196:199], v[44:47]
	v_mfma_f32_16x16x32_bf16 v[40:43], v[164:167], v[196:199], v[40:43]
	v_lshl_add_u64 v[222:223], s[48:49], 0, v[128:129]
	s_mov_b32 m0, s33
	s_nop 0
	global_load_lds_dwordx4 v[222:223], off
	v_mfma_f32_16x16x32_bf16 v[28:31], v[156:159], v[206:209], v[28:31]
	v_mfma_f32_16x16x32_bf16 v[24:27], v[164:167], v[206:209], v[24:27]
	v_mfma_f32_16x16x32_bf16 v[12:15], v[156:159], v[214:217], v[12:15]
	v_mfma_f32_16x16x32_bf16 v[8:11], v[164:167], v[214:217], v[8:11]
	s_setprio 0
	s_setprio 1
	v_mfma_f32_16x16x32_bf16 v[52:55], v[168:171], v[184:187], v[52:55]
	v_mfma_f32_16x16x32_bf16 v[48:51], v[176:179], v[184:187], v[48:51]
	v_mfma_f32_16x16x32_bf16 v[36:39], v[168:171], v[192:195], v[36:39]
	v_mfma_f32_16x16x32_bf16 v[32:35], v[176:179], v[192:195], v[32:35]
	v_mfma_f32_16x16x32_bf16 v[20:23], v[168:171], v[200:203], v[20:23]
	v_mfma_f32_16x16x32_bf16 v[16:19], v[176:179], v[200:203], v[16:19]
	v_mfma_f32_16x16x32_bf16 v[4:7], v[168:171], v[210:213], v[4:7]
	v_mfma_f32_16x16x32_bf16 v[0:3], v[176:179], v[210:213], v[0:3]
	v_mfma_f32_16x16x32_bf16 v[52:55], v[172:175], v[188:191], v[52:55]
	v_mfma_f32_16x16x32_bf16 v[48:51], v[180:183], v[188:191], v[48:51]
	v_mfma_f32_16x16x32_bf16 v[36:39], v[172:175], v[196:199], v[36:39]
	v_mfma_f32_16x16x32_bf16 v[32:35], v[180:183], v[196:199], v[32:35]
	v_lshl_add_u64 v[224:225], s[48:49], 0, v[132:133]
	s_mov_b32 m0, s34
	s_nop 0
	global_load_lds_dwordx4 v[224:225], off
	v_mfma_f32_16x16x32_bf16 v[20:23], v[172:175], v[206:209], v[20:23]
	v_mfma_f32_16x16x32_bf16 v[16:19], v[180:183], v[206:209], v[16:19]
	v_mfma_f32_16x16x32_bf16 v[4:7], v[172:175], v[214:217], v[4:7]
	v_mfma_f32_16x16x32_bf16 v[0:3], v[180:183], v[214:217], v[0:3]
	s_setprio 0
	s_barrier
; #define PG8_STAGE(bufoff, gbase, voff) do { _Pragma("unroll") for (int _i = 0; _i < 2; ++_i) \
;         __builtin_amdgcn_global_load_lds((const unsigned*)((const char*)(gbase) + (voff)[_i]), (PG8_LAS unsigned*)(lds + (bufoff) + ldsw + _i * 8192), 16, 0, 0); } while (0)
; #define PG8_LDA(dst, b, h) do { _Pragma("unroll") for (int m = 0; m < 4; ++m) _Pragma("unroll") for (int k = 0; k < 2; ++k) dst[m][k] = *(const PG8_LAS bf16x8*)(lds + PG8_SA(b, h) + aoff + m * 2048 + k * 1024); } while (0)
; #define PG8_LDB(dst, b, h) do { _Pragma("unroll") for (int n = 0; n < 2; ++n) _Pragma("unroll") for (int k = 0; k < 2; ++k) dst[n][k] = *(const PG8_LAS bf16x8*)(lds + PG8_SB(b, h) + boff + n * 2048 + k * 1024); } while (0)
; #define PG8_MMA(ai, bj, At, Bt) do { __builtin_amdgcn_s_setprio(1); _Pragma("unroll") for (int m = 0; m < 4; ++m) _Pragma("unroll") for (int n = 0; n < 2; ++n) _Pragma("unroll") for (int k = 0; k < 2; ++k) \
;         acc[ai][bj][m][n] = __builtin_amdgcn_mfma_f32_16x16x32_bf16(Bt[n][k], At[m][k], acc[ai][bj][m][n], 0, 0, 0); __builtin_amdgcn_s_setprio(0); } while (0)
; #define PG8_WAIT_V(n) asm volatile("s_waitcnt vmcnt(" #n ")" ::: "memory")
; #define PG8_WAIT_L(n) asm volatile("s_waitcnt lgkmcnt(" #n ")" ::: "memory")
; #define PG8_BAR __builtin_amdgcn_s_barrier()
; #define PG8_SCHED __builtin_amdgcn_sched_barrier(0)
; template <class Epi, class Sched, bool ALIGN_EPI = false, bool SP2 = false>
; __device__ __forceinline__ void gemm_phase(PG8_LAS unsigned char* lds, const Gemm g, const Sched& S, const Epi& E) {
;     ...
;             PG8_LDB(B0, 1, 0); PG8_LDB(B1, 1, 1); PG8_SCHED; PG8_LDA(At, 1, 0); PG8_STAGE(PG8_SA(0, 1), a2 + hstep, voffA);
;             PG8_WAIT_V(8); PG8_WAIT_L(0); PG8_BAR; PG8_MMA(0, 0, At, B0); PG8_MMA(0, 1, At, B1); PG8_BAR; PG8_SCHED;
	s_add_i32 s62, 0, 0x18000
	v_add_u32_e32 v155, s62, v149
	s_add_i32 s63, 0, 0x1c000
	ds_read_b128 v[144:147], v155
	ds_read_b128 v[156:159], v155 offset:1024
	ds_read_b128 v[160:163], v155 offset:2048
	ds_read_b128 v[164:167], v155 offset:3072
	v_add_u32_e32 v155, s63, v149
	ds_read_b128 v[168:171], v155
	ds_read_b128 v[172:175], v155 offset:1024
	ds_read_b128 v[176:179], v155 offset:2048
	ds_read_b128 v[180:183], v155 offset:3072
	s_add_u32 s48, s48, 0x20000
	s_addc_u32 s49, s49, 0
	s_mov_b32 m0, s43
	v_lshl_add_u64 v[226:227], s[48:49], 0, v[128:129]
	ds_read_b128 v[184:187], v153 offset:32768
	ds_read_b128 v[188:191], v153 offset:33792
	ds_read_b128 v[192:195], v153 offset:34816
	ds_read_b128 v[196:199], v153 offset:35840
	ds_read_b128 v[200:203], v153 offset:36864
	ds_read_b128 v[206:209], v153 offset:37888
	ds_read_b128 v[210:213], v153 offset:38912
	ds_read_b128 v[214:217], v153 offset:39936
	global_load_lds_dwordx4 v[226:227], off
	v_lshl_add_u64 v[226:227], s[48:49], 0, v[132:133]
	s_mov_b32 m0, s50
	s_nop 0
	global_load_lds_dwordx4 v[226:227], off
	s_waitcnt vmcnt(8)
	s_waitcnt lgkmcnt(0)
	s_barrier
	s_setprio 1
	s_waitcnt lgkmcnt(0)
	v_mfma_f32_16x16x32_bf16 v[124:127], v[144:147], v[184:187], v[124:127]
	v_mfma_f32_16x16x32_bf16 v[120:123], v[160:163], v[184:187], v[120:123]
	v_mfma_f32_16x16x32_bf16 v[108:111], v[144:147], v[192:195], v[108:111]
	v_mfma_f32_16x16x32_bf16 v[104:107], v[160:163], v[192:195], v[104:107]
	v_mfma_f32_16x16x32_bf16 v[92:95], v[144:147], v[200:203], v[92:95]
	v_mfma_f32_16x16x32_bf16 v[88:91], v[160:163], v[200:203], v[88:91]
	v_mfma_f32_16x16x32_bf16 v[76:79], v[144:147], v[210:213], v[76:79]
	v_mfma_f32_16x16x32_bf16 v[72:75], v[160:163], v[210:213], v[72:75]
	v_mfma_f32_16x16x32_bf16 v[124:127], v[156:159], v[188:191], v[124:127]
	v_mfma_f32_16x16x32_bf16 v[120:123], v[164:167], v[188:191], v[120:123]
	v_mfma_f32_16x16x32_bf16 v[108:111], v[156:159], v[196:199], v[108:111]
	v_mfma_f32_16x16x32_bf16 v[104:107], v[164:167], v[196:199], v[104:107]
	v_mfma_f32_16x16x32_bf16 v[92:95], v[156:159], v[206:209], v[92:95]
	v_mfma_f32_16x16x32_bf16 v[88:91], v[164:167], v[206:209], v[88:91]
	v_mfma_f32_16x16x32_bf16 v[76:79], v[156:159], v[214:217], v[76:79]
	v_mfma_f32_16x16x32_bf16 v[72:75], v[164:167], v[214:217], v[72:75]
	s_setprio 0
	s_setprio 1
	v_mfma_f32_16x16x32_bf16 v[116:119], v[168:171], v[184:187], v[116:119]
	v_mfma_f32_16x16x32_bf16 v[112:115], v[176:179], v[184:187], v[112:115]
	v_mfma_f32_16x16x32_bf16 v[100:103], v[168:171], v[192:195], v[100:103]
	v_mfma_f32_16x16x32_bf16 v[96:99], v[176:179], v[192:195], v[96:99]
	v_mfma_f32_16x16x32_bf16 v[84:87], v[168:171], v[200:203], v[84:87]
	v_mfma_f32_16x16x32_bf16 v[80:83], v[176:179], v[200:203], v[80:83]
	v_mfma_f32_16x16x32_bf16 v[68:71], v[168:171], v[210:213], v[68:71]
	v_mfma_f32_16x16x32_bf16 v[64:67], v[176:179], v[210:213], v[64:67]
	v_mfma_f32_16x16x32_bf16 v[116:119], v[172:175], v[188:191], v[116:119]
	v_mfma_f32_16x16x32_bf16 v[112:115], v[180:183], v[188:191], v[112:115]
	v_mfma_f32_16x16x32_bf16 v[100:103], v[172:175], v[196:199], v[100:103]
	v_mfma_f32_16x16x32_bf16 v[96:99], v[180:183], v[196:199], v[96:99]
	v_mfma_f32_16x16x32_bf16 v[84:87], v[172:175], v[206:209], v[84:87]
	v_mfma_f32_16x16x32_bf16 v[80:83], v[180:183], v[206:209], v[80:83]
	v_mfma_f32_16x16x32_bf16 v[68:71], v[172:175], v[214:217], v[68:71]
	v_mfma_f32_16x16x32_bf16 v[64:67], v[180:183], v[214:217], v[64:67]
	s_setprio 0
	s_barrier
; #define PG8_STAGE(bufoff, gbase, voff) do { _Pragma("unroll") for (int _i = 0; _i < 2; ++_i) \
;         __builtin_amdgcn_global_load_lds((const unsigned*)((const char*)(gbase) + (voff)[_i]), (PG8_LAS unsigned*)(lds + (bufoff) + ldsw + _i * 8192), 16, 0, 0); } while (0)
; #define PG8_LDA(dst, b, h) do { _Pragma("unroll") for (int m = 0; m < 4; ++m) _Pragma("unroll") for (int k = 0; k < 2; ++k) dst[m][k] = *(const PG8_LAS bf16x8*)(lds + PG8_SA(b, h) + aoff + m * 2048 + k * 1024); } while (0)
; #define PG8_MMA(ai, bj, At, Bt) do { __builtin_amdgcn_s_setprio(1); _Pragma("unroll") for (int m = 0; m < 4; ++m) _Pragma("unroll") for (int n = 0; n < 2; ++n) _Pragma("unroll") for (int k = 0; k < 2; ++k) \
;         acc[ai][bj][m][n] = __builtin_amdgcn_mfma_f32_16x16x32_bf16(Bt[n][k], At[m][k], acc[ai][bj][m][n], 0, 0, 0); __builtin_amdgcn_s_setprio(0); } while (0)
; #define PG8_WAIT_V(n) asm volatile("s_waitcnt vmcnt(" #n ")" ::: "memory")
; #define PG8_WAIT_L(n) asm volatile("s_waitcnt lgkmcnt(" #n ")" ::: "memory")
; #define PG8_BAR __builtin_amdgcn_s_barrier()
; #define PG8_SCHED __builtin_amdgcn_sched_barrier(0)
; template <class Epi, class Sched, bool ALIGN_EPI = false, bool SP2 = false>
; __device__ __forceinline__ void gemm_phase(PG8_LAS unsigned char* lds, const Gemm g, const Sched& S, const Epi& E) {
;     ...
;             PG8_LDA(At, 1, 1); PG8_STAGE(PG8_SB(1, 0), b3, voffB); PG8_STAGE(PG8_SB(1, 1), b3 + hstep, voffB); PG8_STAGE(PG8_SA(1, 0), a3, voffA);
;             PG8_WAIT_V(8); PG8_WAIT_L(0); PG8_BAR; PG8_MMA(1, 0, At, B0); PG8_MMA(1, 1, At, B1); PG8_BAR; PG8_SCHED;
	s_add_i32 s48, s62, s15
	v_lshl_add_u64 v[218:219], v[218:219], 0, s[12:13]
	s_mov_b32 m0, s48
	ds_read_b128 v[184:187], v153 offset:49152
	ds_read_b128 v[188:191], v153 offset:50176
	ds_read_b128 v[192:195], v153 offset:51200
	ds_read_b128 v[196:199], v153 offset:52224
	ds_read_b128 v[200:203], v153 offset:53248
	ds_read_b128 v[206:209], v153 offset:54272
	ds_read_b128 v[210:213], v153 offset:55296
	ds_read_b128 v[214:217], v153 offset:56320
	global_load_lds_dwordx4 v[218:219], off
	s_add_i32 m0, s48, 0x2000
	s_add_u32 s46, s46, 0x20080
	v_lshl_add_u64 v[218:219], v[220:221], 0, s[12:13]
	s_addc_u32 s47, s47, 0
	s_add_i32 s48, s63, s15
	global_load_lds_dwordx4 v[218:219], off
	v_lshl_add_u64 v[218:219], s[46:47], 0, v[130:131]
	s_mov_b32 m0, s48
	s_nop 0
	global_load_lds_dwordx4 v[218:219], off
	v_lshl_add_u64 v[218:219], s[46:47], 0, v[134:135]
	s_add_i32 m0, s48, 0x2000
	s_nop 0
	global_load_lds_dwordx4 v[218:219], off
	s_waitcnt vmcnt(6)
	s_waitcnt lgkmcnt(0)
	s_barrier
	s_setprio 1
	s_waitcnt lgkmcnt(0)
	v_mfma_f32_16x16x32_bf16 v[60:63], v[144:147], v[184:187], v[60:63]
	v_mfma_f32_16x16x32_bf16 v[56:59], v[160:163], v[184:187], v[56:59]
	v_mfma_f32_16x16x32_bf16 v[44:47], v[144:147], v[192:195], v[44:47]
	v_mfma_f32_16x16x32_bf16 v[40:43], v[160:163], v[192:195], v[40:43]
	v_mfma_f32_16x16x32_bf16 v[28:31], v[144:147], v[200:203], v[28:31]
	v_mfma_f32_16x16x32_bf16 v[24:27], v[160:163], v[200:203], v[24:27]
	v_mfma_f32_16x16x32_bf16 v[12:15], v[144:147], v[210:213], v[12:15]
	v_mfma_f32_16x16x32_bf16 v[8:11], v[160:163], v[210:213], v[8:11]
	v_mfma_f32_16x16x32_bf16 v[60:63], v[156:159], v[188:191], v[60:63]
	v_mfma_f32_16x16x32_bf16 v[56:59], v[164:167], v[188:191], v[56:59]
	v_mfma_f32_16x16x32_bf16 v[44:47], v[156:159], v[196:199], v[44:47]
	v_mfma_f32_16x16x32_bf16 v[40:43], v[164:167], v[196:199], v[40:43]
	v_lshl_add_u64 v[218:219], v[222:223], 0, s[12:13]
	s_mov_b32 m0, s52
	s_nop 0
	global_load_lds_dwordx4 v[218:219], off
	v_mfma_f32_16x16x32_bf16 v[28:31], v[156:159], v[206:209], v[28:31]
	v_mfma_f32_16x16x32_bf16 v[24:27], v[164:167], v[206:209], v[24:27]
	v_mfma_f32_16x16x32_bf16 v[12:15], v[156:159], v[214:217], v[12:15]
	v_mfma_f32_16x16x32_bf16 v[8:11], v[164:167], v[214:217], v[8:11]
	s_setprio 0
	s_setprio 1
	v_mfma_f32_16x16x32_bf16 v[52:55], v[168:171], v[184:187], v[52:55]
	v_mfma_f32_16x16x32_bf16 v[48:51], v[176:179], v[184:187], v[48:51]
	v_mfma_f32_16x16x32_bf16 v[36:39], v[168:171], v[192:195], v[36:39]
	v_mfma_f32_16x16x32_bf16 v[32:35], v[176:179], v[192:195], v[32:35]
	v_mfma_f32_16x16x32_bf16 v[20:23], v[168:171], v[200:203], v[20:23]
	v_mfma_f32_16x16x32_bf16 v[16:19], v[176:179], v[200:203], v[16:19]
	v_mfma_f32_16x16x32_bf16 v[4:7], v[168:171], v[210:213], v[4:7]
	v_mfma_f32_16x16x32_bf16 v[0:3], v[176:179], v[210:213], v[0:3]
	v_mfma_f32_16x16x32_bf16 v[52:55], v[172:175], v[188:191], v[52:55]
	v_mfma_f32_16x16x32_bf16 v[48:51], v[180:183], v[188:191], v[48:51]
	v_mfma_f32_16x16x32_bf16 v[36:39], v[172:175], v[196:199], v[36:39]
	v_mfma_f32_16x16x32_bf16 v[32:35], v[180:183], v[196:199], v[32:35]
	v_lshl_add_u64 v[218:219], v[224:225], 0, s[12:13]
	s_mov_b32 m0, s53
	s_nop 0
	global_load_lds_dwordx4 v[218:219], off
	v_mfma_f32_16x16x32_bf16 v[20:23], v[172:175], v[206:209], v[20:23]
	v_mfma_f32_16x16x32_bf16 v[16:19], v[180:183], v[206:209], v[16:19]
	v_mfma_f32_16x16x32_bf16 v[4:7], v[172:175], v[214:217], v[4:7]
	v_mfma_f32_16x16x32_bf16 v[0:3], v[180:183], v[214:217], v[0:3]
	s_setprio 0
	s_barrier
	s_add_i32 s61, s61, 2
	s_add_u32 s44, s44, 0x100
	s_addc_u32 s45, s45, 0
	s_add_u32 s59, s59, 0x100
	s_addc_u32 s60, s60, 0
	s_cmp_gt_u32 s61, 5
	s_cbranch_scc0 .LBB0_1816
	s_and_b64 vcc, exec, s[24:25]
	s_cbranch_vccz .LBB0_1819
	s_barrier

; #define PG8_STAGE(bufoff, gbase, voff) do { _Pragma("unroll") for (int _i = 0; _i < 2; ++_i) \
;         __builtin_amdgcn_global_load_lds((const unsigned*)((const char*)(gbase) + (voff)[_i]), (PG8_LAS unsigned*)(lds + (bufoff) + ldsw + _i * 8192), 16, 0, 0); } while (0)
; #define PG8_LDA(dst, b, h) do { _Pragma("unroll") for (int m = 0; m < 4; ++m) _Pragma("unroll") for (int k = 0; k < 2; ++k) dst[m][k] = *(const PG8_LAS bf16x8*)(lds + PG8_SA(b, h) + aoff + m * 2048 + k * 1024); } while (0)
; #define PG8_LDB(dst, b, h) do { _Pragma("unroll") for (int n = 0; n < 2; ++n) _Pragma("unroll") for (int k = 0; k < 2; ++k) dst[n][k] = *(const PG8_LAS bf16x8*)(lds + PG8_SB(b, h) + boff + n * 2048 + k * 1024); } while (0)
; #define PG8_MMA(ai, bj, At, Bt) do { __builtin_amdgcn_s_setprio(1); _Pragma("unroll") for (int m = 0; m < 4; ++m) _Pragma("unroll") for (int n = 0; n < 2; ++n) _Pragma("unroll") for (int k = 0; k < 2; ++k) \
;         acc[ai][bj][m][n] = __builtin_amdgcn_mfma_f32_16x16x32_bf16(Bt[n][k], At[m][k], acc[ai][bj][m][n], 0, 0, 0); __builtin_amdgcn_s_setprio(0); } while (0)
; #define PG8_BAR __builtin_amdgcn_s_barrier()
; template <class Epi, class Sched, bool ALIGN_EPI = false, bool SP2 = false>
; __device__ __forceinline__ void gemm_phase(PG8_LAS unsigned char* lds, const Gemm g, const Sched& S, const Epi& E) {
;     ...
;         const bool has_next = S.next(ui + 1, nxt);
;         const char* nA = has_next ? (const char*)g.A + (size_t)nxt.pm * tstep : cA; const char* nB = has_next ? (const char*)g.Bt + (size_t)nxt.pn * tstep : cB;
;         for (int t = 0; t < nt; t += 2) {
;             const bool last = (t == nt - 2);
;             const char* a1 = cA + (size_t)(t + 1) * kstep;
;             const char* a2 = last ? nA : cA + (size_t)(t + 2) * kstep; const char* b2 = last ? nB : cB + (size_t)(t + 2) * kstep;
;             const char* a3 = a2 + kstep; const char* b3 = b2 + kstep;
;             if (last && has_next) S.a_ready(nxt);
;             if constexpr (SP2) {
;             PG8_LDB(B0, 0, 0); PG8_LDB(B1, 0, 1); PG8_SCHED; PG8_LDA(At, 0, 0); PG8_STAGE(PG8_SA(1, 1), a1 + hstep, voffA);
;             PG8_WAIT_V(8); PG8_WAIT_L(0); PG8_BAR; PG8_MMA(0, 0, At, B0); PG8_MMA(0, 1, At, B1); PG8_BAR; PG8_SCHED;
;             PG8_LDA(At, 0, 1); PG8_STAGE(PG8_SB(0, 0), b2, voffB); PG8_STAGE(PG8_SB(0, 1), b2 + hstep, voffB); PG8_STAGE(PG8_SA(0, 0), a2, voffA);
.LBB0_1899:
	s_ashr_i32 s25, s24, 31
	s_lshl_b64 s[26:27], s[24:25], 19
	s_add_u32 s26, s22, s26
	s_addc_u32 s27, s23, s27
	s_and_b64 s[28:29], s[4:5], exec
	s_cselect_b32 s25, s27, s39
	s_cselect_b32 s53, s26, s38
	s_ashr_i32 s13, s12, 31
	s_lshl_b64 s[28:29], s[12:13], 19
	s_add_u32 s28, s3, s28
	s_addc_u32 s29, s14, s29
	s_and_b64 s[42:43], s[4:5], exec
	s_cselect_b32 s13, s29, s41
	s_cselect_b32 s54, s28, s40
	s_add_u32 s38, s38, 0x40080
	s_addc_u32 s39, s39, 0
	s_add_u32 s55, s40, 0x100
	s_addc_u32 s56, s41, 0
	s_mov_b32 s57, -2
	ds_read_b128 v[144:147], v155
	ds_read_b128 v[148:151], v155 offset:1024
	ds_read_b128 v[160:163], v155 offset:2048
	ds_read_b128 v[164:167], v155 offset:3072
	ds_read_b128 v[168:171], v156
	ds_read_b128 v[172:175], v156 offset:1024
	ds_read_b128 v[176:179], v156 offset:2048
	ds_read_b128 v[180:183], v156 offset:3072
	s_add_u32 s40, s38, 0xfffc0080
	s_addc_u32 s41, s39, -1
	s_cmp_eq_u32 s57, 12
	s_cselect_b32 s43, s25, s41
	s_cselect_b32 s42, s53, s40
	s_cselect_b32 s41, s13, s56
	s_cselect_b32 s40, s54, s55
	v_lshl_add_u64 v[218:219], s[38:39], 0, v[136:137]
	s_add_i32 m0, s34, 0xc000
	ds_read_b128 v[184:187], v157
	ds_read_b128 v[188:191], v157 offset:1024
	ds_read_b128 v[192:195], v157 offset:2048
	ds_read_b128 v[196:199], v157 offset:3072
	ds_read_b128 v[200:203], v157 offset:4096
	ds_read_b128 v[206:209], v157 offset:5120
	ds_read_b128 v[210:213], v157 offset:6144
	ds_read_b128 v[214:217], v157 offset:7168
	global_load_lds_dwordx4 v[218:219], off
	v_lshl_add_u64 v[218:219], s[38:39], 0, v[138:139]
	s_add_i32 m0, s34, 0xe000
	s_nop 0
	global_load_lds_dwordx4 v[218:219], off
	s_waitcnt vmcnt(8)
	s_waitcnt lgkmcnt(0)
	s_barrier
	s_setprio 1
	s_waitcnt lgkmcnt(0)
	v_mfma_f32_16x16x32_bf16 v[124:127], v[144:147], v[184:187], 0
	v_mfma_f32_16x16x32_bf16 v[120:123], v[160:163], v[184:187], 0
	v_mfma_f32_16x16x32_bf16 v[108:111], v[144:147], v[192:195], 0
	v_mfma_f32_16x16x32_bf16 v[104:107], v[160:163], v[192:195], 0
	v_mfma_f32_16x16x32_bf16 v[92:95], v[144:147], v[200:203], 0
	v_mfma_f32_16x16x32_bf16 v[88:91], v[160:163], v[200:203], 0
	v_mfma_f32_16x16x32_bf16 v[76:79], v[144:147], v[210:213], 0
	v_mfma_f32_16x16x32_bf16 v[72:75], v[160:163], v[210:213], 0
	v_mfma_f32_16x16x32_bf16 v[124:127], v[148:151], v[188:191], v[124:127]
	v_mfma_f32_16x16x32_bf16 v[120:123], v[164:167], v[188:191], v[120:123]
	v_mfma_f32_16x16x32_bf16 v[108:111], v[148:151], v[196:199], v[108:111]
	v_mfma_f32_16x16x32_bf16 v[104:107], v[164:167], v[196:199], v[104:107]
	v_mfma_f32_16x16x32_bf16 v[92:95], v[148:151], v[206:209], v[92:95]
	v_mfma_f32_16x16x32_bf16 v[88:91], v[164:167], v[206:209], v[88:91]
	v_mfma_f32_16x16x32_bf16 v[76:79], v[148:151], v[214:217], v[76:79]
	v_mfma_f32_16x16x32_bf16 v[72:75], v[164:167], v[214:217], v[72:75]
	s_setprio 0
	s_setprio 1
	v_mfma_f32_16x16x32_bf16 v[116:119], v[168:171], v[184:187], 0
	v_mfma_f32_16x16x32_bf16 v[112:115], v[176:179], v[184:187], 0
	v_mfma_f32_16x16x32_bf16 v[100:103], v[168:171], v[192:195], 0
	v_mfma_f32_16x16x32_bf16 v[96:99], v[176:179], v[192:195], 0
	v_mfma_f32_16x16x32_bf16 v[84:87], v[168:171], v[200:203], 0
	v_mfma_f32_16x16x32_bf16 v[80:83], v[176:179], v[200:203], 0
	v_mfma_f32_16x16x32_bf16 v[68:71], v[168:171], v[210:213], 0
	v_mfma_f32_16x16x32_bf16 v[64:67], v[176:179], v[210:213], 0
	v_mfma_f32_16x16x32_bf16 v[116:119], v[172:175], v[188:191], v[116:119]
	v_mfma_f32_16x16x32_bf16 v[112:115], v[180:183], v[188:191], v[112:115]
	v_mfma_f32_16x16x32_bf16 v[100:103], v[172:175], v[196:199], v[100:103]
	v_mfma_f32_16x16x32_bf16 v[96:99], v[180:183], v[196:199], v[96:99]
	v_mfma_f32_16x16x32_bf16 v[84:87], v[172:175], v[206:209], v[84:87]
	v_mfma_f32_16x16x32_bf16 v[80:83], v[180:183], v[206:209], v[80:83]
	v_mfma_f32_16x16x32_bf16 v[68:71], v[172:175], v[214:217], v[68:71]
	v_mfma_f32_16x16x32_bf16 v[64:67], v[180:183], v[214:217], v[64:67]
	s_setprio 0
	s_barrier
	s_add_i32 s58, s49, s15
	v_lshl_add_u64 v[218:219], s[40:41], 0, v[132:133]
	s_mov_b32 m0, s58
	ds_read_b128 v[184:187], v157 offset:16384
	ds_read_b128 v[188:191], v157 offset:17408
	ds_read_b128 v[192:195], v157 offset:18432
	ds_read_b128 v[196:199], v157 offset:19456
	ds_read_b128 v[200:203], v157 offset:20480
	ds_read_b128 v[206:209], v157 offset:21504
	ds_read_b128 v[210:213], v157 offset:22528
	ds_read_b128 v[214:217], v157 offset:23552
	global_load_lds_dwordx4 v[218:219], off
	s_add_i32 m0, s58, 0x2000
	s_add_u32 s58, s40, 0x40000
	v_lshl_add_u64 v[220:221], s[40:41], 0, v[128:129]
	s_addc_u32 s59, s41, 0
	s_add_i32 s60, s50, s15
	global_load_lds_dwordx4 v[220:221], off
	v_lshl_add_u64 v[222:223], s[58:59], 0, v[132:133]
	s_mov_b32 m0, s60
	global_load_lds_dwordx4 v[222:223], off
	v_lshl_add_u64 v[222:223], s[58:59], 0, v[128:129]
	s_add_i32 m0, s60, 0x2000
	s_nop 0
	global_load_lds_dwordx4 v[222:223], off
	s_waitcnt vmcnt(6)
	s_waitcnt lgkmcnt(0)
	s_barrier
; #define PG8_STAGE(bufoff, gbase, voff) do { _Pragma("unroll") for (int _i = 0; _i < 2; ++_i) \
;         __builtin_amdgcn_global_load_lds((const unsigned*)((const char*)(gbase) + (voff)[_i]), (PG8_LAS unsigned*)(lds + (bufoff) + ldsw + _i * 8192), 16, 0, 0); } while (0)
; #define PG8_LDA(dst, b, h) do { _Pragma("unroll") for (int m = 0; m < 4; ++m) _Pragma("unroll") for (int k = 0; k < 2; ++k) dst[m][k] = *(const PG8_LAS bf16x8*)(lds + PG8_SA(b, h) + aoff + m * 2048 + k * 1024); } while (0)
; #define PG8_LDB(dst, b, h) do { _Pragma("unroll") for (int n = 0; n < 2; ++n) _Pragma("unroll") for (int k = 0; k < 2; ++k) dst[n][k] = *(const PG8_LAS bf16x8*)(lds + PG8_SB(b, h) + boff + n * 2048 + k * 1024); } while (0)
; #define PG8_MMA(ai, bj, At, Bt) do { __builtin_amdgcn_s_setprio(1); _Pragma("unroll") for (int m = 0; m < 4; ++m) _Pragma("unroll") for (int n = 0; n < 2; ++n) _Pragma("unroll") for (int k = 0; k < 2; ++k) \
;         acc[ai][bj][m][n] = __builtin_amdgcn_mfma_f32_16x16x32_bf16(Bt[n][k], At[m][k], acc[ai][bj][m][n], 0, 0, 0); __builtin_amdgcn_s_setprio(0); } while (0)
; #define PG8_WAIT_V(n) asm volatile("s_waitcnt vmcnt(" #n ")" ::: "memory")
; #define PG8_WAIT_L(n) asm volatile("s_waitcnt lgkmcnt(" #n ")" ::: "memory")
; #define PG8_BAR __builtin_amdgcn_s_barrier()
; #define PG8_SCHED __builtin_amdgcn_sched_barrier(0)
; template <class Epi, class Sched, bool ALIGN_EPI = false, bool SP2 = false>
; __device__ __forceinline__ void gemm_phase(PG8_LAS unsigned char* lds, const Gemm g, const Sched& S, const Epi& E) {
;     ...
;             PG8_LDA(At, 0, 1); PG8_STAGE(PG8_SB(0, 0), b2, voffB); PG8_STAGE(PG8_SB(0, 1), b2 + hstep, voffB); PG8_STAGE(PG8_SA(0, 0), a2, voffA);
;             PG8_WAIT_V(8); PG8_WAIT_L(0); PG8_BAR; PG8_MMA(1, 0, At, B0); PG8_MMA(1, 1, At, B1); PG8_BAR; PG8_SCHED;
;             PG8_LDB(B0, 1, 0); PG8_LDB(B1, 1, 1); PG8_SCHED; PG8_LDA(At, 1, 0); PG8_STAGE(PG8_SA(0, 1), a2 + hstep, voffA);
;             PG8_WAIT_V(8); PG8_WAIT_L(0); PG8_BAR; PG8_MMA(0, 0, At, B0); PG8_MMA(0, 1, At, B1); PG8_BAR; PG8_SCHED;
	s_setprio 1
	s_waitcnt lgkmcnt(0)
	v_mfma_f32_16x16x32_bf16 v[60:63], v[144:147], v[184:187], 0
	v_mfma_f32_16x16x32_bf16 v[56:59], v[160:163], v[184:187], 0
	v_mfma_f32_16x16x32_bf16 v[44:47], v[144:147], v[192:195], 0
	v_mfma_f32_16x16x32_bf16 v[40:43], v[160:163], v[192:195], 0
	v_mfma_f32_16x16x32_bf16 v[28:31], v[144:147], v[200:203], 0
	v_mfma_f32_16x16x32_bf16 v[24:27], v[160:163], v[200:203], 0
	v_mfma_f32_16x16x32_bf16 v[12:15], v[144:147], v[210:213], 0
	v_mfma_f32_16x16x32_bf16 v[8:11], v[160:163], v[210:213], 0
	v_mfma_f32_16x16x32_bf16 v[60:63], v[148:151], v[188:191], v[60:63]
	v_mfma_f32_16x16x32_bf16 v[56:59], v[164:167], v[188:191], v[56:59]
	v_mfma_f32_16x16x32_bf16 v[44:47], v[148:151], v[196:199], v[44:47]
	v_mfma_f32_16x16x32_bf16 v[40:43], v[164:167], v[196:199], v[40:43]
	v_lshl_add_u64 v[222:223], s[42:43], 0, v[134:135]
	s_mov_b32 m0, s34
	s_nop 0
	global_load_lds_dwordx4 v[222:223], off
	v_mfma_f32_16x16x32_bf16 v[28:31], v[148:151], v[206:209], v[28:31]
	v_mfma_f32_16x16x32_bf16 v[24:27], v[164:167], v[206:209], v[24:27]
	v_mfma_f32_16x16x32_bf16 v[12:15], v[148:151], v[214:217], v[12:15]
	v_mfma_f32_16x16x32_bf16 v[8:11], v[164:167], v[214:217], v[8:11]
	s_setprio 0
	s_setprio 1
	v_mfma_f32_16x16x32_bf16 v[52:55], v[168:171], v[184:187], 0
	v_mfma_f32_16x16x32_bf16 v[48:51], v[176:179], v[184:187], 0
	v_mfma_f32_16x16x32_bf16 v[36:39], v[168:171], v[192:195], 0
	v_mfma_f32_16x16x32_bf16 v[32:35], v[176:179], v[192:195], 0
	v_mfma_f32_16x16x32_bf16 v[20:23], v[168:171], v[200:203], 0
	v_mfma_f32_16x16x32_bf16 v[16:19], v[176:179], v[200:203], 0
	v_mfma_f32_16x16x32_bf16 v[4:7], v[168:171], v[210:213], 0
	v_mfma_f32_16x16x32_bf16 v[0:3], v[176:179], v[210:213], 0
	v_mfma_f32_16x16x32_bf16 v[52:55], v[172:175], v[188:191], v[52:55]
	v_mfma_f32_16x16x32_bf16 v[48:51], v[180:183], v[188:191], v[48:51]
	v_mfma_f32_16x16x32_bf16 v[36:39], v[172:175], v[196:199], v[36:39]
	v_mfma_f32_16x16x32_bf16 v[32:35], v[180:183], v[196:199], v[32:35]
	v_lshl_add_u64 v[224:225], s[42:43], 0, v[130:131]
	s_mov_b32 m0, s37
	s_nop 0
	global_load_lds_dwordx4 v[224:225], off
	v_mfma_f32_16x16x32_bf16 v[20:23], v[172:175], v[206:209], v[20:23]
	v_mfma_f32_16x16x32_bf16 v[16:19], v[180:183], v[206:209], v[16:19]
	v_mfma_f32_16x16x32_bf16 v[4:7], v[172:175], v[214:217], v[4:7]
	v_mfma_f32_16x16x32_bf16 v[0:3], v[180:183], v[214:217], v[0:3]
	s_setprio 0
	s_barrier
	s_add_i32 s58, 0, 0x18000
	v_add_u32_e32 v159, s58, v153
	s_add_i32 s59, 0, 0x1c000
	ds_read_b128 v[144:147], v159
	ds_read_b128 v[148:151], v159 offset:1024
	ds_read_b128 v[160:163], v159 offset:2048
	ds_read_b128 v[164:167], v159 offset:3072
	v_add_u32_e32 v159, s59, v153
	ds_read_b128 v[168:171], v159
	ds_read_b128 v[172:175], v159 offset:1024
	ds_read_b128 v[176:179], v159 offset:2048
	ds_read_b128 v[180:183], v159 offset:3072
	s_add_u32 s42, s42, 0x40000
	s_addc_u32 s43, s43, 0
	s_mov_b32 m0, s44
	v_lshl_add_u64 v[226:227], s[42:43], 0, v[134:135]
	ds_read_b128 v[184:187], v157 offset:32768
	ds_read_b128 v[188:191], v157 offset:33792
	ds_read_b128 v[192:195], v157 offset:34816
	ds_read_b128 v[196:199], v157 offset:35840
	ds_read_b128 v[200:203], v157 offset:36864
	ds_read_b128 v[206:209], v157 offset:37888
	ds_read_b128 v[210:213], v157 offset:38912
	ds_read_b128 v[214:217], v157 offset:39936
	global_load_lds_dwordx4 v[226:227], off
	v_lshl_add_u64 v[226:227], s[42:43], 0, v[130:131]
	s_mov_b32 m0, s45
	s_nop 0
	global_load_lds_dwordx4 v[226:227], off
	s_waitcnt vmcnt(8)
	s_waitcnt lgkmcnt(0)
	s_barrier
	s_setprio 1
	s_waitcnt lgkmcnt(0)
	v_mfma_f32_16x16x32_bf16 v[124:127], v[144:147], v[184:187], v[124:127]
	v_mfma_f32_16x16x32_bf16 v[120:123], v[160:163], v[184:187], v[120:123]
	v_mfma_f32_16x16x32_bf16 v[108:111], v[144:147], v[192:195], v[108:111]
	v_mfma_f32_16x16x32_bf16 v[104:107], v[160:163], v[192:195], v[104:107]
	v_mfma_f32_16x16x32_bf16 v[92:95], v[144:147], v[200:203], v[92:95]
	v_mfma_f32_16x16x32_bf16 v[88:91], v[160:163], v[200:203], v[88:91]
	v_mfma_f32_16x16x32_bf16 v[76:79], v[144:147], v[210:213], v[76:79]
	v_mfma_f32_16x16x32_bf16 v[72:75], v[160:163], v[210:213], v[72:75]
	v_mfma_f32_16x16x32_bf16 v[124:127], v[148:151], v[188:191], v[124:127]
	v_mfma_f32_16x16x32_bf16 v[120:123], v[164:167], v[188:191], v[120:123]
	v_mfma_f32_16x16x32_bf16 v[108:111], v[148:151], v[196:199], v[108:111]
	v_mfma_f32_16x16x32_bf16 v[104:107], v[164:167], v[196:199], v[104:107]
	v_mfma_f32_16x16x32_bf16 v[92:95], v[148:151], v[206:209], v[92:95]
	v_mfma_f32_16x16x32_bf16 v[88:91], v[164:167], v[206:209], v[88:91]
	v_mfma_f32_16x16x32_bf16 v[76:79], v[148:151], v[214:217], v[76:79]
	v_mfma_f32_16x16x32_bf16 v[72:75], v[164:167], v[214:217], v[72:75]
	s_setprio 0
	s_setprio 1
	v_mfma_f32_16x16x32_bf16 v[116:119], v[168:171], v[184:187], v[116:119]
	v_mfma_f32_16x16x32_bf16 v[112:115], v[176:179], v[184:187], v[112:115]
	v_mfma_f32_16x16x32_bf16 v[100:103], v[168:171], v[192:195], v[100:103]
	v_mfma_f32_16x16x32_bf16 v[96:99], v[176:179], v[192:195], v[96:99]
	v_mfma_f32_16x16x32_bf16 v[84:87], v[168:171], v[200:203], v[84:87]
	v_mfma_f32_16x16x32_bf16 v[80:83], v[176:179], v[200:203], v[80:83]
	v_mfma_f32_16x16x32_bf16 v[68:71], v[168:171], v[210:213], v[68:71]
	v_mfma_f32_16x16x32_bf16 v[64:67], v[176:179], v[210:213], v[64:67]
	v_mfma_f32_16x16x32_bf16 v[116:119], v[172:175], v[188:191], v[116:119]
	v_mfma_f32_16x16x32_bf16 v[112:115], v[180:183], v[188:191], v[112:115]
	v_mfma_f32_16x16x32_bf16 v[100:103], v[172:175], v[196:199], v[100:103]
	v_mfma_f32_16x16x32_bf16 v[96:99], v[180:183], v[196:199], v[96:99]
	v_mfma_f32_16x16x32_bf16 v[84:87], v[172:175], v[206:209], v[84:87]
	v_mfma_f32_16x16x32_bf16 v[80:83], v[180:183], v[206:209], v[80:83]
	v_mfma_f32_16x16x32_bf16 v[68:71], v[172:175], v[214:217], v[68:71]
	v_mfma_f32_16x16x32_bf16 v[64:67], v[180:183], v[214:217], v[64:67]
	s_setprio 0
	s_barrier
; #define PG8_STAGE(bufoff, gbase, voff) do { _Pragma("unroll") for (int _i = 0; _i < 2; ++_i) \
;         __builtin_amdgcn_global_load_lds((const unsigned*)((const char*)(gbase) + (voff)[_i]), (PG8_LAS unsigned*)(lds + (bufoff) + ldsw + _i * 8192), 16, 0, 0); } while (0)
; #define PG8_LDA(dst, b, h) do { _Pragma("unroll") for (int m = 0; m < 4; ++m) _Pragma("unroll") for (int k = 0; k < 2; ++k) dst[m][k] = *(const PG8_LAS bf16x8*)(lds + PG8_SA(b, h) + aoff + m * 2048 + k * 1024); } while (0)
; #define PG8_LDB(dst, b, h) do { _Pragma("unroll") for (int n = 0; n < 2; ++n) _Pragma("unroll") for (int k = 0; k < 2; ++k) dst[n][k] = *(const PG8_LAS bf16x8*)(lds + PG8_SB(b, h) + boff + n * 2048 + k * 1024); } while (0)
; #define PG8_MMA(ai, bj, At, Bt) do { __builtin_amdgcn_s_setprio(1); _Pragma("unroll") for (int m = 0; m < 4; ++m) _Pragma("unroll") for (int n = 0; n < 2; ++n) _Pragma("unroll") for (int k = 0; k < 2; ++k) \
;         acc[ai][bj][m][n] = __builtin_amdgcn_mfma_f32_16x16x32_bf16(Bt[n][k], At[m][k], acc[ai][bj][m][n], 0, 0, 0); __builtin_amdgcn_s_setprio(0); } while (0)
; #define PG8_WAIT_V(n) asm volatile("s_waitcnt vmcnt(" #n ")" ::: "memory")
; template <class Epi, class Sched, bool ALIGN_EPI = false, bool SP2 = false>
; __device__ __forceinline__ void gemm_phase(PG8_LAS unsigned char* lds, const Gemm g, const Sched& S, const Epi& E) {
;     ...
;             PG8_LDB(B0, 0, 0); PG8_LDB(B1, 0, 1); PG8_SCHED; PG8_LDA(At, 0, 0); PG8_STAGE(PG8_SA(1, 1), a1 + hstep, voffA);
;             PG8_WAIT_V(8); PG8_WAIT_L(0); PG8_BAR; PG8_MMA(0, 0, At, B0); PG8_MMA(0, 1, At, B1); PG8_BAR; PG8_SCHED;
;             PG8_LDA(At, 0, 1); PG8_STAGE(PG8_SB(0, 0), b2, voffB); PG8_STAGE(PG8_SB(0, 1), b2 + hstep, voffB); PG8_STAGE(PG8_SA(0, 0), a2, voffA);
;             PG8_WAIT_V(8); PG8_WAIT_L(0); PG8_BAR; PG8_MMA(1, 0, At, B0); PG8_MMA(1, 1, At, B1); PG8_BAR; PG8_SCHED;
;             PG8_LDB(B0, 1, 0); PG8_LDB(B1, 1, 1); PG8_SCHED; PG8_LDA(At, 1, 0); PG8_STAGE(PG8_SA(0, 1), a2 + hstep, voffA);
;             PG8_WAIT_V(8); PG8_WAIT_L(0); PG8_BAR; PG8_MMA(0, 0, At, B0); PG8_MMA(0, 1, At, B1); PG8_BAR; PG8_SCHED;
;             PG8_LDA(At, 1, 1); PG8_STAGE(PG8_SB(1, 0), b3, voffB); PG8_STAGE(PG8_SB(1, 1), b3 + hstep, voffB); PG8_STAGE(PG8_SA(1, 0), a3, voffA);
;             PG8_WAIT_V(8); PG8_WAIT_L(0); PG8_BAR; PG8_MMA(1, 0, At, B0); PG8_MMA(1, 1, At, B1); PG8_BAR; PG8_SCHED;
	s_add_i32 s42, s58, s15
	v_lshl_add_u64 v[218:219], v[218:219], 0, s[8:9]
	s_mov_b32 m0, s42
	ds_read_b128 v[184:187], v157 offset:49152
	ds_read_b128 v[188:191], v157 offset:50176
	ds_read_b128 v[192:195], v157 offset:51200
	ds_read_b128 v[196:199], v157 offset:52224
	ds_read_b128 v[200:203], v157 offset:53248
	ds_read_b128 v[206:209], v157 offset:54272
	ds_read_b128 v[210:213], v157 offset:55296
	ds_read_b128 v[214:217], v157 offset:56320
	global_load_lds_dwordx4 v[218:219], off
	s_add_i32 m0, s42, 0x2000
	s_add_u32 s40, s40, 0x40080
	v_lshl_add_u64 v[218:219], v[220:221], 0, s[8:9]
	s_addc_u32 s41, s41, 0
	s_add_i32 s42, s59, s15
	global_load_lds_dwordx4 v[218:219], off
	v_lshl_add_u64 v[218:219], s[40:41], 0, v[132:133]
	s_mov_b32 m0, s42
	s_nop 0
	global_load_lds_dwordx4 v[218:219], off
	v_lshl_add_u64 v[218:219], s[40:41], 0, v[128:129]
	s_add_i32 m0, s42, 0x2000
	s_nop 0
	global_load_lds_dwordx4 v[218:219], off
	s_waitcnt vmcnt(6)
	s_waitcnt lgkmcnt(0)
	s_barrier
	s_setprio 1
	s_waitcnt lgkmcnt(0)
	v_mfma_f32_16x16x32_bf16 v[60:63], v[144:147], v[184:187], v[60:63]
	v_mfma_f32_16x16x32_bf16 v[56:59], v[160:163], v[184:187], v[56:59]
	v_mfma_f32_16x16x32_bf16 v[44:47], v[144:147], v[192:195], v[44:47]
	v_mfma_f32_16x16x32_bf16 v[40:43], v[160:163], v[192:195], v[40:43]
	v_mfma_f32_16x16x32_bf16 v[28:31], v[144:147], v[200:203], v[28:31]
	v_mfma_f32_16x16x32_bf16 v[24:27], v[160:163], v[200:203], v[24:27]
	v_mfma_f32_16x16x32_bf16 v[12:15], v[144:147], v[210:213], v[12:15]
	v_mfma_f32_16x16x32_bf16 v[8:11], v[160:163], v[210:213], v[8:11]
	v_mfma_f32_16x16x32_bf16 v[60:63], v[148:151], v[188:191], v[60:63]
	v_mfma_f32_16x16x32_bf16 v[56:59], v[164:167], v[188:191], v[56:59]
	v_mfma_f32_16x16x32_bf16 v[44:47], v[148:151], v[196:199], v[44:47]
	v_mfma_f32_16x16x32_bf16 v[40:43], v[164:167], v[196:199], v[40:43]
	v_lshl_add_u64 v[218:219], v[222:223], 0, s[8:9]
	s_mov_b32 m0, s47
	s_nop 0
	global_load_lds_dwordx4 v[218:219], off
	v_mfma_f32_16x16x32_bf16 v[28:31], v[148:151], v[206:209], v[28:31]
	v_mfma_f32_16x16x32_bf16 v[24:27], v[164:167], v[206:209], v[24:27]
	v_mfma_f32_16x16x32_bf16 v[12:15], v[148:151], v[214:217], v[12:15]
	v_mfma_f32_16x16x32_bf16 v[8:11], v[164:167], v[214:217], v[8:11]
	s_setprio 0
	s_setprio 1
	v_mfma_f32_16x16x32_bf16 v[52:55], v[168:171], v[184:187], v[52:55]
	v_mfma_f32_16x16x32_bf16 v[48:51], v[176:179], v[184:187], v[48:51]
	v_mfma_f32_16x16x32_bf16 v[36:39], v[168:171], v[192:195], v[36:39]
	v_mfma_f32_16x16x32_bf16 v[32:35], v[176:179], v[192:195], v[32:35]
	v_mfma_f32_16x16x32_bf16 v[20:23], v[168:171], v[200:203], v[20:23]
	v_mfma_f32_16x16x32_bf16 v[16:19], v[176:179], v[200:203], v[16:19]
	v_mfma_f32_16x16x32_bf16 v[4:7], v[168:171], v[210:213], v[4:7]
	v_mfma_f32_16x16x32_bf16 v[0:3], v[176:179], v[210:213], v[0:3]
	v_mfma_f32_16x16x32_bf16 v[52:55], v[172:175], v[188:191], v[52:55]
	v_mfma_f32_16x16x32_bf16 v[48:51], v[180:183], v[188:191], v[48:51]
	v_mfma_f32_16x16x32_bf16 v[36:39], v[172:175], v[196:199], v[36:39]
	v_mfma_f32_16x16x32_bf16 v[32:35], v[180:183], v[196:199], v[32:35]
	v_lshl_add_u64 v[218:219], v[224:225], 0, s[8:9]
	s_mov_b32 m0, s48
	s_nop 0
	global_load_lds_dwordx4 v[218:219], off
	v_mfma_f32_16x16x32_bf16 v[20:23], v[172:175], v[206:209], v[20:23]
	v_mfma_f32_16x16x32_bf16 v[16:19], v[180:183], v[206:209], v[16:19]
	v_mfma_f32_16x16x32_bf16 v[4:7], v[172:175], v[214:217], v[4:7]
	v_mfma_f32_16x16x32_bf16 v[0:3], v[180:183], v[214:217], v[0:3]
	s_setprio 0
	s_barrier
	s_add_i32 s57, s57, 2
	s_add_u32 s38, s38, 0x100
	s_addc_u32 s39, s39, 0
	s_add_u32 s55, s55, 0x100
	s_addc_u32 s56, s56, 0
.LBB0_1900:
	ds_read_b128 v[144:147], v155
	ds_read_b128 v[148:151], v155 offset:1024
	ds_read_b128 v[160:163], v155 offset:2048
	ds_read_b128 v[164:167], v155 offset:3072
	ds_read_b128 v[168:171], v156
	ds_read_b128 v[172:175], v156 offset:1024
	ds_read_b128 v[176:179], v156 offset:2048
	ds_read_b128 v[180:183], v156 offset:3072
	s_add_u32 s40, s38, 0xfffc0080
	s_addc_u32 s41, s39, -1
	s_cmp_eq_u32 s57, 12
	s_cselect_b32 s43, s25, s41
	s_cselect_b32 s42, s53, s40
	s_cselect_b32 s41, s13, s56
	s_cselect_b32 s40, s54, s55
	v_lshl_add_u64 v[218:219], s[38:39], 0, v[136:137]
	s_add_i32 m0, s34, 0xc000
	ds_read_b128 v[184:187], v157
	ds_read_b128 v[188:191], v157 offset:1024
	ds_read_b128 v[192:195], v157 offset:2048
	ds_read_b128 v[196:199], v157 offset:3072
	ds_read_b128 v[200:203], v157 offset:4096
	ds_read_b128 v[206:209], v157 offset:5120
	ds_read_b128 v[210:213], v157 offset:6144
	ds_read_b128 v[214:217], v157 offset:7168
	global_load_lds_dwordx4 v[218:219], off
	v_lshl_add_u64 v[218:219], s[38:39], 0, v[138:139]
	s_add_i32 m0, s34, 0xe000
	s_nop 0
	global_load_lds_dwordx4 v[218:219], off
	s_waitcnt vmcnt(8)
	s_waitcnt lgkmcnt(0)
	s_barrier
; #define PG8_STAGE(bufoff, gbase, voff) do { _Pragma("unroll") for (int _i = 0; _i < 2; ++_i) \
;         __builtin_amdgcn_global_load_lds((const unsigned*)((const char*)(gbase) + (voff)[_i]), (PG8_LAS unsigned*)(lds + (bufoff) + ldsw + _i * 8192), 16, 0, 0); } while (0)
; #define PG8_LDA(dst, b, h) do { _Pragma("unroll") for (int m = 0; m < 4; ++m) _Pragma("unroll") for (int k = 0; k < 2; ++k) dst[m][k] = *(const PG8_LAS bf16x8*)(lds + PG8_SA(b, h) + aoff + m * 2048 + k * 1024); } while (0)
; #define PG8_LDB(dst, b, h) do { _Pragma("unroll") for (int n = 0; n < 2; ++n) _Pragma("unroll") for (int k = 0; k < 2; ++k) dst[n][k] = *(const PG8_LAS bf16x8*)(lds + PG8_SB(b, h) + boff + n * 2048 + k * 1024); } while (0)
; #define PG8_MMA(ai, bj, At, Bt) do { __builtin_amdgcn_s_setprio(1); _Pragma("unroll") for (int m = 0; m < 4; ++m) _Pragma("unroll") for (int n = 0; n < 2; ++n) _Pragma("unroll") for (int k = 0; k < 2; ++k) \
;         acc[ai][bj][m][n] = __builtin_amdgcn_mfma_f32_16x16x32_bf16(Bt[n][k], At[m][k], acc[ai][bj][m][n], 0, 0, 0); __builtin_amdgcn_s_setprio(0); } while (0)
; #define PG8_WAIT_V(n) asm volatile("s_waitcnt vmcnt(" #n ")" ::: "memory")
; #define PG8_WAIT_L(n) asm volatile("s_waitcnt lgkmcnt(" #n ")" ::: "memory")
; #define PG8_BAR __builtin_amdgcn_s_barrier()
; #define PG8_SCHED __builtin_amdgcn_sched_barrier(0)
; template <class Epi, class Sched, bool ALIGN_EPI = false, bool SP2 = false>
; __device__ __forceinline__ void gemm_phase(PG8_LAS unsigned char* lds, const Gemm g, const Sched& S, const Epi& E) {
;     ...
;             PG8_LDB(B0, 0, 0); PG8_LDB(B1, 0, 1); PG8_SCHED; PG8_LDA(At, 0, 0); PG8_STAGE(PG8_SA(1, 1), a1 + hstep, voffA);
;             PG8_WAIT_V(8); PG8_WAIT_L(0); PG8_BAR; PG8_MMA(0, 0, At, B0); PG8_MMA(0, 1, At, B1); PG8_BAR; PG8_SCHED;
;             PG8_LDA(At, 0, 1); PG8_STAGE(PG8_SB(0, 0), b2, voffB); PG8_STAGE(PG8_SB(0, 1), b2 + hstep, voffB); PG8_STAGE(PG8_SA(0, 0), a2, voffA);
;             PG8_WAIT_V(8); PG8_WAIT_L(0); PG8_BAR; PG8_MMA(1, 0, At, B0); PG8_MMA(1, 1, At, B1); PG8_BAR; PG8_SCHED;
	s_setprio 1
	s_waitcnt lgkmcnt(0)
	v_mfma_f32_16x16x32_bf16 v[124:127], v[144:147], v[184:187], v[124:127]
	v_mfma_f32_16x16x32_bf16 v[120:123], v[160:163], v[184:187], v[120:123]
	v_mfma_f32_16x16x32_bf16 v[108:111], v[144:147], v[192:195], v[108:111]
	v_mfma_f32_16x16x32_bf16 v[104:107], v[160:163], v[192:195], v[104:107]
	v_mfma_f32_16x16x32_bf16 v[92:95], v[144:147], v[200:203], v[92:95]
	v_mfma_f32_16x16x32_bf16 v[88:91], v[160:163], v[200:203], v[88:91]
	v_mfma_f32_16x16x32_bf16 v[76:79], v[144:147], v[210:213], v[76:79]
	v_mfma_f32_16x16x32_bf16 v[72:75], v[160:163], v[210:213], v[72:75]
	v_mfma_f32_16x16x32_bf16 v[124:127], v[148:151], v[188:191], v[124:127]
	v_mfma_f32_16x16x32_bf16 v[120:123], v[164:167], v[188:191], v[120:123]
	v_mfma_f32_16x16x32_bf16 v[108:111], v[148:151], v[196:199], v[108:111]
	v_mfma_f32_16x16x32_bf16 v[104:107], v[164:167], v[196:199], v[104:107]
	v_mfma_f32_16x16x32_bf16 v[92:95], v[148:151], v[206:209], v[92:95]
	v_mfma_f32_16x16x32_bf16 v[88:91], v[164:167], v[206:209], v[88:91]
	v_mfma_f32_16x16x32_bf16 v[76:79], v[148:151], v[214:217], v[76:79]
	v_mfma_f32_16x16x32_bf16 v[72:75], v[164:167], v[214:217], v[72:75]
	s_setprio 0
	s_setprio 1
	v_mfma_f32_16x16x32_bf16 v[116:119], v[168:171], v[184:187], v[116:119]
	v_mfma_f32_16x16x32_bf16 v[112:115], v[176:179], v[184:187], v[112:115]
	v_mfma_f32_16x16x32_bf16 v[100:103], v[168:171], v[192:195], v[100:103]
	v_mfma_f32_16x16x32_bf16 v[96:99], v[176:179], v[192:195], v[96:99]
	v_mfma_f32_16x16x32_bf16 v[84:87], v[168:171], v[200:203], v[84:87]
	v_mfma_f32_16x16x32_bf16 v[80:83], v[176:179], v[200:203], v[80:83]
	v_mfma_f32_16x16x32_bf16 v[68:71], v[168:171], v[210:213], v[68:71]
	v_mfma_f32_16x16x32_bf16 v[64:67], v[176:179], v[210:213], v[64:67]
	v_mfma_f32_16x16x32_bf16 v[116:119], v[172:175], v[188:191], v[116:119]
	v_mfma_f32_16x16x32_bf16 v[112:115], v[180:183], v[188:191], v[112:115]
	v_mfma_f32_16x16x32_bf16 v[100:103], v[172:175], v[196:199], v[100:103]
	v_mfma_f32_16x16x32_bf16 v[96:99], v[180:183], v[196:199], v[96:99]
	v_mfma_f32_16x16x32_bf16 v[84:87], v[172:175], v[206:209], v[84:87]
	v_mfma_f32_16x16x32_bf16 v[80:83], v[180:183], v[206:209], v[80:83]
	v_mfma_f32_16x16x32_bf16 v[68:71], v[172:175], v[214:217], v[68:71]
	v_mfma_f32_16x16x32_bf16 v[64:67], v[180:183], v[214:217], v[64:67]
	s_setprio 0
	s_barrier
	s_add_i32 s58, s49, s15
	v_lshl_add_u64 v[218:219], s[40:41], 0, v[132:133]
	s_mov_b32 m0, s58
	ds_read_b128 v[184:187], v157 offset:16384
	ds_read_b128 v[188:191], v157 offset:17408
	ds_read_b128 v[192:195], v157 offset:18432
	ds_read_b128 v[196:199], v157 offset:19456
	ds_read_b128 v[200:203], v157 offset:20480
	ds_read_b128 v[206:209], v157 offset:21504
	ds_read_b128 v[210:213], v157 offset:22528
	ds_read_b128 v[214:217], v157 offset:23552
	global_load_lds_dwordx4 v[218:219], off
	s_add_i32 m0, s58, 0x2000
	s_add_u32 s58, s40, 0x40000
	v_lshl_add_u64 v[220:221], s[40:41], 0, v[128:129]
	s_addc_u32 s59, s41, 0
	s_add_i32 s60, s50, s15
	global_load_lds_dwordx4 v[220:221], off
	v_lshl_add_u64 v[222:223], s[58:59], 0, v[132:133]
	s_mov_b32 m0, s60
	global_load_lds_dwordx4 v[222:223], off
	v_lshl_add_u64 v[222:223], s[58:59], 0, v[128:129]
	s_add_i32 m0, s60, 0x2000
	s_nop 0
	global_load_lds_dwordx4 v[222:223], off
	s_waitcnt vmcnt(6)
	s_waitcnt lgkmcnt(0)
	s_barrier
	s_setprio 1
	s_waitcnt lgkmcnt(0)
	v_mfma_f32_16x16x32_bf16 v[60:63], v[144:147], v[184:187], v[60:63]
	v_mfma_f32_16x16x32_bf16 v[56:59], v[160:163], v[184:187], v[56:59]
	v_mfma_f32_16x16x32_bf16 v[44:47], v[144:147], v[192:195], v[44:47]
	v_mfma_f32_16x16x32_bf16 v[40:43], v[160:163], v[192:195], v[40:43]
	v_mfma_f32_16x16x32_bf16 v[28:31], v[144:147], v[200:203], v[28:31]
	v_mfma_f32_16x16x32_bf16 v[24:27], v[160:163], v[200:203], v[24:27]
	v_mfma_f32_16x16x32_bf16 v[12:15], v[144:147], v[210:213], v[12:15]
	v_mfma_f32_16x16x32_bf16 v[8:11], v[160:163], v[210:213], v[8:11]
	v_mfma_f32_16x16x32_bf16 v[60:63], v[148:151], v[188:191], v[60:63]
	v_mfma_f32_16x16x32_bf16 v[56:59], v[164:167], v[188:191], v[56:59]
	v_mfma_f32_16x16x32_bf16 v[44:47], v[148:151], v[196:199], v[44:47]
	v_mfma_f32_16x16x32_bf16 v[40:43], v[164:167], v[196:199], v[40:43]
	v_lshl_add_u64 v[222:223], s[42:43], 0, v[134:135]
	s_mov_b32 m0, s34
	s_nop 0
	global_load_lds_dwordx4 v[222:223], off
	v_mfma_f32_16x16x32_bf16 v[28:31], v[148:151], v[206:209], v[28:31]
	v_mfma_f32_16x16x32_bf16 v[24:27], v[164:167], v[206:209], v[24:27]
	v_mfma_f32_16x16x32_bf16 v[12:15], v[148:151], v[214:217], v[12:15]
	v_mfma_f32_16x16x32_bf16 v[8:11], v[164:167], v[214:217], v[8:11]
	s_setprio 0
	s_setprio 1
	v_mfma_f32_16x16x32_bf16 v[52:55], v[168:171], v[184:187], v[52:55]
	v_mfma_f32_16x16x32_bf16 v[48:51], v[176:179], v[184:187], v[48:51]
	v_mfma_f32_16x16x32_bf16 v[36:39], v[168:171], v[192:195], v[36:39]
	v_mfma_f32_16x16x32_bf16 v[32:35], v[176:179], v[192:195], v[32:35]
	v_mfma_f32_16x16x32_bf16 v[20:23], v[168:171], v[200:203], v[20:23]
	v_mfma_f32_16x16x32_bf16 v[16:19], v[176:179], v[200:203], v[16:19]
	v_mfma_f32_16x16x32_bf16 v[4:7], v[168:171], v[210:213], v[4:7]
	v_mfma_f32_16x16x32_bf16 v[0:3], v[176:179], v[210:213], v[0:3]
	v_mfma_f32_16x16x32_bf16 v[52:55], v[172:175], v[188:191], v[52:55]
	v_mfma_f32_16x16x32_bf16 v[48:51], v[180:183], v[188:191], v[48:51]
	v_mfma_f32_16x16x32_bf16 v[36:39], v[172:175], v[196:199], v[36:39]
	v_mfma_f32_16x16x32_bf16 v[32:35], v[180:183], v[196:199], v[32:35]
	v_lshl_add_u64 v[224:225], s[42:43], 0, v[130:131]
	s_mov_b32 m0, s37
	s_nop 0
	global_load_lds_dwordx4 v[224:225], off
	v_mfma_f32_16x16x32_bf16 v[20:23], v[172:175], v[206:209], v[20:23]
	v_mfma_f32_16x16x32_bf16 v[16:19], v[180:183], v[206:209], v[16:19]
	v_mfma_f32_16x16x32_bf16 v[4:7], v[172:175], v[214:217], v[4:7]
	v_mfma_f32_16x16x32_bf16 v[0:3], v[180:183], v[214:217], v[0:3]
	s_setprio 0
	s_barrier
; #define PG8_STAGE(bufoff, gbase, voff) do { _Pragma("unroll") for (int _i = 0; _i < 2; ++_i) \
;         __builtin_amdgcn_global_load_lds((const unsigned*)((const char*)(gbase) + (voff)[_i]), (PG8_LAS unsigned*)(lds + (bufoff) + ldsw + _i * 8192), 16, 0, 0); } while (0)
; #define PG8_LDA(dst, b, h) do { _Pragma("unroll") for (int m = 0; m < 4; ++m) _Pragma("unroll") for (int k = 0; k < 2; ++k) dst[m][k] = *(const PG8_LAS bf16x8*)(lds + PG8_SA(b, h) + aoff + m * 2048 + k * 1024); } while (0)
; #define PG8_LDB(dst, b, h) do { _Pragma("unroll") for (int n = 0; n < 2; ++n) _Pragma("unroll") for (int k = 0; k < 2; ++k) dst[n][k] = *(const PG8_LAS bf16x8*)(lds + PG8_SB(b, h) + boff + n * 2048 + k * 1024); } while (0)
; #define PG8_MMA(ai, bj, At, Bt) do { __builtin_amdgcn_s_setprio(1); _Pragma("unroll") for (int m = 0; m < 4; ++m) _Pragma("unroll") for (int n = 0; n < 2; ++n) _Pragma("unroll") for (int k = 0; k < 2; ++k) \
;         acc[ai][bj][m][n] = __builtin_amdgcn_mfma_f32_16x16x32_bf16(Bt[n][k], At[m][k], acc[ai][bj][m][n], 0, 0, 0); __builtin_amdgcn_s_setprio(0); } while (0)
; #define PG8_WAIT_V(n) asm volatile("s_waitcnt vmcnt(" #n ")" ::: "memory")
; #define PG8_WAIT_L(n) asm volatile("s_waitcnt lgkmcnt(" #n ")" ::: "memory")
; #define PG8_BAR __builtin_amdgcn_s_barrier()
; #define PG8_SCHED __builtin_amdgcn_sched_barrier(0)
; template <class Epi, class Sched, bool ALIGN_EPI = false, bool SP2 = false>
; __device__ __forceinline__ void gemm_phase(PG8_LAS unsigned char* lds, const Gemm g, const Sched& S, const Epi& E) {
;     ...
;             PG8_LDB(B0, 1, 0); PG8_LDB(B1, 1, 1); PG8_SCHED; PG8_LDA(At, 1, 0); PG8_STAGE(PG8_SA(0, 1), a2 + hstep, voffA);
;             PG8_WAIT_V(8); PG8_WAIT_L(0); PG8_BAR; PG8_MMA(0, 0, At, B0); PG8_MMA(0, 1, At, B1); PG8_BAR; PG8_SCHED;
	s_add_i32 s58, 0, 0x18000
	v_add_u32_e32 v159, s58, v153
	s_add_i32 s59, 0, 0x1c000
	ds_read_b128 v[144:147], v159
	ds_read_b128 v[148:151], v159 offset:1024
	ds_read_b128 v[160:163], v159 offset:2048
	ds_read_b128 v[164:167], v159 offset:3072
	v_add_u32_e32 v159, s59, v153
	ds_read_b128 v[168:171], v159
	ds_read_b128 v[172:175], v159 offset:1024
	ds_read_b128 v[176:179], v159 offset:2048
	ds_read_b128 v[180:183], v159 offset:3072
	s_add_u32 s42, s42, 0x40000
	s_addc_u32 s43, s43, 0
	s_mov_b32 m0, s44
	v_lshl_add_u64 v[226:227], s[42:43], 0, v[134:135]
	ds_read_b128 v[184:187], v157 offset:32768
	ds_read_b128 v[188:191], v157 offset:33792
	ds_read_b128 v[192:195], v157 offset:34816
	ds_read_b128 v[196:199], v157 offset:35840
	ds_read_b128 v[200:203], v157 offset:36864
	ds_read_b128 v[206:209], v157 offset:37888
	ds_read_b128 v[210:213], v157 offset:38912
	ds_read_b128 v[214:217], v157 offset:39936
	global_load_lds_dwordx4 v[226:227], off
	v_lshl_add_u64 v[226:227], s[42:43], 0, v[130:131]
	s_mov_b32 m0, s45
	s_nop 0
	global_load_lds_dwordx4 v[226:227], off
	s_waitcnt vmcnt(8)
	s_waitcnt lgkmcnt(0)
	s_barrier
	s_setprio 1
	s_waitcnt lgkmcnt(0)
	v_mfma_f32_16x16x32_bf16 v[124:127], v[144:147], v[184:187], v[124:127]
	v_mfma_f32_16x16x32_bf16 v[120:123], v[160:163], v[184:187], v[120:123]
	v_mfma_f32_16x16x32_bf16 v[108:111], v[144:147], v[192:195], v[108:111]
	v_mfma_f32_16x16x32_bf16 v[104:107], v[160:163], v[192:195], v[104:107]
	v_mfma_f32_16x16x32_bf16 v[92:95], v[144:147], v[200:203], v[92:95]
	v_mfma_f32_16x16x32_bf16 v[88:91], v[160:163], v[200:203], v[88:91]
	v_mfma_f32_16x16x32_bf16 v[76:79], v[144:147], v[210:213], v[76:79]
	v_mfma_f32_16x16x32_bf16 v[72:75], v[160:163], v[210:213], v[72:75]
	v_mfma_f32_16x16x32_bf16 v[124:127], v[148:151], v[188:191], v[124:127]
	v_mfma_f32_16x16x32_bf16 v[120:123], v[164:167], v[188:191], v[120:123]
	v_mfma_f32_16x16x32_bf16 v[108:111], v[148:151], v[196:199], v[108:111]
	v_mfma_f32_16x16x32_bf16 v[104:107], v[164:167], v[196:199], v[104:107]
	v_mfma_f32_16x16x32_bf16 v[92:95], v[148:151], v[206:209], v[92:95]
	v_mfma_f32_16x16x32_bf16 v[88:91], v[164:167], v[206:209], v[88:91]
	v_mfma_f32_16x16x32_bf16 v[76:79], v[148:151], v[214:217], v[76:79]
	v_mfma_f32_16x16x32_bf16 v[72:75], v[164:167], v[214:217], v[72:75]
	s_setprio 0
	s_setprio 1
	v_mfma_f32_16x16x32_bf16 v[116:119], v[168:171], v[184:187], v[116:119]
	v_mfma_f32_16x16x32_bf16 v[112:115], v[176:179], v[184:187], v[112:115]
	v_mfma_f32_16x16x32_bf16 v[100:103], v[168:171], v[192:195], v[100:103]
	v_mfma_f32_16x16x32_bf16 v[96:99], v[176:179], v[192:195], v[96:99]
	v_mfma_f32_16x16x32_bf16 v[84:87], v[168:171], v[200:203], v[84:87]
	v_mfma_f32_16x16x32_bf16 v[80:83], v[176:179], v[200:203], v[80:83]
	v_mfma_f32_16x16x32_bf16 v[68:71], v[168:171], v[210:213], v[68:71]
	v_mfma_f32_16x16x32_bf16 v[64:67], v[176:179], v[210:213], v[64:67]
	v_mfma_f32_16x16x32_bf16 v[116:119], v[172:175], v[188:191], v[116:119]
	v_mfma_f32_16x16x32_bf16 v[112:115], v[180:183], v[188:191], v[112:115]
	v_mfma_f32_16x16x32_bf16 v[100:103], v[172:175], v[196:199], v[100:103]
	v_mfma_f32_16x16x32_bf16 v[96:99], v[180:183], v[196:199], v[96:99]
	v_mfma_f32_16x16x32_bf16 v[84:87], v[172:175], v[206:209], v[84:87]
	v_mfma_f32_16x16x32_bf16 v[80:83], v[180:183], v[206:209], v[80:83]
	v_mfma_f32_16x16x32_bf16 v[68:71], v[172:175], v[214:217], v[68:71]
	v_mfma_f32_16x16x32_bf16 v[64:67], v[180:183], v[214:217], v[64:67]
	s_setprio 0
	s_barrier
; #define PG8_STAGE(bufoff, gbase, voff) do { _Pragma("unroll") for (int _i = 0; _i < 2; ++_i) \
;         __builtin_amdgcn_global_load_lds((const unsigned*)((const char*)(gbase) + (voff)[_i]), (PG8_LAS unsigned*)(lds + (bufoff) + ldsw + _i * 8192), 16, 0, 0); } while (0)
; #define PG8_LDA(dst, b, h) do { _Pragma("unroll") for (int m = 0; m < 4; ++m) _Pragma("unroll") for (int k = 0; k < 2; ++k) dst[m][k] = *(const PG8_LAS bf16x8*)(lds + PG8_SA(b, h) + aoff + m * 2048 + k * 1024); } while (0)
; #define PG8_MMA(ai, bj, At, Bt) do { __builtin_amdgcn_s_setprio(1); _Pragma("unroll") for (int m = 0; m < 4; ++m) _Pragma("unroll") for (int n = 0; n < 2; ++n) _Pragma("unroll") for (int k = 0; k < 2; ++k) \
;         acc[ai][bj][m][n] = __builtin_amdgcn_mfma_f32_16x16x32_bf16(Bt[n][k], At[m][k], acc[ai][bj][m][n], 0, 0, 0); __builtin_amdgcn_s_setprio(0); } while (0)
; #define PG8_WAIT_V(n) asm volatile("s_waitcnt vmcnt(" #n ")" ::: "memory")
; #define PG8_WAIT_L(n) asm volatile("s_waitcnt lgkmcnt(" #n ")" ::: "memory")
; #define PG8_BAR __builtin_amdgcn_s_barrier()
; #define PG8_SCHED __builtin_amdgcn_sched_barrier(0)
; __device__ __forceinline__ float row_rs(const float* ssp, int row) { const unsigned long long v = ((const unsigned long long*)ssp)[row];
;     return __builtin_amdgcn_rsqf((float)v * (1.0f / 4294967296.0f) * (1.0f / 1024.0f) + RMS_EPS); }
; template <class Epi, class Sched, bool ALIGN_EPI = false, bool SP2 = false>
; __device__ __forceinline__ void gemm_phase(PG8_LAS unsigned char* lds, const Gemm g, const Sched& S, const Epi& E) {
;     ...
;             PG8_LDA(At, 1, 1); PG8_STAGE(PG8_SB(1, 0), b3, voffB); PG8_STAGE(PG8_SB(1, 1), b3 + hstep, voffB); PG8_STAGE(PG8_SA(1, 0), a3, voffA);
;             PG8_WAIT_V(8); PG8_WAIT_L(0); PG8_BAR; PG8_MMA(1, 0, At, B0); PG8_MMA(1, 1, At, B1); PG8_BAR; PG8_SCHED;
	s_add_i32 s42, s58, s15
	v_lshl_add_u64 v[218:219], v[218:219], 0, s[8:9]
	s_mov_b32 m0, s42
	ds_read_b128 v[184:187], v157 offset:49152
	ds_read_b128 v[188:191], v157 offset:50176
	ds_read_b128 v[192:195], v157 offset:51200
	ds_read_b128 v[196:199], v157 offset:52224
	ds_read_b128 v[200:203], v157 offset:53248
	ds_read_b128 v[206:209], v157 offset:54272
	ds_read_b128 v[210:213], v157 offset:55296
	ds_read_b128 v[214:217], v157 offset:56320
	global_load_lds_dwordx4 v[218:219], off
	s_add_i32 m0, s42, 0x2000
	s_add_u32 s40, s40, 0x40080
	v_lshl_add_u64 v[218:219], v[220:221], 0, s[8:9]
	s_addc_u32 s41, s41, 0
	s_add_i32 s42, s59, s15
	global_load_lds_dwordx4 v[218:219], off
	v_lshl_add_u64 v[218:219], s[40:41], 0, v[132:133]
	s_mov_b32 m0, s42
	s_nop 0
	global_load_lds_dwordx4 v[218:219], off
	v_lshl_add_u64 v[218:219], s[40:41], 0, v[128:129]
	s_add_i32 m0, s42, 0x2000
	s_nop 0
	global_load_lds_dwordx4 v[218:219], off
	s_waitcnt vmcnt(6)
	s_waitcnt lgkmcnt(0)
	s_barrier
	s_setprio 1
	s_waitcnt lgkmcnt(0)
	v_mfma_f32_16x16x32_bf16 v[60:63], v[144:147], v[184:187], v[60:63]
	v_mfma_f32_16x16x32_bf16 v[56:59], v[160:163], v[184:187], v[56:59]
	v_mfma_f32_16x16x32_bf16 v[44:47], v[144:147], v[192:195], v[44:47]
	v_mfma_f32_16x16x32_bf16 v[40:43], v[160:163], v[192:195], v[40:43]
	v_mfma_f32_16x16x32_bf16 v[28:31], v[144:147], v[200:203], v[28:31]
	v_mfma_f32_16x16x32_bf16 v[24:27], v[160:163], v[200:203], v[24:27]
	v_mfma_f32_16x16x32_bf16 v[12:15], v[144:147], v[210:213], v[12:15]
	v_mfma_f32_16x16x32_bf16 v[8:11], v[160:163], v[210:213], v[8:11]
	v_mfma_f32_16x16x32_bf16 v[60:63], v[148:151], v[188:191], v[60:63]
	v_mfma_f32_16x16x32_bf16 v[56:59], v[164:167], v[188:191], v[56:59]
	v_mfma_f32_16x16x32_bf16 v[44:47], v[148:151], v[196:199], v[44:47]
	v_mfma_f32_16x16x32_bf16 v[40:43], v[164:167], v[196:199], v[40:43]
	v_lshl_add_u64 v[218:219], v[222:223], 0, s[8:9]
	s_mov_b32 m0, s47
	s_nop 0
	global_load_lds_dwordx4 v[218:219], off
	v_mfma_f32_16x16x32_bf16 v[28:31], v[148:151], v[206:209], v[28:31]
	v_mfma_f32_16x16x32_bf16 v[24:27], v[164:167], v[206:209], v[24:27]
	v_mfma_f32_16x16x32_bf16 v[12:15], v[148:151], v[214:217], v[12:15]
	v_mfma_f32_16x16x32_bf16 v[8:11], v[164:167], v[214:217], v[8:11]
	s_setprio 0
	s_setprio 1
	v_mfma_f32_16x16x32_bf16 v[52:55], v[168:171], v[184:187], v[52:55]
	v_mfma_f32_16x16x32_bf16 v[48:51], v[176:179], v[184:187], v[48:51]
	v_mfma_f32_16x16x32_bf16 v[36:39], v[168:171], v[192:195], v[36:39]
	v_mfma_f32_16x16x32_bf16 v[32:35], v[176:179], v[192:195], v[32:35]
	v_mfma_f32_16x16x32_bf16 v[20:23], v[168:171], v[200:203], v[20:23]
	v_mfma_f32_16x16x32_bf16 v[16:19], v[176:179], v[200:203], v[16:19]
	v_mfma_f32_16x16x32_bf16 v[4:7], v[168:171], v[210:213], v[4:7]
	v_mfma_f32_16x16x32_bf16 v[0:3], v[176:179], v[210:213], v[0:3]
	v_mfma_f32_16x16x32_bf16 v[52:55], v[172:175], v[188:191], v[52:55]
	v_mfma_f32_16x16x32_bf16 v[48:51], v[180:183], v[188:191], v[48:51]
	v_mfma_f32_16x16x32_bf16 v[36:39], v[172:175], v[196:199], v[36:39]
	v_mfma_f32_16x16x32_bf16 v[32:35], v[180:183], v[196:199], v[32:35]
	v_lshl_add_u64 v[218:219], v[224:225], 0, s[8:9]
	s_mov_b32 m0, s48
	s_nop 0
	global_load_lds_dwordx4 v[218:219], off
	v_mfma_f32_16x16x32_bf16 v[20:23], v[172:175], v[206:209], v[20:23]
	v_mfma_f32_16x16x32_bf16 v[16:19], v[180:183], v[206:209], v[16:19]
	v_mfma_f32_16x16x32_bf16 v[4:7], v[172:175], v[214:217], v[4:7]
	v_mfma_f32_16x16x32_bf16 v[0:3], v[180:183], v[214:217], v[0:3]
	s_setprio 0
	s_barrier
	s_add_i32 s57, s57, 2
	s_add_u32 s38, s38, 0x100
	s_addc_u32 s39, s39, 0
	s_add_u32 s55, s55, 0x100
	s_addc_u32 s56, s56, 0
	s_cmp_gt_u32 s57, 13
	s_cbranch_scc0 .LBB0_1900
	v_lshl_add_u32 v144, s36, 8, v152
	v_ashrrev_i32_e32 v145, 31, v144
	v_lshl_add_u64 v[150:151], v[144:145], 3, s[0:1]
	global_load_dwordx2 v[182:183], v[150:151], off
	global_load_dwordx2 v[184:185], v[150:151], off offset:128
	global_load_dwordx2 v[186:187], v[150:151], off offset:256
	global_load_dwordx2 v[188:189], v[150:151], off offset:384
	global_load_dwordx2 v[190:191], v[150:151], off offset:1024
	global_load_dwordx2 v[192:193], v[150:151], off offset:1152
	global_load_dwordx2 v[194:195], v[150:151], off offset:1280
	global_load_dwordx2 v[196:197], v[150:151], off offset:1408
	s_and_b64 vcc, exec, s[10:11]
	s_cbranch_vccz .LBB0_1903
	s_barrier

; #define PG8_STAGE(bufoff, gbase, voff) do { _Pragma("unroll") for (int _i = 0; _i < 2; ++_i) \
;         __builtin_amdgcn_global_load_lds((const unsigned*)((const char*)(gbase) + (voff)[_i]), (PG8_LAS unsigned*)(lds + (bufoff) + ldsw + _i * 8192), 16, 0, 0); } while (0)
; #define PG8_LDA(dst, b, h) do { _Pragma("unroll") for (int m = 0; m < 4; ++m) _Pragma("unroll") for (int k = 0; k < 2; ++k) dst[m][k] = *(const PG8_LAS bf16x8*)(lds + PG8_SA(b, h) + aoff + m * 2048 + k * 1024); } while (0)
; #define PG8_LDB(dst, b, h) do { _Pragma("unroll") for (int n = 0; n < 2; ++n) _Pragma("unroll") for (int k = 0; k < 2; ++k) dst[n][k] = *(const PG8_LAS bf16x8*)(lds + PG8_SB(b, h) + boff + n * 2048 + k * 1024); } while (0)
; #define PG8_MMA(ai, bj, At, Bt) do { __builtin_amdgcn_s_setprio(1); _Pragma("unroll") for (int m = 0; m < 4; ++m) _Pragma("unroll") for (int n = 0; n < 2; ++n) _Pragma("unroll") for (int k = 0; k < 2; ++k) \
;         acc[ai][bj][m][n] = __builtin_amdgcn_mfma_f32_16x16x32_bf16(Bt[n][k], At[m][k], acc[ai][bj][m][n], 0, 0, 0); __builtin_amdgcn_s_setprio(0); } while (0)
; #define PG8_BAR __builtin_amdgcn_s_barrier()
; template <class Epi, class Sched, bool ALIGN_EPI = false, bool SP2 = false>
; __device__ __forceinline__ void gemm_phase(PG8_LAS unsigned char* lds, const Gemm g, const Sched& S, const Epi& E) {
;     ...
;         const bool has_next = S.next(ui + 1, nxt);
;         const char* nA = has_next ? (const char*)g.A + (size_t)nxt.pm * tstep : cA; const char* nB = has_next ? (const char*)g.Bt + (size_t)nxt.pn * tstep : cB;
;         for (int t = 0; t < nt; t += 2) {
;             const bool last = (t == nt - 2);
;             const char* a1 = cA + (size_t)(t + 1) * kstep;
;             const char* a2 = last ? nA : cA + (size_t)(t + 2) * kstep; const char* b2 = last ? nB : cB + (size_t)(t + 2) * kstep;
;             const char* a3 = a2 + kstep; const char* b3 = b2 + kstep;
;             if (last && has_next) S.a_ready(nxt);
;             if constexpr (SP2) {
;             PG8_LDB(B0, 0, 0); PG8_LDB(B1, 0, 1); PG8_SCHED; PG8_LDA(At, 0, 0); PG8_STAGE(PG8_SA(1, 1), a1 + hstep, voffA);
;             PG8_WAIT_V(8); PG8_WAIT_L(0); PG8_BAR; PG8_MMA(0, 0, At, B0); PG8_MMA(0, 1, At, B1); PG8_BAR; PG8_SCHED;
;             PG8_LDA(At, 0, 1); PG8_STAGE(PG8_SB(0, 0), b2, voffB); PG8_STAGE(PG8_SB(0, 1), b2 + hstep, voffB); PG8_STAGE(PG8_SA(0, 0), a2, voffA);
.LBB0_1977:
	s_add_u32 s53, s28, 0x100
	s_addc_u32 s54, s29, 0
	s_mov_b32 s55, -2
	s_waitcnt lgkmcnt(0)
	ds_read_b128 v[144:147], v151
	ds_read_b128 v[156:159], v151 offset:1024
	ds_read_b128 v[160:163], v151 offset:2048
	ds_read_b128 v[164:167], v151 offset:3072
	ds_read_b128 v[168:171], v152
	ds_read_b128 v[172:175], v152 offset:1024
	ds_read_b128 v[176:179], v152 offset:2048
	ds_read_b128 v[180:183], v152 offset:3072
	s_add_u32 s28, s26, 0x100
	s_addc_u32 s29, s27, 0
	s_cmp_eq_u32 s55, 40
	s_cselect_b32 s39, s1, s29
	s_cselect_b32 s38, s0, s28
	s_cselect_b32 s37, s25, s54
	s_cselect_b32 s36, s24, s53
	v_lshl_add_u64 v[218:219], s[26:27], 0, v[136:137]
	s_add_i32 m0, s33, 0xc000
	ds_read_b128 v[184:187], v153
	ds_read_b128 v[188:191], v153 offset:1024
	ds_read_b128 v[192:195], v153 offset:2048
	ds_read_b128 v[196:199], v153 offset:3072
	ds_read_b128 v[200:203], v153 offset:4096
	ds_read_b128 v[206:209], v153 offset:5120
	ds_read_b128 v[210:213], v153 offset:6144
	ds_read_b128 v[214:217], v153 offset:7168
	global_load_lds_dwordx4 v[218:219], off
	v_lshl_add_u64 v[218:219], s[26:27], 0, v[138:139]
	s_add_i32 m0, s33, 0xe000
	s_nop 0
	global_load_lds_dwordx4 v[218:219], off
	s_waitcnt vmcnt(8)
	s_waitcnt lgkmcnt(0)
	s_barrier
	s_setprio 1
	s_waitcnt lgkmcnt(0)
	v_mfma_f32_16x16x32_bf16 v[124:127], v[144:147], v[184:187], 0
	v_mfma_f32_16x16x32_bf16 v[120:123], v[160:163], v[184:187], 0
	v_mfma_f32_16x16x32_bf16 v[108:111], v[144:147], v[192:195], 0
	v_mfma_f32_16x16x32_bf16 v[104:107], v[160:163], v[192:195], 0
	v_mfma_f32_16x16x32_bf16 v[92:95], v[144:147], v[200:203], 0
	v_mfma_f32_16x16x32_bf16 v[88:91], v[160:163], v[200:203], 0
	v_mfma_f32_16x16x32_bf16 v[76:79], v[144:147], v[210:213], 0
	v_mfma_f32_16x16x32_bf16 v[72:75], v[160:163], v[210:213], 0
	v_mfma_f32_16x16x32_bf16 v[124:127], v[156:159], v[188:191], v[124:127]
	v_mfma_f32_16x16x32_bf16 v[120:123], v[164:167], v[188:191], v[120:123]
	v_mfma_f32_16x16x32_bf16 v[108:111], v[156:159], v[196:199], v[108:111]
	v_mfma_f32_16x16x32_bf16 v[104:107], v[164:167], v[196:199], v[104:107]
	v_mfma_f32_16x16x32_bf16 v[92:95], v[156:159], v[206:209], v[92:95]
	v_mfma_f32_16x16x32_bf16 v[88:91], v[164:167], v[206:209], v[88:91]
	v_mfma_f32_16x16x32_bf16 v[76:79], v[156:159], v[214:217], v[76:79]
	v_mfma_f32_16x16x32_bf16 v[72:75], v[164:167], v[214:217], v[72:75]
	s_setprio 0
	s_setprio 1
	v_mfma_f32_16x16x32_bf16 v[116:119], v[168:171], v[184:187], 0
	v_mfma_f32_16x16x32_bf16 v[112:115], v[176:179], v[184:187], 0
	v_mfma_f32_16x16x32_bf16 v[100:103], v[168:171], v[192:195], 0
	v_mfma_f32_16x16x32_bf16 v[96:99], v[176:179], v[192:195], 0
	v_mfma_f32_16x16x32_bf16 v[84:87], v[168:171], v[200:203], 0
	v_mfma_f32_16x16x32_bf16 v[80:83], v[176:179], v[200:203], 0
	v_mfma_f32_16x16x32_bf16 v[68:71], v[168:171], v[210:213], 0
	v_mfma_f32_16x16x32_bf16 v[64:67], v[176:179], v[210:213], 0
	v_mfma_f32_16x16x32_bf16 v[116:119], v[172:175], v[188:191], v[116:119]
	v_mfma_f32_16x16x32_bf16 v[112:115], v[180:183], v[188:191], v[112:115]
	v_mfma_f32_16x16x32_bf16 v[100:103], v[172:175], v[196:199], v[100:103]
	v_mfma_f32_16x16x32_bf16 v[96:99], v[180:183], v[196:199], v[96:99]
	v_mfma_f32_16x16x32_bf16 v[84:87], v[172:175], v[206:209], v[84:87]
	v_mfma_f32_16x16x32_bf16 v[80:83], v[180:183], v[206:209], v[80:83]
	v_mfma_f32_16x16x32_bf16 v[68:71], v[172:175], v[214:217], v[68:71]
	v_mfma_f32_16x16x32_bf16 v[64:67], v[180:183], v[214:217], v[64:67]
	s_setprio 0
	s_barrier
	s_add_i32 s26, s45, s15
	v_lshl_add_u64 v[218:219], s[36:37], 0, v[130:131]
	s_mov_b32 m0, s26
	ds_read_b128 v[184:187], v153 offset:16384
	ds_read_b128 v[188:191], v153 offset:17408
	ds_read_b128 v[192:195], v153 offset:18432
	ds_read_b128 v[196:199], v153 offset:19456
	ds_read_b128 v[200:203], v153 offset:20480
	ds_read_b128 v[206:209], v153 offset:21504
	ds_read_b128 v[210:213], v153 offset:22528
	ds_read_b128 v[214:217], v153 offset:23552
	global_load_lds_dwordx4 v[218:219], off
	s_add_i32 m0, s26, 0x2000
	s_add_u32 s26, s36, 0xb0000
	v_lshl_add_u64 v[220:221], s[36:37], 0, v[134:135]
	s_addc_u32 s27, s37, 0
	s_add_i32 s56, s46, s15
	global_load_lds_dwordx4 v[220:221], off
	v_lshl_add_u64 v[222:223], s[26:27], 0, v[130:131]
	s_mov_b32 m0, s56
	global_load_lds_dwordx4 v[222:223], off
	v_lshl_add_u64 v[222:223], s[26:27], 0, v[134:135]
	s_add_i32 m0, s56, 0x2000
	s_nop 0
	global_load_lds_dwordx4 v[222:223], off
	s_waitcnt vmcnt(6)
	s_waitcnt lgkmcnt(0)
	s_barrier
; #define PG8_STAGE(bufoff, gbase, voff) do { _Pragma("unroll") for (int _i = 0; _i < 2; ++_i) \
;         __builtin_amdgcn_global_load_lds((const unsigned*)((const char*)(gbase) + (voff)[_i]), (PG8_LAS unsigned*)(lds + (bufoff) + ldsw + _i * 8192), 16, 0, 0); } while (0)
; #define PG8_LDA(dst, b, h) do { _Pragma("unroll") for (int m = 0; m < 4; ++m) _Pragma("unroll") for (int k = 0; k < 2; ++k) dst[m][k] = *(const PG8_LAS bf16x8*)(lds + PG8_SA(b, h) + aoff + m * 2048 + k * 1024); } while (0)
; #define PG8_LDB(dst, b, h) do { _Pragma("unroll") for (int n = 0; n < 2; ++n) _Pragma("unroll") for (int k = 0; k < 2; ++k) dst[n][k] = *(const PG8_LAS bf16x8*)(lds + PG8_SB(b, h) + boff + n * 2048 + k * 1024); } while (0)
; #define PG8_MMA(ai, bj, At, Bt) do { __builtin_amdgcn_s_setprio(1); _Pragma("unroll") for (int m = 0; m < 4; ++m) _Pragma("unroll") for (int n = 0; n < 2; ++n) _Pragma("unroll") for (int k = 0; k < 2; ++k) \
;         acc[ai][bj][m][n] = __builtin_amdgcn_mfma_f32_16x16x32_bf16(Bt[n][k], At[m][k], acc[ai][bj][m][n], 0, 0, 0); __builtin_amdgcn_s_setprio(0); } while (0)
; #define PG8_WAIT_V(n) asm volatile("s_waitcnt vmcnt(" #n ")" ::: "memory")
; #define PG8_WAIT_L(n) asm volatile("s_waitcnt lgkmcnt(" #n ")" ::: "memory")
; #define PG8_BAR __builtin_amdgcn_s_barrier()
; #define PG8_SCHED __builtin_amdgcn_sched_barrier(0)
; template <class Epi, class Sched, bool ALIGN_EPI = false, bool SP2 = false>
; __device__ __forceinline__ void gemm_phase(PG8_LAS unsigned char* lds, const Gemm g, const Sched& S, const Epi& E) {
;     ...
;             PG8_LDA(At, 0, 1); PG8_STAGE(PG8_SB(0, 0), b2, voffB); PG8_STAGE(PG8_SB(0, 1), b2 + hstep, voffB); PG8_STAGE(PG8_SA(0, 0), a2, voffA);
;             PG8_WAIT_V(8); PG8_WAIT_L(0); PG8_BAR; PG8_MMA(1, 0, At, B0); PG8_MMA(1, 1, At, B1); PG8_BAR; PG8_SCHED;
;             PG8_LDB(B0, 1, 0); PG8_LDB(B1, 1, 1); PG8_SCHED; PG8_LDA(At, 1, 0); PG8_STAGE(PG8_SA(0, 1), a2 + hstep, voffA);
;             PG8_WAIT_V(8); PG8_WAIT_L(0); PG8_BAR; PG8_MMA(0, 0, At, B0); PG8_MMA(0, 1, At, B1); PG8_BAR; PG8_SCHED;
	s_setprio 1
	s_waitcnt lgkmcnt(0)
	v_mfma_f32_16x16x32_bf16 v[60:63], v[144:147], v[184:187], 0
	v_mfma_f32_16x16x32_bf16 v[56:59], v[160:163], v[184:187], 0
	v_mfma_f32_16x16x32_bf16 v[44:47], v[144:147], v[192:195], 0
	v_mfma_f32_16x16x32_bf16 v[40:43], v[160:163], v[192:195], 0
	v_mfma_f32_16x16x32_bf16 v[28:31], v[144:147], v[200:203], 0
	v_mfma_f32_16x16x32_bf16 v[24:27], v[160:163], v[200:203], 0
	v_mfma_f32_16x16x32_bf16 v[12:15], v[144:147], v[210:213], 0
	v_mfma_f32_16x16x32_bf16 v[8:11], v[160:163], v[210:213], 0
	v_mfma_f32_16x16x32_bf16 v[60:63], v[156:159], v[188:191], v[60:63]
	v_mfma_f32_16x16x32_bf16 v[56:59], v[164:167], v[188:191], v[56:59]
	v_mfma_f32_16x16x32_bf16 v[44:47], v[156:159], v[196:199], v[44:47]
	v_mfma_f32_16x16x32_bf16 v[40:43], v[164:167], v[196:199], v[40:43]
	v_lshl_add_u64 v[222:223], s[38:39], 0, v[128:129]
	s_mov_b32 m0, s33
	s_nop 0
	global_load_lds_dwordx4 v[222:223], off
	v_mfma_f32_16x16x32_bf16 v[28:31], v[156:159], v[206:209], v[28:31]
	v_mfma_f32_16x16x32_bf16 v[24:27], v[164:167], v[206:209], v[24:27]
	v_mfma_f32_16x16x32_bf16 v[12:15], v[156:159], v[214:217], v[12:15]
	v_mfma_f32_16x16x32_bf16 v[8:11], v[164:167], v[214:217], v[8:11]
	s_setprio 0
	s_setprio 1
	v_mfma_f32_16x16x32_bf16 v[52:55], v[168:171], v[184:187], 0
	v_mfma_f32_16x16x32_bf16 v[48:51], v[176:179], v[184:187], 0
	v_mfma_f32_16x16x32_bf16 v[36:39], v[168:171], v[192:195], 0
	v_mfma_f32_16x16x32_bf16 v[32:35], v[176:179], v[192:195], 0
	v_mfma_f32_16x16x32_bf16 v[20:23], v[168:171], v[200:203], 0
	v_mfma_f32_16x16x32_bf16 v[16:19], v[176:179], v[200:203], 0
	v_mfma_f32_16x16x32_bf16 v[4:7], v[168:171], v[210:213], 0
	v_mfma_f32_16x16x32_bf16 v[0:3], v[176:179], v[210:213], 0
	v_mfma_f32_16x16x32_bf16 v[52:55], v[172:175], v[188:191], v[52:55]
	v_mfma_f32_16x16x32_bf16 v[48:51], v[180:183], v[188:191], v[48:51]
	v_mfma_f32_16x16x32_bf16 v[36:39], v[172:175], v[196:199], v[36:39]
	v_mfma_f32_16x16x32_bf16 v[32:35], v[180:183], v[196:199], v[32:35]
	v_lshl_add_u64 v[224:225], s[38:39], 0, v[132:133]
	s_mov_b32 m0, s34
	s_nop 0
	global_load_lds_dwordx4 v[224:225], off
	v_mfma_f32_16x16x32_bf16 v[20:23], v[172:175], v[206:209], v[20:23]
	v_mfma_f32_16x16x32_bf16 v[16:19], v[180:183], v[206:209], v[16:19]
	v_mfma_f32_16x16x32_bf16 v[4:7], v[172:175], v[214:217], v[4:7]
	v_mfma_f32_16x16x32_bf16 v[0:3], v[180:183], v[214:217], v[0:3]
	s_setprio 0
	s_barrier
	s_add_i32 s56, 0, 0x18000
	v_add_u32_e32 v155, s56, v149
	s_add_i32 s57, 0, 0x1c000
	ds_read_b128 v[144:147], v155
	ds_read_b128 v[156:159], v155 offset:1024
	ds_read_b128 v[160:163], v155 offset:2048
	ds_read_b128 v[164:167], v155 offset:3072
	v_add_u32_e32 v155, s57, v149
	ds_read_b128 v[168:171], v155
	ds_read_b128 v[172:175], v155 offset:1024
	ds_read_b128 v[176:179], v155 offset:2048
	ds_read_b128 v[180:183], v155 offset:3072
	s_add_u32 s26, s38, 0xb0000
	s_addc_u32 s27, s39, 0
	s_mov_b32 m0, s40
	v_lshl_add_u64 v[226:227], s[26:27], 0, v[128:129]
	ds_read_b128 v[184:187], v153 offset:32768
	ds_read_b128 v[188:191], v153 offset:33792
	ds_read_b128 v[192:195], v153 offset:34816
	ds_read_b128 v[196:199], v153 offset:35840
	ds_read_b128 v[200:203], v153 offset:36864
	ds_read_b128 v[206:209], v153 offset:37888
	ds_read_b128 v[210:213], v153 offset:38912
	ds_read_b128 v[214:217], v153 offset:39936
	global_load_lds_dwordx4 v[226:227], off
	v_lshl_add_u64 v[226:227], s[26:27], 0, v[132:133]
	s_mov_b32 m0, s41
	s_nop 0
	global_load_lds_dwordx4 v[226:227], off
	s_waitcnt vmcnt(8)
	s_waitcnt lgkmcnt(0)
	s_barrier
	s_setprio 1
	s_waitcnt lgkmcnt(0)
	v_mfma_f32_16x16x32_bf16 v[124:127], v[144:147], v[184:187], v[124:127]
	v_mfma_f32_16x16x32_bf16 v[120:123], v[160:163], v[184:187], v[120:123]
	v_mfma_f32_16x16x32_bf16 v[108:111], v[144:147], v[192:195], v[108:111]
	v_mfma_f32_16x16x32_bf16 v[104:107], v[160:163], v[192:195], v[104:107]
	v_mfma_f32_16x16x32_bf16 v[92:95], v[144:147], v[200:203], v[92:95]
	v_mfma_f32_16x16x32_bf16 v[88:91], v[160:163], v[200:203], v[88:91]
	v_mfma_f32_16x16x32_bf16 v[76:79], v[144:147], v[210:213], v[76:79]
	v_mfma_f32_16x16x32_bf16 v[72:75], v[160:163], v[210:213], v[72:75]
	v_mfma_f32_16x16x32_bf16 v[124:127], v[156:159], v[188:191], v[124:127]
	v_mfma_f32_16x16x32_bf16 v[120:123], v[164:167], v[188:191], v[120:123]
	v_mfma_f32_16x16x32_bf16 v[108:111], v[156:159], v[196:199], v[108:111]
	v_mfma_f32_16x16x32_bf16 v[104:107], v[164:167], v[196:199], v[104:107]
	v_mfma_f32_16x16x32_bf16 v[92:95], v[156:159], v[206:209], v[92:95]
	v_mfma_f32_16x16x32_bf16 v[88:91], v[164:167], v[206:209], v[88:91]
	v_mfma_f32_16x16x32_bf16 v[76:79], v[156:159], v[214:217], v[76:79]
	v_mfma_f32_16x16x32_bf16 v[72:75], v[164:167], v[214:217], v[72:75]
	s_setprio 0
	s_setprio 1
	v_mfma_f32_16x16x32_bf16 v[116:119], v[168:171], v[184:187], v[116:119]
	v_mfma_f32_16x16x32_bf16 v[112:115], v[176:179], v[184:187], v[112:115]
	v_mfma_f32_16x16x32_bf16 v[100:103], v[168:171], v[192:195], v[100:103]
	v_mfma_f32_16x16x32_bf16 v[96:99], v[176:179], v[192:195], v[96:99]
	v_mfma_f32_16x16x32_bf16 v[84:87], v[168:171], v[200:203], v[84:87]
	v_mfma_f32_16x16x32_bf16 v[80:83], v[176:179], v[200:203], v[80:83]
	v_mfma_f32_16x16x32_bf16 v[68:71], v[168:171], v[210:213], v[68:71]
	v_mfma_f32_16x16x32_bf16 v[64:67], v[176:179], v[210:213], v[64:67]
	v_mfma_f32_16x16x32_bf16 v[116:119], v[172:175], v[188:191], v[116:119]
	v_mfma_f32_16x16x32_bf16 v[112:115], v[180:183], v[188:191], v[112:115]
	v_mfma_f32_16x16x32_bf16 v[100:103], v[172:175], v[196:199], v[100:103]
	v_mfma_f32_16x16x32_bf16 v[96:99], v[180:183], v[196:199], v[96:99]
	v_mfma_f32_16x16x32_bf16 v[84:87], v[172:175], v[206:209], v[84:87]
	v_mfma_f32_16x16x32_bf16 v[80:83], v[180:183], v[206:209], v[80:83]
	v_mfma_f32_16x16x32_bf16 v[68:71], v[172:175], v[214:217], v[68:71]
	v_mfma_f32_16x16x32_bf16 v[64:67], v[180:183], v[214:217], v[64:67]
	s_setprio 0
	s_barrier
; #define PG8_STAGE(bufoff, gbase, voff) do { _Pragma("unroll") for (int _i = 0; _i < 2; ++_i) \
;         __builtin_amdgcn_global_load_lds((const unsigned*)((const char*)(gbase) + (voff)[_i]), (PG8_LAS unsigned*)(lds + (bufoff) + ldsw + _i * 8192), 16, 0, 0); } while (0)
; #define PG8_LDA(dst, b, h) do { _Pragma("unroll") for (int m = 0; m < 4; ++m) _Pragma("unroll") for (int k = 0; k < 2; ++k) dst[m][k] = *(const PG8_LAS bf16x8*)(lds + PG8_SA(b, h) + aoff + m * 2048 + k * 1024); } while (0)
; #define PG8_LDB(dst, b, h) do { _Pragma("unroll") for (int n = 0; n < 2; ++n) _Pragma("unroll") for (int k = 0; k < 2; ++k) dst[n][k] = *(const PG8_LAS bf16x8*)(lds + PG8_SB(b, h) + boff + n * 2048 + k * 1024); } while (0)
; #define PG8_MMA(ai, bj, At, Bt) do { __builtin_amdgcn_s_setprio(1); _Pragma("unroll") for (int m = 0; m < 4; ++m) _Pragma("unroll") for (int n = 0; n < 2; ++n) _Pragma("unroll") for (int k = 0; k < 2; ++k) \
;         acc[ai][bj][m][n] = __builtin_amdgcn_mfma_f32_16x16x32_bf16(Bt[n][k], At[m][k], acc[ai][bj][m][n], 0, 0, 0); __builtin_amdgcn_s_setprio(0); } while (0)
; #define PG8_WAIT_V(n) asm volatile("s_waitcnt vmcnt(" #n ")" ::: "memory")
; template <class Epi, class Sched, bool ALIGN_EPI = false, bool SP2 = false>
; __device__ __forceinline__ void gemm_phase(PG8_LAS unsigned char* lds, const Gemm g, const Sched& S, const Epi& E) {
;     ...
;             PG8_LDB(B0, 0, 0); PG8_LDB(B1, 0, 1); PG8_SCHED; PG8_LDA(At, 0, 0); PG8_STAGE(PG8_SA(1, 1), a1 + hstep, voffA);
;             PG8_WAIT_V(8); PG8_WAIT_L(0); PG8_BAR; PG8_MMA(0, 0, At, B0); PG8_MMA(0, 1, At, B1); PG8_BAR; PG8_SCHED;
;             PG8_LDA(At, 0, 1); PG8_STAGE(PG8_SB(0, 0), b2, voffB); PG8_STAGE(PG8_SB(0, 1), b2 + hstep, voffB); PG8_STAGE(PG8_SA(0, 0), a2, voffA);
;             PG8_WAIT_V(8); PG8_WAIT_L(0); PG8_BAR; PG8_MMA(1, 0, At, B0); PG8_MMA(1, 1, At, B1); PG8_BAR; PG8_SCHED;
;             PG8_LDB(B0, 1, 0); PG8_LDB(B1, 1, 1); PG8_SCHED; PG8_LDA(At, 1, 0); PG8_STAGE(PG8_SA(0, 1), a2 + hstep, voffA);
;             PG8_WAIT_V(8); PG8_WAIT_L(0); PG8_BAR; PG8_MMA(0, 0, At, B0); PG8_MMA(0, 1, At, B1); PG8_BAR; PG8_SCHED;
;             PG8_LDA(At, 1, 1); PG8_STAGE(PG8_SB(1, 0), b3, voffB); PG8_STAGE(PG8_SB(1, 1), b3 + hstep, voffB); PG8_STAGE(PG8_SA(1, 0), a3, voffA);
;             PG8_WAIT_V(8); PG8_WAIT_L(0); PG8_BAR; PG8_MMA(1, 0, At, B0); PG8_MMA(1, 1, At, B1); PG8_BAR; PG8_SCHED;
	s_add_i32 s26, s56, s15
	v_lshl_add_u64 v[218:219], v[218:219], 0, s[12:13]
	s_mov_b32 m0, s26
	ds_read_b128 v[184:187], v153 offset:49152
	ds_read_b128 v[188:191], v153 offset:50176
	ds_read_b128 v[192:195], v153 offset:51200
	ds_read_b128 v[196:199], v153 offset:52224
	ds_read_b128 v[200:203], v153 offset:53248
	ds_read_b128 v[206:209], v153 offset:54272
	ds_read_b128 v[210:213], v153 offset:55296
	ds_read_b128 v[214:217], v153 offset:56320
	global_load_lds_dwordx4 v[218:219], off
	s_add_i32 m0, s26, 0x2000
	s_add_u32 s26, s36, 0xb0080
	v_lshl_add_u64 v[218:219], v[220:221], 0, s[12:13]
	s_addc_u32 s27, s37, 0
	s_add_i32 s36, s57, s15
	global_load_lds_dwordx4 v[218:219], off
	v_lshl_add_u64 v[218:219], s[26:27], 0, v[130:131]
	s_mov_b32 m0, s36
	s_nop 0
	global_load_lds_dwordx4 v[218:219], off
	v_lshl_add_u64 v[218:219], s[26:27], 0, v[134:135]
	s_add_i32 m0, s36, 0x2000
	s_nop 0
	global_load_lds_dwordx4 v[218:219], off
	s_waitcnt vmcnt(6)
	s_waitcnt lgkmcnt(0)
	s_barrier
	s_setprio 1
	s_waitcnt lgkmcnt(0)
	v_mfma_f32_16x16x32_bf16 v[60:63], v[144:147], v[184:187], v[60:63]
	v_mfma_f32_16x16x32_bf16 v[56:59], v[160:163], v[184:187], v[56:59]
	v_mfma_f32_16x16x32_bf16 v[44:47], v[144:147], v[192:195], v[44:47]
	v_mfma_f32_16x16x32_bf16 v[40:43], v[160:163], v[192:195], v[40:43]
	v_mfma_f32_16x16x32_bf16 v[28:31], v[144:147], v[200:203], v[28:31]
	v_mfma_f32_16x16x32_bf16 v[24:27], v[160:163], v[200:203], v[24:27]
	v_mfma_f32_16x16x32_bf16 v[12:15], v[144:147], v[210:213], v[12:15]
	v_mfma_f32_16x16x32_bf16 v[8:11], v[160:163], v[210:213], v[8:11]
	v_mfma_f32_16x16x32_bf16 v[60:63], v[156:159], v[188:191], v[60:63]
	v_mfma_f32_16x16x32_bf16 v[56:59], v[164:167], v[188:191], v[56:59]
	v_mfma_f32_16x16x32_bf16 v[44:47], v[156:159], v[196:199], v[44:47]
	v_mfma_f32_16x16x32_bf16 v[40:43], v[164:167], v[196:199], v[40:43]
	v_lshl_add_u64 v[218:219], v[222:223], 0, s[12:13]
	s_mov_b32 m0, s43
	s_nop 0
	global_load_lds_dwordx4 v[218:219], off
	v_mfma_f32_16x16x32_bf16 v[28:31], v[156:159], v[206:209], v[28:31]
	v_mfma_f32_16x16x32_bf16 v[24:27], v[164:167], v[206:209], v[24:27]
	v_mfma_f32_16x16x32_bf16 v[12:15], v[156:159], v[214:217], v[12:15]
	v_mfma_f32_16x16x32_bf16 v[8:11], v[164:167], v[214:217], v[8:11]
	s_setprio 0
	s_setprio 1
	v_mfma_f32_16x16x32_bf16 v[52:55], v[168:171], v[184:187], v[52:55]
	v_mfma_f32_16x16x32_bf16 v[48:51], v[176:179], v[184:187], v[48:51]
	v_mfma_f32_16x16x32_bf16 v[36:39], v[168:171], v[192:195], v[36:39]
	v_mfma_f32_16x16x32_bf16 v[32:35], v[176:179], v[192:195], v[32:35]
	v_mfma_f32_16x16x32_bf16 v[20:23], v[168:171], v[200:203], v[20:23]
	v_mfma_f32_16x16x32_bf16 v[16:19], v[176:179], v[200:203], v[16:19]
	v_mfma_f32_16x16x32_bf16 v[4:7], v[168:171], v[210:213], v[4:7]
	v_mfma_f32_16x16x32_bf16 v[0:3], v[176:179], v[210:213], v[0:3]
	v_mfma_f32_16x16x32_bf16 v[52:55], v[172:175], v[188:191], v[52:55]
	v_mfma_f32_16x16x32_bf16 v[48:51], v[180:183], v[188:191], v[48:51]
	v_mfma_f32_16x16x32_bf16 v[36:39], v[172:175], v[196:199], v[36:39]
	v_mfma_f32_16x16x32_bf16 v[32:35], v[180:183], v[196:199], v[32:35]
	v_lshl_add_u64 v[218:219], v[224:225], 0, s[12:13]
	s_mov_b32 m0, s44
	s_nop 0
	global_load_lds_dwordx4 v[218:219], off
	v_mfma_f32_16x16x32_bf16 v[20:23], v[172:175], v[206:209], v[20:23]
	v_mfma_f32_16x16x32_bf16 v[16:19], v[180:183], v[206:209], v[16:19]
	v_mfma_f32_16x16x32_bf16 v[4:7], v[172:175], v[214:217], v[4:7]
	v_mfma_f32_16x16x32_bf16 v[0:3], v[180:183], v[214:217], v[0:3]
	s_setprio 0
	s_barrier
	s_add_i32 s55, s55, 2
	s_add_u32 s53, s53, 0x100
	s_addc_u32 s54, s54, 0
	s_mov_b64 s[26:27], s[28:29]
.LBB0_1978:
	ds_read_b128 v[144:147], v151
	ds_read_b128 v[156:159], v151 offset:1024
	ds_read_b128 v[160:163], v151 offset:2048
	ds_read_b128 v[164:167], v151 offset:3072
	ds_read_b128 v[168:171], v152
	ds_read_b128 v[172:175], v152 offset:1024
	ds_read_b128 v[176:179], v152 offset:2048
	ds_read_b128 v[180:183], v152 offset:3072
	s_add_u32 s28, s26, 0x100
	s_addc_u32 s29, s27, 0
	s_cmp_eq_u32 s55, 40
	s_cselect_b32 s39, s1, s29
	s_cselect_b32 s38, s0, s28
	s_cselect_b32 s37, s25, s54
	s_cselect_b32 s36, s24, s53
	v_lshl_add_u64 v[218:219], s[26:27], 0, v[136:137]
	s_add_i32 m0, s33, 0xc000
	ds_read_b128 v[184:187], v153
	ds_read_b128 v[188:191], v153 offset:1024
	ds_read_b128 v[192:195], v153 offset:2048
	ds_read_b128 v[196:199], v153 offset:3072
	ds_read_b128 v[200:203], v153 offset:4096
	ds_read_b128 v[206:209], v153 offset:5120
	ds_read_b128 v[210:213], v153 offset:6144
	ds_read_b128 v[214:217], v153 offset:7168
	global_load_lds_dwordx4 v[218:219], off
	v_lshl_add_u64 v[218:219], s[26:27], 0, v[138:139]
	s_add_i32 m0, s33, 0xe000
	s_nop 0
	global_load_lds_dwordx4 v[218:219], off
	s_waitcnt vmcnt(8)
	s_waitcnt lgkmcnt(0)
	s_barrier
; #define PG8_STAGE(bufoff, gbase, voff) do { _Pragma("unroll") for (int _i = 0; _i < 2; ++_i) \
;         __builtin_amdgcn_global_load_lds((const unsigned*)((const char*)(gbase) + (voff)[_i]), (PG8_LAS unsigned*)(lds + (bufoff) + ldsw + _i * 8192), 16, 0, 0); } while (0)
; #define PG8_LDA(dst, b, h) do { _Pragma("unroll") for (int m = 0; m < 4; ++m) _Pragma("unroll") for (int k = 0; k < 2; ++k) dst[m][k] = *(const PG8_LAS bf16x8*)(lds + PG8_SA(b, h) + aoff + m * 2048 + k * 1024); } while (0)
; #define PG8_LDB(dst, b, h) do { _Pragma("unroll") for (int n = 0; n < 2; ++n) _Pragma("unroll") for (int k = 0; k < 2; ++k) dst[n][k] = *(const PG8_LAS bf16x8*)(lds + PG8_SB(b, h) + boff + n * 2048 + k * 1024); } while (0)
; #define PG8_MMA(ai, bj, At, Bt) do { __builtin_amdgcn_s_setprio(1); _Pragma("unroll") for (int m = 0; m < 4; ++m) _Pragma("unroll") for (int n = 0; n < 2; ++n) _Pragma("unroll") for (int k = 0; k < 2; ++k) \
;         acc[ai][bj][m][n] = __builtin_amdgcn_mfma_f32_16x16x32_bf16(Bt[n][k], At[m][k], acc[ai][bj][m][n], 0, 0, 0); __builtin_amdgcn_s_setprio(0); } while (0)
; #define PG8_WAIT_V(n) asm volatile("s_waitcnt vmcnt(" #n ")" ::: "memory")
; #define PG8_WAIT_L(n) asm volatile("s_waitcnt lgkmcnt(" #n ")" ::: "memory")
; #define PG8_BAR __builtin_amdgcn_s_barrier()
; #define PG8_SCHED __builtin_amdgcn_sched_barrier(0)
; template <class Epi, class Sched, bool ALIGN_EPI = false, bool SP2 = false>
; __device__ __forceinline__ void gemm_phase(PG8_LAS unsigned char* lds, const Gemm g, const Sched& S, const Epi& E) {
;     ...
;             PG8_LDB(B0, 0, 0); PG8_LDB(B1, 0, 1); PG8_SCHED; PG8_LDA(At, 0, 0); PG8_STAGE(PG8_SA(1, 1), a1 + hstep, voffA);
;             PG8_WAIT_V(8); PG8_WAIT_L(0); PG8_BAR; PG8_MMA(0, 0, At, B0); PG8_MMA(0, 1, At, B1); PG8_BAR; PG8_SCHED;
;             PG8_LDA(At, 0, 1); PG8_STAGE(PG8_SB(0, 0), b2, voffB); PG8_STAGE(PG8_SB(0, 1), b2 + hstep, voffB); PG8_STAGE(PG8_SA(0, 0), a2, voffA);
;             PG8_WAIT_V(8); PG8_WAIT_L(0); PG8_BAR; PG8_MMA(1, 0, At, B0); PG8_MMA(1, 1, At, B1); PG8_BAR; PG8_SCHED;
	s_setprio 1
	s_waitcnt lgkmcnt(0)
	v_mfma_f32_16x16x32_bf16 v[124:127], v[144:147], v[184:187], v[124:127]
	v_mfma_f32_16x16x32_bf16 v[120:123], v[160:163], v[184:187], v[120:123]
	v_mfma_f32_16x16x32_bf16 v[108:111], v[144:147], v[192:195], v[108:111]
	v_mfma_f32_16x16x32_bf16 v[104:107], v[160:163], v[192:195], v[104:107]
	v_mfma_f32_16x16x32_bf16 v[92:95], v[144:147], v[200:203], v[92:95]
	v_mfma_f32_16x16x32_bf16 v[88:91], v[160:163], v[200:203], v[88:91]
	v_mfma_f32_16x16x32_bf16 v[76:79], v[144:147], v[210:213], v[76:79]
	v_mfma_f32_16x16x32_bf16 v[72:75], v[160:163], v[210:213], v[72:75]
	v_mfma_f32_16x16x32_bf16 v[124:127], v[156:159], v[188:191], v[124:127]
	v_mfma_f32_16x16x32_bf16 v[120:123], v[164:167], v[188:191], v[120:123]
	v_mfma_f32_16x16x32_bf16 v[108:111], v[156:159], v[196:199], v[108:111]
	v_mfma_f32_16x16x32_bf16 v[104:107], v[164:167], v[196:199], v[104:107]
	v_mfma_f32_16x16x32_bf16 v[92:95], v[156:159], v[206:209], v[92:95]
	v_mfma_f32_16x16x32_bf16 v[88:91], v[164:167], v[206:209], v[88:91]
	v_mfma_f32_16x16x32_bf16 v[76:79], v[156:159], v[214:217], v[76:79]
	v_mfma_f32_16x16x32_bf16 v[72:75], v[164:167], v[214:217], v[72:75]
	s_setprio 0
	s_setprio 1
	v_mfma_f32_16x16x32_bf16 v[116:119], v[168:171], v[184:187], v[116:119]
	v_mfma_f32_16x16x32_bf16 v[112:115], v[176:179], v[184:187], v[112:115]
	v_mfma_f32_16x16x32_bf16 v[100:103], v[168:171], v[192:195], v[100:103]
	v_mfma_f32_16x16x32_bf16 v[96:99], v[176:179], v[192:195], v[96:99]
	v_mfma_f32_16x16x32_bf16 v[84:87], v[168:171], v[200:203], v[84:87]
	v_mfma_f32_16x16x32_bf16 v[80:83], v[176:179], v[200:203], v[80:83]
	v_mfma_f32_16x16x32_bf16 v[68:71], v[168:171], v[210:213], v[68:71]
	v_mfma_f32_16x16x32_bf16 v[64:67], v[176:179], v[210:213], v[64:67]
	v_mfma_f32_16x16x32_bf16 v[116:119], v[172:175], v[188:191], v[116:119]
	v_mfma_f32_16x16x32_bf16 v[112:115], v[180:183], v[188:191], v[112:115]
	v_mfma_f32_16x16x32_bf16 v[100:103], v[172:175], v[196:199], v[100:103]
	v_mfma_f32_16x16x32_bf16 v[96:99], v[180:183], v[196:199], v[96:99]
	v_mfma_f32_16x16x32_bf16 v[84:87], v[172:175], v[206:209], v[84:87]
	v_mfma_f32_16x16x32_bf16 v[80:83], v[180:183], v[206:209], v[80:83]
	v_mfma_f32_16x16x32_bf16 v[68:71], v[172:175], v[214:217], v[68:71]
	v_mfma_f32_16x16x32_bf16 v[64:67], v[180:183], v[214:217], v[64:67]
	s_setprio 0
	s_barrier
	s_add_i32 s26, s45, s15
	v_lshl_add_u64 v[218:219], s[36:37], 0, v[130:131]
	s_mov_b32 m0, s26
	ds_read_b128 v[184:187], v153 offset:16384
	ds_read_b128 v[188:191], v153 offset:17408
	ds_read_b128 v[192:195], v153 offset:18432
	ds_read_b128 v[196:199], v153 offset:19456
	ds_read_b128 v[200:203], v153 offset:20480
	ds_read_b128 v[206:209], v153 offset:21504
	ds_read_b128 v[210:213], v153 offset:22528
	ds_read_b128 v[214:217], v153 offset:23552
	global_load_lds_dwordx4 v[218:219], off
	s_add_i32 m0, s26, 0x2000
	s_add_u32 s26, s36, 0xb0000
	v_lshl_add_u64 v[220:221], s[36:37], 0, v[134:135]
	s_addc_u32 s27, s37, 0
	s_add_i32 s56, s46, s15
	global_load_lds_dwordx4 v[220:221], off
	v_lshl_add_u64 v[222:223], s[26:27], 0, v[130:131]
	s_mov_b32 m0, s56
	global_load_lds_dwordx4 v[222:223], off
	v_lshl_add_u64 v[222:223], s[26:27], 0, v[134:135]
	s_add_i32 m0, s56, 0x2000
	s_nop 0
	global_load_lds_dwordx4 v[222:223], off
	s_waitcnt vmcnt(6)
	s_waitcnt lgkmcnt(0)
	s_barrier
	s_setprio 1
	s_waitcnt lgkmcnt(0)
	v_mfma_f32_16x16x32_bf16 v[60:63], v[144:147], v[184:187], v[60:63]
	v_mfma_f32_16x16x32_bf16 v[56:59], v[160:163], v[184:187], v[56:59]
	v_mfma_f32_16x16x32_bf16 v[44:47], v[144:147], v[192:195], v[44:47]
	v_mfma_f32_16x16x32_bf16 v[40:43], v[160:163], v[192:195], v[40:43]
	v_mfma_f32_16x16x32_bf16 v[28:31], v[144:147], v[200:203], v[28:31]
	v_mfma_f32_16x16x32_bf16 v[24:27], v[160:163], v[200:203], v[24:27]
	v_mfma_f32_16x16x32_bf16 v[12:15], v[144:147], v[210:213], v[12:15]
	v_mfma_f32_16x16x32_bf16 v[8:11], v[160:163], v[210:213], v[8:11]
	v_mfma_f32_16x16x32_bf16 v[60:63], v[156:159], v[188:191], v[60:63]
	v_mfma_f32_16x16x32_bf16 v[56:59], v[164:167], v[188:191], v[56:59]
	v_mfma_f32_16x16x32_bf16 v[44:47], v[156:159], v[196:199], v[44:47]
	v_mfma_f32_16x16x32_bf16 v[40:43], v[164:167], v[196:199], v[40:43]
	v_lshl_add_u64 v[222:223], s[38:39], 0, v[128:129]
	s_mov_b32 m0, s33
	s_nop 0
	global_load_lds_dwordx4 v[222:223], off
	v_mfma_f32_16x16x32_bf16 v[28:31], v[156:159], v[206:209], v[28:31]
	v_mfma_f32_16x16x32_bf16 v[24:27], v[164:167], v[206:209], v[24:27]
	v_mfma_f32_16x16x32_bf16 v[12:15], v[156:159], v[214:217], v[12:15]
	v_mfma_f32_16x16x32_bf16 v[8:11], v[164:167], v[214:217], v[8:11]
	s_setprio 0
	s_setprio 1
	v_mfma_f32_16x16x32_bf16 v[52:55], v[168:171], v[184:187], v[52:55]
	v_mfma_f32_16x16x32_bf16 v[48:51], v[176:179], v[184:187], v[48:51]
	v_mfma_f32_16x16x32_bf16 v[36:39], v[168:171], v[192:195], v[36:39]
	v_mfma_f32_16x16x32_bf16 v[32:35], v[176:179], v[192:195], v[32:35]
	v_mfma_f32_16x16x32_bf16 v[20:23], v[168:171], v[200:203], v[20:23]
	v_mfma_f32_16x16x32_bf16 v[16:19], v[176:179], v[200:203], v[16:19]
	v_mfma_f32_16x16x32_bf16 v[4:7], v[168:171], v[210:213], v[4:7]
	v_mfma_f32_16x16x32_bf16 v[0:3], v[176:179], v[210:213], v[0:3]
	v_mfma_f32_16x16x32_bf16 v[52:55], v[172:175], v[188:191], v[52:55]
	v_mfma_f32_16x16x32_bf16 v[48:51], v[180:183], v[188:191], v[48:51]
	v_mfma_f32_16x16x32_bf16 v[36:39], v[172:175], v[196:199], v[36:39]
	v_mfma_f32_16x16x32_bf16 v[32:35], v[180:183], v[196:199], v[32:35]
	v_lshl_add_u64 v[224:225], s[38:39], 0, v[132:133]
	s_mov_b32 m0, s34
	s_nop 0
	global_load_lds_dwordx4 v[224:225], off
	v_mfma_f32_16x16x32_bf16 v[20:23], v[172:175], v[206:209], v[20:23]
	v_mfma_f32_16x16x32_bf16 v[16:19], v[180:183], v[206:209], v[16:19]
	v_mfma_f32_16x16x32_bf16 v[4:7], v[172:175], v[214:217], v[4:7]
	v_mfma_f32_16x16x32_bf16 v[0:3], v[180:183], v[214:217], v[0:3]
	s_setprio 0
	s_barrier
; #define PG8_STAGE(bufoff, gbase, voff) do { _Pragma("unroll") for (int _i = 0; _i < 2; ++_i) \
;         __builtin_amdgcn_global_load_lds((const unsigned*)((const char*)(gbase) + (voff)[_i]), (PG8_LAS unsigned*)(lds + (bufoff) + ldsw + _i * 8192), 16, 0, 0); } while (0)
; #define PG8_LDA(dst, b, h) do { _Pragma("unroll") for (int m = 0; m < 4; ++m) _Pragma("unroll") for (int k = 0; k < 2; ++k) dst[m][k] = *(const PG8_LAS bf16x8*)(lds + PG8_SA(b, h) + aoff + m * 2048 + k * 1024); } while (0)
; #define PG8_LDB(dst, b, h) do { _Pragma("unroll") for (int n = 0; n < 2; ++n) _Pragma("unroll") for (int k = 0; k < 2; ++k) dst[n][k] = *(const PG8_LAS bf16x8*)(lds + PG8_SB(b, h) + boff + n * 2048 + k * 1024); } while (0)
; #define PG8_MMA(ai, bj, At, Bt) do { __builtin_amdgcn_s_setprio(1); _Pragma("unroll") for (int m = 0; m < 4; ++m) _Pragma("unroll") for (int n = 0; n < 2; ++n) _Pragma("unroll") for (int k = 0; k < 2; ++k) \
;         acc[ai][bj][m][n] = __builtin_amdgcn_mfma_f32_16x16x32_bf16(Bt[n][k], At[m][k], acc[ai][bj][m][n], 0, 0, 0); __builtin_amdgcn_s_setprio(0); } while (0)
; #define PG8_WAIT_V(n) asm volatile("s_waitcnt vmcnt(" #n ")" ::: "memory")
; #define PG8_WAIT_L(n) asm volatile("s_waitcnt lgkmcnt(" #n ")" ::: "memory")
; #define PG8_BAR __builtin_amdgcn_s_barrier()
; #define PG8_SCHED __builtin_amdgcn_sched_barrier(0)
; template <class Epi, class Sched, bool ALIGN_EPI = false, bool SP2 = false>
; __device__ __forceinline__ void gemm_phase(PG8_LAS unsigned char* lds, const Gemm g, const Sched& S, const Epi& E) {
;     ...
;             PG8_LDB(B0, 1, 0); PG8_LDB(B1, 1, 1); PG8_SCHED; PG8_LDA(At, 1, 0); PG8_STAGE(PG8_SA(0, 1), a2 + hstep, voffA);
;             PG8_WAIT_V(8); PG8_WAIT_L(0); PG8_BAR; PG8_MMA(0, 0, At, B0); PG8_MMA(0, 1, At, B1); PG8_BAR; PG8_SCHED;
	s_add_i32 s56, 0, 0x18000
	v_add_u32_e32 v155, s56, v149
	s_add_i32 s57, 0, 0x1c000
	ds_read_b128 v[144:147], v155
	ds_read_b128 v[156:159], v155 offset:1024
	ds_read_b128 v[160:163], v155 offset:2048
	ds_read_b128 v[164:167], v155 offset:3072
	v_add_u32_e32 v155, s57, v149
	ds_read_b128 v[168:171], v155
	ds_read_b128 v[172:175], v155 offset:1024
	ds_read_b128 v[176:179], v155 offset:2048
	ds_read_b128 v[180:183], v155 offset:3072
	s_add_u32 s26, s38, 0xb0000
	s_addc_u32 s27, s39, 0
	s_mov_b32 m0, s40
	v_lshl_add_u64 v[226:227], s[26:27], 0, v[128:129]
	ds_read_b128 v[184:187], v153 offset:32768
	ds_read_b128 v[188:191], v153 offset:33792
	ds_read_b128 v[192:195], v153 offset:34816
	ds_read_b128 v[196:199], v153 offset:35840
	ds_read_b128 v[200:203], v153 offset:36864
	ds_read_b128 v[206:209], v153 offset:37888
	ds_read_b128 v[210:213], v153 offset:38912
	ds_read_b128 v[214:217], v153 offset:39936
	global_load_lds_dwordx4 v[226:227], off
	v_lshl_add_u64 v[226:227], s[26:27], 0, v[132:133]
	s_mov_b32 m0, s41
	s_nop 0
	global_load_lds_dwordx4 v[226:227], off
	s_waitcnt vmcnt(8)
	s_waitcnt lgkmcnt(0)
	s_barrier
	s_setprio 1
	s_waitcnt lgkmcnt(0)
	v_mfma_f32_16x16x32_bf16 v[124:127], v[144:147], v[184:187], v[124:127]
	v_mfma_f32_16x16x32_bf16 v[120:123], v[160:163], v[184:187], v[120:123]
	v_mfma_f32_16x16x32_bf16 v[108:111], v[144:147], v[192:195], v[108:111]
	v_mfma_f32_16x16x32_bf16 v[104:107], v[160:163], v[192:195], v[104:107]
	v_mfma_f32_16x16x32_bf16 v[92:95], v[144:147], v[200:203], v[92:95]
	v_mfma_f32_16x16x32_bf16 v[88:91], v[160:163], v[200:203], v[88:91]
	v_mfma_f32_16x16x32_bf16 v[76:79], v[144:147], v[210:213], v[76:79]
	v_mfma_f32_16x16x32_bf16 v[72:75], v[160:163], v[210:213], v[72:75]
	v_mfma_f32_16x16x32_bf16 v[124:127], v[156:159], v[188:191], v[124:127]
	v_mfma_f32_16x16x32_bf16 v[120:123], v[164:167], v[188:191], v[120:123]
	v_mfma_f32_16x16x32_bf16 v[108:111], v[156:159], v[196:199], v[108:111]
	v_mfma_f32_16x16x32_bf16 v[104:107], v[164:167], v[196:199], v[104:107]
	v_mfma_f32_16x16x32_bf16 v[92:95], v[156:159], v[206:209], v[92:95]
	v_mfma_f32_16x16x32_bf16 v[88:91], v[164:167], v[206:209], v[88:91]
	v_mfma_f32_16x16x32_bf16 v[76:79], v[156:159], v[214:217], v[76:79]
	v_mfma_f32_16x16x32_bf16 v[72:75], v[164:167], v[214:217], v[72:75]
	s_setprio 0
	s_setprio 1
	v_mfma_f32_16x16x32_bf16 v[116:119], v[168:171], v[184:187], v[116:119]
	v_mfma_f32_16x16x32_bf16 v[112:115], v[176:179], v[184:187], v[112:115]
	v_mfma_f32_16x16x32_bf16 v[100:103], v[168:171], v[192:195], v[100:103]
	v_mfma_f32_16x16x32_bf16 v[96:99], v[176:179], v[192:195], v[96:99]
	v_mfma_f32_16x16x32_bf16 v[84:87], v[168:171], v[200:203], v[84:87]
	v_mfma_f32_16x16x32_bf16 v[80:83], v[176:179], v[200:203], v[80:83]
	v_mfma_f32_16x16x32_bf16 v[68:71], v[168:171], v[210:213], v[68:71]
	v_mfma_f32_16x16x32_bf16 v[64:67], v[176:179], v[210:213], v[64:67]
	v_mfma_f32_16x16x32_bf16 v[116:119], v[172:175], v[188:191], v[116:119]
	v_mfma_f32_16x16x32_bf16 v[112:115], v[180:183], v[188:191], v[112:115]
	v_mfma_f32_16x16x32_bf16 v[100:103], v[172:175], v[196:199], v[100:103]
	v_mfma_f32_16x16x32_bf16 v[96:99], v[180:183], v[196:199], v[96:99]
	v_mfma_f32_16x16x32_bf16 v[84:87], v[172:175], v[206:209], v[84:87]
	v_mfma_f32_16x16x32_bf16 v[80:83], v[180:183], v[206:209], v[80:83]
	v_mfma_f32_16x16x32_bf16 v[68:71], v[172:175], v[214:217], v[68:71]
	v_mfma_f32_16x16x32_bf16 v[64:67], v[180:183], v[214:217], v[64:67]
	s_setprio 0
	s_barrier
; #define PG8_STAGE(bufoff, gbase, voff) do { _Pragma("unroll") for (int _i = 0; _i < 2; ++_i) \
;         __builtin_amdgcn_global_load_lds((const unsigned*)((const char*)(gbase) + (voff)[_i]), (PG8_LAS unsigned*)(lds + (bufoff) + ldsw + _i * 8192), 16, 0, 0); } while (0)
; #define PG8_LDA(dst, b, h) do { _Pragma("unroll") for (int m = 0; m < 4; ++m) _Pragma("unroll") for (int k = 0; k < 2; ++k) dst[m][k] = *(const PG8_LAS bf16x8*)(lds + PG8_SA(b, h) + aoff + m * 2048 + k * 1024); } while (0)
; #define PG8_MMA(ai, bj, At, Bt) do { __builtin_amdgcn_s_setprio(1); _Pragma("unroll") for (int m = 0; m < 4; ++m) _Pragma("unroll") for (int n = 0; n < 2; ++n) _Pragma("unroll") for (int k = 0; k < 2; ++k) \
;         acc[ai][bj][m][n] = __builtin_amdgcn_mfma_f32_16x16x32_bf16(Bt[n][k], At[m][k], acc[ai][bj][m][n], 0, 0, 0); __builtin_amdgcn_s_setprio(0); } while (0)
; #define PG8_WAIT_V(n) asm volatile("s_waitcnt vmcnt(" #n ")" ::: "memory")
; #define PG8_WAIT_L(n) asm volatile("s_waitcnt lgkmcnt(" #n ")" ::: "memory")
; #define PG8_BAR __builtin_amdgcn_s_barrier()
; #define PG8_SCHED __builtin_amdgcn_sched_barrier(0)
; template <class Epi, class Sched, bool ALIGN_EPI = false, bool SP2 = false>
; __device__ __forceinline__ void gemm_phase(PG8_LAS unsigned char* lds, const Gemm g, const Sched& S, const Epi& E) {
;     ...
;             PG8_LDA(At, 1, 1); PG8_STAGE(PG8_SB(1, 0), b3, voffB); PG8_STAGE(PG8_SB(1, 1), b3 + hstep, voffB); PG8_STAGE(PG8_SA(1, 0), a3, voffA);
;             PG8_WAIT_V(8); PG8_WAIT_L(0); PG8_BAR; PG8_MMA(1, 0, At, B0); PG8_MMA(1, 1, At, B1); PG8_BAR; PG8_SCHED;
	s_add_i32 s26, s56, s15
	v_lshl_add_u64 v[218:219], v[218:219], 0, s[12:13]
	s_mov_b32 m0, s26
	ds_read_b128 v[184:187], v153 offset:49152
	ds_read_b128 v[188:191], v153 offset:50176
	ds_read_b128 v[192:195], v153 offset:51200
	ds_read_b128 v[196:199], v153 offset:52224
	ds_read_b128 v[200:203], v153 offset:53248
	ds_read_b128 v[206:209], v153 offset:54272
	ds_read_b128 v[210:213], v153 offset:55296
	ds_read_b128 v[214:217], v153 offset:56320
	global_load_lds_dwordx4 v[218:219], off
	s_add_i32 m0, s26, 0x2000
	s_add_u32 s26, s36, 0xb0080
	v_lshl_add_u64 v[218:219], v[220:221], 0, s[12:13]
	s_addc_u32 s27, s37, 0
	s_add_i32 s36, s57, s15
	global_load_lds_dwordx4 v[218:219], off
	v_lshl_add_u64 v[218:219], s[26:27], 0, v[130:131]
	s_mov_b32 m0, s36
	s_nop 0
	global_load_lds_dwordx4 v[218:219], off
	v_lshl_add_u64 v[218:219], s[26:27], 0, v[134:135]
	s_add_i32 m0, s36, 0x2000
	s_nop 0
	global_load_lds_dwordx4 v[218:219], off
	s_waitcnt vmcnt(6)
	s_waitcnt lgkmcnt(0)
	s_barrier
	s_setprio 1
	s_waitcnt lgkmcnt(0)
	v_mfma_f32_16x16x32_bf16 v[60:63], v[144:147], v[184:187], v[60:63]
	v_mfma_f32_16x16x32_bf16 v[56:59], v[160:163], v[184:187], v[56:59]
	v_mfma_f32_16x16x32_bf16 v[44:47], v[144:147], v[192:195], v[44:47]
	v_mfma_f32_16x16x32_bf16 v[40:43], v[160:163], v[192:195], v[40:43]
	v_mfma_f32_16x16x32_bf16 v[28:31], v[144:147], v[200:203], v[28:31]
	v_mfma_f32_16x16x32_bf16 v[24:27], v[160:163], v[200:203], v[24:27]
	v_mfma_f32_16x16x32_bf16 v[12:15], v[144:147], v[210:213], v[12:15]
	v_mfma_f32_16x16x32_bf16 v[8:11], v[160:163], v[210:213], v[8:11]
	v_mfma_f32_16x16x32_bf16 v[60:63], v[156:159], v[188:191], v[60:63]
	v_mfma_f32_16x16x32_bf16 v[56:59], v[164:167], v[188:191], v[56:59]
	v_mfma_f32_16x16x32_bf16 v[44:47], v[156:159], v[196:199], v[44:47]
	v_mfma_f32_16x16x32_bf16 v[40:43], v[164:167], v[196:199], v[40:43]
	v_lshl_add_u64 v[218:219], v[222:223], 0, s[12:13]
	s_mov_b32 m0, s43
	s_nop 0
	global_load_lds_dwordx4 v[218:219], off
	v_mfma_f32_16x16x32_bf16 v[28:31], v[156:159], v[206:209], v[28:31]
	v_mfma_f32_16x16x32_bf16 v[24:27], v[164:167], v[206:209], v[24:27]
	v_mfma_f32_16x16x32_bf16 v[12:15], v[156:159], v[214:217], v[12:15]
	v_mfma_f32_16x16x32_bf16 v[8:11], v[164:167], v[214:217], v[8:11]
	s_setprio 0
	s_setprio 1
	v_mfma_f32_16x16x32_bf16 v[52:55], v[168:171], v[184:187], v[52:55]
	v_mfma_f32_16x16x32_bf16 v[48:51], v[176:179], v[184:187], v[48:51]
	v_mfma_f32_16x16x32_bf16 v[36:39], v[168:171], v[192:195], v[36:39]
	v_mfma_f32_16x16x32_bf16 v[32:35], v[176:179], v[192:195], v[32:35]
	v_mfma_f32_16x16x32_bf16 v[20:23], v[168:171], v[200:203], v[20:23]
	v_mfma_f32_16x16x32_bf16 v[16:19], v[176:179], v[200:203], v[16:19]
	v_mfma_f32_16x16x32_bf16 v[4:7], v[168:171], v[210:213], v[4:7]
	v_mfma_f32_16x16x32_bf16 v[0:3], v[176:179], v[210:213], v[0:3]
	v_mfma_f32_16x16x32_bf16 v[52:55], v[172:175], v[188:191], v[52:55]
	v_mfma_f32_16x16x32_bf16 v[48:51], v[180:183], v[188:191], v[48:51]
	v_mfma_f32_16x16x32_bf16 v[36:39], v[172:175], v[196:199], v[36:39]
	v_mfma_f32_16x16x32_bf16 v[32:35], v[180:183], v[196:199], v[32:35]
	v_lshl_add_u64 v[218:219], v[224:225], 0, s[12:13]
	s_mov_b32 m0, s44
	s_nop 0
	global_load_lds_dwordx4 v[218:219], off
	v_mfma_f32_16x16x32_bf16 v[20:23], v[172:175], v[206:209], v[20:23]
	v_mfma_f32_16x16x32_bf16 v[16:19], v[180:183], v[206:209], v[16:19]
	v_mfma_f32_16x16x32_bf16 v[4:7], v[172:175], v[214:217], v[4:7]
	v_mfma_f32_16x16x32_bf16 v[0:3], v[180:183], v[214:217], v[0:3]
	s_setprio 0
	s_barrier
	s_add_i32 s55, s55, 2
	s_add_u32 s53, s53, 0x100
	s_addc_u32 s54, s54, 0
	s_cmp_gt_u32 s55, 41
	s_mov_b64 s[26:27], s[28:29]
	s_cbranch_scc0 .LBB0_1978
	s_and_b64 vcc, exec, s[16:17]
	s_cbranch_vccz .LBB0_1981
	s_barrier
